# whole-file peephole: 64-bit VGPR+VGPR v_lshl_add_u64 -> v_add_co/v_addc pairs where VCC is dead (299 sites) + 32-bit row shift in epilogue store addresses
# baseline (speedup 1.0000x reference)
.LBB0_36:
	v_and_b32_e32 v4, 0x3ff, v3
	v_mov_b32_e32 v5, s66
	v_mov_b32_e32 v23, s65
	v_cmp_gt_u32_e32 vcc, s64, v3
	s_nop 1
	v_cndmask_b32_e32 v8, v4, v3, vcc
	v_cndmask_b32_e32 v4, v5, v23, vcc
	ds_read_b64 v[4:5], v4
	v_cmp_lt_u32_e32 vcc, s71, v3
	s_or_b64 s[52:53], vcc, s[52:53]
	s_waitcnt lgkmcnt(0)
	v_lshl_add_u64 v[4:5], v[8:9], 2, v[4:5]
	flat_load_dword v4, v[4:5]
	v_add_u32_e32 v5, 0x100, v3
	v_mov_b32_e32 v3, v5
	s_waitcnt vmcnt(0) lgkmcnt(0)
	v_mul_f32_e32 v5, 0xbfb8aa3b, v4
	v_fma_f32 v8, v4, s67, -v5
	v_rndne_f32_e32 v23, v5
	v_fmac_f32_e32 v8, 0xb2a5705f, v4
	v_sub_f32_e32 v5, v5, v23
	v_add_f32_e32 v5, v5, v8
	v_cvt_i32_f32_e32 v23, v23
	v_exp_f32_e32 v5, v5
	v_cmp_nlt_f32_e32 vcc, s68, v4
	v_ldexp_f32 v5, v5, v23
	s_nop 0
	v_cndmask_b32_e32 v5, 0, v5, vcc
	v_cmp_ngt_f32_e32 vcc, s69, v4
	s_nop 1
	v_cndmask_b32_e32 v5, v95, v5, vcc
	v_add_f32_e32 v5, 1.0, v5
	v_div_scale_f32 v8, s[54:55], v5, v5, v4
	v_rcp_f32_e32 v23, v8
	v_div_scale_f32 v61, vcc, v4, v5, v4
	v_fma_f32 v65, -v8, v23, 1.0
	v_fmac_f32_e32 v23, v65, v23
	v_mul_f32_e32 v65, v61, v23
	v_fma_f32 v66, -v8, v65, v61
	v_fmac_f32_e32 v65, v66, v23
	v_fma_f32 v8, -v8, v65, v61
	v_div_fmas_f32 v8, v8, v23, v65
	v_div_fixup_f32 v4, v8, v5, v4
	ds_write_b32 v2, v4
	v_add_u32_e32 v2, 0x400, v2
	s_andn2_b64 exec, exec, s[52:53]
	s_cbranch_execnz .LBB0_36
	s_or_b64 exec, exec, s[52:53]
	v_mov_b32_e32 v2, s72
	s_waitcnt lgkmcnt(0)
	s_barrier
	ds_read_b64 v[2:3], v2
	v_mov_b32_e32 v61, v9
	v_mov_b32_e32 v4, 0
	s_mov_b64 s[52:53], 0
	v_mov_b32_e32 v8, v81
	s_waitcnt lgkmcnt(0)
	v_add_co_u32_e32 v2, vcc, v2, v10
	v_addc_co_u32_e32 v3, vcc, v3, v11, vcc
	v_lshl_add_u64 v[2:3], v[60:61], 2, v[2:3]
	v_mov_b32_e32 v5, v4
	v_mov_b32_e32 v68, v4
	v_mov_b32_e32 v69, v4
	v_mov_b32_e32 v70, v4
	v_mov_b32_e32 v71, v4
	v_mov_b32_e32 v72, v4
	v_mov_b32_e32 v73, v4
	v_mov_b32_e32 v23, v4

.LBB0_43:
	s_andn2_saveexec_b64 s[50:51], s[50:51]
	s_cbranch_execz .LBB0_47
	v_add_u16_e32 v8, 0xf180, v1
	v_mul_u32_u24_e32 v23, 0xba2f, v8
	v_lshrrev_b32_e32 v23, 21, v23
	v_mov_b32_e32 v2, s76
	v_mov_b32_e32 v4, s63
	v_mul_lo_u16_e32 v61, 44, v23
	ds_read_b64 v[2:3], v2
	ds_read_b64 v[4:5], v4
	v_sub_u16_e32 v8, v8, v61
	v_lshlrev_b16_e32 v61, 6, v8
	v_or_b32_e32 v8, v77, v61
	v_lshlrev_b32_e32 v8, 12, v8
	s_waitcnt lgkmcnt(0)
	v_add_co_u32_e32 v2, vcc, v2, v8
	v_addc_co_u32_e32 v3, vcc, v3, v9, vcc
	v_lshlrev_b32_e32 v8, 8, v23
	v_add_co_u32_e32 v2, vcc, v2, v8
	v_addc_co_u32_e32 v3, vcc, v3, v9, vcc
	v_lshlrev_b32_e32 v8, 2, v6
	v_add_co_u32_e32 v2, vcc, v2, v8
	v_addc_co_u32_e32 v3, vcc, v3, v9, vcc
	v_add_co_u32_e32 v68, vcc, s77, v2
	v_mov_b32_e32 v71, v9
	s_nop 0
	v_addc_co_u32_e32 v69, vcc, 0, v3, vcc
	flat_load_dwordx4 v[98:101], v[2:3]
	flat_load_dwordx4 v[102:105], v[68:69]
	v_add_co_u32_e32 v68, vcc, s78, v2
	v_lshl_add_u64 v[72:73], v[4:5], 0, v[12:13]
	s_nop 0
	v_addc_co_u32_e32 v69, vcc, 0, v3, vcc
	flat_load_dwordx4 v[106:109], v[68:69]
	v_add_co_u32_e32 v2, vcc, s79, v2
	s_mov_b64 s[52:53], 0
	s_nop 0
	v_addc_co_u32_e32 v3, vcc, 0, v3, vcc
	flat_load_dwordx4 v[110:113], v[2:3]
	v_lshlrev_b32_e32 v2, 6, v23
	v_or_b32_e32 v8, v90, v2
	v_or_b32_e32 v23, v91, v2
	v_or_b32_e32 v70, v92, v2
	v_mov_b32_e32 v3, v9
	v_mov_b32_e32 v69, v9
	v_or_b32_e32 v118, v75, v2
	v_mul_u32_u24_e32 v2, 0x1600, v8
	v_mul_u32_u24_e32 v68, 0x1600, v23
	v_mul_u32_u24_e32 v70, 0x1600, v70
	v_lshlrev_b32_e32 v8, 1, v61
	v_lshl_add_u64 v[2:3], v[8:9], 0, v[2:3]
	v_lshl_add_u64 v[4:5], v[8:9], 0, v[68:69]
	v_lshl_add_u64 v[68:69], v[8:9], 0, v[70:71]
	v_mad_u64_u32 v[70:71], s[54:55], v118, s80, v[8:9]
	v_lshl_add_u64 v[2:3], v[72:73], 0, v[2:3]
	v_lshl_add_u64 v[4:5], v[72:73], 0, v[4:5]
	v_lshl_add_u64 v[68:69], v[72:73], 0, v[68:69]
	v_lshl_add_u64 v[70:71], v[72:73], 0, v[70:71]
	v_mov_b32_e32 v8, v85
	v_add_u32_e32 v65, 0x1040, v78
	v_add_u32_e32 v66, 0x1048, v78
	v_add_u32_e32 v114, 0x2080, v78
	v_add_u32_e32 v115, 0x2088, v78
	v_add_u32_e32 v116, 0x30c0, v78
	v_add_u32_e32 v117, 0x30c8, v78
	s_waitcnt vmcnt(0) lgkmcnt(0)
	ds_write2_b32 v78, v98, v99 offset1:1
	ds_write2_b32 v78, v100, v101 offset0:2 offset1:3
	ds_write2_b32 v65, v102, v103 offset1:1
	ds_write2_b32 v66, v104, v105 offset1:1
	ds_write2_b32 v114, v106, v107 offset1:1
	ds_write2_b32 v115, v108, v109 offset1:1
	ds_write2_b32 v116, v110, v111 offset1:1
	ds_write2_b32 v117, v112, v113 offset1:1
	s_waitcnt lgkmcnt(0)
	s_barrier

.LBB0_48:
	s_andn2_saveexec_b64 s[48:49], s[48:49]
	s_cbranch_execz .LBB0_52
	v_mov_b32_e32 v2, s82
	v_mov_b32_e32 v4, s63
	ds_read_b64 v[2:3], v2
	ds_read_b64 v[4:5], v4
	v_lshlrev_b32_e32 v8, 6, v1
	v_and_or_b32 v8, v8, s59, v77
	v_lshl_add_u32 v61, v1, 2, v96
	v_mul_u32_u24_e32 v8, 0x1600, v8
	v_and_b32_e32 v61, 0x3ffc0, v61
	v_lshlrev_b32_e32 v68, 2, v8
	v_mov_b32_e32 v69, v9
	s_waitcnt lgkmcnt(0)
	v_add_co_u32_e32 v2, vcc, v2, v68
	v_addc_co_u32_e32 v3, vcc, v3, v69, vcc
	v_lshlrev_b32_e32 v68, 2, v61
	v_add_co_u32_e32 v2, vcc, v2, v68
	v_addc_co_u32_e32 v3, vcc, v3, v69, vcc
	v_lshlrev_b32_e32 v68, 2, v6
	v_add_co_u32_e32 v2, vcc, v2, v68
	v_addc_co_u32_e32 v3, vcc, v3, v69, vcc
	v_add_co_u32_e32 v68, vcc, s81, v2
	v_mov_b32_e32 v71, v9
	s_nop 0
	v_addc_co_u32_e32 v69, vcc, 0, v3, vcc
	flat_load_dwordx4 v[98:101], v[2:3]
	flat_load_dwordx4 v[102:105], v[68:69]
	v_add_co_u32_e32 v68, vcc, s83, v2
	v_mov_b32_e32 v73, v9
	s_nop 0
	v_addc_co_u32_e32 v69, vcc, 0, v3, vcc
	flat_load_dwordx4 v[106:109], v[68:69]
	v_add_co_u32_e32 v2, vcc, s84, v2
	v_lshl_add_u64 v[114:115], v[4:5], 0, v[14:15]
	s_nop 0
	v_addc_co_u32_e32 v3, vcc, 0, v3, vcc
	flat_load_dwordx4 v[110:113], v[2:3]
	v_and_b32_e32 v2, 0x3ffc0, v93
	v_or_b32_e32 v3, v90, v2
	v_or_b32_e32 v68, v91, v2
	v_or_b32_e32 v70, v92, v2
	v_or_b32_e32 v2, v75, v2
	v_mov_b32_e32 v69, v9
	v_lshl_or_b32 v8, v3, 11, v23
	v_lshl_or_b32 v68, v68, 11, v23
	v_lshl_or_b32 v70, v70, 11, v23
	v_lshl_or_b32 v72, v2, 11, v23
	s_mov_b64 s[50:51], 0
	v_lshl_add_u64 v[2:3], v[114:115], 0, v[8:9]
	v_lshl_add_u64 v[4:5], v[114:115], 0, v[68:69]
	v_lshl_add_u64 v[68:69], v[114:115], 0, v[70:71]
	v_lshl_add_u64 v[70:71], v[114:115], 0, v[72:73]
	v_mov_b32_e32 v8, v85
	v_add_u32_e32 v61, 0x1040, v78
	v_add_u32_e32 v65, 0x1048, v78
	v_add_u32_e32 v66, 0x2080, v78
	v_add_u32_e32 v116, 0x2088, v78
	v_add_u32_e32 v117, 0x30c0, v78
	v_add_u32_e32 v118, 0x30c8, v78
	s_waitcnt vmcnt(0) lgkmcnt(0)
	ds_write2_b32 v78, v98, v99 offset1:1
	ds_write2_b32 v78, v100, v101 offset0:2 offset1:3
	ds_write2_b32 v61, v102, v103 offset1:1
	ds_write2_b32 v65, v104, v105 offset1:1
	ds_write2_b32 v66, v106, v107 offset1:1
	ds_write2_b32 v116, v108, v109 offset1:1
	ds_write2_b32 v117, v110, v111 offset1:1
	ds_write2_b32 v118, v112, v113 offset1:1
	s_waitcnt lgkmcnt(0)
	s_barrier

.LBB0_53:
	s_andn2_saveexec_b64 s[46:47], s[46:47]
	s_cbranch_execz .LBB0_57
	v_mov_b32_e32 v23, s85
	v_mov_b32_e32 v61, s63
	ds_read_b64 v[70:71], v23
	ds_read_b64 v[72:73], v61
	v_lshlrev_b32_e32 v23, 6, v1
	v_and_or_b32 v23, v23, s59, v77
	v_lshlrev_b32_e32 v98, 12, v23
	v_mov_b32_e32 v99, v9
	v_lshlrev_b32_e32 v23, 4, v1
	s_waitcnt lgkmcnt(0)
	v_add_co_u32_e32 v70, vcc, v70, v98
	v_addc_co_u32_e32 v71, vcc, v71, v99, vcc
	v_and_b32_e32 v98, 0xf00, v23
	v_add_co_u32_e32 v70, vcc, v70, v98
	v_addc_co_u32_e32 v71, vcc, v71, v99, vcc
	v_lshlrev_b32_e32 v98, 2, v6
	v_add_co_u32_e32 v70, vcc, v70, v98
	v_addc_co_u32_e32 v71, vcc, v71, v99, vcc
	v_add_co_u32_e32 v102, vcc, s77, v70
	v_lshl_add_u64 v[72:73], v[72:73], 0, v[16:17]
	s_nop 0
	v_addc_co_u32_e32 v103, vcc, 0, v71, vcc
	flat_load_dwordx4 v[98:101], v[70:71]
	s_nop 0
	flat_load_dwordx4 v[102:105], v[102:103]
	v_add_co_u32_e32 v106, vcc, s78, v70
	s_mov_b64 s[48:49], 0
	s_nop 0
	v_addc_co_u32_e32 v107, vcc, 0, v71, vcc
	flat_load_dwordx4 v[106:109], v[106:107]
	v_add_co_u32_e32 v70, vcc, s79, v70
	v_lshl_add_u64 v[2:3], v[72:73], 0, v[2:3]
	s_nop 0
	v_addc_co_u32_e32 v71, vcc, 0, v71, vcc
	flat_load_dwordx4 v[110:113], v[70:71]
	v_lshl_add_u64 v[70:71], v[72:73], 0, v[8:9]
	v_lshl_add_u64 v[4:5], v[72:73], 0, v[4:5]
	v_lshl_add_u64 v[68:69], v[72:73], 0, v[68:69]
	v_mov_b32_e32 v8, v85
	v_add_u32_e32 v23, 0x1040, v78
	v_add_u32_e32 v61, 0x1048, v78
	v_add_u32_e32 v65, 0x2080, v78
	v_add_u32_e32 v66, 0x2088, v78
	v_add_u32_e32 v114, 0x30c0, v78
	v_add_u32_e32 v115, 0x30c8, v78
	s_waitcnt vmcnt(0) lgkmcnt(0)
	ds_write2_b32 v78, v98, v99 offset1:1
	ds_write2_b32 v78, v100, v101 offset0:2 offset1:3
	ds_write2_b32 v23, v102, v103 offset1:1
	ds_write2_b32 v61, v104, v105 offset1:1
	ds_write2_b32 v65, v106, v107 offset1:1
	ds_write2_b32 v66, v108, v109 offset1:1
	ds_write2_b32 v114, v110, v111 offset1:1
	ds_write2_b32 v115, v112, v113 offset1:1
	s_waitcnt lgkmcnt(0)
	s_barrier

.LBB0_58:
	s_andn2_saveexec_b64 s[44:45], s[44:45]
	s_cbranch_execz .LBB0_62
	v_mov_b32_e32 v23, s86
	v_mov_b32_e32 v61, s63
	ds_read_b64 v[70:71], v23
	ds_read_b64 v[72:73], v61
	v_lshlrev_b32_e32 v23, 6, v1
	v_and_or_b32 v23, v23, s59, v77
	v_lshlrev_b32_e32 v98, 12, v23
	v_mov_b32_e32 v99, v9
	v_lshlrev_b32_e32 v23, 4, v1
	s_waitcnt lgkmcnt(0)
	v_add_co_u32_e32 v70, vcc, v70, v98
	v_addc_co_u32_e32 v71, vcc, v71, v99, vcc
	v_and_b32_e32 v98, 0xf00, v23
	v_add_co_u32_e32 v70, vcc, v70, v98
	v_addc_co_u32_e32 v71, vcc, v71, v99, vcc
	v_lshlrev_b32_e32 v98, 2, v6
	v_add_co_u32_e32 v70, vcc, v70, v98
	v_addc_co_u32_e32 v71, vcc, v71, v99, vcc
	v_add_co_u32_e32 v102, vcc, s77, v70
	v_lshl_add_u64 v[72:73], v[72:73], 0, v[18:19]
	s_nop 0
	v_addc_co_u32_e32 v103, vcc, 0, v71, vcc
	flat_load_dwordx4 v[98:101], v[70:71]
	s_nop 0
	flat_load_dwordx4 v[102:105], v[102:103]
	v_add_co_u32_e32 v106, vcc, s78, v70
	s_mov_b64 s[46:47], 0
	s_nop 0
	v_addc_co_u32_e32 v107, vcc, 0, v71, vcc
	flat_load_dwordx4 v[106:109], v[106:107]
	v_add_co_u32_e32 v70, vcc, s79, v70
	v_lshl_add_u64 v[2:3], v[72:73], 0, v[2:3]
	s_nop 0
	v_addc_co_u32_e32 v71, vcc, 0, v71, vcc
	flat_load_dwordx4 v[110:113], v[70:71]
	v_lshl_add_u64 v[70:71], v[72:73], 0, v[8:9]
	v_lshl_add_u64 v[4:5], v[72:73], 0, v[4:5]
	v_lshl_add_u64 v[68:69], v[72:73], 0, v[68:69]
	v_mov_b32_e32 v8, v85
	v_add_u32_e32 v23, 0x1040, v78
	v_add_u32_e32 v61, 0x1048, v78
	v_add_u32_e32 v65, 0x2080, v78
	v_add_u32_e32 v66, 0x2088, v78
	v_add_u32_e32 v114, 0x30c0, v78
	v_add_u32_e32 v115, 0x30c8, v78
	s_waitcnt vmcnt(0) lgkmcnt(0)
	ds_write2_b32 v78, v98, v99 offset1:1
	ds_write2_b32 v78, v100, v101 offset0:2 offset1:3
	ds_write2_b32 v23, v102, v103 offset1:1
	ds_write2_b32 v61, v104, v105 offset1:1
	ds_write2_b32 v65, v106, v107 offset1:1
	ds_write2_b32 v66, v108, v109 offset1:1
	ds_write2_b32 v114, v110, v111 offset1:1
	ds_write2_b32 v115, v112, v113 offset1:1
	s_waitcnt lgkmcnt(0)
	s_barrier

.LBB0_63:
	s_andn2_saveexec_b64 s[42:43], s[42:43]
	s_cbranch_execz .LBB0_67
	v_mov_b32_e32 v3, s87
	v_mov_b32_e32 v8, s63
	ds_read_b64 v[4:5], v3
	ds_read_b64 v[68:69], v8
	v_lshlrev_b32_e32 v3, 6, v1
	v_lshlrev_b32_e32 v23, 3, v1
	v_and_or_b32 v3, v3, s88, v77
	v_bitop3_b32 v61, v23, s70, v97 bitop3:0x6c
	v_lshlrev_b32_e32 v8, 12, v3
	s_waitcnt lgkmcnt(0)
	v_add_co_u32_e32 v4, vcc, v4, v8
	v_addc_co_u32_e32 v5, vcc, v5, v9, vcc
	v_lshlrev_b32_e32 v8, 2, v61
	v_add_co_u32_e32 v4, vcc, v4, v8
	v_addc_co_u32_e32 v5, vcc, v5, v9, vcc
	v_lshlrev_b32_e32 v8, 2, v6
	v_add_co_u32_e32 v4, vcc, v4, v8
	v_addc_co_u32_e32 v5, vcc, v5, v9, vcc
	v_add_co_u32_e32 v70, vcc, s77, v4
	v_and_b32_e32 v2, 7, v2
	s_nop 0
	v_addc_co_u32_e32 v71, vcc, 0, v5, vcc
	flat_load_dwordx4 v[98:101], v[4:5]
	flat_load_dwordx4 v[102:105], v[70:71]
	v_add_co_u32_e32 v70, vcc, s78, v4
	v_lshlrev_b32_e32 v115, 7, v2
	s_nop 0
	v_addc_co_u32_e32 v71, vcc, 0, v5, vcc
	flat_load_dwordx4 v[106:109], v[70:71]
	v_add_co_u32_e32 v4, vcc, s79, v4
	v_and_b32_e32 v2, 0x7c0, v23
	s_nop 0
	v_addc_co_u32_e32 v5, vcc, 0, v5, vcc
	flat_load_dwordx4 v[110:113], v[4:5]
	v_bitop3_b32 v3, v90, v2, s70 bitop3:0xf6
	v_bitop3_b32 v4, v91, v2, s70 bitop3:0xf6
	v_lshl_add_u64 v[70:71], v[68:69], 0, v[20:21]
	v_lshl_or_b32 v8, v3, 10, v115
	v_bitop3_b32 v23, v92, v2, s70 bitop3:0xf6
	v_bitop3_b32 v116, v75, v2, s70 bitop3:0xf6
	v_lshl_add_u64 v[2:3], v[70:71], 0, v[8:9]
	v_lshl_or_b32 v8, v4, 10, v115
	v_lshl_add_u64 v[4:5], v[70:71], 0, v[8:9]
	v_lshl_or_b32 v8, v23, 10, v115
	v_lshl_add_u64 v[68:69], v[70:71], 0, v[8:9]
	v_lshl_or_b32 v8, v116, 10, v115
	s_mov_b64 s[44:45], 0
	v_lshl_add_u64 v[70:71], v[70:71], 0, v[8:9]
	v_mov_b32_e32 v8, v85
	v_add_u32_e32 v61, 0x1040, v78
	v_add_u32_e32 v65, 0x1048, v78
	v_add_u32_e32 v66, 0x2080, v78
	v_add_u32_e32 v72, 0x2088, v78
	v_add_u32_e32 v73, 0x30c0, v78
	v_add_u32_e32 v114, 0x30c8, v78
	s_waitcnt vmcnt(0) lgkmcnt(0)
	ds_write2_b32 v78, v98, v99 offset1:1
	ds_write2_b32 v78, v100, v101 offset0:2 offset1:3
	ds_write2_b32 v61, v102, v103 offset1:1
	ds_write2_b32 v65, v104, v105 offset1:1
	ds_write2_b32 v66, v106, v107 offset1:1
	ds_write2_b32 v72, v108, v109 offset1:1
	ds_write2_b32 v73, v110, v111 offset1:1
	ds_write2_b32 v114, v112, v113 offset1:1
	s_waitcnt lgkmcnt(0)
	s_barrier

.LBB0_68:
	v_mov_b32_e32 v2, s89
	v_mov_b32_e32 v4, s63
	ds_read_b64 v[2:3], v2
	ds_read_b64 v[72:73], v4
	v_ashrrev_i32_e32 v4, 31, v1
	v_lshrrev_b32_e32 v4, 28, v4
	v_add_u32_e32 v4, v1, v4
	v_and_b32_e32 v5, 0x3fffff0, v4
	v_sub_u32_e32 v5, v1, v5
	v_lshlrev_b32_e32 v110, 6, v5
	v_or_b32_e32 v5, v110, v77
	v_lshlrev_b32_e32 v4, 2, v4
	v_mul_lo_u32 v68, v5, s90
	v_and_b32_e32 v4, 0xffffffc0, v4
	v_ashrrev_i32_e32 v69, 31, v68
	s_waitcnt lgkmcnt(0)
	v_lshl_add_u64 v[2:3], v[68:69], 2, v[2:3]
	v_ashrrev_i32_e32 v5, 31, v4
	v_lshl_add_u64 v[2:3], v[4:5], 2, v[2:3]
	v_lshlrev_b32_e32 v8, 2, v6
	v_add_co_u32_e32 v2, vcc, v2, v8
	v_addc_co_u32_e32 v3, vcc, v3, v9, vcc
	v_add_co_u32_e32 v98, vcc, s91, v2
	v_ashrrev_i32_e32 v111, 31, v110
	s_nop 0
	v_addc_co_u32_e32 v99, vcc, 0, v3, vcc
	flat_load_dwordx4 v[68:71], v[2:3]
	s_nop 0
	flat_load_dwordx4 v[98:101], v[98:99]
	v_add_co_u32_e32 v102, vcc, s92, v2
	v_add_u32_e32 v5, 0x1040, v78
	s_nop 0
	v_addc_co_u32_e32 v103, vcc, 0, v3, vcc
	flat_load_dwordx4 v[102:105], v[102:103]
	v_add_co_u32_e32 v2, vcc, s93, v2
	v_mov_b32_e32 v23, v9
	s_nop 0
	v_addc_co_u32_e32 v3, vcc, 0, v3, vcc
	flat_load_dwordx4 v[106:109], v[2:3]
	v_lshl_add_u64 v[2:3], v[110:111], 1, v[72:73]
	s_mov_b32 s34, 0
	v_add_u32_e32 v8, 0x1048, v78
	v_add_u32_e32 v61, 0x2080, v78
	v_add_u32_e32 v65, 0x2088, v78
	v_add_u32_e32 v66, 0x30c0, v78
	v_add_u32_e32 v112, 0x30c8, v78
	v_or_b32_e32 v4, v75, v4
	v_lshl_add_u64 v[2:3], v[2:3], 0, v[22:23]
	s_waitcnt vmcnt(0) lgkmcnt(0)
	ds_write2_b32 v78, v68, v69 offset1:1
	ds_write2_b32 v78, v70, v71 offset0:2 offset1:3
	ds_write2_b32 v5, v98, v99 offset1:1
	ds_write2_b32 v8, v100, v101 offset1:1
	ds_write2_b32 v61, v102, v103 offset1:1
	ds_write2_b32 v65, v104, v105 offset1:1
	ds_write2_b32 v66, v106, v107 offset1:1
	ds_write2_b32 v112, v108, v109 offset1:1
	v_mov_b32_e32 v5, v85
	s_waitcnt lgkmcnt(0)
	s_barrier

.LBB0_86:
	s_or_b64 exec, exec, s[0:1]
	v_mov_b32_e32 v37, s19
	ds_read_b64 v[64:65], v37
	v_add_co_u32_e32 v52, vcc, v52, v32
	v_addc_co_u32_e32 v53, vcc, v53, v33, vcc
	s_waitcnt lgkmcnt(0)
	flat_load_dwordx4 v[42:45], v[52:53]
	v_add_co_u32_e32 v48, vcc, v48, v32
	v_addc_co_u32_e32 v49, vcc, v49, v33, vcc
	flat_load_dwordx4 v[68:71], v[48:49]
	v_add_co_u32_e32 v72, vcc, v64, v32
	v_addc_co_u32_e32 v73, vcc, v65, v33, vcc
	flat_load_dwordx4 v[64:67], v[72:73]
	v_add_f32_e32 v37, v50, v35
	v_fmamk_f32 v39, v51, 0x3a800000, v55
	v_mul_f32_e32 v41, 0x4b800000, v39
	v_fmamk_f32 v37, v37, 0x3a800000, v55
	v_cmp_gt_f32_e32 vcc, s20, v39
	v_cmp_gt_f32_e64 s[0:1], s20, v37
	v_mov_b32_e32 v35, v33
	v_cndmask_b32_e32 v39, v39, v41, vcc
	v_mul_f32_e32 v41, 0x4b800000, v37
	v_rsq_f32_e32 v39, v39
	v_cndmask_b32_e64 v37, v37, v41, s[0:1]
	v_rsq_f32_e32 v37, v37
	v_lshl_add_u64 v[50:51], v[46:47], 0, v[34:35]
	v_mul_f32_e32 v35, 0x45800000, v39
	v_cndmask_b32_e32 v74, v39, v35, vcc
	v_mul_f32_e32 v35, 0x45800000, v37
	v_cndmask_b32_e64 v76, v37, v35, s[0:1]
	v_pk_mul_f32 v[24:25], v[24:25], v[74:75] op_sel_hi:[1,0]
	v_pk_mul_f32 v[26:27], v[26:27], v[74:75] op_sel_hi:[1,0]
	v_pk_mul_f32 v[28:29], v[28:29], v[76:77] op_sel_hi:[1,0]
	v_pk_mul_f32 v[30:31], v[30:31], v[76:77] op_sel_hi:[1,0]
	v_pk_mul_f32 v[12:13], v[12:13], v[74:75] op_sel_hi:[1,0]
	v_pk_mul_f32 v[14:15], v[14:15], v[74:75] op_sel_hi:[1,0]
	v_pk_mul_f32 v[20:21], v[20:21], v[76:77] op_sel_hi:[1,0]
	v_pk_mul_f32 v[22:23], v[22:23], v[76:77] op_sel_hi:[1,0]
	v_mov_b32_e32 v37, v33
	v_pk_mul_f32 v[8:9], v[8:9], v[74:75] op_sel_hi:[1,0]
	v_pk_mul_f32 v[10:11], v[10:11], v[74:75] op_sel_hi:[1,0]
	v_pk_mul_f32 v[16:17], v[16:17], v[76:77] op_sel_hi:[1,0]
	v_pk_mul_f32 v[18:19], v[18:19], v[76:77] op_sel_hi:[1,0]
	v_mov_b32_e32 v39, v33
	v_pk_mul_f32 v[0:1], v[0:1], v[74:75] op_sel_hi:[1,0]
	v_pk_mul_f32 v[2:3], v[2:3], v[74:75] op_sel_hi:[1,0]
	v_pk_mul_f32 v[4:5], v[4:5], v[76:77] op_sel_hi:[1,0]
	v_pk_mul_f32 v[6:7], v[6:7], v[76:77] op_sel_hi:[1,0]
	v_mov_b32_e32 v41, v33
	s_add_i32 s21, s21, s40
	s_add_i32 s3, s3, s14
	s_cmpk_gt_i32 s21, 0x87f
	s_waitcnt vmcnt(0) lgkmcnt(0)
	v_pk_add_f32 v[42:43], v[42:43], 1.0 op_sel_hi:[1,0]
	v_pk_add_f32 v[44:45], v[44:45], 1.0 op_sel_hi:[1,0]
	v_pk_mul_f32 v[24:25], v[64:65], v[24:25]
	v_pk_mul_f32 v[26:27], v[66:67], v[26:27]
	v_pk_mul_f32 v[28:29], v[64:65], v[28:29]
	v_pk_mul_f32 v[30:31], v[66:67], v[30:31]
	v_pk_fma_f32 v[24:25], v[24:25], v[42:43], v[68:69]
	v_pk_fma_f32 v[26:27], v[26:27], v[44:45], v[70:71]
	v_pk_fma_f32 v[28:29], v[42:43], v[28:29], v[68:69]
	v_pk_fma_f32 v[30:31], v[30:31], v[44:45], v[70:71]
	v_cvt_pk_bf16_f32 v24, v24, v25
	v_cvt_pk_bf16_f32 v25, v26, v27
	v_cvt_pk_bf16_f32 v26, v28, v29
	v_cvt_pk_bf16_f32 v27, v30, v31
	flat_store_dwordx2 v[50:51], v[24:25]
	flat_store_dwordx2 v[50:51], v[26:27] offset:2048
	flat_load_dwordx4 v[24:27], v[72:73] offset:1024
	s_nop 0
	flat_load_dwordx4 v[28:31], v[52:53] offset:1024
	flat_load_dwordx4 v[42:45], v[48:49] offset:1024
	v_lshl_add_u64 v[50:51], v[46:47], 0, v[36:37]
	s_waitcnt vmcnt(0) lgkmcnt(0)
	v_pk_mul_f32 v[12:13], v[12:13], v[24:25]
	v_pk_add_f32 v[28:29], v[28:29], 1.0 op_sel_hi:[1,0]
	v_pk_mul_f32 v[14:15], v[14:15], v[26:27]
	v_pk_add_f32 v[30:31], v[30:31], 1.0 op_sel_hi:[1,0]
	v_pk_mul_f32 v[20:21], v[20:21], v[24:25]
	v_pk_mul_f32 v[22:23], v[22:23], v[26:27]
	v_pk_fma_f32 v[12:13], v[12:13], v[28:29], v[42:43]
	v_pk_fma_f32 v[14:15], v[14:15], v[30:31], v[44:45]
	v_pk_fma_f32 v[20:21], v[20:21], v[28:29], v[42:43]
	v_pk_fma_f32 v[22:23], v[22:23], v[30:31], v[44:45]
	v_cvt_pk_bf16_f32 v12, v12, v13
	v_cvt_pk_bf16_f32 v13, v14, v15
	v_cvt_pk_bf16_f32 v14, v20, v21
	v_cvt_pk_bf16_f32 v15, v22, v23
	flat_store_dwordx2 v[50:51], v[12:13]
	flat_store_dwordx2 v[50:51], v[14:15] offset:2048
	flat_load_dwordx4 v[12:15], v[72:73] offset:2048
	s_nop 0
	flat_load_dwordx4 v[20:23], v[52:53] offset:2048
	flat_load_dwordx4 v[24:27], v[48:49] offset:2048
	v_lshl_add_u64 v[28:29], v[46:47], 0, v[38:39]
	s_waitcnt vmcnt(0) lgkmcnt(0)
	v_pk_mul_f32 v[8:9], v[8:9], v[12:13]
	v_pk_add_f32 v[20:21], v[20:21], 1.0 op_sel_hi:[1,0]
	v_pk_mul_f32 v[10:11], v[10:11], v[14:15]
	v_pk_add_f32 v[22:23], v[22:23], 1.0 op_sel_hi:[1,0]
	v_pk_mul_f32 v[12:13], v[16:17], v[12:13]
	v_pk_mul_f32 v[14:15], v[18:19], v[14:15]
	v_pk_fma_f32 v[8:9], v[8:9], v[20:21], v[24:25]
	v_pk_fma_f32 v[10:11], v[10:11], v[22:23], v[26:27]
	v_pk_fma_f32 v[12:13], v[12:13], v[20:21], v[24:25]
	v_pk_fma_f32 v[14:15], v[14:15], v[22:23], v[26:27]
	v_cvt_pk_bf16_f32 v8, v8, v9
	v_cvt_pk_bf16_f32 v9, v10, v11
	v_cvt_pk_bf16_f32 v10, v12, v13
	v_cvt_pk_bf16_f32 v11, v14, v15
	flat_store_dwordx2 v[28:29], v[8:9]
	flat_store_dwordx2 v[28:29], v[10:11] offset:2048
	flat_load_dwordx4 v[8:11], v[72:73] offset:3072
	s_nop 0
	flat_load_dwordx4 v[12:15], v[52:53] offset:3072
	flat_load_dwordx4 v[16:19], v[48:49] offset:3072
	v_lshl_add_u64 v[20:21], v[46:47], 0, v[40:41]
	s_waitcnt vmcnt(0) lgkmcnt(0)
	v_pk_mul_f32 v[0:1], v[0:1], v[8:9]
	v_pk_add_f32 v[12:13], v[12:13], 1.0 op_sel_hi:[1,0]
	v_pk_mul_f32 v[2:3], v[2:3], v[10:11]
	v_pk_add_f32 v[14:15], v[14:15], 1.0 op_sel_hi:[1,0]
	v_pk_mul_f32 v[4:5], v[4:5], v[8:9]
	v_pk_mul_f32 v[6:7], v[6:7], v[10:11]
	v_pk_fma_f32 v[0:1], v[0:1], v[12:13], v[16:17]
	v_pk_fma_f32 v[2:3], v[2:3], v[14:15], v[18:19]
	v_pk_fma_f32 v[4:5], v[4:5], v[12:13], v[16:17]
	v_pk_fma_f32 v[6:7], v[6:7], v[14:15], v[18:19]
	v_cvt_pk_bf16_f32 v0, v0, v1
	v_cvt_pk_bf16_f32 v1, v2, v3
	v_cvt_pk_bf16_f32 v2, v4, v5
	v_cvt_pk_bf16_f32 v3, v6, v7
	flat_store_dwordx2 v[20:21], v[0:1]
	flat_store_dwordx2 v[20:21], v[2:3] offset:2048
	s_cbranch_scc1 .LBB0_91
.LBB0_87:
	v_mov_b32_e32 v0, v132
	ds_read_b64 v[42:43], v54
	v_ashrrev_i32_e32 v0, 5, v0
	v_and_b32_e32 v0, -2, v0
	v_add_u32_e32 v44, s3, v0
	v_cmp_lt_i32_e32 vcc, s15, v44
	s_and_saveexec_b64 s[0:1], vcc
	s_xor_b64 s[0:1], exec, s[0:1]
	s_cbranch_execz .LBB0_89
	v_mov_b32_e32 v0, s16
	ds_read_b64 v[0:1], v0
	v_add_u32_e32 v2, 0xffff8000, v44
	v_mov_b32_e32 v3, v33
	v_lshlrev_b64 v[2:3], 12, v[2:3]
	v_mov_b32_e32 v45, v33
	s_waitcnt lgkmcnt(0)
	v_add_co_u32_e32 v0, vcc, v0, v2
	v_addc_co_u32_e32 v1, vcc, v1, v3, vcc
	v_add_co_u32_e32 v4, vcc, v0, v32
	v_addc_co_u32_e32 v5, vcc, v1, v33, vcc
	v_add_co_u32_e32 v46, vcc, s17, v4
	flat_load_dwordx4 v[24:27], v[4:5] nt
	flat_load_dwordx4 v[12:15], v[4:5] offset:1024 nt
	flat_load_dwordx4 v[8:11], v[4:5] offset:2048 nt
	flat_load_dwordx4 v[0:3], v[4:5] offset:3072 nt
	v_addc_co_u32_e32 v47, vcc, 0, v5, vcc
	flat_load_dwordx4 v[28:31], v[46:47] nt
	flat_load_dwordx4 v[20:23], v[46:47] offset:1024 nt
	flat_load_dwordx4 v[4:7], v[46:47] offset:3072 nt
	flat_load_dwordx4 v[16:19], v[46:47] offset:2048 nt
	v_cmp_lt_i32_e32 vcc, v58, v57
	v_lshlrev_b64 v[44:45], 11, v[44:45]
	s_waitcnt vmcnt(0) lgkmcnt(0)
	v_pk_mul_f32 v[48:49], v[24:25], v[24:25]
	v_mul_f32_e32 v50, v12, v12
	v_mov_b32_e32 v51, v14
	v_pk_mul_f32 v[46:47], v[26:27], v[26:27]
	v_mov_b32_e32 v65, v9
	v_add_f32_e32 v39, v48, v49
	v_pk_fma_f32 v[80:81], v[12:13], v[12:13], v[50:51] op_sel_hi:[1,1,0]
	v_mov_b32_e32 v64, v21
	v_mov_b32_e32 v53, v8
	v_mov_b32_e32 v75, v1
	v_mul_f32_e32 v48, v29, v29
	v_mov_b32_e32 v50, v28
	v_mov_b32_e32 v52, v20
	v_mov_b32_e32 v74, v17
	v_add_f32_e32 v46, v46, v39
	v_pk_mul_f32 v[64:65], v[64:65], v[64:65]
	v_mov_b32_e32 v49, v81
	v_mov_b32_e32 v67, v15
	v_mov_b32_e32 v69, v10
	v_mov_b32_e32 v73, v0
	v_mov_b32_e32 v66, v30
	v_mov_b32_e32 v68, v22
	v_mov_b32_e32 v72, v16
	v_pk_mul_f32 v[74:75], v[74:75], v[74:75]
	v_pk_fma_f32 v[46:47], v[26:27], v[26:27], v[46:47] op_sel_hi:[1,1,0]
	v_pk_fma_f32 v[48:49], v[50:51], v[50:51], v[48:49]
	v_pk_fma_f32 v[50:51], v[52:53], v[52:53], v[64:65]
	v_mov_b32_e32 v71, v11
	v_mov_b32_e32 v77, v2
	v_mov_b32_e32 v70, v23
	v_mov_b32_e32 v76, v18
	v_pk_fma_f32 v[52:53], v[72:73], v[72:73], v[74:75]
	v_mul_f32_e32 v46, v31, v31
	v_pk_fma_f32 v[48:49], v[66:67], v[66:67], v[48:49]
	v_pk_fma_f32 v[50:51], v[68:69], v[68:69], v[50:51]
	v_mov_b32_e32 v79, v3
	v_mov_b32_e32 v78, v19
	v_pk_fma_f32 v[52:53], v[76:77], v[76:77], v[52:53]
	v_pk_add_f32 v[46:47], v[46:47], v[48:49]
	v_pk_fma_f32 v[48:49], v[70:71], v[70:71], v[50:51]
	v_cndmask_b32_e32 v35, v56, v58, vcc
	v_pk_fma_f32 v[50:51], v[78:79], v[78:79], v[52:53]
	v_pk_add_f32 v[46:47], v[46:47], v[48:49]
	v_lshlrev_b32_e32 v35, 2, v35
	v_pk_add_f32 v[46:47], v[46:47], v[50:51]
	ds_bpermute_b32 v39, v35, v47
	v_mul_f32_e32 v80, v5, v5
	v_pk_fma_f32 v[50:51], v[4:5], v[4:5], v[80:81] op_sel_hi:[1,1,0]
	v_mul_f32_e32 v48, v7, v7
	v_pk_fma_f32 v[50:51], v[6:7], v[6:7], v[50:51]
	v_cmp_lt_i32_e32 vcc, v59, v57
	v_pk_add_f32 v[48:49], v[48:49], v[50:51] op_sel_hi:[0,1]
	s_waitcnt lgkmcnt(0)
	v_mov_b32_e32 v49, v39
	v_cndmask_b32_e32 v37, v56, v59, vcc
	v_lshlrev_b32_e32 v37, 2, v37
	v_pk_add_f32 v[46:47], v[46:47], v[48:49]
	ds_bpermute_b32 v49, v37, v47
	ds_bpermute_b32 v48, v35, v46
	v_cmp_lt_i32_e32 vcc, v60, v57
	v_lshl_add_u64 v[52:53], v[42:43], 0, s[6:7]
	s_waitcnt lgkmcnt(0)
	v_pk_add_f32 v[46:47], v[46:47], v[48:49]
	v_cndmask_b32_e32 v35, v56, v60, vcc
	v_lshlrev_b32_e32 v35, 2, v35
	ds_bpermute_b32 v49, v35, v47
	ds_bpermute_b32 v48, v37, v46
	v_cmp_lt_i32_e32 vcc, v61, v57
	s_waitcnt lgkmcnt(0)
	v_pk_add_f32 v[46:47], v[46:47], v[48:49]
	v_cndmask_b32_e32 v37, v56, v61, vcc
	v_lshlrev_b32_e32 v37, 2, v37
	ds_bpermute_b32 v49, v37, v47
	ds_bpermute_b32 v48, v35, v46
	v_cmp_lt_i32_e32 vcc, v62, v57
	s_waitcnt lgkmcnt(0)
	v_pk_add_f32 v[46:47], v[46:47], v[48:49]
	v_cndmask_b32_e32 v35, v56, v62, vcc
	v_lshlrev_b32_e32 v35, 2, v35
	ds_bpermute_b32 v49, v35, v47
	ds_bpermute_b32 v48, v37, v46
	v_cmp_lt_i32_e32 vcc, v63, v57
	s_waitcnt lgkmcnt(0)
	v_pk_add_f32 v[46:47], v[46:47], v[48:49]
	v_cndmask_b32_e32 v37, v56, v63, vcc
	v_lshlrev_b32_e32 v37, 2, v37
	ds_bpermute_b32 v51, v37, v47
	ds_bpermute_b32 v50, v35, v46
	v_lshl_add_u64 v[48:49], v[42:43], 0, s[4:5]
	v_lshl_add_u64 v[42:43], v[42:43], 0, v[44:45]
	s_waitcnt lgkmcnt(0)
	v_pk_add_f32 v[50:51], v[46:47], v[50:51]
	ds_bpermute_b32 v35, v37, v50
	v_lshl_add_u64 v[46:47], v[42:43], 0, s[8:9]
.LBB0_89:
	s_andn2_saveexec_b64 s[0:1], s[0:1]
	s_cbranch_execz .LBB0_86
	v_mov_b32_e32 v0, s18
	ds_read_b64 v[0:1], v0
	v_ashrrev_i32_e32 v45, 31, v44
	v_lshlrev_b64 v[2:3], 12, v[44:45]
	s_waitcnt lgkmcnt(0)
	v_add_co_u32_e32 v0, vcc, v0, v2
	v_addc_co_u32_e32 v1, vcc, v1, v3, vcc
	v_add_co_u32_e32 v4, vcc, v0, v32
	v_addc_co_u32_e32 v5, vcc, v1, v33, vcc
	v_add_co_u32_e32 v46, vcc, s17, v4
	flat_load_dwordx4 v[24:27], v[4:5] nt
	flat_load_dwordx4 v[12:15], v[4:5] offset:1024 nt
	flat_load_dwordx4 v[8:11], v[4:5] offset:2048 nt
	flat_load_dwordx4 v[0:3], v[4:5] offset:3072 nt
	v_addc_co_u32_e32 v47, vcc, 0, v5, vcc
	flat_load_dwordx4 v[28:31], v[46:47] nt
	flat_load_dwordx4 v[20:23], v[46:47] offset:1024 nt
	flat_load_dwordx4 v[4:7], v[46:47] offset:3072 nt
	flat_load_dwordx4 v[16:19], v[46:47] offset:2048 nt
	v_cmp_lt_i32_e32 vcc, v58, v57
	s_waitcnt vmcnt(0) lgkmcnt(0)
	v_pk_mul_f32 v[48:49], v[24:25], v[24:25]
	v_mul_f32_e32 v50, v12, v12
	v_mov_b32_e32 v51, v14
	v_pk_mul_f32 v[46:47], v[26:27], v[26:27]
	v_mov_b32_e32 v65, v9
	v_add_f32_e32 v39, v48, v49
	v_pk_fma_f32 v[80:81], v[12:13], v[12:13], v[50:51] op_sel_hi:[1,1,0]
	v_mov_b32_e32 v64, v21
	v_mov_b32_e32 v53, v8
	v_mov_b32_e32 v75, v1
	v_mul_f32_e32 v48, v29, v29
	v_mov_b32_e32 v50, v28
	v_mov_b32_e32 v52, v20
	v_mov_b32_e32 v74, v17
	v_add_f32_e32 v46, v46, v39
	v_pk_mul_f32 v[64:65], v[64:65], v[64:65]
	v_mov_b32_e32 v49, v81
	v_mov_b32_e32 v67, v15
	v_mov_b32_e32 v69, v10
	v_mov_b32_e32 v73, v0
	v_mov_b32_e32 v66, v30
	v_mov_b32_e32 v68, v22
	v_mov_b32_e32 v72, v16
	v_pk_mul_f32 v[74:75], v[74:75], v[74:75]
	v_pk_fma_f32 v[46:47], v[26:27], v[26:27], v[46:47] op_sel_hi:[1,1,0]
	v_pk_fma_f32 v[48:49], v[50:51], v[50:51], v[48:49]
	v_pk_fma_f32 v[50:51], v[52:53], v[52:53], v[64:65]
	v_mov_b32_e32 v71, v11
	v_mov_b32_e32 v77, v2
	v_mov_b32_e32 v70, v23
	v_mov_b32_e32 v76, v18
	v_pk_fma_f32 v[52:53], v[72:73], v[72:73], v[74:75]
	v_mul_f32_e32 v46, v31, v31
	v_pk_fma_f32 v[48:49], v[66:67], v[66:67], v[48:49]
	v_pk_fma_f32 v[50:51], v[68:69], v[68:69], v[50:51]
	v_mov_b32_e32 v79, v3
	v_mov_b32_e32 v78, v19
	v_pk_fma_f32 v[52:53], v[76:77], v[76:77], v[52:53]
	v_pk_add_f32 v[46:47], v[46:47], v[48:49]
	v_pk_fma_f32 v[48:49], v[70:71], v[70:71], v[50:51]
	v_cndmask_b32_e32 v35, v56, v58, vcc
	v_pk_fma_f32 v[50:51], v[78:79], v[78:79], v[52:53]
	v_pk_add_f32 v[46:47], v[46:47], v[48:49]
	v_lshlrev_b32_e32 v35, 2, v35
	v_pk_add_f32 v[46:47], v[46:47], v[50:51]
	ds_bpermute_b32 v39, v35, v47
	v_mul_f32_e32 v80, v5, v5
	v_pk_fma_f32 v[50:51], v[4:5], v[4:5], v[80:81] op_sel_hi:[1,1,0]
	v_mul_f32_e32 v48, v7, v7
	v_pk_fma_f32 v[50:51], v[6:7], v[6:7], v[50:51]
	v_cmp_lt_i32_e32 vcc, v59, v57
	v_pk_add_f32 v[48:49], v[48:49], v[50:51] op_sel_hi:[0,1]
	s_waitcnt lgkmcnt(0)
	v_mov_b32_e32 v49, v39
	v_cndmask_b32_e32 v37, v56, v59, vcc
	v_lshlrev_b32_e32 v37, 2, v37
	v_pk_add_f32 v[46:47], v[46:47], v[48:49]
	ds_bpermute_b32 v49, v37, v47
	ds_bpermute_b32 v48, v35, v46
	v_cmp_lt_i32_e32 vcc, v60, v57
	s_waitcnt lgkmcnt(0)
	v_pk_add_f32 v[46:47], v[46:47], v[48:49]
	v_cndmask_b32_e32 v35, v56, v60, vcc
	v_lshlrev_b32_e32 v35, 2, v35
	ds_bpermute_b32 v49, v35, v47
	ds_bpermute_b32 v48, v37, v46
	v_cmp_lt_i32_e32 vcc, v61, v57
	s_waitcnt lgkmcnt(0)
	v_pk_add_f32 v[46:47], v[46:47], v[48:49]
	v_cndmask_b32_e32 v37, v56, v61, vcc
	v_lshlrev_b32_e32 v37, 2, v37
	ds_bpermute_b32 v49, v37, v47
	ds_bpermute_b32 v48, v35, v46
	v_cmp_lt_i32_e32 vcc, v62, v57
	s_waitcnt lgkmcnt(0)
	v_pk_add_f32 v[46:47], v[46:47], v[48:49]
	v_cndmask_b32_e32 v35, v56, v62, vcc
	v_lshlrev_b32_e32 v35, 2, v35
	ds_bpermute_b32 v49, v35, v47
	ds_bpermute_b32 v48, v37, v46
	v_cmp_lt_i32_e32 vcc, v63, v57
	v_ashrrev_i32_e32 v37, 12, v44
	v_lshlrev_b64 v[44:45], 11, v[44:45]
	v_cndmask_b32_e32 v39, v56, v63, vcc
	v_lshlrev_b32_e32 v39, 2, v39
	s_waitcnt lgkmcnt(0)
	v_pk_add_f32 v[46:47], v[46:47], v[48:49]
	ds_bpermute_b32 v51, v39, v47
	ds_bpermute_b32 v50, v35, v46
	v_mul_i32_i24_e32 v48, 0x1800, v37
	v_ashrrev_i32_e32 v49, 31, v48
	v_lshl_add_u64 v[52:53], v[48:49], 2, v[42:43]
	v_lshl_add_u64 v[42:43], v[42:43], 0, v[44:45]
	s_waitcnt lgkmcnt(0)
	v_pk_add_f32 v[50:51], v[46:47], v[50:51]
	ds_bpermute_b32 v35, v39, v50
	v_lshl_add_u64 v[48:49], v[52:53], 0, s[10:11]
	v_lshl_add_u64 v[52:53], v[52:53], 0, s[12:13]
	v_lshl_add_u64 v[46:47], v[42:43], 0, s[8:9]
	s_branch .LBB0_86

.LBB0_146:
	s_cmp_eq_u32 s67, 4
	s_mov_b64 s[4:5], -1
	s_cbranch_scc0 .LBB0_161
	v_mov_b32_e32 v0, s19
	ds_read_b64 v[0:1], v0
	s_waitcnt lgkmcnt(0)
	s_barrier
	v_readfirstlane_b32 s6, v0
	v_readfirstlane_b32 s36, v1
	s_and_saveexec_b64 s[4:5], s[0:1]
	s_cbranch_execz .LBB0_149
	v_mov_b32_e32 v0, s44
	ds_read2_b64 v[0:3], v0 offset1:1
	s_lshl_b32 s27, s26, 1
	v_and_or_b32 v4, s27, 2, v133
	v_lshlrev_b32_e32 v134, 2, v4
	s_waitcnt lgkmcnt(0)
	v_add_co_u32_e32 v0, vcc, v0, v134
	v_addc_co_u32_e32 v1, vcc, v1, v135, vcc
	flat_load_dword v0, v[0:1]
	s_waitcnt vmcnt(0) lgkmcnt(0)
	v_mul_f32_e32 v4, v0, v164
	v_mul_f32_e32 v0, 0x3fb8aa3b, v4
	v_fma_f32 v1, v4, s45, -v0
	v_rndne_f32_e32 v5, v0
	v_fmac_f32_e32 v1, 0x32a5705f, v4
	v_sub_f32_e32 v0, v0, v5
	v_add_f32_e32 v0, v0, v1
	v_cvt_i32_f32_e32 v5, v5
	v_exp_f32_e32 v6, v0
	v_add_co_u32_e32 v0, vcc, v2, v134
	v_addc_co_u32_e32 v1, vcc, v3, v135, vcc
	v_cmp_ngt_f32_e32 vcc, s46, v4
	v_ldexp_f32 v2, v6, v5
	s_nop 0
	v_cndmask_b32_e32 v2, 0, v2, vcc
	v_cmp_nlt_f32_e32 vcc, s47, v4
	s_nop 1
	v_cndmask_b32_e32 v2, v167, v2, vcc
	ds_write_b32 v165, v2
	flat_load_dword v0, v[0:1]
	s_waitcnt vmcnt(0) lgkmcnt(0)
	v_mul_f32_e32 v0, v0, v166
	v_mul_f32_e32 v1, 0x3fb8aa3b, v0
	v_fma_f32 v2, v0, s45, -v1
	v_rndne_f32_e32 v3, v1
	v_fmac_f32_e32 v2, 0x32a5705f, v0
	v_sub_f32_e32 v1, v1, v3
	v_add_f32_e32 v1, v1, v2
	v_cvt_i32_f32_e32 v3, v3
	v_exp_f32_e32 v1, v1
	v_cmp_ngt_f32_e32 vcc, s46, v0
	v_ldexp_f32 v1, v1, v3
	s_nop 0
	v_cndmask_b32_e32 v1, 0, v1, vcc
	v_cmp_nlt_f32_e32 vcc, s47, v0
	s_nop 1
	v_cndmask_b32_e32 v0, v167, v1, vcc
	ds_write_b32 v165, v0 offset:1024

.LBB0_156:
	v_ashrrev_i32_e32 v136, 6, v172
	v_bfe_u32 v137, v136, 1, 1
	v_mul_lo_u32 v136, v136, s55
	s_and_b64 s[68:69], exec, s[28:29]
	v_add_u32_e32 v142, s27, v136
	v_lshlrev_b32_e32 v150, 3, v172
	s_cselect_b32 s6, 8, 12
	v_mov_b32_e32 v128, s19
	s_lshl_b32 s37, s26, 1
	v_lshl_add_u32 v148, v169, 3, v142
	v_and_b32_e32 v140, 0x78, v150
	v_pk_mul_f32 v[116:117], v[116:117], s[18:19] op_sel_hi:[1,0]
	v_pk_mul_f32 v[118:119], v[118:119], s[18:19] op_sel_hi:[1,0]
	v_pk_mul_f32 v[84:85], v[84:85], s[18:19] op_sel_hi:[1,0]
	v_pk_mul_f32 v[86:87], v[86:87], s[18:19] op_sel_hi:[1,0]
	ds_read_b64 v[128:129], v128
	s_ashr_i32 s6, s66, s6
	v_and_or_b32 v149, s37, 2, v137
	v_lshlrev_b32_e32 v138, 9, v137
	v_mad_u32_u24 v152, v170, s57, v148
	v_lshlrev_b32_e32 v139, 2, v140
	v_cvt_pk_bf16_f32 v116, v116, v117
	v_cvt_pk_bf16_f32 v117, v118, v119
	v_pk_mul_f32 v[118:119], v[124:125], s[18:19] op_sel_hi:[1,0]
	v_pk_mul_f32 v[124:125], v[126:127], s[18:19] op_sel_hi:[1,0]
	v_cvt_pk_bf16_f32 v84, v84, v85
	v_cvt_pk_bf16_f32 v85, v86, v87
	v_pk_mul_f32 v[86:87], v[92:93], s[18:19] op_sel_hi:[1,0]
	v_pk_mul_f32 v[92:93], v[94:95], s[18:19] op_sel_hi:[1,0]
	v_add3_u32 v144, s3, v138, v139
	v_add3_u32 v145, s56, v138, v139
	v_lshl_or_b32 v138, s6, 2, v149
	v_cvt_pk_bf16_f32 v118, v118, v119
	v_cvt_pk_bf16_f32 v119, v124, v125
	v_cvt_pk_bf16_f32 v86, v86, v87
	v_cvt_pk_bf16_f32 v87, v92, v93
	v_add_u32_e32 v92, 0x1000, v152
	v_ashrrev_i32_e32 v139, 31, v138
	ds_write2_b64 v152, v[116:117], v[118:119] offset1:4
	v_pk_mul_f32 v[116:117], v[120:121], s[18:19] op_sel_hi:[1,0]
	v_pk_mul_f32 v[118:119], v[122:123], s[18:19] op_sel_hi:[1,0]
	v_pk_mul_f32 v[112:113], v[112:113], s[18:19] op_sel_hi:[1,0]
	v_pk_mul_f32 v[114:115], v[114:115], s[18:19] op_sel_hi:[1,0]
	v_pk_mul_f32 v[108:109], v[108:109], s[18:19] op_sel_hi:[1,0]
	v_pk_mul_f32 v[110:111], v[110:111], s[18:19] op_sel_hi:[1,0]
	v_pk_mul_f32 v[104:105], v[104:105], s[18:19] op_sel_hi:[1,0]
	v_pk_mul_f32 v[106:107], v[106:107], s[18:19] op_sel_hi:[1,0]
	v_pk_mul_f32 v[100:101], v[100:101], s[18:19] op_sel_hi:[1,0]
	v_pk_mul_f32 v[102:103], v[102:103], s[18:19] op_sel_hi:[1,0]
	v_pk_mul_f32 v[96:97], v[96:97], s[18:19] op_sel_hi:[1,0]
	v_pk_mul_f32 v[98:99], v[98:99], s[18:19] op_sel_hi:[1,0]
	ds_write2_b64 v92, v[84:85], v[86:87] offset0:32 offset1:36
	v_pk_mul_f32 v[84:85], v[88:89], s[18:19] op_sel_hi:[1,0]
	v_pk_mul_f32 v[86:87], v[90:91], s[18:19] op_sel_hi:[1,0]
	v_pk_mul_f32 v[80:81], v[80:81], s[18:19] op_sel_hi:[1,0]
	v_pk_mul_f32 v[82:83], v[82:83], s[18:19] op_sel_hi:[1,0]
	v_pk_mul_f32 v[76:77], v[76:77], s[18:19] op_sel_hi:[1,0]
	v_pk_mul_f32 v[78:79], v[78:79], s[18:19] op_sel_hi:[1,0]
	v_pk_mul_f32 v[72:73], v[72:73], s[18:19] op_sel_hi:[1,0]
	v_pk_mul_f32 v[74:75], v[74:75], s[18:19] op_sel_hi:[1,0]
	v_pk_mul_f32 v[68:69], v[68:69], s[18:19] op_sel_hi:[1,0]
	v_pk_mul_f32 v[70:71], v[70:71], s[18:19] op_sel_hi:[1,0]
	v_pk_mul_f32 v[64:65], v[64:65], s[18:19] op_sel_hi:[1,0]
	v_pk_mul_f32 v[66:67], v[66:67], s[18:19] op_sel_hi:[1,0]
	v_lshl_add_u32 v146, v140, 1, v142
	v_lshlrev_b64 v[138:139], 7, v[138:139]
	v_cvt_pk_bf16_f32 v116, v116, v117
	v_cvt_pk_bf16_f32 v117, v118, v119
	v_cvt_pk_bf16_f32 v112, v112, v113
	v_cvt_pk_bf16_f32 v113, v114, v115
	v_cvt_pk_bf16_f32 v108, v108, v109
	v_cvt_pk_bf16_f32 v109, v110, v111
	v_cvt_pk_bf16_f32 v104, v104, v105
	v_cvt_pk_bf16_f32 v105, v106, v107
	v_cvt_pk_bf16_f32 v100, v100, v101
	v_cvt_pk_bf16_f32 v101, v102, v103
	v_cvt_pk_bf16_f32 v96, v96, v97
	v_cvt_pk_bf16_f32 v97, v98, v99
	v_cvt_pk_bf16_f32 v84, v84, v85
	v_cvt_pk_bf16_f32 v85, v86, v87
	v_cvt_pk_bf16_f32 v80, v80, v81
	v_cvt_pk_bf16_f32 v81, v82, v83
	v_cvt_pk_bf16_f32 v76, v76, v77
	v_cvt_pk_bf16_f32 v77, v78, v79
	v_cvt_pk_bf16_f32 v72, v72, v73
	v_cvt_pk_bf16_f32 v73, v74, v75
	v_cvt_pk_bf16_f32 v68, v68, v69
	v_cvt_pk_bf16_f32 v69, v70, v71
	v_cvt_pk_bf16_f32 v64, v64, v65
	v_cvt_pk_bf16_f32 v65, v66, v67
	v_or_b32_e32 v147, v138, v134
	v_and_b32_e32 v138, 24, v150
	v_lshlrev_b32_e32 v150, 8, v149
	v_mov_b32_e32 v151, v135
	ds_write2_b64 v152, v[116:117], v[112:113] offset0:8 offset1:12
	ds_write2_b64 v152, v[108:109], v[104:105] offset0:16 offset1:20
	ds_write2_b64 v152, v[100:101], v[96:97] offset0:24 offset1:28
	ds_write2_b64 v92, v[84:85], v[80:81] offset0:40 offset1:44
	ds_write2_b64 v92, v[76:77], v[72:73] offset0:48 offset1:52
	ds_write2_b64 v92, v[68:69], v[64:65] offset0:56 offset1:60
	v_mad_u32_u24 v64, v169, s57, v146
	s_waitcnt lgkmcnt(8)
	v_lshl_add_u64 v[130:131], v[128:129], 0, s[42:43]
	v_lshl_add_u64 v[136:137], v[128:129], 0, s[4:5]
	v_add_co_u32_e32 v128, vcc, v128, v150
	v_addc_co_u32_e32 v129, vcc, v129, v151, vcc
	ds_read_b128 v[64:67], v64
	v_ashrrev_i32_e32 v141, 31, v171
	v_or_b32_e32 v140, v171, v140
	v_mad_u32_u24 v142, v138, s57, v142
	v_lshl_add_u64 v[128:129], v[134:135], 1, v[128:129]
	v_lshlrev_b32_e32 v134, 1, v138
	v_or_b32_e32 v138, v147, v169
	v_lshl_add_u64 v[140:141], v[140:141], 0, s[38:39]
	v_lshlrev_b64 v[68:69], s36, v[138:139]
	v_add_co_u32_e32 v84, vcc, v68, v140
	v_addc_co_u32_e32 v85, vcc, v69, v141, vcc
	ds_read_b128 v[68:71], v144
	ds_read_b128 v[72:75], v145
	ds_read_b128 v[76:79], v145 offset:16
	s_waitcnt lgkmcnt(3)
	v_and_b32_e32 v87, 0xffff0000, v64
	v_lshlrev_b32_e32 v86, 16, v64
	ds_read_b128 v[80:83], v144 offset:16
	s_waitcnt lgkmcnt(3)
	v_pk_mul_f32 v[68:69], v[68:69], v[86:87]
	v_and_b32_e32 v143, 63, v172
	v_cvt_pk_bf16_f32 v64, v68, v69
	s_waitcnt lgkmcnt(2)
	v_pk_mul_f32 v[68:69], v[72:73], v[86:87]
	v_and_b32_e32 v73, 0xffff0000, v65
	v_lshlrev_b32_e32 v72, 16, v65
	v_pk_mul_f32 v[70:71], v[70:71], v[72:73]
	v_cvt_pk_bf16_f32 v68, v68, v69
	v_cvt_pk_bf16_f32 v65, v70, v71
	v_pk_mul_f32 v[70:71], v[74:75], v[72:73]
	v_add_co_u32_e32 v128, vcc, v128, v134
	v_addc_co_u32_e32 v129, vcc, v129, v135, vcc
	v_cvt_pk_bf16_f32 v69, v70, v71
	v_and_b32_e32 v71, 0xffff0000, v66
	v_lshlrev_b32_e32 v70, 16, v66
	s_waitcnt lgkmcnt(0)
	v_pk_mul_f32 v[72:73], v[80:81], v[70:71]
	v_pk_mul_f32 v[70:71], v[76:77], v[70:71]
	v_cvt_pk_bf16_f32 v66, v72, v73
	v_and_b32_e32 v73, 0xffff0000, v67
	v_lshlrev_b32_e32 v72, 16, v67
	v_pk_mul_f32 v[74:75], v[82:83], v[72:73]
	v_pk_mul_f32 v[72:73], v[78:79], v[72:73]
	v_cvt_pk_bf16_f32 v70, v70, v71
	v_cvt_pk_bf16_f32 v71, v72, v73
	v_lshlrev_b64 v[72:73], 1, v[84:85]
	v_cvt_pk_bf16_f32 v67, v74, v75
	v_add_co_u32_e32 v74, vcc, v136, v72
	v_addc_co_u32_e32 v75, vcc, v137, v73, vcc
	flat_store_dwordx4 v[74:75], v[64:67]
	v_lshl_add_u64 v[128:129], v[128:129], 0, s[16:17]
	s_andn2_b64 vcc, exec, s[34:35]
	v_lshl_add_u64 v[64:65], v[130:131], 0, v[72:73]
	flat_store_dwordx4 v[64:65], v[68:71]
	v_or_b32_e32 v64, 64, v143
	s_nop 0
	v_lshrrev_b32_e32 v71, 4, v64
	v_mad_u32_u24 v65, v71, s57, v146
	ds_read_b128 v[66:69], v65
	v_or_b32_e32 v138, v147, v71
	v_lshlrev_b64 v[72:73], s36, v[138:139]
	v_lshl_add_u64 v[88:89], v[72:73], 0, v[140:141]
	ds_read_b128 v[72:75], v144
	ds_read_b128 v[76:79], v145
	ds_read_b128 v[80:83], v145 offset:16
	s_waitcnt lgkmcnt(0)
	v_and_b32_e32 v91, 0xffff0000, v66
	v_lshlrev_b32_e32 v90, 16, v66
	ds_read_b128 v[84:87], v144 offset:16
	v_pk_mul_f32 v[72:73], v[72:73], v[90:91]
	v_or_b32_e32 v65, 0x80, v143
	v_cvt_pk_bf16_f32 v66, v72, v73
	v_pk_mul_f32 v[72:73], v[76:77], v[90:91]
	v_and_b32_e32 v77, 0xffff0000, v67
	v_lshlrev_b32_e32 v76, 16, v67
	v_pk_mul_f32 v[74:75], v[74:75], v[76:77]
	v_cvt_pk_bf16_f32 v72, v72, v73
	v_cvt_pk_bf16_f32 v67, v74, v75
	v_pk_mul_f32 v[74:75], v[78:79], v[76:77]
	s_nop 0
	v_cvt_pk_bf16_f32 v73, v74, v75
	v_and_b32_e32 v75, 0xffff0000, v68
	v_lshlrev_b32_e32 v74, 16, v68
	s_waitcnt lgkmcnt(0)
	v_pk_mul_f32 v[76:77], v[84:85], v[74:75]
	v_pk_mul_f32 v[74:75], v[80:81], v[74:75]
	v_cvt_pk_bf16_f32 v68, v76, v77
	v_and_b32_e32 v77, 0xffff0000, v69
	v_lshlrev_b32_e32 v76, 16, v69
	v_pk_mul_f32 v[78:79], v[86:87], v[76:77]
	v_pk_mul_f32 v[76:77], v[82:83], v[76:77]
	v_cvt_pk_bf16_f32 v74, v74, v75
	v_cvt_pk_bf16_f32 v75, v76, v77
	v_lshlrev_b64 v[76:77], 1, v[88:89]
	v_cvt_pk_bf16_f32 v69, v78, v79
	v_lshl_add_u64 v[78:79], v[136:137], 0, v[76:77]
	flat_store_dwordx4 v[78:79], v[66:69]
	s_nop 1
	v_lshl_add_u64 v[66:67], v[130:131], 0, v[76:77]
	flat_store_dwordx4 v[66:67], v[72:75]
	s_nop 1
	v_lshrrev_b32_e32 v72, 4, v65
	v_mad_u32_u24 v66, v72, s57, v146
	ds_read_b128 v[66:69], v66
	v_or_b32_e32 v138, v147, v72
	v_lshlrev_b64 v[74:75], s36, v[138:139]
	v_lshl_add_u64 v[90:91], v[74:75], 0, v[140:141]
	ds_read_b128 v[74:77], v144
	ds_read_b128 v[78:81], v145
	ds_read_b128 v[82:85], v145 offset:16
	s_waitcnt lgkmcnt(0)
	v_and_b32_e32 v93, 0xffff0000, v66
	v_lshlrev_b32_e32 v92, 16, v66
	ds_read_b128 v[86:89], v144 offset:16
	v_pk_mul_f32 v[74:75], v[74:75], v[92:93]
	s_nop 0
	v_cvt_pk_bf16_f32 v66, v74, v75
	v_pk_mul_f32 v[74:75], v[78:79], v[92:93]
	v_and_b32_e32 v79, 0xffff0000, v67
	v_lshlrev_b32_e32 v78, 16, v67
	v_pk_mul_f32 v[76:77], v[76:77], v[78:79]
	v_cvt_pk_bf16_f32 v74, v74, v75
	v_cvt_pk_bf16_f32 v67, v76, v77
	v_pk_mul_f32 v[76:77], v[80:81], v[78:79]
	s_nop 0
	v_cvt_pk_bf16_f32 v75, v76, v77
	v_and_b32_e32 v77, 0xffff0000, v68
	v_lshlrev_b32_e32 v76, 16, v68
	s_waitcnt lgkmcnt(0)
	v_pk_mul_f32 v[78:79], v[86:87], v[76:77]
	v_pk_mul_f32 v[76:77], v[82:83], v[76:77]
	v_cvt_pk_bf16_f32 v68, v78, v79
	v_and_b32_e32 v79, 0xffff0000, v69
	v_lshlrev_b32_e32 v78, 16, v69
	v_pk_mul_f32 v[80:81], v[88:89], v[78:79]
	v_pk_mul_f32 v[78:79], v[84:85], v[78:79]
	v_cvt_pk_bf16_f32 v76, v76, v77
	v_cvt_pk_bf16_f32 v77, v78, v79
	v_lshlrev_b64 v[78:79], 1, v[90:91]
	v_cvt_pk_bf16_f32 v69, v80, v81
	v_lshl_add_u64 v[80:81], v[136:137], 0, v[78:79]
	flat_store_dwordx4 v[80:81], v[66:69]
	s_nop 1
	v_lshl_add_u64 v[66:67], v[130:131], 0, v[78:79]
	flat_store_dwordx4 v[66:67], v[74:77]
	v_or_b32_e32 v66, 0xc0, v143
	v_lshrrev_b32_e32 v73, 4, v66
	v_mad_u32_u24 v67, v73, s57, v146
	ds_read_b128 v[74:77], v67
	ds_read_b128 v[78:81], v144
	ds_read_b128 v[82:85], v145
	ds_read_b128 v[86:89], v145 offset:16
	ds_read_b128 v[90:93], v144 offset:16
	v_or_b32_e32 v138, v147, v73
	v_lshlrev_b64 v[68:69], s36, v[138:139]
	s_waitcnt lgkmcnt(0)
	v_and_b32_e32 v95, 0xffff0000, v74
	v_lshlrev_b32_e32 v94, 16, v74
	v_pk_mul_f32 v[78:79], v[78:79], v[94:95]
	v_lshl_add_u64 v[68:69], v[68:69], 0, v[140:141]
	v_cvt_pk_bf16_f32 v74, v78, v79
	v_pk_mul_f32 v[78:79], v[82:83], v[94:95]
	v_and_b32_e32 v83, 0xffff0000, v75
	v_lshlrev_b32_e32 v82, 16, v75
	v_pk_mul_f32 v[80:81], v[80:81], v[82:83]
	v_cvt_pk_bf16_f32 v78, v78, v79
	v_cvt_pk_bf16_f32 v75, v80, v81
	v_pk_mul_f32 v[80:81], v[84:85], v[82:83]
	v_lshlrev_b64 v[68:69], 1, v[68:69]
	v_cvt_pk_bf16_f32 v79, v80, v81
	v_and_b32_e32 v81, 0xffff0000, v76
	v_lshlrev_b32_e32 v80, 16, v76
	v_pk_mul_f32 v[82:83], v[90:91], v[80:81]
	v_pk_mul_f32 v[80:81], v[86:87], v[80:81]
	v_cvt_pk_bf16_f32 v76, v82, v83
	v_and_b32_e32 v83, 0xffff0000, v77
	v_lshlrev_b32_e32 v82, 16, v77
	v_pk_mul_f32 v[84:85], v[92:93], v[82:83]
	v_pk_mul_f32 v[82:83], v[88:89], v[82:83]
	v_cvt_pk_bf16_f32 v80, v80, v81
	v_cvt_pk_bf16_f32 v77, v84, v85
	v_cvt_pk_bf16_f32 v81, v82, v83
	v_lshl_add_u64 v[82:83], v[136:137], 0, v[68:69]
	v_or_b32_e32 v67, 0x100, v143
	flat_store_dwordx4 v[82:83], v[74:77]
	v_lshl_add_u64 v[68:69], v[130:131], 0, v[68:69]
	flat_store_dwordx4 v[68:69], v[78:81]
	v_lshrrev_b32_e32 v74, 4, v67
	v_mad_u32_u24 v68, v74, s57, v146
	ds_read_b128 v[76:79], v68
	ds_read_b128 v[80:83], v144
	ds_read_b128 v[84:87], v145
	ds_read_b128 v[88:91], v145 offset:16
	ds_read_b128 v[92:95], v144 offset:16
	v_or_b32_e32 v138, v147, v74
	v_lshlrev_b64 v[68:69], s36, v[138:139]
	s_waitcnt lgkmcnt(0)
	v_and_b32_e32 v97, 0xffff0000, v76
	v_lshlrev_b32_e32 v96, 16, v76
	v_pk_mul_f32 v[80:81], v[80:81], v[96:97]
	v_lshl_add_u64 v[68:69], v[68:69], 0, v[140:141]
	v_cvt_pk_bf16_f32 v76, v80, v81
	v_pk_mul_f32 v[80:81], v[84:85], v[96:97]
	v_and_b32_e32 v85, 0xffff0000, v77
	v_lshlrev_b32_e32 v84, 16, v77
	v_pk_mul_f32 v[82:83], v[82:83], v[84:85]
	v_cvt_pk_bf16_f32 v80, v80, v81
	v_cvt_pk_bf16_f32 v77, v82, v83
	v_pk_mul_f32 v[82:83], v[86:87], v[84:85]
	v_lshlrev_b64 v[68:69], 1, v[68:69]
	v_cvt_pk_bf16_f32 v81, v82, v83
	v_and_b32_e32 v83, 0xffff0000, v78
	v_lshlrev_b32_e32 v82, 16, v78
	v_pk_mul_f32 v[84:85], v[92:93], v[82:83]
	v_pk_mul_f32 v[82:83], v[88:89], v[82:83]
	v_cvt_pk_bf16_f32 v78, v84, v85
	v_and_b32_e32 v85, 0xffff0000, v79
	v_lshlrev_b32_e32 v84, 16, v79
	v_pk_mul_f32 v[86:87], v[94:95], v[84:85]
	v_pk_mul_f32 v[84:85], v[90:91], v[84:85]
	v_cvt_pk_bf16_f32 v82, v82, v83
	v_cvt_pk_bf16_f32 v79, v86, v87
	v_cvt_pk_bf16_f32 v83, v84, v85
	v_lshl_add_u64 v[84:85], v[136:137], 0, v[68:69]
	v_lshl_add_u64 v[68:69], v[130:131], 0, v[68:69]
	flat_store_dwordx4 v[84:85], v[76:79]
	flat_store_dwordx4 v[68:69], v[80:83]
	v_or_b32_e32 v68, 0x140, v143
	v_lshrrev_b32_e32 v75, 4, v68
	v_mad_u32_u24 v69, v75, s57, v146
	ds_read_b128 v[76:79], v69
	v_or_b32_e32 v138, v147, v75
	v_lshlrev_b64 v[80:81], s36, v[138:139]
	v_lshl_add_u64 v[96:97], v[80:81], 0, v[140:141]
	ds_read_b128 v[80:83], v144
	ds_read_b128 v[84:87], v145
	ds_read_b128 v[88:91], v145 offset:16
	s_waitcnt lgkmcnt(0)
	v_and_b32_e32 v99, 0xffff0000, v76
	v_lshlrev_b32_e32 v98, 16, v76
	ds_read_b128 v[92:95], v144 offset:16
	v_pk_mul_f32 v[80:81], v[80:81], v[98:99]
	v_or_b32_e32 v69, 0x180, v143
	v_cvt_pk_bf16_f32 v76, v80, v81
	v_pk_mul_f32 v[80:81], v[84:85], v[98:99]
	v_and_b32_e32 v85, 0xffff0000, v77
	v_lshlrev_b32_e32 v84, 16, v77
	v_pk_mul_f32 v[82:83], v[82:83], v[84:85]
	v_cvt_pk_bf16_f32 v80, v80, v81
	v_cvt_pk_bf16_f32 v77, v82, v83
	v_pk_mul_f32 v[82:83], v[86:87], v[84:85]
	s_nop 0
	v_cvt_pk_bf16_f32 v81, v82, v83
	v_and_b32_e32 v83, 0xffff0000, v78
	v_lshlrev_b32_e32 v82, 16, v78
	s_waitcnt lgkmcnt(0)
	v_pk_mul_f32 v[84:85], v[92:93], v[82:83]
	v_pk_mul_f32 v[82:83], v[88:89], v[82:83]
	v_cvt_pk_bf16_f32 v78, v84, v85
	v_and_b32_e32 v85, 0xffff0000, v79
	v_lshlrev_b32_e32 v84, 16, v79
	v_pk_mul_f32 v[86:87], v[94:95], v[84:85]
	v_pk_mul_f32 v[84:85], v[90:91], v[84:85]
	v_cvt_pk_bf16_f32 v82, v82, v83
	v_cvt_pk_bf16_f32 v83, v84, v85
	v_lshlrev_b64 v[84:85], 1, v[96:97]
	v_cvt_pk_bf16_f32 v79, v86, v87
	v_lshl_add_u64 v[86:87], v[136:137], 0, v[84:85]
	flat_store_dwordx4 v[86:87], v[76:79]
	s_nop 1
	v_lshl_add_u64 v[76:77], v[130:131], 0, v[84:85]
	flat_store_dwordx4 v[76:77], v[80:83]
	v_lshrrev_b32_e32 v76, 4, v69
	v_mad_u32_u24 v70, v76, s57, v146
	ds_read_b128 v[78:81], v70
	v_or_b32_e32 v138, v147, v76
	v_lshlrev_b64 v[82:83], s36, v[138:139]
	v_lshl_add_u64 v[98:99], v[82:83], 0, v[140:141]
	ds_read_b128 v[82:85], v144
	ds_read_b128 v[86:89], v145
	ds_read_b128 v[90:93], v145 offset:16
	s_waitcnt lgkmcnt(0)
	v_and_b32_e32 v101, 0xffff0000, v78
	v_lshlrev_b32_e32 v100, 16, v78
	ds_read_b128 v[94:97], v144 offset:16
	v_pk_mul_f32 v[82:83], v[82:83], v[100:101]
	v_or_b32_e32 v70, 0x1c0, v143
	v_cvt_pk_bf16_f32 v78, v82, v83
	v_pk_mul_f32 v[82:83], v[86:87], v[100:101]
	v_and_b32_e32 v87, 0xffff0000, v79
	v_lshlrev_b32_e32 v86, 16, v79
	v_pk_mul_f32 v[84:85], v[84:85], v[86:87]
	v_cvt_pk_bf16_f32 v82, v82, v83
	v_cvt_pk_bf16_f32 v79, v84, v85
	v_pk_mul_f32 v[84:85], v[88:89], v[86:87]
	v_lshrrev_b32_e32 v77, 4, v70
	v_cvt_pk_bf16_f32 v83, v84, v85
	v_and_b32_e32 v85, 0xffff0000, v80
	v_lshlrev_b32_e32 v84, 16, v80
	s_waitcnt lgkmcnt(0)
	v_pk_mul_f32 v[86:87], v[94:95], v[84:85]
	v_pk_mul_f32 v[84:85], v[90:91], v[84:85]
	v_cvt_pk_bf16_f32 v80, v86, v87
	v_and_b32_e32 v87, 0xffff0000, v81
	v_lshlrev_b32_e32 v86, 16, v81
	v_pk_mul_f32 v[88:89], v[96:97], v[86:87]
	v_pk_mul_f32 v[86:87], v[92:93], v[86:87]
	v_cvt_pk_bf16_f32 v84, v84, v85
	v_cvt_pk_bf16_f32 v85, v86, v87
	v_lshlrev_b64 v[86:87], 1, v[98:99]
	v_cvt_pk_bf16_f32 v81, v88, v89
	v_lshl_add_u64 v[88:89], v[136:137], 0, v[86:87]
	flat_store_dwordx4 v[88:89], v[78:81]
	v_or_b32_e32 v138, v147, v77
	s_nop 0
	v_lshl_add_u64 v[78:79], v[130:131], 0, v[86:87]
	flat_store_dwordx4 v[78:79], v[82:85]
	v_mad_u32_u24 v78, v77, s57, v146
	ds_read_b128 v[78:81], v78
	v_lshlrev_b64 v[82:83], s36, v[138:139]
	v_lshl_add_u64 v[98:99], v[82:83], 0, v[140:141]
	ds_read_b128 v[82:85], v144
	ds_read_b128 v[86:89], v145
	ds_read_b128 v[90:93], v145 offset:16
	ds_read_b128 v[94:97], v144 offset:16
	s_waitcnt lgkmcnt(0)
	v_and_b32_e32 v101, 0xffff0000, v78
	v_lshlrev_b32_e32 v100, 16, v78
	v_pk_mul_f32 v[82:83], v[82:83], v[100:101]
	s_nop 0
	v_cvt_pk_bf16_f32 v78, v82, v83
	v_pk_mul_f32 v[82:83], v[86:87], v[100:101]
	v_and_b32_e32 v87, 0xffff0000, v79
	v_lshlrev_b32_e32 v86, 16, v79
	v_pk_mul_f32 v[84:85], v[84:85], v[86:87]
	v_cvt_pk_bf16_f32 v82, v82, v83
	v_cvt_pk_bf16_f32 v79, v84, v85
	v_pk_mul_f32 v[84:85], v[88:89], v[86:87]
	s_nop 0
	v_cvt_pk_bf16_f32 v83, v84, v85
	v_and_b32_e32 v85, 0xffff0000, v80
	v_lshlrev_b32_e32 v84, 16, v80
	v_pk_mul_f32 v[86:87], v[94:95], v[84:85]
	v_pk_mul_f32 v[84:85], v[90:91], v[84:85]
	v_cvt_pk_bf16_f32 v80, v86, v87
	v_and_b32_e32 v87, 0xffff0000, v81
	v_lshlrev_b32_e32 v86, 16, v81
	v_pk_mul_f32 v[88:89], v[96:97], v[86:87]
	v_pk_mul_f32 v[86:87], v[92:93], v[86:87]
	v_cvt_pk_bf16_f32 v84, v84, v85
	v_cvt_pk_bf16_f32 v85, v86, v87
	v_lshlrev_b64 v[86:87], 1, v[98:99]
	v_cvt_pk_bf16_f32 v81, v88, v89
	v_lshl_add_u64 v[88:89], v[136:137], 0, v[86:87]
	flat_store_dwordx4 v[88:89], v[78:81]
	s_nop 1
	v_cndmask_b32_e64 v80, 0, 1, s[34:35]
	v_lshl_add_u64 v[78:79], v[130:131], 0, v[86:87]
	v_cmp_ne_u32_e64 s[4:5], 1, v80
	flat_store_dwordx4 v[78:79], v[82:85]
	s_cbranch_vccnz .LBB0_158
	s_nop 0
	v_lshrrev_b32_e32 v82, 2, v143
	v_lshl_add_u32 v78, v82, 1, v142
	ds_read_u16 v79, v78
	ds_read_u16 v80, v78 offset:272
	ds_read_u16 v81, v78 offset:544
	ds_read_u16 v83, v78 offset:816
	ds_read_u16 v84, v78 offset:1088
	ds_read_u16 v85, v78 offset:1360
	ds_read_u16 v86, v78 offset:1632
	ds_read_u16 v87, v78 offset:1904
	v_or_b32_e32 v82, v168, v82
	s_waitcnt lgkmcnt(0)
	v_lshl_or_b32 v78, v80, 16, v79
	v_lshl_or_b32 v79, v83, 16, v81
	v_ashrrev_i32_e32 v83, 31, v82
	v_lshlrev_b64 v[82:83], 10, v[82:83]
	v_lshl_or_b32 v80, v85, 16, v84
	v_lshl_or_b32 v81, v87, 16, v86
	v_add_co_u32_e32 v82, vcc, v128, v82
	v_addc_co_u32_e32 v83, vcc, v129, v83, vcc
	flat_store_dwordx4 v[82:83], v[78:81]
	v_lshrrev_b32_e32 v82, 2, v64
	s_nop 0
	v_lshl_add_u32 v78, v82, 1, v142
	ds_read_u16 v79, v78
	ds_read_u16 v80, v78 offset:272
	ds_read_u16 v81, v78 offset:544
	ds_read_u16 v83, v78 offset:816
	ds_read_u16 v84, v78 offset:1088
	ds_read_u16 v85, v78 offset:1360
	ds_read_u16 v86, v78 offset:1632
	ds_read_u16 v87, v78 offset:1904
	v_or_b32_e32 v82, v168, v82
	s_waitcnt lgkmcnt(0)
	v_lshl_or_b32 v78, v80, 16, v79
	v_lshl_or_b32 v79, v83, 16, v81
	v_ashrrev_i32_e32 v83, 31, v82
	v_lshlrev_b64 v[82:83], 10, v[82:83]
	v_lshl_or_b32 v80, v85, 16, v84
	v_lshl_or_b32 v81, v87, 16, v86
	v_add_co_u32_e32 v82, vcc, v128, v82
	v_addc_co_u32_e32 v83, vcc, v129, v83, vcc
	flat_store_dwordx4 v[82:83], v[78:81]
	v_lshrrev_b32_e32 v82, 2, v65
	s_nop 0
	v_lshl_add_u32 v78, v82, 1, v142
	ds_read_u16 v79, v78
	ds_read_u16 v80, v78 offset:272
	ds_read_u16 v81, v78 offset:544
	ds_read_u16 v83, v78 offset:816
	ds_read_u16 v84, v78 offset:1088
	ds_read_u16 v85, v78 offset:1360
	ds_read_u16 v86, v78 offset:1632
	ds_read_u16 v87, v78 offset:1904
	v_or_b32_e32 v82, v168, v82
	s_waitcnt lgkmcnt(0)
	v_lshl_or_b32 v78, v80, 16, v79
	v_lshl_or_b32 v79, v83, 16, v81
	v_ashrrev_i32_e32 v83, 31, v82
	v_lshlrev_b64 v[82:83], 10, v[82:83]
	v_lshl_or_b32 v80, v85, 16, v84
	v_lshl_or_b32 v81, v87, 16, v86
	v_add_co_u32_e32 v82, vcc, v128, v82
	v_addc_co_u32_e32 v83, vcc, v129, v83, vcc
	flat_store_dwordx4 v[82:83], v[78:81]
	v_lshrrev_b32_e32 v82, 2, v66
	s_nop 0
	v_lshl_add_u32 v78, v82, 1, v142
	ds_read_u16 v79, v78
	ds_read_u16 v80, v78 offset:272
	ds_read_u16 v81, v78 offset:544
	ds_read_u16 v83, v78 offset:816
	ds_read_u16 v84, v78 offset:1088
	ds_read_u16 v85, v78 offset:1360
	ds_read_u16 v86, v78 offset:1632
	ds_read_u16 v87, v78 offset:1904
	v_or_b32_e32 v82, v168, v82
	s_waitcnt lgkmcnt(0)
	v_lshl_or_b32 v78, v80, 16, v79
	v_lshl_or_b32 v79, v83, 16, v81
	v_ashrrev_i32_e32 v83, 31, v82
	v_lshlrev_b64 v[82:83], 10, v[82:83]
	v_lshl_or_b32 v80, v85, 16, v84
	v_lshl_or_b32 v81, v87, 16, v86
	v_add_co_u32_e32 v82, vcc, v128, v82
	v_addc_co_u32_e32 v83, vcc, v129, v83, vcc
	flat_store_dwordx4 v[82:83], v[78:81]
	v_lshrrev_b32_e32 v82, 2, v67
	s_nop 0
	v_lshl_add_u32 v78, v82, 1, v142
	ds_read_u16 v79, v78
	ds_read_u16 v80, v78 offset:272
	ds_read_u16 v81, v78 offset:544
	ds_read_u16 v83, v78 offset:816
	ds_read_u16 v84, v78 offset:1088
	ds_read_u16 v85, v78 offset:1360
	ds_read_u16 v86, v78 offset:1632
	ds_read_u16 v87, v78 offset:1904
	v_or_b32_e32 v82, v168, v82
	s_waitcnt lgkmcnt(0)
	v_lshl_or_b32 v78, v80, 16, v79
	v_lshl_or_b32 v79, v83, 16, v81
	v_ashrrev_i32_e32 v83, 31, v82
	v_lshlrev_b64 v[82:83], 10, v[82:83]
	v_lshl_or_b32 v80, v85, 16, v84
	v_lshl_or_b32 v81, v87, 16, v86
	v_add_co_u32_e32 v82, vcc, v128, v82
	v_addc_co_u32_e32 v83, vcc, v129, v83, vcc
	flat_store_dwordx4 v[82:83], v[78:81]
	v_lshrrev_b32_e32 v82, 2, v68
	s_nop 0
	v_lshl_add_u32 v78, v82, 1, v142
	ds_read_u16 v79, v78
	ds_read_u16 v80, v78 offset:272
	ds_read_u16 v81, v78 offset:544
	ds_read_u16 v83, v78 offset:816
	ds_read_u16 v84, v78 offset:1088
	ds_read_u16 v85, v78 offset:1360
	ds_read_u16 v86, v78 offset:1632
	ds_read_u16 v87, v78 offset:1904
	v_or_b32_e32 v82, v168, v82
	s_waitcnt lgkmcnt(0)
	v_lshl_or_b32 v78, v80, 16, v79
	v_lshl_or_b32 v79, v83, 16, v81
	v_ashrrev_i32_e32 v83, 31, v82
	v_lshlrev_b64 v[82:83], 10, v[82:83]
	v_lshl_or_b32 v80, v85, 16, v84
	v_lshl_or_b32 v81, v87, 16, v86
	v_add_co_u32_e32 v82, vcc, v128, v82
	v_addc_co_u32_e32 v83, vcc, v129, v83, vcc
	flat_store_dwordx4 v[82:83], v[78:81]
	v_lshrrev_b32_e32 v82, 2, v69
	s_nop 0
	v_lshl_add_u32 v78, v82, 1, v142
	ds_read_u16 v79, v78
	ds_read_u16 v80, v78 offset:272
	ds_read_u16 v81, v78 offset:544
	ds_read_u16 v83, v78 offset:816
	ds_read_u16 v84, v78 offset:1088
	ds_read_u16 v85, v78 offset:1360
	ds_read_u16 v86, v78 offset:1632
	ds_read_u16 v87, v78 offset:1904
	v_or_b32_e32 v82, v168, v82
	s_waitcnt lgkmcnt(0)
	v_lshl_or_b32 v78, v80, 16, v79
	v_lshl_or_b32 v79, v83, 16, v81
	v_ashrrev_i32_e32 v83, 31, v82
	v_lshlrev_b64 v[82:83], 10, v[82:83]
	v_lshl_or_b32 v80, v85, 16, v84
	v_lshl_or_b32 v81, v87, 16, v86
	v_add_co_u32_e32 v82, vcc, v128, v82
	v_addc_co_u32_e32 v83, vcc, v129, v83, vcc
	flat_store_dwordx4 v[82:83], v[78:81]
	v_lshrrev_b32_e32 v82, 2, v70
	s_nop 0
	v_lshl_add_u32 v78, v82, 1, v142
	ds_read_u16 v79, v78
	ds_read_u16 v80, v78 offset:272
	ds_read_u16 v81, v78 offset:544
	ds_read_u16 v83, v78 offset:816
	ds_read_u16 v84, v78 offset:1088
	ds_read_u16 v85, v78 offset:1360
	ds_read_u16 v86, v78 offset:1632
	ds_read_u16 v87, v78 offset:1904
	v_or_b32_e32 v82, v168, v82
	s_waitcnt lgkmcnt(0)
	v_lshl_or_b32 v78, v80, 16, v79
	v_lshl_or_b32 v79, v83, 16, v81
	v_ashrrev_i32_e32 v83, 31, v82
	v_lshlrev_b64 v[82:83], 10, v[82:83]
	v_lshl_or_b32 v80, v85, 16, v84
	v_lshl_or_b32 v81, v87, 16, v86
	v_add_co_u32_e32 v82, vcc, v128, v82
	v_addc_co_u32_e32 v83, vcc, v129, v83, vcc
	flat_store_dwordx4 v[82:83], v[78:81]
.LBB0_158:
	s_nop 1
	v_mul_u32_u24_e32 v81, 0x110, v170
	v_pk_mul_f32 v[52:53], v[52:53], s[18:19] op_sel_hi:[1,0]
	v_pk_mul_f32 v[54:55], v[54:55], s[18:19] op_sel_hi:[1,0]
	v_pk_mul_f32 v[20:21], v[20:21], s[18:19] op_sel_hi:[1,0]
	v_pk_mul_f32 v[22:23], v[22:23], s[18:19] op_sel_hi:[1,0]
	v_cvt_pk_bf16_f32 v52, v52, v53
	v_cvt_pk_bf16_f32 v53, v54, v55
	v_add_u32_e32 v81, v148, v81
	v_pk_mul_f32 v[54:55], v[60:61], s[18:19] op_sel_hi:[1,0]
	v_pk_mul_f32 v[60:61], v[62:63], s[18:19] op_sel_hi:[1,0]
	v_cvt_pk_bf16_f32 v20, v20, v21
	v_cvt_pk_bf16_f32 v21, v22, v23
	v_pk_mul_f32 v[22:23], v[28:29], s[18:19] op_sel_hi:[1,0]
	v_pk_mul_f32 v[28:29], v[30:31], s[18:19] op_sel_hi:[1,0]
	v_cvt_pk_bf16_f32 v54, v54, v55
	v_cvt_pk_bf16_f32 v55, v60, v61
	v_cvt_pk_bf16_f32 v22, v22, v23
	v_cvt_pk_bf16_f32 v23, v28, v29
	v_add_u32_e32 v28, 0x1000, v81
	v_pk_mul_f32 v[0:1], v[0:1], s[18:19] op_sel_hi:[1,0]
	v_pk_mul_f32 v[2:3], v[2:3], s[18:19] op_sel_hi:[1,0]
	ds_write2_b64 v81, v[52:53], v[54:55] offset1:4
	v_pk_mul_f32 v[52:53], v[56:57], s[18:19] op_sel_hi:[1,0]
	v_pk_mul_f32 v[54:55], v[58:59], s[18:19] op_sel_hi:[1,0]
	v_pk_mul_f32 v[48:49], v[48:49], s[18:19] op_sel_hi:[1,0]
	v_pk_mul_f32 v[50:51], v[50:51], s[18:19] op_sel_hi:[1,0]
	v_pk_mul_f32 v[44:45], v[44:45], s[18:19] op_sel_hi:[1,0]
	v_pk_mul_f32 v[46:47], v[46:47], s[18:19] op_sel_hi:[1,0]
	v_pk_mul_f32 v[40:41], v[40:41], s[18:19] op_sel_hi:[1,0]
	v_pk_mul_f32 v[42:43], v[42:43], s[18:19] op_sel_hi:[1,0]
	v_pk_mul_f32 v[36:37], v[36:37], s[18:19] op_sel_hi:[1,0]
	v_pk_mul_f32 v[38:39], v[38:39], s[18:19] op_sel_hi:[1,0]
	v_pk_mul_f32 v[32:33], v[32:33], s[18:19] op_sel_hi:[1,0]
	v_pk_mul_f32 v[34:35], v[34:35], s[18:19] op_sel_hi:[1,0]
	ds_write2_b64 v28, v[20:21], v[22:23] offset0:32 offset1:36
	v_pk_mul_f32 v[20:21], v[24:25], s[18:19] op_sel_hi:[1,0]
	v_pk_mul_f32 v[22:23], v[26:27], s[18:19] op_sel_hi:[1,0]
	v_pk_mul_f32 v[16:17], v[16:17], s[18:19] op_sel_hi:[1,0]
	v_pk_mul_f32 v[18:19], v[18:19], s[18:19] op_sel_hi:[1,0]
	v_pk_mul_f32 v[12:13], v[12:13], s[18:19] op_sel_hi:[1,0]
	v_pk_mul_f32 v[14:15], v[14:15], s[18:19] op_sel_hi:[1,0]
	v_pk_mul_f32 v[8:9], v[8:9], s[18:19] op_sel_hi:[1,0]
	v_pk_mul_f32 v[10:11], v[10:11], s[18:19] op_sel_hi:[1,0]
	v_cvt_pk_bf16_f32 v0, v0, v1
	v_cvt_pk_bf16_f32 v1, v2, v3
	v_pk_mul_f32 v[2:3], v[4:5], s[18:19] op_sel_hi:[1,0]
	v_pk_mul_f32 v[4:5], v[6:7], s[18:19] op_sel_hi:[1,0]
	v_mul_u32_u24_e32 v82, 0x110, v169
	v_cvt_pk_bf16_f32 v52, v52, v53
	v_cvt_pk_bf16_f32 v53, v54, v55
	v_cvt_pk_bf16_f32 v48, v48, v49
	v_cvt_pk_bf16_f32 v49, v50, v51
	v_cvt_pk_bf16_f32 v44, v44, v45
	v_cvt_pk_bf16_f32 v45, v46, v47
	v_cvt_pk_bf16_f32 v40, v40, v41
	v_cvt_pk_bf16_f32 v41, v42, v43
	v_cvt_pk_bf16_f32 v36, v36, v37
	v_cvt_pk_bf16_f32 v37, v38, v39
	v_cvt_pk_bf16_f32 v32, v32, v33
	v_cvt_pk_bf16_f32 v33, v34, v35
	v_cvt_pk_bf16_f32 v20, v20, v21
	v_cvt_pk_bf16_f32 v21, v22, v23
	v_cvt_pk_bf16_f32 v16, v16, v17
	v_cvt_pk_bf16_f32 v17, v18, v19
	v_cvt_pk_bf16_f32 v12, v12, v13
	v_cvt_pk_bf16_f32 v13, v14, v15
	v_cvt_pk_bf16_f32 v8, v8, v9
	v_cvt_pk_bf16_f32 v9, v10, v11
	v_cvt_pk_bf16_f32 v2, v2, v3
	v_cvt_pk_bf16_f32 v3, v4, v5
	ds_write2_b64 v81, v[52:53], v[48:49] offset0:8 offset1:12
	ds_write2_b64 v81, v[44:45], v[40:41] offset0:16 offset1:20
	ds_write2_b64 v81, v[36:37], v[32:33] offset0:24 offset1:28
	ds_write2_b64 v28, v[20:21], v[16:17] offset0:40 offset1:44
	ds_write2_b64 v28, v[12:13], v[8:9] offset0:48 offset1:52
	ds_write2_b64 v28, v[0:1], v[2:3] offset0:56 offset1:60
	v_add_u32_e32 v0, v146, v82
	v_or_b32_e32 v24, 32, v147
	ds_read_b128 v[0:3], v0
	v_or_b32_e32 v138, v24, v169
	v_lshlrev_b64 v[4:5], s36, v[138:139]
	v_add_co_u32_e32 v20, vcc, v4, v140
	v_addc_co_u32_e32 v21, vcc, v5, v141, vcc
	ds_read_b128 v[4:7], v144
	ds_read_b128 v[8:11], v145
	ds_read_b128 v[12:15], v145 offset:16
	s_waitcnt lgkmcnt(0)
	v_and_b32_e32 v23, 0xffff0000, v0
	v_lshlrev_b32_e32 v22, 16, v0
	ds_read_b128 v[16:19], v144 offset:16
	v_pk_mul_f32 v[4:5], v[4:5], v[22:23]
	v_mul_u32_u24_e32 v83, 0x110, v71
	v_cvt_pk_bf16_f32 v0, v4, v5
	v_pk_mul_f32 v[4:5], v[8:9], v[22:23]
	v_and_b32_e32 v9, 0xffff0000, v1
	v_lshlrev_b32_e32 v8, 16, v1
	v_pk_mul_f32 v[6:7], v[6:7], v[8:9]
	v_cvt_pk_bf16_f32 v4, v4, v5
	v_cvt_pk_bf16_f32 v1, v6, v7
	v_pk_mul_f32 v[6:7], v[10:11], v[8:9]
	v_or_b32_e32 v138, v24, v71
	v_cvt_pk_bf16_f32 v5, v6, v7
	v_and_b32_e32 v7, 0xffff0000, v2
	v_lshlrev_b32_e32 v6, 16, v2
	s_waitcnt lgkmcnt(0)
	v_pk_mul_f32 v[8:9], v[16:17], v[6:7]
	v_pk_mul_f32 v[6:7], v[12:13], v[6:7]
	v_cvt_pk_bf16_f32 v2, v8, v9
	v_and_b32_e32 v9, 0xffff0000, v3
	v_lshlrev_b32_e32 v8, 16, v3
	v_pk_mul_f32 v[10:11], v[18:19], v[8:9]
	v_pk_mul_f32 v[8:9], v[14:15], v[8:9]
	v_cvt_pk_bf16_f32 v6, v6, v7
	v_cvt_pk_bf16_f32 v7, v8, v9
	v_lshlrev_b64 v[8:9], 1, v[20:21]
	v_cvt_pk_bf16_f32 v3, v10, v11
	v_add_co_u32_e32 v10, vcc, v136, v8
	v_addc_co_u32_e32 v11, vcc, v137, v9, vcc
	flat_store_dwordx4 v[10:11], v[0:3]
	v_mul_u32_u24_e32 v84, 0x110, v72
	v_mul_u32_u24_e32 v85, 0x110, v73
	v_add_co_u32_e32 v0, vcc, v130, v8
	v_addc_co_u32_e32 v1, vcc, v131, v9, vcc
	flat_store_dwordx4 v[0:1], v[4:7]
	v_add_u32_e32 v0, v146, v83
	ds_read_b128 v[0:3], v0
	v_lshlrev_b64 v[4:5], s36, v[138:139]
	v_add_co_u32_e32 v20, vcc, v4, v140
	v_addc_co_u32_e32 v21, vcc, v5, v141, vcc
	ds_read_b128 v[4:7], v144
	ds_read_b128 v[8:11], v145
	ds_read_b128 v[12:15], v145 offset:16
	ds_read_b128 v[16:19], v144 offset:16
	s_waitcnt lgkmcnt(0)
	v_and_b32_e32 v23, 0xffff0000, v0
	v_lshlrev_b32_e32 v22, 16, v0
	v_pk_mul_f32 v[4:5], v[4:5], v[22:23]
	v_or_b32_e32 v138, v24, v72
	v_cvt_pk_bf16_f32 v0, v4, v5
	v_pk_mul_f32 v[4:5], v[8:9], v[22:23]
	v_and_b32_e32 v9, 0xffff0000, v1
	v_lshlrev_b32_e32 v8, 16, v1
	v_pk_mul_f32 v[6:7], v[6:7], v[8:9]
	v_cvt_pk_bf16_f32 v4, v4, v5
	v_cvt_pk_bf16_f32 v1, v6, v7
	v_pk_mul_f32 v[6:7], v[10:11], v[8:9]
	v_mul_u32_u24_e32 v86, 0x110, v74
	v_cvt_pk_bf16_f32 v5, v6, v7
	v_and_b32_e32 v7, 0xffff0000, v2
	v_lshlrev_b32_e32 v6, 16, v2
	v_pk_mul_f32 v[8:9], v[16:17], v[6:7]
	v_pk_mul_f32 v[6:7], v[12:13], v[6:7]
	v_cvt_pk_bf16_f32 v2, v8, v9
	v_and_b32_e32 v9, 0xffff0000, v3
	v_lshlrev_b32_e32 v8, 16, v3
	v_pk_mul_f32 v[10:11], v[18:19], v[8:9]
	v_pk_mul_f32 v[8:9], v[14:15], v[8:9]
	v_cvt_pk_bf16_f32 v6, v6, v7
	v_cvt_pk_bf16_f32 v7, v8, v9
	v_lshlrev_b64 v[8:9], 1, v[20:21]
	v_cvt_pk_bf16_f32 v3, v10, v11
	v_add_co_u32_e32 v10, vcc, v136, v8
	v_addc_co_u32_e32 v11, vcc, v137, v9, vcc
	flat_store_dwordx4 v[10:11], v[0:3]
	v_mul_u32_u24_e32 v80, 0x110, v75
	v_mul_u32_u24_e32 v79, 0x110, v76
	v_add_co_u32_e32 v0, vcc, v130, v8
	v_addc_co_u32_e32 v1, vcc, v131, v9, vcc
	flat_store_dwordx4 v[0:1], v[4:7]
	v_add_u32_e32 v0, v146, v84
	ds_read_b128 v[0:3], v0
	v_lshlrev_b64 v[4:5], s36, v[138:139]
	v_add_co_u32_e32 v20, vcc, v4, v140
	v_addc_co_u32_e32 v21, vcc, v5, v141, vcc
	ds_read_b128 v[4:7], v144
	ds_read_b128 v[8:11], v145
	ds_read_b128 v[12:15], v145 offset:16
	ds_read_b128 v[16:19], v144 offset:16
	s_waitcnt lgkmcnt(0)
	v_and_b32_e32 v23, 0xffff0000, v0
	v_lshlrev_b32_e32 v22, 16, v0
	v_pk_mul_f32 v[4:5], v[4:5], v[22:23]
	v_or_b32_e32 v138, v24, v73
	v_cvt_pk_bf16_f32 v0, v4, v5
	v_pk_mul_f32 v[4:5], v[8:9], v[22:23]
	v_and_b32_e32 v9, 0xffff0000, v1
	v_lshlrev_b32_e32 v8, 16, v1
	v_pk_mul_f32 v[6:7], v[6:7], v[8:9]
	v_cvt_pk_bf16_f32 v4, v4, v5
	v_cvt_pk_bf16_f32 v1, v6, v7
	v_pk_mul_f32 v[6:7], v[10:11], v[8:9]
	v_mul_u32_u24_e32 v78, 0x110, v77
	v_cvt_pk_bf16_f32 v5, v6, v7
	v_and_b32_e32 v7, 0xffff0000, v2
	v_lshlrev_b32_e32 v6, 16, v2
	v_pk_mul_f32 v[8:9], v[16:17], v[6:7]
	v_pk_mul_f32 v[6:7], v[12:13], v[6:7]
	v_cvt_pk_bf16_f32 v2, v8, v9
	v_and_b32_e32 v9, 0xffff0000, v3
	v_lshlrev_b32_e32 v8, 16, v3
	v_pk_mul_f32 v[10:11], v[18:19], v[8:9]
	v_pk_mul_f32 v[8:9], v[14:15], v[8:9]
	v_cvt_pk_bf16_f32 v6, v6, v7
	v_cvt_pk_bf16_f32 v7, v8, v9
	v_lshlrev_b64 v[8:9], 1, v[20:21]
	v_cvt_pk_bf16_f32 v3, v10, v11
	v_add_co_u32_e32 v10, vcc, v136, v8
	v_addc_co_u32_e32 v11, vcc, v137, v9, vcc
	flat_store_dwordx4 v[10:11], v[0:3]
	s_and_b64 vcc, exec, s[4:5]
	s_nop 0
	v_lshl_add_u64 v[0:1], v[130:131], 0, v[8:9]
	flat_store_dwordx4 v[0:1], v[4:7]
	v_add_u32_e32 v0, v146, v85
	ds_read_b128 v[0:3], v0
	v_lshlrev_b64 v[4:5], s36, v[138:139]
	v_lshl_add_u64 v[20:21], v[4:5], 0, v[140:141]
	ds_read_b128 v[4:7], v144
	ds_read_b128 v[8:11], v145
	ds_read_b128 v[12:15], v145 offset:16
	ds_read_b128 v[16:19], v144 offset:16
	s_waitcnt lgkmcnt(0)
	v_and_b32_e32 v23, 0xffff0000, v0
	v_lshlrev_b32_e32 v22, 16, v0
	v_pk_mul_f32 v[4:5], v[4:5], v[22:23]
	v_or_b32_e32 v138, v24, v74
	v_cvt_pk_bf16_f32 v0, v4, v5
	v_pk_mul_f32 v[4:5], v[8:9], v[22:23]
	v_and_b32_e32 v9, 0xffff0000, v1
	v_lshlrev_b32_e32 v8, 16, v1
	v_pk_mul_f32 v[6:7], v[6:7], v[8:9]
	v_cvt_pk_bf16_f32 v4, v4, v5
	v_cvt_pk_bf16_f32 v1, v6, v7
	v_pk_mul_f32 v[6:7], v[10:11], v[8:9]
	s_nop 0
	v_cvt_pk_bf16_f32 v5, v6, v7
	v_and_b32_e32 v7, 0xffff0000, v2
	v_lshlrev_b32_e32 v6, 16, v2
	v_pk_mul_f32 v[8:9], v[16:17], v[6:7]
	v_pk_mul_f32 v[6:7], v[12:13], v[6:7]
	v_cvt_pk_bf16_f32 v2, v8, v9
	v_and_b32_e32 v9, 0xffff0000, v3
	v_lshlrev_b32_e32 v8, 16, v3
	v_pk_mul_f32 v[10:11], v[18:19], v[8:9]
	v_pk_mul_f32 v[8:9], v[14:15], v[8:9]
	v_cvt_pk_bf16_f32 v6, v6, v7
	v_cvt_pk_bf16_f32 v7, v8, v9
	v_lshlrev_b64 v[8:9], 1, v[20:21]
	v_cvt_pk_bf16_f32 v3, v10, v11
	v_lshl_add_u64 v[10:11], v[136:137], 0, v[8:9]
	flat_store_dwordx4 v[10:11], v[0:3]
	s_nop 1
	v_lshl_add_u64 v[0:1], v[130:131], 0, v[8:9]
	flat_store_dwordx4 v[0:1], v[4:7]
	v_add_u32_e32 v0, v146, v86
	ds_read_b128 v[0:3], v0
	v_lshlrev_b64 v[4:5], s36, v[138:139]
	v_lshl_add_u64 v[20:21], v[4:5], 0, v[140:141]
	ds_read_b128 v[4:7], v144
	ds_read_b128 v[8:11], v145
	ds_read_b128 v[12:15], v145 offset:16
	ds_read_b128 v[16:19], v144 offset:16
	s_waitcnt lgkmcnt(0)
	v_and_b32_e32 v23, 0xffff0000, v0
	v_lshlrev_b32_e32 v22, 16, v0
	v_pk_mul_f32 v[4:5], v[4:5], v[22:23]
	v_or_b32_e32 v138, v24, v75
	v_cvt_pk_bf16_f32 v0, v4, v5
	v_pk_mul_f32 v[4:5], v[8:9], v[22:23]
	v_and_b32_e32 v9, 0xffff0000, v1
	v_lshlrev_b32_e32 v8, 16, v1
	v_pk_mul_f32 v[6:7], v[6:7], v[8:9]
	v_cvt_pk_bf16_f32 v4, v4, v5
	v_cvt_pk_bf16_f32 v1, v6, v7
	v_pk_mul_f32 v[6:7], v[10:11], v[8:9]
	s_nop 0
	v_cvt_pk_bf16_f32 v5, v6, v7
	v_and_b32_e32 v7, 0xffff0000, v2
	v_lshlrev_b32_e32 v6, 16, v2
	v_pk_mul_f32 v[8:9], v[16:17], v[6:7]
	v_pk_mul_f32 v[6:7], v[12:13], v[6:7]
	v_cvt_pk_bf16_f32 v2, v8, v9
	v_and_b32_e32 v9, 0xffff0000, v3
	v_lshlrev_b32_e32 v8, 16, v3
	v_pk_mul_f32 v[10:11], v[18:19], v[8:9]
	v_pk_mul_f32 v[8:9], v[14:15], v[8:9]
	v_cvt_pk_bf16_f32 v6, v6, v7
	v_cvt_pk_bf16_f32 v7, v8, v9
	v_lshlrev_b64 v[8:9], 1, v[20:21]
	v_cvt_pk_bf16_f32 v3, v10, v11
	v_lshl_add_u64 v[10:11], v[136:137], 0, v[8:9]
	flat_store_dwordx4 v[10:11], v[0:3]
	s_nop 1
	v_lshl_add_u64 v[0:1], v[130:131], 0, v[8:9]
	flat_store_dwordx4 v[0:1], v[4:7]
	v_add_u32_e32 v0, v146, v80
	ds_read_b128 v[0:3], v0
	v_lshlrev_b64 v[4:5], s36, v[138:139]
	v_lshl_add_u64 v[20:21], v[4:5], 0, v[140:141]
	ds_read_b128 v[4:7], v144
	ds_read_b128 v[8:11], v145
	ds_read_b128 v[12:15], v145 offset:16
	ds_read_b128 v[16:19], v144 offset:16
	s_waitcnt lgkmcnt(0)
	v_and_b32_e32 v23, 0xffff0000, v0
	v_lshlrev_b32_e32 v22, 16, v0
	v_pk_mul_f32 v[4:5], v[4:5], v[22:23]
	v_or_b32_e32 v138, v24, v76
	v_cvt_pk_bf16_f32 v0, v4, v5
	v_pk_mul_f32 v[4:5], v[8:9], v[22:23]
	v_and_b32_e32 v9, 0xffff0000, v1
	v_lshlrev_b32_e32 v8, 16, v1
	v_pk_mul_f32 v[6:7], v[6:7], v[8:9]
	v_cvt_pk_bf16_f32 v4, v4, v5
	v_cvt_pk_bf16_f32 v1, v6, v7
	v_pk_mul_f32 v[6:7], v[10:11], v[8:9]
	s_nop 0
	v_cvt_pk_bf16_f32 v5, v6, v7
	v_and_b32_e32 v7, 0xffff0000, v2
	v_lshlrev_b32_e32 v6, 16, v2
	v_pk_mul_f32 v[8:9], v[16:17], v[6:7]
	v_pk_mul_f32 v[6:7], v[12:13], v[6:7]
	v_cvt_pk_bf16_f32 v2, v8, v9
	v_and_b32_e32 v9, 0xffff0000, v3
	v_lshlrev_b32_e32 v8, 16, v3
	v_pk_mul_f32 v[10:11], v[18:19], v[8:9]
	v_pk_mul_f32 v[8:9], v[14:15], v[8:9]
	v_cvt_pk_bf16_f32 v6, v6, v7
	v_cvt_pk_bf16_f32 v7, v8, v9
	v_lshlrev_b64 v[8:9], 1, v[20:21]
	v_cvt_pk_bf16_f32 v3, v10, v11
	v_lshl_add_u64 v[10:11], v[136:137], 0, v[8:9]
	flat_store_dwordx4 v[10:11], v[0:3]
	s_nop 1
	v_lshl_add_u64 v[0:1], v[130:131], 0, v[8:9]
	flat_store_dwordx4 v[0:1], v[4:7]
	v_add_u32_e32 v0, v146, v79
	ds_read_b128 v[0:3], v0
	v_lshlrev_b64 v[4:5], s36, v[138:139]
	v_lshl_add_u64 v[20:21], v[4:5], 0, v[140:141]
	ds_read_b128 v[4:7], v144
	ds_read_b128 v[8:11], v145
	ds_read_b128 v[12:15], v145 offset:16
	ds_read_b128 v[16:19], v144 offset:16
	s_waitcnt lgkmcnt(0)
	v_and_b32_e32 v23, 0xffff0000, v0
	v_lshlrev_b32_e32 v22, 16, v0
	v_pk_mul_f32 v[4:5], v[4:5], v[22:23]
	v_or_b32_e32 v138, v24, v77
	v_cvt_pk_bf16_f32 v0, v4, v5
	v_pk_mul_f32 v[4:5], v[8:9], v[22:23]
	v_and_b32_e32 v9, 0xffff0000, v1
	v_lshlrev_b32_e32 v8, 16, v1
	v_pk_mul_f32 v[6:7], v[6:7], v[8:9]
	v_cvt_pk_bf16_f32 v4, v4, v5
	v_cvt_pk_bf16_f32 v1, v6, v7
	v_pk_mul_f32 v[6:7], v[10:11], v[8:9]
	s_nop 0
	v_cvt_pk_bf16_f32 v5, v6, v7
	v_and_b32_e32 v7, 0xffff0000, v2
	v_lshlrev_b32_e32 v6, 16, v2
	v_pk_mul_f32 v[8:9], v[16:17], v[6:7]
	v_pk_mul_f32 v[6:7], v[12:13], v[6:7]
	v_cvt_pk_bf16_f32 v2, v8, v9
	v_and_b32_e32 v9, 0xffff0000, v3
	v_lshlrev_b32_e32 v8, 16, v3
	v_pk_mul_f32 v[10:11], v[18:19], v[8:9]
	v_pk_mul_f32 v[8:9], v[14:15], v[8:9]
	v_cvt_pk_bf16_f32 v6, v6, v7
	v_cvt_pk_bf16_f32 v7, v8, v9
	v_lshlrev_b64 v[8:9], 1, v[20:21]
	v_cvt_pk_bf16_f32 v3, v10, v11
	v_lshl_add_u64 v[10:11], v[136:137], 0, v[8:9]
	flat_store_dwordx4 v[10:11], v[0:3]
	s_nop 1
	v_lshl_add_u64 v[0:1], v[130:131], 0, v[8:9]
	flat_store_dwordx4 v[0:1], v[4:7]
	v_add_u32_e32 v0, v146, v78
	ds_read_b128 v[0:3], v0
	v_lshlrev_b64 v[4:5], s36, v[138:139]
	v_lshl_add_u64 v[20:21], v[4:5], 0, v[140:141]
	ds_read_b128 v[4:7], v144
	ds_read_b128 v[8:11], v145
	ds_read_b128 v[12:15], v145 offset:16
	ds_read_b128 v[16:19], v144 offset:16
	s_waitcnt lgkmcnt(0)
	v_and_b32_e32 v23, 0xffff0000, v0
	v_lshlrev_b32_e32 v22, 16, v0
	v_pk_mul_f32 v[4:5], v[4:5], v[22:23]
	s_nop 0
	v_cvt_pk_bf16_f32 v0, v4, v5
	v_pk_mul_f32 v[4:5], v[8:9], v[22:23]
	v_and_b32_e32 v9, 0xffff0000, v1
	v_lshlrev_b32_e32 v8, 16, v1
	v_pk_mul_f32 v[6:7], v[6:7], v[8:9]
	v_cvt_pk_bf16_f32 v4, v4, v5
	v_cvt_pk_bf16_f32 v1, v6, v7
	v_pk_mul_f32 v[6:7], v[10:11], v[8:9]
	s_nop 0
	v_cvt_pk_bf16_f32 v5, v6, v7
	v_and_b32_e32 v7, 0xffff0000, v2
	v_lshlrev_b32_e32 v6, 16, v2
	v_pk_mul_f32 v[8:9], v[16:17], v[6:7]
	v_pk_mul_f32 v[6:7], v[12:13], v[6:7]
	v_cvt_pk_bf16_f32 v2, v8, v9
	v_and_b32_e32 v9, 0xffff0000, v3
	v_lshlrev_b32_e32 v8, 16, v3
	v_pk_mul_f32 v[10:11], v[18:19], v[8:9]
	v_pk_mul_f32 v[8:9], v[14:15], v[8:9]
	v_cvt_pk_bf16_f32 v6, v6, v7
	v_cvt_pk_bf16_f32 v7, v8, v9
	v_lshlrev_b64 v[8:9], 1, v[20:21]
	v_cvt_pk_bf16_f32 v3, v10, v11
	v_lshl_add_u64 v[10:11], v[136:137], 0, v[8:9]
	flat_store_dwordx4 v[10:11], v[0:3]
	s_nop 1
	v_lshl_add_u64 v[0:1], v[130:131], 0, v[8:9]
	flat_store_dwordx4 v[0:1], v[4:7]
	s_cbranch_vccnz .LBB0_160
	s_nop 0
	v_lshrrev_b32_e32 v4, 2, v143
	v_lshl_add_u32 v0, v4, 1, v142
	ds_read_u16 v1, v0
	ds_read_u16 v2, v0 offset:272
	ds_read_u16 v3, v0 offset:544
	ds_read_u16 v5, v0 offset:816
	ds_read_u16 v6, v0 offset:1088
	ds_read_u16 v7, v0 offset:1360
	ds_read_u16 v8, v0 offset:1632
	ds_read_u16 v9, v0 offset:1904
	v_or_b32_e32 v4, v168, v4
	s_waitcnt lgkmcnt(0)
	v_lshl_or_b32 v0, v2, 16, v1
	v_lshl_or_b32 v1, v5, 16, v3
	v_ashrrev_i32_e32 v5, 31, v4
	v_lshlrev_b64 v[4:5], 10, v[4:5]
	v_lshl_or_b32 v2, v7, 16, v6
	v_lshl_or_b32 v3, v9, 16, v8
	v_lshl_add_u64 v[4:5], v[128:129], 0, v[4:5]
	flat_store_dwordx4 v[4:5], v[0:3] offset:64
	v_lshrrev_b32_e32 v4, 2, v64
	s_nop 0
	v_lshl_add_u32 v0, v4, 1, v142
	ds_read_u16 v1, v0
	ds_read_u16 v2, v0 offset:272
	ds_read_u16 v3, v0 offset:544
	ds_read_u16 v5, v0 offset:816
	ds_read_u16 v6, v0 offset:1088
	ds_read_u16 v7, v0 offset:1360
	ds_read_u16 v8, v0 offset:1632
	ds_read_u16 v9, v0 offset:1904
	v_or_b32_e32 v4, v168, v4
	s_waitcnt lgkmcnt(0)
	v_lshl_or_b32 v0, v2, 16, v1
	v_lshl_or_b32 v1, v5, 16, v3
	v_ashrrev_i32_e32 v5, 31, v4
	v_lshlrev_b64 v[4:5], 10, v[4:5]
	v_lshl_or_b32 v2, v7, 16, v6
	v_lshl_or_b32 v3, v9, 16, v8
	v_lshl_add_u64 v[4:5], v[128:129], 0, v[4:5]
	flat_store_dwordx4 v[4:5], v[0:3] offset:64
	v_lshrrev_b32_e32 v4, 2, v65
	s_nop 0
	v_lshl_add_u32 v0, v4, 1, v142
	ds_read_u16 v1, v0
	ds_read_u16 v2, v0 offset:272
	ds_read_u16 v3, v0 offset:544
	ds_read_u16 v5, v0 offset:816
	ds_read_u16 v6, v0 offset:1088
	ds_read_u16 v7, v0 offset:1360
	ds_read_u16 v8, v0 offset:1632
	ds_read_u16 v9, v0 offset:1904
	v_or_b32_e32 v4, v168, v4
	s_waitcnt lgkmcnt(0)
	v_lshl_or_b32 v0, v2, 16, v1
	v_lshl_or_b32 v1, v5, 16, v3
	v_ashrrev_i32_e32 v5, 31, v4
	v_lshlrev_b64 v[4:5], 10, v[4:5]
	v_lshl_or_b32 v2, v7, 16, v6
	v_lshl_or_b32 v3, v9, 16, v8
	v_lshl_add_u64 v[4:5], v[128:129], 0, v[4:5]
	flat_store_dwordx4 v[4:5], v[0:3] offset:64
	v_lshrrev_b32_e32 v4, 2, v66
	s_nop 0
	v_lshl_add_u32 v0, v4, 1, v142
	ds_read_u16 v1, v0
	ds_read_u16 v2, v0 offset:272
	ds_read_u16 v3, v0 offset:544
	ds_read_u16 v5, v0 offset:816
	ds_read_u16 v6, v0 offset:1088
	ds_read_u16 v7, v0 offset:1360
	ds_read_u16 v8, v0 offset:1632
	ds_read_u16 v9, v0 offset:1904
	v_or_b32_e32 v4, v168, v4
	s_waitcnt lgkmcnt(0)
	v_lshl_or_b32 v0, v2, 16, v1
	v_lshl_or_b32 v1, v5, 16, v3
	v_ashrrev_i32_e32 v5, 31, v4
	v_lshlrev_b64 v[4:5], 10, v[4:5]
	v_lshl_or_b32 v2, v7, 16, v6
	v_lshl_or_b32 v3, v9, 16, v8
	v_lshl_add_u64 v[4:5], v[128:129], 0, v[4:5]
	flat_store_dwordx4 v[4:5], v[0:3] offset:64
	v_lshrrev_b32_e32 v4, 2, v67
	s_nop 0
	v_lshl_add_u32 v0, v4, 1, v142
	ds_read_u16 v1, v0
	ds_read_u16 v2, v0 offset:272
	ds_read_u16 v3, v0 offset:544
	ds_read_u16 v5, v0 offset:816
	ds_read_u16 v6, v0 offset:1088
	ds_read_u16 v7, v0 offset:1360
	ds_read_u16 v8, v0 offset:1632
	ds_read_u16 v9, v0 offset:1904
	v_or_b32_e32 v4, v168, v4
	s_waitcnt lgkmcnt(0)
	v_lshl_or_b32 v0, v2, 16, v1
	v_lshl_or_b32 v1, v5, 16, v3
	v_ashrrev_i32_e32 v5, 31, v4
	v_lshlrev_b64 v[4:5], 10, v[4:5]
	v_lshl_or_b32 v2, v7, 16, v6
	v_lshl_or_b32 v3, v9, 16, v8
	v_lshl_add_u64 v[4:5], v[128:129], 0, v[4:5]
	flat_store_dwordx4 v[4:5], v[0:3] offset:64
	v_lshrrev_b32_e32 v4, 2, v68
	s_nop 0
	v_lshl_add_u32 v0, v4, 1, v142
	ds_read_u16 v1, v0
	ds_read_u16 v2, v0 offset:272
	ds_read_u16 v3, v0 offset:544
	ds_read_u16 v5, v0 offset:816
	ds_read_u16 v6, v0 offset:1088
	ds_read_u16 v7, v0 offset:1360
	ds_read_u16 v8, v0 offset:1632
	ds_read_u16 v9, v0 offset:1904
	v_or_b32_e32 v4, v168, v4
	s_waitcnt lgkmcnt(0)
	v_lshl_or_b32 v0, v2, 16, v1
	v_lshl_or_b32 v1, v5, 16, v3
	v_ashrrev_i32_e32 v5, 31, v4
	v_lshlrev_b64 v[4:5], 10, v[4:5]
	v_lshl_or_b32 v2, v7, 16, v6
	v_lshl_or_b32 v3, v9, 16, v8
	v_lshl_add_u64 v[4:5], v[128:129], 0, v[4:5]
	flat_store_dwordx4 v[4:5], v[0:3] offset:64
	v_lshrrev_b32_e32 v4, 2, v69
	s_nop 0
	v_lshl_add_u32 v0, v4, 1, v142
	ds_read_u16 v1, v0
	ds_read_u16 v2, v0 offset:272
	ds_read_u16 v3, v0 offset:544
	ds_read_u16 v5, v0 offset:816
	ds_read_u16 v6, v0 offset:1088
	ds_read_u16 v7, v0 offset:1360
	ds_read_u16 v8, v0 offset:1632
	ds_read_u16 v9, v0 offset:1904
	v_or_b32_e32 v4, v168, v4
	s_waitcnt lgkmcnt(0)
	v_lshl_or_b32 v0, v2, 16, v1
	v_lshl_or_b32 v1, v5, 16, v3
	v_ashrrev_i32_e32 v5, 31, v4
	v_lshlrev_b64 v[4:5], 10, v[4:5]
	v_lshl_or_b32 v2, v7, 16, v6
	v_lshl_or_b32 v3, v9, 16, v8
	v_lshl_add_u64 v[4:5], v[128:129], 0, v[4:5]
	flat_store_dwordx4 v[4:5], v[0:3] offset:64
	v_lshrrev_b32_e32 v4, 2, v70
	s_nop 0
	v_lshl_add_u32 v0, v4, 1, v142
	ds_read_u16 v1, v0
	ds_read_u16 v2, v0 offset:272
	ds_read_u16 v3, v0 offset:544
	ds_read_u16 v5, v0 offset:816
	ds_read_u16 v6, v0 offset:1088
	ds_read_u16 v7, v0 offset:1360
	ds_read_u16 v8, v0 offset:1632
	ds_read_u16 v9, v0 offset:1904
	v_or_b32_e32 v4, v168, v4
	s_waitcnt lgkmcnt(0)
	v_lshl_or_b32 v0, v2, 16, v1
	v_lshl_or_b32 v1, v5, 16, v3
	v_ashrrev_i32_e32 v5, 31, v4
	v_lshlrev_b64 v[4:5], 10, v[4:5]
	v_lshl_or_b32 v2, v7, 16, v6
	v_lshl_or_b32 v3, v9, 16, v8
	v_lshl_add_u64 v[4:5], v[128:129], 0, v[4:5]
	flat_store_dwordx4 v[4:5], v[0:3] offset:64

.LBB0_163:
	s_cmp_lg_u32 s67, 5
	s_cselect_b64 s[4:5], -1, 0
	s_and_b32 s6, s26, -10
	s_cmp_lg_u32 s6, 4
	s_cselect_b64 s[30:31], -1, 0
	v_mov_b32_e32 v0, s19
	s_and_b64 s[34:35], s[30:31], s[4:5]
	ds_read_b64 v[0:1], v0
	s_and_b64 s[4:5], exec, s[28:29]
	s_cselect_b32 s4, 0x8000, 0
	s_add_i32 s4, s66, s4
	s_ashr_i32 s5, s4, 31
	s_lshl_b64 s[4:5], s[4:5], 11
	s_waitcnt lgkmcnt(0)
	v_readfirstlane_b32 s38, v0
	v_readfirstlane_b32 s39, v1
	v_lshl_add_u64 v[0:1], v[0:1], 0, s[4:5]
	v_lshl_add_u64 v[128:129], v[0:1], 0, s[8:9]
	s_mov_b64 s[30:31], -1
	s_and_b64 vcc, exec, s[34:35]
	s_cbranch_vccz .LBB0_175
	v_mov_b32_e32 v10, v132
	s_ashr_i32 s27, s26, 31
	v_lshlrev_b32_e32 v1, 4, v10
	v_and_b32_e32 v0, 32, v10
	v_lshrrev_b32_e32 v2, 1, v10
	v_bitop3_b32 v0, v1, v0, 48 bitop3:0x6c
	v_bfe_u32 v11, v10, 2, 4
	v_and_b32_e32 v12, 32, v2
	v_lshrrev_b32_e32 v13, 1, v0
	v_ashrrev_i32_e32 v14, 3, v10
	v_or_b32_e32 v4, v13, v12
	v_and_or_b32 v0, v14, s48, v11
	v_and_b32_e32 v3, 0xfffffc00, v1
	v_lshl_or_b32 v134, v0, 10, v4
	v_add_u32_e32 v0, 0x2000, v1
	v_add_u32_e32 v2, 0x4000, v1
	v_add_u32_e32 v1, 0x6000, v1
	v_ashrrev_i32_e32 v15, 7, v0
	v_ashrrev_i32_e32 v16, 7, v2
	v_ashrrev_i32_e32 v17, 7, v1
	s_lshl_b64 s[30:31], s[26:27], 19
	v_and_or_b32 v0, v15, s48, v11
	v_and_or_b32 v2, v16, s48, v11
	v_and_or_b32 v1, v17, s48, v11
	v_add_u32_e32 v150, 0, v3
	s_add_u32 s30, s38, s30
	v_lshl_or_b32 v0, v0, 10, v4
	v_lshl_or_b32 v2, v2, 10, v4
	v_lshl_or_b32 v4, v1, 10, v4
	v_add_u32_e32 v1, 0x8000, v150
	v_lshlrev_b64 v[6:7], 1, v[134:135]
	v_readfirstlane_b32 s6, v150
	s_addc_u32 s31, s39, s31
	v_add_co_u32_e32 v8, vcc, v128, v6
	v_addc_co_u32_e32 v9, vcc, v129, v7, vcc
	s_mov_b32 m0, s6
	v_readfirstlane_b32 s6, v1
	v_mov_b32_e32 v1, v135
	v_add_u32_e32 v3, 0x2000, v150
	global_load_lds_dwordx4 v[8:9], off
	v_lshl_add_u64 v[6:7], s[30:31], 0, v[6:7]
	s_mov_b32 m0, s6
	v_lshlrev_b64 v[0:1], 1, v[0:1]
	v_readfirstlane_b32 s6, v3
	v_add_u32_e32 v3, 0xa000, v150
	global_load_lds_dwordx4 v[6:7], off
	v_add_co_u32_e32 v6, vcc, v128, v0
	v_addc_co_u32_e32 v7, vcc, v129, v1, vcc
	s_mov_b32 m0, s6
	v_readfirstlane_b32 s6, v3
	global_load_lds_dwordx4 v[6:7], off
	v_lshl_add_u64 v[0:1], s[30:31], 0, v[0:1]
	s_mov_b32 m0, s6
	v_mov_b32_e32 v3, v135
	v_add_u32_e32 v5, 0x4000, v150
	global_load_lds_dwordx4 v[0:1], off
	v_lshlrev_b64 v[0:1], 1, v[2:3]
	v_readfirstlane_b32 s6, v5
	v_add_co_u32_e32 v2, vcc, v128, v0
	v_addc_co_u32_e32 v3, vcc, v129, v1, vcc
	s_mov_b32 m0, s6
	v_lshl_add_u64 v[0:1], s[30:31], 0, v[0:1]
	global_load_lds_dwordx4 v[2:3], off
	v_add_u32_e32 v2, 0xc000, v150
	v_mov_b32_e32 v5, v135
	v_readfirstlane_b32 s6, v2
	s_mov_b32 m0, s6
	v_and_b32_e32 v18, 15, v10
	global_load_lds_dwordx4 v[0:1], off
	v_lshlrev_b64 v[0:1], 1, v[4:5]
	v_add_u32_e32 v4, 0x6000, v150
	v_add_co_u32_e32 v2, vcc, v128, v0
	v_addc_co_u32_e32 v3, vcc, v129, v1, vcc
	v_readfirstlane_b32 s6, v4
	s_mov_b32 m0, s6
	v_lshl_add_u64 v[0:1], s[30:31], 0, v[0:1]
	global_load_lds_dwordx4 v[2:3], off
	v_add_u32_e32 v2, 0xe000, v150
	v_lshlrev_b32_e32 v6, 10, v11
	v_readfirstlane_b32 s6, v2
	s_mov_b32 m0, s6
	v_lshlrev_b32_e32 v2, 2, v10
	global_load_lds_dwordx4 v[0:1], off
	v_and_b32_e32 v0, 48, v10
	v_lshlrev_b32_e32 v1, 6, v18
	v_and_b32_e32 v2, 32, v2
	v_bitop3_b32 v151, v1, v2, v0 bitop3:0x36
	v_lshlrev_b32_e32 v1, 7, v10
	v_and_b32_e32 v152, 0x6000, v1
	v_lshlrev_b32_e32 v1, 6, v10
	v_and_b32_e32 v153, 0xffffc000, v1
	v_and_b32_e32 v1, 0x3c0, v1
	v_bitop3_b32 v155, v1, v2, v0 bitop3:0x36
	v_lshlrev_b32_e32 v0, 10, v17
	v_and_or_b32 v0, v0, s49, v13
	v_lshlrev_b32_e32 v2, 10, v16
	v_or3_b32 v134, v0, v6, v12
	v_and_or_b32 v2, v2, s49, v13
	v_lshlrev_b32_e32 v4, 10, v15
	v_lshlrev_b64 v[0:1], 1, v[134:135]
	s_add_u32 s30, s30, 0x80
	v_or3_b32 v134, v2, v6, v12
	v_and_or_b32 v4, v4, s49, v13
	v_lshlrev_b32_e32 v7, 10, v14
	s_addc_u32 s31, s31, 0
	v_lshlrev_b64 v[2:3], 1, v[134:135]
	v_or3_b32 v134, v4, v6, v12
	v_and_or_b32 v7, v7, s49, v13
	v_lshlrev_b64 v[4:5], 1, v[134:135]
	v_or3_b32 v134, v7, v6, v12
	s_add_u32 s6, s38, s4
	v_lshlrev_b64 v[6:7], 1, v[134:135]
	s_addc_u32 s27, s39, s5
	v_lshl_add_u64 v[130:131], s[30:31], 0, v[0:1]
	v_lshl_add_u64 v[136:137], s[30:31], 0, v[2:3]
	v_lshl_add_u64 v[138:139], s[30:31], 0, v[4:5]
	v_lshl_add_u64 v[140:141], s[30:31], 0, v[6:7]
	s_add_u32 s30, s6, 0x2400080
	s_nop 0
	s_addc_u32 s31, s27, 0
	v_lshl_add_u64 v[142:143], s[30:31], 0, v[0:1]
	v_or_b32_e32 v154, 0x800, v153
	v_or_b32_e32 v156, 0x1000, v153
	v_or_b32_e32 v157, 0x1800, v153
	v_or_b32_e32 v158, 0x2000, v153
	v_or_b32_e32 v159, 0x2800, v153
	v_or_b32_e32 v160, 0x3000, v153
	v_or_b32_e32 v161, 0x3800, v153
	v_lshl_add_u64 v[144:145], s[30:31], 0, v[2:3]
	v_lshl_add_u64 v[146:147], s[30:31], 0, v[4:5]
	v_lshl_add_u64 v[148:149], s[30:31], 0, v[6:7]
	s_mov_b32 s6, 0
	s_mov_b64 s[30:31], 0
	s_waitcnt vmcnt(0) lgkmcnt(0)
	s_barrier
	v_readfirstlane_b32 s100, v150
	s_and_b32 s27, s6, 0x10000
	s_xor_b32 s34, s27, 0x10000
	s_add_i32 s27, s27, 0
	v_add3_u32 v134, s27, v151, v152
	v_add3_u32 v162, s27, v151, v153
	v_add3_u32 v163, s27, v155, v154
	v_add3_u32 v200, s27, v155, v156
	v_add3_u32 v201, s27, v155, v157
	v_add3_u32 v202, s27, v155, v158
	v_add3_u32 v203, s27, v155, v159
	v_add3_u32 v204, s27, v155, v160
	v_add3_u32 v205, s27, v155, v161
	ds_read_b128 v[184:187], v134 offset:32768
	ds_read_b128 v[168:171], v162
	ds_read_b128 v[172:175], v163
	ds_read_b128 v[176:179], v200
	ds_read_b128 v[180:183], v201
	ds_read_b128 v[188:191], v134 offset:34816
	ds_read_b128 v[192:195], v134 offset:36864
	ds_read_b128 v[196:199], v134 offset:38912
	s_add_i32 s101, s100, s34
	v_readfirstlane_b32 s98, v148
	v_readfirstlane_b32 s99, v149
	v_readfirstlane_b32 vcc_lo, v140
	v_readfirstlane_b32 vcc_hi, v141
	s_sub_u32 s98, s98, 0x1000000
	s_subb_u32 s99, s99, 0
	s_sub_u32 vcc_lo, vcc_lo, 0x1000000
	s_subb_u32 vcc_hi, vcc_hi, 0
	v_subrev_u32_e32 v148, s98, v148
	v_subrev_u32_e32 v140, vcc_lo, v140
	v_subrev_u32_e32 v146, s98, v146
	v_subrev_u32_e32 v138, vcc_lo, v138
	v_subrev_u32_e32 v144, s98, v144
	v_subrev_u32_e32 v136, vcc_lo, v136
	v_subrev_u32_e32 v142, s98, v142
	v_subrev_u32_e32 v130, vcc_lo, v130
	s_mov_b32 m0, s101
	s_nop 0
	global_load_lds_dwordx4 v148, s[98:99]
	s_add_i32 m0, s101, 0x8000
	s_nop 0
	global_load_lds_dwordx4 v140, vcc
	s_add_i32 m0, s101, 0x2000
	s_nop 0
	global_load_lds_dwordx4 v146, s[98:99]
	s_add_i32 m0, s101, 0xa000
	s_nop 0
	global_load_lds_dwordx4 v138, vcc
	s_add_i32 m0, s101, 0x4000
	s_nop 0
	global_load_lds_dwordx4 v144, s[98:99]
	s_add_i32 m0, s101, 0xc000
	s_nop 0
	global_load_lds_dwordx4 v136, vcc
	s_add_i32 m0, s101, 0x6000
	s_nop 0
	global_load_lds_dwordx4 v142, s[98:99]
	s_add_i32 m0, s101, 0xe000
	s_nop 0
	global_load_lds_dwordx4 v130, vcc

.LBB0_174:
	v_ashrrev_i32_e32 v134, 1, v138
	v_and_b32_e32 v134, 0xffffff80, v134
	v_add_u32_e32 v134, s66, v134
	s_waitcnt lgkmcnt(0)
	v_ashrrev_i32_e32 v136, 31, v134
	v_mul_lo_u32 v141, s30, v136
	v_mul_lo_u32 v142, s31, v134
	v_mad_u64_u32 v[136:137], s[36:37], s30, v134, 0
	v_add3_u32 v137, v137, v141, v142
	v_lshl_add_u64 v[130:131], v[136:137], 1, v[130:131]
	s_ashr_i32 s35, s34, 31
	v_and_b32_e32 v134, 0xc0, v138
	v_lshrrev_b32_e32 v140, 6, v138
	v_lshl_add_u64 v[130:131], s[34:35], 1, v[130:131]
	v_lshlrev_b32_e32 v134, 1, v134
	v_add_co_u32_e32 v130, vcc, v130, v134
	v_addc_co_u32_e32 v131, vcc, v131, v135, vcc
	v_mul_lo_u32 v134, v140, s55
	v_add_u32_e32 v136, s27, v134
	v_lshrrev_b32_e32 v134, 1, v138
	v_and_b32_e32 v139, 15, v138
	v_and_b32_e32 v137, 24, v134
	v_lshlrev_b32_e32 v134, 4, v138
	v_bfe_u32 v138, v138, 3, 3
	v_and_b32_e32 v134, 0x70, v134
	v_mul_u32_u24_e32 v140, 0x90, v138
	v_mul_u32_u24_e32 v139, 0x90, v139
	v_pk_mul_f32 v[108:109], v[108:109], s[6:7] op_sel_hi:[1,0]
	v_pk_mul_f32 v[110:111], v[110:111], s[6:7] op_sel_hi:[1,0]
	v_add3_u32 v140, v136, v134, v140
	v_add3_u32 v136, v136, v137, v139
	v_cvt_pk_bf16_f32 v108, v108, v109
	v_cvt_pk_bf16_f32 v109, v110, v111
	v_pk_mul_f32 v[124:125], v[124:125], s[6:7] op_sel_hi:[1,0]
	v_pk_mul_f32 v[126:127], v[126:127], s[6:7] op_sel_hi:[1,0]
	v_pk_mul_f32 v[120:121], v[120:121], s[6:7] op_sel_hi:[1,0]
	v_pk_mul_f32 v[122:123], v[122:123], s[6:7] op_sel_hi:[1,0]
	v_pk_mul_f32 v[116:117], v[116:117], s[6:7] op_sel_hi:[1,0]
	v_pk_mul_f32 v[118:119], v[118:119], s[6:7] op_sel_hi:[1,0]
	ds_write_b64 v136, v[108:109] offset:96
	v_pk_mul_f32 v[108:109], v[112:113], s[6:7] op_sel_hi:[1,0]
	v_pk_mul_f32 v[110:111], v[114:115], s[6:7] op_sel_hi:[1,0]
	v_pk_mul_f32 v[104:105], v[104:105], s[6:7] op_sel_hi:[1,0]
	v_pk_mul_f32 v[106:107], v[106:107], s[6:7] op_sel_hi:[1,0]
	v_pk_mul_f32 v[100:101], v[100:101], s[6:7] op_sel_hi:[1,0]
	v_pk_mul_f32 v[102:103], v[102:103], s[6:7] op_sel_hi:[1,0]
	v_pk_mul_f32 v[96:97], v[96:97], s[6:7] op_sel_hi:[1,0]
	v_pk_mul_f32 v[98:99], v[98:99], s[6:7] op_sel_hi:[1,0]
	v_pk_mul_f32 v[92:93], v[92:93], s[6:7] op_sel_hi:[1,0]
	v_pk_mul_f32 v[94:95], v[94:95], s[6:7] op_sel_hi:[1,0]
	v_pk_mul_f32 v[88:89], v[88:89], s[6:7] op_sel_hi:[1,0]
	v_pk_mul_f32 v[90:91], v[90:91], s[6:7] op_sel_hi:[1,0]
	v_pk_mul_f32 v[84:85], v[84:85], s[6:7] op_sel_hi:[1,0]
	v_pk_mul_f32 v[86:87], v[86:87], s[6:7] op_sel_hi:[1,0]
	v_pk_mul_f32 v[80:81], v[80:81], s[6:7] op_sel_hi:[1,0]
	v_pk_mul_f32 v[82:83], v[82:83], s[6:7] op_sel_hi:[1,0]
	v_pk_mul_f32 v[76:77], v[76:77], s[6:7] op_sel_hi:[1,0]
	v_pk_mul_f32 v[78:79], v[78:79], s[6:7] op_sel_hi:[1,0]
	v_pk_mul_f32 v[72:73], v[72:73], s[6:7] op_sel_hi:[1,0]
	v_pk_mul_f32 v[74:75], v[74:75], s[6:7] op_sel_hi:[1,0]
	v_pk_mul_f32 v[68:69], v[68:69], s[6:7] op_sel_hi:[1,0]
	v_pk_mul_f32 v[70:71], v[70:71], s[6:7] op_sel_hi:[1,0]
	v_pk_mul_f32 v[64:65], v[64:65], s[6:7] op_sel_hi:[1,0]
	v_pk_mul_f32 v[66:67], v[66:67], s[6:7] op_sel_hi:[1,0]
	v_cvt_pk_bf16_f32 v124, v124, v125
	v_cvt_pk_bf16_f32 v125, v126, v127
	v_cvt_pk_bf16_f32 v120, v120, v121
	v_cvt_pk_bf16_f32 v121, v122, v123
	v_cvt_pk_bf16_f32 v116, v116, v117
	v_cvt_pk_bf16_f32 v117, v118, v119
	v_cvt_pk_bf16_f32 v108, v108, v109
	v_cvt_pk_bf16_f32 v109, v110, v111
	v_cvt_pk_bf16_f32 v104, v104, v105
	v_cvt_pk_bf16_f32 v105, v106, v107
	v_cvt_pk_bf16_f32 v100, v100, v101
	v_cvt_pk_bf16_f32 v101, v102, v103
	v_cvt_pk_bf16_f32 v96, v96, v97
	v_cvt_pk_bf16_f32 v97, v98, v99
	v_cvt_pk_bf16_f32 v92, v92, v93
	v_cvt_pk_bf16_f32 v93, v94, v95
	v_cvt_pk_bf16_f32 v88, v88, v89
	v_cvt_pk_bf16_f32 v89, v90, v91
	v_cvt_pk_bf16_f32 v84, v84, v85
	v_cvt_pk_bf16_f32 v85, v86, v87
	v_cvt_pk_bf16_f32 v80, v80, v81
	v_cvt_pk_bf16_f32 v81, v82, v83
	v_cvt_pk_bf16_f32 v76, v76, v77
	v_cvt_pk_bf16_f32 v77, v78, v79
	v_cvt_pk_bf16_f32 v72, v72, v73
	v_cvt_pk_bf16_f32 v73, v74, v75
	v_cvt_pk_bf16_f32 v68, v68, v69
	v_cvt_pk_bf16_f32 v69, v70, v71
	v_cvt_pk_bf16_f32 v64, v64, v65
	v_cvt_pk_bf16_f32 v65, v66, v67
	ds_write_b64 v136, v[124:125]
	ds_write_b64 v136, v[120:121] offset:32
	ds_write_b64 v136, v[116:117] offset:64
	ds_write_b64 v136, v[108:109] offset:2304
	ds_write_b64 v136, v[104:105] offset:2336
	ds_write_b64 v136, v[100:101] offset:2368
	ds_write_b64 v136, v[96:97] offset:2400
	ds_write_b64 v136, v[92:93] offset:4608
	ds_write_b64 v136, v[88:89] offset:4640
	ds_write_b64 v136, v[84:85] offset:4672
	ds_write_b64 v136, v[80:81] offset:4704
	ds_write_b64 v136, v[76:77] offset:6912
	ds_write_b64 v136, v[72:73] offset:6944
	ds_write_b64 v136, v[68:69] offset:6976
	ds_write_b64 v136, v[64:65] offset:7008
	ds_read_b128 v[66:69], v140
	v_mul_u32_u24_e32 v70, s30, v138
	v_add_co_u32_e32 v64, vcc, v130, v134
	v_addc_co_u32_e32 v65, vcc, v131, v135, vcc
	v_lshlrev_b32_e32 v134, 1, v70
	v_add_co_u32_e32 v70, vcc, v64, v134
	v_addc_co_u32_e32 v71, vcc, v65, v135, vcc
	s_waitcnt lgkmcnt(0)
	flat_store_dwordx4 v[70:71], v[66:69] nt
	ds_read_b128 v[66:69], v140 offset:1152
	v_or_b32_e32 v70, 8, v138
	v_mul_u32_u24_e32 v70, s30, v70
	v_lshlrev_b32_e32 v134, 1, v70
	v_add_co_u32_e32 v70, vcc, v64, v134
	v_addc_co_u32_e32 v71, vcc, v65, v135, vcc
	s_waitcnt lgkmcnt(0)
	flat_store_dwordx4 v[70:71], v[66:69] nt
	ds_read_b128 v[66:69], v140 offset:2304
	v_or_b32_e32 v70, 16, v138
	v_mul_u32_u24_e32 v70, s30, v70
	v_lshlrev_b32_e32 v134, 1, v70
	v_add_co_u32_e32 v70, vcc, v64, v134
	v_addc_co_u32_e32 v71, vcc, v65, v135, vcc
	s_waitcnt lgkmcnt(0)
	flat_store_dwordx4 v[70:71], v[66:69] nt
	ds_read_b128 v[66:69], v140 offset:3456
	v_or_b32_e32 v70, 24, v138
	v_mul_u32_u24_e32 v70, s30, v70
	v_lshlrev_b32_e32 v134, 1, v70
	v_add_co_u32_e32 v70, vcc, v64, v134
	v_addc_co_u32_e32 v71, vcc, v65, v135, vcc
	s_waitcnt lgkmcnt(0)
	flat_store_dwordx4 v[70:71], v[66:69] nt
	ds_read_b128 v[66:69], v140 offset:4608
	v_or_b32_e32 v70, 32, v138
	v_mul_u32_u24_e32 v70, s30, v70
	v_lshlrev_b32_e32 v134, 1, v70
	v_add_co_u32_e32 v70, vcc, v64, v134
	v_addc_co_u32_e32 v71, vcc, v65, v135, vcc
	s_waitcnt lgkmcnt(0)
	flat_store_dwordx4 v[70:71], v[66:69] nt
	ds_read_b128 v[66:69], v140 offset:5760
	v_or_b32_e32 v70, 40, v138
	v_mul_u32_u24_e32 v70, s30, v70
	v_lshlrev_b32_e32 v134, 1, v70
	v_add_co_u32_e32 v70, vcc, v64, v134
	v_addc_co_u32_e32 v71, vcc, v65, v135, vcc
	s_waitcnt lgkmcnt(0)
	flat_store_dwordx4 v[70:71], v[66:69] nt
	ds_read_b128 v[66:69], v140 offset:6912
	v_or_b32_e32 v70, 48, v138
	v_mul_u32_u24_e32 v70, s30, v70
	v_lshlrev_b32_e32 v134, 1, v70
	v_add_co_u32_e32 v70, vcc, v64, v134
	v_addc_co_u32_e32 v71, vcc, v65, v135, vcc
	s_waitcnt lgkmcnt(0)
	flat_store_dwordx4 v[70:71], v[66:69] nt
	ds_read_b128 v[66:69], v140 offset:8064
	v_or_b32_e32 v70, 56, v138
	v_mul_u32_u24_e32 v70, s30, v70
	v_lshlrev_b32_e32 v134, 1, v70
	v_pk_mul_f32 v[0:1], v[0:1], s[6:7] op_sel_hi:[1,0]
	v_pk_mul_f32 v[2:3], v[2:3], s[6:7] op_sel_hi:[1,0]
	v_add_co_u32_e32 v70, vcc, v64, v134
	v_addc_co_u32_e32 v71, vcc, v65, v135, vcc
	v_cvt_pk_bf16_f32 v0, v0, v1
	v_cvt_pk_bf16_f32 v1, v2, v3
	s_waitcnt lgkmcnt(0)
	flat_store_dwordx4 v[70:71], v[66:69] nt
	v_pk_mul_f32 v[60:61], v[60:61], s[6:7] op_sel_hi:[1,0]
	v_pk_mul_f32 v[62:63], v[62:63], s[6:7] op_sel_hi:[1,0]
	v_pk_mul_f32 v[56:57], v[56:57], s[6:7] op_sel_hi:[1,0]
	v_pk_mul_f32 v[58:59], v[58:59], s[6:7] op_sel_hi:[1,0]
	v_pk_mul_f32 v[52:53], v[52:53], s[6:7] op_sel_hi:[1,0]
	v_pk_mul_f32 v[54:55], v[54:55], s[6:7] op_sel_hi:[1,0]
	v_pk_mul_f32 v[48:49], v[48:49], s[6:7] op_sel_hi:[1,0]
	v_pk_mul_f32 v[50:51], v[50:51], s[6:7] op_sel_hi:[1,0]
	v_pk_mul_f32 v[44:45], v[44:45], s[6:7] op_sel_hi:[1,0]
	v_pk_mul_f32 v[46:47], v[46:47], s[6:7] op_sel_hi:[1,0]
	v_pk_mul_f32 v[40:41], v[40:41], s[6:7] op_sel_hi:[1,0]
	v_pk_mul_f32 v[42:43], v[42:43], s[6:7] op_sel_hi:[1,0]
	v_pk_mul_f32 v[36:37], v[36:37], s[6:7] op_sel_hi:[1,0]
	v_pk_mul_f32 v[38:39], v[38:39], s[6:7] op_sel_hi:[1,0]
	v_pk_mul_f32 v[32:33], v[32:33], s[6:7] op_sel_hi:[1,0]
	v_pk_mul_f32 v[34:35], v[34:35], s[6:7] op_sel_hi:[1,0]
	v_pk_mul_f32 v[28:29], v[28:29], s[6:7] op_sel_hi:[1,0]
	v_pk_mul_f32 v[30:31], v[30:31], s[6:7] op_sel_hi:[1,0]
	v_pk_mul_f32 v[24:25], v[24:25], s[6:7] op_sel_hi:[1,0]
	v_pk_mul_f32 v[26:27], v[26:27], s[6:7] op_sel_hi:[1,0]
	v_pk_mul_f32 v[20:21], v[20:21], s[6:7] op_sel_hi:[1,0]
	v_pk_mul_f32 v[22:23], v[22:23], s[6:7] op_sel_hi:[1,0]
	v_pk_mul_f32 v[16:17], v[16:17], s[6:7] op_sel_hi:[1,0]
	v_pk_mul_f32 v[18:19], v[18:19], s[6:7] op_sel_hi:[1,0]
	v_pk_mul_f32 v[12:13], v[12:13], s[6:7] op_sel_hi:[1,0]
	v_pk_mul_f32 v[14:15], v[14:15], s[6:7] op_sel_hi:[1,0]
	v_pk_mul_f32 v[8:9], v[8:9], s[6:7] op_sel_hi:[1,0]
	v_pk_mul_f32 v[10:11], v[10:11], s[6:7] op_sel_hi:[1,0]
	ds_write_b64 v136, v[0:1] offset:6976
	v_pk_mul_f32 v[0:1], v[4:5], s[6:7] op_sel_hi:[1,0]
	v_pk_mul_f32 v[2:3], v[6:7], s[6:7] op_sel_hi:[1,0]
	v_cvt_pk_bf16_f32 v60, v60, v61
	v_cvt_pk_bf16_f32 v61, v62, v63
	v_cvt_pk_bf16_f32 v56, v56, v57
	v_cvt_pk_bf16_f32 v57, v58, v59
	v_cvt_pk_bf16_f32 v52, v52, v53
	v_cvt_pk_bf16_f32 v53, v54, v55
	v_cvt_pk_bf16_f32 v48, v48, v49
	v_cvt_pk_bf16_f32 v49, v50, v51
	v_cvt_pk_bf16_f32 v44, v44, v45
	v_cvt_pk_bf16_f32 v45, v46, v47
	v_cvt_pk_bf16_f32 v40, v40, v41
	v_cvt_pk_bf16_f32 v41, v42, v43
	v_cvt_pk_bf16_f32 v36, v36, v37
	v_cvt_pk_bf16_f32 v37, v38, v39
	v_cvt_pk_bf16_f32 v32, v32, v33
	v_cvt_pk_bf16_f32 v33, v34, v35
	v_cvt_pk_bf16_f32 v28, v28, v29
	v_cvt_pk_bf16_f32 v29, v30, v31
	v_cvt_pk_bf16_f32 v24, v24, v25
	v_cvt_pk_bf16_f32 v25, v26, v27
	v_cvt_pk_bf16_f32 v20, v20, v21
	v_cvt_pk_bf16_f32 v21, v22, v23
	v_cvt_pk_bf16_f32 v16, v16, v17
	v_cvt_pk_bf16_f32 v17, v18, v19
	v_cvt_pk_bf16_f32 v12, v12, v13
	v_cvt_pk_bf16_f32 v13, v14, v15
	v_cvt_pk_bf16_f32 v8, v8, v9
	v_cvt_pk_bf16_f32 v9, v10, v11
	v_cvt_pk_bf16_f32 v0, v0, v1
	v_cvt_pk_bf16_f32 v1, v2, v3
	ds_write_b64 v136, v[60:61]
	ds_write_b64 v136, v[56:57] offset:32
	ds_write_b64 v136, v[52:53] offset:64
	ds_write_b64 v136, v[48:49] offset:96
	ds_write_b64 v136, v[44:45] offset:2304
	ds_write_b64 v136, v[40:41] offset:2336
	ds_write_b64 v136, v[36:37] offset:2368
	ds_write_b64 v136, v[32:33] offset:2400
	ds_write_b64 v136, v[28:29] offset:4608
	ds_write_b64 v136, v[24:25] offset:4640
	ds_write_b64 v136, v[20:21] offset:4672
	ds_write_b64 v136, v[16:17] offset:4704
	ds_write_b64 v136, v[12:13] offset:6912
	ds_write_b64 v136, v[8:9] offset:6944
	ds_write_b64 v136, v[0:1] offset:7008
	ds_read_b128 v[0:3], v140
	v_or_b32_e32 v4, 64, v138
	v_mul_u32_u24_e32 v4, s30, v4
	v_lshlrev_b32_e32 v134, 1, v4
	v_add_co_u32_e32 v4, vcc, v64, v134
	v_addc_co_u32_e32 v5, vcc, v65, v135, vcc
	s_waitcnt lgkmcnt(0)
	flat_store_dwordx4 v[4:5], v[0:3] nt
	ds_read_b128 v[0:3], v140 offset:1152
	v_or_b32_e32 v4, 0x48, v138
	v_mul_u32_u24_e32 v4, s30, v4
	v_lshlrev_b32_e32 v134, 1, v4
	v_add_co_u32_e32 v4, vcc, v64, v134
	v_addc_co_u32_e32 v5, vcc, v65, v135, vcc
	s_waitcnt lgkmcnt(0)
	flat_store_dwordx4 v[4:5], v[0:3] nt
	ds_read_b128 v[0:3], v140 offset:2304
	v_or_b32_e32 v4, 0x50, v138
	v_mul_u32_u24_e32 v4, s30, v4
	v_lshlrev_b32_e32 v134, 1, v4
	v_add_co_u32_e32 v4, vcc, v64, v134
	v_addc_co_u32_e32 v5, vcc, v65, v135, vcc
	s_waitcnt lgkmcnt(0)
	flat_store_dwordx4 v[4:5], v[0:3] nt
	ds_read_b128 v[0:3], v140 offset:3456
	v_or_b32_e32 v4, 0x58, v138
	v_mul_u32_u24_e32 v4, s30, v4
	v_lshlrev_b32_e32 v134, 1, v4
	v_add_co_u32_e32 v4, vcc, v64, v134
	v_addc_co_u32_e32 v5, vcc, v65, v135, vcc
	s_waitcnt lgkmcnt(0)
	flat_store_dwordx4 v[4:5], v[0:3] nt
	ds_read_b128 v[0:3], v140 offset:4608
	v_or_b32_e32 v4, 0x60, v138
	v_mul_u32_u24_e32 v4, s30, v4
	v_lshlrev_b32_e32 v134, 1, v4
	v_add_co_u32_e32 v4, vcc, v64, v134
	v_addc_co_u32_e32 v5, vcc, v65, v135, vcc
	s_waitcnt lgkmcnt(0)
	flat_store_dwordx4 v[4:5], v[0:3] nt
	ds_read_b128 v[0:3], v140 offset:5760
	v_or_b32_e32 v4, 0x68, v138
	v_mul_u32_u24_e32 v4, s30, v4
	v_lshlrev_b32_e32 v134, 1, v4
	v_add_co_u32_e32 v4, vcc, v64, v134
	v_addc_co_u32_e32 v5, vcc, v65, v135, vcc
	s_waitcnt lgkmcnt(0)
	flat_store_dwordx4 v[4:5], v[0:3] nt
	ds_read_b128 v[0:3], v140 offset:6912
	v_or_b32_e32 v4, 0x70, v138
	v_mul_u32_u24_e32 v4, s30, v4
	v_lshlrev_b32_e32 v134, 1, v4
	v_add_co_u32_e32 v4, vcc, v64, v134
	v_addc_co_u32_e32 v5, vcc, v65, v135, vcc
	s_waitcnt lgkmcnt(0)
	flat_store_dwordx4 v[4:5], v[0:3] nt
	ds_read_b128 v[0:3], v140 offset:8064
	v_or_b32_e32 v4, 0x78, v138
	v_mul_u32_u24_e32 v4, s30, v4
	v_lshlrev_b32_e32 v134, 1, v4
	v_add_co_u32_e32 v4, vcc, v64, v134
	v_addc_co_u32_e32 v5, vcc, v65, v135, vcc
	s_mov_b64 s[30:31], 0
	s_waitcnt lgkmcnt(0)
	flat_store_dwordx4 v[4:5], v[0:3] nt
.LBB0_175:
	s_and_b64 vcc, exec, s[30:31]
	s_cbranch_vccz .LBB0_179
	v_mov_b32_e32 v10, v132
	s_lshl_b32 s6, s26, 19
	v_lshlrev_b32_e32 v1, 4, v10
	v_and_b32_e32 v0, 32, v10
	v_lshrrev_b32_e32 v2, 1, v10
	v_bitop3_b32 v0, v1, v0, 48 bitop3:0x6c
	v_bfe_u32 v11, v10, 2, 4
	v_and_b32_e32 v12, 32, v2
	v_lshrrev_b32_e32 v13, 1, v0
	v_ashrrev_i32_e32 v14, 3, v10
	v_or_b32_e32 v4, v13, v12
	v_and_or_b32 v0, v14, s48, v11
	v_and_b32_e32 v3, 0xfffffc00, v1
	v_lshl_or_b32 v134, v0, 10, v4
	v_add_u32_e32 v0, 0x2000, v1
	v_add_u32_e32 v2, 0x4000, v1
	v_add_u32_e32 v1, 0x6000, v1
	v_ashrrev_i32_e32 v15, 7, v0
	v_ashrrev_i32_e32 v16, 7, v2
	v_ashrrev_i32_e32 v17, 7, v1
	v_and_or_b32 v0, v15, s48, v11
	v_and_or_b32 v2, v16, s48, v11
	v_and_or_b32 v1, v17, s48, v11
	v_add_u32_e32 v148, 0, v3
	s_add_u32 s30, s38, s6
	v_lshl_or_b32 v0, v0, 10, v4
	v_lshl_or_b32 v2, v2, 10, v4
	v_lshl_or_b32 v4, v1, 10, v4
	v_add_u32_e32 v1, 0x8000, v148
	v_lshlrev_b64 v[6:7], 1, v[134:135]
	v_readfirstlane_b32 s6, v148
	s_addc_u32 s31, s39, 0
	v_add_co_u32_e32 v8, vcc, v128, v6
	v_addc_co_u32_e32 v9, vcc, v129, v7, vcc
	s_mov_b32 m0, s6
	v_readfirstlane_b32 s6, v1
	v_mov_b32_e32 v1, v135
	v_add_u32_e32 v3, 0x2000, v148
	global_load_lds_dwordx4 v[8:9], off
	v_lshl_add_u64 v[6:7], s[30:31], 0, v[6:7]
	s_mov_b32 m0, s6
	v_lshlrev_b64 v[0:1], 1, v[0:1]
	v_readfirstlane_b32 s6, v3
	v_add_u32_e32 v3, 0xa000, v148
	global_load_lds_dwordx4 v[6:7], off
	v_add_co_u32_e32 v6, vcc, v128, v0
	v_addc_co_u32_e32 v7, vcc, v129, v1, vcc
	s_mov_b32 m0, s6
	v_readfirstlane_b32 s6, v3
	global_load_lds_dwordx4 v[6:7], off
	v_lshl_add_u64 v[0:1], s[30:31], 0, v[0:1]
	s_mov_b32 m0, s6
	v_mov_b32_e32 v3, v135
	v_add_u32_e32 v5, 0x4000, v148
	global_load_lds_dwordx4 v[0:1], off
	v_lshlrev_b64 v[0:1], 1, v[2:3]
	v_readfirstlane_b32 s6, v5
	v_add_co_u32_e32 v2, vcc, v128, v0
	v_addc_co_u32_e32 v3, vcc, v129, v1, vcc
	s_mov_b32 m0, s6
	v_lshl_add_u64 v[0:1], s[30:31], 0, v[0:1]
	global_load_lds_dwordx4 v[2:3], off
	v_add_u32_e32 v2, 0xc000, v148
	v_mov_b32_e32 v5, v135
	v_readfirstlane_b32 s6, v2
	s_mov_b32 m0, s6
	v_lshlrev_b32_e32 v6, 10, v11
	global_load_lds_dwordx4 v[0:1], off
	v_lshlrev_b64 v[0:1], 1, v[4:5]
	v_add_u32_e32 v4, 0x6000, v148
	v_add_co_u32_e32 v2, vcc, v128, v0
	v_addc_co_u32_e32 v3, vcc, v129, v1, vcc
	v_readfirstlane_b32 s6, v4
	s_mov_b32 m0, s6
	v_lshl_add_u64 v[0:1], s[30:31], 0, v[0:1]
	global_load_lds_dwordx4 v[2:3], off
	v_add_u32_e32 v2, 0xe000, v148
	s_add_u32 s30, s30, 0x80
	v_readfirstlane_b32 s6, v2
	s_mov_b32 m0, s6
	v_lshlrev_b32_e32 v2, 2, v10
	global_load_lds_dwordx4 v[0:1], off
	v_and_b32_e32 v0, 15, v10
	v_and_b32_e32 v1, 48, v10
	v_lshlrev_b32_e32 v0, 6, v0
	v_and_b32_e32 v2, 32, v2
	v_bitop3_b32 v149, v0, v2, v1 bitop3:0x36
	v_lshlrev_b32_e32 v0, 7, v10
	v_and_b32_e32 v150, 0x6000, v0
	v_lshlrev_b32_e32 v0, 6, v10
	v_and_b32_e32 v151, 0xffffc000, v0
	v_and_b32_e32 v0, 0x3c0, v0
	v_bitop3_b32 v153, v0, v2, v1 bitop3:0x36
	v_lshlrev_b32_e32 v0, 10, v17
	v_and_or_b32 v0, v0, s49, v13
	s_addc_u32 s31, s31, 0
	v_lshlrev_b32_e32 v2, 10, v16
	v_or3_b32 v134, v0, v6, v12
	v_and_or_b32 v2, v2, s49, v13
	v_lshlrev_b32_e32 v4, 10, v15
	s_add_u32 s4, s38, s4
	v_lshlrev_b64 v[0:1], 1, v[134:135]
	v_or3_b32 v134, v2, v6, v12
	v_and_or_b32 v4, v4, s49, v13
	v_lshlrev_b32_e32 v7, 10, v14
	s_addc_u32 s5, s39, s5
	v_lshlrev_b64 v[2:3], 1, v[134:135]
	v_or3_b32 v134, v4, v6, v12
	v_and_or_b32 v7, v7, s49, v13
	s_add_u32 s4, s4, 0x2400080
	s_nop 0
	v_lshlrev_b64 v[4:5], 1, v[134:135]
	v_or3_b32 v134, v7, v6, v12
	s_addc_u32 s5, s5, 0
	v_lshl_add_u64 v[128:129], s[30:31], 0, v[0:1]
	v_lshlrev_b64 v[6:7], 1, v[134:135]
	v_lshl_add_u64 v[140:141], s[4:5], 0, v[0:1]
	v_or_b32_e32 v152, 0x800, v151
	v_or_b32_e32 v154, 0x1000, v151
	v_or_b32_e32 v155, 0x1800, v151
	v_or_b32_e32 v156, 0x2000, v151
	v_or_b32_e32 v157, 0x2800, v151
	v_or_b32_e32 v158, 0x3000, v151
	v_or_b32_e32 v159, 0x3800, v151
	v_lshl_add_u64 v[130:131], s[30:31], 0, v[2:3]
	v_lshl_add_u64 v[136:137], s[30:31], 0, v[4:5]
	v_lshl_add_u64 v[138:139], s[30:31], 0, v[6:7]
	v_lshl_add_u64 v[142:143], s[4:5], 0, v[2:3]
	v_lshl_add_u64 v[144:145], s[4:5], 0, v[4:5]
	v_lshl_add_u64 v[146:147], s[4:5], 0, v[6:7]
	s_mov_b32 s6, 0
	s_mov_b64 s[4:5], 0
	s_waitcnt vmcnt(0) lgkmcnt(0)
	s_barrier
	v_readfirstlane_b32 s100, v148
	s_and_b32 s27, s6, 0x10000
	s_xor_b32 s30, s27, 0x10000
	s_add_i32 s27, s27, 0
	v_add3_u32 v134, s27, v149, v150
	v_add3_u32 v196, s27, v149, v151
	v_add3_u32 v197, s27, v153, v152
	v_add3_u32 v198, s27, v153, v154
	v_add3_u32 v199, s27, v153, v155
	v_add3_u32 v200, s27, v153, v156
	v_add3_u32 v201, s27, v153, v157
	v_add3_u32 v202, s27, v153, v158
	v_add3_u32 v203, s27, v153, v159
	ds_read_b128 v[180:183], v134 offset:32768
	ds_read_b128 v[160:163], v196
	ds_read_b128 v[168:171], v197
	ds_read_b128 v[172:175], v198
	ds_read_b128 v[176:179], v199
	ds_read_b128 v[184:187], v134 offset:34816
	ds_read_b128 v[188:191], v134 offset:36864
	ds_read_b128 v[192:195], v134 offset:38912
	s_add_i32 s101, s100, s30
	v_readfirstlane_b32 s98, v146
	v_readfirstlane_b32 s99, v147
	v_readfirstlane_b32 vcc_lo, v138
	v_readfirstlane_b32 vcc_hi, v139
	s_sub_u32 s98, s98, 0x1000000
	s_subb_u32 s99, s99, 0
	s_sub_u32 vcc_lo, vcc_lo, 0x1000000
	s_subb_u32 vcc_hi, vcc_hi, 0
	v_subrev_u32_e32 v146, s98, v146
	v_subrev_u32_e32 v138, vcc_lo, v138
	v_subrev_u32_e32 v144, s98, v144
	v_subrev_u32_e32 v136, vcc_lo, v136
	v_subrev_u32_e32 v142, s98, v142
	v_subrev_u32_e32 v130, vcc_lo, v130
	v_subrev_u32_e32 v140, s98, v140
	v_subrev_u32_e32 v128, vcc_lo, v128
	s_mov_b32 m0, s101
	s_nop 0
	global_load_lds_dwordx4 v146, s[98:99]
	s_add_i32 m0, s101, 0x8000
	s_nop 0
	global_load_lds_dwordx4 v138, vcc
	s_add_i32 m0, s101, 0x2000
	s_nop 0
	global_load_lds_dwordx4 v144, s[98:99]
	s_add_i32 m0, s101, 0xa000
	s_nop 0
	global_load_lds_dwordx4 v136, vcc
	s_add_i32 m0, s101, 0x4000
	s_nop 0
	global_load_lds_dwordx4 v142, s[98:99]
	s_add_i32 m0, s101, 0xc000
	s_nop 0
	global_load_lds_dwordx4 v130, vcc
	s_add_i32 m0, s101, 0x6000
	s_nop 0
	global_load_lds_dwordx4 v140, s[98:99]
	s_add_i32 m0, s101, 0xe000
	s_nop 0
	global_load_lds_dwordx4 v128, vcc

.Lex_181:
	s_waitcnt lgkmcnt(0)
	s_add_i32 s4, 0, 0x10000
	v_add3_u32 v130, s4, v154, v160
	v_add3_u32 v131, s4, v154, v159
	v_add3_u32 v212, s4, v154, v158
	v_add3_u32 v213, s4, v154, v157
	v_add3_u32 v214, s4, v154, v156
	v_add3_u32 v215, s4, v154, v155
	v_add3_u32 v134, s4, v154, v134
	v_add3_u32 v216, s4, v151, v153
	v_add3_u32 v217, s52, v151, v152
	ds_read_b128 v[136:139], v130
	ds_read_b128 v[140:143], v131
	ds_read_b128 v[144:147], v212
	ds_read_b128 v[158:161], v213
	ds_read_b128 v[168:171], v214
	ds_read_b128 v[172:175], v215
	ds_read_b128 v[154:157], v134
	ds_read_b128 v[176:179], v216
	ds_read_b128 v[148:151], v217
	s_waitcnt lgkmcnt(0)
	v_mfma_f32_16x16x32_bf16 v[16:19], v[148:151], v[140:143], v[16:19]
	v_mfma_f32_16x16x32_bf16 v[180:183], v[148:151], v[136:139], v[36:39]
	s_nop 2
	ds_read_b128 v[36:39], v217 offset:2048
	s_waitcnt lgkmcnt(0)
	v_mfma_f32_16x16x32_bf16 v[12:15], v[36:39], v[140:143], v[12:15]
	v_mfma_f32_16x16x32_bf16 v[184:187], v[36:39], v[136:139], v[28:31]
	s_nop 2
	ds_read_b128 v[28:31], v217 offset:4096
	s_waitcnt lgkmcnt(0)
	v_mfma_f32_16x16x32_bf16 v[4:7], v[28:31], v[140:143], v[4:7]
	v_mfma_f32_16x16x32_bf16 v[92:95], v[148:151], v[172:175], v[92:95]
	v_mfma_f32_16x16x32_bf16 v[76:79], v[148:151], v[168:171], v[76:79]
	v_mfma_f32_16x16x32_bf16 v[60:63], v[148:151], v[158:161], v[60:63]
	v_mfma_f32_16x16x32_bf16 v[204:207], v[36:39], v[172:175], v[88:91]
	v_mfma_f32_16x16x32_bf16 v[208:211], v[36:39], v[168:171], v[72:75]
	v_mfma_f32_16x16x32_bf16 v[72:75], v[148:151], v[176:179], v[124:127]
	v_mfma_f32_16x16x32_bf16 v[188:191], v[28:31], v[136:139], v[20:23]
	v_mfma_f32_16x16x32_bf16 v[84:87], v[28:31], v[172:175], v[84:87]
	v_mfma_f32_16x16x32_bf16 v[68:71], v[28:31], v[168:171], v[68:71]
	v_mfma_f32_16x16x32_bf16 v[88:91], v[148:151], v[154:157], v[108:111]
	ds_read_b128 v[20:23], v217 offset:6144
	s_waitcnt lgkmcnt(0)
	v_mfma_f32_16x16x32_bf16 v[136:139], v[20:23], v[136:139], v[8:11]
	v_mfma_f32_16x16x32_bf16 v[8:11], v[20:23], v[176:179], v[112:115]
	v_mfma_f32_16x16x32_bf16 v[192:195], v[20:23], v[154:157], v[96:99]
	v_mfma_f32_16x16x32_bf16 v[196:199], v[20:23], v[172:175], v[80:83]
	v_mfma_f32_16x16x32_bf16 v[200:203], v[20:23], v[168:171], v[64:67]
	v_mfma_f32_16x16x32_bf16 v[64:67], v[28:31], v[176:179], v[116:119]
	v_mfma_f32_16x16x32_bf16 v[80:83], v[28:31], v[154:157], v[100:103]
	v_mfma_f32_16x16x32_bf16 v[96:99], v[36:39], v[176:179], v[120:123]
	v_mfma_f32_16x16x32_bf16 v[100:103], v[36:39], v[154:157], v[104:107]
	v_mfma_f32_16x16x32_bf16 v[152:155], v[36:39], v[158:161], v[56:59]
	v_mfma_f32_16x16x32_bf16 v[52:55], v[28:31], v[158:161], v[52:55]
	v_mfma_f32_16x16x32_bf16 v[156:159], v[20:23], v[158:161], v[48:51]
	v_mfma_f32_16x16x32_bf16 v[44:47], v[148:151], v[144:147], v[44:47]
	v_mfma_f32_16x16x32_bf16 v[160:163], v[36:39], v[144:147], v[40:43]
	v_mfma_f32_16x16x32_bf16 v[168:171], v[28:31], v[144:147], v[32:35]
	v_mfma_f32_16x16x32_bf16 v[24:27], v[20:23], v[144:147], v[24:27]
	v_mfma_f32_16x16x32_bf16 v[0:3], v[20:23], v[140:143], v[0:3]
	ds_read_b128 v[140:143], v217 offset:1024
	ds_read_b128 v[144:147], v217 offset:3072
	ds_read_b128 v[148:151], v217 offset:5120
	ds_read_b128 v[172:175], v217 offset:7168
	ds_read_b128 v[20:23], v216 offset:1024
	ds_read_b128 v[28:31], v134 offset:1024
	ds_read_b128 v[32:35], v215 offset:1024
	ds_read_b128 v[36:39], v214 offset:1024
	s_waitcnt lgkmcnt(3)
	v_mfma_f32_16x16x32_bf16 v[108:111], v[140:143], v[20:23], v[72:75]
	v_mfma_f32_16x16x32_bf16 v[104:107], v[144:147], v[20:23], v[96:99]
	v_mfma_f32_16x16x32_bf16 v[116:119], v[148:151], v[20:23], v[64:67]
	v_mfma_f32_16x16x32_bf16 v[112:115], v[172:175], v[20:23], v[8:11]
	s_nop 2
	ds_read_b128 v[8:11], v213 offset:1024
	s_waitcnt lgkmcnt(3)
	v_mfma_f32_16x16x32_bf16 v[120:123], v[140:143], v[28:31], v[88:91]
	v_mfma_f32_16x16x32_bf16 v[96:99], v[144:147], v[28:31], v[100:103]
	v_mfma_f32_16x16x32_bf16 v[124:127], v[148:151], v[28:31], v[80:83]
	v_mfma_f32_16x16x32_bf16 v[100:103], v[172:175], v[28:31], v[192:195]
	ds_read_b128 v[20:23], v212 offset:1024
	s_waitcnt lgkmcnt(3)
	v_mfma_f32_16x16x32_bf16 v[88:91], v[140:143], v[32:35], v[92:95]
	v_mfma_f32_16x16x32_bf16 v[80:83], v[144:147], v[32:35], v[204:207]
	v_mfma_f32_16x16x32_bf16 v[92:95], v[148:151], v[32:35], v[84:87]
	v_mfma_f32_16x16x32_bf16 v[84:87], v[172:175], v[32:35], v[196:199]
	ds_read_b128 v[176:179], v131 offset:1024
	s_waitcnt lgkmcnt(3)
	v_mfma_f32_16x16x32_bf16 v[72:75], v[140:143], v[36:39], v[76:79]
	v_mfma_f32_16x16x32_bf16 v[64:67], v[144:147], v[36:39], v[208:211]
	v_mfma_f32_16x16x32_bf16 v[76:79], v[148:151], v[36:39], v[68:71]
	v_mfma_f32_16x16x32_bf16 v[68:71], v[172:175], v[36:39], v[200:203]
	ds_read_b128 v[192:195], v130 offset:1024
	s_waitcnt lgkmcnt(3)
	v_mfma_f32_16x16x32_bf16 v[56:59], v[140:143], v[8:11], v[60:63]
	v_mfma_f32_16x16x32_bf16 v[48:51], v[144:147], v[8:11], v[152:155]
	v_mfma_f32_16x16x32_bf16 v[60:63], v[148:151], v[8:11], v[52:55]
	v_mfma_f32_16x16x32_bf16 v[52:55], v[172:175], v[8:11], v[156:159]
	s_waitcnt lgkmcnt(2)
	v_mfma_f32_16x16x32_bf16 v[40:43], v[140:143], v[20:23], v[44:47]
	v_mfma_f32_16x16x32_bf16 v[32:35], v[144:147], v[20:23], v[160:163]
	v_mfma_f32_16x16x32_bf16 v[44:47], v[148:151], v[20:23], v[168:171]
	v_mfma_f32_16x16x32_bf16 v[36:39], v[172:175], v[20:23], v[24:27]
	s_waitcnt lgkmcnt(1)
	v_mfma_f32_16x16x32_bf16 v[24:27], v[140:143], v[176:179], v[16:19]
	v_mfma_f32_16x16x32_bf16 v[16:19], v[144:147], v[176:179], v[12:15]
	v_mfma_f32_16x16x32_bf16 v[28:31], v[148:151], v[176:179], v[4:7]
	v_mfma_f32_16x16x32_bf16 v[20:23], v[172:175], v[176:179], v[0:3]
	s_waitcnt lgkmcnt(0)
	v_mfma_f32_16x16x32_bf16 v[8:11], v[140:143], v[192:195], v[180:183]
	v_mfma_f32_16x16x32_bf16 v[0:3], v[144:147], v[192:195], v[184:187]
	v_mfma_f32_16x16x32_bf16 v[12:15], v[148:151], v[192:195], v[188:191]
	v_mfma_f32_16x16x32_bf16 v[4:7], v[172:175], v[192:195], v[136:139]
	v_mov_b32_e32 v147, v132
	s_waitcnt vmcnt(0)
	s_barrier
	s_lshl_b32 s26, s26, 8
	v_and_b32_e32 v146, 15, v147
	v_ashrrev_i32_e32 v130, 1, v147
	v_bfe_u32 v148, v147, 4, 2
	v_and_b32_e32 v149, 0xffffff80, v130
	v_or_b32_e32 v130, s66, v146
	v_add_u32_e32 v150, v130, v149
	v_and_b32_e32 v130, 64, v147
	v_lshlrev_b32_e32 v134, 5, v148
	v_add_co_u32_e32 v128, vcc, v128, v134
	v_addc_co_u32_e32 v129, vcc, v129, v135, vcc
	v_lshrrev_b32_e32 v151, 6, v150
	v_cmp_eq_u32_e32 vcc, 0, v130
	v_lshl_add_u64 v[136:137], v[128:129], 0, s[14:15]
	v_or_b32_e32 v130, 48, v146
	v_cndmask_b32_e32 v128, v146, v151, vcc
	v_lshlrev_b32_e32 v128, 8, v128
	v_and_b32_e32 v134, 0x3f00, v128
	v_lshl_add_u64 v[128:129], v[136:137], 0, v[134:135]
	flat_load_dwordx4 v[138:141], v[128:129]
	flat_load_dwordx4 v[142:145], v[128:129] offset:16
	flat_load_dwordx4 v[152:155], v[128:129] offset:128
	flat_load_dwordx4 v[156:159], v[128:129] offset:144
	v_or_b32_e32 v128, 16, v146
	v_cndmask_b32_e32 v128, v128, v151, vcc
	v_lshlrev_b32_e32 v128, 8, v128
	v_and_b32_e32 v134, 0x3f00, v128
	v_lshl_add_u64 v[128:129], v[136:137], 0, v[134:135]
	flat_load_dwordx4 v[160:163], v[128:129]
	flat_load_dwordx4 v[168:171], v[128:129] offset:16
	flat_load_dwordx4 v[172:175], v[128:129] offset:128
	flat_load_dwordx4 v[176:179], v[128:129] offset:144
	v_or_b32_e32 v128, 32, v146
	v_cndmask_b32_e32 v128, v128, v151, vcc
	v_lshlrev_b32_e32 v128, 8, v128
	v_and_b32_e32 v134, 0x3f00, v128
	v_lshl_add_u64 v[128:129], v[136:137], 0, v[134:135]
	flat_load_dwordx4 v[180:183], v[128:129]
	flat_load_dwordx4 v[184:187], v[128:129] offset:16
	flat_load_dwordx4 v[188:191], v[128:129] offset:128
	flat_load_dwordx4 v[192:195], v[128:129] offset:144
	v_cndmask_b32_e32 v130, v130, v151, vcc
	v_lshlrev_b32_e32 v130, 8, v130
	v_and_b32_e32 v134, 0x3f00, v130
	v_lshl_add_u64 v[204:205], v[136:137], 0, v[134:135]
	flat_load_dwordx4 v[196:199], v[204:205]
	flat_load_dwordx4 v[200:203], v[204:205] offset:16
	flat_load_dwordx4 v[128:131], v[204:205] offset:128
	v_or_b32_e32 v134, 1, v151
	v_cndmask_b32_e32 v134, v146, v134, vcc
	v_lshlrev_b32_e32 v134, 8, v134
	v_and_b32_e32 v134, 0x3f00, v134
	s_ashr_i32 s27, s26, 31
	s_waitcnt vmcnt(0) lgkmcnt(0)
	v_mov_b32_e32 v206, v139
	v_mov_b32_e32 v207, v141
	v_mov_b32_e32 v139, v140
	v_mov_b32_e32 v140, v143
	v_mov_b32_e32 v141, v145
	v_mov_b32_e32 v143, v144
	v_mov_b32_e32 v144, v153
	v_mov_b32_e32 v145, v155
	v_mov_b32_e32 v153, v154
	v_mov_b32_e32 v154, v157
	v_mov_b32_e32 v155, v159
	v_mov_b32_e32 v157, v158
	v_pk_mul_f32 v[158:159], v[108:109], v[206:207]
	v_pk_mul_f32 v[206:207], v[116:117], v[206:207]
	v_pk_mul_f32 v[208:209], v[110:111], v[140:141]
	v_pk_mul_f32 v[210:211], v[118:119], v[140:141]
	v_pk_mul_f32 v[214:215], v[112:113], v[144:145]
	v_pk_mul_f32 v[216:217], v[106:107], v[154:155]
	v_pk_mul_f32 v[154:155], v[114:115], v[154:155]
	v_mov_b32_e32 v218, v161
	v_mov_b32_e32 v219, v163
	v_mov_b32_e32 v161, v162
	v_mov_b32_e32 v162, v169
	v_mov_b32_e32 v163, v171
	v_pk_mul_f32 v[212:213], v[104:105], v[144:145]
	v_mov_b32_e32 v169, v170
	v_pk_fma_f32 v[116:117], v[116:117], v[138:139], v[158:159]
	v_pk_fma_f32 v[140:141], v[108:109], v[138:139], v[206:207] neg_lo:[0,0,1] neg_hi:[0,0,1]
	v_pk_fma_f32 v[118:119], v[118:119], v[142:143], v[208:209]
	v_pk_fma_f32 v[144:145], v[110:111], v[142:143], v[210:211] neg_lo:[0,0,1] neg_hi:[0,0,1]
	v_pk_fma_f32 v[138:139], v[104:105], v[152:153], v[214:215] neg_lo:[0,0,1] neg_hi:[0,0,1]
	v_pk_fma_f32 v[142:143], v[106:107], v[156:157], v[154:155] neg_lo:[0,0,1] neg_hi:[0,0,1]
	v_pk_mul_f32 v[104:105], v[120:121], v[218:219]
	v_pk_mul_f32 v[106:107], v[124:125], v[218:219]
	v_pk_mul_f32 v[108:109], v[122:123], v[162:163]
	v_pk_fma_f32 v[110:111], v[112:113], v[152:153], v[212:213]
	v_pk_fma_f32 v[112:113], v[114:115], v[156:157], v[216:217]
	v_pk_mul_f32 v[152:153], v[126:127], v[162:163]
	v_pk_fma_f32 v[104:105], v[124:125], v[160:161], v[104:105]
	v_pk_fma_f32 v[114:115], v[120:121], v[160:161], v[106:107] neg_lo:[0,0,1] neg_hi:[0,0,1]
	v_pk_fma_f32 v[106:107], v[126:127], v[168:169], v[108:109]
	flat_load_dwordx4 v[124:127], v[204:205] offset:144
	v_pk_fma_f32 v[120:121], v[122:123], v[168:169], v[152:153] neg_lo:[0,0,1] neg_hi:[0,0,1]
	v_lshl_add_u64 v[168:169], v[136:137], 0, v[134:135]
	flat_load_dwordx4 v[152:155], v[168:169]
	flat_load_dwordx4 v[156:159], v[168:169] offset:16
	v_mov_b32_e32 v122, v173
	v_mov_b32_e32 v123, v175
	v_pk_mul_f32 v[108:109], v[96:97], v[122:123]
	v_mov_b32_e32 v173, v174
	v_pk_fma_f32 v[108:109], v[100:101], v[172:173], v[108:109]
	v_pk_mul_f32 v[100:101], v[100:101], v[122:123]
	v_mov_b32_e32 v122, v177
	v_mov_b32_e32 v123, v179
	v_pk_fma_f32 v[96:97], v[96:97], v[172:173], v[100:101] neg_lo:[0,0,1] neg_hi:[0,0,1]
	v_pk_mul_f32 v[100:101], v[98:99], v[122:123]
	v_mov_b32_e32 v177, v178
	v_pk_fma_f32 v[100:101], v[102:103], v[176:177], v[100:101]
	v_pk_mul_f32 v[102:103], v[102:103], v[122:123]
	v_mov_b32_e32 v122, v181
	v_mov_b32_e32 v123, v183
	v_pk_fma_f32 v[102:103], v[98:99], v[176:177], v[102:103] neg_lo:[0,0,1] neg_hi:[0,0,1]
	v_pk_mul_f32 v[98:99], v[88:89], v[122:123]
	v_mov_b32_e32 v181, v182
	v_pk_fma_f32 v[98:99], v[92:93], v[180:181], v[98:99]
	v_pk_mul_f32 v[92:93], v[92:93], v[122:123]
	v_mov_b32_e32 v122, v185
	v_mov_b32_e32 v123, v187
	v_pk_fma_f32 v[92:93], v[88:89], v[180:181], v[92:93] neg_lo:[0,0,1] neg_hi:[0,0,1]
	v_pk_mul_f32 v[88:89], v[90:91], v[122:123]
	v_mov_b32_e32 v185, v186
	v_pk_fma_f32 v[88:89], v[94:95], v[184:185], v[88:89]
	v_pk_mul_f32 v[94:95], v[94:95], v[122:123]
	v_mov_b32_e32 v122, v189
	v_mov_b32_e32 v123, v191
	v_pk_fma_f32 v[94:95], v[90:91], v[184:185], v[94:95] neg_lo:[0,0,1] neg_hi:[0,0,1]
	v_pk_mul_f32 v[90:91], v[80:81], v[122:123]
	v_mov_b32_e32 v189, v190
	v_pk_fma_f32 v[90:91], v[84:85], v[188:189], v[90:91]
	v_pk_mul_f32 v[84:85], v[84:85], v[122:123]
	v_mov_b32_e32 v122, v193
	v_mov_b32_e32 v123, v195
	v_pk_fma_f32 v[84:85], v[80:81], v[188:189], v[84:85] neg_lo:[0,0,1] neg_hi:[0,0,1]
	v_pk_mul_f32 v[80:81], v[82:83], v[122:123]
	v_mov_b32_e32 v193, v194
	v_pk_fma_f32 v[80:81], v[86:87], v[192:193], v[80:81]
	v_pk_mul_f32 v[86:87], v[86:87], v[122:123]
	v_or_b32_e32 v122, 0x50, v150
	flat_load_dwordx4 v[160:163], v[168:169] offset:128
	v_lshrrev_b32_e32 v123, 6, v122
	v_cndmask_b32_e32 v122, v122, v123, vcc
	v_lshlrev_b32_e32 v122, 8, v122
	flat_load_dwordx4 v[168:171], v[168:169] offset:144
	v_and_b32_e32 v134, 0x3f00, v122
	v_lshl_add_u64 v[122:123], v[136:137], 0, v[134:135]
	v_mov_b32_e32 v180, v197
	v_mov_b32_e32 v181, v199
	flat_load_dwordx4 v[172:175], v[122:123]
	v_pk_fma_f32 v[86:87], v[82:83], v[192:193], v[86:87] neg_lo:[0,0,1] neg_hi:[0,0,1]
	v_pk_mul_f32 v[82:83], v[72:73], v[180:181]
	v_mov_b32_e32 v197, v198
	v_pk_fma_f32 v[82:83], v[76:77], v[196:197], v[82:83]
	v_pk_mul_f32 v[76:77], v[76:77], v[180:181]
	v_mov_b32_e32 v184, v201
	v_mov_b32_e32 v185, v203
	flat_load_dwordx4 v[176:179], v[122:123] offset:16
	v_pk_fma_f32 v[72:73], v[72:73], v[196:197], v[76:77] neg_lo:[0,0,1] neg_hi:[0,0,1]
	v_pk_mul_f32 v[76:77], v[74:75], v[184:185]
	v_mov_b32_e32 v201, v202
	flat_load_dwordx4 v[180:183], v[122:123] offset:128
	v_pk_fma_f32 v[76:77], v[78:79], v[200:201], v[76:77]
	v_pk_mul_f32 v[78:79], v[78:79], v[184:185]
	flat_load_dwordx4 v[184:187], v[122:123] offset:144
	v_or_b32_e32 v122, 0x60, v150
	v_lshrrev_b32_e32 v123, 6, v122
	v_cndmask_b32_e32 v122, v122, v123, vcc
	v_lshlrev_b32_e32 v122, 8, v122
	v_and_b32_e32 v134, 0x3f00, v122
	v_mov_b32_e32 v192, v129
	v_mov_b32_e32 v193, v131
	v_lshl_add_u64 v[194:195], v[136:137], 0, v[134:135]
	v_pk_fma_f32 v[74:75], v[74:75], v[200:201], v[78:79] neg_lo:[0,0,1] neg_hi:[0,0,1]
	v_pk_mul_f32 v[78:79], v[64:65], v[192:193]
	flat_load_dwordx4 v[188:191], v[194:195]
	v_mov_b32_e32 v129, v130
	v_pk_fma_f32 v[78:79], v[68:69], v[128:129], v[78:79]
	v_pk_mul_f32 v[68:69], v[68:69], v[192:193]
	v_cvt_pk_bf16_f32 v96, v96, v97
	v_pk_fma_f32 v[68:69], v[64:65], v[128:129], v[68:69] neg_lo:[0,0,1] neg_hi:[0,0,1]
	s_waitcnt vmcnt(0) lgkmcnt(0)
	v_mov_b32_e32 v64, v125
	v_mov_b32_e32 v65, v127
	flat_load_dwordx4 v[128:131], v[194:195] offset:16
	v_pk_mul_f32 v[122:123], v[66:67], v[64:65]
	v_mov_b32_e32 v125, v126
	v_pk_mul_f32 v[64:65], v[70:71], v[64:65]
	v_pk_fma_f32 v[122:123], v[70:71], v[124:125], v[122:123]
	v_pk_fma_f32 v[66:67], v[66:67], v[124:125], v[64:65] neg_lo:[0,0,1] neg_hi:[0,0,1]
	flat_load_dwordx4 v[124:127], v[194:195] offset:128
	v_mov_b32_e32 v70, v153
	v_mov_b32_e32 v71, v155
	v_pk_mul_f32 v[64:65], v[56:57], v[70:71]
	v_mov_b32_e32 v153, v154
	v_pk_fma_f32 v[64:65], v[60:61], v[152:153], v[64:65]
	v_pk_mul_f32 v[60:61], v[60:61], v[70:71]
	v_mov_b32_e32 v70, v157
	v_pk_fma_f32 v[56:57], v[56:57], v[152:153], v[60:61] neg_lo:[0,0,1] neg_hi:[0,0,1]
	v_or_b32_e32 v60, 0x70, v150
	v_lshrrev_b32_e32 v61, 6, v60
	v_cndmask_b32_e32 v60, v60, v61, vcc
	v_lshlrev_b32_e32 v60, 8, v60
	flat_load_dwordx4 v[152:155], v[194:195] offset:144
	v_and_b32_e32 v134, 0x3f00, v60
	v_add_co_u32_e32 v136, vcc, v136, v134
	v_addc_co_u32_e32 v137, vcc, v137, v135, vcc
	flat_load_dwordx4 v[192:195], v[136:137]
	v_mov_b32_e32 v71, v159
	v_pk_mul_f32 v[60:61], v[58:59], v[70:71]
	v_mov_b32_e32 v157, v158
	flat_load_dwordx4 v[196:199], v[136:137] offset:16
	v_pk_fma_f32 v[60:61], v[62:63], v[156:157], v[60:61]
	v_pk_mul_f32 v[62:63], v[62:63], v[70:71]
	v_cvt_pk_bf16_f32 v97, v102, v103
	v_pk_fma_f32 v[62:63], v[58:59], v[156:157], v[62:63] neg_lo:[0,0,1] neg_hi:[0,0,1]
	flat_load_dwordx4 v[156:159], v[136:137] offset:128
	v_cvt_pk_bf16_f32 v84, v84, v85
	v_cvt_pk_bf16_f32 v85, v86, v87
	v_cvt_pk_bf16_f32 v110, v110, v111
	v_cvt_pk_bf16_f32 v111, v112, v113
	v_cvt_pk_bf16_f32 v68, v68, v69
	v_mov_b32_e32 v70, v161
	v_mov_b32_e32 v71, v163
	v_pk_mul_f32 v[58:59], v[48:49], v[70:71]
	v_mov_b32_e32 v161, v162
	v_pk_fma_f32 v[58:59], v[52:53], v[160:161], v[58:59]
	v_pk_mul_f32 v[52:53], v[52:53], v[70:71]
	v_cvt_pk_bf16_f32 v69, v66, v67
	v_pk_fma_f32 v[70:71], v[48:49], v[160:161], v[52:53] neg_lo:[0,0,1] neg_hi:[0,0,1]
	v_mov_b32_e32 v48, v169
	v_mov_b32_e32 v49, v171
	v_pk_mul_f32 v[52:53], v[50:51], v[48:49]
	v_mov_b32_e32 v169, v170
	v_pk_fma_f32 v[52:53], v[54:55], v[168:169], v[52:53]
	v_pk_mul_f32 v[48:49], v[54:55], v[48:49]
	v_mov_b32_e32 v54, v173
	v_mov_b32_e32 v55, v175
	v_pk_fma_f32 v[50:51], v[50:51], v[168:169], v[48:49] neg_lo:[0,0,1] neg_hi:[0,0,1]
	v_pk_mul_f32 v[48:49], v[40:41], v[54:55]
	v_mov_b32_e32 v173, v174
	v_pk_fma_f32 v[48:49], v[44:45], v[172:173], v[48:49]
	v_pk_mul_f32 v[44:45], v[44:45], v[54:55]
	v_mov_b32_e32 v54, v177
	v_mov_b32_e32 v55, v179
	v_pk_fma_f32 v[44:45], v[40:41], v[172:173], v[44:45] neg_lo:[0,0,1] neg_hi:[0,0,1]
	v_pk_mul_f32 v[40:41], v[42:43], v[54:55]
	v_mov_b32_e32 v177, v178
	v_pk_fma_f32 v[40:41], v[46:47], v[176:177], v[40:41]
	v_pk_mul_f32 v[46:47], v[46:47], v[54:55]
	v_mov_b32_e32 v54, v181
	v_mov_b32_e32 v55, v183
	v_pk_fma_f32 v[46:47], v[42:43], v[176:177], v[46:47] neg_lo:[0,0,1] neg_hi:[0,0,1]
	v_pk_mul_f32 v[42:43], v[32:33], v[54:55]
	v_mov_b32_e32 v181, v182
	v_pk_fma_f32 v[42:43], v[36:37], v[180:181], v[42:43]
	v_pk_mul_f32 v[36:37], v[36:37], v[54:55]
	v_cvt_pk_bf16_f32 v66, v82, v83
	v_pk_fma_f32 v[54:55], v[32:33], v[180:181], v[36:37] neg_lo:[0,0,1] neg_hi:[0,0,1]
	v_mov_b32_e32 v32, v185
	v_mov_b32_e32 v33, v187
	v_pk_mul_f32 v[36:37], v[34:35], v[32:33]
	v_mov_b32_e32 v185, v186
	v_pk_fma_f32 v[36:37], v[38:39], v[184:185], v[36:37]
	v_pk_mul_f32 v[32:33], v[38:39], v[32:33]
	v_mov_b32_e32 v38, v189
	v_mov_b32_e32 v39, v191
	v_pk_fma_f32 v[34:35], v[34:35], v[184:185], v[32:33] neg_lo:[0,0,1] neg_hi:[0,0,1]
	v_pk_mul_f32 v[32:33], v[24:25], v[38:39]
	v_mov_b32_e32 v189, v190
	v_pk_fma_f32 v[32:33], v[28:29], v[188:189], v[32:33]
	v_pk_mul_f32 v[28:29], v[28:29], v[38:39]
	s_waitcnt vmcnt(0) lgkmcnt(0)
	v_mov_b32_e32 v38, v129
	v_mov_b32_e32 v39, v131
	v_pk_fma_f32 v[28:29], v[24:25], v[188:189], v[28:29] neg_lo:[0,0,1] neg_hi:[0,0,1]
	v_pk_mul_f32 v[24:25], v[26:27], v[38:39]
	v_mov_b32_e32 v129, v130
	v_pk_fma_f32 v[24:25], v[30:31], v[128:129], v[24:25]
	v_pk_mul_f32 v[30:31], v[30:31], v[38:39]
	v_mov_b32_e32 v38, v125
	v_mov_b32_e32 v39, v127
	v_pk_fma_f32 v[30:31], v[26:27], v[128:129], v[30:31] neg_lo:[0,0,1] neg_hi:[0,0,1]
	v_pk_mul_f32 v[26:27], v[16:17], v[38:39]
	v_mov_b32_e32 v125, v126
	v_pk_fma_f32 v[26:27], v[20:21], v[124:125], v[26:27]
	v_pk_mul_f32 v[20:21], v[20:21], v[38:39]
	v_add_u32_e32 v128, s66, v149
	v_pk_fma_f32 v[38:39], v[16:17], v[124:125], v[20:21] neg_lo:[0,0,1] neg_hi:[0,0,1]
	flat_load_dwordx4 v[124:127], v[136:137] offset:144
	v_mov_b32_e32 v16, v153
	v_mov_b32_e32 v17, v155
	v_pk_mul_f32 v[20:21], v[18:19], v[16:17]
	v_mov_b32_e32 v153, v154
	v_pk_fma_f32 v[20:21], v[22:23], v[152:153], v[20:21]
	v_pk_mul_f32 v[16:17], v[22:23], v[16:17]
	v_mov_b32_e32 v22, v193
	v_mov_b32_e32 v23, v195
	v_pk_fma_f32 v[18:19], v[18:19], v[152:153], v[16:17] neg_lo:[0,0,1] neg_hi:[0,0,1]
	v_pk_mul_f32 v[16:17], v[8:9], v[22:23]
	v_mov_b32_e32 v193, v194
	v_pk_fma_f32 v[16:17], v[12:13], v[192:193], v[16:17]
	v_pk_mul_f32 v[12:13], v[12:13], v[22:23]
	v_mov_b32_e32 v22, v197
	v_mov_b32_e32 v23, v199
	v_pk_fma_f32 v[12:13], v[8:9], v[192:193], v[12:13] neg_lo:[0,0,1] neg_hi:[0,0,1]
	v_pk_mul_f32 v[8:9], v[10:11], v[22:23]
	v_mov_b32_e32 v197, v198
	v_pk_fma_f32 v[8:9], v[14:15], v[196:197], v[8:9]
	v_pk_mul_f32 v[14:15], v[14:15], v[22:23]
	v_mov_b32_e32 v22, v157
	v_mov_b32_e32 v23, v159
	v_pk_fma_f32 v[10:11], v[10:11], v[196:197], v[14:15] neg_lo:[0,0,1] neg_hi:[0,0,1]
	v_pk_mul_f32 v[14:15], v[0:1], v[22:23]
	v_mov_b32_e32 v157, v158
	v_pk_fma_f32 v[14:15], v[4:5], v[156:157], v[14:15]
	v_pk_mul_f32 v[4:5], v[4:5], v[22:23]
	v_mov_b32_e32 v22, s19
	ds_read_b64 v[22:23], v22
	v_ashrrev_i32_e32 v129, 31, v128
	v_lshlrev_b64 v[128:129], 10, v[128:129]
	v_lshrrev_b32_e32 v130, 6, v147
	v_mul_u32_u24_e32 v136, 0x90, v146
	s_waitcnt lgkmcnt(0)
	v_add_co_u32_e32 v22, vcc, v22, v128
	v_addc_co_u32_e32 v23, vcc, v23, v129, vcc
	v_and_b32_e32 v128, 0xc0, v147
	v_lshl_add_u64 v[22:23], s[26:27], 1, v[22:23]
	v_lshlrev_b32_e32 v134, 1, v128
	v_mul_lo_u32 v128, v130, s55
	v_lshlrev_b32_e32 v130, 4, v147
	v_add_co_u32_e32 v22, vcc, v22, v134
	v_addc_co_u32_e32 v23, vcc, v23, v135, vcc
	v_add_u32_e32 v128, s4, v128
	v_lshlrev_b32_e32 v129, 3, v148
	v_and_b32_e32 v134, 0x70, v130
	v_bfe_u32 v130, v147, 3, 3
	v_mul_u32_u24_e32 v131, 0x90, v130
	v_add3_u32 v136, v128, v129, v136
	v_add3_u32 v131, v128, v134, v131
	v_cvt_pk_bf16_f32 v128, v140, v141
	v_cvt_pk_bf16_f32 v129, v144, v145
	ds_write_b64 v136, v[96:97] offset:2336
	v_cvt_pk_bf16_f32 v96, v104, v105
	v_cvt_pk_bf16_f32 v97, v106, v107
	ds_write_b64 v136, v[84:85] offset:4640
	v_cvt_pk_bf16_f32 v84, v98, v99
	v_cvt_pk_bf16_f32 v85, v88, v89
	v_cvt_pk_bf16_f32 v67, v76, v77
	ds_write_b64 v136, v[128:129]
	v_cvt_pk_bf16_f32 v128, v138, v139
	v_cvt_pk_bf16_f32 v129, v142, v143
	v_cvt_pk_bf16_f32 v116, v116, v117
	v_cvt_pk_bf16_f32 v117, v118, v119
	ds_write_b64 v136, v[110:111] offset:96
	v_cvt_pk_bf16_f32 v110, v114, v115
	v_cvt_pk_bf16_f32 v111, v120, v121
	ds_write_b64 v136, v[96:97] offset:2368
	v_cvt_pk_bf16_f32 v96, v108, v109
	v_cvt_pk_bf16_f32 v97, v100, v101
	v_cvt_pk_bf16_f32 v92, v92, v93
	v_cvt_pk_bf16_f32 v93, v94, v95
	ds_write_b64 v136, v[84:85] offset:4672
	v_cvt_pk_bf16_f32 v84, v90, v91
	v_cvt_pk_bf16_f32 v85, v80, v81
	v_cvt_pk_bf16_f32 v72, v72, v73
	v_cvt_pk_bf16_f32 v73, v74, v75
	ds_write_b64 v136, v[66:67] offset:6976
	v_cvt_pk_bf16_f32 v66, v78, v79
	v_cvt_pk_bf16_f32 v67, v122, v123
	ds_write_b64 v136, v[128:129] offset:32
	ds_write_b64 v136, v[116:117] offset:64
	ds_write_b64 v136, v[110:111] offset:2304
	ds_write_b64 v136, v[96:97] offset:2400
	ds_write_b64 v136, v[92:93] offset:4608
	ds_write_b64 v136, v[84:85] offset:4704
	ds_write_b64 v136, v[72:73] offset:6912
	ds_write_b64 v136, v[68:69] offset:6944
	ds_write_b64 v136, v[66:67] offset:7008
	ds_read_b128 v[66:69], v131
	v_add_co_u32_e32 v22, vcc, v22, v134
	v_addc_co_u32_e32 v23, vcc, v23, v135, vcc
	v_lshl_add_u64 v[22:23], v[22:23], 0, s[24:25]
	v_lshlrev_b32_e32 v134, 10, v130
	v_add_co_u32_e32 v72, vcc, v22, v134
	v_addc_co_u32_e32 v73, vcc, v23, v135, vcc
	s_waitcnt lgkmcnt(0)
	flat_store_dwordx4 v[72:73], v[66:69] nt
	ds_read_b128 v[66:69], v131 offset:1152
	v_pk_fma_f32 v[0:1], v[0:1], v[156:157], v[4:5] neg_lo:[0,0,1] neg_hi:[0,0,1]
	v_or_b32_e32 v4, 0x2000, v134
	v_mov_b32_e32 v5, v135
	v_add_co_u32_e32 v4, vcc, v22, v4
	v_addc_co_u32_e32 v5, vcc, v23, v5, vcc
	s_waitcnt lgkmcnt(0)
	flat_store_dwordx4 v[4:5], v[66:69] nt
	ds_read_b128 v[66:69], v131 offset:2304
	v_or_b32_e32 v74, 0x4000, v134
	v_mov_b32_e32 v75, v135
	v_add_co_u32_e32 v74, vcc, v22, v74
	v_addc_co_u32_e32 v75, vcc, v23, v75, vcc
	v_or_b32_e32 v76, 0x8000, v134
	s_waitcnt lgkmcnt(0)
	flat_store_dwordx4 v[74:75], v[66:69] nt
	ds_read_b128 v[66:69], v131 offset:3456
	v_or_b32_e32 v74, 0x6000, v134
	v_mov_b32_e32 v75, v135
	v_add_co_u32_e32 v74, vcc, v22, v74
	v_addc_co_u32_e32 v75, vcc, v23, v75, vcc
	v_mov_b32_e32 v77, v135
	s_waitcnt lgkmcnt(0)
	flat_store_dwordx4 v[74:75], v[66:69] nt
	ds_read_b128 v[66:69], v131 offset:4608
	v_add_co_u32_e32 v76, vcc, v22, v76
	v_addc_co_u32_e32 v77, vcc, v23, v77, vcc
	s_waitcnt vmcnt(0)
	v_mov_b32_e32 v4, v125
	v_mov_b32_e32 v5, v127
	v_pk_mul_f32 v[74:75], v[2:3], v[4:5]
	s_waitcnt lgkmcnt(0)
	flat_store_dwordx4 v[76:77], v[66:69] nt
	ds_read_b128 v[66:69], v131 offset:5760
	v_or_b32_e32 v76, 0xa000, v134
	v_mov_b32_e32 v77, v135
	v_add_co_u32_e32 v76, vcc, v22, v76
	v_addc_co_u32_e32 v77, vcc, v23, v77, vcc
	v_mov_b32_e32 v125, v126
	s_waitcnt lgkmcnt(0)
	flat_store_dwordx4 v[76:77], v[66:69] nt
	ds_read_b128 v[66:69], v131 offset:6912
	v_or_b32_e32 v76, 0xc000, v134
	v_mov_b32_e32 v77, v135
	v_add_co_u32_e32 v76, vcc, v22, v76
	v_addc_co_u32_e32 v77, vcc, v23, v77, vcc
	v_pk_mul_f32 v[4:5], v[6:7], v[4:5]
	s_waitcnt lgkmcnt(0)
	flat_store_dwordx4 v[76:77], v[66:69] nt
	ds_read_b128 v[66:69], v131 offset:8064
	v_or_b32_e32 v134, 0xe000, v134
	v_pk_fma_f32 v[2:3], v[2:3], v[124:125], v[4:5] neg_lo:[0,0,1] neg_hi:[0,0,1]
	v_add_co_u32_e32 v4, vcc, v22, v134
	v_addc_co_u32_e32 v5, vcc, v23, v135, vcc
	v_cvt_pk_bf16_f32 v0, v0, v1
	s_waitcnt lgkmcnt(0)
	flat_store_dwordx4 v[4:5], v[66:69] nt
	v_cvt_pk_bf16_f32 v4, v56, v57
	v_cvt_pk_bf16_f32 v5, v62, v63
	ds_write_b64 v136, v[4:5]
	v_cvt_pk_bf16_f32 v4, v70, v71
	v_cvt_pk_bf16_f32 v5, v50, v51
	ds_write_b64 v136, v[4:5] offset:32
	v_cvt_pk_bf16_f32 v4, v64, v65
	v_cvt_pk_bf16_f32 v5, v60, v61
	ds_write_b64 v136, v[4:5] offset:64
	v_cvt_pk_bf16_f32 v4, v58, v59
	v_cvt_pk_bf16_f32 v5, v52, v53
	ds_write_b64 v136, v[4:5] offset:96
	v_cvt_pk_bf16_f32 v4, v44, v45
	v_cvt_pk_bf16_f32 v5, v46, v47
	ds_write_b64 v136, v[4:5] offset:2304
	v_cvt_pk_bf16_f32 v4, v54, v55
	v_cvt_pk_bf16_f32 v5, v34, v35
	ds_write_b64 v136, v[4:5] offset:2336
	v_cvt_pk_bf16_f32 v4, v48, v49
	v_cvt_pk_bf16_f32 v5, v40, v41
	ds_write_b64 v136, v[4:5] offset:2368
	v_cvt_pk_bf16_f32 v4, v42, v43
	v_cvt_pk_bf16_f32 v5, v36, v37
	ds_write_b64 v136, v[4:5] offset:2400
	v_cvt_pk_bf16_f32 v4, v28, v29
	v_cvt_pk_bf16_f32 v5, v30, v31
	ds_write_b64 v136, v[4:5] offset:4608
	v_cvt_pk_bf16_f32 v4, v38, v39
	v_cvt_pk_bf16_f32 v5, v18, v19
	ds_write_b64 v136, v[4:5] offset:4640
	v_cvt_pk_bf16_f32 v4, v32, v33
	v_cvt_pk_bf16_f32 v5, v24, v25
	v_cvt_pk_bf16_f32 v1, v2, v3
	v_pk_fma_f32 v[74:75], v[6:7], v[124:125], v[74:75]
	ds_write_b64 v136, v[4:5] offset:4672
	v_cvt_pk_bf16_f32 v4, v26, v27
	v_cvt_pk_bf16_f32 v5, v20, v21
	ds_write_b64 v136, v[0:1] offset:6944
	v_cvt_pk_bf16_f32 v0, v16, v17
	v_cvt_pk_bf16_f32 v1, v8, v9
	ds_write_b64 v136, v[4:5] offset:4704
	v_cvt_pk_bf16_f32 v4, v12, v13
	v_cvt_pk_bf16_f32 v5, v10, v11
	ds_write_b64 v136, v[0:1] offset:6976
	v_cvt_pk_bf16_f32 v0, v14, v15
	v_cvt_pk_bf16_f32 v1, v74, v75
	ds_write_b64 v136, v[4:5] offset:6912
	ds_write_b64 v136, v[0:1] offset:7008
	ds_read_b128 v[0:3], v131
	v_add_co_u32_e32 v4, vcc, s50, v72
	s_nop 1
	v_addc_co_u32_e32 v5, vcc, 0, v73, vcc
	s_waitcnt lgkmcnt(0)
	flat_store_dwordx4 v[4:5], v[0:3] nt
	ds_read_b128 v[0:3], v131 offset:1152
	v_add_co_u32_e32 v4, vcc, s62, v72
	s_nop 1
	v_addc_co_u32_e32 v5, vcc, 0, v73, vcc
	s_waitcnt lgkmcnt(0)
	flat_store_dwordx4 v[4:5], v[0:3] nt
	ds_read_b128 v[0:3], v131 offset:2304
	v_add_co_u32_e32 v4, vcc, s63, v72
	s_nop 1
	v_addc_co_u32_e32 v5, vcc, 0, v73, vcc
	s_waitcnt lgkmcnt(0)
	flat_store_dwordx4 v[4:5], v[0:3] nt
	ds_read_b128 v[0:3], v131 offset:3456
	v_add_co_u32_e32 v4, vcc, s64, v72
	s_nop 1
	v_addc_co_u32_e32 v5, vcc, 0, v73, vcc
	s_waitcnt lgkmcnt(0)
	flat_store_dwordx4 v[4:5], v[0:3] nt
	ds_read_b128 v[0:3], v131 offset:4608
	v_add_co_u32_e32 v4, vcc, s51, v72
	s_nop 1
	v_addc_co_u32_e32 v5, vcc, 0, v73, vcc
	s_waitcnt lgkmcnt(0)
	flat_store_dwordx4 v[4:5], v[0:3] nt
	ds_read_b128 v[0:3], v131 offset:5760
	v_add_co_u32_e32 v4, vcc, 0x1a000, v72
	s_nop 1
	v_addc_co_u32_e32 v5, vcc, 0, v73, vcc
	s_waitcnt lgkmcnt(0)
	flat_store_dwordx4 v[4:5], v[0:3] nt
	ds_read_b128 v[0:3], v131 offset:6912
	v_add_co_u32_e32 v4, vcc, 0x1c000, v72
	s_nop 1
	v_addc_co_u32_e32 v5, vcc, 0, v73, vcc
	s_waitcnt lgkmcnt(0)
	flat_store_dwordx4 v[4:5], v[0:3] nt
	ds_read_b128 v[0:3], v131 offset:8064
	v_add_co_u32_e32 v4, vcc, 0x1e000, v72
	s_nop 1
	v_addc_co_u32_e32 v5, vcc, 0, v73, vcc
	s_waitcnt lgkmcnt(0)
	flat_store_dwordx4 v[4:5], v[0:3] nt
	s_branch .LBB0_137

.LBB0_233:
	v_bfe_u32 v102, v179, 2, 1
	v_cmp_eq_u32_e64 s[0:1], 0, v102
	v_bfe_u32 v2, v179, 3, 2
	v_lshlrev_b32_e32 v2, 2, v2
	v_cndmask_b32_e64 v0, v171, v172, s[0:1]
	ds_read_b64 v[0:1], v0
	v_mov_b32_e32 v3, v135
	v_lshrrev_b32_e32 v4, 3, v179
	v_cndmask_b32_e64 v134, v175, v176, s[0:1]
	v_and_b32_e32 v104, 4, v179
	s_waitcnt lgkmcnt(0)
	v_add_co_u32_e32 v0, vcc, v0, v2
	v_addc_co_u32_e32 v1, vcc, v1, v3, vcc
	flat_load_dword v97, v[0:1]
	ds_read_b64 v[0:1], v178
	v_lshlrev_b32_e32 v2, 6, v179
	v_and_b32_e32 v103, 0xc0, v2
	v_ashrrev_i32_e32 v2, 3, v179
	v_bfi_b32 v96, -4, v2, v4
	v_lshl_or_b32 v100, v96, 7, v166
	v_lshlrev_b32_e32 v2, 8, v96
	v_ashrrev_i32_e32 v101, 31, v100
	v_or3_b32 v98, v2, v103, v166
	s_waitcnt lgkmcnt(0)
	v_add_co_u32_e32 v2, vcc, v0, v134
	v_addc_co_u32_e32 v3, vcc, v1, v135, vcc
	v_lshlrev_b64 v[4:5], 9, v[100:101]
	s_waitcnt vmcnt(0)
	v_add_co_u32_e32 v32, vcc, v2, v4
	v_addc_co_u32_e32 v33, vcc, v3, v5, vcc
	v_lshlrev_b32_e32 v134, 8, v102
	v_add_co_u32_e32 v2, vcc, v32, v134
	v_addc_co_u32_e32 v3, vcc, v33, v135, vcc
	v_add_co_u32_e32 v28, vcc, v2, v138
	v_addc_co_u32_e32 v29, vcc, v3, v139, vcc
	v_add_co_u32_e32 v8, vcc, s21, v28
	v_ashrrev_i32_e32 v99, 31, v98
	s_nop 0
	v_addc_co_u32_e32 v9, vcc, 0, v29, vcc
	v_add_co_u32_e32 v10, vcc, s22, v28
	v_lshlrev_b64 v[2:3], 9, v[98:99]
	s_nop 0
	v_addc_co_u32_e32 v11, vcc, 0, v29, vcc
	v_add_co_u32_e32 v12, vcc, s23, v28
	v_lshl_add_u64 v[0:1], v[0:1], 0, v[2:3]
	s_nop 0
	v_addc_co_u32_e32 v13, vcc, 0, v29, vcc
	v_lshl_add_u64 v[34:35], v[0:1], 0, s[12:13]
	v_add_co_u32_e32 v14, vcc, s24, v28
	v_lshl_add_u64 v[0:1], v[34:35], 0, v[134:135]
	s_nop 0
	v_addc_co_u32_e32 v15, vcc, 0, v29, vcc
	v_add_co_u32_e32 v40, vcc, v0, v138
	v_addc_co_u32_e32 v41, vcc, v1, v139, vcc
	flat_load_dwordx4 v[0:3], v[8:9]
	flat_load_dwordx4 v[4:7], v[10:11]
	s_nop 0
	flat_load_dwordx4 v[8:11], v[12:13]
	flat_load_dwordx4 v[16:19], v[14:15]
	v_add_co_u32_e32 v12, vcc, s25, v28
	v_xor_b32_e32 v134, 0x100, v134
	s_nop 0
	v_addc_co_u32_e32 v13, vcc, 0, v29, vcc
	v_add_co_u32_e32 v14, vcc, s26, v28
	v_lshl_add_u64 v[32:33], v[32:33], 0, v[134:135]
	s_nop 0
	v_addc_co_u32_e32 v15, vcc, 0, v29, vcc
	v_add_co_u32_e32 v42, vcc, s27, v28
	flat_load_dwordx4 v[20:23], v[12:13]
	flat_load_dwordx4 v[24:27], v[14:15]
	v_addc_co_u32_e32 v43, vcc, 0, v29, vcc
	v_add_co_u32_e32 v48, vcc, s21, v40
	flat_load_dwordx4 v[12:15], v[28:29]
	flat_load_dwordx4 v[36:39], v[40:41]
	v_addc_co_u32_e32 v49, vcc, 0, v41, vcc
	flat_load_dwordx4 v[28:31], v[42:43]
	flat_load_dwordx4 v[44:47], v[48:49]
	v_add_co_u32_e32 v42, vcc, s22, v40
	v_lshl_add_u64 v[76:77], v[32:33], 0, v[138:139]
	s_nop 0
	v_addc_co_u32_e32 v43, vcc, 0, v41, vcc
	v_add_co_u32_e32 v40, vcc, s23, v40
	v_lshl_add_u64 v[32:33], v[34:35], 0, v[134:135]
	s_nop 0
	v_addc_co_u32_e32 v41, vcc, 0, v41, vcc
	v_add_co_u32_e32 v48, vcc, s21, v76
	flat_load_dwordx4 v[56:59], v[42:43]
	flat_load_dwordx4 v[64:67], v[40:41]
	v_addc_co_u32_e32 v49, vcc, 0, v77, vcc
	v_add_co_u32_e32 v50, vcc, s22, v76
	v_lshl_add_u64 v[88:89], v[32:33], 0, v[138:139]
	s_nop 0
	v_addc_co_u32_e32 v51, vcc, 0, v77, vcc
	v_add_co_u32_e32 v52, vcc, s23, v76
	flat_load_dwordx4 v[32:35], v[48:49]
	flat_load_dwordx4 v[40:43], v[50:51]
	v_addc_co_u32_e32 v53, vcc, 0, v77, vcc
	v_add_co_u32_e32 v54, vcc, s24, v76
	s_waitcnt vmcnt(0)
	v_mul_f32_e32 v97, 0x43000000, v97
	v_addc_co_u32_e32 v55, vcc, 0, v77, vcc
	flat_load_dwordx4 v[48:51], v[52:53]
	flat_load_dwordx4 v[60:63], v[54:55]
	v_add_co_u32_e32 v52, vcc, s25, v76
	v_mul_f32_e32 v105, 0x3fb8aa3b, v97
	s_nop 0
	v_addc_co_u32_e32 v53, vcc, 0, v77, vcc
	v_add_co_u32_e32 v54, vcc, s26, v76
	v_fma_f32 v106, v97, s3, -v105
	s_nop 0
	v_addc_co_u32_e32 v55, vcc, 0, v77, vcc
	v_add_co_u32_e32 v78, vcc, 0xe000, v76
	flat_load_dwordx4 v[68:71], v[52:53]
	flat_load_dwordx4 v[72:75], v[54:55]
	v_addc_co_u32_e32 v79, vcc, 0, v77, vcc
	v_add_co_u32_e32 v84, vcc, s21, v88
	flat_load_dwordx4 v[52:55], v[76:77]
	flat_load_dwordx4 v[80:83], v[88:89]
	v_addc_co_u32_e32 v85, vcc, 0, v89, vcc
	v_add_co_u32_e32 v90, vcc, s22, v88
	flat_load_dwordx4 v[76:79], v[78:79]
	s_nop 0
	flat_load_dwordx4 v[84:87], v[84:85]
	v_addc_co_u32_e32 v91, vcc, 0, v89, vcc
	v_add_co_u32_e32 v92, vcc, 0x6000, v88
	v_rndne_f32_e32 v107, v105
	s_nop 0
	v_addc_co_u32_e32 v93, vcc, 0, v89, vcc
	flat_load_dwordx4 v[88:91], v[90:91]
	s_nop 0
	flat_load_dwordx4 v[92:95], v[92:93]
	v_fmac_f32_e32 v106, 0x32a5705f, v97
	v_sub_f32_e32 v105, v105, v107
	v_add_f32_e32 v105, v105, v106
	v_exp_f32_e32 v105, v105
	v_cvt_i32_f32_e32 v106, v107
	v_cmp_ne_u32_e64 s[6:7], 0, v104
	v_cmp_ngt_f32_e32 vcc, s18, v97
	v_or_b32_e32 v103, v103, v165
	v_ldexp_f32 v104, v105, v106
	v_cndmask_b32_e32 v104, 0, v104, vcc
	v_cmp_nlt_f32_e32 vcc, s19, v97
	v_ashrrev_i32_e32 v97, 31, v96
	v_cndmask_b32_e64 v140, v173, v174, s[0:1]
	v_cndmask_b32_e32 v142, v177, v104, vcc
	v_mov_b32_e32 v141, v135
	v_mov_b32_e32 v143, v142
	v_mov_b32_e32 v144, v142
	v_mov_b32_e32 v145, v142
	v_lshlrev_b32_e32 v146, 7, v103
	v_lshlrev_b64 v[148:149], 13, v[100:101]
	v_lshlrev_b64 v[150:151], 13, v[98:99]
	v_lshlrev_b64 v[152:153], 22, v[96:97]
	v_lshlrev_b32_e32 v154, 16, v102
	v_mov_b32_e32 v155, v135
	s_mov_b32 s42, 30
	s_mov_b32 s43, 0
	s_mov_b32 s44, 0
	v_mov_b32_e32 v124, v135
	v_mov_b32_e32 v125, v135
	v_mov_b32_e32 v126, v135
	v_mov_b32_e32 v127, v135
	v_mov_b32_e32 v120, v135
	v_mov_b32_e32 v121, v135
	v_mov_b32_e32 v122, v135
	v_mov_b32_e32 v123, v135
	v_mov_b32_e32 v112, v135
	v_mov_b32_e32 v113, v135
	v_mov_b32_e32 v114, v135
	v_mov_b32_e32 v115, v135
	v_mov_b32_e32 v108, v135
	v_mov_b32_e32 v109, v135
	v_mov_b32_e32 v110, v135
	v_mov_b32_e32 v111, v135
	v_mov_b32_e32 v104, v135
	v_mov_b32_e32 v105, v135
	v_mov_b32_e32 v106, v135
	v_mov_b32_e32 v107, v135
	v_mov_b32_e32 v100, v135
	v_mov_b32_e32 v101, v135
	v_mov_b32_e32 v102, v135
	v_mov_b32_e32 v103, v135
	v_mov_b32_e32 v96, v135
	v_mov_b32_e32 v97, v135
	v_mov_b32_e32 v98, v135
	v_mov_b32_e32 v99, v135
	v_mov_b32_e32 v116, v135
	v_mov_b32_e32 v117, v135
	v_mov_b32_e32 v118, v135
	v_mov_b32_e32 v119, v135
	s_branch .LBB0_235

.LBB0_244:
	s_cmp_lg_u32 s43, 32
	s_cselect_b64 s[16:17], -1, 0
	s_cmp_eq_u32 s43, 32
	ds_write_b128 v168, v[12:15]
	ds_write_b128 v168, v[0:3] offset:4352
	ds_write_b128 v168, v[4:7] offset:8704
	ds_write_b128 v168, v[8:11] offset:13056
	ds_write_b128 v168, v[16:19] offset:17408
	ds_write_b128 v168, v[20:23] offset:21760
	ds_write_b128 v168, v[24:27] offset:26112
	ds_write_b128 v168, v[28:31] offset:30464
	ds_write_b128 v168, v[36:39] offset:34816
	ds_write_b128 v168, v[44:47] offset:39168
	ds_write_b128 v168, v[56:59] offset:43520
	ds_write_b128 v168, v[64:67] offset:47872
	s_cbranch_scc1 .LBB0_246
	v_mov_b32_e32 v0, s20
	ds_read_b64 v[0:1], v0
	s_add_i32 s46, s42, 1
	v_mov_b32_e32 v2, s43
	v_mov_b32_e32 v3, s46
	v_cndmask_b32_e64 v4, v3, v2, s[0:1]
	s_waitcnt lgkmcnt(0)
	v_add_co_u32_e32 v2, vcc, v0, v140
	v_addc_co_u32_e32 v3, vcc, v1, v141, vcc
	v_add_co_u32_e32 v2, vcc, v2, v148
	v_addc_co_u32_e32 v3, vcc, v3, v149, vcc
	v_lshlrev_b32_e32 v134, 8, v4
	v_add_co_u32_e32 v2, vcc, v2, v134
	v_addc_co_u32_e32 v3, vcc, v3, v135, vcc
	v_mov_b32_e32 v137, v135
	v_add_co_u32_e32 v0, vcc, v0, v150
	v_addc_co_u32_e32 v1, vcc, v1, v151, vcc
	v_add_co_u32_e32 v24, vcc, v2, v136
	v_addc_co_u32_e32 v25, vcc, v3, v137, vcc
	v_add_co_u32_e32 v0, vcc, v0, v134
	v_addc_co_u32_e32 v1, vcc, v1, v135, vcc
	v_add_co_u32_e32 v56, vcc, v0, v136
	v_addc_co_u32_e32 v57, vcc, v1, v137, vcc
	v_add_co_u32_e32 v0, vcc, s29, v24
	s_nop 1
	v_addc_co_u32_e32 v1, vcc, 0, v25, vcc
	v_add_co_u32_e32 v4, vcc, s30, v24
	flat_load_dwordx4 v[12:15], v[24:25]
	s_nop 0
	flat_load_dwordx4 v[0:3], v[0:1]
	v_addc_co_u32_e32 v5, vcc, 0, v25, vcc
	v_add_co_u32_e32 v8, vcc, s31, v24
	s_nop 1
	v_addc_co_u32_e32 v9, vcc, 0, v25, vcc
	v_add_co_u32_e32 v16, vcc, s34, v24
	flat_load_dwordx4 v[4:7], v[4:5]
	s_nop 0
	flat_load_dwordx4 v[8:11], v[8:9]
	v_addc_co_u32_e32 v17, vcc, 0, v25, vcc
	v_add_co_u32_e32 v20, vcc, s35, v24
	s_nop 1
	v_addc_co_u32_e32 v21, vcc, 0, v25, vcc
	v_add_co_u32_e32 v26, vcc, s36, v24
	flat_load_dwordx4 v[16:19], v[16:17]
	s_nop 0
	flat_load_dwordx4 v[20:23], v[20:21]
	v_addc_co_u32_e32 v27, vcc, 0, v25, vcc
	v_add_co_u32_e32 v28, vcc, s37, v24
	s_nop 1
	v_addc_co_u32_e32 v29, vcc, 0, v25, vcc
	v_add_co_u32_e32 v36, vcc, s38, v56
	flat_load_dwordx4 v[24:27], v[26:27]
	s_nop 0
	flat_load_dwordx4 v[28:31], v[28:29]
	v_addc_co_u32_e32 v37, vcc, 0, v57, vcc
	v_add_co_u32_e32 v44, vcc, 0x14820000, v56
	s_nop 1
	v_addc_co_u32_e32 v45, vcc, 0, v57, vcc
	v_add_co_u32_e32 v58, vcc, 0x14840000, v56
	flat_load_dwordx4 v[36:39], v[36:37]
	s_nop 0
	flat_load_dwordx4 v[44:47], v[44:45]
	v_addc_co_u32_e32 v59, vcc, 0, v57, vcc
	v_add_co_u32_e32 v64, vcc, 0x14860000, v56
	s_nop 1
	v_addc_co_u32_e32 v65, vcc, 0, v57, vcc
	flat_load_dwordx4 v[56:59], v[58:59]
	s_nop 0
	flat_load_dwordx4 v[64:67], v[64:65]

.LBB0_253:
	s_and_b64 vcc, exec, s[4:5]
	s_cbranch_vccnz .LBB0_255
	v_mov_b32_e32 v137, s28
	ds_read_b64 v[180:181], v137
	v_lshlrev_b64 v[182:183], 17, v[134:135]
	v_mov_b32_e32 v159, v135
	v_mov_b32_e32 v157, v135
	v_cvt_pk_bf16_f32 v184, v124, v125
	s_waitcnt lgkmcnt(0)
	v_add_co_u32_e32 v180, vcc, v180, v182
	v_addc_co_u32_e32 v181, vcc, v181, v183, vcc
	v_add_co_u32_e32 v180, vcc, v180, v152
	v_addc_co_u32_e32 v181, vcc, v181, v153, vcc
	v_add_co_u32_e32 v180, vcc, v180, v154
	v_addc_co_u32_e32 v181, vcc, v181, v155, vcc
	v_add_co_u32_e32 v158, vcc, v180, v158
	v_addc_co_u32_e32 v159, vcc, v181, v159, vcc
	v_add_co_u32_e32 v156, vcc, v158, v156
	v_addc_co_u32_e32 v157, vcc, v159, v157, vcc
	v_cvt_pk_bf16_f32 v158, v120, v121
	v_cvt_pk_bf16_f32 v159, v122, v123
	flat_store_dwordx2 v[156:157], v[158:159] offset:32
	v_cvt_pk_bf16_f32 v158, v116, v117
	v_cvt_pk_bf16_f32 v159, v118, v119
	flat_store_dwordx2 v[156:157], v[158:159] offset:64
	v_cvt_pk_bf16_f32 v158, v112, v113
	v_cvt_pk_bf16_f32 v159, v114, v115
	flat_store_dwordx2 v[156:157], v[158:159] offset:96
	v_cvt_pk_bf16_f32 v158, v108, v109
	v_cvt_pk_bf16_f32 v159, v110, v111
	flat_store_dwordx2 v[156:157], v[158:159] offset:128
	v_cvt_pk_bf16_f32 v158, v104, v105
	v_cvt_pk_bf16_f32 v159, v106, v107
	flat_store_dwordx2 v[156:157], v[158:159] offset:160
	v_cvt_pk_bf16_f32 v158, v100, v101
	v_cvt_pk_bf16_f32 v159, v102, v103
	v_cvt_pk_bf16_f32 v185, v126, v127
	flat_store_dwordx2 v[156:157], v[158:159] offset:192
	v_cvt_pk_bf16_f32 v158, v96, v97
	v_cvt_pk_bf16_f32 v159, v98, v99
	flat_store_dwordx2 v[156:157], v[184:185]
	flat_store_dwordx2 v[156:157], v[158:159] offset:224
.LBB0_255:
	s_andn2_b64 vcc, exec, s[16:17]
	s_waitcnt vmcnt(0)
	ds_write_b128 v168, v[52:55]
	ds_write_b128 v168, v[32:35] offset:4352
	ds_write_b128 v168, v[40:43] offset:8704
	ds_write_b128 v168, v[48:51] offset:13056
	ds_write_b128 v168, v[60:63] offset:17408
	ds_write_b128 v168, v[68:71] offset:21760
	ds_write_b128 v168, v[72:75] offset:26112
	ds_write_b128 v168, v[76:79] offset:30464
	ds_write_b128 v168, v[80:83] offset:34816
	ds_write_b128 v168, v[84:87] offset:39168
	ds_write_b128 v168, v[88:91] offset:43520
	ds_write_b128 v168, v[92:95] offset:47872
	s_cbranch_vccnz .LBB0_234
	v_mov_b32_e32 v32, s20
	ds_read_b64 v[32:33], v32
	v_mov_b32_e32 v34, s42
	v_mov_b32_e32 v35, s14
	v_cndmask_b32_e64 v34, v34, v35, s[0:1]
	v_lshlrev_b32_e32 v134, 8, v34
	s_waitcnt lgkmcnt(0)
	v_add_co_u32_e32 v34, vcc, v32, v140
	v_addc_co_u32_e32 v35, vcc, v33, v141, vcc
	v_add_co_u32_e32 v34, vcc, v34, v148
	v_addc_co_u32_e32 v35, vcc, v35, v149, vcc
	v_add_co_u32_e32 v34, vcc, v34, v134
	v_addc_co_u32_e32 v35, vcc, v35, v135, vcc
	v_mov_b32_e32 v137, v135
	v_add_co_u32_e32 v32, vcc, v32, v150
	v_addc_co_u32_e32 v33, vcc, v33, v151, vcc
	v_add_co_u32_e32 v72, vcc, v34, v136
	v_addc_co_u32_e32 v73, vcc, v35, v137, vcc
	v_add_co_u32_e32 v32, vcc, v32, v134
	v_addc_co_u32_e32 v33, vcc, v33, v135, vcc
	v_add_co_u32_e32 v88, vcc, v32, v136
	v_addc_co_u32_e32 v89, vcc, v33, v137, vcc
	v_add_co_u32_e32 v32, vcc, s29, v72
	s_nop 1
	v_addc_co_u32_e32 v33, vcc, 0, v73, vcc
	v_add_co_u32_e32 v40, vcc, s30, v72
	flat_load_dwordx4 v[52:55], v[72:73]
	s_nop 0
	flat_load_dwordx4 v[32:35], v[32:33]
	v_addc_co_u32_e32 v41, vcc, 0, v73, vcc
	v_add_co_u32_e32 v48, vcc, s31, v72
	s_nop 1
	v_addc_co_u32_e32 v49, vcc, 0, v73, vcc
	v_add_co_u32_e32 v60, vcc, s34, v72
	flat_load_dwordx4 v[40:43], v[40:41]
	s_nop 0
	flat_load_dwordx4 v[48:51], v[48:49]
	v_addc_co_u32_e32 v61, vcc, 0, v73, vcc
	v_add_co_u32_e32 v68, vcc, s35, v72
	s_nop 1
	v_addc_co_u32_e32 v69, vcc, 0, v73, vcc
	v_add_co_u32_e32 v74, vcc, s36, v72
	flat_load_dwordx4 v[60:63], v[60:61]
	s_nop 0
	flat_load_dwordx4 v[68:71], v[68:69]
	v_addc_co_u32_e32 v75, vcc, 0, v73, vcc
	v_add_co_u32_e32 v76, vcc, s37, v72
	s_nop 1
	v_addc_co_u32_e32 v77, vcc, 0, v73, vcc
	v_add_co_u32_e32 v80, vcc, s38, v88
	flat_load_dwordx4 v[72:75], v[74:75]
	s_nop 0
	flat_load_dwordx4 v[76:79], v[76:77]
	v_addc_co_u32_e32 v81, vcc, 0, v89, vcc
	v_add_co_u32_e32 v84, vcc, 0x14820000, v88
	s_nop 1
	v_addc_co_u32_e32 v85, vcc, 0, v89, vcc
	v_add_co_u32_e32 v90, vcc, 0x14840000, v88
	flat_load_dwordx4 v[80:83], v[80:81]
	s_nop 0
	flat_load_dwordx4 v[84:87], v[84:85]
	v_addc_co_u32_e32 v91, vcc, 0, v89, vcc
	v_add_co_u32_e32 v92, vcc, 0x14860000, v88
	s_nop 1
	v_addc_co_u32_e32 v93, vcc, 0, v89, vcc
	flat_load_dwordx4 v[88:91], v[90:91]
	s_nop 0
	flat_load_dwordx4 v[92:95], v[92:93]
	s_branch .LBB0_234

.LBB0_260:
	s_or_b64 exec, exec, s[8:9]
	s_abs_i32 s0, s33
	v_cvt_f32_u32_e32 v0, s0
	v_sub_u32_e32 v1, s33, v147
	v_add_u32_e32 v2, 0xfff, v1
	v_sub_u32_e32 v1, 0xfffff001, v1
	v_rcp_iflag_f32_e32 v0, v0
	s_sub_i32 s1, 0, s0
	v_xor_b32_e32 v3, s33, v2
	v_max_i32_e32 v1, v2, v1
	v_mul_f32_e32 v0, 0x4f7ffffe, v0
	v_cvt_u32_f32_e32 v0, v0
	v_ashrrev_i32_e32 v2, 31, v3
	v_and_b32_e32 v100, 56, v129
	v_lshrrev_b32_e32 v103, 3, v133
	v_mul_lo_u32 v3, s1, v0
	v_mul_hi_u32 v3, v0, v3
	v_add_u32_e32 v0, v0, v3
	v_mul_hi_u32 v0, v1, v0
	v_mul_lo_u32 v3, v0, s0
	v_sub_u32_e32 v1, v1, v3
	v_add_u32_e32 v4, 1, v0
	v_cmp_le_u32_e32 vcc, s0, v1
	v_subrev_u32_e32 v3, s0, v1
	s_waitcnt vmcnt(0)
	v_lshlrev_b32_e32 v40, 1, v100
	v_cndmask_b32_e32 v0, v0, v4, vcc
	v_cndmask_b32_e32 v1, v1, v3, vcc
	v_add_u32_e32 v3, 1, v0
	v_cmp_le_u32_e32 vcc, s0, v1
	s_nop 1
	v_cndmask_b32_e32 v0, v0, v3, vcc
	v_xor_b32_e32 v0, v0, v2
	v_sub_u32_e32 v101, v0, v2
	v_cmp_lt_i32_e64 s[0:1], 0, v101
	s_and_saveexec_b64 s[4:5], s[0:1]
	s_cbranch_execz .LBB0_262
	v_and_b32_e32 v42, 63, v147
	v_sub_u32_e64 v0, v42, 4 clamp
	s_add_i32 s3, 0, 0x240a8
	v_min_u32_e32 v3, 56, v0
	v_mov_b32_e32 v0, s3
	ds_read_b64 v[32:33], v0
	v_lshlrev_b32_e32 v0, 3, v147
	s_movk_i32 s3, 0xf000
	v_and_or_b32 v43, v0, s3, v103
	v_lshl_or_b32 v0, v3, 6, v43
	v_ashrrev_i32_e32 v1, 31, v0
	v_and_b32_e32 v2, 0x1c0, v147
	v_lshlrev_b64 v[0:1], 10, v[0:1]
	s_waitcnt lgkmcnt(0)
	v_add_co_u32_e32 v0, vcc, v32, v0
	v_addc_co_u32_e32 v1, vcc, v33, v1, vcc
	v_lshlrev_b32_e32 v34, 1, v2
	v_mov_b32_e32 v35, 0
	v_add_co_u32_e32 v0, vcc, v0, v34
	v_addc_co_u32_e32 v1, vcc, v1, v35, vcc
	v_mov_b32_e32 v41, v35
	s_movk_i32 s3, 0xffc0
	v_add_co_u32_e32 v8, vcc, v0, v40
	v_addc_co_u32_e32 v9, vcc, v1, v41, vcc
	v_and_or_b32 v0, v147, s3, v166
	s_mov_b32 s3, 0x8800000
	v_add_co_u32_e32 v10, vcc, s3, v8
	s_mov_b32 s3, 0x8808000
	s_nop 0
	v_addc_co_u32_e32 v11, vcc, 0, v9, vcc
	v_add_co_u32_e32 v12, vcc, s3, v8
	v_ashrrev_i32_e32 v1, 31, v0
	s_nop 0
	v_addc_co_u32_e32 v13, vcc, 0, v9, vcc
	s_mov_b32 s3, 0x8810000
	v_lshlrev_b64 v[0:1], 13, v[0:1]
	v_add_co_u32_e32 v16, vcc, s3, v8
	v_lshl_add_u64 v[0:1], v[32:33], 0, v[0:1]
	v_lshlrev_b32_e32 v2, 7, v3
	v_mov_b32_e32 v3, v35
	v_addc_co_u32_e32 v17, vcc, 0, v9, vcc
	s_mov_b32 s3, 0x8818000
	v_add_co_u32_e32 v0, vcc, v0, v2
	v_addc_co_u32_e32 v1, vcc, v1, v3, vcc
	v_mov_b32_e32 v129, v35
	v_add_co_u32_e32 v18, vcc, s3, v8
	v_lshl_add_u64 v[24:25], v[128:129], 1, v[0:1]
	s_nop 0
	v_addc_co_u32_e32 v19, vcc, 0, v9, vcc
	s_mov_b32 s3, 0xa800000
	v_add_co_u32_e32 v26, vcc, s3, v24
	s_mov_b32 s3, 0xa820000
	s_nop 0
	v_addc_co_u32_e32 v27, vcc, 0, v25, vcc
	v_add_co_u32_e32 v28, vcc, s3, v24
	s_mov_b32 s3, 0xa840000
	s_nop 0
	v_addc_co_u32_e32 v29, vcc, 0, v25, vcc
	v_add_co_u32_e32 v36, vcc, s3, v24
	s_mov_b32 s3, 0xa860000
	s_nop 0
	v_addc_co_u32_e32 v37, vcc, 0, v25, vcc
	v_add_co_u32_e32 v38, vcc, s3, v24
	flat_load_dwordx4 v[0:3], v[10:11]
	flat_load_dwordx4 v[4:7], v[12:13]
	s_nop 0
	flat_load_dwordx4 v[8:11], v[16:17]
	flat_load_dwordx4 v[12:15], v[18:19]
	s_nop 0
	flat_load_dwordx4 v[16:19], v[26:27]
	flat_load_dwordx4 v[20:23], v[28:29]
	v_addc_co_u32_e32 v39, vcc, 0, v25, vcc
	flat_load_dwordx4 v[24:27], v[36:37]
	flat_load_dwordx4 v[28:31], v[38:39]
	v_lshl_or_b32 v36, v42, 6, v43
	v_ashrrev_i32_e32 v37, 31, v36
	v_lshlrev_b64 v[36:37], 10, v[36:37]
	v_add_co_u32_e32 v32, vcc, v32, v36
	v_addc_co_u32_e32 v33, vcc, v33, v37, vcc
	v_add_co_u32_e32 v32, vcc, v32, v34
	v_addc_co_u32_e32 v33, vcc, v33, v35, vcc
	v_add_co_u32_e32 v32, vcc, v32, v40
	v_addc_co_u32_e32 v33, vcc, v33, v41, vcc
	v_add_co_u32_e32 v42, vcc, 0x6800000, v32
	s_nop 1
	v_addc_co_u32_e32 v43, vcc, 0, v33, vcc
	v_add_co_u32_e32 v44, vcc, 0x6808000, v32
	s_nop 1
	v_addc_co_u32_e32 v45, vcc, 0, v33, vcc
	flat_load_dwordx4 v[32:35], v[42:43]
	flat_load_dwordx4 v[36:39], v[44:45]

.LBB0_264:
	ds_bpermute_b32 v40, v127, v155
	v_lshlrev_b32_e32 v68, 3, v151
	v_lshlrev_b32_e32 v70, 6, v150
	v_and_b32_e32 v68, 0xfffff000, v68
	v_or3_b32 v68, v68, v70, v165
	s_waitcnt lgkmcnt(0)
	v_add_f32_e32 v40, v155, v40
	ds_bpermute_b32 v69, v134, v40
	v_mov_b32_e32 v42, s80
	ds_read_b64 v[42:43], v42
	s_waitcnt lgkmcnt(1)
	v_add_f32_e32 v40, v40, v69
	v_div_scale_f32 v70, s[34:35], v40, v40, 1.0
	v_rcp_f32_e32 v71, v70
	v_div_scale_f32 v72, vcc, 1.0, v40, 1.0
	v_ashrrev_i32_e32 v69, 31, v68
	v_fma_f32 v73, -v70, v71, 1.0
	v_fmac_f32_e32 v71, v73, v71
	v_mul_f32_e32 v73, v72, v71
	v_fma_f32 v74, -v70, v73, v72
	v_fmac_f32_e32 v73, v74, v71
	v_fma_f32 v70, -v70, v73, v72
	v_div_fmas_f32 v70, v70, v71, v73
	v_lshlrev_b64 v[68:69], 10, v[68:69]
	v_div_fixup_f32 v70, v70, v40, 1.0
	s_waitcnt lgkmcnt(0)
	v_add_co_u32_e32 v42, vcc, v42, v68
	v_addc_co_u32_e32 v43, vcc, v43, v69, vcc
	v_lshlrev_b32_e32 v40, 1, v102
	v_add_co_u32_e32 v42, vcc, v42, v40
	v_addc_co_u32_e32 v43, vcc, v43, v41, vcc
	v_lshl_add_u64 v[42:43], v[130:131], 1, v[42:43]
	v_lshl_add_u64 v[68:69], v[42:43], 0, s[58:59]
	v_pk_mul_f32 v[64:65], v[64:65], v[70:71] op_sel_hi:[1,0]
	v_pk_mul_f32 v[66:67], v[66:67], v[70:71] op_sel_hi:[1,0]
	v_add_co_u32_e32 v42, vcc, s83, v42
	v_cvt_pk_bf16_f32 v64, v64, v65
	v_cvt_pk_bf16_f32 v65, v66, v67
	v_addc_co_u32_e32 v43, vcc, 0, v43, vcc
	flat_store_dwordx2 v[42:43], v[64:65]
	v_pk_mul_f32 v[42:43], v[60:61], v[70:71] op_sel_hi:[1,0]
	v_pk_mul_f32 v[60:61], v[62:63], v[70:71] op_sel_hi:[1,0]
	v_cvt_pk_bf16_f32 v42, v42, v43
	v_cvt_pk_bf16_f32 v43, v60, v61
	flat_store_dwordx2 v[68:69], v[42:43] offset:32
	v_pk_mul_f32 v[42:43], v[56:57], v[70:71] op_sel_hi:[1,0]
	v_pk_mul_f32 v[56:57], v[58:59], v[70:71] op_sel_hi:[1,0]
	v_cvt_pk_bf16_f32 v42, v42, v43
	v_cvt_pk_bf16_f32 v43, v56, v57
	flat_store_dwordx2 v[68:69], v[42:43] offset:64
	v_pk_mul_f32 v[42:43], v[52:53], v[70:71] op_sel_hi:[1,0]
	v_pk_mul_f32 v[52:53], v[54:55], v[70:71] op_sel_hi:[1,0]
	v_cmp_eq_u32_e32 vcc, s86, v101
	v_cvt_pk_bf16_f32 v42, v42, v43
	v_cvt_pk_bf16_f32 v43, v52, v53
	s_or_b64 s[46:47], vcc, s[46:47]
	flat_store_dwordx2 v[68:69], v[42:43] offset:96
	s_andn2_b64 exec, exec, s[46:47]
	s_cbranch_execz .LBB0_319

.LBB0_267:
	s_cmp_eq_u32 s87, 0
	s_cselect_b64 s[36:37], -1, 0
	s_cmp_lg_u32 s87, 0
	s_waitcnt lgkmcnt(0)
	s_barrier
	s_waitcnt vmcnt(0)
	ds_write_b128 v123, v[0:3] offset:9216
	ds_write_b128 v123, v[4:7] offset:13824
	ds_write_b128 v123, v[8:11] offset:18432
	ds_write_b128 v123, v[12:15] offset:23040
	ds_write_b128 v124, v[16:19] offset:27648
	ds_write_b128 v124, v[20:23] offset:32000
	ds_write_b128 v124, v[24:27] offset:36352
	ds_write_b128 v124, v[28:31] offset:40704
	s_cbranch_scc1 .LBB0_271
	ds_write_b128 v123, v[32:35]
	ds_write_b128 v123, v[36:39] offset:4608
	v_mov_b32_e32 v40, s78
	ds_read_b64 v[42:43], v40
	s_mov_b64 s[60:61], 0
	v_mov_b32_e32 v40, v148
	v_mov_b32_e32 v68, v146
	s_waitcnt lgkmcnt(0)
	v_add_co_u32_e32 v42, vcc, v42, v114
	v_addc_co_u32_e32 v43, vcc, v43, v115, vcc

.LBB0_271:
	s_cmp_eq_u32 s87, 5
	s_mov_b64 s[60:61], -1
	s_waitcnt lgkmcnt(0)
	s_barrier
	s_cbranch_scc1 .LBB0_277
	v_mov_b32_e32 v40, s80
	ds_read_b64 v[68:69], v40
	s_lshl_b32 s62, s87, 7
	s_cmp_gt_u32 s87, 2
	s_cbranch_scc0 .LBB0_274
	s_add_i32 s44, s62, 0xfffffe80
	v_add_u32_e32 v42, s44, v152
	v_ashrrev_i32_e32 v43, 31, v42
	v_lshlrev_b64 v[42:43], 10, v[42:43]
	s_waitcnt lgkmcnt(0)
	v_add_co_u32_e32 v42, vcc, v68, v42
	v_addc_co_u32_e32 v43, vcc, v69, v43, vcc
	v_add_co_u32_e32 v70, vcc, v68, v104
	v_addc_co_u32_e32 v71, vcc, v69, v105, vcc
	v_lshl_add_u64 v[42:43], v[42:43], 0, s[50:51]
	v_lshl_add_u64 v[70:71], v[70:71], 0, s[52:53]
	s_mov_b64 s[60:61], 0
.LBB0_274:
	s_andn2_b64 vcc, exec, s[60:61]
	s_mov_b64 s[60:61], 0x1000
	s_cbranch_vccnz .LBB0_276
	s_add_i32 s44, s62, 0x80
	v_add_u32_e32 v42, s44, v153
	v_ashrrev_i32_e32 v43, 31, v42
	v_lshlrev_b64 v[42:43], 10, v[42:43]
	s_waitcnt lgkmcnt(0)
	v_add_co_u32_e32 v42, vcc, v68, v42
	v_addc_co_u32_e32 v43, vcc, v69, v43, vcc
	v_add_co_u32_e32 v68, vcc, v68, v106
	v_addc_co_u32_e32 v69, vcc, v69, v107, vcc
	v_mov_b32_e32 v117, v41
	v_add_co_u32_e32 v68, vcc, v68, v116
	v_addc_co_u32_e32 v69, vcc, v69, v117, vcc
	v_lshl_add_u64 v[42:43], v[42:43], 0, s[54:55]
	v_lshl_add_u64 v[70:71], v[68:69], 0, s[56:57]
	s_mov_b64 s[60:61], 0x10000
.LBB0_276:
	v_lshlrev_b32_e32 v40, 1, v102
	v_add_co_u32_e32 v42, vcc, v42, v40
	v_addc_co_u32_e32 v43, vcc, v43, v41, vcc
	v_lshlrev_b32_e32 v40, 1, v100
	v_add_co_u32_e32 v42, vcc, v42, v40
	v_addc_co_u32_e32 v43, vcc, v43, v41, vcc
	v_add_co_u32_e32 v72, vcc, s81, v42
	s_waitcnt lgkmcnt(0)
	v_lshl_add_u64 v[68:69], s[44:45], 1, v[70:71]
	v_addc_co_u32_e32 v73, vcc, 0, v43, vcc
	v_add_co_u32_e32 v76, vcc, s82, v42
	v_lshl_add_u64 v[88:89], v[128:129], 1, v[68:69]
	s_nop 0
	v_addc_co_u32_e32 v77, vcc, 0, v43, vcc
	flat_load_dwordx4 v[68:71], v[42:43]
	v_add_co_u32_e32 v42, vcc, 0x18000, v42
	s_lshl_b32 s44, s60, 1
	s_nop 0
	v_addc_co_u32_e32 v43, vcc, 0, v43, vcc
	flat_load_dwordx4 v[72:75], v[72:73]
	s_nop 0
	flat_load_dwordx4 v[76:79], v[76:77]
	s_nop 0
	flat_load_dwordx4 v[80:83], v[42:43]
	flat_load_dwordx4 v[84:87], v[88:89]
	v_lshl_add_u64 v[42:43], v[88:89], 0, s[44:45]
	v_lshl_add_u64 v[96:97], v[42:43], 0, s[44:45]
	flat_load_dwordx4 v[88:91], v[42:43]
	flat_load_dwordx4 v[92:95], v[96:97]
	v_lshl_add_u64 v[42:43], v[96:97], 0, s[44:45]
	flat_load_dwordx4 v[96:99], v[42:43]
	s_mov_b64 s[60:61], 0
.LBB0_277:
	s_and_b64 vcc, exec, s[60:61]
	s_cbranch_vccz .LBB0_281
	s_and_saveexec_b64 s[60:61], s[34:35]
	s_cbranch_execz .LBB0_280
	v_mov_b32_e32 v0, s80
	ds_read_b64 v[32:33], v0
	v_mov_b32_e32 v119, v41
	v_lshlrev_b32_e32 v40, 1, v100
	v_mov_b32_e32 v121, v41
	s_waitcnt lgkmcnt(0)
	v_add_co_u32_e32 v0, vcc, v32, v108
	v_addc_co_u32_e32 v1, vcc, v33, v109, vcc
	v_add_co_u32_e32 v2, vcc, v32, v110
	v_addc_co_u32_e32 v3, vcc, v33, v111, vcc
	v_add_co_u32_e32 v0, vcc, v0, v118
	v_addc_co_u32_e32 v1, vcc, v1, v119, vcc
	v_add_co_u32_e32 v8, vcc, v0, v40
	v_addc_co_u32_e32 v9, vcc, v1, v41, vcc
	v_add_co_u32_e32 v0, vcc, v2, v120
	v_addc_co_u32_e32 v1, vcc, v3, v121, vcc
	v_lshl_add_u64 v[24:25], v[128:129], 1, v[0:1]
	v_add_co_u32_e32 v0, vcc, 0x8800000, v8
	v_lshl_add_u64 v[32:33], v[32:33], 0, v[112:113]
	s_nop 0
	v_addc_co_u32_e32 v1, vcc, 0, v9, vcc
	v_add_co_u32_e32 v4, vcc, 0x8808000, v8
	v_lshl_add_u64 v[32:33], v[32:33], 0, v[118:119]
	s_nop 0
	v_addc_co_u32_e32 v5, vcc, 0, v9, vcc
	v_add_co_u32_e32 v10, vcc, 0x8810000, v8
	v_lshl_add_u64 v[32:33], v[32:33], 0, v[40:41]
	s_nop 0
	v_addc_co_u32_e32 v11, vcc, 0, v9, vcc
	v_add_co_u32_e32 v12, vcc, 0x8818000, v8
	flat_load_dwordx4 v[0:3], v[0:1]
	s_nop 0
	flat_load_dwordx4 v[4:7], v[4:5]
	v_addc_co_u32_e32 v13, vcc, 0, v9, vcc
	v_add_co_u32_e32 v16, vcc, 0xa800000, v24
	flat_load_dwordx4 v[8:11], v[10:11]
	s_nop 0
	flat_load_dwordx4 v[12:15], v[12:13]
	v_addc_co_u32_e32 v17, vcc, 0, v25, vcc
	v_add_co_u32_e32 v20, vcc, 0xa820000, v24
	s_nop 1
	v_addc_co_u32_e32 v21, vcc, 0, v25, vcc
	v_add_co_u32_e32 v26, vcc, 0xa840000, v24
	flat_load_dwordx4 v[16:19], v[16:17]
	s_nop 0
	flat_load_dwordx4 v[20:23], v[20:21]
	v_addc_co_u32_e32 v27, vcc, 0, v25, vcc
	v_add_co_u32_e32 v28, vcc, 0xa860000, v24
	s_nop 1
	v_addc_co_u32_e32 v29, vcc, 0, v25, vcc
	v_add_co_u32_e32 v34, vcc, 0x6800000, v32
	flat_load_dwordx4 v[24:27], v[26:27]
	s_nop 0
	flat_load_dwordx4 v[28:31], v[28:29]
	v_addc_co_u32_e32 v35, vcc, 0, v33, vcc
	v_add_co_u32_e32 v36, vcc, 0x6808000, v32
	s_nop 1
	v_addc_co_u32_e32 v37, vcc, 0, v33, vcc
	flat_load_dwordx4 v[32:35], v[34:35]
	s_nop 0
	flat_load_dwordx4 v[36:39], v[36:37]

.LBB0_320:
	s_and_b64 vcc, exec, s[0:1]
	s_cbranch_vccz .LBB0_463
	s_waitcnt vmcnt(0) lgkmcnt(0)
	v_bfe_u32 v0, v133, 4, 2
	s_mov_b64 s[0:1], -1
	s_cmpk_gt_i32 s2, 0x7f
	v_and_b32_e32 v129, 15, v163
	v_lshrrev_b32_e32 v135, 4, v133
	v_lshlrev_b32_e32 v158, 3, v133
	v_lshrrev_b32_e32 v101, 2, v163
	v_lshlrev_b32_e32 v128, 2, v0
	v_lshrrev_b32_e32 v154, 3, v133
	v_lshlrev_b32_e32 v157, 3, v0
	v_lshl_add_u32 v155, v0, 4, v161
	v_lshlrev_b32_e32 v156, 2, v133
	s_cbranch_scc0 .LBB0_379
	v_and_b32_e32 v0, 48, v101
	v_or_b32_e32 v107, v0, v129
	v_sub_u32_e64 v0, v0, 8 clamp
	v_min_u32_e32 v126, 32, v0
	v_add_u32_e32 v53, v126, v128
	v_sub_u32_e32 v0, v53, v107
	v_sub_u32_e64 v1, v107, 8 clamp
	v_max_i32_e32 v0, -15, v0
	v_min_u32_e32 v52, 48, v1
	v_add_u32_e32 v0, 15, v0
	v_add_u32_e32 v54, 16, v52
	v_min_u32_e32 v55, 30, v0
	v_or_b32_e32 v0, 1, v53
	v_cmp_lt_u32_e64 s[6:7], v0, v52
	v_cmp_ge_u32_e64 s[8:9], v0, v54
	v_sub_u32_e32 v0, v0, v107
	v_max_i32_e32 v0, -15, v0
	v_add_u32_e32 v0, 15, v0
	v_min_u32_e32 v56, 30, v0
	v_or_b32_e32 v0, 2, v53
	v_cmp_lt_u32_e64 s[10:11], v0, v52
	v_cmp_ge_u32_e64 s[12:13], v0, v54
	v_sub_u32_e32 v0, v0, v107
	v_max_i32_e32 v0, -15, v0
	v_add_u32_e32 v0, 15, v0
	v_min_u32_e32 v57, 30, v0
	v_or_b32_e32 v0, 3, v53
	v_cmp_lt_u32_e64 s[14:15], v0, v52
	v_cmp_ge_u32_e64 s[16:17], v0, v54
	v_sub_u32_e32 v0, v0, v107
	v_max_i32_e32 v0, -15, v0
	s_mul_i32 s0, s2, 22
	v_add_u32_e32 v0, 15, v0
	s_addk_i32 s0, 0xf500
	v_min_u32_e32 v58, 30, v0
	v_add_u32_e32 v0, 16, v53
	v_add_u32_e32 v103, s0, v162
	v_cmp_lt_u32_e64 s[18:19], v0, v52
	v_sub_u32_e32 v0, v0, v107
	v_max_i32_e32 v0, -15, v0
	v_and_b32_e32 v44, 63, v103
	v_add_u32_e32 v59, 15, v0
	v_sub_u32_e64 v0, v44, 4 clamp
	s_add_i32 s3, 0, 0x240a8
	v_min_u32_e32 v7, 56, v0
	v_mov_b32_e32 v0, s3
	ds_read_b64 v[2:3], v0
	v_lshlrev_b32_e32 v0, 3, v103
	s_movk_i32 s72, 0xf000
	v_and_or_b32 v45, v0, s72, v154
	v_lshl_or_b32 v0, v7, 6, v45
	v_ashrrev_i32_e32 v1, 31, v0
	v_and_b32_e32 v6, 0x1c0, v103
	v_lshlrev_b64 v[0:1], 10, v[0:1]
	v_and_b32_e32 v100, 56, v158
	s_waitcnt lgkmcnt(0)
	v_add_co_u32_e32 v4, vcc, v2, v0
	v_addc_co_u32_e32 v5, vcc, v3, v1, vcc
	v_lshlrev_b32_e32 v0, 1, v6
	v_mov_b32_e32 v1, 0
	v_add_co_u32_e32 v4, vcc, v4, v0
	v_addc_co_u32_e32 v5, vcc, v5, v1, vcc
	v_lshlrev_b32_e32 v36, 1, v100
	v_mov_b32_e32 v37, v1
	v_add_co_u32_e32 v12, vcc, v4, v36
	v_addc_co_u32_e32 v13, vcc, v5, v37, vcc
	s_mov_b32 s74, 0x8800000
	v_add_co_u32_e32 v14, vcc, s74, v12
	s_movk_i32 s73, 0xffc0
	s_nop 0
	v_addc_co_u32_e32 v15, vcc, 0, v13, vcc
	s_mov_b32 s75, 0x8808000
	v_and_or_b32 v4, v103, s73, v135
	v_add_co_u32_e32 v16, vcc, s75, v12
	v_ashrrev_i32_e32 v5, 31, v4
	s_nop 0
	v_addc_co_u32_e32 v17, vcc, 0, v13, vcc
	s_mov_b32 s76, 0x8810000
	v_lshlrev_b64 v[4:5], 13, v[4:5]
	v_add_co_u32_e32 v20, vcc, s76, v12
	v_and_b32_e32 v102, 0x78, v158
	v_lshl_add_u64 v[4:5], v[2:3], 0, v[4:5]
	v_lshlrev_b32_e32 v6, 7, v7
	v_mov_b32_e32 v7, v1
	v_addc_co_u32_e32 v21, vcc, 0, v13, vcc
	s_mov_b32 s77, 0x8818000
	v_add_co_u32_e32 v4, vcc, v4, v6
	v_addc_co_u32_e32 v5, vcc, v5, v7, vcc
	v_lshlrev_b32_e32 v38, 1, v102
	v_mov_b32_e32 v39, v1
	v_add_co_u32_e32 v22, vcc, s77, v12
	v_lshl_add_u64 v[28:29], v[4:5], 0, v[38:39]
	s_nop 0
	v_addc_co_u32_e32 v23, vcc, 0, v13, vcc
	s_mov_b32 s78, 0xa800000
	v_add_co_u32_e32 v30, vcc, s78, v28
	s_mov_b32 s79, 0xa820000
	s_nop 0
	v_addc_co_u32_e32 v31, vcc, 0, v29, vcc
	v_add_co_u32_e32 v32, vcc, s79, v28
	s_mov_b32 s80, 0xa840000
	s_nop 0
	v_addc_co_u32_e32 v33, vcc, 0, v29, vcc
	v_add_co_u32_e32 v40, vcc, s80, v28
	s_mov_b32 s81, 0xa860000
	s_nop 0
	v_addc_co_u32_e32 v41, vcc, 0, v29, vcc
	v_add_co_u32_e32 v42, vcc, s81, v28
	flat_load_dwordx4 v[4:7], v[14:15]
	flat_load_dwordx4 v[8:11], v[16:17]
	s_nop 0
	flat_load_dwordx4 v[12:15], v[20:21]
	flat_load_dwordx4 v[16:19], v[22:23]
	s_nop 0
	flat_load_dwordx4 v[20:23], v[30:31]
	flat_load_dwordx4 v[24:27], v[32:33]
	v_addc_co_u32_e32 v43, vcc, 0, v29, vcc
	flat_load_dwordx4 v[28:31], v[40:41]
	flat_load_dwordx4 v[32:35], v[42:43]
	v_lshl_or_b32 v40, v44, 6, v45
	v_ashrrev_i32_e32 v41, 31, v40
	v_lshlrev_b64 v[40:41], 10, v[40:41]
	v_add_co_u32_e32 v2, vcc, v2, v40
	v_addc_co_u32_e32 v3, vcc, v3, v41, vcc
	v_add_co_u32_e32 v2, vcc, v2, v0
	v_addc_co_u32_e32 v3, vcc, v3, v1, vcc
	v_add_co_u32_e32 v2, vcc, v2, v36
	v_addc_co_u32_e32 v3, vcc, v3, v37, vcc
	s_mov_b32 s82, 0x6800000
	v_add_co_u32_e32 v40, vcc, s82, v2
	s_mov_b32 s20, 0x6808000
	s_nop 0
	v_addc_co_u32_e32 v41, vcc, 0, v3, vcc
	v_add_co_u32_e32 v2, vcc, s20, v2
	v_mul_u32_u24_e32 v39, 0x48, v154
	s_nop 0
	v_addc_co_u32_e32 v3, vcc, 0, v3, vcc
	flat_load_dwordx4 v[44:47], v[40:41]
	flat_load_dwordx4 v[48:51], v[2:3]
	v_lshlrev_b32_e32 v39, 1, v39
	v_add3_u32 v127, v161, v39, v36
	v_mul_u32_u24_e32 v36, 0x110, v135
	v_add3_u32 v130, v161, v36, v38
	v_mbcnt_lo_u32_b32 v38, -1, 0
	v_mbcnt_hi_u32_b32 v38, -1, v38
	v_and_b32_e32 v40, 64, v38
	v_xor_b32_e32 v39, 16, v38
	v_add_u32_e32 v40, 64, v40
	v_cmp_lt_i32_e32 vcc, v39, v40
	v_add_u32_e32 v2, 17, v53
	v_add_u32_e32 v3, 18, v53
	v_add_u32_e32 v37, 19, v53
	v_cndmask_b32_e32 v39, v38, v39, vcc
	v_cmp_lt_u32_e64 s[20:21], v2, v52
	v_cmp_ge_u32_e64 s[22:23], v2, v54
	v_sub_u32_e32 v2, v2, v107
	v_cmp_lt_u32_e64 s[24:25], v3, v52
	v_cmp_ge_u32_e64 s[26:27], v3, v54
	v_sub_u32_e32 v3, v3, v107
	v_cmp_lt_u32_e64 s[28:29], v37, v52
	v_cmp_ge_u32_e64 s[30:31], v37, v54
	v_sub_u32_e32 v37, v37, v107
	v_lshlrev_b32_e32 v134, 2, v39
	v_xor_b32_e32 v39, 32, v38
	v_max_i32_e32 v2, -15, v2
	v_max_i32_e32 v3, -15, v3
	v_max_i32_e32 v37, -15, v37
	v_cmp_lt_i32_e32 vcc, v39, v40
	v_min_u32_e32 v0, 30, v59
	v_add_u32_e32 v2, 15, v2
	v_add_u32_e32 v3, 15, v3
	v_add_u32_e32 v37, 15, v37
	v_cndmask_b32_e32 v38, v38, v39, vcc
	v_min_u32_e32 v2, 30, v2
	v_min_u32_e32 v3, 30, v3
	v_min_u32_e32 v37, 30, v37
	v_sub_u32_e32 v36, v155, v157
	s_movk_i32 s83, 0x90
	v_lshlrev_b32_e32 v136, 2, v38
	v_mul_u32_u24_e32 v38, 0x88, v129
	v_lshl_add_u32 v144, v0, 2, v161
	v_add3_u32 v0, v160, v156, 0
	v_cmp_ge_u32_e64 s[0:1], v53, v52
	v_cmp_lt_u32_e64 s[36:37], v53, v52
	v_cmp_ge_u32_e64 s[4:5], v53, v54
	s_mov_b32 s39, 0
	v_mad_u32_u24 v131, v107, s83, v155
	v_or_b32_e32 v137, 64, v126
	v_mul_u32_u24_e32 v138, 0x90, v129
	v_lshl_add_u32 v139, v38, 1, v36
	v_lshl_add_u32 v140, v55, 2, v161
	v_lshl_add_u32 v141, v56, 2, v161
	v_lshl_add_u32 v142, v57, 2, v161
	v_lshl_add_u32 v143, v58, 2, v161
	v_lshl_add_u32 v145, v2, 2, v161
	v_lshl_add_u32 v146, v3, 2, v161
	v_lshl_add_u32 v148, v37, 2, v161
	v_add_u32_e32 v149, 0xb000, v0
	v_or_b32_e32 v150, 0xffffff00, v133
	s_add_i32 s84, 0, 0x24040
	s_mov_b64 s[42:43], 0x400
	s_movk_i32 s85, 0xd0
	s_mov_b64 s[44:45], 0x1c800000
	s_mov_b64 s[46:47], 0x1ca00000
	s_mov_b64 s[48:49], 0x8800000
	s_mov_b64 s[50:51], 0xa800000
	s_mov_b32 s86, 0x8000
	s_mov_b32 s87, 0x10000
	s_mov_b32 s88, 0xf149f2ca
	s_mov_b32 s89, 0xefa18f08
	v_lshlrev_b32_e32 v104, 1, v128
	s_mov_b64 s[52:53], 0x6800000
	v_mov_b32_e32 v151, 0xf149f2ca
	s_mov_b32 s90, 0
	s_branch .LBB0_324
.LBB0_323:
	ds_bpermute_b32 v0, v134, v164
	v_lshlrev_b32_e32 v69, 3, v152
	v_lshlrev_b32_e32 v70, 6, v105
	v_and_b32_e32 v69, 0xfffff000, v69
	v_mov_b32_e32 v2, s3
	s_waitcnt lgkmcnt(0)
	v_add_f32_e32 v0, v164, v0
	ds_bpermute_b32 v68, v136, v0
	ds_read_b64 v[2:3], v2
	v_mov_b32_e32 v105, v1
	s_add_i32 s90, s90, 1
	s_cmp_eq_u32 s90, 11
	s_waitcnt lgkmcnt(1)
	v_add_f32_e32 v0, v0, v68
	v_div_scale_f32 v71, s[34:35], v0, v0, 1.0
	v_rcp_f32_e32 v72, v71
	v_or3_b32 v68, v69, v70, v107
	v_div_scale_f32 v69, vcc, 1.0, v0, 1.0
	v_fma_f32 v70, -v71, v72, 1.0
	v_fmac_f32_e32 v72, v70, v72
	v_mul_f32_e32 v70, v69, v72
	v_fma_f32 v73, -v71, v70, v69
	v_fmac_f32_e32 v70, v73, v72
	v_fma_f32 v69, -v71, v70, v69
	v_div_fmas_f32 v69, v69, v72, v70
	v_div_fixup_f32 v70, v69, v0, 1.0
	v_ashrrev_i32_e32 v69, 31, v68
	v_lshlrev_b64 v[68:69], 10, v[68:69]
	s_waitcnt lgkmcnt(0)
	v_add_co_u32_e32 v2, vcc, v2, v68
	v_addc_co_u32_e32 v3, vcc, v3, v69, vcc
	v_lshlrev_b32_e32 v0, 1, v106
	v_add_co_u32_e32 v2, vcc, v2, v0
	v_addc_co_u32_e32 v3, vcc, v3, v1, vcc
	v_add_co_u32_e32 v2, vcc, v2, v104
	v_addc_co_u32_e32 v3, vcc, v3, v105, vcc
	v_lshl_add_u64 v[68:69], v[2:3], 0, s[52:53]
	v_pk_mul_f32 v[64:65], v[64:65], v[70:71] op_sel_hi:[1,0]
	v_pk_mul_f32 v[66:67], v[66:67], v[70:71] op_sel_hi:[1,0]
	v_add_co_u32_e32 v2, vcc, s82, v2
	v_cvt_pk_bf16_f32 v64, v64, v65
	v_cvt_pk_bf16_f32 v65, v66, v67
	v_addc_co_u32_e32 v3, vcc, 0, v3, vcc
	global_store_dwordx2 v[2:3], v[64:65], off
	v_pk_mul_f32 v[2:3], v[60:61], v[70:71] op_sel_hi:[1,0]
	v_pk_mul_f32 v[60:61], v[62:63], v[70:71] op_sel_hi:[1,0]
	v_cvt_pk_bf16_f32 v2, v2, v3
	v_cvt_pk_bf16_f32 v3, v60, v61
	global_store_dwordx2 v[68:69], v[2:3], off offset:32
	v_pk_mul_f32 v[2:3], v[56:57], v[70:71] op_sel_hi:[1,0]
	v_pk_mul_f32 v[56:57], v[58:59], v[70:71] op_sel_hi:[1,0]
	v_cvt_pk_bf16_f32 v2, v2, v3
	v_cvt_pk_bf16_f32 v3, v56, v57
	global_store_dwordx2 v[68:69], v[2:3], off offset:64
	v_pk_mul_f32 v[2:3], v[52:53], v[70:71] op_sel_hi:[1,0]
	v_pk_mul_f32 v[52:53], v[54:55], v[70:71] op_sel_hi:[1,0]
	v_cvt_pk_bf16_f32 v2, v2, v3
	v_cvt_pk_bf16_f32 v3, v52, v53
	global_store_dwordx2 v[68:69], v[2:3], off offset:96
	s_cbranch_scc1 .LBB0_378

.LBB0_326:
	s_cmp_eq_u32 s91, 0
	s_cselect_b64 s[34:35], -1, 0
	s_cmp_lg_u32 s91, 0
	s_waitcnt lgkmcnt(0)
	s_barrier
	s_waitcnt vmcnt(0)
	ds_write_b128 v127, v[4:7] offset:9216
	ds_write_b128 v127, v[8:11] offset:13824
	ds_write_b128 v127, v[12:15] offset:18432
	ds_write_b128 v127, v[16:19] offset:23040
	ds_write_b128 v130, v[20:23] offset:27648
	ds_write_b128 v130, v[24:27] offset:32000
	ds_write_b128 v130, v[28:31] offset:36352
	ds_write_b128 v130, v[32:35] offset:40704
	s_cbranch_scc1 .LBB0_330
	ds_write_b128 v127, v[44:47]
	ds_write_b128 v127, v[48:51] offset:4608
	v_mov_b32_e32 v0, s84
	ds_read_b64 v[2:3], v0
	s_mov_b64 s[56:57], 0
	v_mov_b32_e32 v0, v150
	v_mov_b32_e32 v68, v149
	s_waitcnt lgkmcnt(0)
	v_add_co_u32_e32 v2, vcc, v2, v118
	v_addc_co_u32_e32 v3, vcc, v3, v119, vcc

.LBB0_330:
	s_cmp_eq_u32 s91, 5
	s_mov_b64 s[56:57], -1
	s_waitcnt lgkmcnt(0)
	s_barrier
	s_cbranch_scc1 .LBB0_336
	v_mov_b32_e32 v0, s3
	ds_read_b64 v[68:69], v0
	s_lshl_b32 s58, s91, 7
	s_cmp_gt_u32 s91, 2
	s_cbranch_scc0 .LBB0_333
	s_add_i32 s38, s58, 0xfffffe80
	v_add_u32_e32 v2, s38, v153
	v_ashrrev_i32_e32 v3, 31, v2
	v_lshlrev_b64 v[2:3], 10, v[2:3]
	s_waitcnt lgkmcnt(0)
	v_add_co_u32_e32 v2, vcc, v68, v2
	v_addc_co_u32_e32 v3, vcc, v69, v3, vcc
	v_add_co_u32_e32 v70, vcc, v68, v108
	v_addc_co_u32_e32 v71, vcc, v69, v109, vcc
	v_lshl_add_u64 v[2:3], v[2:3], 0, s[44:45]
	v_lshl_add_u64 v[70:71], v[70:71], 0, s[46:47]
	s_mov_b64 s[56:57], 0
.LBB0_333:
	s_andn2_b64 vcc, exec, s[56:57]
	s_mov_b64 s[56:57], 0x1000
	s_cbranch_vccnz .LBB0_335
	s_add_i32 s38, s58, 0x80
	v_add_u32_e32 v2, s38, v159
	v_ashrrev_i32_e32 v3, 31, v2
	v_lshlrev_b64 v[2:3], 10, v[2:3]
	s_waitcnt lgkmcnt(0)
	v_add_co_u32_e32 v2, vcc, v68, v2
	v_addc_co_u32_e32 v3, vcc, v69, v3, vcc
	v_add_co_u32_e32 v68, vcc, v68, v110
	v_addc_co_u32_e32 v69, vcc, v69, v111, vcc
	v_mov_b32_e32 v121, v1
	v_add_co_u32_e32 v68, vcc, v68, v120
	v_addc_co_u32_e32 v69, vcc, v69, v121, vcc
	v_lshl_add_u64 v[2:3], v[2:3], 0, s[48:49]
	v_lshl_add_u64 v[70:71], v[68:69], 0, s[50:51]
	s_mov_b64 s[56:57], 0x10000
.LBB0_335:
	v_lshlrev_b32_e32 v0, 1, v106
	v_add_co_u32_e32 v2, vcc, v2, v0
	v_addc_co_u32_e32 v3, vcc, v3, v1, vcc
	v_lshlrev_b32_e32 v0, 1, v100
	v_add_co_u32_e32 v2, vcc, v2, v0
	v_addc_co_u32_e32 v3, vcc, v3, v1, vcc
	v_add_co_u32_e32 v72, vcc, s86, v2
	s_waitcnt lgkmcnt(0)
	v_lshl_add_u64 v[68:69], s[38:39], 1, v[70:71]
	v_addc_co_u32_e32 v73, vcc, 0, v3, vcc
	v_add_co_u32_e32 v76, vcc, s87, v2
	v_lshlrev_b32_e32 v0, 1, v102
	s_nop 0
	v_addc_co_u32_e32 v77, vcc, 0, v3, vcc
	v_add_co_u32_e32 v88, vcc, v68, v0
	v_addc_co_u32_e32 v89, vcc, v69, v1, vcc
	global_load_dwordx4 v[4:7], v[2:3], off
	v_add_co_u32_e32 v2, vcc, 0x18000, v2
	s_lshl_b32 s38, s56, 1
	s_nop 0
	v_addc_co_u32_e32 v3, vcc, 0, v3, vcc
	global_load_dwordx4 v[8:11], v[72:73], off
	s_nop 0
	global_load_dwordx4 v[12:15], v[76:77], off
	s_nop 0
	global_load_dwordx4 v[16:19], v[2:3], off
	global_load_dwordx4 v[20:23], v[88:89], off
	v_lshl_add_u64 v[2:3], v[88:89], 0, s[38:39]
	v_lshl_add_u64 v[96:97], v[2:3], 0, s[38:39]
	global_load_dwordx4 v[24:27], v[2:3], off
	global_load_dwordx4 v[28:31], v[96:97], off
	v_lshl_add_u64 v[2:3], v[96:97], 0, s[38:39]
	global_load_dwordx4 v[32:35], v[2:3], off
	s_mov_b64 s[56:57], 0
.LBB0_336:
	s_and_b64 vcc, exec, s[56:57]
	s_cbranch_vccz .LBB0_367
	s_andn2_b64 vcc, exec, s[54:55]
	s_cbranch_vccnz .LBB0_339
	v_mov_b32_e32 v0, s3
	ds_read_b64 v[2:3], v0
	v_mov_b32_e32 v123, v1
	v_lshlrev_b32_e32 v0, 1, v100
	v_mov_b32_e32 v125, v1
	s_waitcnt lgkmcnt(0)
	v_add_co_u32_e32 v4, vcc, v2, v112
	v_addc_co_u32_e32 v5, vcc, v3, v113, vcc
	v_add_co_u32_e32 v6, vcc, v2, v114
	v_addc_co_u32_e32 v7, vcc, v3, v115, vcc
	v_add_co_u32_e32 v4, vcc, v4, v122
	v_addc_co_u32_e32 v5, vcc, v5, v123, vcc
	v_add_co_u32_e32 v12, vcc, v4, v0
	v_addc_co_u32_e32 v13, vcc, v5, v1, vcc
	v_add_co_u32_e32 v4, vcc, v6, v124
	v_addc_co_u32_e32 v5, vcc, v7, v125, vcc
	v_lshlrev_b32_e32 v6, 1, v102
	v_mov_b32_e32 v7, v1
	v_add_co_u32_e32 v28, vcc, v4, v6
	v_addc_co_u32_e32 v29, vcc, v5, v7, vcc
	v_add_co_u32_e32 v4, vcc, s74, v12
	v_lshl_add_u64 v[2:3], v[2:3], 0, v[116:117]
	s_nop 0
	v_addc_co_u32_e32 v5, vcc, 0, v13, vcc
	v_add_co_u32_e32 v8, vcc, s75, v12
	v_lshl_add_u64 v[2:3], v[2:3], 0, v[122:123]
	s_nop 0
	v_addc_co_u32_e32 v9, vcc, 0, v13, vcc
	v_add_co_u32_e32 v14, vcc, s76, v12
	v_lshl_add_u64 v[2:3], v[2:3], 0, v[0:1]
	s_nop 0
	v_addc_co_u32_e32 v15, vcc, 0, v13, vcc
	v_add_co_u32_e32 v16, vcc, s77, v12
	global_load_dwordx4 v[4:7], v[4:5], off
	s_nop 0
	global_load_dwordx4 v[8:11], v[8:9], off
	v_addc_co_u32_e32 v17, vcc, 0, v13, vcc
	v_add_co_u32_e32 v20, vcc, s78, v28
	global_load_dwordx4 v[12:15], v[14:15], off
	s_nop 0
	global_load_dwordx4 v[16:19], v[16:17], off
	v_addc_co_u32_e32 v21, vcc, 0, v29, vcc
	v_add_co_u32_e32 v24, vcc, s79, v28
	s_nop 1
	v_addc_co_u32_e32 v25, vcc, 0, v29, vcc
	v_add_co_u32_e32 v30, vcc, s80, v28
	global_load_dwordx4 v[20:23], v[20:21], off
	s_nop 0
	global_load_dwordx4 v[24:27], v[24:25], off
	v_addc_co_u32_e32 v31, vcc, 0, v29, vcc
	v_add_co_u32_e32 v32, vcc, s81, v28
	s_nop 1
	v_addc_co_u32_e32 v33, vcc, 0, v29, vcc
	v_add_co_u32_e32 v44, vcc, 0x6800000, v2
	global_load_dwordx4 v[28:31], v[30:31], off
	s_nop 0
	global_load_dwordx4 v[32:35], v[32:33], off
	v_addc_co_u32_e32 v45, vcc, 0, v3, vcc
	v_add_co_u32_e32 v2, vcc, 0x6808000, v2
	s_nop 1
	v_addc_co_u32_e32 v3, vcc, 0, v3, vcc
	global_load_dwordx4 v[44:47], v[44:45], off
	s_nop 0
	global_load_dwordx4 v[48:51], v[2:3], off

.LBB0_379:
	s_and_b64 vcc, exec, s[0:1]
	s_cbranch_vccz .LBB0_463
	v_bfe_u32 v100, v147, 2, 1
	v_and_b32_e32 v221, 1, v147
	v_mov_b32_e32 v219, 0
	v_mov_b32_e32 v223, 0
	s_nop 0
	v_mul_u32_u24_e32 v220, 0x4400, v221
	v_lshlrev_b32_e32 v218, 15, v221
	v_lshlrev_b32_e32 v222, 19, v221
	v_mul_u32_u24_e32 v221, 0x12000, v221
	s_add_i32 s0, 0, 0x24048
	s_add_i32 s1, 0, 0x24050
	v_mov_b32_e32 v0, s1
	v_mov_b32_e32 v1, s0
	v_cmp_eq_u32_e64 s[0:1], 0, v100
	v_bfe_u32 v2, v147, 3, 2
	v_mov_b32_e32 v137, 0
	v_cndmask_b32_e64 v0, v0, v1, s[0:1]
	ds_read_b64 v[0:1], v0
	v_lshlrev_b32_e32 v2, 2, v2
	v_mov_b32_e32 v3, v137
	s_add_i32 s12, 0, 0x240a8
	v_ashrrev_i32_e32 v5, 3, v147
	s_waitcnt lgkmcnt(0)
	v_add_co_u32_e32 v0, vcc, v0, v2
	v_addc_co_u32_e32 v1, vcc, v1, v3, vcc
	global_load_dword v44, v[0:1], off
	v_and_b32_e32 v1, 4, v147
	v_lshrrev_b32_e32 v0, 3, v147
	v_cmp_ne_u32_e64 s[6:7], 0, v1
	v_mov_b32_e32 v1, s12
	v_bfi_b32 v96, -4, v5, v0
	ds_read_b64 v[0:1], v1
	v_mov_b32_e32 v2, 0x1ce00000
	v_mov_b32_e32 v3, 0x1cc00000
	v_lshlrev_b32_e32 v4, 6, v147
	v_and_b32_e32 v106, 0xc0, v4
	v_cndmask_b32_e64 v136, v2, v3, s[0:1]
	v_lshlrev_b32_e32 v2, 8, v96
	v_lshl_or_b32 v102, v96, 7, v135
	v_or3_b32 v104, v2, v106, v135
	v_ashrrev_i32_e32 v103, 31, v102
	v_ashrrev_i32_e32 v105, 31, v104
	v_lshlrev_b64 v[2:3], 9, v[102:103]
	v_lshlrev_b64 v[4:5], 9, v[104:105]
	s_waitcnt lgkmcnt(0)
	v_add_co_u32_e32 v6, vcc, v0, v136
	v_addc_co_u32_e32 v7, vcc, v1, v137, vcc
	v_and_b32_e32 v134, 0x78, v158
	s_mov_b64 s[4:5], 0x1d000000
	v_lshlrev_b32_e32 v136, 8, v100
	v_add_co_u32_e32 v0, vcc, v0, v4
	v_addc_co_u32_e32 v1, vcc, v1, v5, vcc
	v_add_co_u32_e32 v28, vcc, v6, v2
	v_addc_co_u32_e32 v29, vcc, v7, v3, vcc
	v_lshlrev_b32_e32 v98, 1, v134
	v_mov_b32_e32 v99, v137
	v_lshl_add_u64 v[30:31], v[0:1], 0, s[4:5]
	v_add_co_u32_e32 v0, vcc, v28, v136
	v_addc_co_u32_e32 v1, vcc, v29, v137, vcc
	s_movk_i32 s9, 0x2000
	v_add_co_u32_e32 v32, vcc, v0, v98
	v_addc_co_u32_e32 v33, vcc, v1, v99, vcc
	v_add_co_u32_e32 v32, vcc, v32, v218
	v_addc_co_u32_e32 v33, vcc, v33, v219, vcc
	v_add_co_u32_e32 v12, vcc, s9, v32
	s_movk_i32 s10, 0x4000
	s_nop 0
	v_addc_co_u32_e32 v13, vcc, 0, v33, vcc
	v_add_co_u32_e32 v14, vcc, s10, v32
	s_movk_i32 s11, 0x6000
	s_nop 0
	v_addc_co_u32_e32 v15, vcc, 0, v33, vcc
	v_add_co_u32_e32 v34, vcc, s11, v32
	s_mov_b32 s13, 0x8000
	s_nop 0
	v_addc_co_u32_e32 v35, vcc, 0, v33, vcc
	v_add_co_u32_e32 v36, vcc, s13, v32
	s_mov_b32 s14, 0xa000
	s_nop 0
	v_addc_co_u32_e32 v37, vcc, 0, v33, vcc
	v_add_co_u32_e32 v38, vcc, s14, v32
	s_mov_b32 s15, 0xc000
	s_nop 0
	v_addc_co_u32_e32 v39, vcc, 0, v33, vcc
	v_add_co_u32_e32 v42, vcc, s15, v32
	s_mov_b32 s16, 0xe000
	v_lshl_add_u64 v[2:3], v[30:31], 0, v[136:137]
	v_addc_co_u32_e32 v43, vcc, 0, v33, vcc
	v_add_co_u32_e32 v40, vcc, v2, v98
	v_addc_co_u32_e32 v41, vcc, v3, v99, vcc
	global_load_dwordx4 v[0:3], v[12:13], off
	global_load_dwordx4 v[4:7], v[14:15], off
	global_load_dwordx4 v[8:11], v[34:35], off
	v_add_co_u32_e32 v42, vcc, s16, v32
	s_mov_b32 s8, 0x3fb8aa3b
	s_nop 0
	v_addc_co_u32_e32 v43, vcc, 0, v33, vcc
	v_add_co_u32_e32 v48, vcc, s9, v40
	v_xor_b32_e32 v136, 0x100, v136
	s_nop 0
	v_addc_co_u32_e32 v49, vcc, 0, v41, vcc
	v_add_co_u32_e32 v28, vcc, v28, v136
	v_addc_co_u32_e32 v29, vcc, v29, v137, vcc
	v_add_co_u32_e32 v76, vcc, v28, v98
	v_addc_co_u32_e32 v77, vcc, v29, v99, vcc
	v_add_co_u32_e32 v76, vcc, v76, v218
	v_addc_co_u32_e32 v77, vcc, v77, v219, vcc
	v_add_co_u32_e32 v28, vcc, v30, v136
	v_addc_co_u32_e32 v29, vcc, v31, v137, vcc
	v_add_co_u32_e32 v88, vcc, v28, v98
	v_addc_co_u32_e32 v89, vcc, v29, v99, vcc
	v_mov_b32_e32 v97, 0x12800000
	s_mov_b32 s4, 0xc2ce8ed0
	s_waitcnt vmcnt(0)
	v_mul_f32_e32 v107, 0x43000000, v44
	v_mul_f32_e32 v108, 0x3fb8aa3b, v107
	v_fma_f32 v12, v107, s8, -v108
	v_fmamk_f32 v110, v107, 0x32a5705f, v12
	global_load_dwordx4 v[12:15], v[32:33], off
	global_load_dwordx4 v[36:39], v[40:41], off
	s_nop 0
	global_load_dwordx4 v[44:47], v[48:49], off
	v_add_co_u32_e32 v42, vcc, s10, v40
	v_rndne_f32_e32 v109, v108
	s_nop 0
	v_addc_co_u32_e32 v43, vcc, 0, v41, vcc
	v_add_co_u32_e32 v40, vcc, s11, v40
	v_sub_f32_e32 v99, v108, v109
	s_nop 0
	v_addc_co_u32_e32 v41, vcc, 0, v41, vcc
	v_add_co_u32_e32 v48, vcc, s9, v76
	global_load_dwordx4 v[60:63], v[42:43], off
	global_load_dwordx4 v[64:67], v[40:41], off
	v_addc_co_u32_e32 v49, vcc, 0, v77, vcc
	v_add_co_u32_e32 v50, vcc, s10, v76
	v_add_f32_e32 v99, v99, v110
	s_nop 0
	v_addc_co_u32_e32 v51, vcc, 0, v77, vcc
	v_add_co_u32_e32 v52, vcc, s11, v76
	global_load_dwordx4 v[28:31], v[48:49], off
	global_load_dwordx4 v[40:43], v[50:51], off
	v_addc_co_u32_e32 v53, vcc, 0, v77, vcc
	v_add_co_u32_e32 v54, vcc, s13, v76
	v_exp_f32_e32 v99, v99
	s_nop 0
	v_addc_co_u32_e32 v55, vcc, 0, v77, vcc
	global_load_dwordx4 v[48:51], v[52:53], off
	v_add_co_u32_e32 v52, vcc, s14, v76
	v_cvt_i32_f32_e32 v108, v109
	s_nop 0
	v_addc_co_u32_e32 v53, vcc, 0, v77, vcc
	v_add_co_u32_e32 v54, vcc, s15, v76
	v_mov_b32_e32 v109, 0x10800000
	s_nop 0
	v_addc_co_u32_e32 v55, vcc, 0, v77, vcc
	v_add_co_u32_e32 v90, vcc, s16, v76
	v_addc_co_u32_e32 v91, vcc, 0, v77, vcc
	v_add_co_u32_e32 v92, vcc, s9, v88
	global_load_dwordx4 v[52:55], v[76:77], off
	global_load_dwordx4 v[80:83], v[88:89], off
	v_addc_co_u32_e32 v93, vcc, 0, v89, vcc
	global_load_dwordx4 v[84:87], v[92:93], off
	v_add_co_u32_e32 v90, vcc, s10, v88
	v_cndmask_b32_e64 v138, v97, v109, s[0:1]
	s_nop 0
	v_addc_co_u32_e32 v91, vcc, 0, v89, vcc
	v_add_co_u32_e32 v92, vcc, s11, v88
	v_ldexp_f32 v97, v99, v108
	s_nop 0
	v_addc_co_u32_e32 v93, vcc, 0, v89, vcc
	global_load_dwordx4 v[88:91], v[90:91], off
	s_nop 0
	global_load_dwordx4 v[92:95], v[92:93], off
	v_cmp_ngt_f32_e32 vcc, s4, v107
	s_mov_b32 s4, 0x42b17218
	v_mov_b32_e32 v99, 0x7f800000
	v_cndmask_b32_e32 v97, 0, v97, vcc
	v_cmp_nlt_f32_e32 vcc, s4, v107
	v_and_b32_e32 v165, 48, v101
	v_or_b32_e32 v163, v165, v129
	v_cndmask_b32_e32 v140, v99, v97, vcc
	v_mul_u32_u24_e32 v97, 0x88, v135
	v_lshlrev_b32_e32 v97, 1, v97
	v_add3_u32 v159, v161, v97, v98
	v_or_b32_e32 v98, v106, v163
	s_movk_i32 s4, 0x110
	v_mul_u32_u24_e32 v164, 0x88, v129
	v_ashrrev_i32_e32 v97, 31, v96
	v_lshlrev_b32_e32 v98, 7, v98
	s_mov_b32 s3, 0
	v_mov_b32_e32 v139, v137
	v_mov_b32_e32 v141, v140
	v_mov_b32_e32 v142, v140
	v_mov_b32_e32 v143, v140
	v_mad_u32_u24 v166, v163, s4, v155
	v_lshl_add_u32 v167, v164, 1, v155
	v_sub_u32_e32 v216, v159, v221
	v_sub_u32_e32 v217, v167, v221
	v_add_u32_e32 v216, v216, v220
	v_add_u32_e32 v224, 0x12000, v216
	v_add_u32_e32 v225, 0x12000, v217
	v_lshlrev_b64 v[144:145], 13, v[102:103]
	v_lshlrev_b64 v[146:147], 13, v[104:105]
	v_lshlrev_b64 v[148:149], 22, v[96:97]
	v_lshlrev_b32_e32 v150, 16, v100
	v_mov_b32_e32 v151, v137
	s_mov_b32 s13, 30
	s_add_i32 s14, 0, 0x240a0
	v_lshlrev_b32_e32 v152, 1, v98
	s_mov_b32 s15, 0x20000
	s_mov_b32 s16, 0x40000
	s_mov_b32 s17, 0x60000
	s_mov_b32 s18, 0x80000
	s_mov_b32 s19, 0xa0000
	s_mov_b32 s20, 0xc0000
	s_mov_b32 s21, 0xe0000
	s_mov_b32 s22, 0x14800000
	s_mov_b32 s23, 0
	v_mov_b32_e32 v124, v137
	v_mov_b32_e32 v125, v137
	v_mov_b32_e32 v126, v137
	v_mov_b32_e32 v127, v137
	v_mov_b32_e32 v120, v137
	v_mov_b32_e32 v121, v137
	v_mov_b32_e32 v122, v137
	v_mov_b32_e32 v123, v137
	v_mov_b32_e32 v112, v137
	v_mov_b32_e32 v113, v137
	v_mov_b32_e32 v114, v137
	v_mov_b32_e32 v115, v137
	v_mov_b32_e32 v108, v137
	v_mov_b32_e32 v109, v137
	v_mov_b32_e32 v110, v137
	v_mov_b32_e32 v111, v137
	v_mov_b32_e32 v104, v137
	v_mov_b32_e32 v105, v137
	v_mov_b32_e32 v106, v137
	v_mov_b32_e32 v107, v137
	v_mov_b32_e32 v100, v137
	v_mov_b32_e32 v101, v137
	v_mov_b32_e32 v102, v137
	v_mov_b32_e32 v103, v137
	v_mov_b32_e32 v96, v137
	v_mov_b32_e32 v97, v137
	v_mov_b32_e32 v98, v137
	v_mov_b32_e32 v99, v137
	v_mov_b32_e32 v116, v137
	v_mov_b32_e32 v117, v137
	v_mov_b32_e32 v118, v137
	v_mov_b32_e32 v119, v137
	s_branch .LBB0_382

.LBB0_391:
	s_cmp_lg_u32 s3, 32
	s_cselect_b64 s[10:11], -1, 0
	s_cmp_eq_u32 s3, 32
	ds_write_b128 v216, v[12:15]
	ds_write_b128 v216, v[0:3] offset:4352
	ds_write_b128 v216, v[4:7] offset:8704
	ds_write_b128 v216, v[8:11] offset:13056
	ds_write_b128 v159, v[36:39] offset:34816
	ds_write_b128 v159, v[44:47] offset:39168
	ds_write_b128 v159, v[60:63] offset:43520
	ds_write_b128 v159, v[64:67] offset:47872
	s_cbranch_scc1 .LBB0_393
	v_mov_b32_e32 v0, s12
	ds_read_b64 v[0:1], v0
	s_add_i32 s25, s13, 1
	v_mov_b32_e32 v2, s3
	v_mov_b32_e32 v3, s25
	v_cndmask_b32_e64 v4, v3, v2, s[0:1]
	s_waitcnt lgkmcnt(0)
	v_add_co_u32_e32 v2, vcc, v0, v138
	v_addc_co_u32_e32 v3, vcc, v1, v139, vcc
	v_add_co_u32_e32 v2, vcc, v2, v144
	v_addc_co_u32_e32 v3, vcc, v3, v145, vcc
	v_lshlrev_b32_e32 v136, 8, v4
	v_add_co_u32_e32 v2, vcc, v2, v136
	v_addc_co_u32_e32 v3, vcc, v3, v137, vcc
	v_lshlrev_b32_e32 v4, 1, v134
	v_mov_b32_e32 v5, v137
	v_add_co_u32_e32 v0, vcc, v0, v146
	v_addc_co_u32_e32 v1, vcc, v1, v147, vcc
	v_add_co_u32_e32 v24, vcc, v2, v4
	v_addc_co_u32_e32 v25, vcc, v3, v5, vcc
	v_add_co_u32_e32 v24, vcc, v24, v222
	v_addc_co_u32_e32 v25, vcc, v25, v223, vcc
	v_add_co_u32_e32 v0, vcc, v0, v136
	v_addc_co_u32_e32 v1, vcc, v1, v137, vcc
	v_add_co_u32_e32 v60, vcc, v0, v4
	v_addc_co_u32_e32 v61, vcc, v1, v5, vcc
	v_add_co_u32_e32 v0, vcc, s15, v24
	s_nop 1
	v_addc_co_u32_e32 v1, vcc, 0, v25, vcc
	v_add_co_u32_e32 v4, vcc, s16, v24
	global_load_dwordx4 v[12:15], v[24:25], off
	s_nop 0
	global_load_dwordx4 v[0:3], v[0:1], off
	v_addc_co_u32_e32 v5, vcc, 0, v25, vcc
	v_add_co_u32_e32 v8, vcc, s17, v24
	s_nop 1
	v_addc_co_u32_e32 v9, vcc, 0, v25, vcc
	v_add_co_u32_e32 v16, vcc, s18, v24
	global_load_dwordx4 v[4:7], v[4:5], off
	s_nop 0
	global_load_dwordx4 v[8:11], v[8:9], off
	v_addc_co_u32_e32 v17, vcc, 0, v25, vcc
	v_add_co_u32_e32 v20, vcc, s19, v24
	s_nop 1
	v_addc_co_u32_e32 v21, vcc, 0, v25, vcc
	v_add_co_u32_e32 v26, vcc, s20, v24
	s_nop 0
	v_addc_co_u32_e32 v27, vcc, 0, v25, vcc
	v_add_co_u32_e32 v32, vcc, s21, v24
	s_nop 1
	v_addc_co_u32_e32 v33, vcc, 0, v25, vcc
	v_add_co_u32_e32 v36, vcc, s22, v60
	s_nop 0
	v_addc_co_u32_e32 v37, vcc, 0, v61, vcc
	v_add_co_u32_e32 v44, vcc, 0x14820000, v60
	s_nop 1
	v_addc_co_u32_e32 v45, vcc, 0, v61, vcc
	v_add_co_u32_e32 v62, vcc, 0x14840000, v60
	global_load_dwordx4 v[36:39], v[36:37], off
	s_nop 0
	global_load_dwordx4 v[44:47], v[44:45], off
	v_addc_co_u32_e32 v63, vcc, 0, v61, vcc
	v_add_co_u32_e32 v64, vcc, 0x14860000, v60
	s_nop 1
	v_addc_co_u32_e32 v65, vcc, 0, v61, vcc
	global_load_dwordx4 v[60:63], v[62:63], off
	s_nop 0
	global_load_dwordx4 v[64:67], v[64:65], off

.LBB0_400:
	s_and_b64 vcc, exec, s[4:5]
	s_cbranch_vccnz .LBB0_402
	v_mov_b32_e32 v131, s14
	ds_read_b64 v[168:169], v131
	v_lshlrev_b64 v[170:171], 17, v[136:137]
	v_mov_b32_e32 v153, v137
	v_mov_b32_e32 v131, v137
	s_waitcnt lgkmcnt(0)
	v_add_co_u32_e32 v168, vcc, v168, v170
	v_addc_co_u32_e32 v169, vcc, v169, v171, vcc
	v_add_co_u32_e32 v168, vcc, v168, v148
	v_addc_co_u32_e32 v169, vcc, v169, v149, vcc
	v_add_co_u32_e32 v168, vcc, v168, v150
	v_addc_co_u32_e32 v169, vcc, v169, v151, vcc
	v_add_co_u32_e32 v168, vcc, v168, v152
	v_addc_co_u32_e32 v169, vcc, v169, v153, vcc
	v_and_b32_e32 v170, 4, v128
	v_lshlrev_b32_e32 v170, 3, v170
	v_and_b32_e32 v171, 8, v128
	v_lshl_add_u32 v170, v171, 1, v170
	v_mov_b32_e32 v171, 0
	v_add_co_u32_e32 v168, vcc, v168, v170
	v_addc_co_u32_e32 v169, vcc, v169, v171, vcc
	v_cvt_pk_bf16_f32 v240, v124, v125
	v_cvt_pk_bf16_f32 v241, v126, v127
	v_cvt_pk_bf16_f32 v242, v120, v121
	v_cvt_pk_bf16_f32 v243, v122, v123
	s_nop 1
	v_permlane16_swap_b32_e32 v240, v242
	v_permlane16_swap_b32_e32 v241, v243
	global_store_dwordx4 v[168:169], v[240:243], off
	v_cvt_pk_bf16_f32 v244, v116, v117
	v_cvt_pk_bf16_f32 v245, v118, v119
	v_cvt_pk_bf16_f32 v246, v112, v113
	v_cvt_pk_bf16_f32 v247, v114, v115
	s_nop 1
	v_permlane16_swap_b32_e32 v244, v246
	v_permlane16_swap_b32_e32 v245, v247
	global_store_dwordx4 v[168:169], v[244:247], off offset:64
	v_cvt_pk_bf16_f32 v248, v108, v109
	v_cvt_pk_bf16_f32 v249, v110, v111
	v_cvt_pk_bf16_f32 v250, v104, v105
	v_cvt_pk_bf16_f32 v251, v106, v107
	s_nop 1
	v_permlane16_swap_b32_e32 v248, v250
	v_permlane16_swap_b32_e32 v249, v251
	global_store_dwordx4 v[168:169], v[248:251], off offset:128
	v_cvt_pk_bf16_f32 v252, v100, v101
	v_cvt_pk_bf16_f32 v253, v102, v103
	v_cvt_pk_bf16_f32 v254, v96, v97
	v_cvt_pk_bf16_f32 v255, v98, v99
	s_nop 1
	v_permlane16_swap_b32_e32 v252, v254
	v_permlane16_swap_b32_e32 v253, v255
	global_store_dwordx4 v[168:169], v[252:255], off offset:192
.LBB0_402:
	s_andn2_b64 vcc, exec, s[10:11]
	ds_write_b128 v224, v[52:55]
	ds_write_b128 v224, v[28:31] offset:4352
	ds_write_b128 v224, v[40:43] offset:8704
	ds_write_b128 v224, v[48:51] offset:13056
	ds_write_b128 v159, v[80:83] offset:52224
	ds_write_b128 v159, v[84:87] offset:56576
	ds_write_b128 v159, v[88:91] offset:60928
	ds_write_b128 v159, v[92:95] offset:65280
	s_cbranch_vccnz .LBB0_381
	v_mov_b32_e32 v28, s12
	ds_read_b64 v[28:29], v28
	v_mov_b32_e32 v30, s13
	v_mov_b32_e32 v31, s8
	v_cndmask_b32_e64 v30, v30, v31, s[0:1]
	v_lshlrev_b32_e32 v136, 8, v30
	s_waitcnt lgkmcnt(0)
	v_add_co_u32_e32 v30, vcc, v28, v138
	v_addc_co_u32_e32 v31, vcc, v29, v139, vcc
	v_add_co_u32_e32 v30, vcc, v30, v144
	v_addc_co_u32_e32 v31, vcc, v31, v145, vcc
	v_add_co_u32_e32 v30, vcc, v30, v136
	v_addc_co_u32_e32 v31, vcc, v31, v137, vcc
	v_lshlrev_b32_e32 v40, 1, v134
	v_mov_b32_e32 v41, v137
	v_add_co_u32_e32 v28, vcc, v28, v146
	v_addc_co_u32_e32 v29, vcc, v29, v147, vcc
	v_add_co_u32_e32 v72, vcc, v30, v40
	v_addc_co_u32_e32 v73, vcc, v31, v41, vcc
	v_add_co_u32_e32 v72, vcc, v72, v222
	v_addc_co_u32_e32 v73, vcc, v73, v223, vcc
	v_add_co_u32_e32 v28, vcc, v28, v136
	v_addc_co_u32_e32 v29, vcc, v29, v137, vcc
	v_add_co_u32_e32 v88, vcc, v28, v40
	v_addc_co_u32_e32 v89, vcc, v29, v41, vcc
	v_add_co_u32_e32 v28, vcc, s15, v72
	s_nop 1
	v_addc_co_u32_e32 v29, vcc, 0, v73, vcc
	v_add_co_u32_e32 v40, vcc, s16, v72
	global_load_dwordx4 v[52:55], v[72:73], off
	s_nop 0
	global_load_dwordx4 v[28:31], v[28:29], off
	v_addc_co_u32_e32 v41, vcc, 0, v73, vcc
	v_add_co_u32_e32 v48, vcc, s17, v72
	s_nop 1
	v_addc_co_u32_e32 v49, vcc, 0, v73, vcc
	v_add_co_u32_e32 v56, vcc, s18, v72
	global_load_dwordx4 v[40:43], v[40:41], off
	s_nop 0
	global_load_dwordx4 v[48:51], v[48:49], off
	v_addc_co_u32_e32 v57, vcc, 0, v73, vcc
	v_add_co_u32_e32 v68, vcc, s19, v72
	s_nop 1
	v_addc_co_u32_e32 v69, vcc, 0, v73, vcc
	v_add_co_u32_e32 v74, vcc, s20, v72
	s_nop 0
	v_addc_co_u32_e32 v75, vcc, 0, v73, vcc
	v_add_co_u32_e32 v76, vcc, s21, v72
	s_nop 1
	v_addc_co_u32_e32 v77, vcc, 0, v73, vcc
	v_add_co_u32_e32 v80, vcc, s22, v88
	s_nop 0
	v_addc_co_u32_e32 v81, vcc, 0, v89, vcc
	v_add_co_u32_e32 v84, vcc, 0x14820000, v88
	s_nop 1
	v_addc_co_u32_e32 v85, vcc, 0, v89, vcc
	v_add_co_u32_e32 v90, vcc, 0x14840000, v88
	global_load_dwordx4 v[80:83], v[80:81], off
	s_nop 0
	global_load_dwordx4 v[84:87], v[84:85], off
	v_addc_co_u32_e32 v91, vcc, 0, v89, vcc
	v_add_co_u32_e32 v92, vcc, 0x14860000, v88
	s_nop 1
	v_addc_co_u32_e32 v93, vcc, 0, v89, vcc
	global_load_dwordx4 v[88:91], v[90:91], off
	s_nop 0
	global_load_dwordx4 v[92:95], v[92:93], off
	s_branch .LBB0_381

.LBB0_406:
	s_waitcnt vmcnt(0)
	v_sub_u32_e64 v0, v163, 8 clamp
	v_min_u32_e32 v42, 48, v0
	v_sub_u32_e64 v0, v165, 8 clamp
	v_min_u32_e32 v105, 32, v0
	v_add_u32_e32 v43, v105, v128
	v_sub_u32_e32 v0, v43, v163
	v_max_i32_e32 v0, -15, v0
	v_add_u32_e32 v0, 15, v0
	v_add_u32_e32 v52, 16, v42
	v_min_u32_e32 v53, 30, v0
	v_or_b32_e32 v0, 1, v43
	v_cmp_lt_u32_e64 s[6:7], v0, v42
	v_cmp_ge_u32_e64 s[8:9], v0, v52
	v_sub_u32_e32 v0, v0, v163
	v_max_i32_e32 v0, -15, v0
	v_add_u32_e32 v0, 15, v0
	v_min_u32_e32 v54, 30, v0
	v_or_b32_e32 v0, 2, v43
	v_cmp_lt_u32_e64 s[10:11], v0, v42
	v_cmp_ge_u32_e64 s[12:13], v0, v52
	v_sub_u32_e32 v0, v0, v163
	v_max_i32_e32 v0, -15, v0
	v_add_u32_e32 v0, 15, v0
	v_min_u32_e32 v55, 30, v0
	v_or_b32_e32 v0, 3, v43
	s_mul_i32 s0, s2, 10
	v_cmp_lt_u32_e64 s[14:15], v0, v42
	v_cmp_ge_u32_e64 s[16:17], v0, v52
	v_sub_u32_e32 v0, v0, v163
	s_addk_i32 s0, 0xb00
	v_max_i32_e32 v0, -15, v0
	v_add_u32_e32 v101, s0, v162
	v_add_u32_e32 v0, 15, v0
	v_min_u32_e32 v56, 30, v0
	v_add_u32_e32 v0, 16, v43
	v_and_b32_e32 v44, 63, v101
	v_cmp_lt_u32_e64 s[18:19], v0, v42
	v_sub_u32_e32 v57, v0, v163
	v_sub_u32_e64 v0, v44, 4 clamp
	s_add_i32 s3, 0, 0x240a8
	v_min_u32_e32 v7, 56, v0
	v_mov_b32_e32 v0, s3
	ds_read_b64 v[2:3], v0
	v_lshlrev_b32_e32 v0, 3, v101
	s_movk_i32 s72, 0xf000
	v_and_or_b32 v45, v0, s72, v154
	v_lshl_or_b32 v0, v7, 6, v45
	v_ashrrev_i32_e32 v1, 31, v0
	v_and_b32_e32 v6, 0x1c0, v101
	v_lshlrev_b64 v[0:1], 10, v[0:1]
	v_and_b32_e32 v100, 56, v158
	s_waitcnt lgkmcnt(0)
	v_add_co_u32_e32 v4, vcc, v2, v0
	v_addc_co_u32_e32 v5, vcc, v3, v1, vcc
	v_lshlrev_b32_e32 v0, 1, v6
	v_mov_b32_e32 v1, 0
	v_add_co_u32_e32 v4, vcc, v4, v0
	v_addc_co_u32_e32 v5, vcc, v5, v1, vcc
	v_lshlrev_b32_e32 v36, 1, v100
	v_mov_b32_e32 v37, v1
	v_add_co_u32_e32 v12, vcc, v4, v36
	v_addc_co_u32_e32 v13, vcc, v5, v37, vcc
	s_mov_b32 s20, 0x8800000
	v_add_co_u32_e32 v14, vcc, s20, v12
	s_movk_i32 s73, 0xffc0
	s_nop 0
	v_addc_co_u32_e32 v15, vcc, 0, v13, vcc
	s_mov_b32 s20, 0x8808000
	v_and_or_b32 v4, v101, s73, v135
	v_add_co_u32_e32 v16, vcc, s20, v12
	v_ashrrev_i32_e32 v5, 31, v4
	s_nop 0
	v_addc_co_u32_e32 v17, vcc, 0, v13, vcc
	s_mov_b32 s20, 0x8810000
	v_lshlrev_b64 v[4:5], 13, v[4:5]
	v_add_co_u32_e32 v20, vcc, s20, v12
	v_lshl_add_u64 v[4:5], v[2:3], 0, v[4:5]
	v_lshlrev_b32_e32 v6, 7, v7
	v_mov_b32_e32 v7, v1
	v_addc_co_u32_e32 v21, vcc, 0, v13, vcc
	s_mov_b32 s20, 0x8818000
	v_add_co_u32_e32 v4, vcc, v4, v6
	v_addc_co_u32_e32 v5, vcc, v5, v7, vcc
	v_lshlrev_b32_e32 v102, 1, v134
	v_mov_b32_e32 v103, v1
	v_add_co_u32_e32 v22, vcc, s20, v12
	v_lshl_add_u64 v[28:29], v[4:5], 0, v[102:103]
	s_nop 0
	v_addc_co_u32_e32 v23, vcc, 0, v13, vcc
	s_mov_b32 s20, 0xa800000
	v_add_co_u32_e32 v30, vcc, s20, v28
	s_mov_b32 s20, 0xa820000
	s_nop 0
	v_addc_co_u32_e32 v31, vcc, 0, v29, vcc
	v_add_co_u32_e32 v32, vcc, s20, v28
	s_mov_b32 s20, 0xa840000
	s_nop 0
	v_addc_co_u32_e32 v33, vcc, 0, v29, vcc
	v_add_co_u32_e32 v38, vcc, s20, v28
	s_mov_b32 s20, 0xa860000
	s_nop 0
	v_addc_co_u32_e32 v39, vcc, 0, v29, vcc
	v_add_co_u32_e32 v40, vcc, s20, v28
	flat_load_dwordx4 v[4:7], v[14:15]
	flat_load_dwordx4 v[8:11], v[16:17]
	s_nop 0
	flat_load_dwordx4 v[12:15], v[20:21]
	flat_load_dwordx4 v[16:19], v[22:23]
	s_nop 0
	flat_load_dwordx4 v[20:23], v[30:31]
	flat_load_dwordx4 v[24:27], v[32:33]
	v_addc_co_u32_e32 v41, vcc, 0, v29, vcc
	flat_load_dwordx4 v[28:31], v[38:39]
	flat_load_dwordx4 v[32:35], v[40:41]
	v_lshl_or_b32 v38, v44, 6, v45
	v_ashrrev_i32_e32 v39, 31, v38
	v_lshlrev_b64 v[38:39], 10, v[38:39]
	v_add_co_u32_e32 v2, vcc, v2, v38
	v_addc_co_u32_e32 v3, vcc, v3, v39, vcc
	v_add_co_u32_e32 v2, vcc, v2, v0
	v_addc_co_u32_e32 v3, vcc, v3, v1, vcc
	v_add_co_u32_e32 v2, vcc, v2, v36
	v_addc_co_u32_e32 v3, vcc, v3, v37, vcc
	s_mov_b32 s74, 0x6800000
	v_add_co_u32_e32 v38, vcc, s74, v2
	s_mov_b32 s20, 0x6808000
	s_nop 0
	v_addc_co_u32_e32 v39, vcc, 0, v3, vcc
	v_add_co_u32_e32 v2, vcc, s20, v2
	v_add_u32_e32 v37, 19, v43
	s_nop 0
	v_addc_co_u32_e32 v3, vcc, 0, v3, vcc
	flat_load_dwordx4 v[44:47], v[38:39]
	flat_load_dwordx4 v[48:51], v[2:3]
	v_mul_u32_u24_e32 v38, 0x48, v154
	v_lshlrev_b32_e32 v38, 1, v38
	v_add3_u32 v124, v161, v38, v36
	v_mul_u32_u24_e32 v38, 0x90, v163
	v_lshlrev_b32_e32 v39, 1, v157
	v_add3_u32 v125, v161, v38, v39
	v_mbcnt_lo_u32_b32 v38, -1, 0
	v_mbcnt_hi_u32_b32 v38, -1, v38
	v_and_b32_e32 v40, 64, v38
	v_xor_b32_e32 v39, 16, v38
	v_add_u32_e32 v40, 64, v40
	v_add_u32_e32 v2, 17, v43
	v_add_u32_e32 v3, 18, v43
	v_cmp_lt_i32_e32 vcc, v39, v40
	v_max_i32_e32 v0, -15, v57
	v_cmp_lt_u32_e64 s[20:21], v2, v42
	v_cmp_ge_u32_e64 s[22:23], v2, v52
	v_sub_u32_e32 v2, v2, v163
	v_cmp_lt_u32_e64 s[24:25], v3, v42
	v_cmp_ge_u32_e64 s[26:27], v3, v52
	v_sub_u32_e32 v3, v3, v163
	v_cmp_lt_u32_e64 s[28:29], v37, v42
	v_cmp_ge_u32_e64 s[30:31], v37, v52
	v_sub_u32_e32 v37, v37, v163
	v_cndmask_b32_e32 v39, v38, v39, vcc
	v_add_u32_e32 v0, 15, v0
	v_max_i32_e32 v2, -15, v2
	v_max_i32_e32 v3, -15, v3
	v_max_i32_e32 v37, -15, v37
	v_lshlrev_b32_e32 v126, 2, v39
	v_xor_b32_e32 v39, 32, v38
	v_min_u32_e32 v0, 30, v0
	v_add_u32_e32 v2, 15, v2
	v_add_u32_e32 v3, 15, v3
	v_add_u32_e32 v37, 15, v37
	v_cmp_lt_i32_e32 vcc, v39, v40
	v_min_u32_e32 v2, 30, v2
	v_min_u32_e32 v3, 30, v3
	v_min_u32_e32 v37, 30, v37
	v_sub_u32_e32 v36, v155, v157
	v_cndmask_b32_e32 v38, v38, v39, vcc
	v_lshl_add_u32 v141, v0, 2, v161
	v_add3_u32 v0, v160, v156, 0
	v_cmp_ge_u32_e64 s[0:1], v43, v42
	v_cmp_lt_u32_e64 s[36:37], v43, v42
	v_cmp_ge_u32_e64 s[4:5], v43, v52
	s_mov_b32 s39, 0
	s_movk_i32 s75, 0x90
	v_lshlrev_b32_e32 v127, 2, v38
	v_or_b32_e32 v128, 64, v105
	v_mul_u32_u24_e32 v134, 0x90, v129
	v_lshl_add_u32 v136, v164, 1, v36
	v_lshl_add_u32 v137, v53, 2, v161
	v_lshl_add_u32 v138, v54, 2, v161
	v_lshl_add_u32 v139, v55, 2, v161
	v_lshl_add_u32 v140, v56, 2, v161
	v_lshl_add_u32 v142, v2, 2, v161
	v_lshl_add_u32 v143, v3, 2, v161
	v_lshl_add_u32 v144, v37, 2, v161
	v_add_u32_e32 v145, 0xb000, v0
	v_or_b32_e32 v146, 0xffffff00, v133
	s_add_i32 s76, 0, 0x24040
	s_mov_b64 s[42:43], 0x400
	s_movk_i32 s77, 0xd0
	s_mov_b64 s[44:45], 0x1c800000
	s_mov_b64 s[46:47], 0x1ca00000
	s_mov_b64 s[48:49], 0x8800000
	s_mov_b64 s[50:51], 0xa800000
	s_mov_b32 s78, 0x8000
	s_mov_b32 s79, 0x10000
	s_mov_b32 s80, 0xf149f2ca
	s_mov_b32 s81, 0xefa18f08
	s_mov_b64 s[52:53], 0x6800000
	v_mov_b32_e32 v147, 0xf149f2ca
	s_mov_b32 s82, 0
	s_branch .LBB0_408
.LBB0_407:
	ds_bpermute_b32 v0, v126, v152
	v_lshlrev_b32_e32 v69, 3, v148
	v_lshlrev_b32_e32 v70, 6, v131
	v_and_b32_e32 v69, 0xfffff000, v69
	v_mov_b32_e32 v2, s3
	s_waitcnt lgkmcnt(0)
	v_add_f32_e32 v0, v152, v0
	ds_bpermute_b32 v68, v127, v0
	ds_read_b64 v[2:3], v2
	v_mov_b32_e32 v131, v1
	s_add_i32 s82, s82, 1
	s_cmp_eq_u32 s82, 5
	s_waitcnt lgkmcnt(1)
	v_add_f32_e32 v0, v0, v68
	v_div_scale_f32 v71, s[34:35], v0, v0, 1.0
	v_rcp_f32_e32 v72, v71
	v_or3_b32 v68, v69, v70, v163
	v_div_scale_f32 v69, vcc, 1.0, v0, 1.0
	v_fma_f32 v70, -v71, v72, 1.0
	v_fmac_f32_e32 v72, v70, v72
	v_mul_f32_e32 v70, v69, v72
	v_fma_f32 v73, -v71, v70, v69
	v_fmac_f32_e32 v70, v73, v72
	v_fma_f32 v69, -v71, v70, v69
	v_div_fmas_f32 v69, v69, v72, v70
	v_div_fixup_f32 v70, v69, v0, 1.0
	v_ashrrev_i32_e32 v69, 31, v68
	v_lshlrev_b64 v[68:69], 10, v[68:69]
	s_waitcnt lgkmcnt(0)
	v_add_co_u32_e32 v2, vcc, v2, v68
	v_addc_co_u32_e32 v3, vcc, v3, v69, vcc
	v_lshlrev_b32_e32 v0, 1, v104
	v_add_co_u32_e32 v2, vcc, v2, v0
	v_addc_co_u32_e32 v3, vcc, v3, v1, vcc
	v_add_co_u32_e32 v2, vcc, v2, v130
	v_addc_co_u32_e32 v3, vcc, v3, v131, vcc
	v_lshl_add_u64 v[68:69], v[2:3], 0, s[52:53]
	v_pk_mul_f32 v[64:65], v[64:65], v[70:71] op_sel_hi:[1,0]
	v_pk_mul_f32 v[66:67], v[66:67], v[70:71] op_sel_hi:[1,0]
	v_add_co_u32_e32 v2, vcc, s74, v2
	v_cvt_pk_bf16_f32 v64, v64, v65
	v_cvt_pk_bf16_f32 v65, v66, v67
	v_addc_co_u32_e32 v3, vcc, 0, v3, vcc
	global_store_dwordx2 v[2:3], v[64:65], off
	v_pk_mul_f32 v[2:3], v[60:61], v[70:71] op_sel_hi:[1,0]
	v_pk_mul_f32 v[60:61], v[62:63], v[70:71] op_sel_hi:[1,0]
	v_cvt_pk_bf16_f32 v2, v2, v3
	v_cvt_pk_bf16_f32 v3, v60, v61
	global_store_dwordx2 v[68:69], v[2:3], off offset:32
	v_pk_mul_f32 v[2:3], v[56:57], v[70:71] op_sel_hi:[1,0]
	v_pk_mul_f32 v[56:57], v[58:59], v[70:71] op_sel_hi:[1,0]
	v_cvt_pk_bf16_f32 v2, v2, v3
	v_cvt_pk_bf16_f32 v3, v56, v57
	global_store_dwordx2 v[68:69], v[2:3], off offset:64
	v_pk_mul_f32 v[2:3], v[52:53], v[70:71] op_sel_hi:[1,0]
	v_pk_mul_f32 v[52:53], v[54:55], v[70:71] op_sel_hi:[1,0]
	v_cvt_pk_bf16_f32 v2, v2, v3
	v_cvt_pk_bf16_f32 v3, v52, v53
	global_store_dwordx2 v[68:69], v[2:3], off offset:96
	s_cbranch_scc1 .LBB0_462

.LBB0_410:
	s_cmp_eq_u32 s83, 0
	s_cselect_b64 s[34:35], -1, 0
	s_cmp_lg_u32 s83, 0
	s_waitcnt lgkmcnt(0)
	s_barrier
	s_waitcnt vmcnt(0)
	ds_write_b128 v124, v[4:7] offset:9216
	ds_write_b128 v124, v[8:11] offset:13824
	ds_write_b128 v124, v[12:15] offset:18432
	ds_write_b128 v124, v[16:19] offset:23040
	ds_write_b128 v159, v[20:23] offset:27648
	ds_write_b128 v159, v[24:27] offset:32000
	ds_write_b128 v159, v[28:31] offset:36352
	ds_write_b128 v159, v[32:35] offset:40704
	s_cbranch_scc1 .LBB0_414
	ds_write_b128 v124, v[44:47]
	ds_write_b128 v124, v[48:51] offset:4608
	v_mov_b32_e32 v0, s76
	ds_read_b64 v[2:3], v0
	s_mov_b64 s[56:57], 0
	v_mov_b32_e32 v0, v146
	v_mov_b32_e32 v68, v145
	s_waitcnt lgkmcnt(0)
	v_add_co_u32_e32 v2, vcc, v2, v116
	v_addc_co_u32_e32 v3, vcc, v3, v117, vcc

.LBB0_414:
	s_cmp_eq_u32 s83, 5
	s_mov_b64 s[56:57], -1
	s_waitcnt lgkmcnt(0)
	s_barrier
	s_cbranch_scc1 .LBB0_420
	v_mov_b32_e32 v0, s3
	ds_read_b64 v[68:69], v0
	s_lshl_b32 s58, s83, 7
	s_cmp_gt_u32 s83, 2
	s_cbranch_scc0 .LBB0_417
	s_add_i32 s38, s58, 0xfffffe80
	v_add_u32_e32 v2, s38, v149
	v_ashrrev_i32_e32 v3, 31, v2
	v_lshlrev_b64 v[2:3], 10, v[2:3]
	s_waitcnt lgkmcnt(0)
	v_add_co_u32_e32 v2, vcc, v68, v2
	v_addc_co_u32_e32 v3, vcc, v69, v3, vcc
	v_add_co_u32_e32 v70, vcc, v68, v106
	v_addc_co_u32_e32 v71, vcc, v69, v107, vcc
	v_lshl_add_u64 v[2:3], v[2:3], 0, s[44:45]
	v_lshl_add_u64 v[70:71], v[70:71], 0, s[46:47]
	s_mov_b64 s[56:57], 0
.LBB0_417:
	s_andn2_b64 vcc, exec, s[56:57]
	s_mov_b64 s[56:57], 0x1000
	s_cbranch_vccnz .LBB0_419
	s_add_i32 s38, s58, 0x80
	v_add_u32_e32 v2, s38, v150
	v_ashrrev_i32_e32 v3, 31, v2
	v_lshlrev_b64 v[2:3], 10, v[2:3]
	s_waitcnt lgkmcnt(0)
	v_add_co_u32_e32 v2, vcc, v68, v2
	v_addc_co_u32_e32 v3, vcc, v69, v3, vcc
	v_add_co_u32_e32 v68, vcc, v68, v108
	v_addc_co_u32_e32 v69, vcc, v69, v109, vcc
	v_mov_b32_e32 v119, v1
	v_add_co_u32_e32 v68, vcc, v68, v118
	v_addc_co_u32_e32 v69, vcc, v69, v119, vcc
	v_lshl_add_u64 v[2:3], v[2:3], 0, s[48:49]
	v_lshl_add_u64 v[70:71], v[68:69], 0, s[50:51]
	s_mov_b64 s[56:57], 0x10000
.LBB0_419:
	v_lshlrev_b32_e32 v0, 1, v104
	v_add_co_u32_e32 v2, vcc, v2, v0
	v_addc_co_u32_e32 v3, vcc, v3, v1, vcc
	v_lshlrev_b32_e32 v0, 1, v100
	v_add_co_u32_e32 v2, vcc, v2, v0
	v_addc_co_u32_e32 v3, vcc, v3, v1, vcc
	v_add_co_u32_e32 v72, vcc, s78, v2
	s_waitcnt lgkmcnt(0)
	v_lshl_add_u64 v[68:69], s[38:39], 1, v[70:71]
	v_addc_co_u32_e32 v73, vcc, 0, v3, vcc
	v_add_co_u32_e32 v76, vcc, s79, v2
	v_mov_b32_e32 v103, v1
	s_nop 0
	v_addc_co_u32_e32 v77, vcc, 0, v3, vcc
	v_add_co_u32_e32 v88, vcc, v68, v102
	v_addc_co_u32_e32 v89, vcc, v69, v103, vcc
	global_load_dwordx4 v[4:7], v[2:3], off
	v_add_co_u32_e32 v2, vcc, 0x18000, v2
	s_lshl_b32 s38, s56, 1
	s_nop 0
	v_addc_co_u32_e32 v3, vcc, 0, v3, vcc
	global_load_dwordx4 v[8:11], v[72:73], off
	s_nop 0
	global_load_dwordx4 v[12:15], v[76:77], off
	s_nop 0
	global_load_dwordx4 v[16:19], v[2:3], off
	global_load_dwordx4 v[20:23], v[88:89], off
	v_lshl_add_u64 v[2:3], v[88:89], 0, s[38:39]
	v_lshl_add_u64 v[96:97], v[2:3], 0, s[38:39]
	global_load_dwordx4 v[24:27], v[2:3], off
	global_load_dwordx4 v[28:31], v[96:97], off
	v_lshl_add_u64 v[2:3], v[96:97], 0, s[38:39]
	global_load_dwordx4 v[32:35], v[2:3], off
	s_mov_b64 s[56:57], 0
.LBB0_420:
	s_and_b64 vcc, exec, s[56:57]
	s_cbranch_vccz .LBB0_451
	s_andn2_b64 vcc, exec, s[54:55]
	s_cbranch_vccnz .LBB0_423
	v_mov_b32_e32 v0, s3
	ds_read_b64 v[2:3], v0
	v_mov_b32_e32 v121, v1
	v_lshlrev_b32_e32 v0, 1, v100
	v_mov_b32_e32 v123, v1
	v_mov_b32_e32 v103, v1
	s_waitcnt lgkmcnt(0)
	v_add_co_u32_e32 v4, vcc, v2, v110
	v_addc_co_u32_e32 v5, vcc, v3, v111, vcc
	v_add_co_u32_e32 v6, vcc, v2, v112
	v_addc_co_u32_e32 v7, vcc, v3, v113, vcc
	v_add_co_u32_e32 v4, vcc, v4, v120
	v_addc_co_u32_e32 v5, vcc, v5, v121, vcc
	v_add_co_u32_e32 v12, vcc, v4, v0
	v_addc_co_u32_e32 v13, vcc, v5, v1, vcc
	v_add_co_u32_e32 v4, vcc, v6, v122
	v_addc_co_u32_e32 v5, vcc, v7, v123, vcc
	v_add_co_u32_e32 v28, vcc, v4, v102
	v_addc_co_u32_e32 v29, vcc, v5, v103, vcc
	v_add_co_u32_e32 v4, vcc, 0x8800000, v12
	v_lshl_add_u64 v[2:3], v[2:3], 0, v[114:115]
	s_nop 0
	v_addc_co_u32_e32 v5, vcc, 0, v13, vcc
	v_add_co_u32_e32 v8, vcc, 0x8808000, v12
	v_lshl_add_u64 v[2:3], v[2:3], 0, v[120:121]
	s_nop 0
	v_addc_co_u32_e32 v9, vcc, 0, v13, vcc
	v_add_co_u32_e32 v14, vcc, 0x8810000, v12
	v_lshl_add_u64 v[2:3], v[2:3], 0, v[0:1]
	s_nop 0
	v_addc_co_u32_e32 v15, vcc, 0, v13, vcc
	v_add_co_u32_e32 v16, vcc, 0x8818000, v12
	global_load_dwordx4 v[4:7], v[4:5], off
	s_nop 0
	global_load_dwordx4 v[8:11], v[8:9], off
	v_addc_co_u32_e32 v17, vcc, 0, v13, vcc
	v_add_co_u32_e32 v20, vcc, 0xa800000, v28
	global_load_dwordx4 v[12:15], v[14:15], off
	s_nop 0
	global_load_dwordx4 v[16:19], v[16:17], off
	v_addc_co_u32_e32 v21, vcc, 0, v29, vcc
	v_add_co_u32_e32 v24, vcc, 0xa820000, v28
	s_nop 1
	v_addc_co_u32_e32 v25, vcc, 0, v29, vcc
	v_add_co_u32_e32 v30, vcc, 0xa840000, v28
	global_load_dwordx4 v[20:23], v[20:21], off
	s_nop 0
	global_load_dwordx4 v[24:27], v[24:25], off
	v_addc_co_u32_e32 v31, vcc, 0, v29, vcc
	v_add_co_u32_e32 v32, vcc, 0xa860000, v28
	s_nop 1
	v_addc_co_u32_e32 v33, vcc, 0, v29, vcc
	v_add_co_u32_e32 v44, vcc, 0x6800000, v2
	global_load_dwordx4 v[28:31], v[30:31], off
	s_nop 0
	global_load_dwordx4 v[32:35], v[32:33], off
	v_addc_co_u32_e32 v45, vcc, 0, v3, vcc
	v_add_co_u32_e32 v2, vcc, 0x6808000, v2
	s_nop 1
	v_addc_co_u32_e32 v3, vcc, 0, v3, vcc
	global_load_dwordx4 v[44:47], v[44:45], off
	s_nop 0
	global_load_dwordx4 v[48:51], v[2:3], off

.LBB0_738:
	s_waitcnt lgkmcnt(0)
	ds_read_b32 v8, v202 offset:4
	s_waitcnt vmcnt(0)
	v_lshlrev_b32_e32 v12, 16, v4
	v_and_b32_e32 v13, 0xffff0000, v4
	v_or_b32_e32 v16, s24, v141
	s_mov_b32 s30, 0x20000
	s_waitcnt lgkmcnt(0)
	v_pk_mul_f32 v[12:13], v[8:9], v[12:13] op_sel_hi:[0,1]
	v_cvt_pk_bf16_f32 v4, v12, v13
	v_lshlrev_b32_e32 v12, 16, v5
	v_and_b32_e32 v13, 0xffff0000, v5
	v_pk_mul_f32 v[12:13], v[8:9], v[12:13] op_sel_hi:[0,1]
	v_cvt_pk_bf16_f32 v5, v12, v13
	v_lshlrev_b32_e32 v12, 16, v6
	v_and_b32_e32 v13, 0xffff0000, v6
	v_pk_mul_f32 v[12:13], v[8:9], v[12:13] op_sel_hi:[0,1]
	v_cvt_pk_bf16_f32 v6, v12, v13
	v_lshlrev_b32_e32 v12, 16, v7
	v_and_b32_e32 v13, 0xffff0000, v7
	v_pk_mul_f32 v[8:9], v[8:9], v[12:13] op_sel_hi:[0,1]
	v_cvt_pk_bf16_f32 v7, v8, v9
	ds_write_b128 v85, v[4:7] offset:26112
	flat_load_dwordx4 v[4:7], v[10:11]
	ds_read_b32 v8, v203 offset:4
	s_waitcnt vmcnt(0) lgkmcnt(0)
	v_lshlrev_b32_e32 v10, 16, v4
	v_and_b32_e32 v11, 0xffff0000, v4
	v_pk_mul_f32 v[10:11], v[8:9], v[10:11] op_sel_hi:[0,1]
	v_cvt_pk_bf16_f32 v4, v10, v11
	v_lshlrev_b32_e32 v10, 16, v5
	v_and_b32_e32 v11, 0xffff0000, v5
	v_pk_mul_f32 v[10:11], v[8:9], v[10:11] op_sel_hi:[0,1]
	v_cvt_pk_bf16_f32 v5, v10, v11
	v_lshlrev_b32_e32 v10, 16, v6
	v_and_b32_e32 v11, 0xffff0000, v6
	v_pk_mul_f32 v[10:11], v[8:9], v[10:11] op_sel_hi:[0,1]
	v_cvt_pk_bf16_f32 v6, v10, v11
	v_lshlrev_b32_e32 v10, 16, v7
	v_and_b32_e32 v11, 0xffff0000, v7
	v_pk_mul_f32 v[8:9], v[8:9], v[10:11] op_sel_hi:[0,1]
	v_cvt_pk_bf16_f32 v7, v8, v9
	ds_write_b128 v85, v[4:7] offset:30464
	v_or_b32_e32 v4, v16, v216
	v_ashrrev_i32_e32 v5, 31, v4
	v_lshlrev_b64 v[4:5], 13, v[4:5]
	v_add_co_u32_e32 v12, vcc, v112, v4
	v_addc_co_u32_e32 v13, vcc, v113, v5, vcc
	v_add_co_u32_e32 v14, vcc, s30, v12
	s_waitcnt lgkmcnt(0)
	s_nop 0
	v_addc_co_u32_e32 v15, vcc, 0, v13, vcc
	s_barrier
	global_load_dwordx4 v[4:7], v[12:13], off
	global_load_dwordx4 v[8:11], v[14:15], off
	global_load_dwordx4 v[240:243], v[12:13], off offset:64
	global_load_dwordx4 v[244:247], v[14:15], off offset:64
	global_load_dwordx4 v[248:251], v[12:13], off offset:128
	global_load_dwordx4 v[252:255], v[14:15], off offset:128
	ds_read_b128 v[18:21], v204 offset:34816
	ds_read_b128 v[26:29], v204 offset:39168
	ds_read_b128 v[34:37], v204 offset:43520
	ds_read_b128 v[42:45], v204 offset:47872
	ds_read_b128 v[50:53], v204 offset:52224
	ds_read_b128 v[58:61], v204 offset:56576
	ds_read_b128 v[136:139], v204 offset:60928
	ds_read_b128 v[222:225], v204 offset:65280
	s_mov_b64 s[30:31], 0
	s_waitcnt vmcnt(4) lgkmcnt(0)
	v_mfma_f32_16x16x32_bf16 v[22:25], v[18:21], v[4:7], 0
	v_mfma_f32_16x16x32_bf16 v[18:21], v[18:21], v[8:11], 0
	v_mfma_f32_16x16x32_bf16 v[30:33], v[26:29], v[4:7], 0
	v_mfma_f32_16x16x32_bf16 v[26:29], v[26:29], v[8:11], 0
	v_mfma_f32_16x16x32_bf16 v[38:41], v[34:37], v[4:7], 0
	v_mfma_f32_16x16x32_bf16 v[34:37], v[34:37], v[8:11], 0
	v_mfma_f32_16x16x32_bf16 v[46:49], v[42:45], v[4:7], 0
	v_mfma_f32_16x16x32_bf16 v[42:45], v[42:45], v[8:11], 0
	v_mfma_f32_16x16x32_bf16 v[54:57], v[50:53], v[4:7], 0
	v_mfma_f32_16x16x32_bf16 v[50:53], v[50:53], v[8:11], 0
	v_mfma_f32_16x16x32_bf16 v[62:65], v[58:61], v[4:7], 0
	v_mfma_f32_16x16x32_bf16 v[58:61], v[58:61], v[8:11], 0
	v_mfma_f32_16x16x32_bf16 v[218:221], v[136:139], v[4:7], 0
	v_mfma_f32_16x16x32_bf16 v[136:139], v[136:139], v[8:11], 0
	v_mfma_f32_16x16x32_bf16 v[4:7], v[222:225], v[4:7], 0
	v_mfma_f32_16x16x32_bf16 v[8:11], v[222:225], v[8:11], 0
	ds_read_b128 v[230:233], v204 offset:34880
	s_waitcnt vmcnt(2) lgkmcnt(0)
	v_mfma_f32_16x16x32_bf16 v[22:25], v[230:233], v[240:243], v[22:25]
	v_mfma_f32_16x16x32_bf16 v[18:21], v[230:233], v[244:247], v[18:21]
	ds_read_b128 v[230:233], v204 offset:39232
	s_waitcnt lgkmcnt(0)
	v_mfma_f32_16x16x32_bf16 v[30:33], v[230:233], v[240:243], v[30:33]
	v_mfma_f32_16x16x32_bf16 v[26:29], v[230:233], v[244:247], v[26:29]
	ds_read_b128 v[230:233], v204 offset:43584
	s_waitcnt lgkmcnt(0)
	v_mfma_f32_16x16x32_bf16 v[38:41], v[230:233], v[240:243], v[38:41]
	v_mfma_f32_16x16x32_bf16 v[34:37], v[230:233], v[244:247], v[34:37]
	ds_read_b128 v[230:233], v204 offset:47936
	s_waitcnt lgkmcnt(0)
	v_mfma_f32_16x16x32_bf16 v[46:49], v[230:233], v[240:243], v[46:49]
	v_mfma_f32_16x16x32_bf16 v[42:45], v[230:233], v[244:247], v[42:45]
	ds_read_b128 v[230:233], v204 offset:52288
	s_waitcnt lgkmcnt(0)
	v_mfma_f32_16x16x32_bf16 v[54:57], v[230:233], v[240:243], v[54:57]
	v_mfma_f32_16x16x32_bf16 v[50:53], v[230:233], v[244:247], v[50:53]
	ds_read_b128 v[230:233], v204 offset:56640
	s_waitcnt lgkmcnt(0)
	v_mfma_f32_16x16x32_bf16 v[62:65], v[230:233], v[240:243], v[62:65]
	v_mfma_f32_16x16x32_bf16 v[58:61], v[230:233], v[244:247], v[58:61]
	ds_read_b128 v[230:233], v204 offset:60992
	s_waitcnt lgkmcnt(0)
	v_mfma_f32_16x16x32_bf16 v[218:221], v[230:233], v[240:243], v[218:221]
	v_mfma_f32_16x16x32_bf16 v[136:139], v[230:233], v[244:247], v[136:139]
	ds_read_b128 v[230:233], v204 offset:65344
	s_waitcnt lgkmcnt(0)
	v_mfma_f32_16x16x32_bf16 v[4:7], v[230:233], v[240:243], v[4:7]
	v_mfma_f32_16x16x32_bf16 v[8:11], v[230:233], v[244:247], v[8:11]
	global_load_dwordx4 v[240:243], v[12:13], off offset:192
	global_load_dwordx4 v[244:247], v[14:15], off offset:192
	ds_read_b128 v[230:233], v204 offset:34944
	s_waitcnt vmcnt(2) lgkmcnt(0)
	v_mfma_f32_16x16x32_bf16 v[22:25], v[230:233], v[248:251], v[22:25]
	v_mfma_f32_16x16x32_bf16 v[18:21], v[230:233], v[252:255], v[18:21]
	ds_read_b128 v[230:233], v204 offset:39296
	s_waitcnt lgkmcnt(0)
	v_mfma_f32_16x16x32_bf16 v[30:33], v[230:233], v[248:251], v[30:33]
	v_mfma_f32_16x16x32_bf16 v[26:29], v[230:233], v[252:255], v[26:29]
	ds_read_b128 v[230:233], v204 offset:43648
	s_waitcnt lgkmcnt(0)
	v_mfma_f32_16x16x32_bf16 v[38:41], v[230:233], v[248:251], v[38:41]
	v_mfma_f32_16x16x32_bf16 v[34:37], v[230:233], v[252:255], v[34:37]
	ds_read_b128 v[230:233], v204 offset:48000
	s_waitcnt lgkmcnt(0)
	v_mfma_f32_16x16x32_bf16 v[46:49], v[230:233], v[248:251], v[46:49]
	v_mfma_f32_16x16x32_bf16 v[42:45], v[230:233], v[252:255], v[42:45]
	ds_read_b128 v[230:233], v204 offset:52352
	s_waitcnt lgkmcnt(0)
	v_mfma_f32_16x16x32_bf16 v[54:57], v[230:233], v[248:251], v[54:57]
	v_mfma_f32_16x16x32_bf16 v[50:53], v[230:233], v[252:255], v[50:53]
	ds_read_b128 v[230:233], v204 offset:56704
	s_waitcnt lgkmcnt(0)
	v_mfma_f32_16x16x32_bf16 v[62:65], v[230:233], v[248:251], v[62:65]
	v_mfma_f32_16x16x32_bf16 v[58:61], v[230:233], v[252:255], v[58:61]
	ds_read_b128 v[230:233], v204 offset:61056
	s_waitcnt lgkmcnt(0)
	v_mfma_f32_16x16x32_bf16 v[218:221], v[230:233], v[248:251], v[218:221]
	v_mfma_f32_16x16x32_bf16 v[136:139], v[230:233], v[252:255], v[136:139]
	ds_read_b128 v[230:233], v204 offset:65408
	s_waitcnt lgkmcnt(0)
	v_mfma_f32_16x16x32_bf16 v[4:7], v[230:233], v[248:251], v[4:7]
	s_nop 0
	v_mfma_f32_16x16x32_bf16 v[8:11], v[230:233], v[252:255], v[8:11]
	ds_read_b128 v[226:229], v204 offset:35008
	ds_read_b128 v[230:233], v204
	s_waitcnt vmcnt(0) lgkmcnt(0)
	v_mfma_f32_16x16x32_bf16 v[22:25], v[226:229], v[240:243], v[22:25]
	v_mfma_f32_16x16x32_bf16 v[18:21], v[226:229], v[244:247], v[18:21]
	ds_read_b128 v[226:229], v204 offset:39360
	s_waitcnt lgkmcnt(0)
	v_mfma_f32_16x16x32_bf16 v[30:33], v[226:229], v[240:243], v[30:33]
	v_mfma_f32_16x16x32_bf16 v[26:29], v[226:229], v[244:247], v[26:29]
	ds_read_b128 v[226:229], v204 offset:43712
	s_waitcnt lgkmcnt(0)
	v_mfma_f32_16x16x32_bf16 v[38:41], v[226:229], v[240:243], v[38:41]
	v_mfma_f32_16x16x32_bf16 v[34:37], v[226:229], v[244:247], v[34:37]
	ds_read_b128 v[226:229], v204 offset:48064
	s_waitcnt lgkmcnt(0)
	v_mfma_f32_16x16x32_bf16 v[46:49], v[226:229], v[240:243], v[46:49]
	v_mfma_f32_16x16x32_bf16 v[42:45], v[226:229], v[244:247], v[42:45]
	ds_read_b128 v[226:229], v204 offset:52416
	s_waitcnt lgkmcnt(0)
	v_mfma_f32_16x16x32_bf16 v[54:57], v[226:229], v[240:243], v[54:57]
	v_mfma_f32_16x16x32_bf16 v[50:53], v[226:229], v[244:247], v[50:53]
	ds_read_b128 v[226:229], v204 offset:56768
	s_waitcnt lgkmcnt(0)
	v_mfma_f32_16x16x32_bf16 v[62:65], v[226:229], v[240:243], v[62:65]
	v_mfma_f32_16x16x32_bf16 v[58:61], v[226:229], v[244:247], v[58:61]
	ds_read_b128 v[226:229], v204 offset:61120
	s_waitcnt lgkmcnt(0)
	v_mfma_f32_16x16x32_bf16 v[218:221], v[226:229], v[240:243], v[218:221]
	v_mfma_f32_16x16x32_bf16 v[136:139], v[226:229], v[244:247], v[136:139]
	ds_read_b128 v[226:229], v204 offset:65472
	s_waitcnt lgkmcnt(0)
	v_mfma_f32_16x16x32_bf16 v[222:225], v[226:229], v[240:243], v[4:7]
	s_nop 2
	v_or_b32_e32 v4, v16, v73
	v_lshlrev_b32_e32 v68, 8, v4
	v_add_co_u32_e32 v6, vcc, v0, v68
	v_addc_co_u32_e32 v7, vcc, v1, v69, vcc
	v_add_co_u32_e32 v4, vcc, s37, v6
	v_mfma_f32_16x16x32_bf16 v[8:11], v[226:229], v[244:247], v[8:11]
	s_nop 0
	v_addc_co_u32_e32 v5, vcc, 0, v7, vcc
	global_load_dwordx4 v[12:15], v[6:7], off
	global_load_dwordx4 v[226:229], v[4:5], off
	global_load_dwordx4 v[240:243], v[6:7], off offset:64
	global_load_dwordx4 v[244:247], v[4:5], off offset:64
	global_load_dwordx4 v[248:251], v[6:7], off offset:128
	global_load_dwordx4 v[252:255], v[4:5], off offset:128
	s_waitcnt vmcnt(4) lgkmcnt(0)
	v_mfma_f32_16x16x32_bf16 v[22:25], v[230:233], v[12:15], v[22:25]
	v_mfma_f32_16x16x32_bf16 v[16:19], v[230:233], v[226:229], v[18:21]
	ds_read_b128 v[230:233], v204 offset:4352
	s_waitcnt lgkmcnt(0)
	v_mfma_f32_16x16x32_bf16 v[30:33], v[230:233], v[12:15], v[30:33]
	v_mfma_f32_16x16x32_bf16 v[26:29], v[230:233], v[226:229], v[26:29]
	ds_read_b128 v[230:233], v204 offset:8704
	s_waitcnt lgkmcnt(0)
	v_mfma_f32_16x16x32_bf16 v[38:41], v[230:233], v[12:15], v[38:41]
	v_mfma_f32_16x16x32_bf16 v[34:37], v[230:233], v[226:229], v[34:37]
	ds_read_b128 v[230:233], v204 offset:13056
	s_waitcnt lgkmcnt(0)
	v_mfma_f32_16x16x32_bf16 v[46:49], v[230:233], v[12:15], v[46:49]
	v_mfma_f32_16x16x32_bf16 v[42:45], v[230:233], v[226:229], v[42:45]
	ds_read_b128 v[230:233], v204 offset:17408
	s_waitcnt lgkmcnt(0)
	v_mfma_f32_16x16x32_bf16 v[54:57], v[230:233], v[12:15], v[54:57]
	v_mfma_f32_16x16x32_bf16 v[50:53], v[230:233], v[226:229], v[50:53]
	ds_read_b128 v[230:233], v204 offset:21760
	s_waitcnt lgkmcnt(0)
	v_mfma_f32_16x16x32_bf16 v[62:65], v[230:233], v[12:15], v[62:65]
	v_mfma_f32_16x16x32_bf16 v[58:61], v[230:233], v[226:229], v[58:61]
	ds_read_b128 v[230:233], v204 offset:26112
	s_waitcnt lgkmcnt(0)
	v_mfma_f32_16x16x32_bf16 v[218:221], v[230:233], v[12:15], v[218:221]
	v_mfma_f32_16x16x32_bf16 v[136:139], v[230:233], v[226:229], v[136:139]
	ds_read_b128 v[230:233], v204 offset:30464
	s_waitcnt lgkmcnt(0)
	v_mfma_f32_16x16x32_bf16 v[12:15], v[230:233], v[12:15], v[222:225]
	v_mfma_f32_16x16x32_bf16 v[8:11], v[230:233], v[226:229], v[8:11]
	s_nop 1
	ds_read_b128 v[230:233], v204 offset:64
	s_waitcnt vmcnt(2) lgkmcnt(0)
	v_mfma_f32_16x16x32_bf16 v[20:23], v[230:233], v[240:243], v[22:25]
	v_mfma_f32_16x16x32_bf16 v[16:19], v[230:233], v[244:247], v[16:19]
	ds_read_b128 v[230:233], v204 offset:4416
	s_waitcnt lgkmcnt(0)
	v_mfma_f32_16x16x32_bf16 v[30:33], v[230:233], v[240:243], v[30:33]
	v_mfma_f32_16x16x32_bf16 v[24:27], v[230:233], v[244:247], v[26:29]
	ds_read_b128 v[230:233], v204 offset:8768
	s_waitcnt lgkmcnt(0)
	v_mfma_f32_16x16x32_bf16 v[38:41], v[230:233], v[240:243], v[38:41]
	v_mfma_f32_16x16x32_bf16 v[34:37], v[230:233], v[244:247], v[34:37]
	ds_read_b128 v[230:233], v204 offset:13120
	s_waitcnt lgkmcnt(0)
	v_mfma_f32_16x16x32_bf16 v[46:49], v[230:233], v[240:243], v[46:49]
	v_mfma_f32_16x16x32_bf16 v[42:45], v[230:233], v[244:247], v[42:45]
	ds_read_b128 v[230:233], v204 offset:17472
	s_waitcnt lgkmcnt(0)
	v_mfma_f32_16x16x32_bf16 v[54:57], v[230:233], v[240:243], v[54:57]
	v_mfma_f32_16x16x32_bf16 v[50:53], v[230:233], v[244:247], v[50:53]
	ds_read_b128 v[230:233], v204 offset:21824
	s_waitcnt lgkmcnt(0)
	v_mfma_f32_16x16x32_bf16 v[62:65], v[230:233], v[240:243], v[62:65]
	v_mfma_f32_16x16x32_bf16 v[58:61], v[230:233], v[244:247], v[58:61]
	ds_read_b128 v[230:233], v204 offset:26176
	s_waitcnt lgkmcnt(0)
	v_mfma_f32_16x16x32_bf16 v[218:221], v[230:233], v[240:243], v[218:221]
	v_mfma_f32_16x16x32_bf16 v[136:139], v[230:233], v[244:247], v[136:139]
	ds_read_b128 v[230:233], v204 offset:30528
	s_waitcnt lgkmcnt(0)
	v_mfma_f32_16x16x32_bf16 v[12:15], v[230:233], v[240:243], v[12:15]
	v_mfma_f32_16x16x32_bf16 v[8:11], v[230:233], v[244:247], v[8:11]
	global_load_dwordx4 v[240:243], v[6:7], off offset:192
	global_load_dwordx4 v[244:247], v[4:5], off offset:192
	ds_read_b128 v[230:233], v204 offset:128
	s_waitcnt vmcnt(2) lgkmcnt(0)
	v_mfma_f32_16x16x32_bf16 v[20:23], v[230:233], v[248:251], v[20:23]
	v_mfma_f32_16x16x32_bf16 v[16:19], v[230:233], v[252:255], v[16:19]
	ds_read_b128 v[230:233], v204 offset:4480
	s_waitcnt lgkmcnt(0)
	v_mfma_f32_16x16x32_bf16 v[28:31], v[230:233], v[248:251], v[30:33]
	v_mfma_f32_16x16x32_bf16 v[24:27], v[230:233], v[252:255], v[24:27]
	ds_read_b128 v[230:233], v204 offset:8832
	s_waitcnt lgkmcnt(0)
	v_mfma_f32_16x16x32_bf16 v[38:41], v[230:233], v[248:251], v[38:41]
	v_mfma_f32_16x16x32_bf16 v[32:35], v[230:233], v[252:255], v[34:37]
	ds_read_b128 v[230:233], v204 offset:13184
	s_waitcnt lgkmcnt(0)
	v_mfma_f32_16x16x32_bf16 v[46:49], v[230:233], v[248:251], v[46:49]
	v_mfma_f32_16x16x32_bf16 v[42:45], v[230:233], v[252:255], v[42:45]
	ds_read_b128 v[230:233], v204 offset:17536
	s_waitcnt lgkmcnt(0)
	v_mfma_f32_16x16x32_bf16 v[54:57], v[230:233], v[248:251], v[54:57]
	v_mfma_f32_16x16x32_bf16 v[50:53], v[230:233], v[252:255], v[50:53]
	ds_read_b128 v[230:233], v204 offset:21888
	s_waitcnt lgkmcnt(0)
	v_mfma_f32_16x16x32_bf16 v[62:65], v[230:233], v[248:251], v[62:65]
	v_mfma_f32_16x16x32_bf16 v[58:61], v[230:233], v[252:255], v[58:61]
	ds_read_b128 v[230:233], v204 offset:26240
	s_waitcnt lgkmcnt(0)
	v_mfma_f32_16x16x32_bf16 v[218:221], v[230:233], v[248:251], v[218:221]
	v_mfma_f32_16x16x32_bf16 v[136:139], v[230:233], v[252:255], v[136:139]
	ds_read_b128 v[230:233], v204 offset:30592
	s_waitcnt lgkmcnt(0)
	v_mfma_f32_16x16x32_bf16 v[222:225], v[230:233], v[248:251], v[12:15]
	v_mfma_f32_16x16x32_bf16 v[226:229], v[230:233], v[252:255], v[8:11]
	s_nop 0
	ds_read_b128 v[8:11], v204 offset:192
	s_waitcnt vmcnt(0) lgkmcnt(0)
	v_mfma_f32_16x16x32_bf16 v[4:7], v[8:11], v[240:243], v[20:23]
	v_mfma_f32_16x16x32_bf16 v[8:11], v[8:11], v[244:247], v[16:19]
	s_nop 2
	ds_read_b128 v[16:19], v204 offset:4544
	s_waitcnt lgkmcnt(0)
	v_mfma_f32_16x16x32_bf16 v[12:15], v[16:19], v[240:243], v[28:31]
	v_mfma_f32_16x16x32_bf16 v[16:19], v[16:19], v[244:247], v[24:27]
	s_nop 2
	ds_read_b128 v[24:27], v204 offset:8896
	s_waitcnt lgkmcnt(0)
	v_mfma_f32_16x16x32_bf16 v[20:23], v[24:27], v[240:243], v[38:41]
	v_mfma_f32_16x16x32_bf16 v[24:27], v[24:27], v[244:247], v[32:35]
	s_nop 2
	ds_read_b128 v[32:35], v204 offset:13248
	s_waitcnt lgkmcnt(0)
	v_mfma_f32_16x16x32_bf16 v[28:31], v[32:35], v[240:243], v[46:49]
	v_mfma_f32_16x16x32_bf16 v[32:35], v[32:35], v[244:247], v[42:45]
	s_nop 2
	ds_read_b128 v[40:43], v204 offset:17600
	s_waitcnt lgkmcnt(0)
	v_mfma_f32_16x16x32_bf16 v[36:39], v[40:43], v[240:243], v[54:57]
	v_mfma_f32_16x16x32_bf16 v[40:43], v[40:43], v[244:247], v[50:53]
	s_nop 2
	ds_read_b128 v[48:51], v204 offset:21952
	s_waitcnt lgkmcnt(0)
	v_mfma_f32_16x16x32_bf16 v[44:47], v[48:51], v[240:243], v[62:65]
	s_nop 2
	ds_read_b128 v[64:67], v204 offset:30656
	v_mfma_f32_16x16x32_bf16 v[48:51], v[48:51], v[244:247], v[58:61]
	s_nop 2
	ds_read_b128 v[56:59], v204 offset:26304
	s_waitcnt lgkmcnt(0)
	v_mfma_f32_16x16x32_bf16 v[52:55], v[56:59], v[240:243], v[218:221]
	s_barrier
	v_mfma_f32_16x16x32_bf16 v[56:59], v[56:59], v[244:247], v[136:139]
	s_nop 2
	ds_read_b128 v[136:139], v85
	ds_read_b32 v91, v180
	ds_read_b32 v93, v181 offset:4
	s_waitcnt lgkmcnt(2)
	v_lshlrev_b32_e32 v220, 16, v136
	v_and_b32_e32 v221, 0xffff0000, v136
	s_waitcnt lgkmcnt(0)
	v_mul_f32_e32 v218, v91, v93
	v_pk_mul_f32 v[220:221], v[218:219], v[220:221] op_sel_hi:[0,1]
	v_cvt_pk_bf16_f32 v136, v220, v221
	v_lshlrev_b32_e32 v220, 16, v137
	v_and_b32_e32 v221, 0xffff0000, v137
	v_pk_mul_f32 v[220:221], v[218:219], v[220:221] op_sel_hi:[0,1]
	v_cvt_pk_bf16_f32 v137, v220, v221
	v_lshlrev_b32_e32 v220, 16, v138
	v_and_b32_e32 v221, 0xffff0000, v138
	v_pk_mul_f32 v[220:221], v[218:219], v[220:221] op_sel_hi:[0,1]
	v_cvt_pk_bf16_f32 v138, v220, v221
	v_lshlrev_b32_e32 v220, 16, v139
	v_and_b32_e32 v221, 0xffff0000, v139
	v_pk_mul_f32 v[218:219], v[218:219], v[220:221] op_sel_hi:[0,1]
	v_cvt_pk_bf16_f32 v139, v218, v219
	ds_write_b128 v85, v[136:139]
	ds_read_b128 v[136:139], v85 offset:4352
	ds_read_b32 v91, v182
	ds_read_b32 v93, v183 offset:4
	v_mfma_f32_16x16x32_bf16 v[60:63], v[64:67], v[240:243], v[222:225]
	s_waitcnt lgkmcnt(2)
	v_lshlrev_b32_e32 v220, 16, v136
	v_and_b32_e32 v221, 0xffff0000, v136
	s_waitcnt lgkmcnt(0)
	v_mul_f32_e32 v218, v91, v93
	v_pk_mul_f32 v[220:221], v[218:219], v[220:221] op_sel_hi:[0,1]
	v_cvt_pk_bf16_f32 v136, v220, v221
	v_lshlrev_b32_e32 v220, 16, v137
	v_and_b32_e32 v221, 0xffff0000, v137
	v_pk_mul_f32 v[220:221], v[218:219], v[220:221] op_sel_hi:[0,1]
	v_cvt_pk_bf16_f32 v137, v220, v221
	v_lshlrev_b32_e32 v220, 16, v138
	v_and_b32_e32 v221, 0xffff0000, v138
	v_pk_mul_f32 v[220:221], v[218:219], v[220:221] op_sel_hi:[0,1]
	v_cvt_pk_bf16_f32 v138, v220, v221
	v_lshlrev_b32_e32 v220, 16, v139
	v_and_b32_e32 v221, 0xffff0000, v139
	v_pk_mul_f32 v[218:219], v[218:219], v[220:221] op_sel_hi:[0,1]
	v_cvt_pk_bf16_f32 v139, v218, v219
	ds_write_b128 v85, v[136:139] offset:4352
	ds_read_b128 v[136:139], v85 offset:8704
	ds_read_b32 v91, v184
	ds_read_b32 v93, v185 offset:4
	v_mfma_f32_16x16x32_bf16 v[64:67], v[64:67], v[244:247], v[226:229]
	s_waitcnt lgkmcnt(2)
	v_lshlrev_b32_e32 v220, 16, v136
	v_and_b32_e32 v221, 0xffff0000, v136
	s_waitcnt lgkmcnt(0)
	v_mul_f32_e32 v218, v91, v93
	v_pk_mul_f32 v[220:221], v[218:219], v[220:221] op_sel_hi:[0,1]
	v_cvt_pk_bf16_f32 v136, v220, v221
	v_lshlrev_b32_e32 v220, 16, v137
	v_and_b32_e32 v221, 0xffff0000, v137
	v_pk_mul_f32 v[220:221], v[218:219], v[220:221] op_sel_hi:[0,1]
	v_cvt_pk_bf16_f32 v137, v220, v221
	v_lshlrev_b32_e32 v220, 16, v138
	v_and_b32_e32 v221, 0xffff0000, v138
	v_pk_mul_f32 v[220:221], v[218:219], v[220:221] op_sel_hi:[0,1]
	v_cvt_pk_bf16_f32 v138, v220, v221
	v_lshlrev_b32_e32 v220, 16, v139
	v_and_b32_e32 v221, 0xffff0000, v139
	v_pk_mul_f32 v[218:219], v[218:219], v[220:221] op_sel_hi:[0,1]
	v_cvt_pk_bf16_f32 v139, v218, v219
	ds_write_b128 v85, v[136:139] offset:8704
	ds_read_b128 v[136:139], v85 offset:13056
	ds_read_b32 v91, v186
	ds_read_b32 v93, v187 offset:4
	s_waitcnt lgkmcnt(2)
	v_lshlrev_b32_e32 v220, 16, v136
	v_and_b32_e32 v221, 0xffff0000, v136
	s_waitcnt lgkmcnt(0)
	v_mul_f32_e32 v218, v91, v93
	v_pk_mul_f32 v[220:221], v[218:219], v[220:221] op_sel_hi:[0,1]
	v_cvt_pk_bf16_f32 v136, v220, v221
	v_lshlrev_b32_e32 v220, 16, v137
	v_and_b32_e32 v221, 0xffff0000, v137
	v_pk_mul_f32 v[220:221], v[218:219], v[220:221] op_sel_hi:[0,1]
	v_cvt_pk_bf16_f32 v137, v220, v221
	v_lshlrev_b32_e32 v220, 16, v138
	v_and_b32_e32 v221, 0xffff0000, v138
	v_pk_mul_f32 v[220:221], v[218:219], v[220:221] op_sel_hi:[0,1]
	v_cvt_pk_bf16_f32 v138, v220, v221
	v_lshlrev_b32_e32 v220, 16, v139
	v_and_b32_e32 v221, 0xffff0000, v139
	v_pk_mul_f32 v[218:219], v[218:219], v[220:221] op_sel_hi:[0,1]
	v_cvt_pk_bf16_f32 v139, v218, v219
	ds_write_b128 v85, v[136:139] offset:13056
	ds_read_b128 v[136:139], v85 offset:17408
	ds_read_b32 v91, v188
	ds_read_b32 v93, v189 offset:4
	s_waitcnt lgkmcnt(2)
	v_lshlrev_b32_e32 v220, 16, v136
	v_and_b32_e32 v221, 0xffff0000, v136
	s_waitcnt lgkmcnt(0)
	v_mul_f32_e32 v218, v91, v93
	v_pk_mul_f32 v[220:221], v[218:219], v[220:221] op_sel_hi:[0,1]
	v_cvt_pk_bf16_f32 v136, v220, v221
	v_lshlrev_b32_e32 v220, 16, v137
	v_and_b32_e32 v221, 0xffff0000, v137
	v_pk_mul_f32 v[220:221], v[218:219], v[220:221] op_sel_hi:[0,1]
	v_cvt_pk_bf16_f32 v137, v220, v221
	v_lshlrev_b32_e32 v220, 16, v138
	v_and_b32_e32 v221, 0xffff0000, v138
	v_pk_mul_f32 v[220:221], v[218:219], v[220:221] op_sel_hi:[0,1]
	v_cvt_pk_bf16_f32 v138, v220, v221
	v_lshlrev_b32_e32 v220, 16, v139
	v_and_b32_e32 v221, 0xffff0000, v139
	v_pk_mul_f32 v[218:219], v[218:219], v[220:221] op_sel_hi:[0,1]
	v_cvt_pk_bf16_f32 v139, v218, v219
	ds_write_b128 v85, v[136:139] offset:17408
	ds_read_b128 v[136:139], v85 offset:21760
	ds_read_b32 v91, v190
	ds_read_b32 v93, v191 offset:4
	s_waitcnt lgkmcnt(2)
	v_lshlrev_b32_e32 v220, 16, v136
	v_and_b32_e32 v221, 0xffff0000, v136
	s_waitcnt lgkmcnt(0)
	v_mul_f32_e32 v218, v91, v93
	v_pk_mul_f32 v[220:221], v[218:219], v[220:221] op_sel_hi:[0,1]
	v_cvt_pk_bf16_f32 v136, v220, v221
	v_lshlrev_b32_e32 v220, 16, v137
	v_and_b32_e32 v221, 0xffff0000, v137
	v_pk_mul_f32 v[220:221], v[218:219], v[220:221] op_sel_hi:[0,1]
	v_cvt_pk_bf16_f32 v137, v220, v221
	v_lshlrev_b32_e32 v220, 16, v138
	v_and_b32_e32 v221, 0xffff0000, v138
	v_pk_mul_f32 v[220:221], v[218:219], v[220:221] op_sel_hi:[0,1]
	v_cvt_pk_bf16_f32 v138, v220, v221
	v_lshlrev_b32_e32 v220, 16, v139
	v_and_b32_e32 v221, 0xffff0000, v139
	v_pk_mul_f32 v[218:219], v[218:219], v[220:221] op_sel_hi:[0,1]
	v_cvt_pk_bf16_f32 v139, v218, v219
	ds_write_b128 v85, v[136:139] offset:21760
	ds_read_b128 v[136:139], v85 offset:26112
	ds_read_b32 v91, v192
	ds_read_b32 v93, v193 offset:4
	s_waitcnt lgkmcnt(2)
	v_lshlrev_b32_e32 v220, 16, v136
	v_and_b32_e32 v221, 0xffff0000, v136
	s_waitcnt lgkmcnt(0)
	v_mul_f32_e32 v218, v91, v93
	v_pk_mul_f32 v[220:221], v[218:219], v[220:221] op_sel_hi:[0,1]
	v_cvt_pk_bf16_f32 v136, v220, v221
	v_lshlrev_b32_e32 v220, 16, v137
	v_and_b32_e32 v221, 0xffff0000, v137
	v_pk_mul_f32 v[220:221], v[218:219], v[220:221] op_sel_hi:[0,1]
	v_cvt_pk_bf16_f32 v137, v220, v221
	v_lshlrev_b32_e32 v220, 16, v138
	v_and_b32_e32 v221, 0xffff0000, v138
	v_pk_mul_f32 v[220:221], v[218:219], v[220:221] op_sel_hi:[0,1]
	v_cvt_pk_bf16_f32 v138, v220, v221
	v_lshlrev_b32_e32 v220, 16, v139
	v_and_b32_e32 v221, 0xffff0000, v139
	v_pk_mul_f32 v[218:219], v[218:219], v[220:221] op_sel_hi:[0,1]
	v_cvt_pk_bf16_f32 v139, v218, v219
	ds_write_b128 v85, v[136:139] offset:26112
	ds_read_b128 v[136:139], v85 offset:30464
	ds_read_b32 v91, v194
	ds_read_b32 v93, v195 offset:4
	s_waitcnt lgkmcnt(2)
	v_lshlrev_b32_e32 v220, 16, v136
	v_and_b32_e32 v221, 0xffff0000, v136
	s_waitcnt lgkmcnt(0)
	v_mul_f32_e32 v218, v91, v93
	v_pk_mul_f32 v[220:221], v[218:219], v[220:221] op_sel_hi:[0,1]
	v_cvt_pk_bf16_f32 v136, v220, v221
	v_lshlrev_b32_e32 v220, 16, v137
	v_and_b32_e32 v221, 0xffff0000, v137
	v_pk_mul_f32 v[220:221], v[218:219], v[220:221] op_sel_hi:[0,1]
	v_cvt_pk_bf16_f32 v137, v220, v221
	v_lshlrev_b32_e32 v220, 16, v138
	v_and_b32_e32 v221, 0xffff0000, v138
	v_pk_mul_f32 v[220:221], v[218:219], v[220:221] op_sel_hi:[0,1]
	v_cvt_pk_bf16_f32 v138, v220, v221
	v_lshlrev_b32_e32 v220, 16, v139
	v_and_b32_e32 v221, 0xffff0000, v139
	v_pk_mul_f32 v[218:219], v[218:219], v[220:221] op_sel_hi:[0,1]
	v_cvt_pk_bf16_f32 v139, v218, v219
	ds_write_b128 v85, v[136:139] offset:30464
	v_add_co_u32_e32 v138, vcc, v114, v68
	v_addc_co_u32_e32 v139, vcc, v115, v69, vcc
	v_add_co_u32_e32 v136, vcc, s37, v138
	s_waitcnt lgkmcnt(0)
	s_nop 0
	v_addc_co_u32_e32 v137, vcc, 0, v139, vcc
	s_barrier
	global_load_dwordx4 v[218:221], v[138:139], off
	global_load_dwordx4 v[222:225], v[136:137], off
	global_load_dwordx4 v[240:243], v[138:139], off offset:64
	global_load_dwordx4 v[244:247], v[136:137], off offset:64
	global_load_dwordx4 v[248:251], v[138:139], off offset:128
	global_load_dwordx4 v[252:255], v[136:137], off offset:128
	ds_read_b128 v[226:229], v204
	s_waitcnt vmcnt(4) lgkmcnt(0)
	v_mfma_f32_16x16x32_bf16 v[4:7], v[226:229], v[218:221], v[4:7]
	s_and_b64 vcc, exec, s[20:21]
	v_mfma_f32_16x16x32_bf16 v[8:11], v[226:229], v[222:225], v[8:11]
	ds_read_b128 v[226:229], v204 offset:4352
	s_waitcnt lgkmcnt(0)
	v_mfma_f32_16x16x32_bf16 v[12:15], v[226:229], v[218:221], v[12:15]
	v_mfma_f32_16x16x32_bf16 v[16:19], v[226:229], v[222:225], v[16:19]
	ds_read_b128 v[226:229], v204 offset:8704
	s_waitcnt lgkmcnt(0)
	v_mfma_f32_16x16x32_bf16 v[20:23], v[226:229], v[218:221], v[20:23]
	v_mfma_f32_16x16x32_bf16 v[24:27], v[226:229], v[222:225], v[24:27]
	ds_read_b128 v[226:229], v204 offset:13056
	s_waitcnt lgkmcnt(0)
	v_mfma_f32_16x16x32_bf16 v[28:31], v[226:229], v[218:221], v[28:31]
	v_mfma_f32_16x16x32_bf16 v[32:35], v[226:229], v[222:225], v[32:35]
	ds_read_b128 v[226:229], v204 offset:17408
	s_waitcnt lgkmcnt(0)
	v_mfma_f32_16x16x32_bf16 v[36:39], v[226:229], v[218:221], v[36:39]
	v_mfma_f32_16x16x32_bf16 v[40:43], v[226:229], v[222:225], v[40:43]
	ds_read_b128 v[226:229], v204 offset:21760
	s_waitcnt lgkmcnt(0)
	v_mfma_f32_16x16x32_bf16 v[44:47], v[226:229], v[218:221], v[44:47]
	v_mfma_f32_16x16x32_bf16 v[48:51], v[226:229], v[222:225], v[48:51]
	ds_read_b128 v[226:229], v204 offset:26112
	s_waitcnt lgkmcnt(0)
	v_mfma_f32_16x16x32_bf16 v[52:55], v[226:229], v[218:221], v[52:55]
	v_mfma_f32_16x16x32_bf16 v[56:59], v[226:229], v[222:225], v[56:59]
	ds_read_b128 v[226:229], v204 offset:30464
	s_waitcnt lgkmcnt(0)
	v_mfma_f32_16x16x32_bf16 v[60:63], v[226:229], v[218:221], v[60:63]
	v_mfma_f32_16x16x32_bf16 v[64:67], v[226:229], v[222:225], v[64:67]
	ds_read_b128 v[226:229], v204 offset:64
	s_waitcnt vmcnt(2) lgkmcnt(0)
	v_mfma_f32_16x16x32_bf16 v[4:7], v[226:229], v[240:243], v[4:7]
	v_mfma_f32_16x16x32_bf16 v[8:11], v[226:229], v[244:247], v[8:11]
	ds_read_b128 v[226:229], v204 offset:4416
	s_waitcnt lgkmcnt(0)
	v_mfma_f32_16x16x32_bf16 v[12:15], v[226:229], v[240:243], v[12:15]
	v_mfma_f32_16x16x32_bf16 v[16:19], v[226:229], v[244:247], v[16:19]
	ds_read_b128 v[226:229], v204 offset:8768
	s_waitcnt lgkmcnt(0)
	v_mfma_f32_16x16x32_bf16 v[20:23], v[226:229], v[240:243], v[20:23]
	v_mfma_f32_16x16x32_bf16 v[24:27], v[226:229], v[244:247], v[24:27]
	ds_read_b128 v[226:229], v204 offset:13120
	s_waitcnt lgkmcnt(0)
	v_mfma_f32_16x16x32_bf16 v[28:31], v[226:229], v[240:243], v[28:31]
	v_mfma_f32_16x16x32_bf16 v[32:35], v[226:229], v[244:247], v[32:35]
	ds_read_b128 v[226:229], v204 offset:17472
	s_waitcnt lgkmcnt(0)
	v_mfma_f32_16x16x32_bf16 v[36:39], v[226:229], v[240:243], v[36:39]
	v_mfma_f32_16x16x32_bf16 v[40:43], v[226:229], v[244:247], v[40:43]
	ds_read_b128 v[226:229], v204 offset:21824
	s_waitcnt lgkmcnt(0)
	v_mfma_f32_16x16x32_bf16 v[44:47], v[226:229], v[240:243], v[44:47]
	v_mfma_f32_16x16x32_bf16 v[48:51], v[226:229], v[244:247], v[48:51]
	ds_read_b128 v[226:229], v204 offset:26176
	s_waitcnt lgkmcnt(0)
	v_mfma_f32_16x16x32_bf16 v[52:55], v[226:229], v[240:243], v[52:55]
	v_mfma_f32_16x16x32_bf16 v[56:59], v[226:229], v[244:247], v[56:59]
	ds_read_b128 v[226:229], v204 offset:30528
	s_waitcnt lgkmcnt(0)
	v_mfma_f32_16x16x32_bf16 v[60:63], v[226:229], v[240:243], v[60:63]
	v_mfma_f32_16x16x32_bf16 v[64:67], v[226:229], v[244:247], v[64:67]
	global_load_dwordx4 v[240:243], v[138:139], off offset:192
	global_load_dwordx4 v[244:247], v[136:137], off offset:192
	ds_read_b128 v[226:229], v204 offset:128
	s_waitcnt vmcnt(2) lgkmcnt(0)
	v_mfma_f32_16x16x32_bf16 v[230:233], v[226:229], v[248:251], v[4:7]
	s_nop 2
	ds_read_b128 v[4:7], v204 offset:4480
	s_waitcnt lgkmcnt(0)
	v_mfma_f32_16x16x32_bf16 v[12:15], v[4:7], v[248:251], v[12:15]
	v_mfma_f32_16x16x32_bf16 v[16:19], v[4:7], v[252:255], v[16:19]
	ds_read_b128 v[4:7], v204 offset:8832
	v_mfma_f32_16x16x32_bf16 v[8:11], v[226:229], v[252:255], v[8:11]
	s_waitcnt lgkmcnt(0)
	v_mfma_f32_16x16x32_bf16 v[20:23], v[4:7], v[248:251], v[20:23]
	v_mfma_f32_16x16x32_bf16 v[226:229], v[4:7], v[252:255], v[24:27]
	ds_read_b128 v[4:7], v204 offset:13184
	s_waitcnt lgkmcnt(0)
	v_mfma_f32_16x16x32_bf16 v[28:31], v[4:7], v[248:251], v[28:31]
	ds_read_b128 v[24:27], v204 offset:30592
	v_mfma_f32_16x16x32_bf16 v[32:35], v[4:7], v[252:255], v[32:35]
	ds_read_b128 v[4:7], v204 offset:17536
	s_waitcnt lgkmcnt(0)
	v_mfma_f32_16x16x32_bf16 v[36:39], v[4:7], v[248:251], v[36:39]
	v_mfma_f32_16x16x32_bf16 v[40:43], v[4:7], v[252:255], v[40:43]
	ds_read_b128 v[4:7], v204 offset:21888
	s_waitcnt lgkmcnt(0)
	v_mfma_f32_16x16x32_bf16 v[44:47], v[4:7], v[248:251], v[44:47]
	v_mfma_f32_16x16x32_bf16 v[48:51], v[4:7], v[252:255], v[48:51]
	ds_read_b128 v[4:7], v204 offset:26240
	s_waitcnt lgkmcnt(0)
	v_mfma_f32_16x16x32_bf16 v[52:55], v[4:7], v[248:251], v[52:55]
	v_mfma_f32_16x16x32_bf16 v[56:59], v[4:7], v[252:255], v[56:59]
	v_mfma_f32_16x16x32_bf16 v[4:7], v[24:27], v[248:251], v[60:63]
	v_mfma_f32_16x16x32_bf16 v[24:27], v[24:27], v[252:255], v[64:67]
	s_nop 1
	ds_read_b128 v[136:139], v204 offset:192
	s_waitcnt vmcnt(0) lgkmcnt(0)
	v_mfma_f32_16x16x32_bf16 v[218:221], v[136:139], v[240:243], v[230:233]
	v_mfma_f32_16x16x32_bf16 v[136:139], v[136:139], v[244:247], v[8:11]
	s_nop 2
	ds_read_b128 v[8:11], v204 offset:4544
	s_waitcnt lgkmcnt(0)
	v_mfma_f32_16x16x32_bf16 v[222:225], v[8:11], v[240:243], v[12:15]
	v_mfma_f32_16x16x32_bf16 v[230:233], v[8:11], v[244:247], v[16:19]
	ds_read_b128 v[8:11], v204 offset:8896
	s_waitcnt lgkmcnt(0)
	v_mfma_f32_16x16x32_bf16 v[234:237], v[8:11], v[240:243], v[20:23]
	v_mfma_f32_16x16x32_bf16 v[226:229], v[8:11], v[244:247], v[226:229]
	ds_read_b128 v[8:11], v204 offset:13248
	s_waitcnt lgkmcnt(0)
	v_mfma_f32_16x16x32_bf16 v[28:31], v[8:11], v[240:243], v[28:31]
	v_mfma_f32_16x16x32_bf16 v[32:35], v[8:11], v[244:247], v[32:35]
	ds_read_b128 v[8:11], v204 offset:17600
	s_waitcnt lgkmcnt(0)
	v_mfma_f32_16x16x32_bf16 v[36:39], v[8:11], v[240:243], v[36:39]
	v_mfma_f32_16x16x32_bf16 v[40:43], v[8:11], v[244:247], v[40:43]
	ds_read_b128 v[8:11], v204 offset:21952
	s_waitcnt lgkmcnt(0)
	v_mfma_f32_16x16x32_bf16 v[44:47], v[8:11], v[240:243], v[44:47]
	v_mfma_f32_16x16x32_bf16 v[20:23], v[8:11], v[244:247], v[48:51]
	ds_read_b128 v[8:11], v204 offset:26304
	s_nop 1
	ds_read_b128 v[48:51], v204 offset:30656
	s_waitcnt lgkmcnt(1)
	v_mfma_f32_16x16x32_bf16 v[16:19], v[8:11], v[240:243], v[52:55]
	s_waitcnt lgkmcnt(0)
	s_barrier
	v_mfma_f32_16x16x32_bf16 v[12:15], v[8:11], v[244:247], v[56:59]
	v_cvt_pk_bf16_f32 v20, v20, s0
	s_nop 3
	v_cvt_pk_bf16_f32 v16, v16, s0
	ds_write_b16 v205, v20 offset:21792
	v_mfma_f32_16x16x32_bf16 v[8:11], v[48:51], v[240:243], v[4:7]
	v_cvt_pk_bf16_f32 v20, v21, s0
	v_cvt_pk_bf16_f32 v12, v12, s0
	ds_write_b16 v205, v16 offset:26112
	v_mfma_f32_16x16x32_bf16 v[4:7], v[48:51], v[244:247], v[24:27]
	v_cvt_pk_bf16_f32 v16, v17, s0
	s_nop 2
	v_cvt_pk_bf16_f32 v8, v8, s0
	ds_write_b16 v205, v12 offset:26144
	v_cvt_pk_bf16_f32 v24, v218, s0
	ds_write_b16 v205, v24
	v_cvt_pk_bf16_f32 v24, v219, s0
	ds_write_b16 v205, v24 offset:272
	v_cvt_pk_bf16_f32 v24, v220, s0
	ds_write_b16 v205, v24 offset:544
	v_cvt_pk_bf16_f32 v24, v221, s0
	ds_write_b16 v205, v24 offset:816
	v_cvt_pk_bf16_f32 v24, v136, s0
	ds_write_b16 v205, v24 offset:32
	v_cvt_pk_bf16_f32 v24, v137, s0
	ds_write_b16 v205, v24 offset:304
	v_cvt_pk_bf16_f32 v24, v138, s0
	ds_write_b16 v205, v24 offset:576
	v_cvt_pk_bf16_f32 v24, v139, s0
	ds_write_b16 v205, v24 offset:848
	v_cvt_pk_bf16_f32 v24, v222, s0
	ds_write_b16 v205, v24 offset:4352
	v_cvt_pk_bf16_f32 v24, v223, s0
	ds_write_b16 v205, v24 offset:4624
	v_cvt_pk_bf16_f32 v24, v224, s0
	ds_write_b16 v205, v24 offset:4896
	v_cvt_pk_bf16_f32 v24, v225, s0
	ds_write_b16 v205, v24 offset:5168
	v_cvt_pk_bf16_f32 v24, v230, s0
	ds_write_b16 v205, v24 offset:4384
	v_cvt_pk_bf16_f32 v24, v231, s0
	ds_write_b16 v205, v24 offset:4656
	v_cvt_pk_bf16_f32 v24, v232, s0
	ds_write_b16 v205, v24 offset:4928
	v_cvt_pk_bf16_f32 v24, v233, s0
	ds_write_b16 v205, v24 offset:5200
	v_cvt_pk_bf16_f32 v24, v234, s0
	ds_write_b16 v205, v24 offset:8704
	v_cvt_pk_bf16_f32 v24, v235, s0
	ds_write_b16 v205, v24 offset:8976
	v_cvt_pk_bf16_f32 v24, v236, s0
	ds_write_b16 v205, v24 offset:9248
	v_cvt_pk_bf16_f32 v24, v237, s0
	ds_write_b16 v205, v24 offset:9520
	v_cvt_pk_bf16_f32 v24, v226, s0
	ds_write_b16 v205, v24 offset:8736
	v_cvt_pk_bf16_f32 v24, v227, s0
	ds_write_b16 v205, v24 offset:9008
	v_cvt_pk_bf16_f32 v24, v228, s0
	ds_write_b16 v205, v24 offset:9280
	v_cvt_pk_bf16_f32 v24, v229, s0
	ds_write_b16 v205, v24 offset:9552
	v_cvt_pk_bf16_f32 v24, v28, s0
	ds_write_b16 v205, v24 offset:13056
	v_cvt_pk_bf16_f32 v24, v29, s0
	ds_write_b16 v205, v24 offset:13328
	v_cvt_pk_bf16_f32 v24, v30, s0
	ds_write_b16 v205, v24 offset:13600
	v_cvt_pk_bf16_f32 v24, v31, s0
	ds_write_b16 v205, v24 offset:13872
	v_cvt_pk_bf16_f32 v24, v32, s0
	ds_write_b16 v205, v24 offset:13088
	v_cvt_pk_bf16_f32 v24, v33, s0
	ds_write_b16 v205, v24 offset:13360
	v_cvt_pk_bf16_f32 v24, v34, s0
	ds_write_b16 v205, v24 offset:13632
	v_cvt_pk_bf16_f32 v24, v35, s0
	ds_write_b16 v205, v24 offset:13904
	v_cvt_pk_bf16_f32 v24, v36, s0
	ds_write_b16 v205, v24 offset:17408
	v_cvt_pk_bf16_f32 v24, v37, s0
	ds_write_b16 v205, v24 offset:17680
	v_cvt_pk_bf16_f32 v24, v38, s0
	ds_write_b16 v205, v24 offset:17952
	v_cvt_pk_bf16_f32 v24, v39, s0
	ds_write_b16 v205, v24 offset:18224
	v_cvt_pk_bf16_f32 v24, v40, s0
	ds_write_b16 v205, v24 offset:17440
	v_cvt_pk_bf16_f32 v24, v41, s0
	ds_write_b16 v205, v24 offset:17712
	v_cvt_pk_bf16_f32 v24, v42, s0
	ds_write_b16 v205, v24 offset:17984
	v_cvt_pk_bf16_f32 v24, v43, s0
	ds_write_b16 v205, v24 offset:18256
	v_cvt_pk_bf16_f32 v24, v44, s0
	v_cvt_pk_bf16_f32 v4, v4, s0
	ds_write_b16 v205, v24 offset:21760
	v_cvt_pk_bf16_f32 v24, v45, s0
	v_cvt_pk_bf16_f32 v12, v13, s0
	ds_write_b16 v205, v8 offset:30464
	v_cvt_pk_bf16_f32 v8, v9, s0
	ds_write_b16 v205, v4 offset:30496
	v_cvt_pk_bf16_f32 v4, v5, s0
	ds_write_b16 v205, v24 offset:22032
	v_cvt_pk_bf16_f32 v24, v46, s0
	ds_write_b16 v205, v20 offset:22064
	v_cvt_pk_bf16_f32 v20, v22, s0
	ds_write_b16 v205, v16 offset:26384
	v_cvt_pk_bf16_f32 v16, v18, s0
	ds_write_b16 v205, v12 offset:26416
	v_cvt_pk_bf16_f32 v12, v14, s0
	ds_write_b16 v205, v8 offset:30736
	v_cvt_pk_bf16_f32 v8, v10, s0
	ds_write_b16 v205, v4 offset:30768
	v_cvt_pk_bf16_f32 v4, v6, s0
	ds_write_b16 v205, v24 offset:22304
	v_cvt_pk_bf16_f32 v24, v47, s0
	ds_write_b16 v205, v20 offset:22336
	v_cvt_pk_bf16_f32 v20, v23, s0
	ds_write_b16 v205, v16 offset:26656
	v_cvt_pk_bf16_f32 v16, v19, s0
	ds_write_b16 v205, v12 offset:26688
	v_cvt_pk_bf16_f32 v12, v15, s0
	ds_write_b16 v205, v8 offset:31008
	v_cvt_pk_bf16_f32 v8, v11, s0
	ds_write_b16 v205, v4 offset:31040
	v_cvt_pk_bf16_f32 v4, v7, s0
	ds_write_b16 v205, v24 offset:22576
	ds_write_b16 v205, v20 offset:22608
	ds_write_b16 v205, v16 offset:26928
	ds_write_b16 v205, v12 offset:26960
	ds_write_b16 v205, v8 offset:31280
	ds_write_b16 v205, v4 offset:31312
	s_waitcnt lgkmcnt(0)
	s_barrier
	ds_read_b128 v[4:7], v85
	v_lshl_add_u64 v[8:9], s[24:25], 1, v[116:117]
	v_lshl_add_u64 v[10:11], v[8:9], 0, v[118:119]
	s_movk_i32 s24, 0x80
	s_waitcnt lgkmcnt(0)
	flat_store_dwordx4 v[10:11], v[4:7]
	ds_read_b128 v[4:7], v85 offset:4352
	v_lshl_add_u64 v[10:11], v[8:9], 0, v[120:121]
	s_waitcnt lgkmcnt(0)
	flat_store_dwordx4 v[10:11], v[4:7]
	ds_read_b128 v[4:7], v85 offset:8704
	v_lshl_add_u64 v[10:11], v[8:9], 0, v[122:123]
	s_waitcnt lgkmcnt(0)
	flat_store_dwordx4 v[10:11], v[4:7]
	ds_read_b128 v[4:7], v85 offset:13056
	v_lshl_add_u64 v[10:11], v[8:9], 0, v[124:125]
	s_waitcnt lgkmcnt(0)
	flat_store_dwordx4 v[10:11], v[4:7]
	ds_read_b128 v[4:7], v85 offset:17408
	v_lshl_add_u64 v[10:11], v[8:9], 0, v[126:127]
	s_waitcnt lgkmcnt(0)
	flat_store_dwordx4 v[10:11], v[4:7]
	ds_read_b128 v[4:7], v85 offset:21760
	v_lshl_add_u64 v[10:11], v[8:9], 0, v[128:129]
	s_waitcnt lgkmcnt(0)
	flat_store_dwordx4 v[10:11], v[4:7]
	ds_read_b128 v[4:7], v85 offset:26112
	v_lshl_add_u64 v[10:11], v[8:9], 0, v[130:131]
	v_lshl_add_u64 v[8:9], v[8:9], 0, v[134:135]
	s_waitcnt lgkmcnt(0)
	flat_store_dwordx4 v[10:11], v[4:7]
	ds_read_b128 v[4:7], v85 offset:30464
	s_waitcnt lgkmcnt(0)
	flat_store_dwordx4 v[8:9], v[4:7]
	s_waitcnt lgkmcnt(0)
	s_barrier
	s_cbranch_vccnz .LBB0_743

.LBB0_743:
	v_mov_b32_e32 v0, s38
	ds_read_b64 v[0:1], v0
	v_and_b32_e32 v4, 31, v213
	v_and_b32_e32 v5, 3, v215
	v_lshlrev_b32_e32 v6, 18, v4
	v_lshlrev_b32_e32 v7, 9, v5
	v_lshlrev_b64 v[4:5], 23, v[94:95]
	s_waitcnt lgkmcnt(0)
	v_add_co_u32_e32 v0, vcc, v0, v88
	v_addc_co_u32_e32 v1, vcc, v1, v89, vcc
	v_or3_b32 v4, v4, v6, v7
	v_add_co_u32_e32 v2, vcc, v2, v88
	v_addc_co_u32_e32 v3, vcc, v3, v89, vcc
	v_add_co_u32_e32 v0, vcc, v0, v4
	v_addc_co_u32_e32 v1, vcc, v1, v5, vcc
	v_add_co_u32_e32 v2, vcc, v2, v4
	v_addc_co_u32_e32 v3, vcc, v3, v5, vcc

.Lex_793:
	s_waitcnt lgkmcnt(0)
	v_add3_u32 v130, s46, v156, v162
	v_add3_u32 v151, s46, v156, v161
	v_add3_u32 v202, s46, v156, v160
	v_add3_u32 v198, s46, v156, v159
	v_add3_u32 v186, s46, v156, v158
	v_add3_u32 v187, s46, v156, v157
	v_add3_u32 v188, s46, v156, v155
	v_add3_u32 v189, s46, v152, v154
	v_add3_u32 v190, s47, v152, v153
	ds_read_b128 v[134:137], v130
	ds_read_b128 v[138:141], v151
	ds_read_b128 v[142:145], v202
	ds_read_b128 v[146:149], v198
	ds_read_b128 v[158:161], v186
	ds_read_b128 v[162:165], v187
	ds_read_b128 v[166:169], v188
	ds_read_b128 v[154:157], v189
	ds_read_b128 v[170:173], v190
	s_waitcnt lgkmcnt(0)
	v_mfma_f32_16x16x32_bf16 v[18:21], v[170:173], v[138:141], v[18:21]
	v_mfma_f32_16x16x32_bf16 v[174:177], v[170:173], v[134:137], v[38:41]
	s_nop 2
	ds_read_b128 v[38:41], v190 offset:2048
	s_waitcnt lgkmcnt(0)
	v_mfma_f32_16x16x32_bf16 v[10:13], v[38:41], v[138:141], v[10:13]
	v_mfma_f32_16x16x32_bf16 v[62:65], v[170:173], v[146:149], v[62:65]
	v_mfma_f32_16x16x32_bf16 v[30:33], v[38:41], v[134:137], v[30:33]
	v_mfma_f32_16x16x32_bf16 v[58:61], v[38:41], v[146:149], v[58:61]
	ds_read_b128 v[178:181], v190 offset:4096
	s_waitcnt lgkmcnt(0)
	v_mfma_f32_16x16x32_bf16 v[182:185], v[178:181], v[134:137], v[22:25]
	v_mfma_f32_16x16x32_bf16 v[54:57], v[178:181], v[146:149], v[54:57]
	s_nop 1
	ds_read_b128 v[22:25], v190 offset:6144
	s_waitcnt lgkmcnt(0)
	v_mfma_f32_16x16x32_bf16 v[134:137], v[22:25], v[134:137], v[14:17]
	v_mfma_f32_16x16x32_bf16 v[14:17], v[22:25], v[154:157], v[114:117]
	v_mfma_f32_16x16x32_bf16 v[114:117], v[22:25], v[158:161], v[66:69]
	v_mfma_f32_16x16x32_bf16 v[66:69], v[178:181], v[154:157], v[118:121]
	v_mfma_f32_16x16x32_bf16 v[118:121], v[178:181], v[158:161], v[70:73]
	v_mfma_f32_16x16x32_bf16 v[70:73], v[38:41], v[154:157], v[122:125]
	v_mfma_f32_16x16x32_bf16 v[122:125], v[38:41], v[158:161], v[74:77]
	v_mfma_f32_16x16x32_bf16 v[74:77], v[170:173], v[154:157], v[126:129]
	v_mfma_f32_16x16x32_bf16 v[126:129], v[170:173], v[158:161], v[78:81]
	v_mfma_f32_16x16x32_bf16 v[50:53], v[22:25], v[146:149], v[50:53]
	v_mfma_f32_16x16x32_bf16 v[146:149], v[170:173], v[142:145], v[46:49]
	v_mfma_f32_16x16x32_bf16 v[152:155], v[38:41], v[142:145], v[42:45]
	v_mfma_f32_16x16x32_bf16 v[156:159], v[178:181], v[142:145], v[34:37]
	v_mfma_f32_16x16x32_bf16 v[26:29], v[22:25], v[142:145], v[26:29]
	v_mfma_f32_16x16x32_bf16 v[142:145], v[178:181], v[138:141], v[6:9]
	v_mfma_f32_16x16x32_bf16 v[110:113], v[170:173], v[166:169], v[110:113]
	v_mfma_f32_16x16x32_bf16 v[94:97], v[170:173], v[162:165], v[94:97]
	v_mfma_f32_16x16x32_bf16 v[106:109], v[38:41], v[166:169], v[106:109]
	v_mfma_f32_16x16x32_bf16 v[90:93], v[38:41], v[162:165], v[90:93]
	v_mfma_f32_16x16x32_bf16 v[102:105], v[178:181], v[166:169], v[102:105]
	v_mfma_f32_16x16x32_bf16 v[86:89], v[178:181], v[162:165], v[86:89]
	v_mfma_f32_16x16x32_bf16 v[98:101], v[22:25], v[166:169], v[98:101]
	v_mfma_f32_16x16x32_bf16 v[82:85], v[22:25], v[162:165], v[82:85]
	v_mfma_f32_16x16x32_bf16 v[22:25], v[22:25], v[138:141], v[2:5]
	ds_read_b128 v[138:141], v190 offset:1024
	ds_read_b128 v[160:163], v190 offset:3072
	ds_read_b128 v[164:167], v190 offset:5120
	ds_read_b128 v[168:171], v190 offset:7168
	ds_read_b128 v[2:5], v189 offset:1024
	ds_read_b128 v[6:9], v188 offset:1024
	ds_read_b128 v[34:37], v187 offset:1024
	ds_read_b128 v[38:41], v186 offset:1024
	s_waitcnt lgkmcnt(3)
	v_mfma_f32_16x16x32_bf16 v[178:181], v[138:141], v[2:5], v[74:77]
	v_mfma_f32_16x16x32_bf16 v[186:189], v[160:163], v[2:5], v[70:73]
	v_mfma_f32_16x16x32_bf16 v[190:193], v[164:167], v[2:5], v[66:69]
	v_mfma_f32_16x16x32_bf16 v[194:197], v[168:171], v[2:5], v[14:17]
	ds_read_b128 v[2:5], v198 offset:1024
	s_waitcnt lgkmcnt(3)
	v_mfma_f32_16x16x32_bf16 v[110:113], v[138:141], v[6:9], v[110:113]
	v_mfma_f32_16x16x32_bf16 v[106:109], v[160:163], v[6:9], v[106:109]
	v_mfma_f32_16x16x32_bf16 v[102:105], v[164:167], v[6:9], v[102:105]
	v_mfma_f32_16x16x32_bf16 v[198:201], v[168:171], v[6:9], v[98:101]
	ds_read_b128 v[6:9], v202 offset:1024
	s_waitcnt lgkmcnt(3)
	v_mfma_f32_16x16x32_bf16 v[66:69], v[138:141], v[34:37], v[94:97]
	v_mfma_f32_16x16x32_bf16 v[70:73], v[160:163], v[34:37], v[90:93]
	v_mfma_f32_16x16x32_bf16 v[74:77], v[164:167], v[34:37], v[86:89]
	v_mfma_f32_16x16x32_bf16 v[78:81], v[168:171], v[34:37], v[82:85]
	ds_read_b128 v[14:17], v151 offset:1024
	s_waitcnt lgkmcnt(3)
	v_mfma_f32_16x16x32_bf16 v[82:85], v[138:141], v[38:41], v[126:129]
	v_mfma_f32_16x16x32_bf16 v[86:89], v[160:163], v[38:41], v[122:125]
	v_mfma_f32_16x16x32_bf16 v[90:93], v[164:167], v[38:41], v[118:121]
	v_mfma_f32_16x16x32_bf16 v[94:97], v[168:171], v[38:41], v[114:117]
	ds_read_b128 v[98:101], v130 offset:1024
	s_waitcnt lgkmcnt(3)
	v_mfma_f32_16x16x32_bf16 v[34:37], v[138:141], v[2:5], v[62:65]
	v_mfma_f32_16x16x32_bf16 v[38:41], v[160:163], v[2:5], v[58:61]
	v_mfma_f32_16x16x32_bf16 v[42:45], v[164:167], v[2:5], v[54:57]
	v_mfma_f32_16x16x32_bf16 v[46:49], v[168:171], v[2:5], v[50:53]
	s_waitcnt lgkmcnt(2)
	v_mfma_f32_16x16x32_bf16 v[50:53], v[138:141], v[6:9], v[146:149]
	v_mfma_f32_16x16x32_bf16 v[54:57], v[160:163], v[6:9], v[152:155]
	v_mfma_f32_16x16x32_bf16 v[58:61], v[164:167], v[6:9], v[156:159]
	v_mfma_f32_16x16x32_bf16 v[62:65], v[168:171], v[6:9], v[26:29]
	s_waitcnt lgkmcnt(1)
	v_mfma_f32_16x16x32_bf16 v[2:5], v[138:141], v[14:17], v[18:21]
	v_mfma_f32_16x16x32_bf16 v[6:9], v[160:163], v[14:17], v[10:13]
	v_mfma_f32_16x16x32_bf16 v[10:13], v[164:167], v[14:17], v[142:145]
	v_mfma_f32_16x16x32_bf16 v[14:17], v[168:171], v[14:17], v[22:25]
	s_waitcnt lgkmcnt(0)
	v_mfma_f32_16x16x32_bf16 v[18:21], v[138:141], v[98:101], v[174:177]
	v_mfma_f32_16x16x32_bf16 v[22:25], v[160:163], v[98:101], v[30:33]
	v_mfma_f32_16x16x32_bf16 v[26:29], v[164:167], v[98:101], v[182:185]
	v_mfma_f32_16x16x32_bf16 v[30:33], v[168:171], v[98:101], v[134:137]
	v_lshrrev_b32_e32 v98, 6, v150
	v_mul_lo_u32 v98, v98, s48
	v_add_u32_e32 v101, s46, v98
	v_lshlrev_b32_e32 v98, 2, v150
	v_and_b32_e32 v100, 15, v150
	v_and_b32_e32 v115, 60, v98
	v_ashrrev_i32_e32 v98, 1, v150
	v_bfe_u32 v99, v150, 4, 2
	v_and_b32_e32 v114, 48, v150
	v_and_b32_e32 v116, 0xffffff80, v98
	v_lshlrev_b32_e32 v98, 2, v115
	v_mul_u32_u24_e32 v117, 0x110, v99
	v_mul_u32_u24_e32 v100, 0x110, v100
	v_add3_u32 v98, v101, v98, v117
	v_add3_u32 v101, v101, v114, v100
	s_waitcnt vmcnt(0)
	s_barrier
	ds_write_b128 v101, v[178:181]
	ds_write_b128 v101, v[186:189] offset:64
	ds_write_b128 v101, v[190:193] offset:128
	ds_write_b128 v101, v[194:197] offset:192
	ds_write_b128 v101, v[110:113] offset:4352
	ds_write_b128 v101, v[106:109] offset:4416
	ds_write_b128 v101, v[102:105] offset:4480
	ds_write_b128 v101, v[198:201] offset:4544
	ds_read_b128 v[102:105], v98
	v_add_u32_e32 v100, s28, v116
	s_ashr_i32 s31, s30, 31
	v_and_or_b32 v106, v150, s49, v115
	s_lshl_b64 s[38:39], s[30:31], 1
	s_waitcnt lgkmcnt(0)
	v_mul_f32_e32 v102, 0xbfb8aa3b, v102
	v_mul_f32_e32 v103, 0xbfb8aa3b, v103
	v_mul_f32_e32 v104, 0xbfb8aa3b, v104
	v_mul_f32_e32 v105, 0xbfb8aa3b, v105
	v_exp_f32_e32 v102, v102
	v_exp_f32_e32 v103, v103
	v_exp_f32_e32 v104, v104
	v_exp_f32_e32 v105, v105
	v_add_f32_e32 v102, 1.0, v102
	v_add_f32_e32 v103, 1.0, v103
	v_add_f32_e32 v104, 1.0, v104
	v_add_f32_e32 v105, 1.0, v105
	v_rcp_f32_e32 v102, v102
	v_rcp_f32_e32 v103, v103
	v_rcp_f32_e32 v104, v104
	v_rcp_f32_e32 v105, v105
	v_lshl_add_u64 v[0:1], v[0:1], 0, s[38:39]
	v_cvt_pk_bf16_f32 v102, v102, v103
	v_lshlrev_b32_e32 v130, 1, v106
	v_cvt_pk_bf16_f32 v103, v104, v105
	v_or_b32_e32 v104, v100, v99
	v_ashrrev_i32_e32 v105, 31, v104
	v_add_co_u32_e32 v0, vcc, v0, v130
	v_addc_co_u32_e32 v1, vcc, v1, v131, vcc
	v_lshlrev_b64 v[104:105], 11, v[104:105]
	v_add_co_u32_e32 v104, vcc, v0, v104
	v_addc_co_u32_e32 v105, vcc, v1, v105, vcc
	flat_store_dwordx2 v[104:105], v[102:103]
	ds_read_b128 v[102:105], v98 offset:1088
	s_lshl_b64 s[42:43], s[28:29], 10
	s_mov_b32 s29, 0
	s_waitcnt lgkmcnt(0)
	v_mul_f32_e32 v102, 0xbfb8aa3b, v102
	v_exp_f32_e32 v102, v102
	v_mul_f32_e32 v103, 0xbfb8aa3b, v103
	v_exp_f32_e32 v103, v103
	v_add_f32_e32 v102, 1.0, v102
	v_rcp_f32_e32 v106, v102
	v_add_f32_e32 v102, 1.0, v103
	v_mul_f32_e32 v103, 0xbfb8aa3b, v104
	v_exp_f32_e32 v103, v103
	v_mul_f32_e32 v104, 0xbfb8aa3b, v105
	v_exp_f32_e32 v104, v104
	v_rcp_f32_e32 v105, v102
	v_add_f32_e32 v102, 1.0, v103
	v_rcp_f32_e32 v103, v102
	v_add_f32_e32 v102, 1.0, v104
	v_rcp_f32_e32 v107, v102
	v_or_b32_e32 v102, 4, v99
	v_cvt_pk_bf16_f32 v104, v106, v105
	v_or_b32_e32 v106, v100, v102
	v_cvt_pk_bf16_f32 v105, v103, v107
	v_lshlrev_b32_e32 v106, 11, v106
	v_add_co_u32_e32 v106, vcc, v0, v106
	v_addc_co_u32_e32 v107, vcc, 0, v1, vcc
	flat_store_dwordx2 v[106:107], v[104:105]
	ds_read_b128 v[104:107], v98 offset:2176
	s_waitcnt lgkmcnt(0)
	v_mul_f32_e32 v103, 0xbfb8aa3b, v104
	v_exp_f32_e32 v103, v103
	v_mul_f32_e32 v104, 0xbfb8aa3b, v105
	v_exp_f32_e32 v104, v104
	v_add_f32_e32 v103, 1.0, v103
	v_rcp_f32_e32 v105, v103
	v_add_f32_e32 v103, 1.0, v104
	v_mul_f32_e32 v104, 0xbfb8aa3b, v106
	v_exp_f32_e32 v104, v104
	v_mul_f32_e32 v106, 0xbfb8aa3b, v107
	v_exp_f32_e32 v106, v106
	v_rcp_f32_e32 v107, v103
	v_add_f32_e32 v103, 1.0, v104
	v_rcp_f32_e32 v108, v103
	v_add_f32_e32 v103, 1.0, v106
	v_rcp_f32_e32 v106, v103
	v_or_b32_e32 v103, 8, v99
	v_cvt_pk_bf16_f32 v104, v105, v107
	v_cvt_pk_bf16_f32 v105, v108, v106
	v_or_b32_e32 v106, v100, v103
	v_lshlrev_b32_e32 v106, 11, v106
	v_add_co_u32_e32 v106, vcc, v0, v106
	v_addc_co_u32_e32 v107, vcc, 0, v1, vcc
	flat_store_dwordx2 v[106:107], v[104:105]
	ds_read_b128 v[104:107], v98 offset:3264
	s_waitcnt lgkmcnt(0)
	v_mul_f32_e32 v104, 0xbfb8aa3b, v104
	v_exp_f32_e32 v104, v104
	v_mul_f32_e32 v105, 0xbfb8aa3b, v105
	v_exp_f32_e32 v105, v105
	v_add_f32_e32 v104, 1.0, v104
	v_rcp_f32_e32 v108, v104
	v_add_f32_e32 v104, 1.0, v105
	v_mul_f32_e32 v105, 0xbfb8aa3b, v106
	v_exp_f32_e32 v105, v105
	v_mul_f32_e32 v106, 0xbfb8aa3b, v107
	v_exp_f32_e32 v106, v106
	v_rcp_f32_e32 v107, v104
	v_add_f32_e32 v104, 1.0, v105
	v_rcp_f32_e32 v105, v104
	v_add_f32_e32 v104, 1.0, v106
	v_rcp_f32_e32 v109, v104
	v_or_b32_e32 v104, 12, v99
	v_cvt_pk_bf16_f32 v106, v108, v107
	v_or_b32_e32 v108, v100, v104
	v_cvt_pk_bf16_f32 v107, v105, v109
	v_lshlrev_b32_e32 v108, 11, v108
	v_add_co_u32_e32 v108, vcc, v0, v108
	v_addc_co_u32_e32 v109, vcc, 0, v1, vcc
	flat_store_dwordx2 v[108:109], v[106:107]
	ds_read_b128 v[106:109], v98 offset:4352
	s_waitcnt lgkmcnt(0)
	v_mul_f32_e32 v105, 0xbfb8aa3b, v106
	v_exp_f32_e32 v105, v105
	v_mul_f32_e32 v106, 0xbfb8aa3b, v107
	v_exp_f32_e32 v106, v106
	v_add_f32_e32 v105, 1.0, v105
	v_rcp_f32_e32 v107, v105
	v_add_f32_e32 v105, 1.0, v106
	v_mul_f32_e32 v106, 0xbfb8aa3b, v108
	v_exp_f32_e32 v106, v106
	v_mul_f32_e32 v108, 0xbfb8aa3b, v109
	v_exp_f32_e32 v108, v108
	v_rcp_f32_e32 v109, v105
	v_add_f32_e32 v105, 1.0, v106
	v_rcp_f32_e32 v110, v105
	v_add_f32_e32 v105, 1.0, v108
	v_rcp_f32_e32 v108, v105
	v_or_b32_e32 v105, 16, v99
	v_cvt_pk_bf16_f32 v106, v107, v109
	v_cvt_pk_bf16_f32 v107, v110, v108
	v_or_b32_e32 v108, v100, v105
	v_lshlrev_b32_e32 v108, 11, v108
	v_add_co_u32_e32 v108, vcc, v0, v108
	v_addc_co_u32_e32 v109, vcc, 0, v1, vcc
	flat_store_dwordx2 v[108:109], v[106:107]
	ds_read_b128 v[106:109], v98 offset:5440
	s_waitcnt lgkmcnt(0)
	v_mul_f32_e32 v106, 0xbfb8aa3b, v106
	v_exp_f32_e32 v106, v106
	v_mul_f32_e32 v107, 0xbfb8aa3b, v107
	v_exp_f32_e32 v107, v107
	v_add_f32_e32 v106, 1.0, v106
	v_rcp_f32_e32 v110, v106
	v_add_f32_e32 v106, 1.0, v107
	v_mul_f32_e32 v107, 0xbfb8aa3b, v108
	v_exp_f32_e32 v107, v107
	v_mul_f32_e32 v108, 0xbfb8aa3b, v109
	v_exp_f32_e32 v108, v108
	v_rcp_f32_e32 v109, v106
	v_add_f32_e32 v106, 1.0, v107
	v_rcp_f32_e32 v107, v106
	v_add_f32_e32 v106, 1.0, v108
	v_rcp_f32_e32 v111, v106
	v_or_b32_e32 v106, 20, v99
	v_cvt_pk_bf16_f32 v108, v110, v109
	v_or_b32_e32 v110, v100, v106
	v_cvt_pk_bf16_f32 v109, v107, v111
	v_lshlrev_b32_e32 v110, 11, v110
	v_add_co_u32_e32 v110, vcc, v0, v110
	v_addc_co_u32_e32 v111, vcc, 0, v1, vcc
	flat_store_dwordx2 v[110:111], v[108:109]
	ds_read_b128 v[108:111], v98 offset:6528
	s_waitcnt lgkmcnt(0)
	v_mul_f32_e32 v107, 0xbfb8aa3b, v108
	v_exp_f32_e32 v107, v107
	v_mul_f32_e32 v108, 0xbfb8aa3b, v109
	v_exp_f32_e32 v108, v108
	v_add_f32_e32 v107, 1.0, v107
	v_rcp_f32_e32 v109, v107
	v_add_f32_e32 v107, 1.0, v108
	v_mul_f32_e32 v108, 0xbfb8aa3b, v110
	v_exp_f32_e32 v108, v108
	v_mul_f32_e32 v110, 0xbfb8aa3b, v111
	v_exp_f32_e32 v110, v110
	v_rcp_f32_e32 v111, v107
	v_add_f32_e32 v107, 1.0, v108
	v_rcp_f32_e32 v112, v107
	v_add_f32_e32 v107, 1.0, v110
	v_rcp_f32_e32 v110, v107
	v_or_b32_e32 v107, 24, v99
	v_cvt_pk_bf16_f32 v108, v109, v111
	v_cvt_pk_bf16_f32 v109, v112, v110
	v_or_b32_e32 v110, v100, v107
	v_lshlrev_b32_e32 v110, 11, v110
	v_add_co_u32_e32 v110, vcc, v0, v110
	v_addc_co_u32_e32 v111, vcc, 0, v1, vcc
	flat_store_dwordx2 v[110:111], v[108:109]
	ds_read_b128 v[108:111], v98 offset:7616
	s_waitcnt lgkmcnt(0)
	v_mul_f32_e32 v108, 0xbfb8aa3b, v108
	v_exp_f32_e32 v108, v108
	v_mul_f32_e32 v109, 0xbfb8aa3b, v109
	v_exp_f32_e32 v109, v109
	v_add_f32_e32 v108, 1.0, v108
	v_rcp_f32_e32 v112, v108
	v_add_f32_e32 v108, 1.0, v109
	v_mul_f32_e32 v109, 0xbfb8aa3b, v110
	v_exp_f32_e32 v109, v109
	v_mul_f32_e32 v110, 0xbfb8aa3b, v111
	v_exp_f32_e32 v110, v110
	v_rcp_f32_e32 v111, v108
	v_add_f32_e32 v108, 1.0, v109
	v_rcp_f32_e32 v109, v108
	v_add_f32_e32 v108, 1.0, v110
	v_rcp_f32_e32 v113, v108
	v_or_b32_e32 v108, 28, v99
	v_cvt_pk_bf16_f32 v110, v112, v111
	v_or_b32_e32 v112, v100, v108
	v_cvt_pk_bf16_f32 v111, v109, v113
	v_lshlrev_b32_e32 v112, 11, v112
	v_add_co_u32_e32 v112, vcc, v0, v112
	v_addc_co_u32_e32 v113, vcc, 0, v1, vcc
	flat_store_dwordx2 v[112:113], v[110:111]
	ds_write_b128 v101, v[66:69]
	ds_write_b128 v101, v[70:73] offset:64
	ds_write_b128 v101, v[74:77] offset:128
	ds_write_b128 v101, v[78:81] offset:192
	ds_write_b128 v101, v[82:85] offset:4352
	ds_write_b128 v101, v[86:89] offset:4416
	ds_write_b128 v101, v[90:93] offset:4480
	ds_write_b128 v101, v[94:97] offset:4544
	ds_read_b128 v[66:69], v98
	v_or_b32_e32 v70, 32, v100
	s_waitcnt lgkmcnt(0)
	v_mul_f32_e32 v66, 0xbfb8aa3b, v66
	v_mul_f32_e32 v67, 0xbfb8aa3b, v67
	v_mul_f32_e32 v68, 0xbfb8aa3b, v68
	v_mul_f32_e32 v69, 0xbfb8aa3b, v69
	v_exp_f32_e32 v66, v66
	v_exp_f32_e32 v67, v67
	v_exp_f32_e32 v68, v68
	v_exp_f32_e32 v69, v69
	v_add_f32_e32 v66, 1.0, v66
	v_add_f32_e32 v67, 1.0, v67
	v_add_f32_e32 v68, 1.0, v68
	v_add_f32_e32 v69, 1.0, v69
	v_rcp_f32_e32 v66, v66
	v_rcp_f32_e32 v67, v67
	v_rcp_f32_e32 v68, v68
	v_rcp_f32_e32 v69, v69
	v_cvt_pk_bf16_f32 v66, v66, v67
	v_cvt_pk_bf16_f32 v67, v68, v69
	v_or_b32_e32 v68, v70, v99
	v_lshlrev_b32_e32 v68, 11, v68
	v_add_co_u32_e32 v68, vcc, v0, v68
	v_addc_co_u32_e32 v69, vcc, 0, v1, vcc
	flat_store_dwordx2 v[68:69], v[66:67]
	ds_read_b128 v[66:69], v98 offset:1088
	s_waitcnt lgkmcnt(0)
	v_mul_f32_e32 v66, 0xbfb8aa3b, v66
	v_mul_f32_e32 v67, 0xbfb8aa3b, v67
	v_mul_f32_e32 v68, 0xbfb8aa3b, v68
	v_mul_f32_e32 v69, 0xbfb8aa3b, v69
	v_exp_f32_e32 v66, v66
	v_exp_f32_e32 v67, v67
	v_exp_f32_e32 v68, v68
	v_exp_f32_e32 v69, v69
	v_add_f32_e32 v66, 1.0, v66
	v_add_f32_e32 v67, 1.0, v67
	v_add_f32_e32 v68, 1.0, v68
	v_add_f32_e32 v69, 1.0, v69
	v_rcp_f32_e32 v66, v66
	v_rcp_f32_e32 v67, v67
	v_rcp_f32_e32 v68, v68
	v_rcp_f32_e32 v69, v69
	v_cvt_pk_bf16_f32 v66, v66, v67
	v_cvt_pk_bf16_f32 v67, v68, v69
	v_or_b32_e32 v68, v70, v102
	v_lshlrev_b32_e32 v68, 11, v68
	v_add_co_u32_e32 v68, vcc, v0, v68
	v_addc_co_u32_e32 v69, vcc, 0, v1, vcc
	flat_store_dwordx2 v[68:69], v[66:67]
	ds_read_b128 v[66:69], v98 offset:2176
	s_waitcnt lgkmcnt(0)
	v_mul_f32_e32 v66, 0xbfb8aa3b, v66
	v_mul_f32_e32 v67, 0xbfb8aa3b, v67
	v_mul_f32_e32 v68, 0xbfb8aa3b, v68
	v_mul_f32_e32 v69, 0xbfb8aa3b, v69
	v_exp_f32_e32 v66, v66
	v_exp_f32_e32 v67, v67
	v_exp_f32_e32 v68, v68
	v_exp_f32_e32 v69, v69
	v_add_f32_e32 v66, 1.0, v66
	v_add_f32_e32 v67, 1.0, v67
	v_add_f32_e32 v68, 1.0, v68
	v_add_f32_e32 v69, 1.0, v69
	v_rcp_f32_e32 v66, v66
	v_rcp_f32_e32 v67, v67
	v_rcp_f32_e32 v68, v68
	v_rcp_f32_e32 v69, v69
	v_cvt_pk_bf16_f32 v66, v66, v67
	v_cvt_pk_bf16_f32 v67, v68, v69
	v_or_b32_e32 v68, v70, v103
	v_lshlrev_b32_e32 v68, 11, v68
	v_add_co_u32_e32 v68, vcc, v0, v68
	v_addc_co_u32_e32 v69, vcc, 0, v1, vcc
	flat_store_dwordx2 v[68:69], v[66:67]
	ds_read_b128 v[66:69], v98 offset:3264
	s_waitcnt lgkmcnt(0)
	v_mul_f32_e32 v66, 0xbfb8aa3b, v66
	v_mul_f32_e32 v67, 0xbfb8aa3b, v67
	v_mul_f32_e32 v68, 0xbfb8aa3b, v68
	v_mul_f32_e32 v69, 0xbfb8aa3b, v69
	v_exp_f32_e32 v66, v66
	v_exp_f32_e32 v67, v67
	v_exp_f32_e32 v68, v68
	v_exp_f32_e32 v69, v69
	v_add_f32_e32 v66, 1.0, v66
	v_add_f32_e32 v67, 1.0, v67
	v_add_f32_e32 v68, 1.0, v68
	v_add_f32_e32 v69, 1.0, v69
	v_rcp_f32_e32 v66, v66
	v_rcp_f32_e32 v67, v67
	v_rcp_f32_e32 v68, v68
	v_rcp_f32_e32 v69, v69
	v_cvt_pk_bf16_f32 v66, v66, v67
	v_cvt_pk_bf16_f32 v67, v68, v69
	v_or_b32_e32 v68, v70, v104
	v_lshlrev_b32_e32 v68, 11, v68
	v_add_co_u32_e32 v68, vcc, v0, v68
	v_addc_co_u32_e32 v69, vcc, 0, v1, vcc
	flat_store_dwordx2 v[68:69], v[66:67]
	ds_read_b128 v[66:69], v98 offset:4352
	s_waitcnt lgkmcnt(0)
	v_mul_f32_e32 v66, 0xbfb8aa3b, v66
	v_mul_f32_e32 v67, 0xbfb8aa3b, v67
	v_mul_f32_e32 v68, 0xbfb8aa3b, v68
	v_mul_f32_e32 v69, 0xbfb8aa3b, v69
	v_exp_f32_e32 v66, v66
	v_exp_f32_e32 v67, v67
	v_exp_f32_e32 v68, v68
	v_exp_f32_e32 v69, v69
	v_add_f32_e32 v66, 1.0, v66
	v_add_f32_e32 v67, 1.0, v67
	v_add_f32_e32 v68, 1.0, v68
	v_add_f32_e32 v69, 1.0, v69
	v_rcp_f32_e32 v66, v66
	v_rcp_f32_e32 v67, v67
	v_rcp_f32_e32 v68, v68
	v_rcp_f32_e32 v69, v69
	v_cvt_pk_bf16_f32 v66, v66, v67
	v_cvt_pk_bf16_f32 v67, v68, v69
	v_or_b32_e32 v68, v70, v105
	v_lshlrev_b32_e32 v68, 11, v68
	v_add_co_u32_e32 v68, vcc, v0, v68
	v_addc_co_u32_e32 v69, vcc, 0, v1, vcc
	flat_store_dwordx2 v[68:69], v[66:67]
	ds_read_b128 v[66:69], v98 offset:5440
	s_waitcnt lgkmcnt(0)
	v_mul_f32_e32 v66, 0xbfb8aa3b, v66
	v_mul_f32_e32 v67, 0xbfb8aa3b, v67
	v_mul_f32_e32 v68, 0xbfb8aa3b, v68
	v_mul_f32_e32 v69, 0xbfb8aa3b, v69
	v_exp_f32_e32 v66, v66
	v_exp_f32_e32 v67, v67
	v_exp_f32_e32 v68, v68
	v_exp_f32_e32 v69, v69
	v_add_f32_e32 v66, 1.0, v66
	v_add_f32_e32 v67, 1.0, v67
	v_add_f32_e32 v68, 1.0, v68
	v_add_f32_e32 v69, 1.0, v69
	v_rcp_f32_e32 v66, v66
	v_rcp_f32_e32 v67, v67
	v_rcp_f32_e32 v68, v68
	v_rcp_f32_e32 v69, v69
	v_cvt_pk_bf16_f32 v66, v66, v67
	v_cvt_pk_bf16_f32 v67, v68, v69
	v_or_b32_e32 v68, v70, v106
	v_lshlrev_b32_e32 v68, 11, v68
	v_add_co_u32_e32 v68, vcc, v0, v68
	v_addc_co_u32_e32 v69, vcc, 0, v1, vcc
	flat_store_dwordx2 v[68:69], v[66:67]
	ds_read_b128 v[66:69], v98 offset:6528
	s_waitcnt lgkmcnt(0)
	v_mul_f32_e32 v66, 0xbfb8aa3b, v66
	v_mul_f32_e32 v67, 0xbfb8aa3b, v67
	v_mul_f32_e32 v68, 0xbfb8aa3b, v68
	v_mul_f32_e32 v69, 0xbfb8aa3b, v69
	v_exp_f32_e32 v66, v66
	v_exp_f32_e32 v67, v67
	v_exp_f32_e32 v68, v68
	v_exp_f32_e32 v69, v69
	v_add_f32_e32 v66, 1.0, v66
	v_add_f32_e32 v67, 1.0, v67
	v_add_f32_e32 v68, 1.0, v68
	v_add_f32_e32 v69, 1.0, v69
	v_rcp_f32_e32 v66, v66
	v_rcp_f32_e32 v67, v67
	v_rcp_f32_e32 v68, v68
	v_rcp_f32_e32 v69, v69
	v_cvt_pk_bf16_f32 v66, v66, v67
	v_cvt_pk_bf16_f32 v67, v68, v69
	v_or_b32_e32 v68, v70, v107
	v_lshlrev_b32_e32 v68, 11, v68
	v_add_co_u32_e32 v68, vcc, v0, v68
	v_addc_co_u32_e32 v69, vcc, 0, v1, vcc
	flat_store_dwordx2 v[68:69], v[66:67]
	ds_read_b128 v[66:69], v98 offset:7616
	s_waitcnt lgkmcnt(0)
	v_mul_f32_e32 v66, 0xbfb8aa3b, v66
	v_mul_f32_e32 v67, 0xbfb8aa3b, v67
	v_mul_f32_e32 v68, 0xbfb8aa3b, v68
	v_mul_f32_e32 v69, 0xbfb8aa3b, v69
	v_exp_f32_e32 v66, v66
	v_exp_f32_e32 v67, v67
	v_exp_f32_e32 v68, v68
	v_exp_f32_e32 v69, v69
	v_add_f32_e32 v66, 1.0, v66
	v_add_f32_e32 v67, 1.0, v67
	v_add_f32_e32 v68, 1.0, v68
	v_add_f32_e32 v69, 1.0, v69
	v_rcp_f32_e32 v66, v66
	v_rcp_f32_e32 v67, v67
	v_rcp_f32_e32 v68, v68
	v_rcp_f32_e32 v69, v69
	v_cvt_pk_bf16_f32 v66, v66, v67
	v_cvt_pk_bf16_f32 v67, v68, v69
	v_or_b32_e32 v68, v70, v108
	v_lshlrev_b32_e32 v68, 11, v68
	v_add_co_u32_e32 v68, vcc, v0, v68
	v_addc_co_u32_e32 v69, vcc, 0, v1, vcc
	flat_store_dwordx2 v[68:69], v[66:67]
	ds_write_b128 v101, v[34:37]
	ds_write_b128 v101, v[38:41] offset:64
	ds_write_b128 v101, v[42:45] offset:128
	ds_write_b128 v101, v[46:49] offset:192
	ds_write_b128 v101, v[50:53] offset:4352
	ds_write_b128 v101, v[54:57] offset:4416
	ds_write_b128 v101, v[58:61] offset:4480
	ds_write_b128 v101, v[62:65] offset:4544
	ds_read_b128 v[34:37], v98
	v_or_b32_e32 v38, 64, v100
	s_waitcnt lgkmcnt(0)
	v_mul_f32_e32 v34, 0xbfb8aa3b, v34
	v_mul_f32_e32 v35, 0xbfb8aa3b, v35
	v_mul_f32_e32 v36, 0xbfb8aa3b, v36
	v_mul_f32_e32 v37, 0xbfb8aa3b, v37
	v_exp_f32_e32 v34, v34
	v_exp_f32_e32 v35, v35
	v_exp_f32_e32 v36, v36
	v_exp_f32_e32 v37, v37
	v_add_f32_e32 v34, 1.0, v34
	v_add_f32_e32 v35, 1.0, v35
	v_add_f32_e32 v36, 1.0, v36
	v_add_f32_e32 v37, 1.0, v37
	v_rcp_f32_e32 v34, v34
	v_rcp_f32_e32 v35, v35
	v_rcp_f32_e32 v36, v36
	v_rcp_f32_e32 v37, v37
	v_cvt_pk_bf16_f32 v34, v34, v35
	v_cvt_pk_bf16_f32 v35, v36, v37
	v_or_b32_e32 v36, v38, v99
	v_lshlrev_b32_e32 v36, 11, v36
	v_add_co_u32_e32 v36, vcc, v0, v36
	v_addc_co_u32_e32 v37, vcc, 0, v1, vcc
	flat_store_dwordx2 v[36:37], v[34:35]
	ds_read_b128 v[34:37], v98 offset:1088
	s_waitcnt lgkmcnt(0)
	v_mul_f32_e32 v34, 0xbfb8aa3b, v34
	v_mul_f32_e32 v35, 0xbfb8aa3b, v35
	v_mul_f32_e32 v36, 0xbfb8aa3b, v36
	v_mul_f32_e32 v37, 0xbfb8aa3b, v37
	v_exp_f32_e32 v34, v34
	v_exp_f32_e32 v35, v35
	v_exp_f32_e32 v36, v36
	v_exp_f32_e32 v37, v37
	v_add_f32_e32 v34, 1.0, v34
	v_add_f32_e32 v35, 1.0, v35
	v_add_f32_e32 v36, 1.0, v36
	v_add_f32_e32 v37, 1.0, v37
	v_rcp_f32_e32 v34, v34
	v_rcp_f32_e32 v35, v35
	v_rcp_f32_e32 v36, v36
	v_rcp_f32_e32 v37, v37
	v_cvt_pk_bf16_f32 v34, v34, v35
	v_cvt_pk_bf16_f32 v35, v36, v37
	v_or_b32_e32 v36, v38, v102
	v_lshlrev_b32_e32 v36, 11, v36
	v_add_co_u32_e32 v36, vcc, v0, v36
	v_addc_co_u32_e32 v37, vcc, 0, v1, vcc
	flat_store_dwordx2 v[36:37], v[34:35]
	ds_read_b128 v[34:37], v98 offset:2176
	s_waitcnt lgkmcnt(0)
	v_mul_f32_e32 v34, 0xbfb8aa3b, v34
	v_mul_f32_e32 v35, 0xbfb8aa3b, v35
	v_mul_f32_e32 v36, 0xbfb8aa3b, v36
	v_mul_f32_e32 v37, 0xbfb8aa3b, v37
	v_exp_f32_e32 v34, v34
	v_exp_f32_e32 v35, v35
	v_exp_f32_e32 v36, v36
	v_exp_f32_e32 v37, v37
	v_add_f32_e32 v34, 1.0, v34
	v_add_f32_e32 v35, 1.0, v35
	v_add_f32_e32 v36, 1.0, v36
	v_add_f32_e32 v37, 1.0, v37
	v_rcp_f32_e32 v34, v34
	v_rcp_f32_e32 v35, v35
	v_rcp_f32_e32 v36, v36
	v_rcp_f32_e32 v37, v37
	v_cvt_pk_bf16_f32 v34, v34, v35
	v_cvt_pk_bf16_f32 v35, v36, v37
	v_or_b32_e32 v36, v38, v103
	v_lshlrev_b32_e32 v36, 11, v36
	v_add_co_u32_e32 v36, vcc, v0, v36
	v_addc_co_u32_e32 v37, vcc, 0, v1, vcc
	flat_store_dwordx2 v[36:37], v[34:35]
	ds_read_b128 v[34:37], v98 offset:3264
	s_waitcnt lgkmcnt(0)
	v_mul_f32_e32 v34, 0xbfb8aa3b, v34
	v_mul_f32_e32 v35, 0xbfb8aa3b, v35
	v_mul_f32_e32 v36, 0xbfb8aa3b, v36
	v_mul_f32_e32 v37, 0xbfb8aa3b, v37
	v_exp_f32_e32 v34, v34
	v_exp_f32_e32 v35, v35
	v_exp_f32_e32 v36, v36
	v_exp_f32_e32 v37, v37
	v_add_f32_e32 v34, 1.0, v34
	v_add_f32_e32 v35, 1.0, v35
	v_add_f32_e32 v36, 1.0, v36
	v_add_f32_e32 v37, 1.0, v37
	v_rcp_f32_e32 v34, v34
	v_rcp_f32_e32 v35, v35
	v_rcp_f32_e32 v36, v36
	v_rcp_f32_e32 v37, v37
	v_cvt_pk_bf16_f32 v34, v34, v35
	v_cvt_pk_bf16_f32 v35, v36, v37
	v_or_b32_e32 v36, v38, v104
	v_lshlrev_b32_e32 v36, 11, v36
	v_add_co_u32_e32 v36, vcc, v0, v36
	v_addc_co_u32_e32 v37, vcc, 0, v1, vcc
	flat_store_dwordx2 v[36:37], v[34:35]
	ds_read_b128 v[34:37], v98 offset:4352
	s_waitcnt lgkmcnt(0)
	v_mul_f32_e32 v34, 0xbfb8aa3b, v34
	v_mul_f32_e32 v35, 0xbfb8aa3b, v35
	v_mul_f32_e32 v36, 0xbfb8aa3b, v36
	v_mul_f32_e32 v37, 0xbfb8aa3b, v37
	v_exp_f32_e32 v34, v34
	v_exp_f32_e32 v35, v35
	v_exp_f32_e32 v36, v36
	v_exp_f32_e32 v37, v37
	v_add_f32_e32 v34, 1.0, v34
	v_add_f32_e32 v35, 1.0, v35
	v_add_f32_e32 v36, 1.0, v36
	v_add_f32_e32 v37, 1.0, v37
	v_rcp_f32_e32 v34, v34
	v_rcp_f32_e32 v35, v35
	v_rcp_f32_e32 v36, v36
	v_rcp_f32_e32 v37, v37
	v_cvt_pk_bf16_f32 v34, v34, v35
	v_cvt_pk_bf16_f32 v35, v36, v37
	v_or_b32_e32 v36, v38, v105
	v_lshlrev_b32_e32 v36, 11, v36
	v_add_co_u32_e32 v36, vcc, v0, v36
	v_addc_co_u32_e32 v37, vcc, 0, v1, vcc
	flat_store_dwordx2 v[36:37], v[34:35]
	ds_read_b128 v[34:37], v98 offset:5440
	s_waitcnt lgkmcnt(0)
	v_mul_f32_e32 v34, 0xbfb8aa3b, v34
	v_mul_f32_e32 v35, 0xbfb8aa3b, v35
	v_mul_f32_e32 v36, 0xbfb8aa3b, v36
	v_mul_f32_e32 v37, 0xbfb8aa3b, v37
	v_exp_f32_e32 v34, v34
	v_exp_f32_e32 v35, v35
	v_exp_f32_e32 v36, v36
	v_exp_f32_e32 v37, v37
	v_add_f32_e32 v34, 1.0, v34
	v_add_f32_e32 v35, 1.0, v35
	v_add_f32_e32 v36, 1.0, v36
	v_add_f32_e32 v37, 1.0, v37
	v_rcp_f32_e32 v34, v34
	v_rcp_f32_e32 v35, v35
	v_rcp_f32_e32 v36, v36
	v_rcp_f32_e32 v37, v37
	v_cvt_pk_bf16_f32 v34, v34, v35
	v_cvt_pk_bf16_f32 v35, v36, v37
	v_or_b32_e32 v36, v38, v106
	v_lshlrev_b32_e32 v36, 11, v36
	v_add_co_u32_e32 v36, vcc, v0, v36
	v_addc_co_u32_e32 v37, vcc, 0, v1, vcc
	flat_store_dwordx2 v[36:37], v[34:35]
	ds_read_b128 v[34:37], v98 offset:6528
	s_waitcnt lgkmcnt(0)
	v_mul_f32_e32 v34, 0xbfb8aa3b, v34
	v_mul_f32_e32 v35, 0xbfb8aa3b, v35
	v_mul_f32_e32 v36, 0xbfb8aa3b, v36
	v_mul_f32_e32 v37, 0xbfb8aa3b, v37
	v_exp_f32_e32 v34, v34
	v_exp_f32_e32 v35, v35
	v_exp_f32_e32 v36, v36
	v_exp_f32_e32 v37, v37
	v_add_f32_e32 v34, 1.0, v34
	v_add_f32_e32 v35, 1.0, v35
	v_add_f32_e32 v36, 1.0, v36
	v_add_f32_e32 v37, 1.0, v37
	v_rcp_f32_e32 v34, v34
	v_rcp_f32_e32 v35, v35
	v_rcp_f32_e32 v36, v36
	v_rcp_f32_e32 v37, v37
	v_cvt_pk_bf16_f32 v34, v34, v35
	v_cvt_pk_bf16_f32 v35, v36, v37
	v_or_b32_e32 v36, v38, v107
	v_lshlrev_b32_e32 v36, 11, v36
	v_add_co_u32_e32 v36, vcc, v0, v36
	v_addc_co_u32_e32 v37, vcc, 0, v1, vcc
	flat_store_dwordx2 v[36:37], v[34:35]
	ds_read_b128 v[34:37], v98 offset:7616
	s_waitcnt lgkmcnt(0)
	v_mul_f32_e32 v34, 0xbfb8aa3b, v34
	v_mul_f32_e32 v35, 0xbfb8aa3b, v35
	v_mul_f32_e32 v36, 0xbfb8aa3b, v36
	v_mul_f32_e32 v37, 0xbfb8aa3b, v37
	v_exp_f32_e32 v34, v34
	v_exp_f32_e32 v35, v35
	v_exp_f32_e32 v36, v36
	v_exp_f32_e32 v37, v37
	v_add_f32_e32 v34, 1.0, v34
	v_add_f32_e32 v35, 1.0, v35
	v_add_f32_e32 v36, 1.0, v36
	v_add_f32_e32 v37, 1.0, v37
	v_rcp_f32_e32 v34, v34
	v_rcp_f32_e32 v35, v35
	v_rcp_f32_e32 v36, v36
	v_rcp_f32_e32 v37, v37
	v_cvt_pk_bf16_f32 v34, v34, v35
	v_cvt_pk_bf16_f32 v35, v36, v37
	v_or_b32_e32 v36, v38, v108
	v_lshlrev_b32_e32 v36, 11, v36
	v_add_co_u32_e32 v36, vcc, v0, v36
	v_addc_co_u32_e32 v37, vcc, 0, v1, vcc
	flat_store_dwordx2 v[36:37], v[34:35]
	ds_write_b128 v101, v[2:5]
	ds_write_b128 v101, v[6:9] offset:64
	ds_write_b128 v101, v[10:13] offset:128
	ds_write_b128 v101, v[14:17] offset:192
	ds_write_b128 v101, v[18:21] offset:4352
	ds_write_b128 v101, v[22:25] offset:4416
	ds_write_b128 v101, v[26:29] offset:4480
	ds_write_b128 v101, v[30:33] offset:4544
	ds_read_b128 v[2:5], v98
	v_or_b32_e32 v6, 0x60, v100
	v_mov_b32_e32 v20, v132
	v_mov_b32_e32 v7, v131
	v_mov_b32_e32 v11, v131
	s_waitcnt lgkmcnt(0)
	v_mul_f32_e32 v2, 0xbfb8aa3b, v2
	v_mul_f32_e32 v3, 0xbfb8aa3b, v3
	v_mul_f32_e32 v4, 0xbfb8aa3b, v4
	v_mul_f32_e32 v5, 0xbfb8aa3b, v5
	v_exp_f32_e32 v2, v2
	v_exp_f32_e32 v3, v3
	v_exp_f32_e32 v4, v4
	v_exp_f32_e32 v5, v5
	v_add_f32_e32 v2, 1.0, v2
	v_add_f32_e32 v3, 1.0, v3
	v_add_f32_e32 v4, 1.0, v4
	v_add_f32_e32 v5, 1.0, v5
	v_rcp_f32_e32 v2, v2
	v_rcp_f32_e32 v3, v3
	v_rcp_f32_e32 v4, v4
	v_rcp_f32_e32 v5, v5
	v_mov_b32_e32 v19, v131
	v_cvt_pk_bf16_f32 v2, v2, v3
	v_cvt_pk_bf16_f32 v3, v4, v5
	v_or_b32_e32 v4, v6, v99
	v_lshlrev_b32_e32 v4, 11, v4
	v_add_co_u32_e32 v4, vcc, v0, v4
	v_addc_co_u32_e32 v5, vcc, 0, v1, vcc
	flat_store_dwordx2 v[4:5], v[2:3]
	ds_read_b128 v[2:5], v98 offset:1088
	s_waitcnt lgkmcnt(0)
	v_mul_f32_e32 v2, 0xbfb8aa3b, v2
	v_mul_f32_e32 v3, 0xbfb8aa3b, v3
	v_mul_f32_e32 v4, 0xbfb8aa3b, v4
	v_mul_f32_e32 v5, 0xbfb8aa3b, v5
	v_exp_f32_e32 v2, v2
	v_exp_f32_e32 v3, v3
	v_exp_f32_e32 v4, v4
	v_exp_f32_e32 v5, v5
	v_add_f32_e32 v2, 1.0, v2
	v_add_f32_e32 v3, 1.0, v3
	v_add_f32_e32 v4, 1.0, v4
	v_add_f32_e32 v5, 1.0, v5
	v_rcp_f32_e32 v2, v2
	v_rcp_f32_e32 v3, v3
	v_rcp_f32_e32 v4, v4
	v_rcp_f32_e32 v5, v5
	v_cvt_pk_bf16_f32 v2, v2, v3
	v_cvt_pk_bf16_f32 v3, v4, v5
	v_or_b32_e32 v4, v6, v102
	v_lshlrev_b32_e32 v4, 11, v4
	v_add_co_u32_e32 v4, vcc, v0, v4
	v_addc_co_u32_e32 v5, vcc, 0, v1, vcc
	flat_store_dwordx2 v[4:5], v[2:3]
	ds_read_b128 v[2:5], v98 offset:2176
	s_waitcnt lgkmcnt(0)
	v_mul_f32_e32 v2, 0xbfb8aa3b, v2
	v_mul_f32_e32 v3, 0xbfb8aa3b, v3
	v_mul_f32_e32 v4, 0xbfb8aa3b, v4
	v_mul_f32_e32 v5, 0xbfb8aa3b, v5
	v_exp_f32_e32 v2, v2
	v_exp_f32_e32 v3, v3
	v_exp_f32_e32 v4, v4
	v_exp_f32_e32 v5, v5
	v_add_f32_e32 v2, 1.0, v2
	v_add_f32_e32 v3, 1.0, v3
	v_add_f32_e32 v4, 1.0, v4
	v_add_f32_e32 v5, 1.0, v5
	v_rcp_f32_e32 v2, v2
	v_rcp_f32_e32 v3, v3
	v_rcp_f32_e32 v4, v4
	v_rcp_f32_e32 v5, v5
	v_cvt_pk_bf16_f32 v2, v2, v3
	v_cvt_pk_bf16_f32 v3, v4, v5
	v_or_b32_e32 v4, v6, v103
	v_lshlrev_b32_e32 v4, 11, v4
	v_add_co_u32_e32 v4, vcc, v0, v4
	v_addc_co_u32_e32 v5, vcc, 0, v1, vcc
	flat_store_dwordx2 v[4:5], v[2:3]
	ds_read_b128 v[2:5], v98 offset:3264
	s_waitcnt lgkmcnt(0)
	v_mul_f32_e32 v2, 0xbfb8aa3b, v2
	v_mul_f32_e32 v3, 0xbfb8aa3b, v3
	v_mul_f32_e32 v4, 0xbfb8aa3b, v4
	v_mul_f32_e32 v5, 0xbfb8aa3b, v5
	v_exp_f32_e32 v2, v2
	v_exp_f32_e32 v3, v3
	v_exp_f32_e32 v4, v4
	v_exp_f32_e32 v5, v5
	v_add_f32_e32 v2, 1.0, v2
	v_add_f32_e32 v3, 1.0, v3
	v_add_f32_e32 v4, 1.0, v4
	v_add_f32_e32 v5, 1.0, v5
	v_rcp_f32_e32 v2, v2
	v_rcp_f32_e32 v3, v3
	v_rcp_f32_e32 v4, v4
	v_rcp_f32_e32 v5, v5
	v_cvt_pk_bf16_f32 v2, v2, v3
	v_cvt_pk_bf16_f32 v3, v4, v5
	v_or_b32_e32 v4, v6, v104
	v_lshlrev_b32_e32 v4, 11, v4
	v_add_co_u32_e32 v4, vcc, v0, v4
	v_addc_co_u32_e32 v5, vcc, 0, v1, vcc
	flat_store_dwordx2 v[4:5], v[2:3]
	ds_read_b128 v[2:5], v98 offset:4352
	s_waitcnt lgkmcnt(0)
	v_mul_f32_e32 v2, 0xbfb8aa3b, v2
	v_mul_f32_e32 v3, 0xbfb8aa3b, v3
	v_mul_f32_e32 v4, 0xbfb8aa3b, v4
	v_mul_f32_e32 v5, 0xbfb8aa3b, v5
	v_exp_f32_e32 v2, v2
	v_exp_f32_e32 v3, v3
	v_exp_f32_e32 v4, v4
	v_exp_f32_e32 v5, v5
	v_add_f32_e32 v2, 1.0, v2
	v_add_f32_e32 v3, 1.0, v3
	v_add_f32_e32 v4, 1.0, v4
	v_add_f32_e32 v5, 1.0, v5
	v_rcp_f32_e32 v2, v2
	v_rcp_f32_e32 v3, v3
	v_rcp_f32_e32 v4, v4
	v_rcp_f32_e32 v5, v5
	v_cvt_pk_bf16_f32 v2, v2, v3
	v_cvt_pk_bf16_f32 v3, v4, v5
	v_or_b32_e32 v4, v6, v105
	v_lshlrev_b32_e32 v4, 11, v4
	v_add_co_u32_e32 v4, vcc, v0, v4
	v_addc_co_u32_e32 v5, vcc, 0, v1, vcc
	flat_store_dwordx2 v[4:5], v[2:3]
	ds_read_b128 v[2:5], v98 offset:5440
	s_waitcnt lgkmcnt(0)
	v_mul_f32_e32 v2, 0xbfb8aa3b, v2
	v_mul_f32_e32 v3, 0xbfb8aa3b, v3
	v_mul_f32_e32 v4, 0xbfb8aa3b, v4
	v_mul_f32_e32 v5, 0xbfb8aa3b, v5
	v_exp_f32_e32 v2, v2
	v_exp_f32_e32 v3, v3
	v_exp_f32_e32 v4, v4
	v_exp_f32_e32 v5, v5
	v_add_f32_e32 v2, 1.0, v2
	v_add_f32_e32 v3, 1.0, v3
	v_add_f32_e32 v4, 1.0, v4
	v_add_f32_e32 v5, 1.0, v5
	v_rcp_f32_e32 v2, v2
	v_rcp_f32_e32 v3, v3
	v_rcp_f32_e32 v4, v4
	v_rcp_f32_e32 v5, v5
	v_cvt_pk_bf16_f32 v2, v2, v3
	v_cvt_pk_bf16_f32 v3, v4, v5
	v_or_b32_e32 v4, v6, v106
	v_lshlrev_b32_e32 v4, 11, v4
	v_add_co_u32_e32 v4, vcc, v0, v4
	v_addc_co_u32_e32 v5, vcc, 0, v1, vcc
	flat_store_dwordx2 v[4:5], v[2:3]
	ds_read_b128 v[2:5], v98 offset:6528
	s_waitcnt lgkmcnt(0)
	v_mul_f32_e32 v2, 0xbfb8aa3b, v2
	v_mul_f32_e32 v3, 0xbfb8aa3b, v3
	v_mul_f32_e32 v4, 0xbfb8aa3b, v4
	v_mul_f32_e32 v5, 0xbfb8aa3b, v5
	v_exp_f32_e32 v2, v2
	v_exp_f32_e32 v3, v3
	v_exp_f32_e32 v4, v4
	v_exp_f32_e32 v5, v5
	v_add_f32_e32 v2, 1.0, v2
	v_add_f32_e32 v3, 1.0, v3
	v_add_f32_e32 v4, 1.0, v4
	v_add_f32_e32 v5, 1.0, v5
	v_rcp_f32_e32 v2, v2
	v_rcp_f32_e32 v3, v3
	v_rcp_f32_e32 v4, v4
	v_rcp_f32_e32 v5, v5
	v_cvt_pk_bf16_f32 v2, v2, v3
	v_cvt_pk_bf16_f32 v3, v4, v5
	v_or_b32_e32 v4, v6, v107
	v_lshlrev_b32_e32 v4, 11, v4
	v_add_co_u32_e32 v4, vcc, v0, v4
	v_addc_co_u32_e32 v5, vcc, 0, v1, vcc
	flat_store_dwordx2 v[4:5], v[2:3]
	ds_read_b128 v[2:5], v98 offset:7616
	v_mov_b32_e32 v98, v132
	s_waitcnt lgkmcnt(0)
	v_mul_f32_e32 v2, 0xbfb8aa3b, v2
	v_mul_f32_e32 v3, 0xbfb8aa3b, v3
	v_mul_f32_e32 v4, 0xbfb8aa3b, v4
	v_mul_f32_e32 v5, 0xbfb8aa3b, v5
	v_exp_f32_e32 v2, v2
	v_exp_f32_e32 v3, v3
	v_exp_f32_e32 v4, v4
	v_exp_f32_e32 v5, v5
	v_add_f32_e32 v2, 1.0, v2
	v_add_f32_e32 v3, 1.0, v3
	v_add_f32_e32 v4, 1.0, v4
	v_add_f32_e32 v5, 1.0, v5
	v_rcp_f32_e32 v2, v2
	v_rcp_f32_e32 v3, v3
	v_rcp_f32_e32 v4, v4
	v_rcp_f32_e32 v5, v5
	v_cvt_pk_bf16_f32 v2, v2, v3
	v_cvt_pk_bf16_f32 v3, v4, v5
	v_or_b32_e32 v4, v6, v108
	v_ashrrev_i32_e32 v5, 31, v4
	v_lshlrev_b64 v[4:5], 11, v[4:5]
	v_add_co_u32_e32 v0, vcc, v0, v4
	v_addc_co_u32_e32 v1, vcc, v1, v5, vcc
	flat_store_dwordx2 v[0:1], v[2:3]
	v_mov_b32_e32 v0, s3
	ds_read_b128 v[0:3], v0
	s_waitcnt lgkmcnt(0)
	v_lshl_add_u64 v[4:5], v[2:3], 0, s[42:43]
	s_lshl_b64 s[42:43], s[30:31], 10
	v_lshl_add_u64 v[2:3], v[2:3], 0, s[42:43]
	v_lshl_add_u64 v[16:17], v[2:3], 0, s[12:13]
	v_lshlrev_b32_e32 v2, 4, v20
	v_and_b32_e32 v3, 32, v20
	v_bitop3_b32 v3, v2, v3, 48 bitop3:0x6c
	v_lshl_add_u64 v[14:15], v[4:5], 0, s[10:11]
	v_lshrrev_b32_e32 v5, 1, v20
	v_lshrrev_b32_e32 v3, 1, v3
	v_bfe_u32 v4, v20, 2, 4
	v_and_or_b32 v3, v5, 32, v3
	v_lshrrev_b32_e32 v5, 3, v20
	v_and_or_b32 v5, v5, s50, v4
	v_lshl_or_b32 v130, v5, 9, v3
	v_add_u32_e32 v5, 0x2000, v2
	v_lshrrev_b32_e32 v5, 7, v5
	v_and_or_b32 v5, v5, s50, v4
	v_lshl_or_b32 v6, v5, 9, v3
	v_add_u32_e32 v5, 0x4000, v2
	v_and_b32_e32 v21, 0xfffffc00, v2
	v_lshrrev_b32_e32 v5, 7, v5
	v_add_u32_e32 v2, 0x6000, v2
	v_and_or_b32 v5, v5, s50, v4
	v_lshrrev_b32_e32 v2, 7, v2
	v_add_u32_e32 v45, 0, v21
	v_lshl_or_b32 v10, v5, 9, v3
	v_and_or_b32 v2, v2, s50, v4
	v_add_u32_e32 v44, 0x8000, v45
	v_lshlrev_b64 v[4:5], 1, v[130:131]
	v_readfirstlane_b32 s60, v45
	v_lshl_or_b32 v18, v2, 9, v3
	v_add_co_u32_e32 v2, vcc, v14, v4
	v_addc_co_u32_e32 v3, vcc, v15, v5, vcc
	s_mov_b32 m0, s60
	v_readfirstlane_b32 s58, v44
	v_add_u32_e32 v46, 0x2000, v45
	global_load_lds_dwordx4 v[2:3], off
	v_add_co_u32_e32 v4, vcc, v16, v4
	v_addc_co_u32_e32 v5, vcc, v17, v5, vcc
	s_mov_b32 m0, s58
	v_lshlrev_b64 v[8:9], 1, v[6:7]
	v_readfirstlane_b32 s59, v46
	v_add_u32_e32 v47, 0xa000, v45
	global_load_lds_dwordx4 v[4:5], off
	v_add_co_u32_e32 v6, vcc, v14, v8
	v_addc_co_u32_e32 v7, vcc, v15, v9, vcc
	s_mov_b32 m0, s59
	v_readfirstlane_b32 s61, v47
	v_add_u32_e32 v48, 0x4000, v45
	global_load_lds_dwordx4 v[6:7], off
	v_add_co_u32_e32 v8, vcc, v16, v8
	v_addc_co_u32_e32 v9, vcc, v17, v9, vcc
	s_mov_b32 m0, s61
	v_lshlrev_b64 v[12:13], 1, v[10:11]
	v_readfirstlane_b32 s62, v48
	v_add_u32_e32 v49, 0xc000, v45
	v_lshlrev_b64 v[18:19], 1, v[18:19]
	v_and_b32_e32 v22, 15, v20
	global_load_lds_dwordx4 v[8:9], off
	v_add_co_u32_e32 v10, vcc, v14, v12
	v_addc_co_u32_e32 v11, vcc, v15, v13, vcc
	s_mov_b32 m0, s62
	v_add_co_u32_e32 v12, vcc, v16, v12
	v_addc_co_u32_e32 v13, vcc, v17, v13, vcc
	v_readfirstlane_b32 s63, v49
	v_add_co_u32_e32 v14, vcc, v14, v18
	v_addc_co_u32_e32 v15, vcc, v15, v19, vcc
	v_add_u32_e32 v50, 0x6000, v45
	v_add_co_u32_e32 v16, vcc, v16, v18
	v_addc_co_u32_e32 v17, vcc, v17, v19, vcc
	v_lshlrev_b32_e32 v19, 2, v20
	global_load_lds_dwordx4 v[10:11], off
	s_mov_b32 m0, s63
	v_readfirstlane_b32 s64, v50
	v_add_u32_e32 v51, 0xe000, v45
	v_and_b32_e32 v23, 48, v20
	v_lshlrev_b32_e32 v18, 6, v22
	v_and_b32_e32 v22, 32, v19
	global_load_lds_dwordx4 v[12:13], off
	s_mov_b32 m0, s64
	v_readfirstlane_b32 s65, v51
	v_bitop3_b32 v96, v18, v22, v23 bitop3:0x36
	v_lshlrev_b32_e32 v18, 7, v20
	v_add_u32_e32 v37, s46, v21
	global_load_lds_dwordx4 v[14:15], off
	s_mov_b32 m0, s65
	v_and_b32_e32 v97, 0x6000, v18
	v_lshlrev_b32_e32 v18, 6, v20
	v_add_u32_e32 v36, s47, v21
	v_readfirstlane_b32 s53, v37
	global_load_lds_dwordx4 v[16:17], off
	v_and_b32_e32 v99, 0xffffc000, v18
	v_and_b32_e32 v20, 0x3c0, v18
	v_lshl_add_u64 v[18:19], v[2:3], 0, s[6:7]
	s_mov_b32 m0, s53
	v_readfirstlane_b32 s0, v36
	v_add_u32_e32 v38, 0x2000, v37
	s_waitcnt vmcnt(0)
	s_waitcnt vmcnt(0) lgkmcnt(0)
	s_barrier
	global_load_lds_dwordx4 v[18:19], off
	v_lshl_add_u64 v[18:19], v[4:5], 0, s[6:7]
	s_mov_b32 m0, s0
	v_readfirstlane_b32 s42, v38
	v_add_u32_e32 v39, 0x2000, v36
	global_load_lds_dwordx4 v[18:19], off
	v_lshl_add_u64 v[18:19], v[6:7], 0, s[6:7]
	s_mov_b32 m0, s42
	v_readfirstlane_b32 s43, v39
	v_add_u32_e32 v40, 0x4000, v37
	global_load_lds_dwordx4 v[18:19], off
	v_lshl_add_u64 v[18:19], v[8:9], 0, s[6:7]
	s_mov_b32 m0, s43
	v_readfirstlane_b32 s54, v40
	v_add_u32_e32 v41, 0x4000, v36
	global_load_lds_dwordx4 v[18:19], off
	v_lshl_add_u64 v[18:19], v[10:11], 0, s[6:7]
	s_mov_b32 m0, s54
	v_readfirstlane_b32 s55, v41
	v_add_u32_e32 v42, 0x6000, v37
	global_load_lds_dwordx4 v[18:19], off
	v_lshl_add_u64 v[18:19], v[12:13], 0, s[6:7]
	s_mov_b32 m0, s55
	v_readfirstlane_b32 s56, v42
	v_add_u32_e32 v43, 0x6000, v36
	global_load_lds_dwordx4 v[18:19], off
	v_lshl_add_u64 v[18:19], v[14:15], 0, s[6:7]
	s_mov_b32 m0, s56
	v_readfirstlane_b32 s57, v43
	global_load_lds_dwordx4 v[18:19], off
	v_lshl_add_u64 v[18:19], v[16:17], 0, s[6:7]
	s_mov_b32 m0, s57
	v_add_u32_e32 v129, 0, v96
	global_load_lds_dwordx4 v[18:19], off
	v_add_u32_e32 v18, v129, v97
	ds_read_b128 v[24:27], v18 offset:32768
	ds_read_b128 v[56:59], v18 offset:34816
	ds_read_b128 v[64:67], v18 offset:36864
	ds_read_b128 v[72:75], v18 offset:38912
	v_bitop3_b32 v130, v20, v22, v23 bitop3:0x36
	v_add_u32_e32 v23, 0, v130
	v_or_b32_e32 v222, 0x3000, v99
	v_add_u32_e32 v20, v23, v222
	ds_read_b128 v[32:35], v20
	v_or_b32_e32 v223, 0x2800, v99
	v_add_u32_e32 v21, v23, v223
	s_waitcnt lgkmcnt(0)
	v_mfma_f32_16x16x32_bf16 v[76:79], v[24:27], v[32:35], 0
	v_or_b32_e32 v128, 0x3800, v99
	v_or_b32_e32 v218, 0x2000, v99
	v_or_b32_e32 v219, 0x1000, v99
	v_mfma_f32_16x16x32_bf16 v[80:83], v[56:59], v[32:35], 0
	v_or_b32_e32 v220, 0x1800, v99
	v_add_u32_e32 v19, v23, v128
	v_add_u32_e32 v22, v23, v218
	v_mfma_f32_16x16x32_bf16 v[84:87], v[64:67], v[32:35], 0
	ds_read_b128 v[28:31], v19
	ds_read_b128 v[112:115], v22
	v_mfma_f32_16x16x32_bf16 v[88:91], v[72:75], v[32:35], 0
	ds_read_b128 v[32:35], v21
	s_waitcnt lgkmcnt(0)
	v_mfma_f32_16x16x32_bf16 v[92:95], v[24:27], v[32:35], 0
	v_mfma_f32_16x16x32_bf16 v[100:103], v[56:59], v[32:35], 0
	v_mfma_f32_16x16x32_bf16 v[104:107], v[64:67], v[32:35], 0
	v_mfma_f32_16x16x32_bf16 v[108:111], v[72:75], v[32:35], 0
	v_add_u32_e32 v32, v129, v99
	v_or_b32_e32 v129, 0x800, v99
	v_add_u32_e32 v33, v23, v129
	v_add_u32_e32 v34, v23, v219
	v_add_u32_e32 v35, v23, v220
	ds_read_b128 v[134:137], v32
	ds_read_b128 v[150:153], v33
	ds_read_b128 v[166:169], v34
	ds_read_b128 v[182:185], v35
	s_waitcnt lgkmcnt(0)
	v_mfma_f32_16x16x32_bf16 v[178:181], v[64:67], v[166:169], 0
	v_mfma_f32_16x16x32_bf16 v[162:165], v[64:67], v[150:153], 0
	v_mfma_f32_16x16x32_bf16 v[146:149], v[64:67], v[134:137], 0
	v_mfma_f32_16x16x32_bf16 v[68:71], v[64:67], v[28:31], 0
	v_mfma_f32_16x16x32_bf16 v[124:127], v[64:67], v[112:115], 0
	v_mfma_f32_16x16x32_bf16 v[64:67], v[64:67], v[182:185], 0
	v_mfma_f32_16x16x32_bf16 v[174:177], v[56:59], v[166:169], 0
	v_mfma_f32_16x16x32_bf16 v[158:161], v[56:59], v[150:153], 0
	v_mfma_f32_16x16x32_bf16 v[142:145], v[56:59], v[134:137], 0
	v_mfma_f32_16x16x32_bf16 v[60:63], v[56:59], v[28:31], 0
	v_mfma_f32_16x16x32_bf16 v[120:123], v[56:59], v[112:115], 0
	v_mfma_f32_16x16x32_bf16 v[56:59], v[56:59], v[182:185], 0
	v_mfma_f32_16x16x32_bf16 v[170:173], v[24:27], v[166:169], 0
	v_mfma_f32_16x16x32_bf16 v[154:157], v[24:27], v[150:153], 0
	v_mfma_f32_16x16x32_bf16 v[138:141], v[24:27], v[134:137], 0
	v_mfma_f32_16x16x32_bf16 v[52:55], v[24:27], v[28:31], 0
	v_mfma_f32_16x16x32_bf16 v[116:119], v[24:27], v[112:115], 0
	v_mfma_f32_16x16x32_bf16 v[24:27], v[24:27], v[182:185], 0
	v_mfma_f32_16x16x32_bf16 v[166:169], v[72:75], v[166:169], 0
	v_mfma_f32_16x16x32_bf16 v[150:153], v[72:75], v[150:153], 0
	v_mfma_f32_16x16x32_bf16 v[134:137], v[72:75], v[134:137], 0
	v_mfma_f32_16x16x32_bf16 v[28:31], v[72:75], v[28:31], 0
	v_mfma_f32_16x16x32_bf16 v[112:115], v[72:75], v[112:115], 0
	v_mfma_f32_16x16x32_bf16 v[72:75], v[72:75], v[182:185], 0
	ds_read_b128 v[182:185], v18 offset:33792
	ds_read_b128 v[186:189], v18 offset:35840
	ds_read_b128 v[190:193], v18 offset:37888
	ds_read_b128 v[198:201], v18 offset:39936
	ds_read_b128 v[194:197], v32 offset:1024
	ds_read_b128 v[202:205], v33 offset:1024
	ds_read_b128 v[206:209], v34 offset:1024
	ds_read_b128 v[210:213], v35 offset:1024
	s_waitcnt lgkmcnt(0)
	v_mfma_f32_16x16x32_bf16 v[138:141], v[182:185], v[194:197], v[138:141]
	v_mfma_f32_16x16x32_bf16 v[142:145], v[186:189], v[194:197], v[142:145]
	v_mfma_f32_16x16x32_bf16 v[146:149], v[190:193], v[194:197], v[146:149]
	v_mfma_f32_16x16x32_bf16 v[134:137], v[198:201], v[194:197], v[134:137]
	ds_read_b128 v[194:197], v22 offset:1024
	v_mfma_f32_16x16x32_bf16 v[154:157], v[182:185], v[202:205], v[154:157]
	v_mfma_f32_16x16x32_bf16 v[158:161], v[186:189], v[202:205], v[158:161]
	v_mfma_f32_16x16x32_bf16 v[162:165], v[190:193], v[202:205], v[162:165]
	v_mfma_f32_16x16x32_bf16 v[150:153], v[198:201], v[202:205], v[150:153]
	ds_read_b128 v[202:205], v21 offset:1024
	v_mfma_f32_16x16x32_bf16 v[170:173], v[182:185], v[206:209], v[170:173]
	v_mfma_f32_16x16x32_bf16 v[174:177], v[186:189], v[206:209], v[174:177]
	v_mfma_f32_16x16x32_bf16 v[178:181], v[190:193], v[206:209], v[178:181]
	v_mfma_f32_16x16x32_bf16 v[166:169], v[198:201], v[206:209], v[166:169]
	ds_read_b128 v[206:209], v20 offset:1024
	v_mfma_f32_16x16x32_bf16 v[214:217], v[182:185], v[210:213], v[24:27]
	v_mfma_f32_16x16x32_bf16 v[56:59], v[186:189], v[210:213], v[56:59]
	v_mfma_f32_16x16x32_bf16 v[64:67], v[190:193], v[210:213], v[64:67]
	v_mfma_f32_16x16x32_bf16 v[72:75], v[198:201], v[210:213], v[72:75]
	ds_read_b128 v[24:27], v19 offset:1024
	s_waitcnt lgkmcnt(0)
	v_mfma_f32_16x16x32_bf16 v[116:119], v[182:185], v[194:197], v[116:119]
	v_mfma_f32_16x16x32_bf16 v[120:123], v[186:189], v[194:197], v[120:123]
	v_mfma_f32_16x16x32_bf16 v[124:127], v[190:193], v[194:197], v[124:127]
	v_mfma_f32_16x16x32_bf16 v[112:115], v[198:201], v[194:197], v[112:115]
	v_mfma_f32_16x16x32_bf16 v[92:95], v[182:185], v[202:205], v[92:95]
	v_mfma_f32_16x16x32_bf16 v[100:103], v[186:189], v[202:205], v[100:103]
	v_mfma_f32_16x16x32_bf16 v[104:107], v[190:193], v[202:205], v[104:107]
	v_mfma_f32_16x16x32_bf16 v[108:111], v[198:201], v[202:205], v[108:111]
	v_mfma_f32_16x16x32_bf16 v[76:79], v[182:185], v[206:209], v[76:79]
	v_mfma_f32_16x16x32_bf16 v[80:83], v[186:189], v[206:209], v[80:83]
	v_mfma_f32_16x16x32_bf16 v[84:87], v[190:193], v[206:209], v[84:87]
	v_mfma_f32_16x16x32_bf16 v[88:91], v[198:201], v[206:209], v[88:91]
	v_mfma_f32_16x16x32_bf16 v[52:55], v[182:185], v[24:27], v[52:55]
	v_mfma_f32_16x16x32_bf16 v[60:63], v[186:189], v[24:27], v[60:63]
	v_mfma_f32_16x16x32_bf16 v[68:71], v[190:193], v[24:27], v[68:71]
	v_mfma_f32_16x16x32_bf16 v[182:185], v[198:201], v[24:27], v[28:31]
	s_mov_b32 m0, s60
	v_lshl_add_u64 v[24:25], v[2:3], 0, s[14:15]
	s_waitcnt vmcnt(0)
	s_waitcnt vmcnt(0)
	s_barrier
	global_load_lds_dwordx4 v[24:25], off
	v_lshl_add_u64 v[24:25], v[4:5], 0, s[14:15]
	s_mov_b32 m0, s58
	v_add3_u32 v23, s47, v96, v97
	global_load_lds_dwordx4 v[24:25], off
	v_lshl_add_u64 v[24:25], v[6:7], 0, s[14:15]
	s_mov_b32 m0, s59
	s_nop 0
	global_load_lds_dwordx4 v[24:25], off
	v_lshl_add_u64 v[24:25], v[8:9], 0, s[14:15]
	s_mov_b32 m0, s61
	s_nop 0
	global_load_lds_dwordx4 v[24:25], off
	v_lshl_add_u64 v[24:25], v[10:11], 0, s[14:15]
	s_mov_b32 m0, s62
	s_nop 0
	global_load_lds_dwordx4 v[24:25], off
	v_lshl_add_u64 v[24:25], v[12:13], 0, s[14:15]
	s_mov_b32 m0, s63
	s_nop 0
	global_load_lds_dwordx4 v[24:25], off
	v_lshl_add_u64 v[24:25], v[14:15], 0, s[14:15]
	s_mov_b32 m0, s64
	s_nop 0
	global_load_lds_dwordx4 v[24:25], off
	v_lshl_add_u64 v[24:25], v[16:17], 0, s[14:15]
	s_mov_b32 m0, s65
	s_nop 0
	global_load_lds_dwordx4 v[24:25], off
	ds_read_b128 v[186:189], v23
	ds_read_b128 v[190:193], v23 offset:2048
	ds_read_b128 v[194:197], v23 offset:4096
	ds_read_b128 v[198:201], v23 offset:6144
	v_add3_u32 v24, s46, v96, v99
	v_add_u32_e32 v96, s46, v130
	ds_read_b128 v[28:31], v24
	v_add_u32_e32 v25, v96, v129
	v_add_u32_e32 v26, v96, v219
	v_add_u32_e32 v27, v96, v220
	ds_read_b128 v[202:205], v25
	ds_read_b128 v[206:209], v26
	ds_read_b128 v[210:213], v27
	s_waitcnt lgkmcnt(0)
	v_mfma_f32_16x16x32_bf16 v[138:141], v[186:189], v[28:31], v[138:141]
	v_mfma_f32_16x16x32_bf16 v[142:145], v[190:193], v[28:31], v[142:145]
	v_mfma_f32_16x16x32_bf16 v[146:149], v[194:197], v[28:31], v[146:149]
	v_mfma_f32_16x16x32_bf16 v[134:137], v[198:201], v[28:31], v[134:137]
	v_add_u32_e32 v28, v96, v218
	v_add_u32_e32 v29, v96, v223
	v_add_u32_e32 v30, v96, v222
	v_add_u32_e32 v31, v96, v128
	ds_read_b128 v[218:221], v28
	v_mfma_f32_16x16x32_bf16 v[154:157], v[186:189], v[202:205], v[154:157]
	v_mfma_f32_16x16x32_bf16 v[158:161], v[190:193], v[202:205], v[158:161]
	v_mfma_f32_16x16x32_bf16 v[162:165], v[194:197], v[202:205], v[162:165]
	v_mfma_f32_16x16x32_bf16 v[150:153], v[198:201], v[202:205], v[150:153]
	ds_read_b128 v[202:205], v29
	v_mfma_f32_16x16x32_bf16 v[170:173], v[186:189], v[206:209], v[170:173]
	v_mfma_f32_16x16x32_bf16 v[174:177], v[190:193], v[206:209], v[174:177]
	v_mfma_f32_16x16x32_bf16 v[178:181], v[194:197], v[206:209], v[178:181]
	v_mfma_f32_16x16x32_bf16 v[166:169], v[198:201], v[206:209], v[166:169]
	ds_read_b128 v[206:209], v30
	v_mfma_f32_16x16x32_bf16 v[214:217], v[186:189], v[210:213], v[214:217]
	v_mfma_f32_16x16x32_bf16 v[56:59], v[190:193], v[210:213], v[56:59]
	v_mfma_f32_16x16x32_bf16 v[64:67], v[194:197], v[210:213], v[64:67]
	v_mfma_f32_16x16x32_bf16 v[72:75], v[198:201], v[210:213], v[72:75]
	ds_read_b128 v[210:213], v31
	s_waitcnt lgkmcnt(0)
	v_mfma_f32_16x16x32_bf16 v[116:119], v[186:189], v[218:221], v[116:119]
	v_mfma_f32_16x16x32_bf16 v[120:123], v[190:193], v[218:221], v[120:123]
	v_mfma_f32_16x16x32_bf16 v[124:127], v[194:197], v[218:221], v[124:127]
	v_mfma_f32_16x16x32_bf16 v[112:115], v[198:201], v[218:221], v[112:115]
	v_mfma_f32_16x16x32_bf16 v[92:95], v[186:189], v[202:205], v[92:95]
	v_mfma_f32_16x16x32_bf16 v[100:103], v[190:193], v[202:205], v[100:103]
	v_mfma_f32_16x16x32_bf16 v[104:107], v[194:197], v[202:205], v[104:107]
	v_mfma_f32_16x16x32_bf16 v[108:111], v[198:201], v[202:205], v[108:111]
	v_mfma_f32_16x16x32_bf16 v[76:79], v[186:189], v[206:209], v[76:79]
	v_mfma_f32_16x16x32_bf16 v[80:83], v[190:193], v[206:209], v[80:83]
	v_mfma_f32_16x16x32_bf16 v[84:87], v[194:197], v[206:209], v[84:87]
	v_mfma_f32_16x16x32_bf16 v[88:91], v[198:201], v[206:209], v[88:91]
	v_mfma_f32_16x16x32_bf16 v[52:55], v[186:189], v[210:213], v[52:55]
	v_mfma_f32_16x16x32_bf16 v[60:63], v[190:193], v[210:213], v[60:63]
	v_mfma_f32_16x16x32_bf16 v[68:71], v[194:197], v[210:213], v[68:71]
	v_mfma_f32_16x16x32_bf16 v[182:185], v[198:201], v[210:213], v[182:185]
	ds_read_b128 v[186:189], v23 offset:1024
	ds_read_b128 v[190:193], v23 offset:3072
	ds_read_b128 v[194:197], v23 offset:5120
	ds_read_b128 v[202:205], v23 offset:7168
	ds_read_b128 v[198:201], v24 offset:1024
	ds_read_b128 v[206:209], v25 offset:1024
	ds_read_b128 v[210:213], v26 offset:1024
	ds_read_b128 v[218:221], v27 offset:1024
	s_waitcnt lgkmcnt(0)
	v_mfma_f32_16x16x32_bf16 v[138:141], v[186:189], v[198:201], v[138:141]
	v_mfma_f32_16x16x32_bf16 v[142:145], v[190:193], v[198:201], v[142:145]
	v_mfma_f32_16x16x32_bf16 v[146:149], v[194:197], v[198:201], v[146:149]
	v_mfma_f32_16x16x32_bf16 v[134:137], v[202:205], v[198:201], v[134:137]
	ds_read_b128 v[198:201], v28 offset:1024
	v_mfma_f32_16x16x32_bf16 v[154:157], v[186:189], v[206:209], v[154:157]
	v_mfma_f32_16x16x32_bf16 v[158:161], v[190:193], v[206:209], v[158:161]
	v_mfma_f32_16x16x32_bf16 v[162:165], v[194:197], v[206:209], v[162:165]
	v_mfma_f32_16x16x32_bf16 v[150:153], v[202:205], v[206:209], v[150:153]
	ds_read_b128 v[206:209], v29 offset:1024
	v_mfma_f32_16x16x32_bf16 v[170:173], v[186:189], v[210:213], v[170:173]
	v_mfma_f32_16x16x32_bf16 v[174:177], v[190:193], v[210:213], v[174:177]
	v_mfma_f32_16x16x32_bf16 v[178:181], v[194:197], v[210:213], v[178:181]
	v_mfma_f32_16x16x32_bf16 v[166:169], v[202:205], v[210:213], v[166:169]
	ds_read_b128 v[210:213], v30 offset:1024
	v_mfma_f32_16x16x32_bf16 v[214:217], v[186:189], v[218:221], v[214:217]
	v_mfma_f32_16x16x32_bf16 v[56:59], v[190:193], v[218:221], v[56:59]
	v_mfma_f32_16x16x32_bf16 v[64:67], v[194:197], v[218:221], v[64:67]
	v_mfma_f32_16x16x32_bf16 v[72:75], v[202:205], v[218:221], v[72:75]
	ds_read_b128 v[218:221], v31 offset:1024
	s_waitcnt lgkmcnt(0)
	v_mfma_f32_16x16x32_bf16 v[116:119], v[186:189], v[198:201], v[116:119]
	v_mfma_f32_16x16x32_bf16 v[120:123], v[190:193], v[198:201], v[120:123]
	v_mfma_f32_16x16x32_bf16 v[124:127], v[194:197], v[198:201], v[124:127]
	v_mfma_f32_16x16x32_bf16 v[112:115], v[202:205], v[198:201], v[112:115]
	v_mfma_f32_16x16x32_bf16 v[92:95], v[186:189], v[206:209], v[92:95]
	v_mfma_f32_16x16x32_bf16 v[100:103], v[190:193], v[206:209], v[100:103]
	v_mfma_f32_16x16x32_bf16 v[104:107], v[194:197], v[206:209], v[104:107]
	v_mfma_f32_16x16x32_bf16 v[108:111], v[202:205], v[206:209], v[108:111]
	v_mfma_f32_16x16x32_bf16 v[76:79], v[186:189], v[210:213], v[76:79]
	v_mfma_f32_16x16x32_bf16 v[80:83], v[190:193], v[210:213], v[80:83]
	v_mfma_f32_16x16x32_bf16 v[84:87], v[194:197], v[210:213], v[84:87]
	v_mfma_f32_16x16x32_bf16 v[88:91], v[202:205], v[210:213], v[88:91]
	v_mfma_f32_16x16x32_bf16 v[52:55], v[186:189], v[218:221], v[52:55]
	v_mfma_f32_16x16x32_bf16 v[60:63], v[190:193], v[218:221], v[60:63]
	v_mfma_f32_16x16x32_bf16 v[68:71], v[194:197], v[218:221], v[68:71]
	v_mfma_f32_16x16x32_bf16 v[182:185], v[202:205], v[218:221], v[182:185]
	s_mov_b32 m0, s53
	v_lshl_add_u64 v[96:97], v[2:3], 0, s[16:17]
	s_waitcnt vmcnt(0)
	s_waitcnt vmcnt(0)
	s_barrier
	global_load_lds_dwordx4 v[96:97], off
	v_lshl_add_u64 v[96:97], v[4:5], 0, s[16:17]
	s_mov_b32 m0, s0
	s_nop 0
	global_load_lds_dwordx4 v[96:97], off
	v_lshl_add_u64 v[96:97], v[6:7], 0, s[16:17]
	s_mov_b32 m0, s42
	s_nop 0
	global_load_lds_dwordx4 v[96:97], off
	v_lshl_add_u64 v[96:97], v[8:9], 0, s[16:17]
	s_mov_b32 m0, s43
	s_nop 0
	global_load_lds_dwordx4 v[96:97], off
	v_lshl_add_u64 v[96:97], v[10:11], 0, s[16:17]
	s_mov_b32 m0, s54
	s_nop 0
	global_load_lds_dwordx4 v[96:97], off
	v_lshl_add_u64 v[96:97], v[12:13], 0, s[16:17]
	s_mov_b32 m0, s55
	s_nop 0
	global_load_lds_dwordx4 v[96:97], off
	v_lshl_add_u64 v[96:97], v[14:15], 0, s[16:17]
	s_mov_b32 m0, s56
	s_nop 0
	global_load_lds_dwordx4 v[96:97], off
	v_lshl_add_u64 v[96:97], v[16:17], 0, s[16:17]
	s_mov_b32 m0, s57
	s_nop 0
	global_load_lds_dwordx4 v[96:97], off
	ds_read_b128 v[186:189], v18 offset:32768
	ds_read_b128 v[190:193], v18 offset:34816
	ds_read_b128 v[194:197], v18 offset:36864
	ds_read_b128 v[202:205], v18 offset:38912
	ds_read_b128 v[198:201], v32
	ds_read_b128 v[206:209], v33
	ds_read_b128 v[210:213], v34
	ds_read_b128 v[218:221], v35
	s_waitcnt lgkmcnt(0)
	v_mfma_f32_16x16x32_bf16 v[138:141], v[186:189], v[198:201], v[138:141]
	v_mfma_f32_16x16x32_bf16 v[142:145], v[190:193], v[198:201], v[142:145]
	v_mfma_f32_16x16x32_bf16 v[146:149], v[194:197], v[198:201], v[146:149]
	v_mfma_f32_16x16x32_bf16 v[134:137], v[202:205], v[198:201], v[134:137]
	ds_read_b128 v[198:201], v22
	v_mfma_f32_16x16x32_bf16 v[154:157], v[186:189], v[206:209], v[154:157]
	v_mfma_f32_16x16x32_bf16 v[158:161], v[190:193], v[206:209], v[158:161]
	v_mfma_f32_16x16x32_bf16 v[162:165], v[194:197], v[206:209], v[162:165]
	v_mfma_f32_16x16x32_bf16 v[150:153], v[202:205], v[206:209], v[150:153]
	ds_read_b128 v[206:209], v21
	v_mfma_f32_16x16x32_bf16 v[170:173], v[186:189], v[210:213], v[170:173]
	v_mfma_f32_16x16x32_bf16 v[174:177], v[190:193], v[210:213], v[174:177]
	v_mfma_f32_16x16x32_bf16 v[178:181], v[194:197], v[210:213], v[178:181]
	v_mfma_f32_16x16x32_bf16 v[166:169], v[202:205], v[210:213], v[166:169]
	ds_read_b128 v[210:213], v20
	v_mfma_f32_16x16x32_bf16 v[214:217], v[186:189], v[218:221], v[214:217]
	v_mfma_f32_16x16x32_bf16 v[56:59], v[190:193], v[218:221], v[56:59]
	v_mfma_f32_16x16x32_bf16 v[64:67], v[194:197], v[218:221], v[64:67]
	v_mfma_f32_16x16x32_bf16 v[72:75], v[202:205], v[218:221], v[72:75]
	ds_read_b128 v[218:221], v19
	s_waitcnt lgkmcnt(0)
	v_mfma_f32_16x16x32_bf16 v[116:119], v[186:189], v[198:201], v[116:119]
	v_mfma_f32_16x16x32_bf16 v[120:123], v[190:193], v[198:201], v[120:123]
	v_mfma_f32_16x16x32_bf16 v[124:127], v[194:197], v[198:201], v[124:127]
	v_mfma_f32_16x16x32_bf16 v[112:115], v[202:205], v[198:201], v[112:115]
	v_mfma_f32_16x16x32_bf16 v[92:95], v[186:189], v[206:209], v[92:95]
	v_mfma_f32_16x16x32_bf16 v[100:103], v[190:193], v[206:209], v[100:103]
	v_mfma_f32_16x16x32_bf16 v[104:107], v[194:197], v[206:209], v[104:107]
	v_mfma_f32_16x16x32_bf16 v[108:111], v[202:205], v[206:209], v[108:111]
	v_mfma_f32_16x16x32_bf16 v[76:79], v[186:189], v[210:213], v[76:79]
	v_mfma_f32_16x16x32_bf16 v[80:83], v[190:193], v[210:213], v[80:83]
	v_mfma_f32_16x16x32_bf16 v[84:87], v[194:197], v[210:213], v[84:87]
	v_mfma_f32_16x16x32_bf16 v[88:91], v[202:205], v[210:213], v[88:91]
	v_mfma_f32_16x16x32_bf16 v[52:55], v[186:189], v[218:221], v[52:55]
	v_mfma_f32_16x16x32_bf16 v[60:63], v[190:193], v[218:221], v[60:63]
	v_mfma_f32_16x16x32_bf16 v[68:71], v[194:197], v[218:221], v[68:71]
	v_mfma_f32_16x16x32_bf16 v[182:185], v[202:205], v[218:221], v[182:185]
	ds_read_b128 v[186:189], v18 offset:33792
	ds_read_b128 v[190:193], v18 offset:35840
	ds_read_b128 v[194:197], v18 offset:37888
	ds_read_b128 v[202:205], v18 offset:39936
	ds_read_b128 v[198:201], v32 offset:1024
	ds_read_b128 v[206:209], v33 offset:1024
	ds_read_b128 v[210:213], v34 offset:1024
	ds_read_b128 v[218:221], v35 offset:1024
	s_waitcnt lgkmcnt(0)
	v_mfma_f32_16x16x32_bf16 v[138:141], v[186:189], v[198:201], v[138:141]
	v_mfma_f32_16x16x32_bf16 v[142:145], v[190:193], v[198:201], v[142:145]
	v_mfma_f32_16x16x32_bf16 v[146:149], v[194:197], v[198:201], v[146:149]
	v_mfma_f32_16x16x32_bf16 v[134:137], v[202:205], v[198:201], v[134:137]
	ds_read_b128 v[198:201], v22 offset:1024
	v_mfma_f32_16x16x32_bf16 v[154:157], v[186:189], v[206:209], v[154:157]
	v_mfma_f32_16x16x32_bf16 v[158:161], v[190:193], v[206:209], v[158:161]
	v_mfma_f32_16x16x32_bf16 v[162:165], v[194:197], v[206:209], v[162:165]
	v_mfma_f32_16x16x32_bf16 v[150:153], v[202:205], v[206:209], v[150:153]
	ds_read_b128 v[206:209], v21 offset:1024
	v_mfma_f32_16x16x32_bf16 v[170:173], v[186:189], v[210:213], v[170:173]
	v_mfma_f32_16x16x32_bf16 v[174:177], v[190:193], v[210:213], v[174:177]
	v_mfma_f32_16x16x32_bf16 v[178:181], v[194:197], v[210:213], v[178:181]
	v_mfma_f32_16x16x32_bf16 v[166:169], v[202:205], v[210:213], v[166:169]
	ds_read_b128 v[210:213], v20 offset:1024
	v_mfma_f32_16x16x32_bf16 v[214:217], v[186:189], v[218:221], v[214:217]
	v_mfma_f32_16x16x32_bf16 v[56:59], v[190:193], v[218:221], v[56:59]
	v_mfma_f32_16x16x32_bf16 v[64:67], v[194:197], v[218:221], v[64:67]
	v_mfma_f32_16x16x32_bf16 v[72:75], v[202:205], v[218:221], v[72:75]
	ds_read_b128 v[218:221], v19 offset:1024
	s_waitcnt lgkmcnt(0)
	v_mfma_f32_16x16x32_bf16 v[116:119], v[186:189], v[198:201], v[116:119]
	v_mfma_f32_16x16x32_bf16 v[120:123], v[190:193], v[198:201], v[120:123]
	v_mfma_f32_16x16x32_bf16 v[124:127], v[194:197], v[198:201], v[124:127]
	v_mfma_f32_16x16x32_bf16 v[112:115], v[202:205], v[198:201], v[112:115]
	v_mfma_f32_16x16x32_bf16 v[92:95], v[186:189], v[206:209], v[92:95]
	v_mfma_f32_16x16x32_bf16 v[100:103], v[190:193], v[206:209], v[100:103]
	v_mfma_f32_16x16x32_bf16 v[104:107], v[194:197], v[206:209], v[104:107]
	v_mfma_f32_16x16x32_bf16 v[108:111], v[202:205], v[206:209], v[108:111]
	v_mfma_f32_16x16x32_bf16 v[76:79], v[186:189], v[210:213], v[76:79]
	v_mfma_f32_16x16x32_bf16 v[80:83], v[190:193], v[210:213], v[80:83]
	v_mfma_f32_16x16x32_bf16 v[84:87], v[194:197], v[210:213], v[84:87]
	v_mfma_f32_16x16x32_bf16 v[88:91], v[202:205], v[210:213], v[88:91]
	v_mfma_f32_16x16x32_bf16 v[52:55], v[186:189], v[218:221], v[52:55]
	v_mfma_f32_16x16x32_bf16 v[60:63], v[190:193], v[218:221], v[60:63]
	v_mfma_f32_16x16x32_bf16 v[68:71], v[194:197], v[218:221], v[68:71]
	v_mfma_f32_16x16x32_bf16 v[182:185], v[202:205], v[218:221], v[182:185]
	v_readfirstlane_b32 s56, v45
	v_lshl_add_u64 v[96:97], v[2:3], 0, s[18:19]
	s_mov_b32 m0, s56
	v_readfirstlane_b32 s0, v44
	s_waitcnt vmcnt(0)
	s_waitcnt vmcnt(0)
	s_barrier
	global_load_lds_dwordx4 v[96:97], off
	v_lshl_add_u64 v[96:97], v[4:5], 0, s[18:19]
	s_mov_b32 m0, s0
	v_readfirstlane_b32 s42, v46
	global_load_lds_dwordx4 v[96:97], off
	v_lshl_add_u64 v[44:45], v[6:7], 0, s[18:19]
	s_mov_b32 m0, s42
	v_readfirstlane_b32 s43, v47
	global_load_lds_dwordx4 v[44:45], off
	v_lshl_add_u64 v[44:45], v[8:9], 0, s[18:19]
	s_mov_b32 m0, s43
	v_readfirstlane_b32 s53, v48
	global_load_lds_dwordx4 v[44:45], off
	v_lshl_add_u64 v[44:45], v[10:11], 0, s[18:19]
	s_mov_b32 m0, s53
	v_readfirstlane_b32 s54, v49
	global_load_lds_dwordx4 v[44:45], off
	v_lshl_add_u64 v[44:45], v[12:13], 0, s[18:19]
	s_mov_b32 m0, s54
	v_readfirstlane_b32 s55, v50
	global_load_lds_dwordx4 v[44:45], off
	v_lshl_add_u64 v[44:45], v[14:15], 0, s[18:19]
	s_mov_b32 m0, s55
	v_readfirstlane_b32 s57, v51
	global_load_lds_dwordx4 v[44:45], off
	v_lshl_add_u64 v[44:45], v[16:17], 0, s[18:19]
	s_mov_b32 m0, s57
	s_nop 0
	global_load_lds_dwordx4 v[44:45], off
	ds_read_b128 v[44:47], v23
	ds_read_b128 v[48:51], v23 offset:2048
	ds_read_b128 v[186:189], v23 offset:4096
	ds_read_b128 v[194:197], v23 offset:6144
	ds_read_b128 v[190:193], v24
	ds_read_b128 v[198:201], v25
	ds_read_b128 v[202:205], v26
	ds_read_b128 v[206:209], v27
	s_waitcnt lgkmcnt(0)
	v_mfma_f32_16x16x32_bf16 v[138:141], v[44:47], v[190:193], v[138:141]
	v_mfma_f32_16x16x32_bf16 v[142:145], v[48:51], v[190:193], v[142:145]
	v_mfma_f32_16x16x32_bf16 v[146:149], v[186:189], v[190:193], v[146:149]
	v_mfma_f32_16x16x32_bf16 v[134:137], v[194:197], v[190:193], v[134:137]
	ds_read_b128 v[190:193], v28
	v_mfma_f32_16x16x32_bf16 v[154:157], v[44:47], v[198:201], v[154:157]
	v_mfma_f32_16x16x32_bf16 v[158:161], v[48:51], v[198:201], v[158:161]
	v_mfma_f32_16x16x32_bf16 v[162:165], v[186:189], v[198:201], v[162:165]
	v_mfma_f32_16x16x32_bf16 v[150:153], v[194:197], v[198:201], v[150:153]
	ds_read_b128 v[198:201], v29
	v_mfma_f32_16x16x32_bf16 v[170:173], v[44:47], v[202:205], v[170:173]
	v_mfma_f32_16x16x32_bf16 v[174:177], v[48:51], v[202:205], v[174:177]
	v_mfma_f32_16x16x32_bf16 v[178:181], v[186:189], v[202:205], v[178:181]
	v_mfma_f32_16x16x32_bf16 v[166:169], v[194:197], v[202:205], v[166:169]
	ds_read_b128 v[202:205], v30
	v_mfma_f32_16x16x32_bf16 v[210:213], v[44:47], v[206:209], v[214:217]
	v_mfma_f32_16x16x32_bf16 v[56:59], v[48:51], v[206:209], v[56:59]
	v_mfma_f32_16x16x32_bf16 v[64:67], v[186:189], v[206:209], v[64:67]
	v_mfma_f32_16x16x32_bf16 v[72:75], v[194:197], v[206:209], v[72:75]
	ds_read_b128 v[206:209], v31
	s_waitcnt lgkmcnt(0)
	v_mfma_f32_16x16x32_bf16 v[116:119], v[44:47], v[190:193], v[116:119]
	v_mfma_f32_16x16x32_bf16 v[120:123], v[48:51], v[190:193], v[120:123]
	v_mfma_f32_16x16x32_bf16 v[124:127], v[186:189], v[190:193], v[124:127]
	v_mfma_f32_16x16x32_bf16 v[112:115], v[194:197], v[190:193], v[112:115]
	v_mfma_f32_16x16x32_bf16 v[92:95], v[44:47], v[198:201], v[92:95]
	v_mfma_f32_16x16x32_bf16 v[100:103], v[48:51], v[198:201], v[100:103]
	v_mfma_f32_16x16x32_bf16 v[104:107], v[186:189], v[198:201], v[104:107]
	v_mfma_f32_16x16x32_bf16 v[108:111], v[194:197], v[198:201], v[108:111]
	v_mfma_f32_16x16x32_bf16 v[76:79], v[44:47], v[202:205], v[76:79]
	v_mfma_f32_16x16x32_bf16 v[80:83], v[48:51], v[202:205], v[80:83]
	v_mfma_f32_16x16x32_bf16 v[84:87], v[186:189], v[202:205], v[84:87]
	v_mfma_f32_16x16x32_bf16 v[88:91], v[194:197], v[202:205], v[88:91]
	v_mfma_f32_16x16x32_bf16 v[44:47], v[44:47], v[206:209], v[52:55]
	v_mfma_f32_16x16x32_bf16 v[48:51], v[48:51], v[206:209], v[60:63]
	v_mfma_f32_16x16x32_bf16 v[52:55], v[186:189], v[206:209], v[68:71]
	v_mfma_f32_16x16x32_bf16 v[60:63], v[194:197], v[206:209], v[182:185]
	s_nop 1
	ds_read_b128 v[68:71], v23 offset:1024
	ds_read_b128 v[182:185], v23 offset:3072
	ds_read_b128 v[186:189], v23 offset:5120
	ds_read_b128 v[194:197], v23 offset:7168
	ds_read_b128 v[190:193], v24 offset:1024
	ds_read_b128 v[198:201], v25 offset:1024
	ds_read_b128 v[202:205], v26 offset:1024
	ds_read_b128 v[206:209], v27 offset:1024
	s_waitcnt lgkmcnt(0)
	v_mfma_f32_16x16x32_bf16 v[138:141], v[68:71], v[190:193], v[138:141]
	v_mfma_f32_16x16x32_bf16 v[142:145], v[182:185], v[190:193], v[142:145]
	v_mfma_f32_16x16x32_bf16 v[146:149], v[186:189], v[190:193], v[146:149]
	v_mfma_f32_16x16x32_bf16 v[134:137], v[194:197], v[190:193], v[134:137]
	ds_read_b128 v[190:193], v28 offset:1024
	v_mfma_f32_16x16x32_bf16 v[154:157], v[68:71], v[198:201], v[154:157]
	v_mfma_f32_16x16x32_bf16 v[158:161], v[182:185], v[198:201], v[158:161]
	v_mfma_f32_16x16x32_bf16 v[162:165], v[186:189], v[198:201], v[162:165]
	v_mfma_f32_16x16x32_bf16 v[150:153], v[194:197], v[198:201], v[150:153]
	ds_read_b128 v[198:201], v29 offset:1024
	v_mfma_f32_16x16x32_bf16 v[170:173], v[68:71], v[202:205], v[170:173]
	v_mfma_f32_16x16x32_bf16 v[174:177], v[182:185], v[202:205], v[174:177]
	v_mfma_f32_16x16x32_bf16 v[178:181], v[186:189], v[202:205], v[178:181]
	v_mfma_f32_16x16x32_bf16 v[166:169], v[194:197], v[202:205], v[166:169]
	ds_read_b128 v[202:205], v30 offset:1024
	v_mfma_f32_16x16x32_bf16 v[210:213], v[68:71], v[206:209], v[210:213]
	v_mfma_f32_16x16x32_bf16 v[56:59], v[182:185], v[206:209], v[56:59]
	v_mfma_f32_16x16x32_bf16 v[64:67], v[186:189], v[206:209], v[64:67]
	v_mfma_f32_16x16x32_bf16 v[72:75], v[194:197], v[206:209], v[72:75]
	ds_read_b128 v[206:209], v31 offset:1024
	s_waitcnt lgkmcnt(0)
	v_mfma_f32_16x16x32_bf16 v[116:119], v[68:71], v[190:193], v[116:119]
	v_mfma_f32_16x16x32_bf16 v[120:123], v[182:185], v[190:193], v[120:123]
	v_mfma_f32_16x16x32_bf16 v[124:127], v[186:189], v[190:193], v[124:127]
	v_mfma_f32_16x16x32_bf16 v[112:115], v[194:197], v[190:193], v[112:115]
	v_mfma_f32_16x16x32_bf16 v[92:95], v[68:71], v[198:201], v[92:95]
	v_mfma_f32_16x16x32_bf16 v[100:103], v[182:185], v[198:201], v[100:103]
	v_mfma_f32_16x16x32_bf16 v[104:107], v[186:189], v[198:201], v[104:107]
	v_mfma_f32_16x16x32_bf16 v[108:111], v[194:197], v[198:201], v[108:111]
	v_mfma_f32_16x16x32_bf16 v[76:79], v[68:71], v[202:205], v[76:79]
	v_mfma_f32_16x16x32_bf16 v[80:83], v[182:185], v[202:205], v[80:83]
	v_mfma_f32_16x16x32_bf16 v[84:87], v[186:189], v[202:205], v[84:87]
	v_mfma_f32_16x16x32_bf16 v[88:91], v[194:197], v[202:205], v[88:91]
	v_mfma_f32_16x16x32_bf16 v[44:47], v[68:71], v[206:209], v[44:47]
	v_mfma_f32_16x16x32_bf16 v[48:51], v[182:185], v[206:209], v[48:51]
	v_mfma_f32_16x16x32_bf16 v[52:55], v[186:189], v[206:209], v[52:55]
	v_mfma_f32_16x16x32_bf16 v[60:63], v[194:197], v[206:209], v[60:63]
	v_readfirstlane_b32 s64, v37
	v_lshl_add_u64 v[68:69], v[2:3], 0, s[20:21]
	s_mov_b32 m0, s64
	v_readfirstlane_b32 s58, v36
	s_waitcnt vmcnt(0)
	s_waitcnt vmcnt(0)
	s_barrier
	global_load_lds_dwordx4 v[68:69], off
	v_lshl_add_u64 v[68:69], v[4:5], 0, s[20:21]
	s_mov_b32 m0, s58
	v_readfirstlane_b32 s59, v38
	global_load_lds_dwordx4 v[68:69], off
	v_lshl_add_u64 v[36:37], v[6:7], 0, s[20:21]
	s_mov_b32 m0, s59
	v_readfirstlane_b32 s60, v39
	global_load_lds_dwordx4 v[36:37], off
	v_lshl_add_u64 v[36:37], v[8:9], 0, s[20:21]
	s_mov_b32 m0, s60
	v_readfirstlane_b32 s61, v40
	global_load_lds_dwordx4 v[36:37], off
	v_lshl_add_u64 v[36:37], v[10:11], 0, s[20:21]
	s_mov_b32 m0, s61
	v_readfirstlane_b32 s62, v41
	global_load_lds_dwordx4 v[36:37], off
	v_lshl_add_u64 v[36:37], v[12:13], 0, s[20:21]
	s_mov_b32 m0, s62
	v_readfirstlane_b32 s63, v42
	global_load_lds_dwordx4 v[36:37], off
	v_lshl_add_u64 v[36:37], v[14:15], 0, s[20:21]
	s_mov_b32 m0, s63
	v_readfirstlane_b32 s65, v43
	global_load_lds_dwordx4 v[36:37], off
	v_lshl_add_u64 v[36:37], v[16:17], 0, s[20:21]
	s_mov_b32 m0, s65
	s_nop 0
	global_load_lds_dwordx4 v[36:37], off
	ds_read_b128 v[36:39], v18 offset:32768
	ds_read_b128 v[40:43], v18 offset:34816
	ds_read_b128 v[68:71], v18 offset:36864
	ds_read_b128 v[186:189], v18 offset:38912
	ds_read_b128 v[182:185], v32
	ds_read_b128 v[190:193], v33
	ds_read_b128 v[194:197], v34
	ds_read_b128 v[198:201], v35
	s_waitcnt lgkmcnt(0)
	v_mfma_f32_16x16x32_bf16 v[138:141], v[36:39], v[182:185], v[138:141]
	v_mfma_f32_16x16x32_bf16 v[142:145], v[40:43], v[182:185], v[142:145]
	v_mfma_f32_16x16x32_bf16 v[146:149], v[68:71], v[182:185], v[146:149]
	v_mfma_f32_16x16x32_bf16 v[134:137], v[186:189], v[182:185], v[134:137]
	ds_read_b128 v[182:185], v22
	v_mfma_f32_16x16x32_bf16 v[154:157], v[36:39], v[190:193], v[154:157]
	v_mfma_f32_16x16x32_bf16 v[158:161], v[40:43], v[190:193], v[158:161]
	v_mfma_f32_16x16x32_bf16 v[162:165], v[68:71], v[190:193], v[162:165]
	v_mfma_f32_16x16x32_bf16 v[150:153], v[186:189], v[190:193], v[150:153]
	ds_read_b128 v[190:193], v21
	v_mfma_f32_16x16x32_bf16 v[170:173], v[36:39], v[194:197], v[170:173]
	v_mfma_f32_16x16x32_bf16 v[174:177], v[40:43], v[194:197], v[174:177]
	v_mfma_f32_16x16x32_bf16 v[178:181], v[68:71], v[194:197], v[178:181]
	v_mfma_f32_16x16x32_bf16 v[166:169], v[186:189], v[194:197], v[166:169]
	ds_read_b128 v[194:197], v20
	v_mfma_f32_16x16x32_bf16 v[202:205], v[36:39], v[198:201], v[210:213]
	v_mfma_f32_16x16x32_bf16 v[56:59], v[40:43], v[198:201], v[56:59]
	v_mfma_f32_16x16x32_bf16 v[64:67], v[68:71], v[198:201], v[64:67]
	v_mfma_f32_16x16x32_bf16 v[72:75], v[186:189], v[198:201], v[72:75]
	ds_read_b128 v[198:201], v19
	s_waitcnt lgkmcnt(0)
	v_mfma_f32_16x16x32_bf16 v[116:119], v[36:39], v[182:185], v[116:119]
	v_mfma_f32_16x16x32_bf16 v[120:123], v[40:43], v[182:185], v[120:123]
	v_mfma_f32_16x16x32_bf16 v[124:127], v[68:71], v[182:185], v[124:127]
	v_mfma_f32_16x16x32_bf16 v[112:115], v[186:189], v[182:185], v[112:115]
	v_mfma_f32_16x16x32_bf16 v[92:95], v[36:39], v[190:193], v[92:95]
	v_mfma_f32_16x16x32_bf16 v[100:103], v[40:43], v[190:193], v[100:103]
	v_mfma_f32_16x16x32_bf16 v[104:107], v[68:71], v[190:193], v[104:107]
	v_mfma_f32_16x16x32_bf16 v[108:111], v[186:189], v[190:193], v[108:111]
	v_mfma_f32_16x16x32_bf16 v[76:79], v[36:39], v[194:197], v[76:79]
	v_mfma_f32_16x16x32_bf16 v[80:83], v[40:43], v[194:197], v[80:83]
	v_mfma_f32_16x16x32_bf16 v[84:87], v[68:71], v[194:197], v[84:87]
	v_mfma_f32_16x16x32_bf16 v[88:91], v[186:189], v[194:197], v[88:91]
	v_mfma_f32_16x16x32_bf16 v[36:39], v[36:39], v[198:201], v[44:47]
	v_mfma_f32_16x16x32_bf16 v[40:43], v[40:43], v[198:201], v[48:51]
	v_mfma_f32_16x16x32_bf16 v[44:47], v[68:71], v[198:201], v[52:55]
	v_mfma_f32_16x16x32_bf16 v[48:51], v[186:189], v[198:201], v[60:63]
	s_nop 1
	ds_read_b128 v[52:55], v18 offset:33792
	ds_read_b128 v[60:63], v18 offset:35840
	ds_read_b128 v[68:71], v18 offset:37888
	ds_read_b128 v[186:189], v18 offset:39936
	ds_read_b128 v[182:185], v32 offset:1024
	ds_read_b128 v[190:193], v33 offset:1024
	ds_read_b128 v[194:197], v34 offset:1024
	ds_read_b128 v[198:201], v35 offset:1024
	s_waitcnt lgkmcnt(0)
	v_mfma_f32_16x16x32_bf16 v[138:141], v[52:55], v[182:185], v[138:141]
	v_mfma_f32_16x16x32_bf16 v[142:145], v[60:63], v[182:185], v[142:145]
	v_mfma_f32_16x16x32_bf16 v[146:149], v[68:71], v[182:185], v[146:149]
	v_mfma_f32_16x16x32_bf16 v[134:137], v[186:189], v[182:185], v[134:137]
	ds_read_b128 v[182:185], v22 offset:1024
	v_mfma_f32_16x16x32_bf16 v[154:157], v[52:55], v[190:193], v[154:157]
	v_mfma_f32_16x16x32_bf16 v[158:161], v[60:63], v[190:193], v[158:161]
	v_mfma_f32_16x16x32_bf16 v[162:165], v[68:71], v[190:193], v[162:165]
	v_mfma_f32_16x16x32_bf16 v[150:153], v[186:189], v[190:193], v[150:153]
	ds_read_b128 v[190:193], v21 offset:1024
	v_mfma_f32_16x16x32_bf16 v[170:173], v[52:55], v[194:197], v[170:173]
	v_mfma_f32_16x16x32_bf16 v[174:177], v[60:63], v[194:197], v[174:177]
	v_mfma_f32_16x16x32_bf16 v[178:181], v[68:71], v[194:197], v[178:181]
	v_mfma_f32_16x16x32_bf16 v[166:169], v[186:189], v[194:197], v[166:169]
	ds_read_b128 v[194:197], v20 offset:1024
	v_mfma_f32_16x16x32_bf16 v[202:205], v[52:55], v[198:201], v[202:205]
	v_mfma_f32_16x16x32_bf16 v[56:59], v[60:63], v[198:201], v[56:59]
	v_mfma_f32_16x16x32_bf16 v[64:67], v[68:71], v[198:201], v[64:67]
	v_mfma_f32_16x16x32_bf16 v[72:75], v[186:189], v[198:201], v[72:75]
	ds_read_b128 v[198:201], v19 offset:1024
	s_waitcnt lgkmcnt(0)
	v_mfma_f32_16x16x32_bf16 v[116:119], v[52:55], v[182:185], v[116:119]
	v_mfma_f32_16x16x32_bf16 v[120:123], v[60:63], v[182:185], v[120:123]
	v_mfma_f32_16x16x32_bf16 v[124:127], v[68:71], v[182:185], v[124:127]
	v_mfma_f32_16x16x32_bf16 v[112:115], v[186:189], v[182:185], v[112:115]
	v_mfma_f32_16x16x32_bf16 v[92:95], v[52:55], v[190:193], v[92:95]
	v_mfma_f32_16x16x32_bf16 v[100:103], v[60:63], v[190:193], v[100:103]
	v_mfma_f32_16x16x32_bf16 v[104:107], v[68:71], v[190:193], v[104:107]
	v_mfma_f32_16x16x32_bf16 v[108:111], v[186:189], v[190:193], v[108:111]
	v_mfma_f32_16x16x32_bf16 v[76:79], v[52:55], v[194:197], v[76:79]
	v_mfma_f32_16x16x32_bf16 v[80:83], v[60:63], v[194:197], v[80:83]
	v_mfma_f32_16x16x32_bf16 v[84:87], v[68:71], v[194:197], v[84:87]
	v_mfma_f32_16x16x32_bf16 v[88:91], v[186:189], v[194:197], v[88:91]
	v_mfma_f32_16x16x32_bf16 v[36:39], v[52:55], v[198:201], v[36:39]
	v_mfma_f32_16x16x32_bf16 v[40:43], v[60:63], v[198:201], v[40:43]
	v_mfma_f32_16x16x32_bf16 v[44:47], v[68:71], v[198:201], v[44:47]
	v_mfma_f32_16x16x32_bf16 v[48:51], v[186:189], v[198:201], v[48:51]
	s_mov_b32 m0, s56
	v_lshl_add_u64 v[52:53], v[2:3], 0, s[22:23]
	s_waitcnt vmcnt(0)
	s_waitcnt vmcnt(0)
	s_barrier
	global_load_lds_dwordx4 v[52:53], off
	v_lshl_add_u64 v[52:53], v[4:5], 0, s[22:23]
	s_mov_b32 m0, s0
	s_nop 0
	global_load_lds_dwordx4 v[52:53], off
	v_lshl_add_u64 v[52:53], v[6:7], 0, s[22:23]
	s_mov_b32 m0, s42
	s_nop 0
	global_load_lds_dwordx4 v[52:53], off
	v_lshl_add_u64 v[52:53], v[8:9], 0, s[22:23]
	s_mov_b32 m0, s43
	s_nop 0
	global_load_lds_dwordx4 v[52:53], off
	v_lshl_add_u64 v[52:53], v[10:11], 0, s[22:23]
	s_mov_b32 m0, s53
	s_nop 0
	global_load_lds_dwordx4 v[52:53], off
	v_lshl_add_u64 v[52:53], v[12:13], 0, s[22:23]
	s_mov_b32 m0, s54
	s_nop 0
	global_load_lds_dwordx4 v[52:53], off
	v_lshl_add_u64 v[52:53], v[14:15], 0, s[22:23]
	s_mov_b32 m0, s55
	s_nop 0
	global_load_lds_dwordx4 v[52:53], off
	v_lshl_add_u64 v[52:53], v[16:17], 0, s[22:23]
	s_mov_b32 m0, s57
	s_nop 0
	global_load_lds_dwordx4 v[52:53], off
	ds_read_b128 v[52:55], v23
	ds_read_b128 v[60:63], v23 offset:2048
	ds_read_b128 v[68:71], v23 offset:4096
	ds_read_b128 v[186:189], v23 offset:6144
	ds_read_b128 v[182:185], v24
	ds_read_b128 v[190:193], v25
	ds_read_b128 v[194:197], v26
	ds_read_b128 v[198:201], v27
	s_waitcnt lgkmcnt(0)
	v_mfma_f32_16x16x32_bf16 v[138:141], v[52:55], v[182:185], v[138:141]
	v_mfma_f32_16x16x32_bf16 v[142:145], v[60:63], v[182:185], v[142:145]
	v_mfma_f32_16x16x32_bf16 v[146:149], v[68:71], v[182:185], v[146:149]
	v_mfma_f32_16x16x32_bf16 v[134:137], v[186:189], v[182:185], v[134:137]
	ds_read_b128 v[182:185], v28
	v_mfma_f32_16x16x32_bf16 v[154:157], v[52:55], v[190:193], v[154:157]
	v_mfma_f32_16x16x32_bf16 v[158:161], v[60:63], v[190:193], v[158:161]
	v_mfma_f32_16x16x32_bf16 v[162:165], v[68:71], v[190:193], v[162:165]
	v_mfma_f32_16x16x32_bf16 v[150:153], v[186:189], v[190:193], v[150:153]
	ds_read_b128 v[190:193], v29
	v_mfma_f32_16x16x32_bf16 v[170:173], v[52:55], v[194:197], v[170:173]
	v_mfma_f32_16x16x32_bf16 v[174:177], v[60:63], v[194:197], v[174:177]
	v_mfma_f32_16x16x32_bf16 v[178:181], v[68:71], v[194:197], v[178:181]
	v_mfma_f32_16x16x32_bf16 v[166:169], v[186:189], v[194:197], v[166:169]
	ds_read_b128 v[194:197], v30
	v_mfma_f32_16x16x32_bf16 v[202:205], v[52:55], v[198:201], v[202:205]
	v_mfma_f32_16x16x32_bf16 v[56:59], v[60:63], v[198:201], v[56:59]
	v_mfma_f32_16x16x32_bf16 v[64:67], v[68:71], v[198:201], v[64:67]
	v_mfma_f32_16x16x32_bf16 v[72:75], v[186:189], v[198:201], v[72:75]
	ds_read_b128 v[198:201], v31
	s_waitcnt lgkmcnt(0)
	v_mfma_f32_16x16x32_bf16 v[116:119], v[52:55], v[182:185], v[116:119]
	v_mfma_f32_16x16x32_bf16 v[120:123], v[60:63], v[182:185], v[120:123]
	v_mfma_f32_16x16x32_bf16 v[124:127], v[68:71], v[182:185], v[124:127]
	v_mfma_f32_16x16x32_bf16 v[112:115], v[186:189], v[182:185], v[112:115]
	v_mfma_f32_16x16x32_bf16 v[92:95], v[52:55], v[190:193], v[92:95]
	v_mfma_f32_16x16x32_bf16 v[100:103], v[60:63], v[190:193], v[100:103]
	v_mfma_f32_16x16x32_bf16 v[104:107], v[68:71], v[190:193], v[104:107]
	v_mfma_f32_16x16x32_bf16 v[108:111], v[186:189], v[190:193], v[108:111]
	v_mfma_f32_16x16x32_bf16 v[76:79], v[52:55], v[194:197], v[76:79]
	v_mfma_f32_16x16x32_bf16 v[80:83], v[60:63], v[194:197], v[80:83]
	v_mfma_f32_16x16x32_bf16 v[84:87], v[68:71], v[194:197], v[84:87]
	v_mfma_f32_16x16x32_bf16 v[88:91], v[186:189], v[194:197], v[88:91]
	v_mfma_f32_16x16x32_bf16 v[36:39], v[52:55], v[198:201], v[36:39]
	v_mfma_f32_16x16x32_bf16 v[40:43], v[60:63], v[198:201], v[40:43]
	v_mfma_f32_16x16x32_bf16 v[44:47], v[68:71], v[198:201], v[44:47]
	v_mfma_f32_16x16x32_bf16 v[48:51], v[186:189], v[198:201], v[48:51]
	ds_read_b128 v[52:55], v23 offset:1024
	ds_read_b128 v[60:63], v23 offset:3072
	ds_read_b128 v[68:71], v23 offset:5120
	ds_read_b128 v[186:189], v23 offset:7168
	ds_read_b128 v[182:185], v24 offset:1024
	ds_read_b128 v[190:193], v25 offset:1024
	ds_read_b128 v[194:197], v26 offset:1024
	ds_read_b128 v[198:201], v27 offset:1024
	s_waitcnt lgkmcnt(0)
	v_mfma_f32_16x16x32_bf16 v[138:141], v[52:55], v[182:185], v[138:141]
	v_mfma_f32_16x16x32_bf16 v[142:145], v[60:63], v[182:185], v[142:145]
	v_mfma_f32_16x16x32_bf16 v[146:149], v[68:71], v[182:185], v[146:149]
	v_mfma_f32_16x16x32_bf16 v[134:137], v[186:189], v[182:185], v[134:137]
	ds_read_b128 v[182:185], v28 offset:1024
	v_mfma_f32_16x16x32_bf16 v[154:157], v[52:55], v[190:193], v[154:157]
	v_mfma_f32_16x16x32_bf16 v[158:161], v[60:63], v[190:193], v[158:161]
	v_mfma_f32_16x16x32_bf16 v[162:165], v[68:71], v[190:193], v[162:165]
	v_mfma_f32_16x16x32_bf16 v[150:153], v[186:189], v[190:193], v[150:153]
	ds_read_b128 v[190:193], v29 offset:1024
	v_mfma_f32_16x16x32_bf16 v[170:173], v[52:55], v[194:197], v[170:173]
	v_mfma_f32_16x16x32_bf16 v[174:177], v[60:63], v[194:197], v[174:177]
	v_mfma_f32_16x16x32_bf16 v[178:181], v[68:71], v[194:197], v[178:181]
	v_mfma_f32_16x16x32_bf16 v[166:169], v[186:189], v[194:197], v[166:169]
	ds_read_b128 v[194:197], v30 offset:1024
	v_mfma_f32_16x16x32_bf16 v[202:205], v[52:55], v[198:201], v[202:205]
	v_mfma_f32_16x16x32_bf16 v[56:59], v[60:63], v[198:201], v[56:59]
	v_mfma_f32_16x16x32_bf16 v[64:67], v[68:71], v[198:201], v[64:67]
	v_mfma_f32_16x16x32_bf16 v[72:75], v[186:189], v[198:201], v[72:75]
	ds_read_b128 v[198:201], v31 offset:1024
	s_waitcnt lgkmcnt(0)
	v_mfma_f32_16x16x32_bf16 v[116:119], v[52:55], v[182:185], v[116:119]
	v_mfma_f32_16x16x32_bf16 v[120:123], v[60:63], v[182:185], v[120:123]
	v_mfma_f32_16x16x32_bf16 v[124:127], v[68:71], v[182:185], v[124:127]
	v_mfma_f32_16x16x32_bf16 v[112:115], v[186:189], v[182:185], v[112:115]
	v_mfma_f32_16x16x32_bf16 v[92:95], v[52:55], v[190:193], v[92:95]
	v_mfma_f32_16x16x32_bf16 v[100:103], v[60:63], v[190:193], v[100:103]
	v_mfma_f32_16x16x32_bf16 v[104:107], v[68:71], v[190:193], v[104:107]
	v_mfma_f32_16x16x32_bf16 v[108:111], v[186:189], v[190:193], v[108:111]
	v_mfma_f32_16x16x32_bf16 v[76:79], v[52:55], v[194:197], v[76:79]
	v_mfma_f32_16x16x32_bf16 v[80:83], v[60:63], v[194:197], v[80:83]
	v_mfma_f32_16x16x32_bf16 v[84:87], v[68:71], v[194:197], v[84:87]
	v_mfma_f32_16x16x32_bf16 v[88:91], v[186:189], v[194:197], v[88:91]
	v_mfma_f32_16x16x32_bf16 v[36:39], v[52:55], v[198:201], v[36:39]
	v_mfma_f32_16x16x32_bf16 v[40:43], v[60:63], v[198:201], v[40:43]
	v_mfma_f32_16x16x32_bf16 v[44:47], v[68:71], v[198:201], v[44:47]
	v_mfma_f32_16x16x32_bf16 v[48:51], v[186:189], v[198:201], v[48:51]
	s_mov_b32 m0, s64
	v_lshl_add_u64 v[2:3], v[2:3], 0, s[24:25]
	s_waitcnt vmcnt(0)
	s_waitcnt vmcnt(0)
	s_barrier
	global_load_lds_dwordx4 v[2:3], off
	v_lshl_add_u64 v[2:3], v[4:5], 0, s[24:25]
	s_mov_b32 m0, s58
	s_nop 0
	global_load_lds_dwordx4 v[2:3], off
	v_lshl_add_u64 v[2:3], v[6:7], 0, s[24:25]
	s_mov_b32 m0, s59
	s_nop 0
	global_load_lds_dwordx4 v[2:3], off
	v_lshl_add_u64 v[2:3], v[8:9], 0, s[24:25]
	s_mov_b32 m0, s60
	s_nop 0
	global_load_lds_dwordx4 v[2:3], off
	v_lshl_add_u64 v[2:3], v[10:11], 0, s[24:25]
	s_mov_b32 m0, s61
	s_nop 0
	global_load_lds_dwordx4 v[2:3], off
	v_lshl_add_u64 v[2:3], v[12:13], 0, s[24:25]
	s_mov_b32 m0, s62
	s_nop 0
	global_load_lds_dwordx4 v[2:3], off
	v_lshl_add_u64 v[2:3], v[14:15], 0, s[24:25]
	s_mov_b32 m0, s63
	s_nop 0
	global_load_lds_dwordx4 v[2:3], off
	v_lshl_add_u64 v[2:3], v[16:17], 0, s[24:25]
	s_mov_b32 m0, s65
	s_nop 0
	global_load_lds_dwordx4 v[2:3], off
	ds_read_b128 v[2:5], v18 offset:32768
	ds_read_b128 v[6:9], v18 offset:34816
	ds_read_b128 v[10:13], v18 offset:36864
	ds_read_b128 v[52:55], v18 offset:38912
	ds_read_b128 v[14:17], v32
	ds_read_b128 v[60:63], v33
	ds_read_b128 v[68:71], v34
	ds_read_b128 v[182:185], v35
	s_waitcnt lgkmcnt(0)
	v_mfma_f32_16x16x32_bf16 v[138:141], v[2:5], v[14:17], v[138:141]
	v_mfma_f32_16x16x32_bf16 v[142:145], v[6:9], v[14:17], v[142:145]
	v_mfma_f32_16x16x32_bf16 v[146:149], v[10:13], v[14:17], v[146:149]
	v_mfma_f32_16x16x32_bf16 v[14:17], v[52:55], v[14:17], v[134:137]
	s_nop 2
	ds_read_b128 v[134:137], v22
	v_mfma_f32_16x16x32_bf16 v[154:157], v[2:5], v[60:63], v[154:157]
	v_mfma_f32_16x16x32_bf16 v[158:161], v[6:9], v[60:63], v[158:161]
	v_mfma_f32_16x16x32_bf16 v[162:165], v[10:13], v[60:63], v[162:165]
	v_mfma_f32_16x16x32_bf16 v[60:63], v[52:55], v[60:63], v[150:153]
	s_nop 2
	ds_read_b128 v[150:153], v21
	v_mfma_f32_16x16x32_bf16 v[170:173], v[2:5], v[68:71], v[170:173]
	v_mfma_f32_16x16x32_bf16 v[174:177], v[6:9], v[68:71], v[174:177]
	v_mfma_f32_16x16x32_bf16 v[178:181], v[10:13], v[68:71], v[178:181]
	v_mfma_f32_16x16x32_bf16 v[68:71], v[52:55], v[68:71], v[166:169]
	s_nop 2
	ds_read_b128 v[166:169], v20
	v_mfma_f32_16x16x32_bf16 v[186:189], v[2:5], v[182:185], v[202:205]
	v_mfma_f32_16x16x32_bf16 v[56:59], v[6:9], v[182:185], v[56:59]
	v_mfma_f32_16x16x32_bf16 v[64:67], v[10:13], v[182:185], v[64:67]
	v_mfma_f32_16x16x32_bf16 v[72:75], v[52:55], v[182:185], v[72:75]
	ds_read_b128 v[182:185], v19
	s_waitcnt lgkmcnt(0)
	v_mfma_f32_16x16x32_bf16 v[116:119], v[2:5], v[134:137], v[116:119]
	v_mfma_f32_16x16x32_bf16 v[120:123], v[6:9], v[134:137], v[120:123]
	v_mfma_f32_16x16x32_bf16 v[124:127], v[10:13], v[134:137], v[124:127]
	v_mfma_f32_16x16x32_bf16 v[112:115], v[52:55], v[134:137], v[112:115]
	v_mfma_f32_16x16x32_bf16 v[92:95], v[2:5], v[150:153], v[92:95]
	v_mfma_f32_16x16x32_bf16 v[100:103], v[6:9], v[150:153], v[100:103]
	v_mfma_f32_16x16x32_bf16 v[104:107], v[10:13], v[150:153], v[104:107]
	v_mfma_f32_16x16x32_bf16 v[108:111], v[52:55], v[150:153], v[108:111]
	v_mfma_f32_16x16x32_bf16 v[76:79], v[2:5], v[166:169], v[76:79]
	v_mfma_f32_16x16x32_bf16 v[80:83], v[6:9], v[166:169], v[80:83]
	v_mfma_f32_16x16x32_bf16 v[84:87], v[10:13], v[166:169], v[84:87]
	v_mfma_f32_16x16x32_bf16 v[88:91], v[52:55], v[166:169], v[88:91]
	v_mfma_f32_16x16x32_bf16 v[2:5], v[2:5], v[182:185], v[36:39]
	v_mfma_f32_16x16x32_bf16 v[6:9], v[6:9], v[182:185], v[40:43]
	v_mfma_f32_16x16x32_bf16 v[10:13], v[10:13], v[182:185], v[44:47]
	v_mfma_f32_16x16x32_bf16 v[36:39], v[52:55], v[182:185], v[48:51]
	s_nop 0
	ds_read_b128 v[40:43], v18 offset:33792
	ds_read_b128 v[44:47], v18 offset:35840
	ds_read_b128 v[48:51], v18 offset:37888
	ds_read_b128 v[134:137], v18 offset:39936
	ds_read_b128 v[52:55], v32 offset:1024
	ds_read_b128 v[150:153], v33 offset:1024
	ds_read_b128 v[166:169], v34 offset:1024
	ds_read_b128 v[32:35], v35 offset:1024
	s_waitcnt lgkmcnt(0)
	v_mfma_f32_16x16x32_bf16 v[138:141], v[40:43], v[52:55], v[138:141]
	v_mfma_f32_16x16x32_bf16 v[142:145], v[44:47], v[52:55], v[142:145]
	v_mfma_f32_16x16x32_bf16 v[146:149], v[48:51], v[52:55], v[146:149]
	v_mfma_f32_16x16x32_bf16 v[14:17], v[134:137], v[52:55], v[14:17]
	ds_read_b128 v[52:55], v22 offset:1024
	v_mfma_f32_16x16x32_bf16 v[154:157], v[40:43], v[150:153], v[154:157]
	v_mfma_f32_16x16x32_bf16 v[158:161], v[44:47], v[150:153], v[158:161]
	v_mfma_f32_16x16x32_bf16 v[162:165], v[48:51], v[150:153], v[162:165]
	v_mfma_f32_16x16x32_bf16 v[60:63], v[134:137], v[150:153], v[60:63]
	ds_read_b128 v[150:153], v21 offset:1024
	v_mfma_f32_16x16x32_bf16 v[170:173], v[40:43], v[166:169], v[170:173]
	v_mfma_f32_16x16x32_bf16 v[174:177], v[44:47], v[166:169], v[174:177]
	v_mfma_f32_16x16x32_bf16 v[178:181], v[48:51], v[166:169], v[178:181]
	v_mfma_f32_16x16x32_bf16 v[68:71], v[134:137], v[166:169], v[68:71]
	ds_read_b128 v[166:169], v20 offset:1024
	v_mfma_f32_16x16x32_bf16 v[182:185], v[40:43], v[32:35], v[186:189]
	v_mfma_f32_16x16x32_bf16 v[56:59], v[44:47], v[32:35], v[56:59]
	v_mfma_f32_16x16x32_bf16 v[64:67], v[48:51], v[32:35], v[64:67]
	v_mfma_f32_16x16x32_bf16 v[32:35], v[134:137], v[32:35], v[72:75]
	ds_read_b128 v[18:21], v19 offset:1024
	s_waitcnt lgkmcnt(0)
	v_mfma_f32_16x16x32_bf16 v[72:75], v[40:43], v[52:55], v[116:119]
	v_mfma_f32_16x16x32_bf16 v[116:119], v[44:47], v[52:55], v[120:123]
	v_mfma_f32_16x16x32_bf16 v[120:123], v[48:51], v[52:55], v[124:127]
	v_mfma_f32_16x16x32_bf16 v[52:55], v[134:137], v[52:55], v[112:115]
	v_mfma_f32_16x16x32_bf16 v[92:95], v[40:43], v[150:153], v[92:95]
	v_mfma_f32_16x16x32_bf16 v[100:103], v[44:47], v[150:153], v[100:103]
	v_mfma_f32_16x16x32_bf16 v[104:107], v[48:51], v[150:153], v[104:107]
	v_mfma_f32_16x16x32_bf16 v[108:111], v[134:137], v[150:153], v[108:111]
	v_mfma_f32_16x16x32_bf16 v[76:79], v[40:43], v[166:169], v[76:79]
	v_mfma_f32_16x16x32_bf16 v[80:83], v[44:47], v[166:169], v[80:83]
	v_mfma_f32_16x16x32_bf16 v[84:87], v[48:51], v[166:169], v[84:87]
	v_mfma_f32_16x16x32_bf16 v[88:91], v[134:137], v[166:169], v[88:91]
	v_mfma_f32_16x16x32_bf16 v[2:5], v[40:43], v[18:21], v[2:5]
	v_mfma_f32_16x16x32_bf16 v[6:9], v[44:47], v[18:21], v[6:9]
	v_mfma_f32_16x16x32_bf16 v[10:13], v[48:51], v[18:21], v[10:13]
	v_mfma_f32_16x16x32_bf16 v[18:21], v[134:137], v[18:21], v[36:39]
	s_waitcnt vmcnt(0)
	s_waitcnt vmcnt(0)
	s_barrier
	s_nop 0
	ds_read_b128 v[36:39], v31
	ds_read_b128 v[40:43], v30
	ds_read_b128 v[44:47], v29
	ds_read_b128 v[48:51], v28
	ds_read_b128 v[112:115], v27
	ds_read_b128 v[124:127], v26
	ds_read_b128 v[134:137], v25
	ds_read_b128 v[150:153], v24
	ds_read_b128 v[166:169], v23
	s_waitcnt lgkmcnt(0)
	v_mfma_f32_16x16x32_bf16 v[186:189], v[166:169], v[36:39], v[2:5]
	s_nop 2
	ds_read_b128 v[2:5], v23 offset:2048
	s_waitcnt lgkmcnt(0)
	v_mfma_f32_16x16x32_bf16 v[190:193], v[2:5], v[36:39], v[6:9]
	s_nop 2
	ds_read_b128 v[6:9], v23 offset:4096
	s_waitcnt lgkmcnt(0)
	v_mfma_f32_16x16x32_bf16 v[194:197], v[6:9], v[36:39], v[10:13]
	s_nop 2
	ds_read_b128 v[10:13], v23 offset:6144
	s_waitcnt lgkmcnt(0)
	v_mfma_f32_16x16x32_bf16 v[198:201], v[10:13], v[36:39], v[18:21]
	v_mfma_f32_16x16x32_bf16 v[18:21], v[10:13], v[134:137], v[60:63]
	v_mfma_f32_16x16x32_bf16 v[36:39], v[10:13], v[124:127], v[68:71]
	v_mfma_f32_16x16x32_bf16 v[68:71], v[6:9], v[134:137], v[162:165]
	v_mfma_f32_16x16x32_bf16 v[162:165], v[6:9], v[112:115], v[64:67]
	v_mfma_f32_16x16x32_bf16 v[64:67], v[2:5], v[150:153], v[142:145]
	v_mfma_f32_16x16x32_bf16 v[142:145], v[2:5], v[134:137], v[158:161]
	v_mfma_f32_16x16x32_bf16 v[134:137], v[166:169], v[134:137], v[154:157]
	v_mfma_f32_16x16x32_bf16 v[154:157], v[166:169], v[40:43], v[76:79]
	v_mfma_f32_16x16x32_bf16 v[60:63], v[6:9], v[150:153], v[146:149]
	v_mfma_f32_16x16x32_bf16 v[146:149], v[6:9], v[124:127], v[178:181]
	v_mfma_f32_16x16x32_bf16 v[158:161], v[2:5], v[124:127], v[174:177]
	v_mfma_f32_16x16x32_bf16 v[124:127], v[166:169], v[124:127], v[170:173]
	v_mfma_f32_16x16x32_bf16 v[170:173], v[6:9], v[40:43], v[84:87]
	v_mfma_f32_16x16x32_bf16 v[138:141], v[166:169], v[150:153], v[138:141]
	v_mfma_f32_16x16x32_bf16 v[56:59], v[2:5], v[112:115], v[56:59]
	v_mfma_f32_16x16x32_bf16 v[116:119], v[2:5], v[48:51], v[116:119]
	v_mfma_f32_16x16x32_bf16 v[120:123], v[6:9], v[48:51], v[120:123]
	v_mfma_f32_16x16x32_bf16 v[14:17], v[10:13], v[150:153], v[14:17]
	v_mfma_f32_16x16x32_bf16 v[150:153], v[166:169], v[48:51], v[72:75]
	v_mfma_f32_16x16x32_bf16 v[48:51], v[10:13], v[48:51], v[52:55]
	v_mfma_f32_16x16x32_bf16 v[52:55], v[166:169], v[44:47], v[92:95]
	v_mfma_f32_16x16x32_bf16 v[32:35], v[10:13], v[112:115], v[32:35]
	v_mfma_f32_16x16x32_bf16 v[112:115], v[166:169], v[112:115], v[182:185]
	v_mfma_f32_16x16x32_bf16 v[166:169], v[2:5], v[40:43], v[80:83]
	v_mfma_f32_16x16x32_bf16 v[104:107], v[6:9], v[44:47], v[104:107]
	v_mfma_f32_16x16x32_bf16 v[108:111], v[10:13], v[44:47], v[108:111]
	v_mfma_f32_16x16x32_bf16 v[100:103], v[2:5], v[44:47], v[100:103]
	v_mfma_f32_16x16x32_bf16 v[174:177], v[10:13], v[40:43], v[88:91]
	ds_read_b128 v[178:181], v23 offset:1024
	ds_read_b128 v[182:185], v23 offset:3072
	ds_read_b128 v[202:205], v23 offset:5120
	ds_read_b128 v[206:209], v23 offset:7168
	ds_read_b128 v[2:5], v24 offset:1024
	ds_read_b128 v[6:9], v25 offset:1024
	ds_read_b128 v[10:13], v26 offset:1024
	ds_read_b128 v[22:25], v27 offset:1024
	s_waitcnt lgkmcnt(3)
	v_mfma_f32_16x16x32_bf16 v[138:141], v[178:181], v[2:5], v[138:141]
	v_mfma_f32_16x16x32_bf16 v[210:213], v[182:185], v[2:5], v[64:67]
	v_mfma_f32_16x16x32_bf16 v[214:217], v[202:205], v[2:5], v[60:63]
	v_mfma_f32_16x16x32_bf16 v[218:221], v[206:209], v[2:5], v[14:17]
	ds_read_b128 v[2:5], v28 offset:1024
	s_waitcnt lgkmcnt(3)
	v_mfma_f32_16x16x32_bf16 v[134:137], v[178:181], v[6:9], v[134:137]
	v_mfma_f32_16x16x32_bf16 v[142:145], v[182:185], v[6:9], v[142:145]
	v_mfma_f32_16x16x32_bf16 v[222:225], v[202:205], v[6:9], v[68:71]
	v_mfma_f32_16x16x32_bf16 v[226:229], v[206:209], v[6:9], v[18:21]
	ds_read_b128 v[6:9], v29 offset:1024
	s_waitcnt lgkmcnt(3)
	v_mfma_f32_16x16x32_bf16 v[66:69], v[178:181], v[10:13], v[124:127]
	v_mfma_f32_16x16x32_bf16 v[70:73], v[182:185], v[10:13], v[158:161]
	v_mfma_f32_16x16x32_bf16 v[74:77], v[202:205], v[10:13], v[146:149]
	v_mfma_f32_16x16x32_bf16 v[78:81], v[206:209], v[10:13], v[36:39]
	ds_read_b128 v[14:17], v30 offset:1024
	s_waitcnt lgkmcnt(3)
	v_mfma_f32_16x16x32_bf16 v[82:85], v[178:181], v[22:25], v[112:115]
	v_mfma_f32_16x16x32_bf16 v[86:89], v[182:185], v[22:25], v[56:59]
	v_mfma_f32_16x16x32_bf16 v[90:93], v[202:205], v[22:25], v[162:165]
	v_mfma_f32_16x16x32_bf16 v[94:97], v[206:209], v[22:25], v[32:35]
	s_nop 2
	ds_read_b128 v[30:33], v31 offset:1024
	s_waitcnt lgkmcnt(3)
	v_mfma_f32_16x16x32_bf16 v[34:37], v[178:181], v[2:5], v[150:153]
	v_mfma_f32_16x16x32_bf16 v[38:41], v[182:185], v[2:5], v[116:119]
	v_mfma_f32_16x16x32_bf16 v[42:45], v[202:205], v[2:5], v[120:123]
	v_mfma_f32_16x16x32_bf16 v[46:49], v[206:209], v[2:5], v[48:51]
	s_waitcnt lgkmcnt(2)
	v_mfma_f32_16x16x32_bf16 v[50:53], v[178:181], v[6:9], v[52:55]
	v_mfma_f32_16x16x32_bf16 v[54:57], v[182:185], v[6:9], v[100:103]
	v_mfma_f32_16x16x32_bf16 v[58:61], v[202:205], v[6:9], v[104:107]
	v_mfma_f32_16x16x32_bf16 v[62:65], v[206:209], v[6:9], v[108:111]
	s_waitcnt lgkmcnt(1)
	v_mfma_f32_16x16x32_bf16 v[2:5], v[178:181], v[14:17], v[154:157]
	v_mfma_f32_16x16x32_bf16 v[6:9], v[182:185], v[14:17], v[166:169]
	v_mfma_f32_16x16x32_bf16 v[10:13], v[202:205], v[14:17], v[170:173]
	v_mfma_f32_16x16x32_bf16 v[14:17], v[206:209], v[14:17], v[174:177]
	s_waitcnt lgkmcnt(0)
	v_mfma_f32_16x16x32_bf16 v[18:21], v[178:181], v[30:33], v[186:189]
	v_mfma_f32_16x16x32_bf16 v[22:25], v[182:185], v[30:33], v[190:193]
	v_mfma_f32_16x16x32_bf16 v[26:29], v[202:205], v[30:33], v[194:197]
	v_mfma_f32_16x16x32_bf16 v[30:33], v[206:209], v[30:33], v[198:201]
	v_lshlrev_b32_e32 v101, 2, v98
	v_and_b32_e32 v112, 60, v101
	v_ashrrev_i32_e32 v101, 1, v98
	v_lshrrev_b32_e32 v99, 6, v98
	v_and_b32_e32 v101, 0xffffff80, v101
	v_and_b32_e32 v100, 15, v98
	v_mul_lo_u32 v99, v99, s48
	v_add_u32_e32 v107, s28, v101
	v_bfe_u32 v108, v98, 4, 2
	v_add_u32_e32 v109, s46, v99
	v_and_b32_e32 v99, 48, v98
	v_and_or_b32 v102, v98, s49, v112
	v_mul_u32_u24_e32 v98, 0x110, v100
	v_or_b32_e32 v100, v107, v108
	v_lshl_add_u64 v[0:1], v[0:1], 0, s[38:39]
	v_lshlrev_b32_e32 v130, 1, v102
	v_ashrrev_i32_e32 v101, 31, v100
	v_add_co_u32_e32 v0, vcc, v0, v130
	v_addc_co_u32_e32 v1, vcc, v1, v131, vcc
	v_add3_u32 v99, v109, v99, v98
	v_lshlrev_b64 v[100:101], 11, v[100:101]
	s_waitcnt vmcnt(0)
	s_barrier
	ds_write_b128 v99, v[138:141]
	ds_write_b128 v99, v[210:213] offset:64
	ds_write_b128 v99, v[214:217] offset:128
	ds_write_b128 v99, v[218:221] offset:192
	ds_write_b128 v99, v[134:137] offset:4352
	ds_write_b128 v99, v[142:145] offset:4416
	ds_write_b128 v99, v[222:225] offset:4480
	ds_write_b128 v99, v[226:229] offset:4544
	v_add_co_u32_e32 v114, vcc, v0, v100
	v_addc_co_u32_e32 v115, vcc, v1, v101, vcc
	flat_load_dwordx2 v[116:117], v[114:115]
	v_or_b32_e32 v100, 4, v108
	v_or_b32_e32 v102, v107, v100
	v_ashrrev_i32_e32 v103, 31, v102
	v_lshlrev_b64 v[102:103], 11, v[102:103]
	v_add_co_u32_e32 v118, vcc, v0, v102
	v_addc_co_u32_e32 v119, vcc, v1, v103, vcc
	flat_load_dwordx2 v[120:121], v[118:119]
	v_or_b32_e32 v101, 8, v108
	v_or_b32_e32 v102, v107, v101
	v_ashrrev_i32_e32 v103, 31, v102
	v_lshlrev_b64 v[102:103], 11, v[102:103]
	v_add_co_u32_e32 v122, vcc, v0, v102
	v_addc_co_u32_e32 v123, vcc, v1, v103, vcc
	flat_load_dwordx2 v[124:125], v[122:123]
	v_or_b32_e32 v102, 12, v108
	v_or_b32_e32 v104, v107, v102
	v_ashrrev_i32_e32 v105, 31, v104
	v_lshlrev_b64 v[104:105], 11, v[104:105]
	v_add_co_u32_e32 v126, vcc, v0, v104
	v_addc_co_u32_e32 v127, vcc, v1, v105, vcc
	flat_load_dwordx2 v[128:129], v[126:127]
	v_or_b32_e32 v103, 16, v108
	v_or_b32_e32 v104, v107, v103
	v_ashrrev_i32_e32 v105, 31, v104
	v_lshlrev_b64 v[104:105], 11, v[104:105]
	v_add_co_u32_e32 v134, vcc, v0, v104
	v_addc_co_u32_e32 v135, vcc, v1, v105, vcc
	flat_load_dwordx2 v[136:137], v[134:135]
	v_or_b32_e32 v104, 20, v108
	v_or_b32_e32 v110, v107, v104
	v_ashrrev_i32_e32 v111, 31, v110
	v_lshlrev_b64 v[110:111], 11, v[110:111]
	v_add_co_u32_e32 v138, vcc, v0, v110
	v_addc_co_u32_e32 v139, vcc, v1, v111, vcc
	flat_load_dwordx2 v[140:141], v[138:139]
	v_or_b32_e32 v105, 24, v108
	v_or_b32_e32 v110, v107, v105
	v_ashrrev_i32_e32 v111, 31, v110
	v_lshlrev_b64 v[110:111], 11, v[110:111]
	v_add_co_u32_e32 v142, vcc, v0, v110
	v_addc_co_u32_e32 v143, vcc, v1, v111, vcc
	flat_load_dwordx2 v[144:145], v[142:143]
	v_or_b32_e32 v106, 28, v108
	v_or_b32_e32 v146, v107, v106
	v_lshlrev_b32_e32 v146, 11, v146
	v_add_co_u32_e32 v146, vcc, v0, v146
	v_addc_co_u32_e32 v147, vcc, 0, v1, vcc
	flat_load_dwordx2 v[148:149], v[146:147]
	v_mul_u32_u24_e32 v98, 0x110, v108
	v_lshlrev_b32_e32 v110, 2, v112
	v_add3_u32 v98, v109, v110, v98
	ds_read_b128 v[110:113], v98
	s_add_i32 s0, s30, 0x1600
	s_lshl_b64 s[42:43], s[0:1], 11
	s_waitcnt vmcnt(0) lgkmcnt(0)
	v_and_b32_e32 v151, 0xffff0000, v116
	v_lshlrev_b32_e32 v150, 16, v116
	v_and_b32_e32 v153, 0xffff0000, v117
	v_lshlrev_b32_e32 v152, 16, v117
	v_pk_mul_f32 v[110:111], v[110:111], v[150:151]
	v_pk_mul_f32 v[112:113], v[112:113], v[152:153]
	v_cvt_pk_bf16_f32 v110, v110, v111
	v_cvt_pk_bf16_f32 v111, v112, v113
	flat_store_dwordx2 v[114:115], v[110:111]
	ds_read_b128 v[110:113], v98 offset:1088
	v_and_b32_e32 v115, 0xffff0000, v120
	v_lshlrev_b32_e32 v114, 16, v120
	v_and_b32_e32 v117, 0xffff0000, v121
	v_lshlrev_b32_e32 v116, 16, v121
	s_waitcnt lgkmcnt(0)
	v_pk_mul_f32 v[110:111], v[110:111], v[114:115]
	v_pk_mul_f32 v[112:113], v[112:113], v[116:117]
	v_cvt_pk_bf16_f32 v110, v110, v111
	v_cvt_pk_bf16_f32 v111, v112, v113
	flat_store_dwordx2 v[118:119], v[110:111]
	ds_read_b128 v[110:113], v98 offset:2176
	v_and_b32_e32 v115, 0xffff0000, v124
	v_lshlrev_b32_e32 v114, 16, v124
	v_and_b32_e32 v117, 0xffff0000, v125
	v_lshlrev_b32_e32 v116, 16, v125
	s_waitcnt lgkmcnt(0)
	v_pk_mul_f32 v[110:111], v[110:111], v[114:115]
	v_pk_mul_f32 v[112:113], v[112:113], v[116:117]
	v_cvt_pk_bf16_f32 v110, v110, v111
	v_cvt_pk_bf16_f32 v111, v112, v113
	flat_store_dwordx2 v[122:123], v[110:111]
	ds_read_b128 v[110:113], v98 offset:3264
	v_and_b32_e32 v115, 0xffff0000, v128
	v_lshlrev_b32_e32 v114, 16, v128
	v_mov_b32_e32 v150, v132
	s_waitcnt lgkmcnt(0)
	v_pk_mul_f32 v[110:111], v[110:111], v[114:115]
	v_and_b32_e32 v115, 0xffff0000, v129
	v_lshlrev_b32_e32 v114, 16, v129
	v_pk_mul_f32 v[112:113], v[112:113], v[114:115]
	v_cvt_pk_bf16_f32 v110, v110, v111
	v_cvt_pk_bf16_f32 v111, v112, v113
	flat_store_dwordx2 v[126:127], v[110:111]
	ds_read_b128 v[110:113], v98 offset:4352
	v_and_b32_e32 v115, 0xffff0000, v136
	v_lshlrev_b32_e32 v114, 16, v136
	s_waitcnt lgkmcnt(0)
	v_pk_mul_f32 v[110:111], v[110:111], v[114:115]
	v_and_b32_e32 v115, 0xffff0000, v137
	v_lshlrev_b32_e32 v114, 16, v137
	v_pk_mul_f32 v[112:113], v[112:113], v[114:115]
	v_cvt_pk_bf16_f32 v110, v110, v111
	v_cvt_pk_bf16_f32 v111, v112, v113
	flat_store_dwordx2 v[134:135], v[110:111]
	ds_read_b128 v[110:113], v98 offset:5440
	v_and_b32_e32 v115, 0xffff0000, v140
	v_lshlrev_b32_e32 v114, 16, v140
	s_waitcnt lgkmcnt(0)
	v_pk_mul_f32 v[110:111], v[110:111], v[114:115]
	v_and_b32_e32 v115, 0xffff0000, v141
	v_lshlrev_b32_e32 v114, 16, v141
	v_pk_mul_f32 v[112:113], v[112:113], v[114:115]
	v_cvt_pk_bf16_f32 v110, v110, v111
	v_cvt_pk_bf16_f32 v111, v112, v113
	flat_store_dwordx2 v[138:139], v[110:111]
	ds_read_b128 v[110:113], v98 offset:6528
	v_and_b32_e32 v115, 0xffff0000, v144
	v_lshlrev_b32_e32 v114, 16, v144
	s_waitcnt lgkmcnt(0)
	v_pk_mul_f32 v[110:111], v[110:111], v[114:115]
	v_and_b32_e32 v115, 0xffff0000, v145
	v_lshlrev_b32_e32 v114, 16, v145
	v_pk_mul_f32 v[112:113], v[112:113], v[114:115]
	v_cvt_pk_bf16_f32 v110, v110, v111
	v_cvt_pk_bf16_f32 v111, v112, v113
	flat_store_dwordx2 v[142:143], v[110:111]
	ds_read_b128 v[110:113], v98 offset:7616
	v_and_b32_e32 v115, 0xffff0000, v148
	v_lshlrev_b32_e32 v114, 16, v148
	s_waitcnt lgkmcnt(0)
	v_pk_mul_f32 v[110:111], v[110:111], v[114:115]
	v_and_b32_e32 v115, 0xffff0000, v149
	v_lshlrev_b32_e32 v114, 16, v149
	v_pk_mul_f32 v[112:113], v[112:113], v[114:115]
	v_cvt_pk_bf16_f32 v110, v110, v111
	v_cvt_pk_bf16_f32 v111, v112, v113
	flat_store_dwordx2 v[146:147], v[110:111]
	ds_write_b128 v99, v[66:69]
	v_or_b32_e32 v68, 32, v107
	v_or_b32_e32 v66, v68, v108
	v_ashrrev_i32_e32 v67, 31, v66
	v_lshlrev_b64 v[66:67], 11, v[66:67]
	ds_write_b128 v99, v[70:73] offset:64
	ds_write_b128 v99, v[74:77] offset:128
	ds_write_b128 v99, v[78:81] offset:192
	ds_write_b128 v99, v[82:85] offset:4352
	ds_write_b128 v99, v[86:89] offset:4416
	ds_write_b128 v99, v[90:93] offset:4480
	ds_write_b128 v99, v[94:97] offset:4544
	v_add_co_u32_e32 v70, vcc, v0, v66
	v_addc_co_u32_e32 v71, vcc, v1, v67, vcc
	flat_load_dwordx2 v[72:73], v[70:71]
	v_or_b32_e32 v66, v68, v100
	v_ashrrev_i32_e32 v67, 31, v66
	v_lshlrev_b64 v[66:67], 11, v[66:67]
	v_add_co_u32_e32 v74, vcc, v0, v66
	v_addc_co_u32_e32 v75, vcc, v1, v67, vcc
	flat_load_dwordx2 v[76:77], v[74:75]
	v_or_b32_e32 v66, v68, v101
	v_ashrrev_i32_e32 v67, 31, v66
	v_lshlrev_b64 v[66:67], 11, v[66:67]
	v_add_co_u32_e32 v78, vcc, v0, v66
	v_addc_co_u32_e32 v79, vcc, v1, v67, vcc
	flat_load_dwordx2 v[80:81], v[78:79]
	v_or_b32_e32 v66, v68, v102
	v_ashrrev_i32_e32 v67, 31, v66
	v_lshlrev_b64 v[66:67], 11, v[66:67]
	v_add_co_u32_e32 v82, vcc, v0, v66
	v_addc_co_u32_e32 v83, vcc, v1, v67, vcc
	flat_load_dwordx2 v[84:85], v[82:83]
	v_or_b32_e32 v66, v68, v103
	v_ashrrev_i32_e32 v67, 31, v66
	v_lshlrev_b64 v[66:67], 11, v[66:67]
	v_add_co_u32_e32 v86, vcc, v0, v66
	v_addc_co_u32_e32 v87, vcc, v1, v67, vcc
	flat_load_dwordx2 v[88:89], v[86:87]
	v_or_b32_e32 v66, v68, v104
	v_ashrrev_i32_e32 v67, 31, v66
	v_lshlrev_b64 v[66:67], 11, v[66:67]
	v_add_co_u32_e32 v90, vcc, v0, v66
	v_addc_co_u32_e32 v91, vcc, v1, v67, vcc
	flat_load_dwordx2 v[92:93], v[90:91]
	v_or_b32_e32 v66, v68, v105
	v_ashrrev_i32_e32 v67, 31, v66
	v_lshlrev_b64 v[66:67], 11, v[66:67]
	v_add_co_u32_e32 v94, vcc, v0, v66
	v_addc_co_u32_e32 v95, vcc, v1, v67, vcc
	flat_load_dwordx2 v[96:97], v[94:95]
	v_or_b32_e32 v66, v68, v106
	v_ashrrev_i32_e32 v67, 31, v66
	v_lshlrev_b64 v[66:67], 11, v[66:67]
	v_add_co_u32_e32 v110, vcc, v0, v66
	v_addc_co_u32_e32 v111, vcc, v1, v67, vcc
	flat_load_dwordx2 v[112:113], v[110:111]
	ds_read_b128 v[66:69], v98
	s_waitcnt vmcnt(0) lgkmcnt(0)
	v_and_b32_e32 v115, 0xffff0000, v72
	v_lshlrev_b32_e32 v114, 16, v72
	v_and_b32_e32 v117, 0xffff0000, v73
	v_lshlrev_b32_e32 v116, 16, v73
	v_pk_mul_f32 v[66:67], v[66:67], v[114:115]
	v_pk_mul_f32 v[68:69], v[68:69], v[116:117]
	v_cvt_pk_bf16_f32 v66, v66, v67
	v_cvt_pk_bf16_f32 v67, v68, v69
	flat_store_dwordx2 v[70:71], v[66:67]
	ds_read_b128 v[66:69], v98 offset:1088
	v_and_b32_e32 v71, 0xffff0000, v76
	v_lshlrev_b32_e32 v70, 16, v76
	v_and_b32_e32 v73, 0xffff0000, v77
	v_lshlrev_b32_e32 v72, 16, v77
	s_waitcnt lgkmcnt(0)
	v_pk_mul_f32 v[66:67], v[66:67], v[70:71]
	v_pk_mul_f32 v[68:69], v[68:69], v[72:73]
	v_cvt_pk_bf16_f32 v66, v66, v67
	v_cvt_pk_bf16_f32 v67, v68, v69
	flat_store_dwordx2 v[74:75], v[66:67]
	ds_read_b128 v[66:69], v98 offset:2176
	v_and_b32_e32 v71, 0xffff0000, v80
	v_lshlrev_b32_e32 v70, 16, v80
	v_and_b32_e32 v73, 0xffff0000, v81
	v_lshlrev_b32_e32 v72, 16, v81
	s_waitcnt lgkmcnt(0)
	v_pk_mul_f32 v[66:67], v[66:67], v[70:71]
	v_pk_mul_f32 v[68:69], v[68:69], v[72:73]
	v_cvt_pk_bf16_f32 v66, v66, v67
	v_cvt_pk_bf16_f32 v67, v68, v69
	flat_store_dwordx2 v[78:79], v[66:67]
	ds_read_b128 v[66:69], v98 offset:3264
	v_and_b32_e32 v71, 0xffff0000, v84
	v_lshlrev_b32_e32 v70, 16, v84
	v_and_b32_e32 v73, 0xffff0000, v85
	v_lshlrev_b32_e32 v72, 16, v85
	s_waitcnt lgkmcnt(0)
	v_pk_mul_f32 v[66:67], v[66:67], v[70:71]
	v_pk_mul_f32 v[68:69], v[68:69], v[72:73]
	v_cvt_pk_bf16_f32 v66, v66, v67
	v_cvt_pk_bf16_f32 v67, v68, v69
	flat_store_dwordx2 v[82:83], v[66:67]
	ds_read_b128 v[66:69], v98 offset:4352
	v_and_b32_e32 v71, 0xffff0000, v88
	v_lshlrev_b32_e32 v70, 16, v88
	v_and_b32_e32 v73, 0xffff0000, v89
	v_lshlrev_b32_e32 v72, 16, v89
	s_waitcnt lgkmcnt(0)
	v_pk_mul_f32 v[66:67], v[66:67], v[70:71]
	v_pk_mul_f32 v[68:69], v[68:69], v[72:73]
	v_cvt_pk_bf16_f32 v66, v66, v67
	v_cvt_pk_bf16_f32 v67, v68, v69
	flat_store_dwordx2 v[86:87], v[66:67]
	ds_read_b128 v[66:69], v98 offset:5440
	v_and_b32_e32 v71, 0xffff0000, v92
	v_lshlrev_b32_e32 v70, 16, v92
	v_and_b32_e32 v73, 0xffff0000, v93
	v_lshlrev_b32_e32 v72, 16, v93
	s_waitcnt lgkmcnt(0)
	v_pk_mul_f32 v[66:67], v[66:67], v[70:71]
	v_pk_mul_f32 v[68:69], v[68:69], v[72:73]
	v_cvt_pk_bf16_f32 v66, v66, v67
	v_cvt_pk_bf16_f32 v67, v68, v69
	flat_store_dwordx2 v[90:91], v[66:67]
	ds_read_b128 v[66:69], v98 offset:6528
	v_and_b32_e32 v71, 0xffff0000, v96
	v_lshlrev_b32_e32 v70, 16, v96
	v_and_b32_e32 v73, 0xffff0000, v97
	v_lshlrev_b32_e32 v72, 16, v97
	s_waitcnt lgkmcnt(0)
	v_pk_mul_f32 v[66:67], v[66:67], v[70:71]
	v_pk_mul_f32 v[68:69], v[68:69], v[72:73]
	v_cvt_pk_bf16_f32 v66, v66, v67
	v_cvt_pk_bf16_f32 v67, v68, v69
	flat_store_dwordx2 v[94:95], v[66:67]
	ds_read_b128 v[66:69], v98 offset:7616
	v_and_b32_e32 v71, 0xffff0000, v112
	v_lshlrev_b32_e32 v70, 16, v112
	v_and_b32_e32 v73, 0xffff0000, v113
	v_lshlrev_b32_e32 v72, 16, v113
	s_waitcnt lgkmcnt(0)
	v_pk_mul_f32 v[66:67], v[66:67], v[70:71]
	v_pk_mul_f32 v[68:69], v[68:69], v[72:73]
	v_cvt_pk_bf16_f32 v66, v66, v67
	v_cvt_pk_bf16_f32 v67, v68, v69
	flat_store_dwordx2 v[110:111], v[66:67]
	ds_write_b128 v99, v[34:37]
	v_or_b32_e32 v36, 64, v107
	v_or_b32_e32 v34, v36, v108
	v_ashrrev_i32_e32 v35, 31, v34
	v_lshlrev_b64 v[34:35], 11, v[34:35]
	ds_write_b128 v99, v[38:41] offset:64
	ds_write_b128 v99, v[42:45] offset:128
	ds_write_b128 v99, v[46:49] offset:192
	ds_write_b128 v99, v[50:53] offset:4352
	ds_write_b128 v99, v[54:57] offset:4416
	ds_write_b128 v99, v[58:61] offset:4480
	ds_write_b128 v99, v[62:65] offset:4544
	v_add_co_u32_e32 v38, vcc, v0, v34
	v_addc_co_u32_e32 v39, vcc, v1, v35, vcc
	flat_load_dwordx2 v[40:41], v[38:39]
	v_or_b32_e32 v34, v36, v100
	v_ashrrev_i32_e32 v35, 31, v34
	v_lshlrev_b64 v[34:35], 11, v[34:35]
	v_add_co_u32_e32 v42, vcc, v0, v34
	v_addc_co_u32_e32 v43, vcc, v1, v35, vcc
	flat_load_dwordx2 v[44:45], v[42:43]
	v_or_b32_e32 v34, v36, v101
	v_ashrrev_i32_e32 v35, 31, v34
	v_lshlrev_b64 v[34:35], 11, v[34:35]
	v_add_co_u32_e32 v46, vcc, v0, v34
	v_addc_co_u32_e32 v47, vcc, v1, v35, vcc
	flat_load_dwordx2 v[48:49], v[46:47]
	v_or_b32_e32 v34, v36, v102
	v_ashrrev_i32_e32 v35, 31, v34
	v_lshlrev_b64 v[34:35], 11, v[34:35]
	v_add_co_u32_e32 v50, vcc, v0, v34
	v_addc_co_u32_e32 v51, vcc, v1, v35, vcc
	flat_load_dwordx2 v[52:53], v[50:51]
	v_or_b32_e32 v34, v36, v103
	v_ashrrev_i32_e32 v35, 31, v34
	v_lshlrev_b64 v[34:35], 11, v[34:35]
	v_add_co_u32_e32 v54, vcc, v0, v34
	v_addc_co_u32_e32 v55, vcc, v1, v35, vcc
	flat_load_dwordx2 v[56:57], v[54:55]
	v_or_b32_e32 v34, v36, v104
	v_ashrrev_i32_e32 v35, 31, v34
	v_lshlrev_b64 v[34:35], 11, v[34:35]
	v_add_co_u32_e32 v58, vcc, v0, v34
	v_addc_co_u32_e32 v59, vcc, v1, v35, vcc
	flat_load_dwordx2 v[60:61], v[58:59]
	v_or_b32_e32 v34, v36, v105
	v_ashrrev_i32_e32 v35, 31, v34
	v_lshlrev_b64 v[34:35], 11, v[34:35]
	v_add_co_u32_e32 v62, vcc, v0, v34
	v_addc_co_u32_e32 v63, vcc, v1, v35, vcc
	flat_load_dwordx2 v[64:65], v[62:63]
	v_or_b32_e32 v34, v36, v106
	v_ashrrev_i32_e32 v35, 31, v34
	v_lshlrev_b64 v[34:35], 11, v[34:35]
	v_add_co_u32_e32 v66, vcc, v0, v34
	v_addc_co_u32_e32 v67, vcc, v1, v35, vcc
	flat_load_dwordx2 v[68:69], v[66:67]
	ds_read_b128 v[34:37], v98
	v_or_b32_e32 v76, 0x60, v107
	v_or_b32_e32 v70, v76, v108
	v_ashrrev_i32_e32 v71, 31, v70
	s_waitcnt vmcnt(0) lgkmcnt(0)
	v_and_b32_e32 v73, 0xffff0000, v40
	v_lshlrev_b32_e32 v72, 16, v40
	v_and_b32_e32 v75, 0xffff0000, v41
	v_lshlrev_b32_e32 v74, 16, v41
	v_pk_mul_f32 v[34:35], v[34:35], v[72:73]
	v_pk_mul_f32 v[36:37], v[36:37], v[74:75]
	v_cvt_pk_bf16_f32 v34, v34, v35
	v_cvt_pk_bf16_f32 v35, v36, v37
	flat_store_dwordx2 v[38:39], v[34:35]
	ds_read_b128 v[34:37], v98 offset:1088
	v_and_b32_e32 v39, 0xffff0000, v44
	v_lshlrev_b32_e32 v38, 16, v44
	v_and_b32_e32 v41, 0xffff0000, v45
	v_lshlrev_b32_e32 v40, 16, v45
	s_waitcnt lgkmcnt(0)
	v_pk_mul_f32 v[34:35], v[34:35], v[38:39]
	v_pk_mul_f32 v[36:37], v[36:37], v[40:41]
	v_cvt_pk_bf16_f32 v34, v34, v35
	v_cvt_pk_bf16_f32 v35, v36, v37
	flat_store_dwordx2 v[42:43], v[34:35]
	ds_read_b128 v[34:37], v98 offset:2176
	v_and_b32_e32 v39, 0xffff0000, v48
	v_lshlrev_b32_e32 v38, 16, v48
	v_and_b32_e32 v41, 0xffff0000, v49
	v_lshlrev_b32_e32 v40, 16, v49
	s_waitcnt lgkmcnt(0)
	v_pk_mul_f32 v[34:35], v[34:35], v[38:39]
	v_pk_mul_f32 v[36:37], v[36:37], v[40:41]
	v_cvt_pk_bf16_f32 v34, v34, v35
	v_cvt_pk_bf16_f32 v35, v36, v37
	flat_store_dwordx2 v[46:47], v[34:35]
	ds_read_b128 v[34:37], v98 offset:3264
	v_and_b32_e32 v39, 0xffff0000, v52
	v_lshlrev_b32_e32 v38, 16, v52
	v_and_b32_e32 v41, 0xffff0000, v53
	v_lshlrev_b32_e32 v40, 16, v53
	s_waitcnt lgkmcnt(0)
	v_pk_mul_f32 v[34:35], v[34:35], v[38:39]
	v_pk_mul_f32 v[36:37], v[36:37], v[40:41]
	v_cvt_pk_bf16_f32 v34, v34, v35
	v_cvt_pk_bf16_f32 v35, v36, v37
	flat_store_dwordx2 v[50:51], v[34:35]
	ds_read_b128 v[34:37], v98 offset:4352
	v_and_b32_e32 v39, 0xffff0000, v56
	v_lshlrev_b32_e32 v38, 16, v56
	v_and_b32_e32 v41, 0xffff0000, v57
	v_lshlrev_b32_e32 v40, 16, v57
	s_waitcnt lgkmcnt(0)
	v_pk_mul_f32 v[34:35], v[34:35], v[38:39]
	v_pk_mul_f32 v[36:37], v[36:37], v[40:41]
	v_cvt_pk_bf16_f32 v34, v34, v35
	v_cvt_pk_bf16_f32 v35, v36, v37
	flat_store_dwordx2 v[54:55], v[34:35]
	ds_read_b128 v[34:37], v98 offset:5440
	v_and_b32_e32 v39, 0xffff0000, v60
	v_lshlrev_b32_e32 v38, 16, v60
	v_and_b32_e32 v41, 0xffff0000, v61
	v_lshlrev_b32_e32 v40, 16, v61
	s_waitcnt lgkmcnt(0)
	v_pk_mul_f32 v[34:35], v[34:35], v[38:39]
	v_pk_mul_f32 v[36:37], v[36:37], v[40:41]
	v_cvt_pk_bf16_f32 v34, v34, v35
	v_cvt_pk_bf16_f32 v35, v36, v37
	flat_store_dwordx2 v[58:59], v[34:35]
	ds_read_b128 v[34:37], v98 offset:6528
	v_and_b32_e32 v39, 0xffff0000, v64
	v_lshlrev_b32_e32 v38, 16, v64
	v_and_b32_e32 v41, 0xffff0000, v65
	v_lshlrev_b32_e32 v40, 16, v65
	s_waitcnt lgkmcnt(0)
	v_pk_mul_f32 v[34:35], v[34:35], v[38:39]
	v_pk_mul_f32 v[36:37], v[36:37], v[40:41]
	v_cvt_pk_bf16_f32 v34, v34, v35
	v_cvt_pk_bf16_f32 v35, v36, v37
	flat_store_dwordx2 v[62:63], v[34:35]
	ds_read_b128 v[34:37], v98 offset:7616
	v_and_b32_e32 v39, 0xffff0000, v68
	v_lshlrev_b32_e32 v38, 16, v68
	v_and_b32_e32 v41, 0xffff0000, v69
	v_lshlrev_b32_e32 v40, 16, v69
	s_waitcnt lgkmcnt(0)
	v_pk_mul_f32 v[34:35], v[34:35], v[38:39]
	v_pk_mul_f32 v[36:37], v[36:37], v[40:41]
	v_cvt_pk_bf16_f32 v34, v34, v35
	v_cvt_pk_bf16_f32 v35, v36, v37
	flat_store_dwordx2 v[66:67], v[34:35]
	ds_write_b128 v99, v[2:5]
	v_lshlrev_b64 v[2:3], 11, v[70:71]
	ds_write_b128 v99, v[6:9] offset:64
	ds_write_b128 v99, v[10:13] offset:128
	ds_write_b128 v99, v[14:17] offset:192
	ds_write_b128 v99, v[18:21] offset:4352
	ds_write_b128 v99, v[22:25] offset:4416
	ds_write_b128 v99, v[26:29] offset:4480
	ds_write_b128 v99, v[30:33] offset:4544
	v_add_co_u32_e32 v4, vcc, v0, v2
	v_addc_co_u32_e32 v5, vcc, v1, v3, vcc
	flat_load_dwordx2 v[6:7], v[4:5]
	v_or_b32_e32 v2, v76, v100
	v_ashrrev_i32_e32 v3, 31, v2
	v_lshlrev_b64 v[2:3], 11, v[2:3]
	v_add_co_u32_e32 v8, vcc, v0, v2
	v_addc_co_u32_e32 v9, vcc, v1, v3, vcc
	flat_load_dwordx2 v[10:11], v[8:9]
	v_or_b32_e32 v2, v76, v101
	v_ashrrev_i32_e32 v3, 31, v2
	v_lshlrev_b64 v[2:3], 11, v[2:3]
	v_add_co_u32_e32 v12, vcc, v0, v2
	v_addc_co_u32_e32 v13, vcc, v1, v3, vcc
	flat_load_dwordx2 v[14:15], v[12:13]
	v_or_b32_e32 v2, v76, v102
	v_ashrrev_i32_e32 v3, 31, v2
	v_lshlrev_b64 v[2:3], 11, v[2:3]
	v_add_co_u32_e32 v16, vcc, v0, v2
	v_addc_co_u32_e32 v17, vcc, v1, v3, vcc
	flat_load_dwordx2 v[18:19], v[16:17]
	v_or_b32_e32 v2, v76, v103
	v_ashrrev_i32_e32 v3, 31, v2
	v_lshlrev_b64 v[2:3], 11, v[2:3]
	v_add_co_u32_e32 v20, vcc, v0, v2
	v_addc_co_u32_e32 v21, vcc, v1, v3, vcc
	flat_load_dwordx2 v[22:23], v[20:21]
	v_or_b32_e32 v2, v76, v104
	v_ashrrev_i32_e32 v3, 31, v2
	v_lshlrev_b64 v[2:3], 11, v[2:3]
	v_add_co_u32_e32 v24, vcc, v0, v2
	v_addc_co_u32_e32 v25, vcc, v1, v3, vcc
	flat_load_dwordx2 v[26:27], v[24:25]
	v_or_b32_e32 v2, v76, v105
	v_ashrrev_i32_e32 v3, 31, v2
	v_lshlrev_b64 v[2:3], 11, v[2:3]
	v_add_co_u32_e32 v28, vcc, v0, v2
	v_addc_co_u32_e32 v29, vcc, v1, v3, vcc
	flat_load_dwordx2 v[30:31], v[28:29]
	v_or_b32_e32 v2, v76, v106
	v_ashrrev_i32_e32 v3, 31, v2
	v_lshlrev_b64 v[2:3], 11, v[2:3]
	v_add_co_u32_e32 v32, vcc, v0, v2
	v_addc_co_u32_e32 v33, vcc, v1, v3, vcc
	flat_load_dwordx2 v[34:35], v[32:33]
	ds_read_b128 v[0:3], v98
	v_mov_b32_e32 v40, s51
	v_mov_b32_e32 v41, v132
	s_waitcnt vmcnt(0) lgkmcnt(0)
	v_and_b32_e32 v37, 0xffff0000, v6
	v_lshlrev_b32_e32 v36, 16, v6
	v_and_b32_e32 v39, 0xffff0000, v7
	v_lshlrev_b32_e32 v38, 16, v7
	v_pk_mul_f32 v[0:1], v[0:1], v[36:37]
	v_pk_mul_f32 v[2:3], v[2:3], v[38:39]
	v_cvt_pk_bf16_f32 v0, v0, v1
	v_cvt_pk_bf16_f32 v1, v2, v3
	flat_store_dwordx2 v[4:5], v[0:1]
	ds_read_b128 v[0:3], v98 offset:1088
	v_and_b32_e32 v5, 0xffff0000, v10
	v_lshlrev_b32_e32 v4, 16, v10
	v_and_b32_e32 v7, 0xffff0000, v11
	v_lshlrev_b32_e32 v6, 16, v11
	s_waitcnt lgkmcnt(0)
	v_pk_mul_f32 v[0:1], v[0:1], v[4:5]
	v_pk_mul_f32 v[2:3], v[2:3], v[6:7]
	v_cvt_pk_bf16_f32 v0, v0, v1
	v_cvt_pk_bf16_f32 v1, v2, v3
	flat_store_dwordx2 v[8:9], v[0:1]
	ds_read_b128 v[0:3], v98 offset:2176
	v_and_b32_e32 v5, 0xffff0000, v14
	v_lshlrev_b32_e32 v4, 16, v14
	v_and_b32_e32 v7, 0xffff0000, v15
	v_lshlrev_b32_e32 v6, 16, v15
	s_waitcnt lgkmcnt(0)
	v_pk_mul_f32 v[0:1], v[0:1], v[4:5]
	v_pk_mul_f32 v[2:3], v[2:3], v[6:7]
	v_cvt_pk_bf16_f32 v0, v0, v1
	v_cvt_pk_bf16_f32 v1, v2, v3
	flat_store_dwordx2 v[12:13], v[0:1]
	ds_read_b128 v[0:3], v98 offset:3264
	v_and_b32_e32 v5, 0xffff0000, v18
	v_lshlrev_b32_e32 v4, 16, v18
	v_and_b32_e32 v7, 0xffff0000, v19
	v_lshlrev_b32_e32 v6, 16, v19
	s_waitcnt lgkmcnt(0)
	v_pk_mul_f32 v[0:1], v[0:1], v[4:5]
	v_pk_mul_f32 v[2:3], v[2:3], v[6:7]
	v_cvt_pk_bf16_f32 v0, v0, v1
	v_cvt_pk_bf16_f32 v1, v2, v3
	flat_store_dwordx2 v[16:17], v[0:1]
	ds_read_b128 v[0:3], v98 offset:4352
	v_and_b32_e32 v5, 0xffff0000, v22
	v_lshlrev_b32_e32 v4, 16, v22
	v_and_b32_e32 v7, 0xffff0000, v23
	v_lshlrev_b32_e32 v6, 16, v23
	s_waitcnt lgkmcnt(0)
	v_pk_mul_f32 v[0:1], v[0:1], v[4:5]
	v_pk_mul_f32 v[2:3], v[2:3], v[6:7]
	v_cvt_pk_bf16_f32 v0, v0, v1
	v_cvt_pk_bf16_f32 v1, v2, v3
	flat_store_dwordx2 v[20:21], v[0:1]
	ds_read_b128 v[0:3], v98 offset:5440
	v_and_b32_e32 v5, 0xffff0000, v26
	v_lshlrev_b32_e32 v4, 16, v26
	v_and_b32_e32 v7, 0xffff0000, v27
	v_lshlrev_b32_e32 v6, 16, v27
	s_waitcnt lgkmcnt(0)
	v_pk_mul_f32 v[0:1], v[0:1], v[4:5]
	v_pk_mul_f32 v[2:3], v[2:3], v[6:7]
	v_cvt_pk_bf16_f32 v0, v0, v1
	v_cvt_pk_bf16_f32 v1, v2, v3
	flat_store_dwordx2 v[24:25], v[0:1]
	ds_read_b128 v[0:3], v98 offset:6528
	v_and_b32_e32 v5, 0xffff0000, v30
	v_lshlrev_b32_e32 v4, 16, v30
	v_and_b32_e32 v7, 0xffff0000, v31
	v_lshlrev_b32_e32 v6, 16, v31
	s_waitcnt lgkmcnt(0)
	v_pk_mul_f32 v[0:1], v[0:1], v[4:5]
	v_pk_mul_f32 v[2:3], v[2:3], v[6:7]
	v_cvt_pk_bf16_f32 v0, v0, v1
	v_cvt_pk_bf16_f32 v1, v2, v3
	flat_store_dwordx2 v[28:29], v[0:1]
	ds_read_b128 v[0:3], v98 offset:7616
	v_and_b32_e32 v5, 0xffff0000, v34
	v_lshlrev_b32_e32 v4, 16, v34
	v_and_b32_e32 v7, 0xffff0000, v35
	v_lshlrev_b32_e32 v6, 16, v35
	s_waitcnt lgkmcnt(0)
	v_pk_mul_f32 v[0:1], v[0:1], v[4:5]
	v_pk_mul_f32 v[2:3], v[2:3], v[6:7]
	v_cvt_pk_bf16_f32 v0, v0, v1
	v_cvt_pk_bf16_f32 v1, v2, v3
	flat_store_dwordx2 v[32:33], v[0:1]
	ds_read_b64 v[128:129], v40
	s_waitcnt lgkmcnt(0)
	v_lshl_add_u64 v[2:3], v[128:129], 0, s[42:43]
	v_lshlrev_b32_e32 v5, 4, v41
	v_and_b32_e32 v0, 32, v41
	v_lshrrev_b32_e32 v1, 1, v41
	v_bitop3_b32 v0, v5, v0, 48 bitop3:0x6c
	v_bfe_u32 v16, v41, 2, 4
	v_ashrrev_i32_e32 v17, 3, v41
	v_and_b32_e32 v9, 0xfffffc00, v5
	v_and_b32_e32 v18, 32, v1
	v_add_u32_e32 v1, 0x2000, v5
	v_lshrrev_b32_e32 v19, 1, v0
	v_add_u32_e32 v8, 0x4000, v5
	v_add_u32_e32 v5, 0x6000, v5
	v_and_or_b32 v4, v17, s44, v16
	v_ashrrev_i32_e32 v20, 7, v1
	v_or_b32_e32 v10, v19, v18
	v_ashrrev_i32_e32 v21, 7, v8
	v_ashrrev_i32_e32 v22, 7, v5
	v_and_or_b32 v6, v20, s44, v16
	v_lshl_add_u64 v[0:1], v[128:129], 0, s[36:37]
	v_lshl_or_b32 v130, v4, 10, v10
	v_and_or_b32 v8, v21, s44, v16
	v_and_or_b32 v5, v22, s44, v16
	v_add_u32_e32 v151, 0, v9
	v_lshl_or_b32 v4, v6, 10, v10
	v_lshl_add_u64 v[6:7], v[0:1], 0, s[4:5]
	v_lshl_or_b32 v8, v8, 10, v10
	v_lshl_or_b32 v10, v5, 10, v10
	v_add_u32_e32 v5, 0x8000, v151
	v_lshlrev_b64 v[12:13], 1, v[130:131]
	v_readfirstlane_b32 s0, v151
	v_add_co_u32_e32 v14, vcc, v6, v12
	v_addc_co_u32_e32 v15, vcc, v7, v13, vcc
	s_mov_b32 m0, s0
	v_readfirstlane_b32 s0, v5
	v_mov_b32_e32 v5, v131
	v_add_u32_e32 v9, 0x2000, v151
	global_load_lds_dwordx4 v[14:15], off
	v_add_co_u32_e32 v12, vcc, v2, v12
	v_addc_co_u32_e32 v13, vcc, v3, v13, vcc
	s_mov_b32 m0, s0
	v_lshlrev_b64 v[4:5], 1, v[4:5]
	v_readfirstlane_b32 s0, v9
	v_add_u32_e32 v9, 0xa000, v151
	global_load_lds_dwordx4 v[12:13], off
	v_add_co_u32_e32 v12, vcc, v6, v4
	v_addc_co_u32_e32 v13, vcc, v7, v5, vcc
	s_mov_b32 m0, s0
	v_readfirstlane_b32 s0, v9
	global_load_lds_dwordx4 v[12:13], off
	v_add_co_u32_e32 v4, vcc, v2, v4
	v_addc_co_u32_e32 v5, vcc, v3, v5, vcc
	s_mov_b32 m0, s0
	v_mov_b32_e32 v9, v131
	v_add_u32_e32 v11, 0x4000, v151
	global_load_lds_dwordx4 v[4:5], off
	v_lshlrev_b64 v[4:5], 1, v[8:9]
	v_readfirstlane_b32 s0, v11
	v_add_co_u32_e32 v8, vcc, v6, v4
	v_addc_co_u32_e32 v9, vcc, v7, v5, vcc
	s_mov_b32 m0, s0
	v_add_co_u32_e32 v4, vcc, v2, v4
	v_addc_co_u32_e32 v5, vcc, v3, v5, vcc
	global_load_lds_dwordx4 v[8:9], off
	v_add_u32_e32 v8, 0xc000, v151
	v_mov_b32_e32 v11, v131
	v_readfirstlane_b32 s0, v8
	s_mov_b32 m0, s0
	v_add_u32_e32 v8, 0x6000, v151
	global_load_lds_dwordx4 v[4:5], off
	v_lshlrev_b64 v[4:5], 1, v[10:11]
	v_readfirstlane_b32 s0, v8
	v_add_co_u32_e32 v6, vcc, v6, v4
	v_addc_co_u32_e32 v7, vcc, v7, v5, vcc
	s_mov_b32 m0, s0
	v_add_co_u32_e32 v4, vcc, v2, v4
	v_addc_co_u32_e32 v5, vcc, v3, v5, vcc
	global_load_lds_dwordx4 v[6:7], off
	v_add_u32_e32 v6, 0xe000, v151
	v_and_b32_e32 v23, 15, v41
	v_readfirstlane_b32 s0, v6
	s_mov_b32 m0, s0
	v_lshlrev_b32_e32 v6, 2, v41
	global_load_lds_dwordx4 v[4:5], off
	v_and_b32_e32 v4, 48, v41
	v_lshlrev_b32_e32 v5, 6, v23
	v_and_b32_e32 v6, 32, v6
	v_bitop3_b32 v152, v5, v6, v4 bitop3:0x36
	v_lshlrev_b32_e32 v5, 7, v41
	v_and_b32_e32 v153, 0x6000, v5
	v_lshlrev_b32_e32 v5, 6, v41
	v_and_b32_e32 v154, 0xffffc000, v5
	v_and_b32_e32 v5, 0x3c0, v5
	v_bitop3_b32 v156, v5, v6, v4 bitop3:0x36
	v_lshlrev_b32_e32 v4, 10, v22
	v_and_or_b32 v4, v4, s45, v19
	v_lshlrev_b32_e32 v10, 10, v16
	v_lshlrev_b32_e32 v6, 10, v21
	v_or3_b32 v130, v4, v10, v18
	v_and_or_b32 v6, v6, s45, v19
	v_lshlrev_b32_e32 v8, 10, v20
	v_lshlrev_b64 v[4:5], 1, v[130:131]
	v_or3_b32 v130, v6, v10, v18
	v_and_or_b32 v8, v8, s45, v19
	v_lshlrev_b32_e32 v11, 10, v17
	v_lshlrev_b64 v[6:7], 1, v[130:131]
	v_or3_b32 v130, v8, v10, v18
	v_and_or_b32 v11, v11, s45, v19
	s_nop 0
	v_lshl_add_u64 v[2:3], v[2:3], 0, s[6:7]
	v_lshlrev_b64 v[8:9], 1, v[130:131]
	v_or3_b32 v130, v11, v10, v18
	v_lshl_add_u64 v[0:1], v[0:1], 0, s[8:9]
	v_add_co_u32_e32 v138, vcc, v2, v8
	v_addc_co_u32_e32 v139, vcc, v3, v9, vcc
	v_lshlrev_b64 v[10:11], 1, v[130:131]
	v_add_co_u32_e32 v146, vcc, v0, v8
	v_addc_co_u32_e32 v147, vcc, v1, v9, vcc
	v_or_b32_e32 v155, 0x800, v154
	v_or_b32_e32 v157, 0x1000, v154
	v_or_b32_e32 v158, 0x1800, v154
	v_or_b32_e32 v159, 0x2000, v154
	v_or_b32_e32 v160, 0x2800, v154
	v_or_b32_e32 v161, 0x3000, v154
	v_or_b32_e32 v162, 0x3800, v154
	v_add_co_u32_e32 v134, vcc, v2, v4
	v_addc_co_u32_e32 v135, vcc, v3, v5, vcc
	v_add_co_u32_e32 v136, vcc, v2, v6
	v_addc_co_u32_e32 v137, vcc, v3, v7, vcc
	v_add_co_u32_e32 v140, vcc, v2, v10
	v_addc_co_u32_e32 v141, vcc, v3, v11, vcc
	v_add_co_u32_e32 v142, vcc, v0, v4
	v_addc_co_u32_e32 v143, vcc, v1, v5, vcc
	v_add_co_u32_e32 v144, vcc, v0, v6
	v_addc_co_u32_e32 v145, vcc, v1, v7, vcc
	v_add_co_u32_e32 v148, vcc, v0, v10
	v_addc_co_u32_e32 v149, vcc, v1, v11, vcc
	s_mov_b64 s[42:43], 0
	s_waitcnt vmcnt(0) lgkmcnt(0)
	s_barrier
	v_readfirstlane_b32 s100, v151
	s_and_b32 s0, s29, 0x10000
	s_xor_b32 s53, s0, 0x10000
	s_add_i32 s0, s0, 0
	v_add3_u32 v130, s0, v152, v153
	v_add3_u32 v163, s0, v152, v154
	v_add3_u32 v196, s0, v156, v155
	v_add3_u32 v197, s0, v156, v157
	v_add3_u32 v198, s0, v156, v158
	v_add3_u32 v199, s0, v156, v159
	v_add3_u32 v200, s0, v156, v160
	v_add3_u32 v201, s0, v156, v161
	v_add3_u32 v202, s0, v156, v162
	ds_read_b128 v[180:183], v130 offset:32768
	ds_read_b128 v[164:167], v163
	ds_read_b128 v[168:171], v196
	ds_read_b128 v[172:175], v197
	ds_read_b128 v[176:179], v198
	ds_read_b128 v[184:187], v130 offset:34816
	ds_read_b128 v[188:191], v130 offset:36864
	ds_read_b128 v[192:195], v130 offset:38912
	s_add_i32 s101, s100, s53
	v_readfirstlane_b32 s98, v148
	v_readfirstlane_b32 s99, v149
	v_readfirstlane_b32 vcc_lo, v140
	v_readfirstlane_b32 vcc_hi, v141
	s_sub_u32 s98, s98, 0x1000000
	s_subb_u32 s99, s99, 0
	s_sub_u32 vcc_lo, vcc_lo, 0x1000000
	s_subb_u32 vcc_hi, vcc_hi, 0
	v_subrev_u32_e32 v148, s98, v148
	v_subrev_u32_e32 v140, vcc_lo, v140
	v_subrev_u32_e32 v146, s98, v146
	v_subrev_u32_e32 v138, vcc_lo, v138
	v_subrev_u32_e32 v144, s98, v144
	v_subrev_u32_e32 v136, vcc_lo, v136
	v_subrev_u32_e32 v142, s98, v142
	v_subrev_u32_e32 v134, vcc_lo, v134
	s_mov_b32 m0, s101
	s_nop 0
	global_load_lds_dwordx4 v148, s[98:99]
	s_add_i32 m0, s101, 0x8000
	s_nop 0
	global_load_lds_dwordx4 v140, vcc
	s_add_i32 m0, s101, 0x2000
	s_nop 0
	global_load_lds_dwordx4 v146, s[98:99]
	s_add_i32 m0, s101, 0xa000
	s_nop 0
	global_load_lds_dwordx4 v138, vcc
	s_add_i32 m0, s101, 0x4000
	s_nop 0
	global_load_lds_dwordx4 v144, s[98:99]
	s_add_i32 m0, s101, 0xc000
	s_nop 0
	global_load_lds_dwordx4 v136, vcc
	s_add_i32 m0, s101, 0x6000
	s_nop 0
	global_load_lds_dwordx4 v142, s[98:99]
	s_add_i32 m0, s101, 0xe000
	s_nop 0
	global_load_lds_dwordx4 v134, vcc

.Lex_795:
	s_waitcnt lgkmcnt(0)
	v_add3_u32 v130, s46, v156, v162
	v_add3_u32 v151, s46, v156, v161
	v_add3_u32 v206, s46, v156, v160
	v_add3_u32 v198, s46, v156, v159
	v_add3_u32 v186, s46, v156, v158
	v_add3_u32 v187, s46, v156, v157
	v_add3_u32 v188, s46, v156, v155
	v_add3_u32 v189, s46, v152, v154
	v_add3_u32 v190, s47, v152, v153
	ds_read_b128 v[134:137], v130
	ds_read_b128 v[138:141], v151
	ds_read_b128 v[142:145], v206
	ds_read_b128 v[146:149], v198
	ds_read_b128 v[158:161], v186
	ds_read_b128 v[162:165], v187
	ds_read_b128 v[166:169], v188
	ds_read_b128 v[154:157], v189
	ds_read_b128 v[170:173], v190
	s_waitcnt lgkmcnt(0)
	v_mfma_f32_16x16x32_bf16 v[16:19], v[170:173], v[138:141], v[16:19]
	v_mfma_f32_16x16x32_bf16 v[174:177], v[170:173], v[134:137], v[36:39]
	s_nop 2
	ds_read_b128 v[36:39], v190 offset:2048
	s_waitcnt lgkmcnt(0)
	v_mfma_f32_16x16x32_bf16 v[12:15], v[36:39], v[138:141], v[12:15]
	v_mfma_f32_16x16x32_bf16 v[60:63], v[170:173], v[146:149], v[60:63]
	v_mfma_f32_16x16x32_bf16 v[28:31], v[36:39], v[134:137], v[28:31]
	v_mfma_f32_16x16x32_bf16 v[56:59], v[36:39], v[146:149], v[56:59]
	ds_read_b128 v[178:181], v190 offset:4096
	s_waitcnt lgkmcnt(0)
	v_mfma_f32_16x16x32_bf16 v[182:185], v[178:181], v[134:137], v[20:23]
	v_mfma_f32_16x16x32_bf16 v[52:55], v[178:181], v[146:149], v[52:55]
	s_nop 1
	ds_read_b128 v[20:23], v190 offset:6144
	s_waitcnt lgkmcnt(0)
	v_mfma_f32_16x16x32_bf16 v[134:137], v[20:23], v[134:137], v[8:11]
	v_mfma_f32_16x16x32_bf16 v[8:11], v[20:23], v[154:157], v[112:115]
	v_mfma_f32_16x16x32_bf16 v[112:115], v[20:23], v[158:161], v[64:67]
	v_mfma_f32_16x16x32_bf16 v[64:67], v[178:181], v[154:157], v[116:119]
	v_mfma_f32_16x16x32_bf16 v[116:119], v[178:181], v[158:161], v[68:71]
	v_mfma_f32_16x16x32_bf16 v[68:71], v[36:39], v[154:157], v[120:123]
	v_mfma_f32_16x16x32_bf16 v[120:123], v[36:39], v[158:161], v[72:75]
	v_mfma_f32_16x16x32_bf16 v[72:75], v[170:173], v[154:157], v[124:127]
	v_mfma_f32_16x16x32_bf16 v[124:127], v[170:173], v[158:161], v[76:79]
	v_mfma_f32_16x16x32_bf16 v[48:51], v[20:23], v[146:149], v[48:51]
	v_mfma_f32_16x16x32_bf16 v[146:149], v[170:173], v[142:145], v[44:47]
	v_mfma_f32_16x16x32_bf16 v[152:155], v[36:39], v[142:145], v[40:43]
	v_mfma_f32_16x16x32_bf16 v[156:159], v[178:181], v[142:145], v[32:35]
	v_mfma_f32_16x16x32_bf16 v[24:27], v[20:23], v[142:145], v[24:27]
	v_mfma_f32_16x16x32_bf16 v[142:145], v[178:181], v[138:141], v[4:7]
	v_mfma_f32_16x16x32_bf16 v[108:111], v[170:173], v[166:169], v[108:111]
	v_mfma_f32_16x16x32_bf16 v[92:95], v[170:173], v[162:165], v[92:95]
	v_mfma_f32_16x16x32_bf16 v[104:107], v[36:39], v[166:169], v[104:107]
	v_mfma_f32_16x16x32_bf16 v[88:91], v[36:39], v[162:165], v[88:91]
	v_mfma_f32_16x16x32_bf16 v[100:103], v[178:181], v[166:169], v[100:103]
	v_mfma_f32_16x16x32_bf16 v[84:87], v[178:181], v[162:165], v[84:87]
	v_mfma_f32_16x16x32_bf16 v[96:99], v[20:23], v[166:169], v[96:99]
	v_mfma_f32_16x16x32_bf16 v[80:83], v[20:23], v[162:165], v[80:83]
	v_mfma_f32_16x16x32_bf16 v[20:23], v[20:23], v[138:141], v[0:3]
	ds_read_b128 v[138:141], v190 offset:1024
	ds_read_b128 v[160:163], v190 offset:3072
	ds_read_b128 v[164:167], v190 offset:5120
	ds_read_b128 v[168:171], v190 offset:7168
	ds_read_b128 v[0:3], v189 offset:1024
	ds_read_b128 v[4:7], v188 offset:1024
	ds_read_b128 v[32:35], v187 offset:1024
	ds_read_b128 v[36:39], v186 offset:1024
	s_waitcnt lgkmcnt(3)
	v_mfma_f32_16x16x32_bf16 v[178:181], v[138:141], v[0:3], v[72:75]
	v_mfma_f32_16x16x32_bf16 v[186:189], v[160:163], v[0:3], v[68:71]
	v_mfma_f32_16x16x32_bf16 v[190:193], v[164:167], v[0:3], v[64:67]
	v_mfma_f32_16x16x32_bf16 v[194:197], v[168:171], v[0:3], v[8:11]
	ds_read_b128 v[0:3], v198 offset:1024
	s_waitcnt lgkmcnt(3)
	v_mfma_f32_16x16x32_bf16 v[108:111], v[138:141], v[4:7], v[108:111]
	v_mfma_f32_16x16x32_bf16 v[104:107], v[160:163], v[4:7], v[104:107]
	v_mfma_f32_16x16x32_bf16 v[198:201], v[164:167], v[4:7], v[100:103]
	v_mfma_f32_16x16x32_bf16 v[202:205], v[168:171], v[4:7], v[96:99]
	ds_read_b128 v[4:7], v206 offset:1024
	s_waitcnt lgkmcnt(3)
	v_mfma_f32_16x16x32_bf16 v[64:67], v[138:141], v[32:35], v[92:95]
	v_mfma_f32_16x16x32_bf16 v[68:71], v[160:163], v[32:35], v[88:91]
	v_mfma_f32_16x16x32_bf16 v[72:75], v[164:167], v[32:35], v[84:87]
	v_mfma_f32_16x16x32_bf16 v[76:79], v[168:171], v[32:35], v[80:83]
	ds_read_b128 v[96:99], v151 offset:1024
	s_waitcnt lgkmcnt(3)
	v_mfma_f32_16x16x32_bf16 v[80:83], v[138:141], v[36:39], v[124:127]
	v_mfma_f32_16x16x32_bf16 v[84:87], v[160:163], v[36:39], v[120:123]
	v_mfma_f32_16x16x32_bf16 v[88:91], v[164:167], v[36:39], v[116:119]
	v_mfma_f32_16x16x32_bf16 v[92:95], v[168:171], v[36:39], v[112:115]
	ds_read_b128 v[100:103], v130 offset:1024
	s_waitcnt lgkmcnt(3)
	v_mfma_f32_16x16x32_bf16 v[32:35], v[138:141], v[0:3], v[60:63]
	v_mfma_f32_16x16x32_bf16 v[36:39], v[160:163], v[0:3], v[56:59]
	v_mfma_f32_16x16x32_bf16 v[40:43], v[164:167], v[0:3], v[52:55]
	v_mfma_f32_16x16x32_bf16 v[44:47], v[168:171], v[0:3], v[48:51]
	s_waitcnt lgkmcnt(2)
	v_mfma_f32_16x16x32_bf16 v[48:51], v[138:141], v[4:7], v[146:149]
	v_mfma_f32_16x16x32_bf16 v[52:55], v[160:163], v[4:7], v[152:155]
	v_mfma_f32_16x16x32_bf16 v[56:59], v[164:167], v[4:7], v[156:159]
	v_mfma_f32_16x16x32_bf16 v[60:63], v[168:171], v[4:7], v[24:27]
	s_waitcnt lgkmcnt(1)
	v_mfma_f32_16x16x32_bf16 v[0:3], v[138:141], v[96:99], v[16:19]
	v_mfma_f32_16x16x32_bf16 v[4:7], v[160:163], v[96:99], v[12:15]
	v_mfma_f32_16x16x32_bf16 v[8:11], v[164:167], v[96:99], v[142:145]
	v_mfma_f32_16x16x32_bf16 v[12:15], v[168:171], v[96:99], v[20:23]
	s_waitcnt lgkmcnt(0)
	v_mfma_f32_16x16x32_bf16 v[16:19], v[138:141], v[100:103], v[174:177]
	v_mfma_f32_16x16x32_bf16 v[20:23], v[160:163], v[100:103], v[28:31]
	v_mfma_f32_16x16x32_bf16 v[24:27], v[164:167], v[100:103], v[182:185]
	v_mfma_f32_16x16x32_bf16 v[28:31], v[168:171], v[100:103], v[134:137]
	v_lshrrev_b32_e32 v96, 6, v150
	v_lshlrev_b32_e32 v98, 2, v150
	v_and_b32_e32 v97, 15, v150
	v_mul_lo_u32 v96, v96, s48
	v_and_b32_e32 v112, 60, v98
	v_bfe_u32 v99, v150, 4, 2
	v_add_u32_e32 v96, s46, v96
	v_and_b32_e32 v100, 48, v150
	v_lshlrev_b32_e32 v98, 2, v112
	v_mul_u32_u24_e32 v101, 0x110, v99
	v_mul_u32_u24_e32 v97, 0x110, v97
	v_add3_u32 v98, v96, v98, v101
	v_add3_u32 v101, v96, v100, v97
	s_waitcnt vmcnt(0)
	s_barrier
	ds_write_b128 v101, v[178:181]
	ds_write_b128 v101, v[186:189] offset:64
	ds_write_b128 v101, v[190:193] offset:128
	ds_write_b128 v101, v[194:197] offset:192
	ds_write_b128 v101, v[108:111] offset:4352
	ds_write_b128 v101, v[104:107] offset:4416
	ds_write_b128 v101, v[198:201] offset:4480
	ds_write_b128 v101, v[202:205] offset:4544
	ds_read_b128 v[102:105], v98
	v_ashrrev_i32_e32 v113, 1, v150
	v_and_b32_e32 v96, 0xffffff80, v113
	v_and_or_b32 v106, v150, s49, v112
	v_add_u32_e32 v100, s28, v96
	s_waitcnt lgkmcnt(0)
	v_mul_f32_e32 v102, 0xbfb8aa3b, v102
	v_mul_f32_e32 v103, 0xbfb8aa3b, v103
	v_mul_f32_e32 v104, 0xbfb8aa3b, v104
	v_mul_f32_e32 v105, 0xbfb8aa3b, v105
	v_exp_f32_e32 v102, v102
	v_exp_f32_e32 v103, v103
	v_exp_f32_e32 v104, v104
	v_exp_f32_e32 v105, v105
	v_add_f32_e32 v102, 1.0, v102
	v_add_f32_e32 v103, 1.0, v103
	v_add_f32_e32 v104, 1.0, v104
	v_add_f32_e32 v105, 1.0, v105
	v_rcp_f32_e32 v102, v102
	v_rcp_f32_e32 v103, v103
	v_rcp_f32_e32 v104, v104
	v_rcp_f32_e32 v105, v105
	v_lshl_add_u64 v[96:97], v[128:129], 0, s[38:39]
	v_lshlrev_b32_e32 v130, 1, v106
	v_cvt_pk_bf16_f32 v102, v102, v103
	v_cvt_pk_bf16_f32 v103, v104, v105
	v_or_b32_e32 v104, v100, v99
	v_add_co_u32_e32 v96, vcc, v96, v130
	v_addc_co_u32_e32 v97, vcc, v97, v131, vcc
	v_ashrrev_i32_e32 v105, 31, v104
	v_lshl_add_u64 v[96:97], v[96:97], 0, s[26:27]
	v_lshlrev_b64 v[104:105], 11, v[104:105]
	v_add_co_u32_e32 v104, vcc, v96, v104
	v_addc_co_u32_e32 v105, vcc, v97, v105, vcc
	flat_store_dwordx2 v[104:105], v[102:103]
	ds_read_b128 v[102:105], v98 offset:1088
	v_mov_b32_e32 v150, v132
	s_waitcnt lgkmcnt(0)
	v_mul_f32_e32 v102, 0xbfb8aa3b, v102
	v_exp_f32_e32 v102, v102
	v_mul_f32_e32 v103, 0xbfb8aa3b, v103
	v_exp_f32_e32 v103, v103
	v_add_f32_e32 v102, 1.0, v102
	v_rcp_f32_e32 v106, v102
	v_add_f32_e32 v102, 1.0, v103
	v_mul_f32_e32 v103, 0xbfb8aa3b, v104
	v_exp_f32_e32 v103, v103
	v_mul_f32_e32 v104, 0xbfb8aa3b, v105
	v_exp_f32_e32 v104, v104
	v_rcp_f32_e32 v105, v102
	v_add_f32_e32 v102, 1.0, v103
	v_rcp_f32_e32 v103, v102
	v_add_f32_e32 v102, 1.0, v104
	v_rcp_f32_e32 v107, v102
	v_or_b32_e32 v102, 4, v99
	v_cvt_pk_bf16_f32 v104, v106, v105
	v_or_b32_e32 v106, v100, v102
	v_cvt_pk_bf16_f32 v105, v103, v107
	v_lshlrev_b32_e32 v106, 11, v106
	v_add_co_u32_e32 v106, vcc, v96, v106
	v_addc_co_u32_e32 v107, vcc, 0, v97, vcc
	flat_store_dwordx2 v[106:107], v[104:105]
	ds_read_b128 v[104:107], v98 offset:2176
	s_waitcnt lgkmcnt(0)
	v_mul_f32_e32 v103, 0xbfb8aa3b, v104
	v_exp_f32_e32 v103, v103
	v_mul_f32_e32 v104, 0xbfb8aa3b, v105
	v_exp_f32_e32 v104, v104
	v_add_f32_e32 v103, 1.0, v103
	v_rcp_f32_e32 v105, v103
	v_add_f32_e32 v103, 1.0, v104
	v_mul_f32_e32 v104, 0xbfb8aa3b, v106
	v_exp_f32_e32 v104, v104
	v_mul_f32_e32 v106, 0xbfb8aa3b, v107
	v_exp_f32_e32 v106, v106
	v_rcp_f32_e32 v107, v103
	v_add_f32_e32 v103, 1.0, v104
	v_rcp_f32_e32 v108, v103
	v_add_f32_e32 v103, 1.0, v106
	v_rcp_f32_e32 v106, v103
	v_or_b32_e32 v103, 8, v99
	v_cvt_pk_bf16_f32 v104, v105, v107
	v_cvt_pk_bf16_f32 v105, v108, v106
	v_or_b32_e32 v106, v100, v103
	v_lshlrev_b32_e32 v106, 11, v106
	v_add_co_u32_e32 v106, vcc, v96, v106
	v_addc_co_u32_e32 v107, vcc, 0, v97, vcc
	flat_store_dwordx2 v[106:107], v[104:105]
	ds_read_b128 v[104:107], v98 offset:3264
	s_waitcnt lgkmcnt(0)
	v_mul_f32_e32 v104, 0xbfb8aa3b, v104
	v_exp_f32_e32 v104, v104
	v_mul_f32_e32 v105, 0xbfb8aa3b, v105
	v_exp_f32_e32 v105, v105
	v_add_f32_e32 v104, 1.0, v104
	v_rcp_f32_e32 v108, v104
	v_add_f32_e32 v104, 1.0, v105
	v_mul_f32_e32 v105, 0xbfb8aa3b, v106
	v_exp_f32_e32 v105, v105
	v_mul_f32_e32 v106, 0xbfb8aa3b, v107
	v_exp_f32_e32 v106, v106
	v_rcp_f32_e32 v107, v104
	v_add_f32_e32 v104, 1.0, v105
	v_rcp_f32_e32 v105, v104
	v_add_f32_e32 v104, 1.0, v106
	v_rcp_f32_e32 v109, v104
	v_or_b32_e32 v104, 12, v99
	v_cvt_pk_bf16_f32 v106, v108, v107
	v_or_b32_e32 v108, v100, v104
	v_cvt_pk_bf16_f32 v107, v105, v109
	v_lshlrev_b32_e32 v108, 11, v108
	v_add_co_u32_e32 v108, vcc, v96, v108
	v_addc_co_u32_e32 v109, vcc, 0, v97, vcc
	flat_store_dwordx2 v[108:109], v[106:107]
	ds_read_b128 v[106:109], v98 offset:4352
	s_waitcnt lgkmcnt(0)
	v_mul_f32_e32 v105, 0xbfb8aa3b, v106
	v_exp_f32_e32 v105, v105
	v_mul_f32_e32 v106, 0xbfb8aa3b, v107
	v_exp_f32_e32 v106, v106
	v_add_f32_e32 v105, 1.0, v105
	v_rcp_f32_e32 v107, v105
	v_add_f32_e32 v105, 1.0, v106
	v_mul_f32_e32 v106, 0xbfb8aa3b, v108
	v_exp_f32_e32 v106, v106
	v_mul_f32_e32 v108, 0xbfb8aa3b, v109
	v_exp_f32_e32 v108, v108
	v_rcp_f32_e32 v109, v105
	v_add_f32_e32 v105, 1.0, v106
	v_rcp_f32_e32 v110, v105
	v_add_f32_e32 v105, 1.0, v108
	v_rcp_f32_e32 v108, v105
	v_or_b32_e32 v105, 16, v99
	v_cvt_pk_bf16_f32 v106, v107, v109
	v_cvt_pk_bf16_f32 v107, v110, v108
	v_or_b32_e32 v108, v100, v105
	v_lshlrev_b32_e32 v108, 11, v108
	v_add_co_u32_e32 v108, vcc, v96, v108
	v_addc_co_u32_e32 v109, vcc, 0, v97, vcc
	flat_store_dwordx2 v[108:109], v[106:107]
	ds_read_b128 v[106:109], v98 offset:5440
	s_waitcnt lgkmcnt(0)
	v_mul_f32_e32 v106, 0xbfb8aa3b, v106
	v_exp_f32_e32 v106, v106
	v_mul_f32_e32 v107, 0xbfb8aa3b, v107
	v_exp_f32_e32 v107, v107
	v_add_f32_e32 v106, 1.0, v106
	v_rcp_f32_e32 v110, v106
	v_add_f32_e32 v106, 1.0, v107
	v_mul_f32_e32 v107, 0xbfb8aa3b, v108
	v_exp_f32_e32 v107, v107
	v_mul_f32_e32 v108, 0xbfb8aa3b, v109
	v_exp_f32_e32 v108, v108
	v_rcp_f32_e32 v109, v106
	v_add_f32_e32 v106, 1.0, v107
	v_rcp_f32_e32 v107, v106
	v_add_f32_e32 v106, 1.0, v108
	v_rcp_f32_e32 v111, v106
	v_or_b32_e32 v106, 20, v99
	v_cvt_pk_bf16_f32 v108, v110, v109
	v_or_b32_e32 v110, v100, v106
	v_cvt_pk_bf16_f32 v109, v107, v111
	v_lshlrev_b32_e32 v110, 11, v110
	v_add_co_u32_e32 v110, vcc, v96, v110
	v_addc_co_u32_e32 v111, vcc, 0, v97, vcc
	flat_store_dwordx2 v[110:111], v[108:109]
	ds_read_b128 v[108:111], v98 offset:6528
	s_waitcnt lgkmcnt(0)
	v_mul_f32_e32 v107, 0xbfb8aa3b, v108
	v_exp_f32_e32 v107, v107
	v_mul_f32_e32 v108, 0xbfb8aa3b, v109
	v_exp_f32_e32 v108, v108
	v_add_f32_e32 v107, 1.0, v107
	v_rcp_f32_e32 v109, v107
	v_add_f32_e32 v107, 1.0, v108
	v_mul_f32_e32 v108, 0xbfb8aa3b, v110
	v_exp_f32_e32 v108, v108
	v_mul_f32_e32 v110, 0xbfb8aa3b, v111
	v_exp_f32_e32 v110, v110
	v_rcp_f32_e32 v111, v107
	v_add_f32_e32 v107, 1.0, v108
	v_rcp_f32_e32 v112, v107
	v_add_f32_e32 v107, 1.0, v110
	v_rcp_f32_e32 v110, v107
	v_or_b32_e32 v107, 24, v99
	v_cvt_pk_bf16_f32 v108, v109, v111
	v_cvt_pk_bf16_f32 v109, v112, v110
	v_or_b32_e32 v110, v100, v107
	v_lshlrev_b32_e32 v110, 11, v110
	v_add_co_u32_e32 v110, vcc, v96, v110
	v_addc_co_u32_e32 v111, vcc, 0, v97, vcc
	flat_store_dwordx2 v[110:111], v[108:109]
	ds_read_b128 v[108:111], v98 offset:7616
	s_waitcnt lgkmcnt(0)
	v_mul_f32_e32 v108, 0xbfb8aa3b, v108
	v_exp_f32_e32 v108, v108
	v_mul_f32_e32 v109, 0xbfb8aa3b, v109
	v_exp_f32_e32 v109, v109
	v_add_f32_e32 v108, 1.0, v108
	v_rcp_f32_e32 v112, v108
	v_add_f32_e32 v108, 1.0, v109
	v_mul_f32_e32 v109, 0xbfb8aa3b, v110
	v_exp_f32_e32 v109, v109
	v_mul_f32_e32 v110, 0xbfb8aa3b, v111
	v_exp_f32_e32 v110, v110
	v_rcp_f32_e32 v111, v108
	v_add_f32_e32 v108, 1.0, v109
	v_rcp_f32_e32 v109, v108
	v_add_f32_e32 v108, 1.0, v110
	v_rcp_f32_e32 v113, v108
	v_or_b32_e32 v108, 28, v99
	v_cvt_pk_bf16_f32 v110, v112, v111
	v_or_b32_e32 v112, v100, v108
	v_cvt_pk_bf16_f32 v111, v109, v113
	v_lshlrev_b32_e32 v112, 11, v112
	v_add_co_u32_e32 v112, vcc, v96, v112
	v_addc_co_u32_e32 v113, vcc, 0, v97, vcc
	flat_store_dwordx2 v[112:113], v[110:111]
	ds_write_b128 v101, v[64:67]
	ds_write_b128 v101, v[68:71] offset:64
	ds_write_b128 v101, v[72:75] offset:128
	ds_write_b128 v101, v[76:79] offset:192
	ds_write_b128 v101, v[80:83] offset:4352
	ds_write_b128 v101, v[84:87] offset:4416
	ds_write_b128 v101, v[88:91] offset:4480
	ds_write_b128 v101, v[92:95] offset:4544
	ds_read_b128 v[64:67], v98
	v_or_b32_e32 v68, 32, v100
	s_waitcnt lgkmcnt(0)
	v_mul_f32_e32 v64, 0xbfb8aa3b, v64
	v_mul_f32_e32 v65, 0xbfb8aa3b, v65
	v_mul_f32_e32 v66, 0xbfb8aa3b, v66
	v_mul_f32_e32 v67, 0xbfb8aa3b, v67
	v_exp_f32_e32 v64, v64
	v_exp_f32_e32 v65, v65
	v_exp_f32_e32 v66, v66
	v_exp_f32_e32 v67, v67
	v_add_f32_e32 v64, 1.0, v64
	v_add_f32_e32 v65, 1.0, v65
	v_add_f32_e32 v66, 1.0, v66
	v_add_f32_e32 v67, 1.0, v67
	v_rcp_f32_e32 v64, v64
	v_rcp_f32_e32 v65, v65
	v_rcp_f32_e32 v66, v66
	v_rcp_f32_e32 v67, v67
	v_cvt_pk_bf16_f32 v64, v64, v65
	v_cvt_pk_bf16_f32 v65, v66, v67
	v_or_b32_e32 v66, v68, v99
	v_lshlrev_b32_e32 v66, 11, v66
	v_add_co_u32_e32 v66, vcc, v96, v66
	v_addc_co_u32_e32 v67, vcc, 0, v97, vcc
	flat_store_dwordx2 v[66:67], v[64:65]
	ds_read_b128 v[64:67], v98 offset:1088
	s_waitcnt lgkmcnt(0)
	v_mul_f32_e32 v64, 0xbfb8aa3b, v64
	v_mul_f32_e32 v65, 0xbfb8aa3b, v65
	v_mul_f32_e32 v66, 0xbfb8aa3b, v66
	v_mul_f32_e32 v67, 0xbfb8aa3b, v67
	v_exp_f32_e32 v64, v64
	v_exp_f32_e32 v65, v65
	v_exp_f32_e32 v66, v66
	v_exp_f32_e32 v67, v67
	v_add_f32_e32 v64, 1.0, v64
	v_add_f32_e32 v65, 1.0, v65
	v_add_f32_e32 v66, 1.0, v66
	v_add_f32_e32 v67, 1.0, v67
	v_rcp_f32_e32 v64, v64
	v_rcp_f32_e32 v65, v65
	v_rcp_f32_e32 v66, v66
	v_rcp_f32_e32 v67, v67
	v_cvt_pk_bf16_f32 v64, v64, v65
	v_cvt_pk_bf16_f32 v65, v66, v67
	v_or_b32_e32 v66, v68, v102
	v_lshlrev_b32_e32 v66, 11, v66
	v_add_co_u32_e32 v66, vcc, v96, v66
	v_addc_co_u32_e32 v67, vcc, 0, v97, vcc
	flat_store_dwordx2 v[66:67], v[64:65]
	ds_read_b128 v[64:67], v98 offset:2176
	s_waitcnt lgkmcnt(0)
	v_mul_f32_e32 v64, 0xbfb8aa3b, v64
	v_mul_f32_e32 v65, 0xbfb8aa3b, v65
	v_mul_f32_e32 v66, 0xbfb8aa3b, v66
	v_mul_f32_e32 v67, 0xbfb8aa3b, v67
	v_exp_f32_e32 v64, v64
	v_exp_f32_e32 v65, v65
	v_exp_f32_e32 v66, v66
	v_exp_f32_e32 v67, v67
	v_add_f32_e32 v64, 1.0, v64
	v_add_f32_e32 v65, 1.0, v65
	v_add_f32_e32 v66, 1.0, v66
	v_add_f32_e32 v67, 1.0, v67
	v_rcp_f32_e32 v64, v64
	v_rcp_f32_e32 v65, v65
	v_rcp_f32_e32 v66, v66
	v_rcp_f32_e32 v67, v67
	v_cvt_pk_bf16_f32 v64, v64, v65
	v_cvt_pk_bf16_f32 v65, v66, v67
	v_or_b32_e32 v66, v68, v103
	v_lshlrev_b32_e32 v66, 11, v66
	v_add_co_u32_e32 v66, vcc, v96, v66
	v_addc_co_u32_e32 v67, vcc, 0, v97, vcc
	flat_store_dwordx2 v[66:67], v[64:65]
	ds_read_b128 v[64:67], v98 offset:3264
	s_waitcnt lgkmcnt(0)
	v_mul_f32_e32 v64, 0xbfb8aa3b, v64
	v_mul_f32_e32 v65, 0xbfb8aa3b, v65
	v_mul_f32_e32 v66, 0xbfb8aa3b, v66
	v_mul_f32_e32 v67, 0xbfb8aa3b, v67
	v_exp_f32_e32 v64, v64
	v_exp_f32_e32 v65, v65
	v_exp_f32_e32 v66, v66
	v_exp_f32_e32 v67, v67
	v_add_f32_e32 v64, 1.0, v64
	v_add_f32_e32 v65, 1.0, v65
	v_add_f32_e32 v66, 1.0, v66
	v_add_f32_e32 v67, 1.0, v67
	v_rcp_f32_e32 v64, v64
	v_rcp_f32_e32 v65, v65
	v_rcp_f32_e32 v66, v66
	v_rcp_f32_e32 v67, v67
	v_cvt_pk_bf16_f32 v64, v64, v65
	v_cvt_pk_bf16_f32 v65, v66, v67
	v_or_b32_e32 v66, v68, v104
	v_lshlrev_b32_e32 v66, 11, v66
	v_add_co_u32_e32 v66, vcc, v96, v66
	v_addc_co_u32_e32 v67, vcc, 0, v97, vcc
	flat_store_dwordx2 v[66:67], v[64:65]
	ds_read_b128 v[64:67], v98 offset:4352
	s_waitcnt lgkmcnt(0)
	v_mul_f32_e32 v64, 0xbfb8aa3b, v64
	v_mul_f32_e32 v65, 0xbfb8aa3b, v65
	v_mul_f32_e32 v66, 0xbfb8aa3b, v66
	v_mul_f32_e32 v67, 0xbfb8aa3b, v67
	v_exp_f32_e32 v64, v64
	v_exp_f32_e32 v65, v65
	v_exp_f32_e32 v66, v66
	v_exp_f32_e32 v67, v67
	v_add_f32_e32 v64, 1.0, v64
	v_add_f32_e32 v65, 1.0, v65
	v_add_f32_e32 v66, 1.0, v66
	v_add_f32_e32 v67, 1.0, v67
	v_rcp_f32_e32 v64, v64
	v_rcp_f32_e32 v65, v65
	v_rcp_f32_e32 v66, v66
	v_rcp_f32_e32 v67, v67
	v_cvt_pk_bf16_f32 v64, v64, v65
	v_cvt_pk_bf16_f32 v65, v66, v67
	v_or_b32_e32 v66, v68, v105
	v_lshlrev_b32_e32 v66, 11, v66
	v_add_co_u32_e32 v66, vcc, v96, v66
	v_addc_co_u32_e32 v67, vcc, 0, v97, vcc
	flat_store_dwordx2 v[66:67], v[64:65]
	ds_read_b128 v[64:67], v98 offset:5440
	s_waitcnt lgkmcnt(0)
	v_mul_f32_e32 v64, 0xbfb8aa3b, v64
	v_mul_f32_e32 v65, 0xbfb8aa3b, v65
	v_mul_f32_e32 v66, 0xbfb8aa3b, v66
	v_mul_f32_e32 v67, 0xbfb8aa3b, v67
	v_exp_f32_e32 v64, v64
	v_exp_f32_e32 v65, v65
	v_exp_f32_e32 v66, v66
	v_exp_f32_e32 v67, v67
	v_add_f32_e32 v64, 1.0, v64
	v_add_f32_e32 v65, 1.0, v65
	v_add_f32_e32 v66, 1.0, v66
	v_add_f32_e32 v67, 1.0, v67
	v_rcp_f32_e32 v64, v64
	v_rcp_f32_e32 v65, v65
	v_rcp_f32_e32 v66, v66
	v_rcp_f32_e32 v67, v67
	v_cvt_pk_bf16_f32 v64, v64, v65
	v_cvt_pk_bf16_f32 v65, v66, v67
	v_or_b32_e32 v66, v68, v106
	v_lshlrev_b32_e32 v66, 11, v66
	v_add_co_u32_e32 v66, vcc, v96, v66
	v_addc_co_u32_e32 v67, vcc, 0, v97, vcc
	flat_store_dwordx2 v[66:67], v[64:65]
	ds_read_b128 v[64:67], v98 offset:6528
	s_waitcnt lgkmcnt(0)
	v_mul_f32_e32 v64, 0xbfb8aa3b, v64
	v_mul_f32_e32 v65, 0xbfb8aa3b, v65
	v_mul_f32_e32 v66, 0xbfb8aa3b, v66
	v_mul_f32_e32 v67, 0xbfb8aa3b, v67
	v_exp_f32_e32 v64, v64
	v_exp_f32_e32 v65, v65
	v_exp_f32_e32 v66, v66
	v_exp_f32_e32 v67, v67
	v_add_f32_e32 v64, 1.0, v64
	v_add_f32_e32 v65, 1.0, v65
	v_add_f32_e32 v66, 1.0, v66
	v_add_f32_e32 v67, 1.0, v67
	v_rcp_f32_e32 v64, v64
	v_rcp_f32_e32 v65, v65
	v_rcp_f32_e32 v66, v66
	v_rcp_f32_e32 v67, v67
	v_cvt_pk_bf16_f32 v64, v64, v65
	v_cvt_pk_bf16_f32 v65, v66, v67
	v_or_b32_e32 v66, v68, v107
	v_lshlrev_b32_e32 v66, 11, v66
	v_add_co_u32_e32 v66, vcc, v96, v66
	v_addc_co_u32_e32 v67, vcc, 0, v97, vcc
	flat_store_dwordx2 v[66:67], v[64:65]
	ds_read_b128 v[64:67], v98 offset:7616
	s_waitcnt lgkmcnt(0)
	v_mul_f32_e32 v64, 0xbfb8aa3b, v64
	v_mul_f32_e32 v65, 0xbfb8aa3b, v65
	v_mul_f32_e32 v66, 0xbfb8aa3b, v66
	v_mul_f32_e32 v67, 0xbfb8aa3b, v67
	v_exp_f32_e32 v64, v64
	v_exp_f32_e32 v65, v65
	v_exp_f32_e32 v66, v66
	v_exp_f32_e32 v67, v67
	v_add_f32_e32 v64, 1.0, v64
	v_add_f32_e32 v65, 1.0, v65
	v_add_f32_e32 v66, 1.0, v66
	v_add_f32_e32 v67, 1.0, v67
	v_rcp_f32_e32 v64, v64
	v_rcp_f32_e32 v65, v65
	v_rcp_f32_e32 v66, v66
	v_rcp_f32_e32 v67, v67
	v_cvt_pk_bf16_f32 v64, v64, v65
	v_cvt_pk_bf16_f32 v65, v66, v67
	v_or_b32_e32 v66, v68, v108
	v_lshlrev_b32_e32 v66, 11, v66
	v_add_co_u32_e32 v66, vcc, v96, v66
	v_addc_co_u32_e32 v67, vcc, 0, v97, vcc
	flat_store_dwordx2 v[66:67], v[64:65]
	ds_write_b128 v101, v[32:35]
	ds_write_b128 v101, v[36:39] offset:64
	ds_write_b128 v101, v[40:43] offset:128
	ds_write_b128 v101, v[44:47] offset:192
	ds_write_b128 v101, v[48:51] offset:4352
	ds_write_b128 v101, v[52:55] offset:4416
	ds_write_b128 v101, v[56:59] offset:4480
	ds_write_b128 v101, v[60:63] offset:4544
	ds_read_b128 v[32:35], v98
	v_or_b32_e32 v36, 64, v100
	s_waitcnt lgkmcnt(0)
	v_mul_f32_e32 v32, 0xbfb8aa3b, v32
	v_mul_f32_e32 v33, 0xbfb8aa3b, v33
	v_mul_f32_e32 v34, 0xbfb8aa3b, v34
	v_mul_f32_e32 v35, 0xbfb8aa3b, v35
	v_exp_f32_e32 v32, v32
	v_exp_f32_e32 v33, v33
	v_exp_f32_e32 v34, v34
	v_exp_f32_e32 v35, v35
	v_add_f32_e32 v32, 1.0, v32
	v_add_f32_e32 v33, 1.0, v33
	v_add_f32_e32 v34, 1.0, v34
	v_add_f32_e32 v35, 1.0, v35
	v_rcp_f32_e32 v32, v32
	v_rcp_f32_e32 v33, v33
	v_rcp_f32_e32 v34, v34
	v_rcp_f32_e32 v35, v35
	v_cvt_pk_bf16_f32 v32, v32, v33
	v_cvt_pk_bf16_f32 v33, v34, v35
	v_or_b32_e32 v34, v36, v99
	v_lshlrev_b32_e32 v34, 11, v34
	v_add_co_u32_e32 v34, vcc, v96, v34
	v_addc_co_u32_e32 v35, vcc, 0, v97, vcc
	flat_store_dwordx2 v[34:35], v[32:33]
	ds_read_b128 v[32:35], v98 offset:1088
	s_waitcnt lgkmcnt(0)
	v_mul_f32_e32 v32, 0xbfb8aa3b, v32
	v_mul_f32_e32 v33, 0xbfb8aa3b, v33
	v_mul_f32_e32 v34, 0xbfb8aa3b, v34
	v_mul_f32_e32 v35, 0xbfb8aa3b, v35
	v_exp_f32_e32 v32, v32
	v_exp_f32_e32 v33, v33
	v_exp_f32_e32 v34, v34
	v_exp_f32_e32 v35, v35
	v_add_f32_e32 v32, 1.0, v32
	v_add_f32_e32 v33, 1.0, v33
	v_add_f32_e32 v34, 1.0, v34
	v_add_f32_e32 v35, 1.0, v35
	v_rcp_f32_e32 v32, v32
	v_rcp_f32_e32 v33, v33
	v_rcp_f32_e32 v34, v34
	v_rcp_f32_e32 v35, v35
	v_cvt_pk_bf16_f32 v32, v32, v33
	v_cvt_pk_bf16_f32 v33, v34, v35
	v_or_b32_e32 v34, v36, v102
	v_lshlrev_b32_e32 v34, 11, v34
	v_add_co_u32_e32 v34, vcc, v96, v34
	v_addc_co_u32_e32 v35, vcc, 0, v97, vcc
	flat_store_dwordx2 v[34:35], v[32:33]
	ds_read_b128 v[32:35], v98 offset:2176
	s_waitcnt lgkmcnt(0)
	v_mul_f32_e32 v32, 0xbfb8aa3b, v32
	v_mul_f32_e32 v33, 0xbfb8aa3b, v33
	v_mul_f32_e32 v34, 0xbfb8aa3b, v34
	v_mul_f32_e32 v35, 0xbfb8aa3b, v35
	v_exp_f32_e32 v32, v32
	v_exp_f32_e32 v33, v33
	v_exp_f32_e32 v34, v34
	v_exp_f32_e32 v35, v35
	v_add_f32_e32 v32, 1.0, v32
	v_add_f32_e32 v33, 1.0, v33
	v_add_f32_e32 v34, 1.0, v34
	v_add_f32_e32 v35, 1.0, v35
	v_rcp_f32_e32 v32, v32
	v_rcp_f32_e32 v33, v33
	v_rcp_f32_e32 v34, v34
	v_rcp_f32_e32 v35, v35
	v_cvt_pk_bf16_f32 v32, v32, v33
	v_cvt_pk_bf16_f32 v33, v34, v35
	v_or_b32_e32 v34, v36, v103
	v_lshlrev_b32_e32 v34, 11, v34
	v_add_co_u32_e32 v34, vcc, v96, v34
	v_addc_co_u32_e32 v35, vcc, 0, v97, vcc
	flat_store_dwordx2 v[34:35], v[32:33]
	ds_read_b128 v[32:35], v98 offset:3264
	s_waitcnt lgkmcnt(0)
	v_mul_f32_e32 v32, 0xbfb8aa3b, v32
	v_mul_f32_e32 v33, 0xbfb8aa3b, v33
	v_mul_f32_e32 v34, 0xbfb8aa3b, v34
	v_mul_f32_e32 v35, 0xbfb8aa3b, v35
	v_exp_f32_e32 v32, v32
	v_exp_f32_e32 v33, v33
	v_exp_f32_e32 v34, v34
	v_exp_f32_e32 v35, v35
	v_add_f32_e32 v32, 1.0, v32
	v_add_f32_e32 v33, 1.0, v33
	v_add_f32_e32 v34, 1.0, v34
	v_add_f32_e32 v35, 1.0, v35
	v_rcp_f32_e32 v32, v32
	v_rcp_f32_e32 v33, v33
	v_rcp_f32_e32 v34, v34
	v_rcp_f32_e32 v35, v35
	v_cvt_pk_bf16_f32 v32, v32, v33
	v_cvt_pk_bf16_f32 v33, v34, v35
	v_or_b32_e32 v34, v36, v104
	v_lshlrev_b32_e32 v34, 11, v34
	v_add_co_u32_e32 v34, vcc, v96, v34
	v_addc_co_u32_e32 v35, vcc, 0, v97, vcc
	flat_store_dwordx2 v[34:35], v[32:33]
	ds_read_b128 v[32:35], v98 offset:4352
	s_waitcnt lgkmcnt(0)
	v_mul_f32_e32 v32, 0xbfb8aa3b, v32
	v_mul_f32_e32 v33, 0xbfb8aa3b, v33
	v_mul_f32_e32 v34, 0xbfb8aa3b, v34
	v_mul_f32_e32 v35, 0xbfb8aa3b, v35
	v_exp_f32_e32 v32, v32
	v_exp_f32_e32 v33, v33
	v_exp_f32_e32 v34, v34
	v_exp_f32_e32 v35, v35
	v_add_f32_e32 v32, 1.0, v32
	v_add_f32_e32 v33, 1.0, v33
	v_add_f32_e32 v34, 1.0, v34
	v_add_f32_e32 v35, 1.0, v35
	v_rcp_f32_e32 v32, v32
	v_rcp_f32_e32 v33, v33
	v_rcp_f32_e32 v34, v34
	v_rcp_f32_e32 v35, v35
	v_cvt_pk_bf16_f32 v32, v32, v33
	v_cvt_pk_bf16_f32 v33, v34, v35
	v_or_b32_e32 v34, v36, v105
	v_lshlrev_b32_e32 v34, 11, v34
	v_add_co_u32_e32 v34, vcc, v96, v34
	v_addc_co_u32_e32 v35, vcc, 0, v97, vcc
	flat_store_dwordx2 v[34:35], v[32:33]
	ds_read_b128 v[32:35], v98 offset:5440
	s_waitcnt lgkmcnt(0)
	v_mul_f32_e32 v32, 0xbfb8aa3b, v32
	v_mul_f32_e32 v33, 0xbfb8aa3b, v33
	v_mul_f32_e32 v34, 0xbfb8aa3b, v34
	v_mul_f32_e32 v35, 0xbfb8aa3b, v35
	v_exp_f32_e32 v32, v32
	v_exp_f32_e32 v33, v33
	v_exp_f32_e32 v34, v34
	v_exp_f32_e32 v35, v35
	v_add_f32_e32 v32, 1.0, v32
	v_add_f32_e32 v33, 1.0, v33
	v_add_f32_e32 v34, 1.0, v34
	v_add_f32_e32 v35, 1.0, v35
	v_rcp_f32_e32 v32, v32
	v_rcp_f32_e32 v33, v33
	v_rcp_f32_e32 v34, v34
	v_rcp_f32_e32 v35, v35
	v_cvt_pk_bf16_f32 v32, v32, v33
	v_cvt_pk_bf16_f32 v33, v34, v35
	v_or_b32_e32 v34, v36, v106
	v_lshlrev_b32_e32 v34, 11, v34
	v_add_co_u32_e32 v34, vcc, v96, v34
	v_addc_co_u32_e32 v35, vcc, 0, v97, vcc
	flat_store_dwordx2 v[34:35], v[32:33]
	ds_read_b128 v[32:35], v98 offset:6528
	s_waitcnt lgkmcnt(0)
	v_mul_f32_e32 v32, 0xbfb8aa3b, v32
	v_mul_f32_e32 v33, 0xbfb8aa3b, v33
	v_mul_f32_e32 v34, 0xbfb8aa3b, v34
	v_mul_f32_e32 v35, 0xbfb8aa3b, v35
	v_exp_f32_e32 v32, v32
	v_exp_f32_e32 v33, v33
	v_exp_f32_e32 v34, v34
	v_exp_f32_e32 v35, v35
	v_add_f32_e32 v32, 1.0, v32
	v_add_f32_e32 v33, 1.0, v33
	v_add_f32_e32 v34, 1.0, v34
	v_add_f32_e32 v35, 1.0, v35
	v_rcp_f32_e32 v32, v32
	v_rcp_f32_e32 v33, v33
	v_rcp_f32_e32 v34, v34
	v_rcp_f32_e32 v35, v35
	v_cvt_pk_bf16_f32 v32, v32, v33
	v_cvt_pk_bf16_f32 v33, v34, v35
	v_or_b32_e32 v34, v36, v107
	v_lshlrev_b32_e32 v34, 11, v34
	v_add_co_u32_e32 v34, vcc, v96, v34
	v_addc_co_u32_e32 v35, vcc, 0, v97, vcc
	flat_store_dwordx2 v[34:35], v[32:33]
	ds_read_b128 v[32:35], v98 offset:7616
	s_waitcnt lgkmcnt(0)
	v_mul_f32_e32 v32, 0xbfb8aa3b, v32
	v_mul_f32_e32 v33, 0xbfb8aa3b, v33
	v_mul_f32_e32 v34, 0xbfb8aa3b, v34
	v_mul_f32_e32 v35, 0xbfb8aa3b, v35
	v_exp_f32_e32 v32, v32
	v_exp_f32_e32 v33, v33
	v_exp_f32_e32 v34, v34
	v_exp_f32_e32 v35, v35
	v_add_f32_e32 v32, 1.0, v32
	v_add_f32_e32 v33, 1.0, v33
	v_add_f32_e32 v34, 1.0, v34
	v_add_f32_e32 v35, 1.0, v35
	v_rcp_f32_e32 v32, v32
	v_rcp_f32_e32 v33, v33
	v_rcp_f32_e32 v34, v34
	v_rcp_f32_e32 v35, v35
	v_cvt_pk_bf16_f32 v32, v32, v33
	v_cvt_pk_bf16_f32 v33, v34, v35
	v_or_b32_e32 v34, v36, v108
	v_lshlrev_b32_e32 v34, 11, v34
	v_add_co_u32_e32 v34, vcc, v96, v34
	v_addc_co_u32_e32 v35, vcc, 0, v97, vcc
	flat_store_dwordx2 v[34:35], v[32:33]
	ds_write_b128 v101, v[0:3]
	ds_write_b128 v101, v[4:7] offset:64
	ds_write_b128 v101, v[8:11] offset:128
	ds_write_b128 v101, v[12:15] offset:192
	ds_write_b128 v101, v[16:19] offset:4352
	ds_write_b128 v101, v[20:23] offset:4416
	ds_write_b128 v101, v[24:27] offset:4480
	ds_write_b128 v101, v[28:31] offset:4544
	ds_read_b128 v[0:3], v98
	v_or_b32_e32 v4, 0x60, v100
	v_mov_b32_e32 v12, v132
	s_waitcnt lgkmcnt(0)
	v_mul_f32_e32 v0, 0xbfb8aa3b, v0
	v_mul_f32_e32 v1, 0xbfb8aa3b, v1
	v_mul_f32_e32 v2, 0xbfb8aa3b, v2
	v_mul_f32_e32 v3, 0xbfb8aa3b, v3
	v_exp_f32_e32 v0, v0
	v_exp_f32_e32 v1, v1
	v_exp_f32_e32 v2, v2
	v_exp_f32_e32 v3, v3
	v_add_f32_e32 v0, 1.0, v0
	v_add_f32_e32 v1, 1.0, v1
	v_add_f32_e32 v2, 1.0, v2
	v_add_f32_e32 v3, 1.0, v3
	v_rcp_f32_e32 v0, v0
	v_rcp_f32_e32 v1, v1
	v_rcp_f32_e32 v2, v2
	v_rcp_f32_e32 v3, v3
	v_cvt_pk_bf16_f32 v0, v0, v1
	v_cvt_pk_bf16_f32 v1, v2, v3
	v_or_b32_e32 v2, v4, v99
	v_lshlrev_b32_e32 v2, 11, v2
	v_add_co_u32_e32 v2, vcc, v96, v2
	v_addc_co_u32_e32 v3, vcc, 0, v97, vcc
	flat_store_dwordx2 v[2:3], v[0:1]
	ds_read_b128 v[0:3], v98 offset:1088
	s_waitcnt lgkmcnt(0)
	v_mul_f32_e32 v0, 0xbfb8aa3b, v0
	v_mul_f32_e32 v1, 0xbfb8aa3b, v1
	v_mul_f32_e32 v2, 0xbfb8aa3b, v2
	v_mul_f32_e32 v3, 0xbfb8aa3b, v3
	v_exp_f32_e32 v0, v0
	v_exp_f32_e32 v1, v1
	v_exp_f32_e32 v2, v2
	v_exp_f32_e32 v3, v3
	v_add_f32_e32 v0, 1.0, v0
	v_add_f32_e32 v1, 1.0, v1
	v_add_f32_e32 v2, 1.0, v2
	v_add_f32_e32 v3, 1.0, v3
	v_rcp_f32_e32 v0, v0
	v_rcp_f32_e32 v1, v1
	v_rcp_f32_e32 v2, v2
	v_rcp_f32_e32 v3, v3
	v_cvt_pk_bf16_f32 v0, v0, v1
	v_cvt_pk_bf16_f32 v1, v2, v3
	v_or_b32_e32 v2, v4, v102
	v_lshlrev_b32_e32 v2, 11, v2
	v_add_co_u32_e32 v2, vcc, v96, v2
	v_addc_co_u32_e32 v3, vcc, 0, v97, vcc
	flat_store_dwordx2 v[2:3], v[0:1]
	ds_read_b128 v[0:3], v98 offset:2176
	s_waitcnt lgkmcnt(0)
	v_mul_f32_e32 v0, 0xbfb8aa3b, v0
	v_mul_f32_e32 v1, 0xbfb8aa3b, v1
	v_mul_f32_e32 v2, 0xbfb8aa3b, v2
	v_mul_f32_e32 v3, 0xbfb8aa3b, v3
	v_exp_f32_e32 v0, v0
	v_exp_f32_e32 v1, v1
	v_exp_f32_e32 v2, v2
	v_exp_f32_e32 v3, v3
	v_add_f32_e32 v0, 1.0, v0
	v_add_f32_e32 v1, 1.0, v1
	v_add_f32_e32 v2, 1.0, v2
	v_add_f32_e32 v3, 1.0, v3
	v_rcp_f32_e32 v0, v0
	v_rcp_f32_e32 v1, v1
	v_rcp_f32_e32 v2, v2
	v_rcp_f32_e32 v3, v3
	v_cvt_pk_bf16_f32 v0, v0, v1
	v_cvt_pk_bf16_f32 v1, v2, v3
	v_or_b32_e32 v2, v4, v103
	v_lshlrev_b32_e32 v2, 11, v2
	v_add_co_u32_e32 v2, vcc, v96, v2
	v_addc_co_u32_e32 v3, vcc, 0, v97, vcc
	flat_store_dwordx2 v[2:3], v[0:1]
	ds_read_b128 v[0:3], v98 offset:3264
	s_waitcnt lgkmcnt(0)
	v_mul_f32_e32 v0, 0xbfb8aa3b, v0
	v_mul_f32_e32 v1, 0xbfb8aa3b, v1
	v_mul_f32_e32 v2, 0xbfb8aa3b, v2
	v_mul_f32_e32 v3, 0xbfb8aa3b, v3
	v_exp_f32_e32 v0, v0
	v_exp_f32_e32 v1, v1
	v_exp_f32_e32 v2, v2
	v_exp_f32_e32 v3, v3
	v_add_f32_e32 v0, 1.0, v0
	v_add_f32_e32 v1, 1.0, v1
	v_add_f32_e32 v2, 1.0, v2
	v_add_f32_e32 v3, 1.0, v3
	v_rcp_f32_e32 v0, v0
	v_rcp_f32_e32 v1, v1
	v_rcp_f32_e32 v2, v2
	v_rcp_f32_e32 v3, v3
	v_cvt_pk_bf16_f32 v0, v0, v1
	v_cvt_pk_bf16_f32 v1, v2, v3
	v_or_b32_e32 v2, v4, v104
	v_lshlrev_b32_e32 v2, 11, v2
	v_add_co_u32_e32 v2, vcc, v96, v2
	v_addc_co_u32_e32 v3, vcc, 0, v97, vcc
	flat_store_dwordx2 v[2:3], v[0:1]
	ds_read_b128 v[0:3], v98 offset:4352
	s_waitcnt lgkmcnt(0)
	v_mul_f32_e32 v0, 0xbfb8aa3b, v0
	v_mul_f32_e32 v1, 0xbfb8aa3b, v1
	v_mul_f32_e32 v2, 0xbfb8aa3b, v2
	v_mul_f32_e32 v3, 0xbfb8aa3b, v3
	v_exp_f32_e32 v0, v0
	v_exp_f32_e32 v1, v1
	v_exp_f32_e32 v2, v2
	v_exp_f32_e32 v3, v3
	v_add_f32_e32 v0, 1.0, v0
	v_add_f32_e32 v1, 1.0, v1
	v_add_f32_e32 v2, 1.0, v2
	v_add_f32_e32 v3, 1.0, v3
	v_rcp_f32_e32 v0, v0
	v_rcp_f32_e32 v1, v1
	v_rcp_f32_e32 v2, v2
	v_rcp_f32_e32 v3, v3
	v_cvt_pk_bf16_f32 v0, v0, v1
	v_cvt_pk_bf16_f32 v1, v2, v3
	v_or_b32_e32 v2, v4, v105
	v_lshlrev_b32_e32 v2, 11, v2
	v_add_co_u32_e32 v2, vcc, v96, v2
	v_addc_co_u32_e32 v3, vcc, 0, v97, vcc
	flat_store_dwordx2 v[2:3], v[0:1]
	ds_read_b128 v[0:3], v98 offset:5440
	s_waitcnt lgkmcnt(0)
	v_mul_f32_e32 v0, 0xbfb8aa3b, v0
	v_mul_f32_e32 v1, 0xbfb8aa3b, v1
	v_mul_f32_e32 v2, 0xbfb8aa3b, v2
	v_mul_f32_e32 v3, 0xbfb8aa3b, v3
	v_exp_f32_e32 v0, v0
	v_exp_f32_e32 v1, v1
	v_exp_f32_e32 v2, v2
	v_exp_f32_e32 v3, v3
	v_add_f32_e32 v0, 1.0, v0
	v_add_f32_e32 v1, 1.0, v1
	v_add_f32_e32 v2, 1.0, v2
	v_add_f32_e32 v3, 1.0, v3
	v_rcp_f32_e32 v0, v0
	v_rcp_f32_e32 v1, v1
	v_rcp_f32_e32 v2, v2
	v_rcp_f32_e32 v3, v3
	v_cvt_pk_bf16_f32 v0, v0, v1
	v_cvt_pk_bf16_f32 v1, v2, v3
	v_or_b32_e32 v2, v4, v106
	v_lshlrev_b32_e32 v2, 11, v2
	v_add_co_u32_e32 v2, vcc, v96, v2
	v_addc_co_u32_e32 v3, vcc, 0, v97, vcc
	flat_store_dwordx2 v[2:3], v[0:1]
	ds_read_b128 v[0:3], v98 offset:6528
	s_waitcnt lgkmcnt(0)
	v_mul_f32_e32 v0, 0xbfb8aa3b, v0
	v_mul_f32_e32 v1, 0xbfb8aa3b, v1
	v_mul_f32_e32 v2, 0xbfb8aa3b, v2
	v_mul_f32_e32 v3, 0xbfb8aa3b, v3
	v_exp_f32_e32 v0, v0
	v_exp_f32_e32 v1, v1
	v_exp_f32_e32 v2, v2
	v_exp_f32_e32 v3, v3
	v_add_f32_e32 v0, 1.0, v0
	v_add_f32_e32 v1, 1.0, v1
	v_add_f32_e32 v2, 1.0, v2
	v_add_f32_e32 v3, 1.0, v3
	v_rcp_f32_e32 v0, v0
	v_rcp_f32_e32 v1, v1
	v_rcp_f32_e32 v2, v2
	v_rcp_f32_e32 v3, v3
	v_cvt_pk_bf16_f32 v0, v0, v1
	v_cvt_pk_bf16_f32 v1, v2, v3
	v_or_b32_e32 v2, v4, v107
	v_ashrrev_i32_e32 v3, 31, v2
	v_lshlrev_b64 v[2:3], 11, v[2:3]
	v_add_co_u32_e32 v2, vcc, v96, v2
	v_addc_co_u32_e32 v3, vcc, v97, v3, vcc
	flat_store_dwordx2 v[2:3], v[0:1]
	ds_read_b128 v[0:3], v98 offset:7616
	s_waitcnt lgkmcnt(0)
	v_mul_f32_e32 v0, 0xbfb8aa3b, v0
	v_mul_f32_e32 v1, 0xbfb8aa3b, v1
	v_mul_f32_e32 v2, 0xbfb8aa3b, v2
	v_mul_f32_e32 v3, 0xbfb8aa3b, v3
	v_exp_f32_e32 v0, v0
	v_exp_f32_e32 v1, v1
	v_exp_f32_e32 v2, v2
	v_exp_f32_e32 v3, v3
	v_add_f32_e32 v0, 1.0, v0
	v_add_f32_e32 v1, 1.0, v1
	v_add_f32_e32 v2, 1.0, v2
	v_add_f32_e32 v3, 1.0, v3
	v_rcp_f32_e32 v0, v0
	v_rcp_f32_e32 v1, v1
	v_rcp_f32_e32 v2, v2
	v_rcp_f32_e32 v3, v3
	v_cvt_pk_bf16_f32 v0, v0, v1
	v_cvt_pk_bf16_f32 v1, v2, v3
	v_or_b32_e32 v2, v4, v108
	v_ashrrev_i32_e32 v3, 31, v2
	v_lshlrev_b64 v[2:3], 11, v[2:3]
	v_add_co_u32_e32 v2, vcc, v96, v2
	v_addc_co_u32_e32 v3, vcc, v97, v3, vcc
	flat_store_dwordx2 v[2:3], v[0:1]
	v_mov_b32_e32 v0, s3
	ds_read_b128 v[0:3], v0
	s_waitcnt lgkmcnt(0)
	v_readfirstlane_b32 s0, v3
	v_readfirstlane_b32 s29, v2
	v_lshlrev_b32_e32 v3, 4, v12
	v_and_b32_e32 v2, 32, v12
	s_add_u32 s42, s29, s36
	v_lshrrev_b32_e32 v4, 1, v12
	v_bitop3_b32 v2, v3, v2, 48 bitop3:0x6c
	s_addc_u32 s43, s0, s37
	v_bfe_u32 v13, v12, 2, 4
	v_and_b32_e32 v14, 32, v4
	v_lshrrev_b32_e32 v15, 1, v2
	v_ashrrev_i32_e32 v16, 3, v12
	s_add_u32 s36, s42, 0x18800000
	v_or_b32_e32 v6, v15, v14
	v_and_or_b32 v2, v16, s44, v13
	s_addc_u32 s37, s43, 0
	s_lshl_b64 s[38:39], s[30:31], 11
	v_and_b32_e32 v5, 0xfffffc00, v3
	v_lshl_or_b32 v130, v2, 10, v6
	v_add_u32_e32 v2, 0x2000, v3
	v_add_u32_e32 v4, 0x4000, v3
	v_add_u32_e32 v3, 0x6000, v3
	s_add_u32 s53, s29, s38
	v_ashrrev_i32_e32 v17, 7, v2
	v_ashrrev_i32_e32 v18, 7, v4
	v_ashrrev_i32_e32 v19, 7, v3
	s_addc_u32 s54, s0, s39
	v_and_or_b32 v2, v17, s44, v13
	v_and_or_b32 v4, v18, s44, v13
	v_and_or_b32 v3, v19, s44, v13
	v_add_u32_e32 v151, 0, v5
	s_add_u32 s38, s53, 0xe00000
	v_lshl_or_b32 v2, v2, 10, v6
	v_lshl_or_b32 v4, v4, 10, v6
	v_lshl_or_b32 v6, v3, 10, v6
	v_add_u32_e32 v3, 0x8000, v151
	v_lshlrev_b64 v[8:9], 1, v[130:131]
	v_readfirstlane_b32 s55, v151
	s_addc_u32 s39, s54, 0
	v_lshl_add_u64 v[10:11], s[36:37], 0, v[8:9]
	s_mov_b32 m0, s55
	v_readfirstlane_b32 s55, v3
	v_mov_b32_e32 v3, v131
	v_add_u32_e32 v5, 0x2000, v151
	global_load_lds_dwordx4 v[10:11], off
	v_lshl_add_u64 v[8:9], s[38:39], 0, v[8:9]
	s_mov_b32 m0, s55
	v_lshlrev_b64 v[2:3], 1, v[2:3]
	v_readfirstlane_b32 s55, v5
	v_add_u32_e32 v5, 0xa000, v151
	global_load_lds_dwordx4 v[8:9], off
	v_lshl_add_u64 v[8:9], s[36:37], 0, v[2:3]
	s_mov_b32 m0, s55
	v_readfirstlane_b32 s55, v5
	global_load_lds_dwordx4 v[8:9], off
	v_lshl_add_u64 v[2:3], s[38:39], 0, v[2:3]
	s_mov_b32 m0, s55
	v_mov_b32_e32 v5, v131
	v_add_u32_e32 v7, 0x4000, v151
	global_load_lds_dwordx4 v[2:3], off
	v_lshlrev_b64 v[2:3], 1, v[4:5]
	v_readfirstlane_b32 s55, v7
	v_lshl_add_u64 v[4:5], s[36:37], 0, v[2:3]
	s_mov_b32 m0, s55
	v_lshl_add_u64 v[2:3], s[38:39], 0, v[2:3]
	global_load_lds_dwordx4 v[4:5], off
	v_add_u32_e32 v4, 0xc000, v151
	v_mov_b32_e32 v7, v131
	v_readfirstlane_b32 s55, v4
	s_mov_b32 m0, s55
	v_and_b32_e32 v20, 15, v12
	global_load_lds_dwordx4 v[2:3], off
	v_lshlrev_b64 v[2:3], 1, v[6:7]
	v_add_u32_e32 v6, 0x6000, v151
	v_lshl_add_u64 v[4:5], s[36:37], 0, v[2:3]
	v_readfirstlane_b32 s36, v6
	s_mov_b32 m0, s36
	v_lshl_add_u64 v[2:3], s[38:39], 0, v[2:3]
	global_load_lds_dwordx4 v[4:5], off
	v_add_u32_e32 v4, 0xe000, v151
	v_lshlrev_b32_e32 v8, 10, v13
	v_readfirstlane_b32 s36, v4
	s_mov_b32 m0, s36
	v_lshlrev_b32_e32 v4, 2, v12
	global_load_lds_dwordx4 v[2:3], off
	v_and_b32_e32 v2, 48, v12
	v_lshlrev_b32_e32 v3, 6, v20
	v_and_b32_e32 v4, 32, v4
	v_bitop3_b32 v152, v3, v4, v2 bitop3:0x36
	v_lshlrev_b32_e32 v3, 7, v12
	v_and_b32_e32 v153, 0x6000, v3
	v_lshlrev_b32_e32 v3, 6, v12
	v_and_b32_e32 v154, 0xffffc000, v3
	v_and_b32_e32 v3, 0x3c0, v3
	v_bitop3_b32 v156, v3, v4, v2 bitop3:0x36
	v_lshlrev_b32_e32 v2, 10, v19
	v_and_or_b32 v2, v2, s45, v15
	v_lshlrev_b32_e32 v4, 10, v18
	v_or3_b32 v130, v2, v8, v14
	v_and_or_b32 v4, v4, s45, v15
	v_lshlrev_b32_e32 v6, 10, v17
	v_lshlrev_b64 v[2:3], 1, v[130:131]
	v_or3_b32 v130, v4, v8, v14
	v_and_or_b32 v6, v6, s45, v15
	v_lshlrev_b32_e32 v9, 10, v16
	v_lshlrev_b64 v[4:5], 1, v[130:131]
	v_or3_b32 v130, v6, v8, v14
	v_and_or_b32 v9, v9, s45, v15
	s_add_u32 s36, s53, 0xe00080
	v_lshlrev_b64 v[6:7], 1, v[130:131]
	v_or3_b32 v130, v9, v8, v14
	s_addc_u32 s37, s54, 0
	v_lshlrev_b64 v[8:9], 1, v[130:131]
	s_nop 0
	v_lshl_add_u64 v[134:135], s[36:37], 0, v[2:3]
	v_lshl_add_u64 v[136:137], s[36:37], 0, v[4:5]
	v_lshl_add_u64 v[138:139], s[36:37], 0, v[6:7]
	v_lshl_add_u64 v[140:141], s[36:37], 0, v[8:9]
	s_add_u32 s36, s42, 0x18800080
	s_addc_u32 s37, s43, 0
	v_or_b32_e32 v155, 0x800, v154
	v_or_b32_e32 v157, 0x1000, v154
	v_or_b32_e32 v158, 0x1800, v154
	v_or_b32_e32 v159, 0x2000, v154
	v_or_b32_e32 v160, 0x2800, v154
	v_or_b32_e32 v161, 0x3000, v154
	v_or_b32_e32 v162, 0x3800, v154
	v_lshl_add_u64 v[142:143], s[36:37], 0, v[2:3]
	v_lshl_add_u64 v[144:145], s[36:37], 0, v[4:5]
	v_lshl_add_u64 v[146:147], s[36:37], 0, v[6:7]
	v_lshl_add_u64 v[148:149], s[36:37], 0, v[8:9]
	s_mov_b32 s38, 0
	s_mov_b64 s[36:37], 0
	s_waitcnt vmcnt(0) lgkmcnt(0)
	s_barrier
	v_readfirstlane_b32 s100, v151
	s_and_b32 s39, s38, 0x10000
	s_xor_b32 s42, s39, 0x10000
	s_add_i32 s39, s39, 0
	v_add3_u32 v130, s39, v152, v153
	v_add3_u32 v163, s39, v152, v154
	v_add3_u32 v196, s39, v156, v155
	v_add3_u32 v197, s39, v156, v157
	v_add3_u32 v198, s39, v156, v158
	v_add3_u32 v199, s39, v156, v159
	v_add3_u32 v200, s39, v156, v160
	v_add3_u32 v201, s39, v156, v161
	v_add3_u32 v202, s39, v156, v162
	ds_read_b128 v[180:183], v130 offset:32768
	ds_read_b128 v[164:167], v163
	ds_read_b128 v[168:171], v196
	ds_read_b128 v[172:175], v197
	ds_read_b128 v[176:179], v198
	ds_read_b128 v[184:187], v130 offset:34816
	ds_read_b128 v[188:191], v130 offset:36864
	ds_read_b128 v[192:195], v130 offset:38912
	s_add_i32 s101, s100, s42
	v_readfirstlane_b32 s98, v148
	v_readfirstlane_b32 s99, v149
	v_readfirstlane_b32 vcc_lo, v140
	v_readfirstlane_b32 vcc_hi, v141
	s_sub_u32 s98, s98, 0x1000000
	s_subb_u32 s99, s99, 0
	s_sub_u32 vcc_lo, vcc_lo, 0x1000000
	s_subb_u32 vcc_hi, vcc_hi, 0
	v_subrev_u32_e32 v148, s98, v148
	v_subrev_u32_e32 v140, vcc_lo, v140
	v_subrev_u32_e32 v146, s98, v146
	v_subrev_u32_e32 v138, vcc_lo, v138
	v_subrev_u32_e32 v144, s98, v144
	v_subrev_u32_e32 v136, vcc_lo, v136
	v_subrev_u32_e32 v142, s98, v142
	v_subrev_u32_e32 v134, vcc_lo, v134
	s_mov_b32 m0, s101
	s_nop 0
	global_load_lds_dwordx4 v148, s[98:99]
	s_add_i32 m0, s101, 0x8000
	s_nop 0
	global_load_lds_dwordx4 v140, vcc
	s_add_i32 m0, s101, 0x2000
	s_nop 0
	global_load_lds_dwordx4 v146, s[98:99]
	s_add_i32 m0, s101, 0xa000
	s_nop 0
	global_load_lds_dwordx4 v138, vcc
	s_add_i32 m0, s101, 0x4000
	s_nop 0
	global_load_lds_dwordx4 v144, s[98:99]
	s_add_i32 m0, s101, 0xc000
	s_nop 0
	global_load_lds_dwordx4 v136, vcc
	s_add_i32 m0, s101, 0x6000
	s_nop 0
	global_load_lds_dwordx4 v142, s[98:99]
	s_add_i32 m0, s101, 0xe000
	s_nop 0
	global_load_lds_dwordx4 v134, vcc

.LBB0_894:
	v_mov_b32_e32 v27, v132
	v_cmp_lt_i32_e32 vcc, v21, v20
	ds_read_b128 v[28:31], v3
	ds_read_b64 v[32:33], v18
	v_cndmask_b32_e32 v34, v19, v21, vcc
	v_cmp_lt_i32_e32 vcc, v22, v20
	v_ashrrev_i32_e32 v27, 5, v27
	v_and_b32_e32 v27, -2, v27
	v_cndmask_b32_e32 v35, v19, v22, vcc
	v_cmp_lt_i32_e32 vcc, v23, v20
	v_lshlrev_b32_e32 v133, 2, v34
	v_add_u32_e32 v34, s3, v27
	v_cndmask_b32_e32 v36, v19, v23, vcc
	v_cmp_lt_i32_e32 vcc, v24, v20
	v_lshlrev_b32_e32 v150, 2, v35
	v_ashrrev_i32_e32 v35, 31, v34
	v_cndmask_b32_e32 v37, v19, v24, vcc
	v_cmp_lt_i32_e32 vcc, v25, v20
	v_lshlrev_b32_e32 v151, 2, v36
	v_lshlrev_b32_e32 v152, 2, v37
	v_ashrrev_i32_e32 v27, 12, v34
	v_lshlrev_b64 v[36:37], 12, v[34:35]
	v_cndmask_b32_e32 v38, v19, v25, vcc
	v_cmp_lt_i32_e32 vcc, v26, v20
	v_mul_i32_i24_e32 v48, 0x1800, v27
	s_waitcnt lgkmcnt(0)
	v_lshl_add_u64 v[28:29], v[28:29], 0, v[36:37]
	v_cndmask_b32_e32 v39, v19, v26, vcc
	v_lshlrev_b64 v[34:35], 11, v[34:35]
	v_add_co_u32_e32 v50, vcc, v32, v0
	v_addc_co_u32_e32 v51, vcc, v33, v1, vcc
	v_ashrrev_i32_e32 v49, 31, v48
	v_add_co_u32_e32 v62, vcc, v28, v0
	v_addc_co_u32_e32 v63, vcc, v29, v1, vcc
	v_lshlrev_b32_e32 v153, 2, v38
	v_lshlrev_b32_e32 v154, 2, v39
	v_add_co_u32_e32 v52, vcc, v30, v34
	v_addc_co_u32_e32 v53, vcc, v31, v35, vcc
	flat_load_dwordx4 v[32:35], v[50:51]
	flat_load_dwordx4 v[36:39], v[50:51] offset:1024
	flat_load_dwordx4 v[40:43], v[50:51] offset:2048
	flat_load_dwordx4 v[44:47], v[50:51] offset:3072
	v_lshl_add_u64 v[54:55], v[48:49], 2, v[30:31]
	flat_load_dwordx4 v[28:31], v[62:63] nt
	flat_load_dwordx4 v[48:51], v[62:63] offset:1024 nt
	v_add_co_u32_e32 v80, vcc, s14, v62
	v_lshl_add_u64 v[60:61], v[52:53], 0, s[10:11]
	v_lshl_add_u64 v[76:77], v[54:55], 0, s[6:7]
	v_lshl_add_u64 v[78:79], v[54:55], 0, s[8:9]
	flat_load_dwordx4 v[52:55], v[62:63] offset:2048 nt
	flat_load_dwordx4 v[56:59], v[62:63] offset:3072 nt
	v_addc_co_u32_e32 v81, vcc, 0, v63, vcc
	v_add_co_u32_e32 v108, vcc, v60, v4
	v_addc_co_u32_e32 v109, vcc, v61, v5, vcc
	v_add_co_u32_e32 v110, vcc, v60, v8
	v_addc_co_u32_e32 v111, vcc, v61, v9, vcc
	v_add_co_u32_e32 v112, vcc, v60, v12
	v_addc_co_u32_e32 v113, vcc, v61, v13, vcc
	v_add_co_u32_e32 v114, vcc, v60, v16
	v_addc_co_u32_e32 v115, vcc, v61, v17, vcc
	flat_load_dwordx4 v[60:63], v[80:81] nt
	flat_load_dwordx4 v[64:67], v[80:81] offset:1024 nt
	flat_load_dwordx4 v[68:71], v[80:81] offset:2048 nt
	flat_load_dwordx4 v[72:75], v[80:81] offset:3072 nt
	v_add_co_u32_e32 v96, vcc, v76, v0
	v_addc_co_u32_e32 v97, vcc, v77, v1, vcc
	v_add_co_u32_e32 v98, vcc, v78, v0
	v_addc_co_u32_e32 v99, vcc, v79, v1, vcc
	v_add_co_u32_e32 v100, vcc, v78, v6
	v_addc_co_u32_e32 v101, vcc, v79, v7, vcc
	v_add_co_u32_e32 v102, vcc, v78, v10
	v_addc_co_u32_e32 v103, vcc, v79, v11, vcc
	v_add_co_u32_e32 v104, vcc, v78, v14
	v_addc_co_u32_e32 v105, vcc, v79, v15, vcc
	v_add_co_u32_e32 v116, vcc, v76, v6
	v_addc_co_u32_e32 v117, vcc, v77, v7, vcc
	v_add_co_u32_e32 v118, vcc, v76, v10
	v_addc_co_u32_e32 v119, vcc, v77, v11, vcc
	v_add_co_u32_e32 v120, vcc, v76, v14
	v_addc_co_u32_e32 v121, vcc, v77, v15, vcc
	flat_load_dwordx4 v[76:79], v[98:99]
	flat_load_dwordx4 v[80:83], v[100:101]
	flat_load_dwordx4 v[84:87], v[102:103]
	flat_load_dwordx4 v[88:91], v[104:105]
	flat_load_dwordx4 v[92:95], v[96:97]
	s_nop 0
	flat_load_dwordx4 v[96:99], v[116:117]
	flat_load_dwordx4 v[100:103], v[118:119]
	flat_load_dwordx4 v[104:107], v[120:121]
	s_add_i32 s16, s16, s40
	s_add_i32 s3, s3, s13
	s_cmpk_gt_i32 s16, 0x7ff
	s_waitcnt vmcnt(0) lgkmcnt(0)
	v_mov_b32_e32 v118, v29
	v_mov_b32_e32 v119, v49
	v_mov_b32_e32 v116, v28
	v_mov_b32_e32 v117, v48
	v_pk_mul_f32 v[118:119], v[118:119], v[118:119]
	v_mov_b32_e32 v120, v30
	v_mov_b32_e32 v126, v53
	v_mov_b32_e32 v127, v57
	v_mov_b32_e32 v124, v52
	v_mov_b32_e32 v125, v56
	v_pk_mul_f32 v[126:127], v[126:127], v[126:127]
	v_mov_b32_e32 v136, v61
	v_mov_b32_e32 v137, v65
	v_mov_b32_e32 v134, v60
	v_mov_b32_e32 v135, v64
	v_mov_b32_e32 v144, v69
	v_mov_b32_e32 v145, v73
	v_pk_fma_f32 v[116:117], v[116:117], v[116:117], v[118:119]
	v_pk_mul_f32 v[118:119], v[136:137], v[136:137]
	v_mov_b32_e32 v121, v50
	v_mov_b32_e32 v128, v54
	v_mov_b32_e32 v129, v58
	v_mov_b32_e32 v138, v62
	v_mov_b32_e32 v139, v66
	v_mov_b32_e32 v142, v68
	v_mov_b32_e32 v143, v72
	v_pk_fma_f32 v[124:125], v[124:125], v[124:125], v[126:127]
	v_pk_mul_f32 v[126:127], v[144:145], v[144:145]
	v_pk_fma_f32 v[118:119], v[134:135], v[134:135], v[118:119]
	v_mov_b32_e32 v122, v31
	v_mov_b32_e32 v123, v51
	v_mov_b32_e32 v140, v63
	v_mov_b32_e32 v141, v67
	v_mov_b32_e32 v146, v70
	v_mov_b32_e32 v147, v74
	v_pk_fma_f32 v[116:117], v[120:121], v[120:121], v[116:117]
	v_pk_fma_f32 v[120:121], v[128:129], v[128:129], v[124:125]
	v_pk_fma_f32 v[124:125], v[142:143], v[142:143], v[126:127]
	v_pk_fma_f32 v[118:119], v[138:139], v[138:139], v[118:119]
	v_mov_b32_e32 v130, v55
	v_mov_b32_e32 v131, v59
	v_mov_b32_e32 v148, v71
	v_mov_b32_e32 v149, v75
	v_pk_fma_f32 v[116:117], v[122:123], v[122:123], v[116:117]
	v_pk_fma_f32 v[122:123], v[146:147], v[146:147], v[124:125]
	v_pk_fma_f32 v[118:119], v[140:141], v[140:141], v[118:119]
	v_pk_fma_f32 v[120:121], v[130:131], v[130:131], v[120:121]
	v_pk_fma_f32 v[122:123], v[148:149], v[148:149], v[122:123]
	v_mov_b32_e32 v125, v116
	v_mov_b32_e32 v124, v118
	v_mov_b32_e32 v116, v119
	v_mov_b32_e32 v127, v120
	v_mov_b32_e32 v126, v122
	v_pk_add_f32 v[116:117], v[124:125], v[116:117]
	v_mov_b32_e32 v120, v123
	v_pk_add_f32 v[116:117], v[116:117], v[126:127]
	v_pk_add_f32 v[76:77], v[76:77], 1.0 op_sel_hi:[1,0]
	v_pk_add_f32 v[116:117], v[116:117], v[120:121]
	ds_bpermute_b32 v119, v133, v117
	ds_bpermute_b32 v118, v133, v116
	v_pk_add_f32 v[78:79], v[78:79], 1.0 op_sel_hi:[1,0]
	v_pk_add_f32 v[80:81], v[80:81], 1.0 op_sel_hi:[1,0]
	v_pk_add_f32 v[82:83], v[82:83], 1.0 op_sel_hi:[1,0]
	v_pk_add_f32 v[84:85], v[84:85], 1.0 op_sel_hi:[1,0]
	s_waitcnt lgkmcnt(0)
	v_pk_add_f32 v[116:117], v[116:117], v[118:119]
	ds_bpermute_b32 v119, v150, v117
	ds_bpermute_b32 v118, v150, v116
	v_pk_add_f32 v[86:87], v[86:87], 1.0 op_sel_hi:[1,0]
	v_pk_add_f32 v[88:89], v[88:89], 1.0 op_sel_hi:[1,0]
	v_pk_add_f32 v[90:91], v[90:91], 1.0 op_sel_hi:[1,0]
	s_waitcnt lgkmcnt(0)
	v_pk_add_f32 v[116:117], v[116:117], v[118:119]
	ds_bpermute_b32 v119, v151, v117
	ds_bpermute_b32 v118, v151, v116
	s_waitcnt lgkmcnt(0)
	v_pk_add_f32 v[116:117], v[116:117], v[118:119]
	ds_bpermute_b32 v119, v152, v117
	ds_bpermute_b32 v118, v152, v116
	s_waitcnt lgkmcnt(0)
	v_pk_add_f32 v[116:117], v[116:117], v[118:119]
	ds_bpermute_b32 v119, v153, v117
	ds_bpermute_b32 v118, v153, v116
	s_waitcnt lgkmcnt(0)
	v_pk_add_f32 v[116:117], v[116:117], v[118:119]
	ds_bpermute_b32 v119, v154, v117
	ds_bpermute_b32 v118, v154, v116
	s_waitcnt lgkmcnt(0)
	v_pk_add_f32 v[116:117], v[116:117], v[118:119]
	s_nop 0
	v_pk_fma_f32 v[116:117], v[116:117], s[12:13], v[2:3] op_sel_hi:[1,0,0]
	s_nop 0
	v_mul_f32_e32 v27, 0x4b800000, v117
	v_cmp_gt_f32_e64 s[4:5], s15, v117
	v_mul_f32_e32 v118, 0x4b800000, v116
	v_cmp_gt_f32_e32 vcc, s15, v116
	v_cndmask_b32_e64 v27, v117, v27, s[4:5]
	v_rsq_f32_e32 v27, v27
	v_cndmask_b32_e32 v116, v116, v118, vcc
	v_rsq_f32_e32 v117, v116
	v_mul_f32_e32 v116, 0x45800000, v27
	v_cndmask_b32_e64 v116, v27, v116, s[4:5]
	v_mul_f32_e32 v118, 0x45800000, v117
	v_cndmask_b32_e32 v118, v117, v118, vcc
	v_pk_mul_f32 v[28:29], v[28:29], v[116:117] op_sel_hi:[1,0]
	v_pk_mul_f32 v[30:31], v[30:31], v[116:117] op_sel_hi:[1,0]
	v_pk_mul_f32 v[60:61], v[60:61], v[118:119] op_sel_hi:[1,0]
	v_pk_mul_f32 v[62:63], v[62:63], v[118:119] op_sel_hi:[1,0]
	v_pk_mul_f32 v[48:49], v[48:49], v[116:117] op_sel_hi:[1,0]
	v_pk_mul_f32 v[50:51], v[50:51], v[116:117] op_sel_hi:[1,0]
	v_pk_mul_f32 v[64:65], v[64:65], v[118:119] op_sel_hi:[1,0]
	v_pk_mul_f32 v[66:67], v[66:67], v[118:119] op_sel_hi:[1,0]
	v_pk_mul_f32 v[52:53], v[52:53], v[116:117] op_sel_hi:[1,0]
	v_pk_mul_f32 v[54:55], v[54:55], v[116:117] op_sel_hi:[1,0]
	v_pk_mul_f32 v[68:69], v[68:69], v[118:119] op_sel_hi:[1,0]
	v_pk_mul_f32 v[70:71], v[70:71], v[118:119] op_sel_hi:[1,0]
	v_pk_mul_f32 v[56:57], v[56:57], v[116:117] op_sel_hi:[1,0]
	v_pk_mul_f32 v[58:59], v[58:59], v[116:117] op_sel_hi:[1,0]
	v_pk_mul_f32 v[72:73], v[72:73], v[118:119] op_sel_hi:[1,0]
	v_pk_mul_f32 v[74:75], v[74:75], v[118:119] op_sel_hi:[1,0]
	v_pk_mul_f32 v[28:29], v[32:33], v[28:29]
	v_pk_mul_f32 v[30:31], v[34:35], v[30:31]
	v_pk_mul_f32 v[32:33], v[32:33], v[60:61]
	v_pk_mul_f32 v[34:35], v[34:35], v[62:63]
	v_pk_mul_f32 v[48:49], v[48:49], v[36:37]
	v_pk_mul_f32 v[50:51], v[50:51], v[38:39]
	v_pk_mul_f32 v[36:37], v[64:65], v[36:37]
	v_pk_mul_f32 v[38:39], v[66:67], v[38:39]
	v_pk_mul_f32 v[52:53], v[52:53], v[40:41]
	v_pk_mul_f32 v[54:55], v[54:55], v[42:43]
	v_pk_mul_f32 v[40:41], v[68:69], v[40:41]
	v_pk_mul_f32 v[42:43], v[70:71], v[42:43]
	v_pk_mul_f32 v[56:57], v[56:57], v[44:45]
	v_pk_mul_f32 v[58:59], v[58:59], v[46:47]
	v_pk_mul_f32 v[44:45], v[72:73], v[44:45]
	v_pk_mul_f32 v[46:47], v[74:75], v[46:47]
	v_pk_fma_f32 v[28:29], v[28:29], v[76:77], v[92:93]
	v_pk_fma_f32 v[30:31], v[30:31], v[78:79], v[94:95]
	v_pk_fma_f32 v[32:33], v[76:77], v[32:33], v[92:93]
	v_pk_fma_f32 v[34:35], v[34:35], v[78:79], v[94:95]
	v_pk_fma_f32 v[48:49], v[48:49], v[80:81], v[96:97]
	v_pk_fma_f32 v[50:51], v[50:51], v[82:83], v[98:99]
	v_pk_fma_f32 v[36:37], v[36:37], v[80:81], v[96:97]
	v_pk_fma_f32 v[38:39], v[38:39], v[82:83], v[98:99]
	v_pk_fma_f32 v[52:53], v[52:53], v[84:85], v[100:101]
	v_pk_fma_f32 v[54:55], v[54:55], v[86:87], v[102:103]
	v_pk_fma_f32 v[40:41], v[40:41], v[84:85], v[100:101]
	v_pk_fma_f32 v[42:43], v[42:43], v[86:87], v[102:103]
	v_pk_fma_f32 v[56:57], v[56:57], v[88:89], v[104:105]
	v_pk_fma_f32 v[58:59], v[58:59], v[90:91], v[106:107]
	v_pk_fma_f32 v[44:45], v[44:45], v[88:89], v[104:105]
	v_pk_fma_f32 v[46:47], v[46:47], v[90:91], v[106:107]
	v_cvt_pk_bf16_f32 v28, v28, v29
	v_cvt_pk_bf16_f32 v29, v30, v31
	v_cvt_pk_bf16_f32 v30, v32, v33
	v_cvt_pk_bf16_f32 v31, v34, v35
	v_cvt_pk_bf16_f32 v32, v48, v49
	v_cvt_pk_bf16_f32 v33, v50, v51
	v_cvt_pk_bf16_f32 v34, v36, v37
	v_cvt_pk_bf16_f32 v35, v38, v39
	v_cvt_pk_bf16_f32 v36, v52, v53
	v_cvt_pk_bf16_f32 v37, v54, v55
	v_cvt_pk_bf16_f32 v38, v40, v41
	v_cvt_pk_bf16_f32 v39, v42, v43
	v_cvt_pk_bf16_f32 v40, v56, v57
	v_cvt_pk_bf16_f32 v41, v58, v59
	v_cvt_pk_bf16_f32 v42, v44, v45
	v_cvt_pk_bf16_f32 v43, v46, v47
	flat_store_dwordx2 v[108:109], v[28:29]
	flat_store_dwordx2 v[108:109], v[30:31] offset:2048
	flat_store_dwordx2 v[110:111], v[32:33]
	flat_store_dwordx2 v[110:111], v[34:35] offset:2048
	flat_store_dwordx2 v[112:113], v[36:37]
	flat_store_dwordx2 v[112:113], v[38:39] offset:2048
	flat_store_dwordx2 v[114:115], v[40:41]
	flat_store_dwordx2 v[114:115], v[42:43] offset:2048
	s_cbranch_scc0 .LBB0_894

.Lnxn_942:
	s_waitcnt lgkmcnt(0)
	s_waitcnt lgkmcnt(3)
	v_mfma_f32_16x16x32_bf16 v[108:111], v[178:181], v[162:165], v[108:111]
	v_mfma_f32_16x16x32_bf16 v[92:95], v[178:181], v[166:169], v[92:95]
	v_mfma_f32_16x16x32_bf16 v[76:79], v[178:181], v[170:173], v[76:79]
	v_mfma_f32_16x16x32_bf16 v[60:63], v[178:181], v[174:177], v[60:63]
	ds_read_b128 v[240:243], v197
	ds_read_b128 v[244:247], v198
	s_waitcnt lgkmcnt(4)
	v_mfma_f32_16x16x32_bf16 v[104:107], v[182:185], v[162:165], v[104:107]
	v_mfma_f32_16x16x32_bf16 v[88:91], v[182:185], v[166:169], v[88:91]
	v_mfma_f32_16x16x32_bf16 v[72:75], v[182:185], v[170:173], v[72:75]
	v_mfma_f32_16x16x32_bf16 v[56:59], v[182:185], v[174:177], v[56:59]
	ds_read_b128 v[248:251], v199
	ds_read_b128 v[252:255], v200
	s_waitcnt lgkmcnt(5)
	v_mfma_f32_16x16x32_bf16 v[100:103], v[186:189], v[162:165], v[100:103]
	v_mfma_f32_16x16x32_bf16 v[84:87], v[186:189], v[166:169], v[84:87]
	v_mfma_f32_16x16x32_bf16 v[68:71], v[186:189], v[170:173], v[68:71]
	v_mfma_f32_16x16x32_bf16 v[52:55], v[186:189], v[174:177], v[52:55]
	s_waitcnt lgkmcnt(4)
	v_mfma_f32_16x16x32_bf16 v[96:99], v[190:193], v[162:165], v[96:99]
	v_mfma_f32_16x16x32_bf16 v[80:83], v[190:193], v[166:169], v[80:83]
	v_mfma_f32_16x16x32_bf16 v[64:67], v[190:193], v[170:173], v[64:67]
	v_mfma_f32_16x16x32_bf16 v[48:51], v[190:193], v[174:177], v[48:51]
	ds_read_b128 v[162:165], v161 offset:1024
	ds_read_b128 v[166:169], v194 offset:1024
	ds_read_b128 v[170:173], v195 offset:1024
	ds_read_b128 v[174:177], v196 offset:1024
	s_waitcnt lgkmcnt(4)
	v_mfma_f32_16x16x32_bf16 v[44:47], v[178:181], v[240:243], v[44:47]
	v_mfma_f32_16x16x32_bf16 v[28:31], v[178:181], v[244:247], v[28:31]
	v_mfma_f32_16x16x32_bf16 v[12:15], v[178:181], v[248:251], v[12:15]
	v_mfma_f32_16x16x32_bf16 v[112:115], v[178:181], v[252:255], v[112:115]
	ds_read_b128 v[178:181], v128 offset:33792
	v_mfma_f32_16x16x32_bf16 v[40:43], v[182:185], v[240:243], v[40:43]
	v_mfma_f32_16x16x32_bf16 v[24:27], v[182:185], v[244:247], v[24:27]
	v_mfma_f32_16x16x32_bf16 v[8:11], v[182:185], v[248:251], v[8:11]
	v_mfma_f32_16x16x32_bf16 v[116:119], v[182:185], v[252:255], v[116:119]
	ds_read_b128 v[182:185], v128 offset:35840
	v_mfma_f32_16x16x32_bf16 v[36:39], v[186:189], v[240:243], v[36:39]
	v_mfma_f32_16x16x32_bf16 v[20:23], v[186:189], v[244:247], v[20:23]
	v_mfma_f32_16x16x32_bf16 v[4:7], v[186:189], v[248:251], v[4:7]
	v_mfma_f32_16x16x32_bf16 v[120:123], v[186:189], v[252:255], v[120:123]
	ds_read_b128 v[186:189], v128 offset:37888
	v_mfma_f32_16x16x32_bf16 v[32:35], v[190:193], v[240:243], v[32:35]
	v_mfma_f32_16x16x32_bf16 v[16:19], v[190:193], v[244:247], v[16:19]
	v_mfma_f32_16x16x32_bf16 v[0:3], v[190:193], v[248:251], v[0:3]
	v_mfma_f32_16x16x32_bf16 v[124:127], v[190:193], v[252:255], v[124:127]
	ds_read_b128 v[190:193], v128 offset:39936
	s_waitcnt lgkmcnt(3)
	v_mfma_f32_16x16x32_bf16 v[108:111], v[178:181], v[162:165], v[108:111]
	v_mfma_f32_16x16x32_bf16 v[92:95], v[178:181], v[166:169], v[92:95]
	v_mfma_f32_16x16x32_bf16 v[76:79], v[178:181], v[170:173], v[76:79]
	v_mfma_f32_16x16x32_bf16 v[60:63], v[178:181], v[174:177], v[60:63]
	ds_read_b128 v[240:243], v197 offset:1024
	ds_read_b128 v[244:247], v198 offset:1024
	s_waitcnt lgkmcnt(4)
	v_mfma_f32_16x16x32_bf16 v[104:107], v[182:185], v[162:165], v[104:107]
	v_mfma_f32_16x16x32_bf16 v[88:91], v[182:185], v[166:169], v[88:91]
	v_mfma_f32_16x16x32_bf16 v[72:75], v[182:185], v[170:173], v[72:75]
	v_mfma_f32_16x16x32_bf16 v[56:59], v[182:185], v[174:177], v[56:59]
	ds_read_b128 v[248:251], v199 offset:1024
	ds_read_b128 v[252:255], v200 offset:1024
	s_waitcnt lgkmcnt(5)
	v_mfma_f32_16x16x32_bf16 v[100:103], v[186:189], v[162:165], v[100:103]
	v_mfma_f32_16x16x32_bf16 v[84:87], v[186:189], v[166:169], v[84:87]
	v_mfma_f32_16x16x32_bf16 v[68:71], v[186:189], v[170:173], v[68:71]
	v_mfma_f32_16x16x32_bf16 v[52:55], v[186:189], v[174:177], v[52:55]
	s_waitcnt lgkmcnt(4)
	v_mfma_f32_16x16x32_bf16 v[96:99], v[190:193], v[162:165], v[96:99]
	v_mfma_f32_16x16x32_bf16 v[80:83], v[190:193], v[166:169], v[80:83]
	v_mfma_f32_16x16x32_bf16 v[64:67], v[190:193], v[170:173], v[64:67]
	v_mfma_f32_16x16x32_bf16 v[48:51], v[190:193], v[174:177], v[48:51]
	s_waitcnt lgkmcnt(0)
	v_mfma_f32_16x16x32_bf16 v[44:47], v[178:181], v[240:243], v[44:47]
	v_mfma_f32_16x16x32_bf16 v[28:31], v[178:181], v[244:247], v[28:31]
	v_mfma_f32_16x16x32_bf16 v[12:15], v[178:181], v[248:251], v[12:15]
	v_mfma_f32_16x16x32_bf16 v[112:115], v[178:181], v[252:255], v[112:115]
	v_mfma_f32_16x16x32_bf16 v[40:43], v[182:185], v[240:243], v[40:43]
	v_mfma_f32_16x16x32_bf16 v[24:27], v[182:185], v[244:247], v[24:27]
	v_mfma_f32_16x16x32_bf16 v[8:11], v[182:185], v[248:251], v[8:11]
	v_mfma_f32_16x16x32_bf16 v[116:119], v[182:185], v[252:255], v[116:119]
	v_mfma_f32_16x16x32_bf16 v[36:39], v[186:189], v[240:243], v[36:39]
	v_mfma_f32_16x16x32_bf16 v[20:23], v[186:189], v[244:247], v[20:23]
	v_mfma_f32_16x16x32_bf16 v[4:7], v[186:189], v[248:251], v[4:7]
	v_mfma_f32_16x16x32_bf16 v[120:123], v[186:189], v[252:255], v[120:123]
	v_mfma_f32_16x16x32_bf16 v[32:35], v[190:193], v[240:243], v[32:35]
	v_mfma_f32_16x16x32_bf16 v[16:19], v[190:193], v[244:247], v[16:19]
	v_mfma_f32_16x16x32_bf16 v[0:3], v[190:193], v[248:251], v[0:3]
	v_mfma_f32_16x16x32_bf16 v[124:127], v[190:193], v[252:255], v[124:127]
	v_mov_b32_e32 v128, s3
	s_waitcnt vmcnt(8)
	s_barrier
	ds_read_b64 v[130:131], v128
	v_ashrrev_i32_e32 v128, 1, v148
	v_and_b32_e32 v128, 0xffffff80, v128
	v_add_u32_e32 v128, s16, v128
	s_ashr_i32 s15, s14, 31
	s_waitcnt lgkmcnt(0)
	v_mad_i64_i32 v[130:131], s[16:17], v128, s23, v[130:131]
	v_and_b32_e32 v128, 0xc0, v148
	v_lshrrev_b32_e32 v135, 6, v148
	v_lshl_add_u64 v[130:131], s[14:15], 1, v[130:131]
	v_lshlrev_b32_e32 v128, 1, v128
	v_add_co_u32_e32 v130, vcc, v130, v128
	v_addc_co_u32_e32 v131, vcc, v131, v129, vcc
	v_mul_lo_u32 v128, v135, s27
	v_add_u32_e32 v135, s24, v128
	v_lshrrev_b32_e32 v128, 1, v148
	v_and_b32_e32 v136, 24, v128
	v_lshlrev_b32_e32 v128, 4, v148
	v_bfe_u32 v137, v148, 3, 3
	v_and_b32_e32 v134, 15, v148
	v_and_b32_e32 v128, 0x70, v128
	v_mul_u32_u24_e32 v138, 0x90, v137
	v_add_co_u32_e32 v130, vcc, v130, v128
	v_addc_co_u32_e32 v131, vcc, v131, v129, vcc
	v_add3_u32 v138, v135, v128, v138
	v_mul_u32_u24_e32 v128, 0x90, v134
	v_add3_u32 v134, v135, v136, v128
	v_cvt_pk_bf16_f32 v108, v108, v109
	v_cvt_pk_bf16_f32 v109, v110, v111
	v_cvt_pk_bf16_f32 v104, v104, v105
	v_cvt_pk_bf16_f32 v105, v106, v107
	v_cvt_pk_bf16_f32 v100, v100, v101
	v_cvt_pk_bf16_f32 v101, v102, v103
	v_cvt_pk_bf16_f32 v96, v96, v97
	v_cvt_pk_bf16_f32 v97, v98, v99
	v_cvt_pk_bf16_f32 v92, v92, v93
	v_cvt_pk_bf16_f32 v93, v94, v95
	v_cvt_pk_bf16_f32 v88, v88, v89
	v_cvt_pk_bf16_f32 v89, v90, v91
	v_cvt_pk_bf16_f32 v84, v84, v85
	v_cvt_pk_bf16_f32 v85, v86, v87
	v_cvt_pk_bf16_f32 v80, v80, v81
	v_cvt_pk_bf16_f32 v81, v82, v83
	v_cvt_pk_bf16_f32 v76, v76, v77
	v_cvt_pk_bf16_f32 v77, v78, v79
	v_cvt_pk_bf16_f32 v72, v72, v73
	v_cvt_pk_bf16_f32 v73, v74, v75
	v_cvt_pk_bf16_f32 v68, v68, v69
	v_cvt_pk_bf16_f32 v69, v70, v71
	v_cvt_pk_bf16_f32 v64, v64, v65
	v_cvt_pk_bf16_f32 v65, v66, v67
	v_cvt_pk_bf16_f32 v60, v60, v61
	v_cvt_pk_bf16_f32 v61, v62, v63
	v_cvt_pk_bf16_f32 v56, v56, v57
	v_cvt_pk_bf16_f32 v57, v58, v59
	v_cvt_pk_bf16_f32 v52, v52, v53
	v_cvt_pk_bf16_f32 v53, v54, v55
	v_cvt_pk_bf16_f32 v48, v48, v49
	v_cvt_pk_bf16_f32 v49, v50, v51
	ds_write_b64 v134, v[108:109]
	ds_write_b64 v134, v[104:105] offset:32
	ds_write_b64 v134, v[100:101] offset:64
	ds_write_b64 v134, v[96:97] offset:96
	ds_write_b64 v134, v[92:93] offset:2304
	ds_write_b64 v134, v[88:89] offset:2336
	ds_write_b64 v134, v[84:85] offset:2368
	ds_write_b64 v134, v[80:81] offset:2400
	ds_write_b64 v134, v[76:77] offset:4608
	ds_write_b64 v134, v[72:73] offset:4640
	ds_write_b64 v134, v[68:69] offset:4672
	ds_write_b64 v134, v[64:65] offset:4704
	ds_write_b64 v134, v[60:61] offset:6912
	ds_write_b64 v134, v[56:57] offset:6944
	ds_write_b64 v134, v[52:53] offset:6976
	ds_write_b64 v134, v[48:49] offset:7008
	ds_read_b128 v[48:51], v138
	v_mul_u32_u24_e32 v54, 0xc00, v137
	v_lshl_add_u64 v[52:53], v[130:131], 0, s[12:13]
	v_lshlrev_b32_e32 v128, 1, v54
	v_add_co_u32_e32 v54, vcc, v52, v128
	v_addc_co_u32_e32 v55, vcc, v53, v129, vcc
	s_waitcnt lgkmcnt(0)
	global_store_dwordx4 v[54:55], v[48:51], off nt
	ds_read_b128 v[48:51], v138 offset:1152
	v_add_co_u32_e32 v56, vcc, s21, v54
	v_cvt_pk_bf16_f32 v0, v0, v1
	s_nop 0
	v_addc_co_u32_e32 v57, vcc, 0, v55, vcc
	s_waitcnt lgkmcnt(0)
	global_store_dwordx4 v[56:57], v[48:51], off nt
	ds_read_b128 v[48:51], v138 offset:2304
	v_add_co_u32_e32 v56, vcc, s25, v54
	v_cvt_pk_bf16_f32 v1, v2, v3
	s_nop 0
	v_addc_co_u32_e32 v57, vcc, 0, v55, vcc
	s_waitcnt lgkmcnt(0)
	global_store_dwordx4 v[56:57], v[48:51], off nt
	ds_read_b128 v[48:51], v138 offset:3456
	v_add_co_u32_e32 v56, vcc, s28, v54
	v_cvt_pk_bf16_f32 v44, v44, v45
	s_nop 0
	v_addc_co_u32_e32 v57, vcc, 0, v55, vcc
	s_waitcnt lgkmcnt(0)
	global_store_dwordx4 v[56:57], v[48:51], off nt
	ds_read_b128 v[48:51], v138 offset:4608
	v_or_b32_e32 v56, 0x30000, v128
	v_mov_b32_e32 v57, v129
	v_add_co_u32_e32 v56, vcc, v52, v56
	v_addc_co_u32_e32 v57, vcc, v53, v57, vcc
	v_cvt_pk_bf16_f32 v45, v46, v47
	s_waitcnt lgkmcnt(0)
	global_store_dwordx4 v[56:57], v[48:51], off nt
	ds_read_b128 v[48:51], v138 offset:5760
	v_add_u32_e32 v56, 0x3c000, v128
	v_mov_b32_e32 v57, v129
	v_add_co_u32_e32 v56, vcc, v52, v56
	v_addc_co_u32_e32 v57, vcc, v53, v57, vcc
	v_cvt_pk_bf16_f32 v40, v40, v41
	s_waitcnt lgkmcnt(0)
	global_store_dwordx4 v[56:57], v[48:51], off nt
	ds_read_b128 v[48:51], v138 offset:6912
	v_add_u32_e32 v56, 0x48000, v128
	v_mov_b32_e32 v57, v129
	v_add_co_u32_e32 v56, vcc, v52, v56
	v_addc_co_u32_e32 v57, vcc, v53, v57, vcc
	v_add_u32_e32 v128, 0x54000, v128
	s_waitcnt lgkmcnt(0)
	global_store_dwordx4 v[56:57], v[48:51], off nt
	ds_read_b128 v[48:51], v138 offset:8064
	v_add_co_u32_e32 v52, vcc, v52, v128
	v_addc_co_u32_e32 v53, vcc, v53, v129, vcc
	v_cvt_pk_bf16_f32 v41, v42, v43
	v_cvt_pk_bf16_f32 v36, v36, v37
	v_cvt_pk_bf16_f32 v37, v38, v39
	s_waitcnt lgkmcnt(0)
	global_store_dwordx4 v[52:53], v[48:51], off nt
	ds_write_b64 v134, v[0:1] offset:4704
	v_cvt_pk_bf16_f32 v0, v112, v113
	v_cvt_pk_bf16_f32 v1, v114, v115
	ds_write_b64 v134, v[0:1] offset:6912
	v_cvt_pk_bf16_f32 v0, v116, v117
	v_cvt_pk_bf16_f32 v1, v118, v119
	ds_write_b64 v134, v[0:1] offset:6944
	v_cvt_pk_bf16_f32 v0, v120, v121
	v_cvt_pk_bf16_f32 v1, v122, v123
	v_cvt_pk_bf16_f32 v32, v32, v33
	v_cvt_pk_bf16_f32 v33, v34, v35
	v_cvt_pk_bf16_f32 v28, v28, v29
	v_cvt_pk_bf16_f32 v29, v30, v31
	v_cvt_pk_bf16_f32 v24, v24, v25
	v_cvt_pk_bf16_f32 v25, v26, v27
	v_cvt_pk_bf16_f32 v20, v20, v21
	v_cvt_pk_bf16_f32 v21, v22, v23
	v_cvt_pk_bf16_f32 v16, v16, v17
	v_cvt_pk_bf16_f32 v17, v18, v19
	v_cvt_pk_bf16_f32 v12, v12, v13
	v_cvt_pk_bf16_f32 v13, v14, v15
	v_cvt_pk_bf16_f32 v8, v8, v9
	v_cvt_pk_bf16_f32 v9, v10, v11
	v_cvt_pk_bf16_f32 v4, v4, v5
	v_cvt_pk_bf16_f32 v5, v6, v7
	ds_write_b64 v134, v[0:1] offset:6976
	v_cvt_pk_bf16_f32 v0, v124, v125
	v_cvt_pk_bf16_f32 v1, v126, v127
	ds_write_b64 v134, v[44:45]
	ds_write_b64 v134, v[40:41] offset:32
	ds_write_b64 v134, v[36:37] offset:64
	ds_write_b64 v134, v[32:33] offset:96
	ds_write_b64 v134, v[28:29] offset:2304
	ds_write_b64 v134, v[24:25] offset:2336
	ds_write_b64 v134, v[20:21] offset:2368
	ds_write_b64 v134, v[16:17] offset:2400
	ds_write_b64 v134, v[12:13] offset:4608
	ds_write_b64 v134, v[8:9] offset:4640
	ds_write_b64 v134, v[4:5] offset:4672
	ds_write_b64 v134, v[0:1] offset:7008
	ds_read_b128 v[0:3], v138
	v_add_co_u32_e32 v4, vcc, s29, v54
	s_add_i32 s39, s39, s40
	s_nop 0
	v_addc_co_u32_e32 v5, vcc, 0, v55, vcc
	s_waitcnt lgkmcnt(0)
	global_store_dwordx4 v[4:5], v[0:3], off nt
	ds_read_b128 v[0:3], v138 offset:1152
	v_add_co_u32_e32 v4, vcc, s30, v54
	s_cmpk_gt_i32 s39, 0x5ff
	s_nop 0
	v_addc_co_u32_e32 v5, vcc, 0, v55, vcc
	s_waitcnt lgkmcnt(0)
	global_store_dwordx4 v[4:5], v[0:3], off nt
	ds_read_b128 v[0:3], v138 offset:2304
	v_add_co_u32_e32 v4, vcc, s31, v54
	s_nop 1
	v_addc_co_u32_e32 v5, vcc, 0, v55, vcc
	s_waitcnt lgkmcnt(0)
	global_store_dwordx4 v[4:5], v[0:3], off nt
	ds_read_b128 v[0:3], v138 offset:3456
	v_add_co_u32_e32 v4, vcc, s34, v54
	s_nop 1
	v_addc_co_u32_e32 v5, vcc, 0, v55, vcc
	s_waitcnt lgkmcnt(0)
	global_store_dwordx4 v[4:5], v[0:3], off nt
	ds_read_b128 v[0:3], v138 offset:4608
	v_add_co_u32_e32 v4, vcc, s35, v54
	s_nop 1
	v_addc_co_u32_e32 v5, vcc, 0, v55, vcc
	s_waitcnt lgkmcnt(0)
	global_store_dwordx4 v[4:5], v[0:3], off nt
	ds_read_b128 v[0:3], v138 offset:5760
	v_add_co_u32_e32 v4, vcc, s38, v54
	s_nop 1
	v_addc_co_u32_e32 v5, vcc, 0, v55, vcc
	s_waitcnt lgkmcnt(0)
	global_store_dwordx4 v[4:5], v[0:3], off nt
	ds_read_b128 v[0:3], v138 offset:6912
	v_add_co_u32_e32 v4, vcc, 0xa8000, v54
	s_nop 1
	v_addc_co_u32_e32 v5, vcc, 0, v55, vcc
	s_waitcnt lgkmcnt(0)
	global_store_dwordx4 v[4:5], v[0:3], off nt
	ds_read_b128 v[0:3], v138 offset:8064
	v_add_co_u32_e32 v4, vcc, 0xb4000, v54
	s_nop 1
	v_addc_co_u32_e32 v5, vcc, 0, v55, vcc
	s_waitcnt lgkmcnt(0)
	global_store_dwordx4 v[4:5], v[0:3], off nt
	s_cbranch_scc0 .LBB0_941

.LBB0_991:
	v_cmp_gt_i32_e32 vcc, s18, v148
	s_and_saveexec_b64 s[16:17], vcc
	s_cbranch_execz .LBB0_990
	v_mul_hi_i32 v0, v148, s19
	v_mov_b32_e32 v2, s21
	v_lshrrev_b32_e32 v1, 31, v0
	v_ashrrev_i32_e32 v0, 5, v0
	ds_read_b64 v[44:45], v2
	v_add_u32_e32 v1, v0, v1
	v_mul_lo_u32 v0, v1, s20
	v_mov_b32_e32 v2, s23
	v_sub_u32_e32 v0, v148, v0
	ds_read_b128 v[10:13], v2
	v_and_b32_e32 v2, 0x1ff, v1
	v_lshlrev_b32_e32 v138, 3, v1
	v_lshlrev_b32_e32 v0, 3, v0
	v_cmp_ne_u32_e64 s[4:5], 0, v2
	s_waitcnt lgkmcnt(0)
	v_lshl_add_u64 v[50:51], v[44:45], 0, s[12:13]
	v_ashrrev_i32_e32 v1, 31, v0
	v_subbrev_co_u32_e64 v2, vcc, 0, v138, s[4:5]
	v_mad_i64_i32 v[2:3], s[6:7], v2, s22, v[50:51]
	v_lshlrev_b64 v[56:57], 1, v[0:1]
	v_add_co_u32_e32 v2, vcc, v2, v56
	v_addc_co_u32_e32 v3, vcc, v3, v57, vcc
	flat_load_dwordx4 v[32:35], v[2:3] offset:3072 nt
	flat_load_dwordx4 v[36:39], v[2:3] nt
	v_add_u32_e32 v2, 8, v138
	v_and_b32_e32 v3, 0xff8, v2
	v_cmp_eq_u32_e32 vcc, 0, v3
	v_or_b32_e32 v162, 1, v138
	v_or_b32_e32 v161, 2, v138
	v_cndmask_b32_e32 v4, v2, v138, vcc
	v_mad_i64_i32 v[4:5], s[6:7], v4, s22, v[50:51]
	v_lshl_add_u64 v[4:5], v[4:5], 0, v[56:57]
	flat_load_dwordx4 v[46:49], v[4:5] nt
	flat_load_dwordx4 v[40:43], v[4:5] offset:3072 nt
	v_add_u32_e32 v128, 0xb00, v0
	v_lshlrev_b64 v[0:1], 2, v[0:1]
	v_mad_i64_i32 v[2:3], s[6:7], v138, s22, v[50:51]
	v_mad_i64_i32 v[4:5], s[6:7], v162, s22, v[50:51]
	v_mad_i64_i32 v[6:7], s[6:7], v161, s22, v[50:51]
	v_lshl_add_u64 v[54:55], v[10:11], 0, v[0:1]
	v_add_co_u32_e64 v62, s[6:7], s24, v54
	v_lshl_add_u64 v[16:17], v[2:3], 0, v[56:57]
	s_nop 0
	v_addc_co_u32_e64 v63, s[6:7], 0, v55, s[6:7]
	v_lshl_add_u64 v[18:19], v[4:5], 0, v[56:57]
	v_lshl_add_u64 v[52:53], v[6:7], 0, v[56:57]
	v_lshl_add_u64 v[60:61], v[12:13], 0, v[0:1]
	flat_load_dwordx4 v[116:119], v[16:17] nt
	flat_load_dwordx4 v[112:115], v[18:19] nt
	flat_load_dwordx4 v[0:3], v[54:55]
	flat_load_dwordx4 v[4:7], v[62:63] offset:2048
	v_add_co_u32_e64 v130, s[6:7], s25, v54
	v_lshlrev_b64 v[14:15], 2, v[128:129]
	s_nop 0
	v_addc_co_u32_e64 v131, s[6:7], 0, v55, s[6:7]
	v_lshl_add_u64 v[58:59], v[10:11], 0, v[14:15]
	flat_load_dwordx4 v[8:11], v[130:131]
	flat_load_dwordx4 v[20:23], v[60:61]
	flat_load_dwordx4 v[124:127], v[16:17] offset:3072 nt
	v_add_co_u32_e64 v134, s[6:7], s24, v58
	v_lshl_add_u64 v[136:137], v[12:13], 0, v[14:15]
	s_nop 0
	v_addc_co_u32_e64 v135, s[6:7], 0, v59, s[6:7]
	v_add_co_u32_e64 v140, s[6:7], s25, v58
	flat_load_dwordx4 v[28:31], v[134:135] offset:2048
	flat_load_dwordx4 v[24:27], v[58:59]
	flat_load_dwordx4 v[120:123], v[18:19] offset:3072 nt
	flat_load_dwordx4 v[108:111], v[52:53] nt
	flat_load_dwordx4 v[104:107], v[52:53] offset:3072 nt
	v_addc_co_u32_e64 v141, s[6:7], 0, v59, s[6:7]
	flat_load_dwordx4 v[12:15], v[136:137]
	flat_load_dwordx4 v[16:19], v[140:141]
	v_or_b32_e32 v160, 3, v138
	v_or_b32_e32 v159, 4, v138
	v_or_b32_e32 v158, 5, v138
	v_or_b32_e32 v153, 6, v138
	v_or_b32_e32 v128, 7, v138
	v_lshl_add_u64 v[44:45], v[44:45], 0, v[56:57]
	s_waitcnt vmcnt(0) lgkmcnt(0)
	v_cndmask_b32_e64 v139, 0, v35, s[4:5]
	v_cndmask_b32_e64 v163, 0, v34, s[4:5]
	v_cndmask_b32_e64 v168, 0, v33, s[4:5]
	v_cndmask_b32_e64 v146, 0, v32, s[4:5]
	v_cndmask_b32_e64 v176, 0, v39, s[4:5]
	v_cndmask_b32_e64 v170, 0, v38, s[4:5]
	v_cndmask_b32_e64 v166, 0, v37, s[4:5]
	v_cndmask_b32_e64 v142, 0, v36, s[4:5]
	v_mad_i64_i32 v[32:33], s[4:5], v160, s22, v[50:51]
	v_lshl_add_u64 v[32:33], v[32:33], 0, v[56:57]
	flat_load_dwordx4 v[100:103], v[32:33] nt
	flat_load_dwordx4 v[96:99], v[32:33] offset:3072 nt
	v_mad_i64_i32 v[32:33], s[4:5], v159, s22, v[50:51]
	v_lshl_add_u64 v[32:33], v[32:33], 0, v[56:57]
	flat_load_dwordx4 v[92:95], v[32:33] nt
	flat_load_dwordx4 v[88:91], v[32:33] offset:3072 nt
	v_mad_i64_i32 v[32:33], s[4:5], v158, s22, v[50:51]
	v_lshl_add_u64 v[32:33], v[32:33], 0, v[56:57]
	flat_load_dwordx4 v[84:87], v[32:33] nt
	flat_load_dwordx4 v[80:83], v[32:33] offset:3072 nt
	v_mad_i64_i32 v[32:33], s[4:5], v153, s22, v[50:51]
	v_lshl_add_u64 v[32:33], v[32:33], 0, v[56:57]
	flat_load_dwordx4 v[76:79], v[32:33] nt
	flat_load_dwordx4 v[72:75], v[32:33] offset:3072 nt
	v_mad_i64_i32 v[32:33], s[4:5], v128, s22, v[50:51]
	v_lshl_add_u64 v[32:33], v[32:33], 0, v[56:57]
	flat_load_dwordx4 v[68:71], v[32:33] nt
	flat_load_dwordx4 v[64:67], v[32:33] offset:3072 nt
	flat_load_dwordx4 v[36:39], v[62:63] offset:2064
	s_nop 0
	flat_load_dwordx4 v[32:35], v[54:55] offset:16
	v_cndmask_b32_e64 v149, v43, 0, vcc
	v_cndmask_b32_e64 v150, v42, 0, vcc
	v_cndmask_b32_e64 v151, v41, 0, vcc
	v_cndmask_b32_e64 v152, v40, 0, vcc
	flat_load_dwordx4 v[40:43], v[130:131] offset:16
	flat_load_dwordx4 v[52:55], v[60:61] offset:16
	v_lshlrev_b32_e32 v144, 16, v116
	v_and_b32_e32 v145, 0xffff0000, v116
	v_cndmask_b32_e64 v156, v47, 0, vcc
	v_cndmask_b32_e64 v157, v46, 0, vcc
	v_lshl_add_u64 v[130:131], v[44:45], 0, s[14:15]
	v_lshlrev_b32_e32 v44, 16, v142
	v_and_b32_e32 v45, 0xffff0000, v142
	v_pk_mul_f32 v[46:47], v[4:5], v[144:145]
	flat_load_dwordx4 v[60:63], v[134:135] offset:2064
	s_nop 0
	flat_load_dwordx4 v[56:59], v[58:59] offset:16
	v_pk_fma_f32 v[44:45], v[0:1], v[44:45], v[46:47]
	v_lshlrev_b32_e32 v134, 16, v112
	v_and_b32_e32 v135, 0xffff0000, v112
	v_pk_fma_f32 v[44:45], v[8:9], v[134:135], v[44:45]
	v_cndmask_b32_e64 v154, v49, 0, vcc
	v_cndmask_b32_e64 v155, v48, 0, vcc
	v_pk_add_f32 v[142:143], v[44:45], v[20:21]
	flat_load_dwordx4 v[44:47], v[140:141] offset:16
	flat_load_dwordx4 v[48:51], v[136:137] offset:16
	v_mul_f32_e32 v112, 0xbfb8aa3b, v142
	v_exp_f32_e32 v112, v112
	v_mul_f32_e32 v116, 0xbfb8aa3b, v143
	v_exp_f32_e32 v116, v116
	v_lshlrev_b32_e32 v136, 16, v146
	v_add_f32_e32 v112, 1.0, v112
	v_and_b32_e32 v137, 0xffff0000, v146
	v_rcp_f32_e32 v146, v112
	v_add_f32_e32 v112, 1.0, v116
	v_lshlrev_b32_e32 v164, 16, v124
	v_and_b32_e32 v165, 0xffff0000, v124
	v_rcp_f32_e32 v147, v112
	v_pk_mul_f32 v[140:141], v[28:29], v[164:165]
	v_and_b32_e32 v167, 0xffff0000, v117
	v_pk_fma_f32 v[140:141], v[24:25], v[136:137], v[140:141]
	v_lshlrev_b32_e32 v136, 16, v120
	v_and_b32_e32 v137, 0xffff0000, v120
	v_pk_fma_f32 v[140:141], v[16:17], v[136:137], v[140:141]
	v_pk_mul_f32 v[142:143], v[142:143], v[146:147]
	v_pk_add_f32 v[140:141], v[140:141], v[12:13]
	v_lshlrev_b32_e32 v112, 16, v113
	v_pk_mul_f32 v[140:141], v[140:141], v[142:143]
	v_lshlrev_b32_e32 v142, 16, v166
	v_and_b32_e32 v143, 0xffff0000, v166
	v_lshlrev_b32_e32 v166, 16, v117
	v_pk_mul_f32 v[116:117], v[6:7], v[166:167]
	v_and_b32_e32 v113, 0xffff0000, v113
	v_pk_fma_f32 v[116:117], v[2:3], v[142:143], v[116:117]
	v_lshlrev_b32_e32 v142, 16, v168
	v_pk_fma_f32 v[116:117], v[10:11], v[112:113], v[116:117]
	v_and_b32_e32 v143, 0xffff0000, v168
	v_pk_add_f32 v[116:117], v[116:117], v[22:23]
	v_lshlrev_b32_e32 v168, 16, v125
	v_and_b32_e32 v169, 0xffff0000, v125
	v_mul_f32_e32 v120, 0xbfb8aa3b, v116
	v_cvt_pk_bf16_f32 v140, v140, v141
	v_pk_mul_f32 v[124:125], v[30:31], v[168:169]
	v_exp_f32_e32 v141, v120
	v_mul_f32_e32 v120, 0xbfb8aa3b, v117
	v_pk_fma_f32 v[124:125], v[26:27], v[142:143], v[124:125]
	v_exp_f32_e32 v143, v120
	v_add_f32_e32 v141, 1.0, v141
	v_rcp_f32_e32 v142, v141
	v_lshlrev_b32_e32 v120, 16, v121
	v_add_f32_e32 v141, 1.0, v143
	v_rcp_f32_e32 v143, v141
	v_and_b32_e32 v121, 0xffff0000, v121
	v_pk_fma_f32 v[124:125], v[18:19], v[120:121], v[124:125]
	v_and_b32_e32 v171, 0xffff0000, v118
	v_pk_add_f32 v[124:125], v[124:125], v[14:15]
	v_pk_mul_f32 v[116:117], v[116:117], v[142:143]
	v_lshlrev_b32_e32 v172, 16, v126
	v_pk_mul_f32 v[116:117], v[124:125], v[116:117]
	v_and_b32_e32 v173, 0xffff0000, v126
	v_cvt_pk_bf16_f32 v141, v116, v117
	v_lshlrev_b32_e32 v116, 16, v170
	v_and_b32_e32 v117, 0xffff0000, v170
	v_lshlrev_b32_e32 v170, 16, v118
	s_waitcnt vmcnt(0) lgkmcnt(0)
	v_pk_mul_f32 v[124:125], v[36:37], v[170:171]
	v_and_b32_e32 v177, 0xffff0000, v127
	v_pk_fma_f32 v[124:125], v[32:33], v[116:117], v[124:125]
	v_lshlrev_b32_e32 v116, 16, v114
	v_and_b32_e32 v117, 0xffff0000, v114
	v_pk_fma_f32 v[124:125], v[40:41], v[116:117], v[124:125]
	v_pk_mul_f32 v[146:147], v[60:61], v[172:173]
	v_pk_add_f32 v[142:143], v[124:125], v[52:53]
	v_lshlrev_b32_e32 v124, 16, v163
	v_mul_f32_e32 v114, 0xbfb8aa3b, v142
	v_exp_f32_e32 v114, v114
	v_mul_f32_e32 v118, 0xbfb8aa3b, v143
	v_exp_f32_e32 v118, v118
	v_and_b32_e32 v125, 0xffff0000, v163
	v_add_f32_e32 v114, 1.0, v114
	v_rcp_f32_e32 v174, v114
	v_add_f32_e32 v114, 1.0, v118
	v_rcp_f32_e32 v175, v114
	v_pk_fma_f32 v[146:147], v[56:57], v[124:125], v[146:147]
	v_lshlrev_b32_e32 v124, 16, v122
	v_and_b32_e32 v125, 0xffff0000, v122
	v_pk_fma_f32 v[146:147], v[44:45], v[124:125], v[146:147]
	v_pk_mul_f32 v[142:143], v[142:143], v[174:175]
	v_pk_add_f32 v[146:147], v[146:147], v[48:49]
	v_lshlrev_b32_e32 v174, 16, v119
	v_and_b32_e32 v175, 0xffff0000, v119
	v_pk_mul_f32 v[142:143], v[146:147], v[142:143]
	v_lshlrev_b32_e32 v146, 16, v176
	v_and_b32_e32 v147, 0xffff0000, v176
	v_pk_mul_f32 v[118:119], v[38:39], v[174:175]
	v_lshlrev_b32_e32 v114, 16, v115
	v_pk_fma_f32 v[118:119], v[34:35], v[146:147], v[118:119]
	v_and_b32_e32 v115, 0xffff0000, v115
	v_pk_fma_f32 v[118:119], v[42:43], v[114:115], v[118:119]
	v_lshlrev_b32_e32 v146, 16, v139
	v_pk_add_f32 v[118:119], v[118:119], v[54:55]
	v_and_b32_e32 v147, 0xffff0000, v139
	v_mul_f32_e32 v122, 0xbfb8aa3b, v118
	v_exp_f32_e32 v122, v122
	v_mul_f32_e32 v139, 0xbfb8aa3b, v119
	v_exp_f32_e32 v139, v139
	v_lshlrev_b32_e32 v176, 16, v127
	v_add_f32_e32 v122, 1.0, v122
	v_rcp_f32_e32 v178, v122
	v_add_f32_e32 v122, 1.0, v139
	v_rcp_f32_e32 v179, v122
	v_pk_mul_f32 v[126:127], v[62:63], v[176:177]
	v_cvt_pk_bf16_f32 v142, v142, v143
	v_pk_fma_f32 v[126:127], v[58:59], v[146:147], v[126:127]
	v_lshlrev_b32_e32 v146, 16, v123
	v_and_b32_e32 v147, 0xffff0000, v123
	v_pk_fma_f32 v[122:123], v[46:47], v[146:147], v[126:127]
	v_pk_mul_f32 v[118:119], v[118:119], v[178:179]
	v_pk_add_f32 v[122:123], v[122:123], v[50:51]
	v_lshlrev_b32_e32 v126, 16, v108
	v_pk_mul_f32 v[118:119], v[122:123], v[118:119]
	v_and_b32_e32 v127, 0xffff0000, v108
	v_cvt_pk_bf16_f32 v143, v118, v119
	v_mad_i64_i32 v[118:119], s[4:5], v138, s26, v[130:131]
	flat_store_dwordx4 v[118:119], v[140:143]
	v_pk_mul_f32 v[118:119], v[4:5], v[134:135]
	v_pk_mul_f32 v[122:123], v[28:29], v[136:137]
	v_pk_fma_f32 v[118:119], v[0:1], v[144:145], v[118:119]
	v_pk_fma_f32 v[122:123], v[24:25], v[164:165], v[122:123]
	v_pk_fma_f32 v[118:119], v[8:9], v[126:127], v[118:119]
	v_lshlrev_b32_e32 v144, 16, v104
	v_pk_add_f32 v[118:119], v[118:119], v[20:21]
	v_and_b32_e32 v145, 0xffff0000, v104
	v_mul_f32_e32 v108, 0xbfb8aa3b, v118
	v_exp_f32_e32 v108, v108
	v_mul_f32_e32 v138, 0xbfb8aa3b, v119
	v_exp_f32_e32 v139, v138
	v_pk_fma_f32 v[122:123], v[16:17], v[144:145], v[122:123]
	v_add_f32_e32 v108, 1.0, v108
	v_rcp_f32_e32 v138, v108
	v_add_f32_e32 v108, 1.0, v139
	v_rcp_f32_e32 v139, v108
	v_pk_add_f32 v[122:123], v[122:123], v[12:13]
	v_lshlrev_b32_e32 v142, 16, v105
	v_and_b32_e32 v143, 0xffff0000, v105
	v_pk_mul_f32 v[118:119], v[118:119], v[138:139]
	s_nop 0
	v_pk_mul_f32 v[118:119], v[122:123], v[118:119]
	v_lshlrev_b32_e32 v122, 16, v109
	v_cvt_pk_bf16_f32 v104, v118, v119
	v_pk_mul_f32 v[118:119], v[6:7], v[112:113]
	v_and_b32_e32 v123, 0xffff0000, v109
	v_pk_fma_f32 v[118:119], v[2:3], v[166:167], v[118:119]
	s_nop 0
	v_pk_fma_f32 v[108:109], v[10:11], v[122:123], v[118:119]
	v_pk_mul_f32 v[118:119], v[30:31], v[120:121]
	v_pk_add_f32 v[108:109], v[108:109], v[22:23]
	v_pk_fma_f32 v[118:119], v[26:27], v[168:169], v[118:119]
	v_mul_f32_e32 v138, 0xbfb8aa3b, v108
	v_mul_f32_e32 v139, 0xbfb8aa3b, v109
	v_exp_f32_e32 v138, v138
	v_exp_f32_e32 v139, v139
	v_pk_fma_f32 v[118:119], v[18:19], v[142:143], v[118:119]
	v_add_f32_e32 v138, 1.0, v138
	v_add_f32_e32 v139, 1.0, v139
	v_rcp_f32_e32 v138, v138
	v_rcp_f32_e32 v139, v139
	v_pk_add_f32 v[118:119], v[118:119], v[14:15]
	v_pk_mul_f32 v[108:109], v[108:109], v[138:139]
	s_nop 0
	v_pk_mul_f32 v[108:109], v[118:119], v[108:109]
	v_lshlrev_b32_e32 v118, 16, v110
	v_cvt_pk_bf16_f32 v105, v108, v109
	v_pk_mul_f32 v[108:109], v[36:37], v[116:117]
	v_and_b32_e32 v119, 0xffff0000, v110
	v_pk_fma_f32 v[108:109], v[32:33], v[170:171], v[108:109]
	v_pk_mul_f32 v[138:139], v[60:61], v[124:125]
	v_pk_fma_f32 v[108:109], v[40:41], v[118:119], v[108:109]
	v_pk_fma_f32 v[138:139], v[56:57], v[172:173], v[138:139]
	v_pk_add_f32 v[108:109], v[108:109], v[52:53]
	s_nop 0
	v_mul_f32_e32 v110, 0xbfb8aa3b, v108
	v_exp_f32_e32 v110, v110
	v_mul_f32_e32 v140, 0xbfb8aa3b, v109
	v_exp_f32_e32 v141, v140
	v_lshlrev_b32_e32 v140, 16, v106
	v_add_f32_e32 v110, 1.0, v110
	v_rcp_f32_e32 v164, v110
	v_add_f32_e32 v110, 1.0, v141
	v_rcp_f32_e32 v165, v110
	v_and_b32_e32 v141, 0xffff0000, v106
	v_pk_fma_f32 v[138:139], v[44:45], v[140:141], v[138:139]
	v_lshlrev_b32_e32 v110, 16, v111
	v_pk_add_f32 v[138:139], v[138:139], v[48:49]
	v_pk_mul_f32 v[108:109], v[108:109], v[164:165]
	v_and_b32_e32 v111, 0xffff0000, v111
	v_pk_mul_f32 v[108:109], v[138:139], v[108:109]
	v_pk_mul_f32 v[138:139], v[62:63], v[146:147]
	v_cvt_pk_bf16_f32 v106, v108, v109
	v_pk_mul_f32 v[108:109], v[38:39], v[114:115]
	v_pk_fma_f32 v[164:165], v[58:59], v[176:177], v[138:139]
	v_pk_fma_f32 v[108:109], v[34:35], v[174:175], v[108:109]
	s_nop 0
	v_pk_fma_f32 v[108:109], v[42:43], v[110:111], v[108:109]
	s_nop 0
	v_pk_add_f32 v[108:109], v[108:109], v[54:55]
	s_nop 0
	v_mul_f32_e32 v138, 0xbfb8aa3b, v108
	v_exp_f32_e32 v139, v138
	v_mul_f32_e32 v138, 0xbfb8aa3b, v109
	v_exp_f32_e32 v163, v138
	v_lshlrev_b32_e32 v138, 16, v107
	v_add_f32_e32 v139, 1.0, v139
	v_rcp_f32_e32 v166, v139
	v_add_f32_e32 v139, 1.0, v163
	v_rcp_f32_e32 v167, v139
	v_and_b32_e32 v139, 0xffff0000, v107
	v_pk_fma_f32 v[164:165], v[46:47], v[138:139], v[164:165]
	v_pk_mul_f32 v[108:109], v[108:109], v[166:167]
	v_pk_add_f32 v[164:165], v[164:165], v[50:51]
	s_nop 0
	v_pk_mul_f32 v[108:109], v[164:165], v[108:109]
	s_nop 0
	v_cvt_pk_bf16_f32 v107, v108, v109
	v_mad_i64_i32 v[108:109], s[4:5], v162, s26, v[130:131]
	flat_store_dwordx4 v[108:109], v[104:107]
	v_lshlrev_b32_e32 v108, 16, v100
	v_and_b32_e32 v109, 0xffff0000, v100
	v_pk_mul_f32 v[104:105], v[4:5], v[126:127]
	v_pk_mul_f32 v[106:107], v[28:29], v[144:145]
	v_pk_fma_f32 v[104:105], v[0:1], v[134:135], v[104:105]
	v_pk_fma_f32 v[106:107], v[24:25], v[136:137], v[106:107]
	v_pk_fma_f32 v[104:105], v[8:9], v[108:109], v[104:105]
	v_lshlrev_b32_e32 v136, 16, v96
	v_pk_add_f32 v[104:105], v[104:105], v[20:21]
	v_and_b32_e32 v137, 0xffff0000, v96
	v_mul_f32_e32 v100, 0xbfb8aa3b, v104
	v_exp_f32_e32 v100, v100
	v_mul_f32_e32 v134, 0xbfb8aa3b, v105
	v_exp_f32_e32 v135, v134
	v_pk_fma_f32 v[106:107], v[16:17], v[136:137], v[106:107]
	v_add_f32_e32 v100, 1.0, v100
	v_rcp_f32_e32 v134, v100
	v_add_f32_e32 v100, 1.0, v135
	v_rcp_f32_e32 v135, v100
	v_pk_add_f32 v[106:107], v[106:107], v[12:13]
	v_pk_mul_f32 v[104:105], v[104:105], v[134:135]
	s_nop 0
	v_pk_mul_f32 v[104:105], v[106:107], v[104:105]
	v_lshlrev_b32_e32 v106, 16, v101
	v_cvt_pk_bf16_f32 v96, v104, v105
	v_pk_mul_f32 v[104:105], v[6:7], v[122:123]
	v_and_b32_e32 v107, 0xffff0000, v101
	v_pk_fma_f32 v[104:105], v[2:3], v[112:113], v[104:105]
	v_lshlrev_b32_e32 v134, 16, v97
	v_pk_fma_f32 v[100:101], v[10:11], v[106:107], v[104:105]
	v_pk_mul_f32 v[104:105], v[30:31], v[142:143]
	v_pk_add_f32 v[100:101], v[100:101], v[22:23]
	v_pk_fma_f32 v[104:105], v[26:27], v[120:121], v[104:105]
	v_mul_f32_e32 v112, 0xbfb8aa3b, v100
	v_mul_f32_e32 v113, 0xbfb8aa3b, v101
	v_exp_f32_e32 v112, v112
	v_exp_f32_e32 v113, v113
	v_and_b32_e32 v135, 0xffff0000, v97
	v_pk_fma_f32 v[104:105], v[18:19], v[134:135], v[104:105]
	v_add_f32_e32 v112, 1.0, v112
	v_add_f32_e32 v113, 1.0, v113
	v_rcp_f32_e32 v112, v112
	v_rcp_f32_e32 v113, v113
	v_pk_add_f32 v[104:105], v[104:105], v[14:15]
	v_lshlrev_b32_e32 v120, 16, v99
	v_and_b32_e32 v121, 0xffff0000, v99
	v_pk_mul_f32 v[100:101], v[100:101], v[112:113]
	v_pk_mul_f32 v[112:113], v[60:61], v[140:141]
	v_pk_mul_f32 v[100:101], v[104:105], v[100:101]
	v_lshlrev_b32_e32 v104, 16, v102
	v_cvt_pk_bf16_f32 v97, v100, v101
	v_pk_mul_f32 v[100:101], v[36:37], v[118:119]
	v_and_b32_e32 v105, 0xffff0000, v102
	v_pk_fma_f32 v[100:101], v[32:33], v[116:117], v[100:101]
	v_pk_fma_f32 v[112:113], v[56:57], v[124:125], v[112:113]
	v_pk_fma_f32 v[100:101], v[40:41], v[104:105], v[100:101]
	v_lshlrev_b32_e32 v124, 16, v98
	v_pk_add_f32 v[100:101], v[100:101], v[52:53]
	v_and_b32_e32 v125, 0xffff0000, v98
	v_mul_f32_e32 v102, 0xbfb8aa3b, v100
	v_exp_f32_e32 v102, v102
	v_mul_f32_e32 v116, 0xbfb8aa3b, v101
	v_exp_f32_e32 v117, v116
	v_pk_fma_f32 v[112:113], v[44:45], v[124:125], v[112:113]
	v_add_f32_e32 v102, 1.0, v102
	v_rcp_f32_e32 v116, v102
	v_add_f32_e32 v102, 1.0, v117
	v_rcp_f32_e32 v117, v102
	v_pk_add_f32 v[112:113], v[112:113], v[48:49]
	v_lshlrev_b32_e32 v102, 16, v103
	v_and_b32_e32 v103, 0xffff0000, v103
	v_pk_mul_f32 v[100:101], v[100:101], v[116:117]
	v_lshlrev_b32_e32 v116, 16, v88
	v_pk_mul_f32 v[100:101], v[112:113], v[100:101]
	v_pk_mul_f32 v[112:113], v[62:63], v[138:139]
	v_cvt_pk_bf16_f32 v98, v100, v101
	v_pk_mul_f32 v[100:101], v[38:39], v[110:111]
	v_pk_fma_f32 v[112:113], v[58:59], v[146:147], v[112:113]
	v_pk_fma_f32 v[100:101], v[34:35], v[114:115], v[100:101]
	v_pk_fma_f32 v[112:113], v[46:47], v[120:121], v[112:113]
	v_pk_fma_f32 v[100:101], v[42:43], v[102:103], v[100:101]
	v_pk_add_f32 v[112:113], v[112:113], v[50:51]
	v_pk_add_f32 v[100:101], v[100:101], v[54:55]
	v_and_b32_e32 v117, 0xffff0000, v88
	v_mul_f32_e32 v114, 0xbfb8aa3b, v100
	v_mul_f32_e32 v115, 0xbfb8aa3b, v101
	v_exp_f32_e32 v114, v114
	v_exp_f32_e32 v115, v115
	v_add_f32_e32 v114, 1.0, v114
	v_add_f32_e32 v115, 1.0, v115
	v_rcp_f32_e32 v114, v114
	v_rcp_f32_e32 v115, v115
	s_nop 0
	v_pk_mul_f32 v[100:101], v[100:101], v[114:115]
	s_nop 0
	v_pk_mul_f32 v[100:101], v[112:113], v[100:101]
	v_lshlrev_b32_e32 v114, 16, v89
	v_cvt_pk_bf16_f32 v99, v100, v101
	v_mad_i64_i32 v[100:101], s[4:5], v161, s26, v[130:131]
	flat_store_dwordx4 v[100:101], v[96:99]
	v_lshlrev_b32_e32 v100, 16, v92
	v_and_b32_e32 v101, 0xffff0000, v92
	v_pk_mul_f32 v[96:97], v[4:5], v[108:109]
	v_pk_mul_f32 v[98:99], v[28:29], v[136:137]
	v_pk_fma_f32 v[96:97], v[0:1], v[126:127], v[96:97]
	v_pk_fma_f32 v[98:99], v[24:25], v[144:145], v[98:99]
	v_pk_fma_f32 v[96:97], v[8:9], v[100:101], v[96:97]
	v_pk_fma_f32 v[98:99], v[16:17], v[116:117], v[98:99]
	v_pk_add_f32 v[96:97], v[96:97], v[20:21]
	v_pk_add_f32 v[98:99], v[98:99], v[12:13]
	v_mul_f32_e32 v92, 0xbfb8aa3b, v96
	v_exp_f32_e32 v92, v92
	v_mul_f32_e32 v112, 0xbfb8aa3b, v97
	v_exp_f32_e32 v113, v112
	v_and_b32_e32 v115, 0xffff0000, v89
	v_add_f32_e32 v92, 1.0, v92
	v_rcp_f32_e32 v112, v92
	v_add_f32_e32 v92, 1.0, v113
	v_rcp_f32_e32 v113, v92
	s_nop 0
	v_pk_mul_f32 v[96:97], v[96:97], v[112:113]
	s_nop 0
	v_pk_mul_f32 v[96:97], v[98:99], v[96:97]
	v_lshlrev_b32_e32 v98, 16, v93
	v_cvt_pk_bf16_f32 v88, v96, v97
	v_pk_mul_f32 v[96:97], v[6:7], v[106:107]
	v_and_b32_e32 v99, 0xffff0000, v93
	v_pk_fma_f32 v[96:97], v[2:3], v[122:123], v[96:97]
	s_nop 0
	v_pk_fma_f32 v[92:93], v[10:11], v[98:99], v[96:97]
	v_pk_mul_f32 v[96:97], v[30:31], v[134:135]
	v_pk_add_f32 v[92:93], v[92:93], v[22:23]
	v_pk_fma_f32 v[96:97], v[26:27], v[142:143], v[96:97]
	v_mul_f32_e32 v112, 0xbfb8aa3b, v92
	v_mul_f32_e32 v113, 0xbfb8aa3b, v93
	v_exp_f32_e32 v112, v112
	v_exp_f32_e32 v113, v113
	v_pk_fma_f32 v[96:97], v[18:19], v[114:115], v[96:97]
	v_add_f32_e32 v112, 1.0, v112
	v_add_f32_e32 v113, 1.0, v113
	v_rcp_f32_e32 v112, v112
	v_rcp_f32_e32 v113, v113
	v_pk_add_f32 v[96:97], v[96:97], v[14:15]
	v_pk_mul_f32 v[92:93], v[92:93], v[112:113]
	s_nop 0
	v_pk_mul_f32 v[92:93], v[96:97], v[92:93]
	v_lshlrev_b32_e32 v96, 16, v94
	v_cvt_pk_bf16_f32 v89, v92, v93
	v_pk_mul_f32 v[92:93], v[36:37], v[104:105]
	v_and_b32_e32 v97, 0xffff0000, v94
	v_pk_fma_f32 v[92:93], v[32:33], v[118:119], v[92:93]
	v_pk_mul_f32 v[112:113], v[60:61], v[124:125]
	v_pk_fma_f32 v[92:93], v[40:41], v[96:97], v[92:93]
	v_pk_fma_f32 v[118:119], v[56:57], v[140:141], v[112:113]
	v_pk_add_f32 v[92:93], v[92:93], v[52:53]
	s_nop 0
	v_mul_f32_e32 v94, 0xbfb8aa3b, v92
	v_exp_f32_e32 v94, v94
	v_mul_f32_e32 v112, 0xbfb8aa3b, v93
	v_exp_f32_e32 v113, v112
	v_lshlrev_b32_e32 v112, 16, v90
	v_add_f32_e32 v94, 1.0, v94
	v_rcp_f32_e32 v122, v94
	v_add_f32_e32 v94, 1.0, v113
	v_rcp_f32_e32 v123, v94
	v_and_b32_e32 v113, 0xffff0000, v90
	v_pk_fma_f32 v[118:119], v[44:45], v[112:113], v[118:119]
	v_lshlrev_b32_e32 v94, 16, v95
	v_pk_add_f32 v[118:119], v[118:119], v[48:49]
	v_pk_mul_f32 v[92:93], v[92:93], v[122:123]
	v_and_b32_e32 v95, 0xffff0000, v95
	v_pk_mul_f32 v[92:93], v[118:119], v[92:93]
	s_nop 0
	v_cvt_pk_bf16_f32 v90, v92, v93
	v_pk_mul_f32 v[92:93], v[38:39], v[102:103]
	s_nop 0
	v_pk_fma_f32 v[92:93], v[34:35], v[110:111], v[92:93]
	v_pk_mul_f32 v[110:111], v[62:63], v[120:121]
	v_pk_fma_f32 v[92:93], v[42:43], v[94:95], v[92:93]
	v_pk_fma_f32 v[118:119], v[58:59], v[138:139], v[110:111]
	v_pk_add_f32 v[92:93], v[92:93], v[54:55]
	s_nop 0
	v_mul_f32_e32 v110, 0xbfb8aa3b, v92
	v_exp_f32_e32 v111, v110
	v_mul_f32_e32 v110, 0xbfb8aa3b, v93
	v_exp_f32_e32 v123, v110
	v_lshlrev_b32_e32 v110, 16, v91
	v_add_f32_e32 v111, 1.0, v111
	v_rcp_f32_e32 v122, v111
	v_add_f32_e32 v111, 1.0, v123
	v_rcp_f32_e32 v123, v111
	v_and_b32_e32 v111, 0xffff0000, v91
	v_pk_fma_f32 v[118:119], v[46:47], v[110:111], v[118:119]
	v_pk_mul_f32 v[92:93], v[92:93], v[122:123]
	v_pk_add_f32 v[118:119], v[118:119], v[50:51]
	s_nop 0
	v_pk_mul_f32 v[92:93], v[118:119], v[92:93]
	s_nop 0
	v_cvt_pk_bf16_f32 v91, v92, v93
	v_mad_i64_i32 v[92:93], s[4:5], v160, s26, v[130:131]
	flat_store_dwordx4 v[92:93], v[88:91]
	v_lshlrev_b32_e32 v92, 16, v84
	v_and_b32_e32 v93, 0xffff0000, v84
	v_pk_mul_f32 v[88:89], v[4:5], v[100:101]
	v_pk_mul_f32 v[90:91], v[28:29], v[116:117]
	v_pk_fma_f32 v[88:89], v[0:1], v[108:109], v[88:89]
	v_pk_fma_f32 v[90:91], v[24:25], v[136:137], v[90:91]
	v_pk_fma_f32 v[88:89], v[8:9], v[92:93], v[88:89]
	s_nop 0
	v_pk_add_f32 v[88:89], v[88:89], v[20:21]
	s_nop 0
	v_mul_f32_e32 v84, 0xbfb8aa3b, v88
	v_exp_f32_e32 v84, v84
	v_mul_f32_e32 v108, 0xbfb8aa3b, v89
	v_exp_f32_e32 v109, v108
	v_lshlrev_b32_e32 v108, 16, v80
	v_add_f32_e32 v84, 1.0, v84
	v_rcp_f32_e32 v118, v84
	v_add_f32_e32 v84, 1.0, v109
	v_rcp_f32_e32 v119, v84
	v_and_b32_e32 v109, 0xffff0000, v80
	v_pk_fma_f32 v[90:91], v[16:17], v[108:109], v[90:91]
	v_pk_mul_f32 v[88:89], v[88:89], v[118:119]
	v_pk_add_f32 v[90:91], v[90:91], v[12:13]
	s_nop 0
	v_pk_mul_f32 v[88:89], v[90:91], v[88:89]
	v_lshlrev_b32_e32 v90, 16, v85
	v_cvt_pk_bf16_f32 v80, v88, v89
	v_pk_mul_f32 v[88:89], v[6:7], v[98:99]
	v_and_b32_e32 v91, 0xffff0000, v85
	v_pk_fma_f32 v[88:89], v[2:3], v[106:107], v[88:89]
	s_nop 0
	v_pk_fma_f32 v[84:85], v[10:11], v[90:91], v[88:89]
	v_pk_mul_f32 v[88:89], v[30:31], v[114:115]
	v_pk_add_f32 v[84:85], v[84:85], v[22:23]
	v_pk_fma_f32 v[88:89], v[26:27], v[134:135], v[88:89]
	v_mul_f32_e32 v106, 0xbfb8aa3b, v84
	v_exp_f32_e32 v107, v106
	v_mul_f32_e32 v106, 0xbfb8aa3b, v85
	v_exp_f32_e32 v119, v106
	v_lshlrev_b32_e32 v106, 16, v81
	v_add_f32_e32 v107, 1.0, v107
	v_rcp_f32_e32 v118, v107
	v_add_f32_e32 v107, 1.0, v119
	v_rcp_f32_e32 v119, v107
	v_and_b32_e32 v107, 0xffff0000, v81
	v_pk_fma_f32 v[88:89], v[18:19], v[106:107], v[88:89]
	v_pk_mul_f32 v[84:85], v[84:85], v[118:119]
	v_pk_add_f32 v[88:89], v[88:89], v[14:15]
	s_nop 0
	v_pk_mul_f32 v[84:85], v[88:89], v[84:85]
	v_lshlrev_b32_e32 v88, 16, v86
	v_cvt_pk_bf16_f32 v81, v84, v85
	v_pk_mul_f32 v[84:85], v[36:37], v[96:97]
	v_and_b32_e32 v89, 0xffff0000, v86
	v_pk_fma_f32 v[84:85], v[32:33], v[104:105], v[84:85]
	v_pk_mul_f32 v[104:105], v[60:61], v[112:113]
	v_pk_fma_f32 v[84:85], v[40:41], v[88:89], v[84:85]
	v_pk_fma_f32 v[118:119], v[56:57], v[124:125], v[104:105]
	v_pk_add_f32 v[84:85], v[84:85], v[52:53]
	s_nop 0
	v_mul_f32_e32 v86, 0xbfb8aa3b, v84
	v_exp_f32_e32 v86, v86
	v_mul_f32_e32 v104, 0xbfb8aa3b, v85
	v_exp_f32_e32 v105, v104
	v_lshlrev_b32_e32 v104, 16, v82
	v_add_f32_e32 v86, 1.0, v86
	v_rcp_f32_e32 v122, v86
	v_add_f32_e32 v86, 1.0, v105
	v_rcp_f32_e32 v123, v86
	v_and_b32_e32 v105, 0xffff0000, v82
	v_pk_fma_f32 v[118:119], v[44:45], v[104:105], v[118:119]
	v_pk_mul_f32 v[84:85], v[84:85], v[122:123]
	v_pk_add_f32 v[118:119], v[118:119], v[48:49]
	s_nop 0
	v_pk_mul_f32 v[84:85], v[118:119], v[84:85]
	s_nop 0
	v_cvt_pk_bf16_f32 v82, v84, v85
	v_pk_mul_f32 v[84:85], v[38:39], v[94:95]
	s_nop 0
	v_pk_fma_f32 v[102:103], v[34:35], v[102:103], v[84:85]
	v_lshlrev_b32_e32 v84, 16, v87
	v_and_b32_e32 v85, 0xffff0000, v87
	v_pk_fma_f32 v[86:87], v[42:43], v[84:85], v[102:103]
	v_pk_mul_f32 v[102:103], v[62:63], v[110:111]
	v_pk_add_f32 v[86:87], v[86:87], v[54:55]
	v_pk_fma_f32 v[118:119], v[58:59], v[120:121], v[102:103]
	v_mul_f32_e32 v102, 0xbfb8aa3b, v86
	v_exp_f32_e32 v103, v102
	v_mul_f32_e32 v102, 0xbfb8aa3b, v87
	v_exp_f32_e32 v121, v102
	v_lshlrev_b32_e32 v102, 16, v83
	v_add_f32_e32 v103, 1.0, v103
	v_rcp_f32_e32 v120, v103
	v_add_f32_e32 v103, 1.0, v121
	v_rcp_f32_e32 v121, v103
	v_and_b32_e32 v103, 0xffff0000, v83
	v_pk_fma_f32 v[118:119], v[46:47], v[102:103], v[118:119]
	v_pk_mul_f32 v[86:87], v[86:87], v[120:121]
	v_pk_add_f32 v[118:119], v[118:119], v[50:51]
	s_nop 0
	v_pk_mul_f32 v[86:87], v[118:119], v[86:87]
	s_nop 0
	v_cvt_pk_bf16_f32 v83, v86, v87
	v_mad_i64_i32 v[86:87], s[4:5], v159, s26, v[130:131]
	flat_store_dwordx4 v[86:87], v[80:83]
	v_pk_mul_f32 v[86:87], v[28:29], v[108:109]
	s_nop 0
	v_pk_mul_f32 v[80:81], v[4:5], v[92:93]
	v_lshlrev_b32_e32 v82, 16, v76
	v_pk_fma_f32 v[80:81], v[0:1], v[100:101], v[80:81]
	v_and_b32_e32 v83, 0xffff0000, v76
	v_pk_fma_f32 v[80:81], v[8:9], v[82:83], v[80:81]
	v_pk_fma_f32 v[86:87], v[24:25], v[116:117], v[86:87]
	v_pk_add_f32 v[80:81], v[80:81], v[20:21]
	s_nop 0
	v_mul_f32_e32 v76, 0xbfb8aa3b, v80
	v_exp_f32_e32 v76, v76
	v_mul_f32_e32 v100, 0xbfb8aa3b, v81
	v_exp_f32_e32 v101, v100
	v_lshlrev_b32_e32 v100, 16, v72
	v_add_f32_e32 v76, 1.0, v76
	v_rcp_f32_e32 v116, v76
	v_add_f32_e32 v76, 1.0, v101
	v_rcp_f32_e32 v117, v76
	v_and_b32_e32 v101, 0xffff0000, v72
	v_pk_fma_f32 v[86:87], v[16:17], v[100:101], v[86:87]
	v_pk_mul_f32 v[80:81], v[80:81], v[116:117]
	v_pk_add_f32 v[86:87], v[86:87], v[12:13]
	s_nop 0
	v_pk_mul_f32 v[80:81], v[86:87], v[80:81]
	s_nop 0
	v_cvt_pk_bf16_f32 v116, v80, v81
	v_pk_mul_f32 v[80:81], v[6:7], v[90:91]
	s_nop 0
	v_pk_fma_f32 v[86:87], v[2:3], v[98:99], v[80:81]
	v_lshlrev_b32_e32 v80, 16, v77
	v_and_b32_e32 v81, 0xffff0000, v77
	v_pk_fma_f32 v[76:77], v[10:11], v[80:81], v[86:87]
	v_pk_mul_f32 v[86:87], v[30:31], v[106:107]
	v_pk_add_f32 v[76:77], v[76:77], v[22:23]
	v_pk_fma_f32 v[86:87], v[26:27], v[114:115], v[86:87]
	v_mul_f32_e32 v72, 0xbfb8aa3b, v76
	v_exp_f32_e32 v72, v72
	v_mul_f32_e32 v98, 0xbfb8aa3b, v77
	v_exp_f32_e32 v99, v98
	v_lshlrev_b32_e32 v98, 16, v73
	v_add_f32_e32 v72, 1.0, v72
	v_rcp_f32_e32 v114, v72
	v_add_f32_e32 v72, 1.0, v99
	v_rcp_f32_e32 v115, v72
	v_and_b32_e32 v99, 0xffff0000, v73
	v_pk_fma_f32 v[72:73], v[18:19], v[98:99], v[86:87]
	v_pk_mul_f32 v[86:87], v[60:61], v[104:105]
	v_pk_add_f32 v[72:73], v[72:73], v[14:15]
	v_pk_mul_f32 v[76:77], v[76:77], v[114:115]
	s_nop 0
	v_pk_mul_f32 v[72:73], v[72:73], v[76:77]
	v_lshlrev_b32_e32 v76, 16, v78
	v_cvt_pk_bf16_f32 v117, v72, v73
	v_pk_mul_f32 v[72:73], v[36:37], v[88:89]
	v_and_b32_e32 v77, 0xffff0000, v78
	v_pk_fma_f32 v[72:73], v[32:33], v[96:97], v[72:73]
	v_pk_fma_f32 v[96:97], v[56:57], v[112:113], v[86:87]
	v_pk_fma_f32 v[72:73], v[40:41], v[76:77], v[72:73]
	s_nop 0
	v_pk_add_f32 v[72:73], v[72:73], v[52:53]
	s_nop 0
	v_mul_f32_e32 v78, 0xbfb8aa3b, v72
	v_exp_f32_e32 v78, v78
	v_mul_f32_e32 v86, 0xbfb8aa3b, v73
	v_exp_f32_e32 v87, v86
	v_lshlrev_b32_e32 v86, 16, v74
	v_add_f32_e32 v78, 1.0, v78
	v_rcp_f32_e32 v112, v78
	v_add_f32_e32 v78, 1.0, v87
	v_rcp_f32_e32 v113, v78
	v_and_b32_e32 v87, 0xffff0000, v74
	v_pk_fma_f32 v[96:97], v[44:45], v[86:87], v[96:97]
	v_pk_mul_f32 v[72:73], v[72:73], v[112:113]
	v_pk_add_f32 v[96:97], v[96:97], v[48:49]
	s_nop 0
	v_pk_mul_f32 v[72:73], v[96:97], v[72:73]
	s_nop 0
	v_cvt_pk_bf16_f32 v118, v72, v73
	v_pk_mul_f32 v[72:73], v[38:39], v[84:85]
	s_nop 0
	v_pk_fma_f32 v[94:95], v[34:35], v[94:95], v[72:73]
	v_lshlrev_b32_e32 v72, 16, v79
	v_and_b32_e32 v73, 0xffff0000, v79
	v_pk_fma_f32 v[78:79], v[42:43], v[72:73], v[94:95]
	v_pk_mul_f32 v[94:95], v[62:63], v[102:103]
	v_pk_add_f32 v[78:79], v[78:79], v[54:55]
	v_pk_fma_f32 v[94:95], v[58:59], v[110:111], v[94:95]
	v_mul_f32_e32 v74, 0xbfb8aa3b, v78
	v_exp_f32_e32 v96, v74
	v_mul_f32_e32 v74, 0xbfb8aa3b, v79
	v_exp_f32_e32 v97, v74
	v_lshlrev_b32_e32 v74, 16, v75
	v_add_f32_e32 v96, 1.0, v96
	v_rcp_f32_e32 v96, v96
	v_add_f32_e32 v97, 1.0, v97
	v_rcp_f32_e32 v97, v97
	v_and_b32_e32 v75, 0xffff0000, v75
	v_pk_fma_f32 v[94:95], v[46:47], v[74:75], v[94:95]
	v_pk_mul_f32 v[78:79], v[78:79], v[96:97]
	v_pk_add_f32 v[94:95], v[94:95], v[50:51]
	s_nop 0
	v_pk_mul_f32 v[78:79], v[94:95], v[78:79]
	v_pk_mul_f32 v[94:95], v[28:29], v[100:101]
	v_cvt_pk_bf16_f32 v119, v78, v79
	v_mad_i64_i32 v[78:79], s[4:5], v158, s26, v[130:131]
	flat_store_dwordx4 v[78:79], v[116:119]
	v_pk_mul_f32 v[78:79], v[4:5], v[82:83]
	v_pk_fma_f32 v[94:95], v[24:25], v[108:109], v[94:95]
	v_pk_fma_f32 v[78:79], v[0:1], v[92:93], v[78:79]
	v_lshlrev_b32_e32 v92, 16, v68
	v_and_b32_e32 v93, 0xffff0000, v68
	v_pk_fma_f32 v[78:79], v[8:9], v[92:93], v[78:79]
	v_pk_mul_f32 v[4:5], v[4:5], v[92:93]
	v_pk_add_f32 v[78:79], v[78:79], v[20:21]
	v_pk_fma_f32 v[0:1], v[0:1], v[82:83], v[4:5]
	v_mul_f32_e32 v68, 0xbfb8aa3b, v78
	v_lshlrev_b32_e32 v4, 16, v157
	v_and_b32_e32 v5, 0xffff0000, v157
	v_exp_f32_e32 v68, v68
	v_mul_f32_e32 v96, 0xbfb8aa3b, v79
	v_pk_fma_f32 v[0:1], v[8:9], v[4:5], v[0:1]
	v_exp_f32_e32 v97, v96
	v_pk_add_f32 v[0:1], v[0:1], v[20:21]
	v_add_f32_e32 v68, 1.0, v68
	v_mul_f32_e32 v8, 0xbfb8aa3b, v0
	v_exp_f32_e32 v9, v8
	v_mul_f32_e32 v8, 0xbfb8aa3b, v1
	v_exp_f32_e32 v21, v8
	v_rcp_f32_e32 v108, v68
	v_add_f32_e32 v68, 1.0, v97
	v_rcp_f32_e32 v109, v68
	v_add_f32_e32 v9, 1.0, v9
	v_lshlrev_b32_e32 v96, 16, v64
	v_and_b32_e32 v97, 0xffff0000, v64
	v_rcp_f32_e32 v20, v9
	v_add_f32_e32 v9, 1.0, v21
	v_pk_fma_f32 v[94:95], v[16:17], v[96:97], v[94:95]
	v_rcp_f32_e32 v21, v9
	v_pk_add_f32 v[94:95], v[94:95], v[12:13]
	v_pk_mul_f32 v[78:79], v[78:79], v[108:109]
	v_pk_mul_f32 v[4:5], v[28:29], v[96:97]
	v_pk_mul_f32 v[78:79], v[94:95], v[78:79]
	v_pk_fma_f32 v[4:5], v[24:25], v[100:101], v[4:5]
	v_lshlrev_b32_e32 v8, 16, v152
	v_and_b32_e32 v9, 0xffff0000, v152
	v_cvt_pk_bf16_f32 v64, v78, v79
	v_pk_mul_f32 v[78:79], v[6:7], v[80:81]
	v_pk_fma_f32 v[4:5], v[16:17], v[8:9], v[4:5]
	v_pk_fma_f32 v[78:79], v[2:3], v[90:91], v[78:79]
	v_lshlrev_b32_e32 v68, 16, v69
	v_and_b32_e32 v69, 0xffff0000, v69
	v_pk_add_f32 v[4:5], v[4:5], v[12:13]
	v_pk_mul_f32 v[0:1], v[0:1], v[20:21]
	v_pk_fma_f32 v[78:79], v[10:11], v[68:69], v[78:79]
	v_pk_mul_f32 v[0:1], v[4:5], v[0:1]
	v_pk_mul_f32 v[4:5], v[6:7], v[68:69]
	v_pk_add_f32 v[78:79], v[78:79], v[22:23]
	v_pk_fma_f32 v[2:3], v[2:3], v[80:81], v[4:5]
	v_lshlrev_b32_e32 v4, 16, v156
	v_and_b32_e32 v5, 0xffff0000, v156
	v_mul_f32_e32 v94, 0xbfb8aa3b, v78
	v_pk_fma_f32 v[2:3], v[10:11], v[4:5], v[2:3]
	v_pk_mul_f32 v[90:91], v[30:31], v[98:99]
	v_exp_f32_e32 v95, v94
	v_mul_f32_e32 v94, 0xbfb8aa3b, v79
	v_pk_add_f32 v[2:3], v[2:3], v[22:23]
	v_pk_fma_f32 v[90:91], v[26:27], v[106:107], v[90:91]
	v_exp_f32_e32 v107, v94
	v_cvt_pk_bf16_f32 v0, v0, v1
	v_mul_f32_e32 v1, 0xbfb8aa3b, v2
	v_exp_f32_e32 v1, v1
	v_mul_f32_e32 v6, 0xbfb8aa3b, v3
	v_exp_f32_e32 v7, v6
	v_add_f32_e32 v95, 1.0, v95
	v_rcp_f32_e32 v106, v95
	v_add_f32_e32 v95, 1.0, v107
	v_rcp_f32_e32 v107, v95
	v_add_f32_e32 v1, 1.0, v1
	v_rcp_f32_e32 v8, v1
	v_add_f32_e32 v1, 1.0, v7
	v_lshlrev_b32_e32 v94, 16, v65
	v_and_b32_e32 v95, 0xffff0000, v65
	v_rcp_f32_e32 v9, v1
	v_pk_fma_f32 v[90:91], v[18:19], v[94:95], v[90:91]
	v_pk_mul_f32 v[4:5], v[30:31], v[94:95]
	v_pk_add_f32 v[90:91], v[90:91], v[14:15]
	v_pk_mul_f32 v[78:79], v[78:79], v[106:107]
	v_pk_fma_f32 v[4:5], v[26:27], v[98:99], v[4:5]
	v_lshlrev_b32_e32 v6, 16, v151
	v_and_b32_e32 v7, 0xffff0000, v151
	v_pk_mul_f32 v[78:79], v[90:91], v[78:79]
	v_pk_fma_f32 v[4:5], v[18:19], v[6:7], v[4:5]
	v_cvt_pk_bf16_f32 v65, v78, v79
	v_pk_mul_f32 v[78:79], v[36:37], v[76:77]
	v_pk_add_f32 v[4:5], v[4:5], v[14:15]
	v_pk_mul_f32 v[2:3], v[2:3], v[8:9]
	v_pk_fma_f32 v[78:79], v[32:33], v[88:89], v[78:79]
	v_lshlrev_b32_e32 v88, 16, v70
	v_and_b32_e32 v89, 0xffff0000, v70
	v_pk_mul_f32 v[2:3], v[4:5], v[2:3]
	v_pk_fma_f32 v[78:79], v[40:41], v[88:89], v[78:79]
	v_cvt_pk_bf16_f32 v1, v2, v3
	v_pk_mul_f32 v[2:3], v[36:37], v[88:89]
	v_lshlrev_b32_e32 v4, 16, v155
	v_pk_fma_f32 v[2:3], v[32:33], v[76:77], v[2:3]
	v_and_b32_e32 v5, 0xffff0000, v155
	v_pk_add_f32 v[78:79], v[78:79], v[52:53]
	v_pk_fma_f32 v[2:3], v[40:41], v[4:5], v[2:3]
	v_pk_mul_f32 v[90:91], v[60:61], v[86:87]
	v_mul_f32_e32 v70, 0xbfb8aa3b, v78
	v_pk_add_f32 v[2:3], v[2:3], v[52:53]
	v_pk_fma_f32 v[90:91], v[56:57], v[104:105], v[90:91]
	v_exp_f32_e32 v70, v70
	v_mul_f32_e32 v104, 0xbfb8aa3b, v79
	v_mul_f32_e32 v6, 0xbfb8aa3b, v2
	v_exp_f32_e32 v105, v104
	v_exp_f32_e32 v7, v6
	v_mul_f32_e32 v6, 0xbfb8aa3b, v3
	v_exp_f32_e32 v9, v6
	v_add_f32_e32 v70, 1.0, v70
	v_rcp_f32_e32 v106, v70
	v_add_f32_e32 v70, 1.0, v105
	v_add_f32_e32 v7, 1.0, v7
	v_rcp_f32_e32 v107, v70
	v_rcp_f32_e32 v8, v7
	v_add_f32_e32 v7, 1.0, v9
	v_lshlrev_b32_e32 v104, 16, v66
	v_and_b32_e32 v105, 0xffff0000, v66
	v_rcp_f32_e32 v9, v7
	v_pk_mul_f32 v[4:5], v[60:61], v[104:105]
	v_pk_fma_f32 v[90:91], v[44:45], v[104:105], v[90:91]
	v_pk_fma_f32 v[4:5], v[56:57], v[86:87], v[4:5]
	v_lshlrev_b32_e32 v6, 16, v150
	v_and_b32_e32 v7, 0xffff0000, v150
	v_pk_add_f32 v[90:91], v[90:91], v[48:49]
	v_pk_mul_f32 v[78:79], v[78:79], v[106:107]
	v_pk_fma_f32 v[4:5], v[44:45], v[6:7], v[4:5]
	v_pk_mul_f32 v[78:79], v[90:91], v[78:79]
	v_lshlrev_b32_e32 v70, 16, v71
	v_and_b32_e32 v71, 0xffff0000, v71
	v_pk_add_f32 v[4:5], v[4:5], v[48:49]
	v_pk_mul_f32 v[2:3], v[2:3], v[8:9]
	v_cvt_pk_bf16_f32 v66, v78, v79
	v_pk_mul_f32 v[78:79], v[38:39], v[72:73]
	v_pk_mul_f32 v[2:3], v[4:5], v[2:3]
	v_pk_mul_f32 v[4:5], v[38:39], v[70:71]
	v_pk_fma_f32 v[78:79], v[34:35], v[84:85], v[78:79]
	v_pk_fma_f32 v[4:5], v[34:35], v[72:73], v[4:5]
	v_lshlrev_b32_e32 v6, 16, v154
	v_and_b32_e32 v7, 0xffff0000, v154
	v_pk_fma_f32 v[78:79], v[42:43], v[70:71], v[78:79]
	v_pk_fma_f32 v[4:5], v[42:43], v[6:7], v[4:5]
	v_pk_add_f32 v[78:79], v[78:79], v[54:55]
	v_pk_add_f32 v[4:5], v[4:5], v[54:55]
	v_mul_f32_e32 v90, 0xbfb8aa3b, v78
	v_cvt_pk_bf16_f32 v2, v2, v3
	v_mul_f32_e32 v3, 0xbfb8aa3b, v4
	v_pk_mul_f32 v[84:85], v[62:63], v[74:75]
	v_exp_f32_e32 v91, v90
	v_mul_f32_e32 v90, 0xbfb8aa3b, v79
	v_exp_f32_e32 v3, v3
	v_mul_f32_e32 v8, 0xbfb8aa3b, v5
	v_pk_fma_f32 v[84:85], v[58:59], v[102:103], v[84:85]
	v_exp_f32_e32 v103, v90
	v_exp_f32_e32 v9, v8
	v_add_f32_e32 v91, 1.0, v91
	v_add_f32_e32 v3, 1.0, v3
	v_rcp_f32_e32 v102, v91
	v_add_f32_e32 v91, 1.0, v103
	v_rcp_f32_e32 v10, v3
	v_add_f32_e32 v3, 1.0, v9
	v_lshlrev_b32_e32 v90, 16, v67
	v_rcp_f32_e32 v103, v91
	v_and_b32_e32 v91, 0xffff0000, v67
	v_rcp_f32_e32 v11, v3
	v_pk_mul_f32 v[6:7], v[62:63], v[90:91]
	v_lshlrev_b32_e32 v8, 16, v149
	v_pk_fma_f32 v[6:7], v[58:59], v[74:75], v[6:7]
	v_and_b32_e32 v9, 0xffff0000, v149
	v_pk_fma_f32 v[84:85], v[46:47], v[90:91], v[84:85]
	v_pk_fma_f32 v[6:7], v[46:47], v[8:9], v[6:7]
	v_pk_add_f32 v[84:85], v[84:85], v[50:51]
	v_pk_mul_f32 v[78:79], v[78:79], v[102:103]
	v_pk_add_f32 v[6:7], v[6:7], v[50:51]
	v_pk_mul_f32 v[4:5], v[4:5], v[10:11]
	v_pk_mul_f32 v[78:79], v[84:85], v[78:79]
	v_pk_mul_f32 v[4:5], v[6:7], v[4:5]
	v_cvt_pk_bf16_f32 v67, v78, v79
	v_mad_i64_i32 v[78:79], s[4:5], v153, s26, v[130:131]
	v_cvt_pk_bf16_f32 v3, v4, v5
	v_mad_i64_i32 v[4:5], s[4:5], v128, s26, v[130:131]
	flat_store_dwordx4 v[78:79], v[64:67]
	flat_store_dwordx4 v[4:5], v[0:3]
	s_branch .LBB0_990

.Lnxn_1040:
	s_waitcnt lgkmcnt(0)
	s_waitcnt lgkmcnt(3)
	v_mfma_f32_16x16x32_bf16 v[108:111], v[178:181], v[162:165], v[108:111]
	v_mfma_f32_16x16x32_bf16 v[92:95], v[178:181], v[166:169], v[92:95]
	v_mfma_f32_16x16x32_bf16 v[76:79], v[178:181], v[170:173], v[76:79]
	v_mfma_f32_16x16x32_bf16 v[60:63], v[178:181], v[174:177], v[60:63]
	ds_read_b128 v[240:243], v197
	ds_read_b128 v[244:247], v198
	s_waitcnt lgkmcnt(4)
	v_mfma_f32_16x16x32_bf16 v[104:107], v[182:185], v[162:165], v[104:107]
	v_mfma_f32_16x16x32_bf16 v[88:91], v[182:185], v[166:169], v[88:91]
	v_mfma_f32_16x16x32_bf16 v[72:75], v[182:185], v[170:173], v[72:75]
	v_mfma_f32_16x16x32_bf16 v[56:59], v[182:185], v[174:177], v[56:59]
	ds_read_b128 v[248:251], v199
	ds_read_b128 v[252:255], v200
	s_waitcnt lgkmcnt(5)
	v_mfma_f32_16x16x32_bf16 v[100:103], v[186:189], v[162:165], v[100:103]
	v_mfma_f32_16x16x32_bf16 v[84:87], v[186:189], v[166:169], v[84:87]
	v_mfma_f32_16x16x32_bf16 v[68:71], v[186:189], v[170:173], v[68:71]
	v_mfma_f32_16x16x32_bf16 v[52:55], v[186:189], v[174:177], v[52:55]
	s_waitcnt lgkmcnt(4)
	v_mfma_f32_16x16x32_bf16 v[96:99], v[190:193], v[162:165], v[96:99]
	v_mfma_f32_16x16x32_bf16 v[80:83], v[190:193], v[166:169], v[80:83]
	v_mfma_f32_16x16x32_bf16 v[64:67], v[190:193], v[170:173], v[64:67]
	v_mfma_f32_16x16x32_bf16 v[48:51], v[190:193], v[174:177], v[48:51]
	ds_read_b128 v[162:165], v161 offset:1024
	ds_read_b128 v[166:169], v194 offset:1024
	ds_read_b128 v[170:173], v195 offset:1024
	ds_read_b128 v[174:177], v196 offset:1024
	s_waitcnt lgkmcnt(4)
	v_mfma_f32_16x16x32_bf16 v[44:47], v[178:181], v[240:243], v[44:47]
	v_mfma_f32_16x16x32_bf16 v[28:31], v[178:181], v[244:247], v[28:31]
	v_mfma_f32_16x16x32_bf16 v[12:15], v[178:181], v[248:251], v[12:15]
	v_mfma_f32_16x16x32_bf16 v[112:115], v[178:181], v[252:255], v[112:115]
	ds_read_b128 v[178:181], v128 offset:33792
	v_mfma_f32_16x16x32_bf16 v[40:43], v[182:185], v[240:243], v[40:43]
	v_mfma_f32_16x16x32_bf16 v[24:27], v[182:185], v[244:247], v[24:27]
	v_mfma_f32_16x16x32_bf16 v[8:11], v[182:185], v[248:251], v[8:11]
	v_mfma_f32_16x16x32_bf16 v[116:119], v[182:185], v[252:255], v[116:119]
	ds_read_b128 v[182:185], v128 offset:35840
	v_mfma_f32_16x16x32_bf16 v[36:39], v[186:189], v[240:243], v[36:39]
	v_mfma_f32_16x16x32_bf16 v[20:23], v[186:189], v[244:247], v[20:23]
	v_mfma_f32_16x16x32_bf16 v[4:7], v[186:189], v[248:251], v[4:7]
	v_mfma_f32_16x16x32_bf16 v[120:123], v[186:189], v[252:255], v[120:123]
	ds_read_b128 v[186:189], v128 offset:37888
	v_mfma_f32_16x16x32_bf16 v[32:35], v[190:193], v[240:243], v[32:35]
	v_mfma_f32_16x16x32_bf16 v[16:19], v[190:193], v[244:247], v[16:19]
	v_mfma_f32_16x16x32_bf16 v[0:3], v[190:193], v[248:251], v[0:3]
	v_mfma_f32_16x16x32_bf16 v[124:127], v[190:193], v[252:255], v[124:127]
	ds_read_b128 v[190:193], v128 offset:39936
	s_waitcnt lgkmcnt(3)
	v_mfma_f32_16x16x32_bf16 v[108:111], v[178:181], v[162:165], v[108:111]
	v_mfma_f32_16x16x32_bf16 v[92:95], v[178:181], v[166:169], v[92:95]
	v_mfma_f32_16x16x32_bf16 v[76:79], v[178:181], v[170:173], v[76:79]
	v_mfma_f32_16x16x32_bf16 v[60:63], v[178:181], v[174:177], v[60:63]
	ds_read_b128 v[240:243], v197 offset:1024
	ds_read_b128 v[244:247], v198 offset:1024
	s_waitcnt lgkmcnt(4)
	v_mfma_f32_16x16x32_bf16 v[104:107], v[182:185], v[162:165], v[104:107]
	v_mfma_f32_16x16x32_bf16 v[88:91], v[182:185], v[166:169], v[88:91]
	v_mfma_f32_16x16x32_bf16 v[72:75], v[182:185], v[170:173], v[72:75]
	v_mfma_f32_16x16x32_bf16 v[56:59], v[182:185], v[174:177], v[56:59]
	ds_read_b128 v[248:251], v199 offset:1024
	ds_read_b128 v[252:255], v200 offset:1024
	s_waitcnt lgkmcnt(5)
	v_mfma_f32_16x16x32_bf16 v[100:103], v[186:189], v[162:165], v[100:103]
	v_mfma_f32_16x16x32_bf16 v[84:87], v[186:189], v[166:169], v[84:87]
	v_mfma_f32_16x16x32_bf16 v[68:71], v[186:189], v[170:173], v[68:71]
	v_mfma_f32_16x16x32_bf16 v[52:55], v[186:189], v[174:177], v[52:55]
	s_waitcnt lgkmcnt(4)
	v_mfma_f32_16x16x32_bf16 v[96:99], v[190:193], v[162:165], v[96:99]
	v_mfma_f32_16x16x32_bf16 v[80:83], v[190:193], v[166:169], v[80:83]
	v_mfma_f32_16x16x32_bf16 v[64:67], v[190:193], v[170:173], v[64:67]
	v_mfma_f32_16x16x32_bf16 v[48:51], v[190:193], v[174:177], v[48:51]
	s_waitcnt lgkmcnt(0)
	v_mfma_f32_16x16x32_bf16 v[44:47], v[178:181], v[240:243], v[44:47]
	v_mfma_f32_16x16x32_bf16 v[28:31], v[178:181], v[244:247], v[28:31]
	v_mfma_f32_16x16x32_bf16 v[12:15], v[178:181], v[248:251], v[12:15]
	v_mfma_f32_16x16x32_bf16 v[112:115], v[178:181], v[252:255], v[112:115]
	v_mfma_f32_16x16x32_bf16 v[40:43], v[182:185], v[240:243], v[40:43]
	v_mfma_f32_16x16x32_bf16 v[24:27], v[182:185], v[244:247], v[24:27]
	v_mfma_f32_16x16x32_bf16 v[8:11], v[182:185], v[248:251], v[8:11]
	v_mfma_f32_16x16x32_bf16 v[116:119], v[182:185], v[252:255], v[116:119]
	v_mfma_f32_16x16x32_bf16 v[36:39], v[186:189], v[240:243], v[36:39]
	v_mfma_f32_16x16x32_bf16 v[20:23], v[186:189], v[244:247], v[20:23]
	v_mfma_f32_16x16x32_bf16 v[4:7], v[186:189], v[248:251], v[4:7]
	v_mfma_f32_16x16x32_bf16 v[120:123], v[186:189], v[252:255], v[120:123]
	v_mfma_f32_16x16x32_bf16 v[32:35], v[190:193], v[240:243], v[32:35]
	v_mfma_f32_16x16x32_bf16 v[16:19], v[190:193], v[244:247], v[16:19]
	v_mfma_f32_16x16x32_bf16 v[0:3], v[190:193], v[248:251], v[0:3]
	v_mfma_f32_16x16x32_bf16 v[124:127], v[190:193], v[252:255], v[124:127]
	v_mov_b32_e32 v128, s20
	s_waitcnt vmcnt(8)
	s_barrier
	ds_read_b64 v[130:131], v128
	v_ashrrev_i32_e32 v128, 1, v148
	v_and_b32_e32 v128, 0xffffff80, v128
	v_add_u32_e32 v128, s16, v128
	s_ashr_i32 s15, s14, 31
	s_waitcnt lgkmcnt(0)
	v_mad_i64_i32 v[130:131], s[16:17], v128, s26, v[130:131]
	v_and_b32_e32 v128, 0xc0, v148
	v_lshrrev_b32_e32 v135, 6, v148
	v_lshl_add_u64 v[130:131], s[14:15], 1, v[130:131]
	v_lshlrev_b32_e32 v128, 1, v128
	v_add_co_u32_e32 v130, vcc, v130, v128
	v_addc_co_u32_e32 v131, vcc, v131, v129, vcc
	v_mul_lo_u32 v128, v135, s27
	v_add_u32_e32 v135, s24, v128
	v_lshrrev_b32_e32 v128, 1, v148
	v_and_b32_e32 v136, 24, v128
	v_lshlrev_b32_e32 v128, 4, v148
	v_bfe_u32 v137, v148, 3, 3
	v_and_b32_e32 v134, 15, v148
	v_and_b32_e32 v128, 0x70, v128
	v_mul_u32_u24_e32 v138, 0x90, v137
	v_add_co_u32_e32 v130, vcc, v130, v128
	v_addc_co_u32_e32 v131, vcc, v131, v129, vcc
	v_add3_u32 v138, v135, v128, v138
	v_mul_u32_u24_e32 v128, 0x90, v134
	v_add3_u32 v134, v135, v136, v128
	v_cvt_pk_bf16_f32 v108, v108, v109
	v_cvt_pk_bf16_f32 v109, v110, v111
	v_cvt_pk_bf16_f32 v104, v104, v105
	v_cvt_pk_bf16_f32 v105, v106, v107
	v_cvt_pk_bf16_f32 v100, v100, v101
	v_cvt_pk_bf16_f32 v101, v102, v103
	v_cvt_pk_bf16_f32 v96, v96, v97
	v_cvt_pk_bf16_f32 v97, v98, v99
	v_cvt_pk_bf16_f32 v92, v92, v93
	v_cvt_pk_bf16_f32 v93, v94, v95
	v_cvt_pk_bf16_f32 v88, v88, v89
	v_cvt_pk_bf16_f32 v89, v90, v91
	v_cvt_pk_bf16_f32 v84, v84, v85
	v_cvt_pk_bf16_f32 v85, v86, v87
	v_cvt_pk_bf16_f32 v80, v80, v81
	v_cvt_pk_bf16_f32 v81, v82, v83
	v_cvt_pk_bf16_f32 v76, v76, v77
	v_cvt_pk_bf16_f32 v77, v78, v79
	v_cvt_pk_bf16_f32 v72, v72, v73
	v_cvt_pk_bf16_f32 v73, v74, v75
	v_cvt_pk_bf16_f32 v68, v68, v69
	v_cvt_pk_bf16_f32 v69, v70, v71
	v_cvt_pk_bf16_f32 v64, v64, v65
	v_cvt_pk_bf16_f32 v65, v66, v67
	v_cvt_pk_bf16_f32 v60, v60, v61
	v_cvt_pk_bf16_f32 v61, v62, v63
	v_cvt_pk_bf16_f32 v56, v56, v57
	v_cvt_pk_bf16_f32 v57, v58, v59
	v_cvt_pk_bf16_f32 v52, v52, v53
	v_cvt_pk_bf16_f32 v53, v54, v55
	v_cvt_pk_bf16_f32 v48, v48, v49
	v_cvt_pk_bf16_f32 v49, v50, v51
	ds_write_b64 v134, v[108:109]
	ds_write_b64 v134, v[104:105] offset:32
	ds_write_b64 v134, v[100:101] offset:64
	ds_write_b64 v134, v[96:97] offset:96
	ds_write_b64 v134, v[92:93] offset:2304
	ds_write_b64 v134, v[88:89] offset:2336
	ds_write_b64 v134, v[84:85] offset:2368
	ds_write_b64 v134, v[80:81] offset:2400
	ds_write_b64 v134, v[76:77] offset:4608
	ds_write_b64 v134, v[72:73] offset:4640
	ds_write_b64 v134, v[68:69] offset:4672
	ds_write_b64 v134, v[64:65] offset:4704
	ds_write_b64 v134, v[60:61] offset:6912
	ds_write_b64 v134, v[56:57] offset:6944
	ds_write_b64 v134, v[52:53] offset:6976
	ds_write_b64 v134, v[48:49] offset:7008
	ds_read_b128 v[48:51], v138
	v_mul_u32_u24_e32 v54, 0xa00, v137
	v_lshl_add_u64 v[52:53], v[130:131], 0, s[12:13]
	v_lshlrev_b32_e32 v128, 1, v54
	v_add_co_u32_e32 v54, vcc, v52, v128
	v_addc_co_u32_e32 v55, vcc, v53, v129, vcc
	s_waitcnt lgkmcnt(0)
	global_store_dwordx4 v[54:55], v[48:51], off nt
	ds_read_b128 v[48:51], v138 offset:1152
	v_add_co_u32_e32 v56, vcc, s22, v54
	v_cvt_pk_bf16_f32 v0, v0, v1
	s_nop 0
	v_addc_co_u32_e32 v57, vcc, 0, v55, vcc
	s_waitcnt lgkmcnt(0)
	global_store_dwordx4 v[56:57], v[48:51], off nt
	ds_read_b128 v[48:51], v138 offset:2304
	v_add_co_u32_e32 v56, vcc, s28, v54
	v_cvt_pk_bf16_f32 v1, v2, v3
	s_nop 0
	v_addc_co_u32_e32 v57, vcc, 0, v55, vcc
	s_waitcnt lgkmcnt(0)
	global_store_dwordx4 v[56:57], v[48:51], off nt
	ds_read_b128 v[48:51], v138 offset:3456
	v_add_co_u32_e32 v56, vcc, s29, v54
	v_cvt_pk_bf16_f32 v44, v44, v45
	s_nop 0
	v_addc_co_u32_e32 v57, vcc, 0, v55, vcc
	s_waitcnt lgkmcnt(0)
	global_store_dwordx4 v[56:57], v[48:51], off nt
	ds_read_b128 v[48:51], v138 offset:4608
	v_add_u32_e32 v56, 0x28000, v128
	v_mov_b32_e32 v57, v129
	v_add_co_u32_e32 v56, vcc, v52, v56
	v_addc_co_u32_e32 v57, vcc, v53, v57, vcc
	v_cvt_pk_bf16_f32 v45, v46, v47
	s_waitcnt lgkmcnt(0)
	global_store_dwordx4 v[56:57], v[48:51], off nt
	ds_read_b128 v[48:51], v138 offset:5760
	v_add_u32_e32 v56, 0x32000, v128
	v_mov_b32_e32 v57, v129
	v_add_co_u32_e32 v56, vcc, v52, v56
	v_addc_co_u32_e32 v57, vcc, v53, v57, vcc
	v_cvt_pk_bf16_f32 v40, v40, v41
	s_waitcnt lgkmcnt(0)
	global_store_dwordx4 v[56:57], v[48:51], off nt
	ds_read_b128 v[48:51], v138 offset:6912
	v_add_u32_e32 v56, 0x3c000, v128
	v_mov_b32_e32 v57, v129
	v_add_co_u32_e32 v56, vcc, v52, v56
	v_addc_co_u32_e32 v57, vcc, v53, v57, vcc
	v_add_u32_e32 v128, 0x46000, v128
	s_waitcnt lgkmcnt(0)
	global_store_dwordx4 v[56:57], v[48:51], off nt
	ds_read_b128 v[48:51], v138 offset:8064
	v_add_co_u32_e32 v52, vcc, v52, v128
	v_addc_co_u32_e32 v53, vcc, v53, v129, vcc
	v_cvt_pk_bf16_f32 v41, v42, v43
	v_cvt_pk_bf16_f32 v36, v36, v37
	v_cvt_pk_bf16_f32 v37, v38, v39
	s_waitcnt lgkmcnt(0)
	global_store_dwordx4 v[52:53], v[48:51], off nt
	ds_write_b64 v134, v[0:1] offset:4704
	v_cvt_pk_bf16_f32 v0, v112, v113
	v_cvt_pk_bf16_f32 v1, v114, v115
	ds_write_b64 v134, v[0:1] offset:6912
	v_cvt_pk_bf16_f32 v0, v116, v117
	v_cvt_pk_bf16_f32 v1, v118, v119
	ds_write_b64 v134, v[0:1] offset:6944
	v_cvt_pk_bf16_f32 v0, v120, v121
	v_cvt_pk_bf16_f32 v1, v122, v123
	v_cvt_pk_bf16_f32 v32, v32, v33
	v_cvt_pk_bf16_f32 v33, v34, v35
	v_cvt_pk_bf16_f32 v28, v28, v29
	v_cvt_pk_bf16_f32 v29, v30, v31
	v_cvt_pk_bf16_f32 v24, v24, v25
	v_cvt_pk_bf16_f32 v25, v26, v27
	v_cvt_pk_bf16_f32 v20, v20, v21
	v_cvt_pk_bf16_f32 v21, v22, v23
	v_cvt_pk_bf16_f32 v16, v16, v17
	v_cvt_pk_bf16_f32 v17, v18, v19
	v_cvt_pk_bf16_f32 v12, v12, v13
	v_cvt_pk_bf16_f32 v13, v14, v15
	v_cvt_pk_bf16_f32 v8, v8, v9
	v_cvt_pk_bf16_f32 v9, v10, v11
	v_cvt_pk_bf16_f32 v4, v4, v5
	v_cvt_pk_bf16_f32 v5, v6, v7
	ds_write_b64 v134, v[0:1] offset:6976
	v_cvt_pk_bf16_f32 v0, v124, v125
	v_cvt_pk_bf16_f32 v1, v126, v127
	ds_write_b64 v134, v[44:45]
	ds_write_b64 v134, v[40:41] offset:32
	ds_write_b64 v134, v[36:37] offset:64
	ds_write_b64 v134, v[32:33] offset:96
	ds_write_b64 v134, v[28:29] offset:2304
	ds_write_b64 v134, v[24:25] offset:2336
	ds_write_b64 v134, v[20:21] offset:2368
	ds_write_b64 v134, v[16:17] offset:2400
	ds_write_b64 v134, v[12:13] offset:4608
	ds_write_b64 v134, v[8:9] offset:4640
	ds_write_b64 v134, v[4:5] offset:4672
	ds_write_b64 v134, v[0:1] offset:7008
	ds_read_b128 v[0:3], v138
	v_add_co_u32_e32 v4, vcc, s30, v54
	s_add_i32 s42, s42, s40
	s_nop 0
	v_addc_co_u32_e32 v5, vcc, 0, v55, vcc
	s_waitcnt lgkmcnt(0)
	global_store_dwordx4 v[4:5], v[0:3], off nt
	ds_read_b128 v[0:3], v138 offset:1152
	v_add_co_u32_e32 v4, vcc, s31, v54
	s_cmpk_gt_i32 s42, 0x4ff
	s_nop 0
	v_addc_co_u32_e32 v5, vcc, 0, v55, vcc
	s_waitcnt lgkmcnt(0)
	global_store_dwordx4 v[4:5], v[0:3], off nt
	ds_read_b128 v[0:3], v138 offset:2304
	v_add_co_u32_e32 v4, vcc, s34, v54
	s_nop 1
	v_addc_co_u32_e32 v5, vcc, 0, v55, vcc
	s_waitcnt lgkmcnt(0)
	global_store_dwordx4 v[4:5], v[0:3], off nt
	ds_read_b128 v[0:3], v138 offset:3456
	v_add_co_u32_e32 v4, vcc, s35, v54
	s_nop 1
	v_addc_co_u32_e32 v5, vcc, 0, v55, vcc
	s_waitcnt lgkmcnt(0)
	global_store_dwordx4 v[4:5], v[0:3], off nt
	ds_read_b128 v[0:3], v138 offset:4608
	v_add_co_u32_e32 v4, vcc, s38, v54
	s_nop 1
	v_addc_co_u32_e32 v5, vcc, 0, v55, vcc
	s_waitcnt lgkmcnt(0)
	global_store_dwordx4 v[4:5], v[0:3], off nt
	ds_read_b128 v[0:3], v138 offset:5760
	v_add_co_u32_e32 v4, vcc, s39, v54
	s_nop 1
	v_addc_co_u32_e32 v5, vcc, 0, v55, vcc
	s_waitcnt lgkmcnt(0)
	global_store_dwordx4 v[4:5], v[0:3], off nt
	ds_read_b128 v[0:3], v138 offset:6912
	v_add_co_u32_e32 v4, vcc, 0x8c000, v54
	s_nop 1
	v_addc_co_u32_e32 v5, vcc, 0, v55, vcc
	s_waitcnt lgkmcnt(0)
	global_store_dwordx4 v[4:5], v[0:3], off nt
	ds_read_b128 v[0:3], v138 offset:8064
	v_add_co_u32_e32 v4, vcc, 0x96000, v54
	s_nop 1
	v_addc_co_u32_e32 v5, vcc, 0, v55, vcc
	s_waitcnt lgkmcnt(0)
	global_store_dwordx4 v[4:5], v[0:3], off nt
	s_cbranch_scc0 .LBB0_1039

.LBB0_1089:
	v_cmp_gt_i32_e32 vcc, s18, v148
	s_and_saveexec_b64 s[16:17], vcc
	s_cbranch_execz .LBB0_1088
	v_mul_hi_i32 v0, v148, s19
	v_lshrrev_b32_e32 v1, 31, v0
	v_ashrrev_i32_e32 v0, 6, v0
	v_add_u32_e32 v5, v0, v1
	v_mov_b32_e32 v1, s21
	ds_read_b64 v[44:45], v1
	v_mul_lo_u32 v0, v5, s20
	v_sub_u32_e32 v0, v148, v0
	v_and_b32_e32 v6, 0x1ff, v5
	v_lshlrev_b32_e32 v138, 3, v5
	v_lshlrev_b32_e32 v4, 3, v0
	v_cmp_ne_u32_e64 s[4:5], 0, v6
	s_waitcnt lgkmcnt(0)
	v_lshl_add_u64 v[50:51], v[44:45], 0, s[12:13]
	v_ashrrev_i32_e32 v5, 31, v4
	v_subbrev_co_u32_e64 v6, vcc, 0, v138, s[4:5]
	v_mad_i64_i32 v[6:7], s[6:7], v6, s22, v[50:51]
	v_lshlrev_b64 v[56:57], 1, v[4:5]
	v_mov_b32_e32 v0, s23
	v_add_co_u32_e32 v6, vcc, v6, v56
	v_addc_co_u32_e32 v7, vcc, v7, v57, vcc
	ds_read_b128 v[0:3], v0
	flat_load_dwordx4 v[32:35], v[6:7] offset:2560 nt
	flat_load_dwordx4 v[36:39], v[6:7] nt
	v_add_u32_e32 v6, 8, v138
	v_and_b32_e32 v7, 0xff8, v6
	v_cmp_eq_u32_e32 vcc, 0, v7
	v_add_u32_e32 v128, 0x600, v4
	v_or_b32_e32 v162, 1, v138
	v_cndmask_b32_e32 v10, v6, v138, vcc
	v_mad_i64_i32 v[10:11], s[6:7], v10, s22, v[50:51]
	v_lshl_add_u64 v[10:11], v[10:11], 0, v[56:57]
	flat_load_dwordx4 v[46:49], v[10:11] nt
	flat_load_dwordx4 v[40:43], v[10:11] offset:2560 nt
	v_or_b32_e32 v161, 2, v138
	v_lshlrev_b64 v[12:13], 2, v[128:129]
	v_mad_i64_i32 v[6:7], s[6:7], v138, s22, v[50:51]
	v_mad_i64_i32 v[8:9], s[6:7], v162, s22, v[50:51]
	v_mad_i64_i32 v[10:11], s[6:7], v161, s22, v[50:51]
	s_waitcnt lgkmcnt(0)
	v_lshl_add_u64 v[54:55], v[0:1], 0, v[12:13]
	v_mov_b32_e32 v5, v129
	v_add_u32_e32 v4, 0x1100, v4
	v_add_co_u32_e64 v62, s[6:7], s24, v54
	v_lshlrev_b64 v[4:5], 2, v[4:5]
	v_lshl_add_u64 v[14:15], v[6:7], 0, v[56:57]
	v_addc_co_u32_e64 v63, s[6:7], 0, v55, s[6:7]
	v_lshl_add_u64 v[16:17], v[8:9], 0, v[56:57]
	v_lshl_add_u64 v[58:59], v[0:1], 0, v[4:5]
	v_lshl_add_u64 v[60:61], v[2:3], 0, v[12:13]
	v_lshl_add_u64 v[136:137], v[2:3], 0, v[4:5]
	flat_load_dwordx4 v[116:119], v[14:15] nt
	flat_load_dwordx4 v[112:115], v[16:17] nt
	flat_load_dwordx4 v[0:3], v[54:55]
	flat_load_dwordx4 v[4:7], v[62:63] offset:2048
	v_add_co_u32_e64 v130, s[6:7], s25, v54
	v_lshl_add_u64 v[52:53], v[10:11], 0, v[56:57]
	s_nop 0
	v_addc_co_u32_e64 v131, s[6:7], 0, v55, s[6:7]
	flat_load_dwordx4 v[8:11], v[130:131]
	flat_load_dwordx4 v[20:23], v[60:61]
	flat_load_dwordx4 v[124:127], v[14:15] offset:2560 nt
	flat_load_dwordx4 v[120:123], v[16:17] offset:2560 nt
	v_add_co_u32_e64 v134, s[6:7], s24, v58
	v_or_b32_e32 v160, 3, v138
	s_nop 0
	v_addc_co_u32_e64 v135, s[6:7], 0, v59, s[6:7]
	flat_load_dwordx4 v[28:31], v[134:135] offset:2048
	flat_load_dwordx4 v[24:27], v[58:59]
	v_add_co_u32_e64 v140, s[6:7], s25, v58
	v_or_b32_e32 v159, 4, v138
	s_nop 0
	v_addc_co_u32_e64 v141, s[6:7], 0, v59, s[6:7]
	flat_load_dwordx4 v[12:15], v[136:137]
	flat_load_dwordx4 v[16:19], v[140:141]
	flat_load_dwordx4 v[108:111], v[52:53] nt
	flat_load_dwordx4 v[104:107], v[52:53] offset:2560 nt
	v_or_b32_e32 v158, 5, v138
	v_or_b32_e32 v153, 6, v138
	v_or_b32_e32 v128, 7, v138
	v_lshl_add_u64 v[44:45], v[44:45], 0, v[56:57]
	s_waitcnt vmcnt(0)
	v_cndmask_b32_e64 v139, 0, v35, s[4:5]
	v_cndmask_b32_e64 v163, 0, v34, s[4:5]
	v_cndmask_b32_e64 v168, 0, v33, s[4:5]
	v_cndmask_b32_e64 v146, 0, v32, s[4:5]
	v_cndmask_b32_e64 v176, 0, v39, s[4:5]
	v_cndmask_b32_e64 v170, 0, v38, s[4:5]
	v_cndmask_b32_e64 v166, 0, v37, s[4:5]
	v_cndmask_b32_e64 v142, 0, v36, s[4:5]
	v_mad_i64_i32 v[32:33], s[4:5], v160, s22, v[50:51]
	v_lshl_add_u64 v[32:33], v[32:33], 0, v[56:57]
	flat_load_dwordx4 v[100:103], v[32:33] nt
	flat_load_dwordx4 v[96:99], v[32:33] offset:2560 nt
	v_mad_i64_i32 v[32:33], s[4:5], v159, s22, v[50:51]
	v_lshl_add_u64 v[32:33], v[32:33], 0, v[56:57]
	flat_load_dwordx4 v[92:95], v[32:33] nt
	flat_load_dwordx4 v[88:91], v[32:33] offset:2560 nt
	v_mad_i64_i32 v[32:33], s[4:5], v158, s22, v[50:51]
	v_lshl_add_u64 v[32:33], v[32:33], 0, v[56:57]
	flat_load_dwordx4 v[84:87], v[32:33] nt
	flat_load_dwordx4 v[80:83], v[32:33] offset:2560 nt
	v_mad_i64_i32 v[32:33], s[4:5], v153, s22, v[50:51]
	v_lshl_add_u64 v[32:33], v[32:33], 0, v[56:57]
	flat_load_dwordx4 v[76:79], v[32:33] nt
	flat_load_dwordx4 v[72:75], v[32:33] offset:2560 nt
	v_mad_i64_i32 v[32:33], s[4:5], v128, s22, v[50:51]
	v_lshl_add_u64 v[32:33], v[32:33], 0, v[56:57]
	flat_load_dwordx4 v[68:71], v[32:33] nt
	flat_load_dwordx4 v[64:67], v[32:33] offset:2560 nt
	flat_load_dwordx4 v[36:39], v[62:63] offset:2064
	s_nop 0
	flat_load_dwordx4 v[32:35], v[54:55] offset:16
	v_cndmask_b32_e64 v149, v43, 0, vcc
	v_cndmask_b32_e64 v150, v42, 0, vcc
	v_cndmask_b32_e64 v151, v41, 0, vcc
	v_cndmask_b32_e64 v152, v40, 0, vcc
	flat_load_dwordx4 v[40:43], v[130:131] offset:16
	flat_load_dwordx4 v[52:55], v[60:61] offset:16
	s_waitcnt lgkmcnt(0)
	v_lshlrev_b32_e32 v144, 16, v116
	v_and_b32_e32 v145, 0xffff0000, v116
	v_cndmask_b32_e64 v156, v47, 0, vcc
	v_cndmask_b32_e64 v157, v46, 0, vcc
	v_lshl_add_u64 v[130:131], v[44:45], 0, s[14:15]
	v_lshlrev_b32_e32 v44, 16, v142
	v_and_b32_e32 v45, 0xffff0000, v142
	v_pk_mul_f32 v[46:47], v[4:5], v[144:145]
	flat_load_dwordx4 v[60:63], v[134:135] offset:2064
	s_nop 0
	flat_load_dwordx4 v[56:59], v[58:59] offset:16
	v_pk_fma_f32 v[44:45], v[0:1], v[44:45], v[46:47]
	v_lshlrev_b32_e32 v134, 16, v112
	v_and_b32_e32 v135, 0xffff0000, v112
	v_pk_fma_f32 v[44:45], v[8:9], v[134:135], v[44:45]
	v_cndmask_b32_e64 v154, v49, 0, vcc
	v_cndmask_b32_e64 v155, v48, 0, vcc
	v_pk_add_f32 v[142:143], v[44:45], v[20:21]
	flat_load_dwordx4 v[44:47], v[140:141] offset:16
	flat_load_dwordx4 v[48:51], v[136:137] offset:16
	v_mul_f32_e32 v112, 0xbfb8aa3b, v142
	v_exp_f32_e32 v112, v112
	v_mul_f32_e32 v116, 0xbfb8aa3b, v143
	v_exp_f32_e32 v116, v116
	v_lshlrev_b32_e32 v136, 16, v146
	v_add_f32_e32 v112, 1.0, v112
	v_and_b32_e32 v137, 0xffff0000, v146
	v_rcp_f32_e32 v146, v112
	v_add_f32_e32 v112, 1.0, v116
	v_lshlrev_b32_e32 v164, 16, v124
	v_and_b32_e32 v165, 0xffff0000, v124
	v_rcp_f32_e32 v147, v112
	v_pk_mul_f32 v[140:141], v[28:29], v[164:165]
	v_and_b32_e32 v167, 0xffff0000, v117
	v_pk_fma_f32 v[140:141], v[24:25], v[136:137], v[140:141]
	v_lshlrev_b32_e32 v136, 16, v120
	v_and_b32_e32 v137, 0xffff0000, v120
	v_pk_fma_f32 v[140:141], v[16:17], v[136:137], v[140:141]
	v_pk_mul_f32 v[142:143], v[142:143], v[146:147]
	v_pk_add_f32 v[140:141], v[140:141], v[12:13]
	v_lshlrev_b32_e32 v112, 16, v113
	v_pk_mul_f32 v[140:141], v[140:141], v[142:143]
	v_lshlrev_b32_e32 v142, 16, v166
	v_and_b32_e32 v143, 0xffff0000, v166
	v_lshlrev_b32_e32 v166, 16, v117
	v_pk_mul_f32 v[116:117], v[6:7], v[166:167]
	v_and_b32_e32 v113, 0xffff0000, v113
	v_pk_fma_f32 v[116:117], v[2:3], v[142:143], v[116:117]
	v_lshlrev_b32_e32 v142, 16, v168
	v_pk_fma_f32 v[116:117], v[10:11], v[112:113], v[116:117]
	v_and_b32_e32 v143, 0xffff0000, v168
	v_pk_add_f32 v[116:117], v[116:117], v[22:23]
	v_lshlrev_b32_e32 v168, 16, v125
	v_and_b32_e32 v169, 0xffff0000, v125
	v_mul_f32_e32 v120, 0xbfb8aa3b, v116
	v_cvt_pk_bf16_f32 v140, v140, v141
	v_pk_mul_f32 v[124:125], v[30:31], v[168:169]
	v_exp_f32_e32 v141, v120
	v_mul_f32_e32 v120, 0xbfb8aa3b, v117
	v_pk_fma_f32 v[124:125], v[26:27], v[142:143], v[124:125]
	v_exp_f32_e32 v143, v120
	v_add_f32_e32 v141, 1.0, v141
	v_rcp_f32_e32 v142, v141
	v_lshlrev_b32_e32 v120, 16, v121
	v_add_f32_e32 v141, 1.0, v143
	v_rcp_f32_e32 v143, v141
	v_and_b32_e32 v121, 0xffff0000, v121
	v_pk_fma_f32 v[124:125], v[18:19], v[120:121], v[124:125]
	v_and_b32_e32 v171, 0xffff0000, v118
	v_pk_add_f32 v[124:125], v[124:125], v[14:15]
	v_pk_mul_f32 v[116:117], v[116:117], v[142:143]
	v_lshlrev_b32_e32 v172, 16, v126
	v_pk_mul_f32 v[116:117], v[124:125], v[116:117]
	v_and_b32_e32 v173, 0xffff0000, v126
	v_cvt_pk_bf16_f32 v141, v116, v117
	v_lshlrev_b32_e32 v116, 16, v170
	v_and_b32_e32 v117, 0xffff0000, v170
	v_lshlrev_b32_e32 v170, 16, v118
	s_waitcnt vmcnt(0)
	v_pk_mul_f32 v[124:125], v[36:37], v[170:171]
	v_and_b32_e32 v177, 0xffff0000, v127
	v_pk_fma_f32 v[124:125], v[32:33], v[116:117], v[124:125]
	v_lshlrev_b32_e32 v116, 16, v114
	v_and_b32_e32 v117, 0xffff0000, v114
	v_pk_fma_f32 v[124:125], v[40:41], v[116:117], v[124:125]
	s_waitcnt lgkmcnt(0)
	v_pk_mul_f32 v[146:147], v[60:61], v[172:173]
	v_pk_add_f32 v[142:143], v[124:125], v[52:53]
	v_lshlrev_b32_e32 v124, 16, v163
	v_mul_f32_e32 v114, 0xbfb8aa3b, v142
	v_exp_f32_e32 v114, v114
	v_mul_f32_e32 v118, 0xbfb8aa3b, v143
	v_exp_f32_e32 v118, v118
	v_and_b32_e32 v125, 0xffff0000, v163
	v_add_f32_e32 v114, 1.0, v114
	v_rcp_f32_e32 v174, v114
	v_add_f32_e32 v114, 1.0, v118
	v_rcp_f32_e32 v175, v114
	v_pk_fma_f32 v[146:147], v[56:57], v[124:125], v[146:147]
	v_lshlrev_b32_e32 v124, 16, v122
	v_and_b32_e32 v125, 0xffff0000, v122
	v_pk_fma_f32 v[146:147], v[44:45], v[124:125], v[146:147]
	v_pk_mul_f32 v[142:143], v[142:143], v[174:175]
	v_pk_add_f32 v[146:147], v[146:147], v[48:49]
	v_lshlrev_b32_e32 v174, 16, v119
	v_and_b32_e32 v175, 0xffff0000, v119
	v_pk_mul_f32 v[142:143], v[146:147], v[142:143]
	v_lshlrev_b32_e32 v146, 16, v176
	v_and_b32_e32 v147, 0xffff0000, v176
	v_pk_mul_f32 v[118:119], v[38:39], v[174:175]
	v_lshlrev_b32_e32 v114, 16, v115
	v_pk_fma_f32 v[118:119], v[34:35], v[146:147], v[118:119]
	v_and_b32_e32 v115, 0xffff0000, v115
	v_pk_fma_f32 v[118:119], v[42:43], v[114:115], v[118:119]
	v_lshlrev_b32_e32 v146, 16, v139
	v_pk_add_f32 v[118:119], v[118:119], v[54:55]
	v_and_b32_e32 v147, 0xffff0000, v139
	v_mul_f32_e32 v122, 0xbfb8aa3b, v118
	v_exp_f32_e32 v122, v122
	v_mul_f32_e32 v139, 0xbfb8aa3b, v119
	v_exp_f32_e32 v139, v139
	v_lshlrev_b32_e32 v176, 16, v127
	v_add_f32_e32 v122, 1.0, v122
	v_rcp_f32_e32 v178, v122
	v_add_f32_e32 v122, 1.0, v139
	v_rcp_f32_e32 v179, v122
	v_pk_mul_f32 v[126:127], v[62:63], v[176:177]
	v_cvt_pk_bf16_f32 v142, v142, v143
	v_pk_fma_f32 v[126:127], v[58:59], v[146:147], v[126:127]
	v_lshlrev_b32_e32 v146, 16, v123
	v_and_b32_e32 v147, 0xffff0000, v123
	v_pk_fma_f32 v[122:123], v[46:47], v[146:147], v[126:127]
	v_pk_mul_f32 v[118:119], v[118:119], v[178:179]
	v_pk_add_f32 v[122:123], v[122:123], v[50:51]
	v_lshlrev_b32_e32 v126, 16, v108
	v_pk_mul_f32 v[118:119], v[122:123], v[118:119]
	v_and_b32_e32 v127, 0xffff0000, v108
	v_cvt_pk_bf16_f32 v143, v118, v119
	v_mad_i64_i32 v[118:119], s[4:5], v138, s26, v[130:131]
	flat_store_dwordx4 v[118:119], v[140:143]
	v_pk_mul_f32 v[118:119], v[4:5], v[134:135]
	v_pk_mul_f32 v[122:123], v[28:29], v[136:137]
	v_pk_fma_f32 v[118:119], v[0:1], v[144:145], v[118:119]
	v_pk_fma_f32 v[122:123], v[24:25], v[164:165], v[122:123]
	v_pk_fma_f32 v[118:119], v[8:9], v[126:127], v[118:119]
	v_lshlrev_b32_e32 v144, 16, v104
	v_pk_add_f32 v[118:119], v[118:119], v[20:21]
	v_and_b32_e32 v145, 0xffff0000, v104
	v_mul_f32_e32 v108, 0xbfb8aa3b, v118
	v_exp_f32_e32 v108, v108
	v_mul_f32_e32 v138, 0xbfb8aa3b, v119
	v_exp_f32_e32 v139, v138
	v_pk_fma_f32 v[122:123], v[16:17], v[144:145], v[122:123]
	v_add_f32_e32 v108, 1.0, v108
	v_rcp_f32_e32 v138, v108
	v_add_f32_e32 v108, 1.0, v139
	v_rcp_f32_e32 v139, v108
	v_pk_add_f32 v[122:123], v[122:123], v[12:13]
	v_lshlrev_b32_e32 v142, 16, v105
	v_and_b32_e32 v143, 0xffff0000, v105
	v_pk_mul_f32 v[118:119], v[118:119], v[138:139]
	s_nop 0
	v_pk_mul_f32 v[118:119], v[122:123], v[118:119]
	v_lshlrev_b32_e32 v122, 16, v109
	v_cvt_pk_bf16_f32 v104, v118, v119
	v_pk_mul_f32 v[118:119], v[6:7], v[112:113]
	v_and_b32_e32 v123, 0xffff0000, v109
	v_pk_fma_f32 v[118:119], v[2:3], v[166:167], v[118:119]
	s_nop 0
	v_pk_fma_f32 v[108:109], v[10:11], v[122:123], v[118:119]
	v_pk_mul_f32 v[118:119], v[30:31], v[120:121]
	v_pk_add_f32 v[108:109], v[108:109], v[22:23]
	v_pk_fma_f32 v[118:119], v[26:27], v[168:169], v[118:119]
	v_mul_f32_e32 v138, 0xbfb8aa3b, v108
	v_mul_f32_e32 v139, 0xbfb8aa3b, v109
	v_exp_f32_e32 v138, v138
	v_exp_f32_e32 v139, v139
	v_pk_fma_f32 v[118:119], v[18:19], v[142:143], v[118:119]
	v_add_f32_e32 v138, 1.0, v138
	v_add_f32_e32 v139, 1.0, v139
	v_rcp_f32_e32 v138, v138
	v_rcp_f32_e32 v139, v139
	v_pk_add_f32 v[118:119], v[118:119], v[14:15]
	v_pk_mul_f32 v[108:109], v[108:109], v[138:139]
	s_nop 0
	v_pk_mul_f32 v[108:109], v[118:119], v[108:109]
	v_lshlrev_b32_e32 v118, 16, v110
	v_cvt_pk_bf16_f32 v105, v108, v109
	v_pk_mul_f32 v[108:109], v[36:37], v[116:117]
	v_and_b32_e32 v119, 0xffff0000, v110
	v_pk_fma_f32 v[108:109], v[32:33], v[170:171], v[108:109]
	v_pk_mul_f32 v[138:139], v[60:61], v[124:125]
	v_pk_fma_f32 v[108:109], v[40:41], v[118:119], v[108:109]
	v_pk_fma_f32 v[138:139], v[56:57], v[172:173], v[138:139]
	v_pk_add_f32 v[108:109], v[108:109], v[52:53]
	s_nop 0
	v_mul_f32_e32 v110, 0xbfb8aa3b, v108
	v_exp_f32_e32 v110, v110
	v_mul_f32_e32 v140, 0xbfb8aa3b, v109
	v_exp_f32_e32 v141, v140
	v_lshlrev_b32_e32 v140, 16, v106
	v_add_f32_e32 v110, 1.0, v110
	v_rcp_f32_e32 v164, v110
	v_add_f32_e32 v110, 1.0, v141
	v_rcp_f32_e32 v165, v110
	v_and_b32_e32 v141, 0xffff0000, v106
	v_pk_fma_f32 v[138:139], v[44:45], v[140:141], v[138:139]
	v_lshlrev_b32_e32 v110, 16, v111
	v_pk_add_f32 v[138:139], v[138:139], v[48:49]
	v_pk_mul_f32 v[108:109], v[108:109], v[164:165]
	v_and_b32_e32 v111, 0xffff0000, v111
	v_pk_mul_f32 v[108:109], v[138:139], v[108:109]
	v_pk_mul_f32 v[138:139], v[62:63], v[146:147]
	v_cvt_pk_bf16_f32 v106, v108, v109
	v_pk_mul_f32 v[108:109], v[38:39], v[114:115]
	v_pk_fma_f32 v[164:165], v[58:59], v[176:177], v[138:139]
	v_pk_fma_f32 v[108:109], v[34:35], v[174:175], v[108:109]
	s_nop 0
	v_pk_fma_f32 v[108:109], v[42:43], v[110:111], v[108:109]
	s_nop 0
	v_pk_add_f32 v[108:109], v[108:109], v[54:55]
	s_nop 0
	v_mul_f32_e32 v138, 0xbfb8aa3b, v108
	v_exp_f32_e32 v139, v138
	v_mul_f32_e32 v138, 0xbfb8aa3b, v109
	v_exp_f32_e32 v163, v138
	v_lshlrev_b32_e32 v138, 16, v107
	v_add_f32_e32 v139, 1.0, v139
	v_rcp_f32_e32 v166, v139
	v_add_f32_e32 v139, 1.0, v163
	v_rcp_f32_e32 v167, v139
	v_and_b32_e32 v139, 0xffff0000, v107
	v_pk_fma_f32 v[164:165], v[46:47], v[138:139], v[164:165]
	v_pk_mul_f32 v[108:109], v[108:109], v[166:167]
	v_pk_add_f32 v[164:165], v[164:165], v[50:51]
	s_nop 0
	v_pk_mul_f32 v[108:109], v[164:165], v[108:109]
	s_nop 0
	v_cvt_pk_bf16_f32 v107, v108, v109
	v_mad_i64_i32 v[108:109], s[4:5], v162, s26, v[130:131]
	flat_store_dwordx4 v[108:109], v[104:107]
	v_lshlrev_b32_e32 v108, 16, v100
	v_and_b32_e32 v109, 0xffff0000, v100
	v_pk_mul_f32 v[104:105], v[4:5], v[126:127]
	v_pk_mul_f32 v[106:107], v[28:29], v[144:145]
	v_pk_fma_f32 v[104:105], v[0:1], v[134:135], v[104:105]
	v_pk_fma_f32 v[106:107], v[24:25], v[136:137], v[106:107]
	v_pk_fma_f32 v[104:105], v[8:9], v[108:109], v[104:105]
	v_lshlrev_b32_e32 v136, 16, v96
	v_pk_add_f32 v[104:105], v[104:105], v[20:21]
	v_and_b32_e32 v137, 0xffff0000, v96
	v_mul_f32_e32 v100, 0xbfb8aa3b, v104
	v_exp_f32_e32 v100, v100
	v_mul_f32_e32 v134, 0xbfb8aa3b, v105
	v_exp_f32_e32 v135, v134
	v_pk_fma_f32 v[106:107], v[16:17], v[136:137], v[106:107]
	v_add_f32_e32 v100, 1.0, v100
	v_rcp_f32_e32 v134, v100
	v_add_f32_e32 v100, 1.0, v135
	v_rcp_f32_e32 v135, v100
	v_pk_add_f32 v[106:107], v[106:107], v[12:13]
	v_pk_mul_f32 v[104:105], v[104:105], v[134:135]
	s_nop 0
	v_pk_mul_f32 v[104:105], v[106:107], v[104:105]
	v_lshlrev_b32_e32 v106, 16, v101
	v_cvt_pk_bf16_f32 v96, v104, v105
	v_pk_mul_f32 v[104:105], v[6:7], v[122:123]
	v_and_b32_e32 v107, 0xffff0000, v101
	v_pk_fma_f32 v[104:105], v[2:3], v[112:113], v[104:105]
	v_lshlrev_b32_e32 v134, 16, v97
	v_pk_fma_f32 v[100:101], v[10:11], v[106:107], v[104:105]
	v_pk_mul_f32 v[104:105], v[30:31], v[142:143]
	v_pk_add_f32 v[100:101], v[100:101], v[22:23]
	v_pk_fma_f32 v[104:105], v[26:27], v[120:121], v[104:105]
	v_mul_f32_e32 v112, 0xbfb8aa3b, v100
	v_mul_f32_e32 v113, 0xbfb8aa3b, v101
	v_exp_f32_e32 v112, v112
	v_exp_f32_e32 v113, v113
	v_and_b32_e32 v135, 0xffff0000, v97
	v_pk_fma_f32 v[104:105], v[18:19], v[134:135], v[104:105]
	v_add_f32_e32 v112, 1.0, v112
	v_add_f32_e32 v113, 1.0, v113
	v_rcp_f32_e32 v112, v112
	v_rcp_f32_e32 v113, v113
	v_pk_add_f32 v[104:105], v[104:105], v[14:15]
	v_lshlrev_b32_e32 v120, 16, v99
	v_and_b32_e32 v121, 0xffff0000, v99
	v_pk_mul_f32 v[100:101], v[100:101], v[112:113]
	v_pk_mul_f32 v[112:113], v[60:61], v[140:141]
	v_pk_mul_f32 v[100:101], v[104:105], v[100:101]
	v_lshlrev_b32_e32 v104, 16, v102
	v_cvt_pk_bf16_f32 v97, v100, v101
	v_pk_mul_f32 v[100:101], v[36:37], v[118:119]
	v_and_b32_e32 v105, 0xffff0000, v102
	v_pk_fma_f32 v[100:101], v[32:33], v[116:117], v[100:101]
	v_pk_fma_f32 v[112:113], v[56:57], v[124:125], v[112:113]
	v_pk_fma_f32 v[100:101], v[40:41], v[104:105], v[100:101]
	v_lshlrev_b32_e32 v124, 16, v98
	v_pk_add_f32 v[100:101], v[100:101], v[52:53]
	v_and_b32_e32 v125, 0xffff0000, v98
	v_mul_f32_e32 v102, 0xbfb8aa3b, v100
	v_exp_f32_e32 v102, v102
	v_mul_f32_e32 v116, 0xbfb8aa3b, v101
	v_exp_f32_e32 v117, v116
	v_pk_fma_f32 v[112:113], v[44:45], v[124:125], v[112:113]
	v_add_f32_e32 v102, 1.0, v102
	v_rcp_f32_e32 v116, v102
	v_add_f32_e32 v102, 1.0, v117
	v_rcp_f32_e32 v117, v102
	v_pk_add_f32 v[112:113], v[112:113], v[48:49]
	v_lshlrev_b32_e32 v102, 16, v103
	v_and_b32_e32 v103, 0xffff0000, v103
	v_pk_mul_f32 v[100:101], v[100:101], v[116:117]
	v_lshlrev_b32_e32 v116, 16, v88
	v_pk_mul_f32 v[100:101], v[112:113], v[100:101]
	v_pk_mul_f32 v[112:113], v[62:63], v[138:139]
	v_cvt_pk_bf16_f32 v98, v100, v101
	v_pk_mul_f32 v[100:101], v[38:39], v[110:111]
	v_pk_fma_f32 v[112:113], v[58:59], v[146:147], v[112:113]
	v_pk_fma_f32 v[100:101], v[34:35], v[114:115], v[100:101]
	v_pk_fma_f32 v[112:113], v[46:47], v[120:121], v[112:113]
	v_pk_fma_f32 v[100:101], v[42:43], v[102:103], v[100:101]
	v_pk_add_f32 v[112:113], v[112:113], v[50:51]
	v_pk_add_f32 v[100:101], v[100:101], v[54:55]
	v_and_b32_e32 v117, 0xffff0000, v88
	v_mul_f32_e32 v114, 0xbfb8aa3b, v100
	v_mul_f32_e32 v115, 0xbfb8aa3b, v101
	v_exp_f32_e32 v114, v114
	v_exp_f32_e32 v115, v115
	v_add_f32_e32 v114, 1.0, v114
	v_add_f32_e32 v115, 1.0, v115
	v_rcp_f32_e32 v114, v114
	v_rcp_f32_e32 v115, v115
	s_nop 0
	v_pk_mul_f32 v[100:101], v[100:101], v[114:115]
	s_nop 0
	v_pk_mul_f32 v[100:101], v[112:113], v[100:101]
	v_lshlrev_b32_e32 v114, 16, v89
	v_cvt_pk_bf16_f32 v99, v100, v101
	v_mad_i64_i32 v[100:101], s[4:5], v161, s26, v[130:131]
	flat_store_dwordx4 v[100:101], v[96:99]
	v_lshlrev_b32_e32 v100, 16, v92
	v_and_b32_e32 v101, 0xffff0000, v92
	v_pk_mul_f32 v[96:97], v[4:5], v[108:109]
	v_pk_mul_f32 v[98:99], v[28:29], v[136:137]
	v_pk_fma_f32 v[96:97], v[0:1], v[126:127], v[96:97]
	v_pk_fma_f32 v[98:99], v[24:25], v[144:145], v[98:99]
	v_pk_fma_f32 v[96:97], v[8:9], v[100:101], v[96:97]
	v_pk_fma_f32 v[98:99], v[16:17], v[116:117], v[98:99]
	v_pk_add_f32 v[96:97], v[96:97], v[20:21]
	v_pk_add_f32 v[98:99], v[98:99], v[12:13]
	v_mul_f32_e32 v92, 0xbfb8aa3b, v96
	v_exp_f32_e32 v92, v92
	v_mul_f32_e32 v112, 0xbfb8aa3b, v97
	v_exp_f32_e32 v113, v112
	v_and_b32_e32 v115, 0xffff0000, v89
	v_add_f32_e32 v92, 1.0, v92
	v_rcp_f32_e32 v112, v92
	v_add_f32_e32 v92, 1.0, v113
	v_rcp_f32_e32 v113, v92
	s_nop 0
	v_pk_mul_f32 v[96:97], v[96:97], v[112:113]
	s_nop 0
	v_pk_mul_f32 v[96:97], v[98:99], v[96:97]
	v_lshlrev_b32_e32 v98, 16, v93
	v_cvt_pk_bf16_f32 v88, v96, v97
	v_pk_mul_f32 v[96:97], v[6:7], v[106:107]
	v_and_b32_e32 v99, 0xffff0000, v93
	v_pk_fma_f32 v[96:97], v[2:3], v[122:123], v[96:97]
	s_nop 0
	v_pk_fma_f32 v[92:93], v[10:11], v[98:99], v[96:97]
	v_pk_mul_f32 v[96:97], v[30:31], v[134:135]
	v_pk_add_f32 v[92:93], v[92:93], v[22:23]
	v_pk_fma_f32 v[96:97], v[26:27], v[142:143], v[96:97]
	v_mul_f32_e32 v112, 0xbfb8aa3b, v92
	v_mul_f32_e32 v113, 0xbfb8aa3b, v93
	v_exp_f32_e32 v112, v112
	v_exp_f32_e32 v113, v113
	v_pk_fma_f32 v[96:97], v[18:19], v[114:115], v[96:97]
	v_add_f32_e32 v112, 1.0, v112
	v_add_f32_e32 v113, 1.0, v113
	v_rcp_f32_e32 v112, v112
	v_rcp_f32_e32 v113, v113
	v_pk_add_f32 v[96:97], v[96:97], v[14:15]
	v_pk_mul_f32 v[92:93], v[92:93], v[112:113]
	s_nop 0
	v_pk_mul_f32 v[92:93], v[96:97], v[92:93]
	v_lshlrev_b32_e32 v96, 16, v94
	v_cvt_pk_bf16_f32 v89, v92, v93
	v_pk_mul_f32 v[92:93], v[36:37], v[104:105]
	v_and_b32_e32 v97, 0xffff0000, v94
	v_pk_fma_f32 v[92:93], v[32:33], v[118:119], v[92:93]
	v_pk_mul_f32 v[112:113], v[60:61], v[124:125]
	v_pk_fma_f32 v[92:93], v[40:41], v[96:97], v[92:93]
	v_pk_fma_f32 v[118:119], v[56:57], v[140:141], v[112:113]
	v_pk_add_f32 v[92:93], v[92:93], v[52:53]
	s_nop 0
	v_mul_f32_e32 v94, 0xbfb8aa3b, v92
	v_exp_f32_e32 v94, v94
	v_mul_f32_e32 v112, 0xbfb8aa3b, v93
	v_exp_f32_e32 v113, v112
	v_lshlrev_b32_e32 v112, 16, v90
	v_add_f32_e32 v94, 1.0, v94
	v_rcp_f32_e32 v122, v94
	v_add_f32_e32 v94, 1.0, v113
	v_rcp_f32_e32 v123, v94
	v_and_b32_e32 v113, 0xffff0000, v90
	v_pk_fma_f32 v[118:119], v[44:45], v[112:113], v[118:119]
	v_lshlrev_b32_e32 v94, 16, v95
	v_pk_add_f32 v[118:119], v[118:119], v[48:49]
	v_pk_mul_f32 v[92:93], v[92:93], v[122:123]
	v_and_b32_e32 v95, 0xffff0000, v95
	v_pk_mul_f32 v[92:93], v[118:119], v[92:93]
	s_nop 0
	v_cvt_pk_bf16_f32 v90, v92, v93
	v_pk_mul_f32 v[92:93], v[38:39], v[102:103]
	s_nop 0
	v_pk_fma_f32 v[92:93], v[34:35], v[110:111], v[92:93]
	v_pk_mul_f32 v[110:111], v[62:63], v[120:121]
	v_pk_fma_f32 v[92:93], v[42:43], v[94:95], v[92:93]
	v_pk_fma_f32 v[118:119], v[58:59], v[138:139], v[110:111]
	v_pk_add_f32 v[92:93], v[92:93], v[54:55]
	s_nop 0
	v_mul_f32_e32 v110, 0xbfb8aa3b, v92
	v_exp_f32_e32 v111, v110
	v_mul_f32_e32 v110, 0xbfb8aa3b, v93
	v_exp_f32_e32 v123, v110
	v_lshlrev_b32_e32 v110, 16, v91
	v_add_f32_e32 v111, 1.0, v111
	v_rcp_f32_e32 v122, v111
	v_add_f32_e32 v111, 1.0, v123
	v_rcp_f32_e32 v123, v111
	v_and_b32_e32 v111, 0xffff0000, v91
	v_pk_fma_f32 v[118:119], v[46:47], v[110:111], v[118:119]
	v_pk_mul_f32 v[92:93], v[92:93], v[122:123]
	v_pk_add_f32 v[118:119], v[118:119], v[50:51]
	s_nop 0
	v_pk_mul_f32 v[92:93], v[118:119], v[92:93]
	s_nop 0
	v_cvt_pk_bf16_f32 v91, v92, v93
	v_mad_i64_i32 v[92:93], s[4:5], v160, s26, v[130:131]
	flat_store_dwordx4 v[92:93], v[88:91]
	v_lshlrev_b32_e32 v92, 16, v84
	v_and_b32_e32 v93, 0xffff0000, v84
	v_pk_mul_f32 v[88:89], v[4:5], v[100:101]
	v_pk_mul_f32 v[90:91], v[28:29], v[116:117]
	v_pk_fma_f32 v[88:89], v[0:1], v[108:109], v[88:89]
	v_pk_fma_f32 v[90:91], v[24:25], v[136:137], v[90:91]
	v_pk_fma_f32 v[88:89], v[8:9], v[92:93], v[88:89]
	s_nop 0
	v_pk_add_f32 v[88:89], v[88:89], v[20:21]
	s_nop 0
	v_mul_f32_e32 v84, 0xbfb8aa3b, v88
	v_exp_f32_e32 v84, v84
	v_mul_f32_e32 v108, 0xbfb8aa3b, v89
	v_exp_f32_e32 v109, v108
	v_lshlrev_b32_e32 v108, 16, v80
	v_add_f32_e32 v84, 1.0, v84
	v_rcp_f32_e32 v118, v84
	v_add_f32_e32 v84, 1.0, v109
	v_rcp_f32_e32 v119, v84
	v_and_b32_e32 v109, 0xffff0000, v80
	v_pk_fma_f32 v[90:91], v[16:17], v[108:109], v[90:91]
	v_pk_mul_f32 v[88:89], v[88:89], v[118:119]
	v_pk_add_f32 v[90:91], v[90:91], v[12:13]
	s_nop 0
	v_pk_mul_f32 v[88:89], v[90:91], v[88:89]
	v_lshlrev_b32_e32 v90, 16, v85
	v_cvt_pk_bf16_f32 v80, v88, v89
	v_pk_mul_f32 v[88:89], v[6:7], v[98:99]
	v_and_b32_e32 v91, 0xffff0000, v85
	v_pk_fma_f32 v[88:89], v[2:3], v[106:107], v[88:89]
	s_nop 0
	v_pk_fma_f32 v[84:85], v[10:11], v[90:91], v[88:89]
	v_pk_mul_f32 v[88:89], v[30:31], v[114:115]
	v_pk_add_f32 v[84:85], v[84:85], v[22:23]
	v_pk_fma_f32 v[88:89], v[26:27], v[134:135], v[88:89]
	v_mul_f32_e32 v106, 0xbfb8aa3b, v84
	v_exp_f32_e32 v107, v106
	v_mul_f32_e32 v106, 0xbfb8aa3b, v85
	v_exp_f32_e32 v119, v106
	v_lshlrev_b32_e32 v106, 16, v81
	v_add_f32_e32 v107, 1.0, v107
	v_rcp_f32_e32 v118, v107
	v_add_f32_e32 v107, 1.0, v119
	v_rcp_f32_e32 v119, v107
	v_and_b32_e32 v107, 0xffff0000, v81
	v_pk_fma_f32 v[88:89], v[18:19], v[106:107], v[88:89]
	v_pk_mul_f32 v[84:85], v[84:85], v[118:119]
	v_pk_add_f32 v[88:89], v[88:89], v[14:15]
	s_nop 0
	v_pk_mul_f32 v[84:85], v[88:89], v[84:85]
	v_lshlrev_b32_e32 v88, 16, v86
	v_cvt_pk_bf16_f32 v81, v84, v85
	v_pk_mul_f32 v[84:85], v[36:37], v[96:97]
	v_and_b32_e32 v89, 0xffff0000, v86
	v_pk_fma_f32 v[84:85], v[32:33], v[104:105], v[84:85]
	v_pk_mul_f32 v[104:105], v[60:61], v[112:113]
	v_pk_fma_f32 v[84:85], v[40:41], v[88:89], v[84:85]
	v_pk_fma_f32 v[118:119], v[56:57], v[124:125], v[104:105]
	v_pk_add_f32 v[84:85], v[84:85], v[52:53]
	s_nop 0
	v_mul_f32_e32 v86, 0xbfb8aa3b, v84
	v_exp_f32_e32 v86, v86
	v_mul_f32_e32 v104, 0xbfb8aa3b, v85
	v_exp_f32_e32 v105, v104
	v_lshlrev_b32_e32 v104, 16, v82
	v_add_f32_e32 v86, 1.0, v86
	v_rcp_f32_e32 v122, v86
	v_add_f32_e32 v86, 1.0, v105
	v_rcp_f32_e32 v123, v86
	v_and_b32_e32 v105, 0xffff0000, v82
	v_pk_fma_f32 v[118:119], v[44:45], v[104:105], v[118:119]
	v_pk_mul_f32 v[84:85], v[84:85], v[122:123]
	v_pk_add_f32 v[118:119], v[118:119], v[48:49]
	s_nop 0
	v_pk_mul_f32 v[84:85], v[118:119], v[84:85]
	s_nop 0
	v_cvt_pk_bf16_f32 v82, v84, v85
	v_pk_mul_f32 v[84:85], v[38:39], v[94:95]
	s_nop 0
	v_pk_fma_f32 v[102:103], v[34:35], v[102:103], v[84:85]
	v_lshlrev_b32_e32 v84, 16, v87
	v_and_b32_e32 v85, 0xffff0000, v87
	v_pk_fma_f32 v[86:87], v[42:43], v[84:85], v[102:103]
	v_pk_mul_f32 v[102:103], v[62:63], v[110:111]
	v_pk_add_f32 v[86:87], v[86:87], v[54:55]
	v_pk_fma_f32 v[118:119], v[58:59], v[120:121], v[102:103]
	v_mul_f32_e32 v102, 0xbfb8aa3b, v86
	v_exp_f32_e32 v103, v102
	v_mul_f32_e32 v102, 0xbfb8aa3b, v87
	v_exp_f32_e32 v121, v102
	v_lshlrev_b32_e32 v102, 16, v83
	v_add_f32_e32 v103, 1.0, v103
	v_rcp_f32_e32 v120, v103
	v_add_f32_e32 v103, 1.0, v121
	v_rcp_f32_e32 v121, v103
	v_and_b32_e32 v103, 0xffff0000, v83
	v_pk_fma_f32 v[118:119], v[46:47], v[102:103], v[118:119]
	v_pk_mul_f32 v[86:87], v[86:87], v[120:121]
	v_pk_add_f32 v[118:119], v[118:119], v[50:51]
	s_nop 0
	v_pk_mul_f32 v[86:87], v[118:119], v[86:87]
	s_nop 0
	v_cvt_pk_bf16_f32 v83, v86, v87
	v_mad_i64_i32 v[86:87], s[4:5], v159, s26, v[130:131]
	flat_store_dwordx4 v[86:87], v[80:83]
	v_pk_mul_f32 v[86:87], v[28:29], v[108:109]
	s_nop 0
	v_pk_mul_f32 v[80:81], v[4:5], v[92:93]
	v_lshlrev_b32_e32 v82, 16, v76
	v_pk_fma_f32 v[80:81], v[0:1], v[100:101], v[80:81]
	v_and_b32_e32 v83, 0xffff0000, v76
	v_pk_fma_f32 v[80:81], v[8:9], v[82:83], v[80:81]
	v_pk_fma_f32 v[86:87], v[24:25], v[116:117], v[86:87]
	v_pk_add_f32 v[80:81], v[80:81], v[20:21]
	s_nop 0
	v_mul_f32_e32 v76, 0xbfb8aa3b, v80
	v_exp_f32_e32 v76, v76
	v_mul_f32_e32 v100, 0xbfb8aa3b, v81
	v_exp_f32_e32 v101, v100
	v_lshlrev_b32_e32 v100, 16, v72
	v_add_f32_e32 v76, 1.0, v76
	v_rcp_f32_e32 v116, v76
	v_add_f32_e32 v76, 1.0, v101
	v_rcp_f32_e32 v117, v76
	v_and_b32_e32 v101, 0xffff0000, v72
	v_pk_fma_f32 v[86:87], v[16:17], v[100:101], v[86:87]
	v_pk_mul_f32 v[80:81], v[80:81], v[116:117]
	v_pk_add_f32 v[86:87], v[86:87], v[12:13]
	s_nop 0
	v_pk_mul_f32 v[80:81], v[86:87], v[80:81]
	s_nop 0
	v_cvt_pk_bf16_f32 v116, v80, v81
	v_pk_mul_f32 v[80:81], v[6:7], v[90:91]
	s_nop 0
	v_pk_fma_f32 v[86:87], v[2:3], v[98:99], v[80:81]
	v_lshlrev_b32_e32 v80, 16, v77
	v_and_b32_e32 v81, 0xffff0000, v77
	v_pk_fma_f32 v[76:77], v[10:11], v[80:81], v[86:87]
	v_pk_mul_f32 v[86:87], v[30:31], v[106:107]
	v_pk_add_f32 v[76:77], v[76:77], v[22:23]
	v_pk_fma_f32 v[86:87], v[26:27], v[114:115], v[86:87]
	v_mul_f32_e32 v72, 0xbfb8aa3b, v76
	v_exp_f32_e32 v72, v72
	v_mul_f32_e32 v98, 0xbfb8aa3b, v77
	v_exp_f32_e32 v99, v98
	v_lshlrev_b32_e32 v98, 16, v73
	v_add_f32_e32 v72, 1.0, v72
	v_rcp_f32_e32 v114, v72
	v_add_f32_e32 v72, 1.0, v99
	v_rcp_f32_e32 v115, v72
	v_and_b32_e32 v99, 0xffff0000, v73
	v_pk_fma_f32 v[72:73], v[18:19], v[98:99], v[86:87]
	v_pk_mul_f32 v[86:87], v[60:61], v[104:105]
	v_pk_add_f32 v[72:73], v[72:73], v[14:15]
	v_pk_mul_f32 v[76:77], v[76:77], v[114:115]
	s_nop 0
	v_pk_mul_f32 v[72:73], v[72:73], v[76:77]
	v_lshlrev_b32_e32 v76, 16, v78
	v_cvt_pk_bf16_f32 v117, v72, v73
	v_pk_mul_f32 v[72:73], v[36:37], v[88:89]
	v_and_b32_e32 v77, 0xffff0000, v78
	v_pk_fma_f32 v[72:73], v[32:33], v[96:97], v[72:73]
	v_pk_fma_f32 v[96:97], v[56:57], v[112:113], v[86:87]
	v_pk_fma_f32 v[72:73], v[40:41], v[76:77], v[72:73]
	s_nop 0
	v_pk_add_f32 v[72:73], v[72:73], v[52:53]
	s_nop 0
	v_mul_f32_e32 v78, 0xbfb8aa3b, v72
	v_exp_f32_e32 v78, v78
	v_mul_f32_e32 v86, 0xbfb8aa3b, v73
	v_exp_f32_e32 v87, v86
	v_lshlrev_b32_e32 v86, 16, v74
	v_add_f32_e32 v78, 1.0, v78
	v_rcp_f32_e32 v112, v78
	v_add_f32_e32 v78, 1.0, v87
	v_rcp_f32_e32 v113, v78
	v_and_b32_e32 v87, 0xffff0000, v74
	v_pk_fma_f32 v[96:97], v[44:45], v[86:87], v[96:97]
	v_pk_mul_f32 v[72:73], v[72:73], v[112:113]
	v_pk_add_f32 v[96:97], v[96:97], v[48:49]
	s_nop 0
	v_pk_mul_f32 v[72:73], v[96:97], v[72:73]
	s_nop 0
	v_cvt_pk_bf16_f32 v118, v72, v73
	v_pk_mul_f32 v[72:73], v[38:39], v[84:85]
	s_nop 0
	v_pk_fma_f32 v[94:95], v[34:35], v[94:95], v[72:73]
	v_lshlrev_b32_e32 v72, 16, v79
	v_and_b32_e32 v73, 0xffff0000, v79
	v_pk_fma_f32 v[78:79], v[42:43], v[72:73], v[94:95]
	v_pk_mul_f32 v[94:95], v[62:63], v[102:103]
	v_pk_add_f32 v[78:79], v[78:79], v[54:55]
	v_pk_fma_f32 v[94:95], v[58:59], v[110:111], v[94:95]
	v_mul_f32_e32 v74, 0xbfb8aa3b, v78
	v_exp_f32_e32 v96, v74
	v_mul_f32_e32 v74, 0xbfb8aa3b, v79
	v_exp_f32_e32 v97, v74
	v_lshlrev_b32_e32 v74, 16, v75
	v_add_f32_e32 v96, 1.0, v96
	v_rcp_f32_e32 v96, v96
	v_add_f32_e32 v97, 1.0, v97
	v_rcp_f32_e32 v97, v97
	v_and_b32_e32 v75, 0xffff0000, v75
	v_pk_fma_f32 v[94:95], v[46:47], v[74:75], v[94:95]
	v_pk_mul_f32 v[78:79], v[78:79], v[96:97]
	v_pk_add_f32 v[94:95], v[94:95], v[50:51]
	s_nop 0
	v_pk_mul_f32 v[78:79], v[94:95], v[78:79]
	v_pk_mul_f32 v[94:95], v[28:29], v[100:101]
	v_cvt_pk_bf16_f32 v119, v78, v79
	v_mad_i64_i32 v[78:79], s[4:5], v158, s26, v[130:131]
	flat_store_dwordx4 v[78:79], v[116:119]
	v_pk_mul_f32 v[78:79], v[4:5], v[82:83]
	v_pk_fma_f32 v[94:95], v[24:25], v[108:109], v[94:95]
	v_pk_fma_f32 v[78:79], v[0:1], v[92:93], v[78:79]
	v_lshlrev_b32_e32 v92, 16, v68
	v_and_b32_e32 v93, 0xffff0000, v68
	v_pk_fma_f32 v[78:79], v[8:9], v[92:93], v[78:79]
	v_pk_mul_f32 v[4:5], v[4:5], v[92:93]
	v_pk_add_f32 v[78:79], v[78:79], v[20:21]
	v_pk_fma_f32 v[0:1], v[0:1], v[82:83], v[4:5]
	v_mul_f32_e32 v68, 0xbfb8aa3b, v78
	v_lshlrev_b32_e32 v4, 16, v157
	v_and_b32_e32 v5, 0xffff0000, v157
	v_exp_f32_e32 v68, v68
	v_mul_f32_e32 v96, 0xbfb8aa3b, v79
	v_pk_fma_f32 v[0:1], v[8:9], v[4:5], v[0:1]
	v_exp_f32_e32 v97, v96
	v_pk_add_f32 v[0:1], v[0:1], v[20:21]
	v_add_f32_e32 v68, 1.0, v68
	v_mul_f32_e32 v8, 0xbfb8aa3b, v0
	v_exp_f32_e32 v9, v8
	v_mul_f32_e32 v8, 0xbfb8aa3b, v1
	v_exp_f32_e32 v21, v8
	v_rcp_f32_e32 v108, v68
	v_add_f32_e32 v68, 1.0, v97
	v_rcp_f32_e32 v109, v68
	v_add_f32_e32 v9, 1.0, v9
	v_lshlrev_b32_e32 v96, 16, v64
	v_and_b32_e32 v97, 0xffff0000, v64
	v_rcp_f32_e32 v20, v9
	v_add_f32_e32 v9, 1.0, v21
	v_pk_fma_f32 v[94:95], v[16:17], v[96:97], v[94:95]
	v_rcp_f32_e32 v21, v9
	v_pk_add_f32 v[94:95], v[94:95], v[12:13]
	v_pk_mul_f32 v[78:79], v[78:79], v[108:109]
	v_pk_mul_f32 v[4:5], v[28:29], v[96:97]
	v_pk_mul_f32 v[78:79], v[94:95], v[78:79]
	v_pk_fma_f32 v[4:5], v[24:25], v[100:101], v[4:5]
	v_lshlrev_b32_e32 v8, 16, v152
	v_and_b32_e32 v9, 0xffff0000, v152
	v_cvt_pk_bf16_f32 v64, v78, v79
	v_pk_mul_f32 v[78:79], v[6:7], v[80:81]
	v_pk_fma_f32 v[4:5], v[16:17], v[8:9], v[4:5]
	v_pk_fma_f32 v[78:79], v[2:3], v[90:91], v[78:79]
	v_lshlrev_b32_e32 v68, 16, v69
	v_and_b32_e32 v69, 0xffff0000, v69
	v_pk_add_f32 v[4:5], v[4:5], v[12:13]
	v_pk_mul_f32 v[0:1], v[0:1], v[20:21]
	v_pk_fma_f32 v[78:79], v[10:11], v[68:69], v[78:79]
	v_pk_mul_f32 v[0:1], v[4:5], v[0:1]
	v_pk_mul_f32 v[4:5], v[6:7], v[68:69]
	v_pk_add_f32 v[78:79], v[78:79], v[22:23]
	v_pk_fma_f32 v[2:3], v[2:3], v[80:81], v[4:5]
	v_lshlrev_b32_e32 v4, 16, v156
	v_and_b32_e32 v5, 0xffff0000, v156
	v_mul_f32_e32 v94, 0xbfb8aa3b, v78
	v_pk_fma_f32 v[2:3], v[10:11], v[4:5], v[2:3]
	v_pk_mul_f32 v[90:91], v[30:31], v[98:99]
	v_exp_f32_e32 v95, v94
	v_mul_f32_e32 v94, 0xbfb8aa3b, v79
	v_pk_add_f32 v[2:3], v[2:3], v[22:23]
	v_pk_fma_f32 v[90:91], v[26:27], v[106:107], v[90:91]
	v_exp_f32_e32 v107, v94
	v_cvt_pk_bf16_f32 v0, v0, v1
	v_mul_f32_e32 v1, 0xbfb8aa3b, v2
	v_exp_f32_e32 v1, v1
	v_mul_f32_e32 v6, 0xbfb8aa3b, v3
	v_exp_f32_e32 v7, v6
	v_add_f32_e32 v95, 1.0, v95
	v_rcp_f32_e32 v106, v95
	v_add_f32_e32 v95, 1.0, v107
	v_rcp_f32_e32 v107, v95
	v_add_f32_e32 v1, 1.0, v1
	v_rcp_f32_e32 v8, v1
	v_add_f32_e32 v1, 1.0, v7
	v_lshlrev_b32_e32 v94, 16, v65
	v_and_b32_e32 v95, 0xffff0000, v65
	v_rcp_f32_e32 v9, v1
	v_pk_fma_f32 v[90:91], v[18:19], v[94:95], v[90:91]
	v_pk_mul_f32 v[4:5], v[30:31], v[94:95]
	v_pk_add_f32 v[90:91], v[90:91], v[14:15]
	v_pk_mul_f32 v[78:79], v[78:79], v[106:107]
	v_pk_fma_f32 v[4:5], v[26:27], v[98:99], v[4:5]
	v_lshlrev_b32_e32 v6, 16, v151
	v_and_b32_e32 v7, 0xffff0000, v151
	v_pk_mul_f32 v[78:79], v[90:91], v[78:79]
	v_pk_fma_f32 v[4:5], v[18:19], v[6:7], v[4:5]
	v_cvt_pk_bf16_f32 v65, v78, v79
	v_pk_mul_f32 v[78:79], v[36:37], v[76:77]
	v_pk_add_f32 v[4:5], v[4:5], v[14:15]
	v_pk_mul_f32 v[2:3], v[2:3], v[8:9]
	v_pk_fma_f32 v[78:79], v[32:33], v[88:89], v[78:79]
	v_lshlrev_b32_e32 v88, 16, v70
	v_and_b32_e32 v89, 0xffff0000, v70
	v_pk_mul_f32 v[2:3], v[4:5], v[2:3]
	v_pk_fma_f32 v[78:79], v[40:41], v[88:89], v[78:79]
	v_cvt_pk_bf16_f32 v1, v2, v3
	v_pk_mul_f32 v[2:3], v[36:37], v[88:89]
	v_lshlrev_b32_e32 v4, 16, v155
	v_pk_fma_f32 v[2:3], v[32:33], v[76:77], v[2:3]
	v_and_b32_e32 v5, 0xffff0000, v155
	v_pk_add_f32 v[78:79], v[78:79], v[52:53]
	v_pk_fma_f32 v[2:3], v[40:41], v[4:5], v[2:3]
	v_pk_mul_f32 v[90:91], v[60:61], v[86:87]
	v_mul_f32_e32 v70, 0xbfb8aa3b, v78
	v_pk_add_f32 v[2:3], v[2:3], v[52:53]
	v_pk_fma_f32 v[90:91], v[56:57], v[104:105], v[90:91]
	v_exp_f32_e32 v70, v70
	v_mul_f32_e32 v104, 0xbfb8aa3b, v79
	v_mul_f32_e32 v6, 0xbfb8aa3b, v2
	v_exp_f32_e32 v105, v104
	v_exp_f32_e32 v7, v6
	v_mul_f32_e32 v6, 0xbfb8aa3b, v3
	v_exp_f32_e32 v9, v6
	v_add_f32_e32 v70, 1.0, v70
	v_rcp_f32_e32 v106, v70
	v_add_f32_e32 v70, 1.0, v105
	v_add_f32_e32 v7, 1.0, v7
	v_rcp_f32_e32 v107, v70
	v_rcp_f32_e32 v8, v7
	v_add_f32_e32 v7, 1.0, v9
	v_lshlrev_b32_e32 v104, 16, v66
	v_and_b32_e32 v105, 0xffff0000, v66
	v_rcp_f32_e32 v9, v7
	v_pk_mul_f32 v[4:5], v[60:61], v[104:105]
	v_pk_fma_f32 v[90:91], v[44:45], v[104:105], v[90:91]
	v_pk_fma_f32 v[4:5], v[56:57], v[86:87], v[4:5]
	v_lshlrev_b32_e32 v6, 16, v150
	v_and_b32_e32 v7, 0xffff0000, v150
	v_pk_add_f32 v[90:91], v[90:91], v[48:49]
	v_pk_mul_f32 v[78:79], v[78:79], v[106:107]
	v_pk_fma_f32 v[4:5], v[44:45], v[6:7], v[4:5]
	v_pk_mul_f32 v[78:79], v[90:91], v[78:79]
	v_lshlrev_b32_e32 v70, 16, v71
	v_and_b32_e32 v71, 0xffff0000, v71
	v_pk_add_f32 v[4:5], v[4:5], v[48:49]
	v_pk_mul_f32 v[2:3], v[2:3], v[8:9]
	v_cvt_pk_bf16_f32 v66, v78, v79
	v_pk_mul_f32 v[78:79], v[38:39], v[72:73]
	v_pk_mul_f32 v[2:3], v[4:5], v[2:3]
	v_pk_mul_f32 v[4:5], v[38:39], v[70:71]
	v_pk_fma_f32 v[78:79], v[34:35], v[84:85], v[78:79]
	v_pk_fma_f32 v[4:5], v[34:35], v[72:73], v[4:5]
	v_lshlrev_b32_e32 v6, 16, v154
	v_and_b32_e32 v7, 0xffff0000, v154
	v_pk_fma_f32 v[78:79], v[42:43], v[70:71], v[78:79]
	v_pk_fma_f32 v[4:5], v[42:43], v[6:7], v[4:5]
	v_pk_add_f32 v[78:79], v[78:79], v[54:55]
	v_pk_add_f32 v[4:5], v[4:5], v[54:55]
	v_mul_f32_e32 v90, 0xbfb8aa3b, v78
	v_cvt_pk_bf16_f32 v2, v2, v3
	v_mul_f32_e32 v3, 0xbfb8aa3b, v4
	v_pk_mul_f32 v[84:85], v[62:63], v[74:75]
	v_exp_f32_e32 v91, v90
	v_mul_f32_e32 v90, 0xbfb8aa3b, v79
	v_exp_f32_e32 v3, v3
	v_mul_f32_e32 v8, 0xbfb8aa3b, v5
	v_pk_fma_f32 v[84:85], v[58:59], v[102:103], v[84:85]
	v_exp_f32_e32 v103, v90
	v_exp_f32_e32 v9, v8
	v_add_f32_e32 v91, 1.0, v91
	v_add_f32_e32 v3, 1.0, v3
	v_rcp_f32_e32 v102, v91
	v_add_f32_e32 v91, 1.0, v103
	v_rcp_f32_e32 v10, v3
	v_add_f32_e32 v3, 1.0, v9
	v_lshlrev_b32_e32 v90, 16, v67
	v_rcp_f32_e32 v103, v91
	v_and_b32_e32 v91, 0xffff0000, v67
	v_rcp_f32_e32 v11, v3
	v_pk_mul_f32 v[6:7], v[62:63], v[90:91]
	v_lshlrev_b32_e32 v8, 16, v149
	v_pk_fma_f32 v[6:7], v[58:59], v[74:75], v[6:7]
	v_and_b32_e32 v9, 0xffff0000, v149
	v_pk_fma_f32 v[84:85], v[46:47], v[90:91], v[84:85]
	v_pk_fma_f32 v[6:7], v[46:47], v[8:9], v[6:7]
	v_pk_add_f32 v[84:85], v[84:85], v[50:51]
	v_pk_mul_f32 v[78:79], v[78:79], v[102:103]
	v_pk_add_f32 v[6:7], v[6:7], v[50:51]
	v_pk_mul_f32 v[4:5], v[4:5], v[10:11]
	v_pk_mul_f32 v[78:79], v[84:85], v[78:79]
	v_pk_mul_f32 v[4:5], v[6:7], v[4:5]
	v_cvt_pk_bf16_f32 v67, v78, v79
	v_mad_i64_i32 v[78:79], s[4:5], v153, s26, v[130:131]
	v_cvt_pk_bf16_f32 v3, v4, v5
	v_mad_i64_i32 v[4:5], s[4:5], v128, s26, v[130:131]
	flat_store_dwordx4 v[78:79], v[64:67]
	flat_store_dwordx4 v[4:5], v[0:3]
	s_branch .LBB0_1088
